# UV sweep with 2-partition chunks (64 runs per wave): smaller L2 working set
# speedup vs baseline: 1.1379x; 1.0461x over previous
; __device__ __forceinline__ unsigned f2key(float f) { const unsigned u = __float_as_uint(f); return (u & 0x80000000u) ? ~u : (u | 0x80000000u); }
; __device__ __forceinline__ void peer_tile(const Args& A, LAS unsigned char* lds, int tile) {
;     ...
;         const int tg = w & 3, hg = w >> 2, tl = 16 * tg + l15;
;         const size_t m = (size_t)tile * 64 + tl;
;         unsigned LA[4][2][16];
; #pragma unroll
;         for (int hh = 0; hh < 4; ++hh) {
;             const int h = 4 * hg + hh;
; #pragma unroll
;             for (int p = 0; p < 2; ++p) {
;                 const int hp = 2 * h + p;
;                 unsigned k0[16], k1[16];
;                 { const bf16_t* sp = QRY + m * 2048 + hp * 128 + 32 * g;
;                   const u32x4 s0 = *(const u32x4*)sp, s1 = *(const u32x4*)(sp + 8), s2 = *(const u32x4*)(sp + 16), s3 = *(const u32x4*)(sp + 24);
;                   const unsigned sw[16] = {s0.x, s0.y, s0.z, s0.w, s1.x, s1.y, s1.z, s1.w, s2.x, s2.y, s2.z, s2.w, s3.x, s3.y, s3.z, s3.w};
; #pragma unroll
;                   for (int i = 0; i < 16; ++i) {
;                       const float lo = (float)__builtin_bit_cast(_Float16, (unsigned short)(sw[i] & 0xffffu)), hi = (float)__builtin_bit_cast(_Float16, (unsigned short)(sw[i] >> 16));
;                       const unsigned klo = (f2key(lo) & ~127u) | (unsigned)(127 - (32 * g + 2 * i)), khi = (f2key(hi) & ~127u) | (unsigned)(127 - (32 * g + 2 * i + 1));
;                       if (i < 8) { k0[2 * i] = klo; k0[2 * i + 1] = khi; } else { k1[2 * (i - 8)] = klo; k1[2 * (i - 8) + 1] = khi; } } }
.LBB0_699:
	v_mov_b32_e32 v19, v214
	s_ashr_i32 s3, s2, 31
	v_ashrrev_i32_e32 v7, 6, v19
	v_and_b32_e32 v0, 15, v19
	v_lshlrev_b32_e32 v1, 4, v7
	v_and_or_b32 v13, v1, 48, v0
	s_lshl_b64 s[28:29], s[2:3], 6
	v_or_b32_e32 v0, s28, v13
	v_mov_b32_e32 v1, s29
	v_bfe_u32 v221, v19, 4, 2
	v_ashrrev_i32_e32 v11, 8, v19
	v_lshlrev_b64 v[0:1], 12, v[0:1]
	v_lshlrev_b32_e32 v2, 10, v11
	v_lshl_add_u64 v[0:1], s[54:55], 0, v[0:1]
	v_lshlrev_b32_e32 v112, 6, v221
	v_lshl_add_u64 v[0:1], v[0:1], 0, v[112:113]
	v_ashrrev_i32_e32 v3, 31, v2
	v_lshl_add_u64 v[4:5], v[2:3], 1, v[0:1]
	global_load_dwordx4 v[20:23], v[4:5], off
	global_load_dwordx4 v[24:27], v[4:5], off offset:16
	global_load_dwordx4 v[0:3], v[4:5], off offset:48
	global_load_dwordx4 v[28:31], v[4:5], off offset:32
	v_lshlrev_b32_e32 v15, 5, v221
	v_or_b32_e32 v8, 8, v15
	v_or_b32_e32 v14, 2, v15
	v_or_b32_e32 v12, 4, v15
	v_or_b32_e32 v10, 6, v15
	v_and_b32_e32 v9, 63, v19
	v_cmp_gt_u32_e64 s[0:1], 16, v9
	v_cmp_gt_u32_e64 s[4:5], 32, v9
	v_mul_lo_u32 v6, v19, s17
	s_mov_b32 s3, 8
	s_waitcnt vmcnt(3)
	v_cvt_f32_f16_sdwa v17, v20 dst_sel:DWORD dst_unused:UNUSED_PAD src0_sel:WORD_1
	v_cvt_f32_f16_e32 v16, v20
	v_cvt_f32_f16_sdwa v20, v21 dst_sel:DWORD dst_unused:UNUSED_PAD src0_sel:WORD_1
	v_cvt_f32_f16_e32 v18, v21
	v_cvt_f32_f16_e32 v21, v22
	v_cvt_f32_f16_sdwa v22, v22 dst_sel:DWORD dst_unused:UNUSED_PAD src0_sel:WORD_1
	v_not_b32_e32 v34, v17
	v_or_b32_e32 v35, 0x80000000, v17
	v_cmp_gt_i32_e32 vcc, 0, v17
	v_not_b32_e32 v36, v16
	v_or_b32_e32 v37, 0x80000000, v16
	v_cndmask_b32_e32 v17, v35, v34, vcc
	v_cmp_gt_i32_e32 vcc, 0, v16
	v_cvt_f32_f16_e32 v32, v23
	v_cvt_f32_f16_sdwa v23, v23 dst_sel:DWORD dst_unused:UNUSED_PAD src0_sel:WORD_1
	v_not_b32_e32 v38, v20
	v_or_b32_e32 v39, 0x80000000, v20
	v_cndmask_b32_e32 v16, v37, v36, vcc
	v_cmp_gt_i32_e32 vcc, 0, v20
	v_not_b32_e32 v40, v18
	v_or_b32_e32 v41, 0x80000000, v18
	v_cndmask_b32_e32 v20, v39, v38, vcc
	v_cmp_gt_i32_e32 vcc, 0, v18
	s_waitcnt vmcnt(2)
	v_cvt_f32_f16_e32 v33, v24
	v_cvt_f32_f16_sdwa v24, v24 dst_sel:DWORD dst_unused:UNUSED_PAD src0_sel:WORD_1
	v_not_b32_e32 v42, v22
	v_or_b32_e32 v43, 0x80000000, v22
	v_cndmask_b32_e32 v18, v41, v40, vcc
	v_cmp_gt_i32_e32 vcc, 0, v22
	v_not_b32_e32 v44, v21
	v_or_b32_e32 v45, 0x80000000, v21
	v_cndmask_b32_e32 v22, v43, v42, vcc
	v_cmp_gt_i32_e32 vcc, 0, v21
	v_not_b32_e32 v46, v23
	v_or_b32_e32 v47, 0x80000000, v23
	v_cndmask_b32_e32 v21, v45, v44, vcc
	v_cmp_gt_i32_e32 vcc, 0, v23
	v_not_b32_e32 v48, v32
	v_or_b32_e32 v49, 0x80000000, v32
	v_cndmask_b32_e32 v23, v47, v46, vcc
	v_cmp_gt_i32_e32 vcc, 0, v32
	v_and_b32_e32 v16, 0xffffff80, v16
	v_not_b32_e32 v50, v24
	v_or_b32_e32 v51, 0x80000000, v24
	v_cndmask_b32_e32 v32, v49, v48, vcc
	v_sub_u32_e32 v16, v16, v15
	v_cmp_gt_i32_e32 vcc, 0, v24
	v_add_u32_e32 v35, 0x7f, v16
	v_and_b32_e32 v17, 0xffffff80, v17
	v_cndmask_b32_e32 v16, v51, v50, vcc
	v_and_b32_e32 v16, 0xffffff80, v16
	v_sub_u32_e32 v17, v17, v15
	v_sub_u32_e32 v16, v16, v8
	v_add_u32_e32 v34, 0x7e, v17
	v_add_u32_e32 v41, 0x7e, v16
	v_not_b32_e32 v16, v33
	v_or_b32_e32 v17, 0x80000000, v33
	v_cmp_gt_i32_e32 vcc, 0, v33
	v_and_b32_e32 v20, 0xffffff80, v20
	v_and_b32_e32 v18, 0xffffff80, v18
	v_cndmask_b32_e32 v16, v17, v16, vcc
	v_cvt_f32_f16_sdwa v17, v25 dst_sel:DWORD dst_unused:UNUSED_PAD src0_sel:WORD_1
	v_and_b32_e32 v21, 0xffffff80, v21
	v_sub_u32_e32 v20, v20, v14
	v_sub_u32_e32 v18, v18, v14
	v_sub_u32_e32 v21, v21, v12
	v_add_u32_e32 v36, 0x7e, v20
	v_add_u32_e32 v37, 0x7f, v18
	v_add_u32_e32 v39, 0x7f, v21
	v_and_b32_e32 v16, 0xffffff80, v16
	v_cvt_f32_f16_e32 v18, v25
	v_not_b32_e32 v20, v17
	v_or_b32_e32 v21, 0x80000000, v17
	v_cmp_gt_i32_e32 vcc, 0, v17
	v_sub_u32_e32 v16, v16, v8
	v_add_u32_e32 v33, 0x7f, v16
	v_cndmask_b32_e32 v17, v21, v20, vcc
	v_or_b32_e32 v16, 10, v15
	v_and_b32_e32 v17, 0xffffff80, v17
	v_sub_u32_e32 v17, v17, v16
	v_add_u32_e32 v42, 0x7e, v17
	v_not_b32_e32 v17, v18
	v_or_b32_e32 v20, 0x80000000, v18
	v_cmp_gt_i32_e32 vcc, 0, v18
	v_cvt_f32_f16_sdwa v18, v26 dst_sel:DWORD dst_unused:UNUSED_PAD src0_sel:WORD_1
	v_and_b32_e32 v22, 0xffffff80, v22
	v_sub_u32_e32 v22, v22, v12
	v_cndmask_b32_e32 v17, v20, v17, vcc
	v_add_u32_e32 v38, 0x7e, v22
	v_and_b32_e32 v17, 0xffffff80, v17
	v_cvt_f32_f16_e32 v20, v26
	v_not_b32_e32 v21, v18
	v_or_b32_e32 v22, 0x80000000, v18
	v_cmp_gt_i32_e32 vcc, 0, v18
	v_sub_u32_e32 v17, v17, v16
	v_add_u32_e32 v43, 0x7f, v17
	v_cndmask_b32_e32 v18, v22, v21, vcc
	v_or_b32_e32 v17, 12, v15
	v_and_b32_e32 v18, 0xffffff80, v18
	v_sub_u32_e32 v18, v18, v17
	v_add_u32_e32 v44, 0x7e, v18
	v_not_b32_e32 v18, v20
	v_or_b32_e32 v21, 0x80000000, v20
	v_cmp_gt_i32_e32 vcc, 0, v20
	v_cvt_f32_f16_sdwa v20, v27 dst_sel:DWORD dst_unused:UNUSED_PAD src0_sel:WORD_1
	v_and_b32_e32 v23, 0xffffff80, v23
	v_sub_u32_e32 v23, v23, v10
	v_cndmask_b32_e32 v18, v21, v18, vcc
	v_add_u32_e32 v40, 0x7e, v23
	v_and_b32_e32 v18, 0xffffff80, v18
	v_cvt_f32_f16_e32 v21, v27
	v_not_b32_e32 v22, v20
	v_or_b32_e32 v23, 0x80000000, v20
	v_cmp_gt_i32_e32 vcc, 0, v20
	v_sub_u32_e32 v18, v18, v17
	v_add_u32_e32 v45, 0x7f, v18
	v_cndmask_b32_e32 v20, v23, v22, vcc
	v_or_b32_e32 v18, 14, v15
	v_and_b32_e32 v20, 0xffffff80, v20
	v_sub_u32_e32 v20, v20, v18
	v_add_u32_e32 v27, 0x7e, v20
	v_not_b32_e32 v20, v21
	v_or_b32_e32 v22, 0x80000000, v21
	v_cmp_gt_i32_e32 vcc, 0, v21
	s_waitcnt vmcnt(0)
; __device__ __forceinline__ unsigned f2key(float f) { const unsigned u = __float_as_uint(f); return (u & 0x80000000u) ? ~u : (u | 0x80000000u); }
; __device__ __forceinline__ void peer_tile(const Args& A, LAS unsigned char* lds, int tile) {
;     ...
;                   for (int i = 0; i < 16; ++i) {
;                       const float lo = (float)__builtin_bit_cast(_Float16, (unsigned short)(sw[i] & 0xffffu)), hi = (float)__builtin_bit_cast(_Float16, (unsigned short)(sw[i] >> 16));
;                       const unsigned klo = (f2key(lo) & ~127u) | (unsigned)(127 - (32 * g + 2 * i)), khi = (f2key(hi) & ~127u) | (unsigned)(127 - (32 * g + 2 * i + 1));
;                       if (i < 8) { k0[2 * i] = klo; k0[2 * i + 1] = khi; } else { k1[2 * (i - 8)] = klo; k1[2 * (i - 8) + 1] = khi; } } }
;                 sort16_desc(k0); sort16_desc(k1); merge16(k0, k1);
	v_cvt_f32_f16_sdwa v21, v28 dst_sel:DWORD dst_unused:UNUSED_PAD src0_sel:WORD_1
	v_and_b32_e32 v32, 0xffffff80, v32
	v_cndmask_b32_e32 v20, v22, v20, vcc
	v_and_b32_e32 v20, 0xffffff80, v20
	v_cvt_f32_f16_e32 v22, v28
	v_not_b32_e32 v23, v21
	v_or_b32_e32 v24, 0x80000000, v21
	v_cmp_gt_i32_e32 vcc, 0, v21
	v_sub_u32_e32 v20, v20, v18
	v_add_u32_e32 v46, 0x7f, v20
	v_cndmask_b32_e32 v21, v24, v23, vcc
	v_or_b32_e32 v20, 16, v15
	v_and_b32_e32 v21, 0xffffff80, v21
	v_sub_u32_e32 v21, v21, v20
	v_add_u32_e32 v47, 0x7e, v21
	v_not_b32_e32 v21, v22
	v_or_b32_e32 v23, 0x80000000, v22
	v_cmp_gt_i32_e32 vcc, 0, v22
	v_cvt_f32_f16_sdwa v22, v29 dst_sel:DWORD dst_unused:UNUSED_PAD src0_sel:WORD_1
	v_sub_u32_e32 v32, v32, v10
	v_cndmask_b32_e32 v21, v23, v21, vcc
	v_and_b32_e32 v21, 0xffffff80, v21
	v_cvt_f32_f16_e32 v23, v29
	v_not_b32_e32 v24, v22
	v_or_b32_e32 v25, 0x80000000, v22
	v_cmp_gt_i32_e32 vcc, 0, v22
	v_sub_u32_e32 v21, v21, v20
	v_add_u32_e32 v48, 0x7f, v21
	v_cndmask_b32_e32 v22, v25, v24, vcc
	v_or_b32_e32 v21, 18, v15
	v_and_b32_e32 v22, 0xffffff80, v22
	v_sub_u32_e32 v22, v22, v21
	v_add_u32_e32 v29, 0x7e, v22
	v_not_b32_e32 v22, v23
	v_or_b32_e32 v24, 0x80000000, v23
	v_cmp_gt_i32_e32 vcc, 0, v23
	v_cvt_f32_f16_sdwa v23, v30 dst_sel:DWORD dst_unused:UNUSED_PAD src0_sel:WORD_1
	v_add_u32_e32 v32, 0x7f, v32
	v_cndmask_b32_e32 v22, v24, v22, vcc
	v_and_b32_e32 v22, 0xffffff80, v22
	v_cvt_f32_f16_e32 v24, v30
	v_not_b32_e32 v25, v23
	v_or_b32_e32 v26, 0x80000000, v23
	v_cmp_gt_i32_e32 vcc, 0, v23
	v_sub_u32_e32 v22, v22, v21
	v_add_u32_e32 v49, 0x7f, v22
	v_cndmask_b32_e32 v23, v26, v25, vcc
	v_or_b32_e32 v22, 20, v15
	v_and_b32_e32 v23, 0xffffff80, v23
	v_sub_u32_e32 v23, v23, v22
	v_add_u32_e32 v30, 0x7e, v23
	v_not_b32_e32 v23, v24
	v_or_b32_e32 v25, 0x80000000, v24
	v_cmp_gt_i32_e32 vcc, 0, v24
	v_cvt_f32_f16_sdwa v24, v31 dst_sel:DWORD dst_unused:UNUSED_PAD src0_sel:WORD_1
	v_max_u32_e32 v64, v48, v47
	v_cndmask_b32_e32 v23, v25, v23, vcc
	v_and_b32_e32 v23, 0xffffff80, v23
	v_cvt_f32_f16_e32 v25, v31
	v_not_b32_e32 v26, v24
	v_or_b32_e32 v28, 0x80000000, v24
	v_cmp_gt_i32_e32 vcc, 0, v24
	v_sub_u32_e32 v23, v23, v22
	v_add_u32_e32 v50, 0x7f, v23
	v_cndmask_b32_e32 v24, v28, v26, vcc
	v_or_b32_e32 v23, 22, v15
	v_and_b32_e32 v24, 0xffffff80, v24
	v_sub_u32_e32 v24, v24, v23
	v_add_u32_e32 v31, 0x7e, v24
	v_not_b32_e32 v24, v25
	v_or_b32_e32 v26, 0x80000000, v25
	v_cmp_gt_i32_e32 vcc, 0, v25
	v_cvt_f32_f16_sdwa v25, v0 dst_sel:DWORD dst_unused:UNUSED_PAD src0_sel:WORD_1
	v_cvt_f32_f16_e32 v0, v0
	v_cndmask_b32_e32 v24, v26, v24, vcc
	v_and_b32_e32 v24, 0xffffff80, v24
	v_not_b32_e32 v26, v25
	v_or_b32_e32 v28, 0x80000000, v25
	v_cmp_gt_i32_e32 vcc, 0, v25
	v_sub_u32_e32 v24, v24, v23
	v_add_u32_e32 v51, 0x7f, v24
	v_cndmask_b32_e32 v25, v28, v26, vcc
	v_or_b32_e32 v24, 24, v15
	v_and_b32_e32 v25, 0xffffff80, v25
	v_sub_u32_e32 v25, v25, v24
	v_add_u32_e32 v52, 0x7e, v25
	v_not_b32_e32 v25, v0
	v_or_b32_e32 v26, 0x80000000, v0
	v_cmp_gt_i32_e32 vcc, 0, v0
	v_min_u32_e32 v47, v48, v47
	v_max_u32_e32 v48, v29, v49
	v_cndmask_b32_e32 v0, v26, v25, vcc
	v_cvt_f32_f16_sdwa v26, v1 dst_sel:DWORD dst_unused:UNUSED_PAD src0_sel:WORD_1
	v_cvt_f32_f16_e32 v1, v1
	v_or_b32_e32 v25, 26, v15
	v_and_b32_e32 v0, 0xffffff80, v0
	v_not_b32_e32 v28, v26
	v_or_b32_e32 v53, 0x80000000, v26
	v_cmp_gt_i32_e32 vcc, 0, v26
	v_sub_u32_e32 v0, v0, v24
	v_add_u32_e32 v0, 0x7f, v0
	v_cndmask_b32_e32 v26, v53, v28, vcc
	v_and_b32_e32 v26, 0xffffff80, v26
	v_sub_u32_e32 v26, v26, v25
	v_add_u32_e32 v53, 0x7e, v26
	v_not_b32_e32 v26, v1
	v_or_b32_e32 v28, 0x80000000, v1
	v_cmp_gt_i32_e32 vcc, 0, v1
	v_min_u32_e32 v29, v29, v49
	v_max_u32_e32 v49, v50, v30
	v_cndmask_b32_e32 v1, v28, v26, vcc
	v_cvt_f32_f16_sdwa v28, v2 dst_sel:DWORD dst_unused:UNUSED_PAD src0_sel:WORD_1
	v_cvt_f32_f16_e32 v2, v2
	v_or_b32_e32 v26, 28, v15
	v_and_b32_e32 v1, 0xffffff80, v1
	v_not_b32_e32 v54, v28
	v_or_b32_e32 v55, 0x80000000, v28
	v_cmp_gt_i32_e32 vcc, 0, v28
	v_sub_u32_e32 v1, v1, v25
	v_add_u32_e32 v1, 0x7f, v1
	v_cndmask_b32_e32 v28, v55, v54, vcc
	v_and_b32_e32 v28, 0xffffff80, v28
	v_sub_u32_e32 v28, v28, v26
	v_add_u32_e32 v54, 0x7e, v28
	v_not_b32_e32 v28, v2
	v_or_b32_e32 v55, 0x80000000, v2
	v_cmp_gt_i32_e32 vcc, 0, v2
	v_min_u32_e32 v30, v50, v30
	v_max_u32_e32 v50, v31, v51
	v_cndmask_b32_e32 v2, v55, v28, vcc
	v_cvt_f32_f16_e32 v55, v3
	v_cvt_f32_f16_sdwa v3, v3 dst_sel:DWORD dst_unused:UNUSED_PAD src0_sel:WORD_1
	v_and_b32_e32 v2, 0xffffff80, v2
	v_or_b32_e32 v28, 30, v15
	v_not_b32_e32 v56, v55
	v_or_b32_e32 v57, 0x80000000, v55
	v_cmp_gt_i32_e32 vcc, 0, v55
	v_sub_u32_e32 v2, v2, v26
	v_add_u32_e32 v2, 0x7f, v2
	v_cndmask_b32_e32 v55, v57, v56, vcc
	v_not_b32_e32 v56, v3
	v_or_b32_e32 v57, 0x80000000, v3
	v_cmp_gt_i32_e32 vcc, 0, v3
	v_and_b32_e32 v55, 0xffffff80, v55
	v_sub_u32_e32 v55, v55, v28
	v_cndmask_b32_e32 v3, v57, v56, vcc
	v_and_b32_e32 v3, 0xffffff80, v3
	v_sub_u32_e32 v3, v3, v28
	v_add_u32_e32 v55, 0x7f, v55
	v_add_u32_e32 v3, 0x7e, v3
	v_max_u32_e32 v56, v35, v34
	v_min_u32_e32 v34, v35, v34
	v_max_u32_e32 v35, v36, v37
	v_min_u32_e32 v36, v36, v37
	v_max_u32_e32 v37, v39, v38
	v_min_u32_e32 v38, v39, v38
	v_max_u32_e32 v39, v40, v32
	v_min_u32_e32 v32, v40, v32
	v_max_u32_e32 v40, v33, v41
	v_min_u32_e32 v33, v33, v41
	v_max_u32_e32 v41, v42, v43
	v_min_u32_e32 v42, v42, v43
	v_max_u32_e32 v43, v45, v44
	v_min_u32_e32 v44, v45, v44
	v_max_u32_e32 v45, v27, v46
	v_min_u32_e32 v27, v27, v46
	v_min_u32_e32 v31, v31, v51
	v_max_u32_e32 v51, v0, v52
	v_min_u32_e32 v0, v0, v52
	v_max_u32_e32 v52, v53, v1
	v_min_u32_e32 v1, v53, v1
	v_max_u32_e32 v53, v2, v54
; #define CE_DESC(a, b) do { const unsigned _mx = (a) > (b) ? (a) : (b), _mn = (a) > (b) ? (b) : (a); (a) = _mx; (b) = _mn; } while (0)
; __device__ __forceinline__ void sort16_desc(unsigned (&k)[16]) {
; #pragma unroll
;     for (int size = 2; size <= 16; size <<= 1)
; #pragma unroll
;         for (int stride = size >> 1; stride > 0; stride >>= 1)
; #pragma unroll
;             for (int i = 0; i < 16; ++i) { const int j = i ^ stride;
;                 if (j > i) { if ((i & size) == 0) CE_DESC(k[i], k[j]); else CE_DESC(k[j], k[i]); } }
; }
	v_min_u32_e32 v2, v2, v54
	v_max_u32_e32 v54, v3, v55
	v_min_u32_e32 v3, v3, v55
	v_max_u32_e32 v46, v56, v36
	v_min_u32_e32 v36, v56, v36
	v_max_u32_e32 v56, v34, v35
	v_min_u32_e32 v34, v34, v35
	v_max_u32_e32 v35, v32, v37
	v_min_u32_e32 v32, v32, v37
	v_max_u32_e32 v37, v39, v38
	v_min_u32_e32 v38, v39, v38
	v_max_u32_e32 v39, v40, v42
	v_min_u32_e32 v40, v40, v42
	v_max_u32_e32 v42, v33, v41
	v_min_u32_e32 v33, v33, v41
	v_max_u32_e32 v41, v27, v43
	v_min_u32_e32 v27, v27, v43
	v_max_u32_e32 v43, v45, v44
	v_min_u32_e32 v44, v45, v44
	v_max_u32_e32 v55, v64, v29
	v_min_u32_e32 v29, v64, v29
	v_max_u32_e32 v64, v47, v48
	v_min_u32_e32 v47, v47, v48
	v_max_u32_e32 v48, v31, v49
	v_min_u32_e32 v31, v31, v49
	v_max_u32_e32 v49, v50, v30
	v_min_u32_e32 v30, v50, v30
	v_max_u32_e32 v50, v51, v1
	v_min_u32_e32 v1, v51, v1
	v_max_u32_e32 v51, v0, v52
	v_min_u32_e32 v0, v0, v52
	v_max_u32_e32 v52, v3, v53
	v_min_u32_e32 v3, v3, v53
	v_max_u32_e32 v53, v54, v2
	v_min_u32_e32 v2, v54, v2
	v_max_u32_e32 v45, v46, v56
	v_min_u32_e32 v46, v46, v56
	v_max_u32_e32 v56, v36, v34
	v_min_u32_e32 v34, v36, v34
	v_max_u32_e32 v36, v38, v32
	v_min_u32_e32 v32, v38, v32
	v_max_u32_e32 v38, v37, v35
	v_min_u32_e32 v35, v37, v35
	v_max_u32_e32 v37, v39, v42
	v_min_u32_e32 v39, v39, v42
	v_max_u32_e32 v42, v40, v33
	v_min_u32_e32 v33, v40, v33
	v_max_u32_e32 v40, v44, v27
	v_min_u32_e32 v27, v44, v27
	v_max_u32_e32 v44, v43, v41
	v_min_u32_e32 v41, v43, v41
	v_max_u32_e32 v54, v55, v64
	v_min_u32_e32 v55, v55, v64
	v_max_u32_e32 v64, v29, v47
	v_min_u32_e32 v29, v29, v47
	v_max_u32_e32 v47, v30, v31
	v_min_u32_e32 v30, v30, v31
	v_max_u32_e32 v31, v49, v48
	v_min_u32_e32 v48, v49, v48
	v_max_u32_e32 v49, v50, v51
	v_min_u32_e32 v50, v50, v51
	v_max_u32_e32 v51, v1, v0
	v_min_u32_e32 v0, v1, v0
	v_max_u32_e32 v1, v2, v3
	v_min_u32_e32 v2, v2, v3
	v_max_u32_e32 v3, v53, v52
	v_min_u32_e32 v52, v53, v52
	v_max_u32_e32 v43, v45, v32
	v_min_u32_e32 v32, v45, v32
	v_max_u32_e32 v45, v46, v36
	v_min_u32_e32 v36, v46, v36
	v_max_u32_e32 v46, v56, v35
	v_min_u32_e32 v35, v56, v35
	v_max_u32_e32 v56, v34, v38
	v_min_u32_e32 v34, v34, v38
	v_max_u32_e32 v38, v27, v37
	v_min_u32_e32 v27, v27, v37
	v_max_u32_e32 v37, v40, v39
	v_min_u32_e32 v39, v40, v39
	v_max_u32_e32 v40, v41, v42
	v_min_u32_e32 v41, v41, v42
	v_max_u32_e32 v42, v44, v33
	v_min_u32_e32 v33, v44, v33
	v_max_u32_e32 v53, v54, v30
	v_min_u32_e32 v30, v54, v30
	v_max_u32_e32 v54, v55, v47
	v_min_u32_e32 v47, v55, v47
	v_max_u32_e32 v55, v64, v48
	v_min_u32_e32 v48, v64, v48
	v_max_u32_e32 v64, v29, v31
	v_min_u32_e32 v29, v29, v31
	v_max_u32_e32 v31, v2, v49
	v_min_u32_e32 v2, v2, v49
	v_max_u32_e32 v49, v1, v50
	v_min_u32_e32 v1, v1, v50
	v_max_u32_e32 v50, v52, v51
	v_min_u32_e32 v51, v52, v51
	v_max_u32_e32 v52, v3, v0
	v_min_u32_e32 v0, v3, v0
	v_max_u32_e32 v44, v43, v46
	v_min_u32_e32 v43, v43, v46
	v_max_u32_e32 v46, v45, v56
	v_min_u32_e32 v45, v45, v56
	v_max_u32_e32 v56, v32, v35
	v_min_u32_e32 v32, v32, v35
	v_max_u32_e32 v35, v36, v34
	v_min_u32_e32 v34, v36, v34
	v_max_u32_e32 v36, v41, v27
	v_min_u32_e32 v27, v41, v27
	v_max_u32_e32 v41, v33, v39
	v_min_u32_e32 v33, v33, v39
	v_max_u32_e32 v39, v40, v38
	v_min_u32_e32 v38, v40, v38
	v_max_u32_e32 v40, v42, v37
	v_min_u32_e32 v37, v42, v37
	v_max_u32_e32 v3, v53, v55
	v_min_u32_e32 v53, v53, v55
	v_max_u32_e32 v55, v54, v64
	v_min_u32_e32 v54, v54, v64
	v_max_u32_e32 v64, v30, v48
	v_min_u32_e32 v30, v30, v48
	v_max_u32_e32 v48, v47, v29
	v_min_u32_e32 v29, v47, v29
	v_max_u32_e32 v47, v51, v2
	v_min_u32_e32 v2, v51, v2
	v_max_u32_e32 v51, v0, v1
	v_min_u32_e32 v0, v0, v1
	v_max_u32_e32 v1, v50, v31
	v_min_u32_e32 v31, v50, v31
	v_max_u32_e32 v50, v52, v49
	v_min_u32_e32 v49, v52, v49
	v_max_u32_e32 v42, v44, v46
	v_min_u32_e32 v44, v44, v46
	v_max_u32_e32 v46, v43, v45
	v_min_u32_e32 v43, v43, v45
	v_max_u32_e32 v45, v56, v35
	v_min_u32_e32 v35, v56, v35
	v_max_u32_e32 v56, v32, v34
	v_min_u32_e32 v32, v32, v34
	v_max_u32_e32 v34, v33, v27
	v_min_u32_e32 v27, v33, v27
	v_max_u32_e32 v33, v41, v36
	v_min_u32_e32 v36, v41, v36
	v_max_u32_e32 v41, v37, v38
	v_min_u32_e32 v37, v37, v38
	v_max_u32_e32 v38, v40, v39
	v_min_u32_e32 v39, v40, v39
	v_max_u32_e32 v52, v3, v55
	v_min_u32_e32 v3, v3, v55
	v_max_u32_e32 v55, v53, v54
	v_min_u32_e32 v53, v53, v54
	v_max_u32_e32 v54, v64, v48
	v_min_u32_e32 v48, v64, v48
	v_max_u32_e32 v64, v30, v29
	v_min_u32_e32 v29, v30, v29
	v_max_u32_e32 v30, v0, v2
	v_min_u32_e32 v0, v0, v2
	v_max_u32_e32 v2, v51, v47
	v_min_u32_e32 v47, v51, v47
	v_max_u32_e32 v51, v49, v31
	v_min_u32_e32 v31, v49, v31
	v_max_u32_e32 v49, v50, v1
	v_min_u32_e32 v1, v50, v1
	v_max_u32_e32 v40, v42, v27
	v_min_u32_e32 v27, v42, v27
	v_max_u32_e32 v42, v44, v34
	v_min_u32_e32 v34, v44, v34
	v_max_u32_e32 v44, v46, v36
	v_min_u32_e32 v36, v46, v36
	v_max_u32_e32 v46, v43, v33
	v_min_u32_e32 v33, v43, v33
	v_max_u32_e32 v43, v45, v37
	v_min_u32_e32 v37, v45, v37
	v_max_u32_e32 v45, v35, v41
	v_min_u32_e32 v35, v35, v41
	v_max_u32_e32 v41, v56, v39
	v_min_u32_e32 v39, v56, v39
	v_max_u32_e32 v56, v32, v38
	v_min_u32_e32 v32, v32, v38
	v_max_u32_e32 v50, v52, v0
	v_min_u32_e32 v0, v52, v0
	v_max_u32_e32 v52, v3, v30
	v_min_u32_e32 v3, v3, v30
	v_max_u32_e32 v30, v55, v47
	v_min_u32_e32 v47, v55, v47
	v_max_u32_e32 v55, v53, v2
	v_min_u32_e32 v2, v53, v2
	v_max_u32_e32 v53, v54, v31
	v_min_u32_e32 v31, v54, v31
	v_max_u32_e32 v54, v48, v51
	v_min_u32_e32 v48, v48, v51
	v_max_u32_e32 v51, v64, v1
	v_min_u32_e32 v1, v64, v1
	v_max_u32_e32 v64, v29, v49
	v_min_u32_e32 v29, v29, v49
	v_max_u32_e32 v38, v40, v43
	v_min_u32_e32 v40, v40, v43
; #define CE_DESC(a, b) do { const unsigned _mx = (a) > (b) ? (a) : (b), _mn = (a) > (b) ? (b) : (a); (a) = _mx; (b) = _mn; } while (0)
; __device__ __forceinline__ void merge16(unsigned (&a)[16], const unsigned (&b)[16]) {
; #pragma unroll
;     for (int i = 0; i < 16; ++i) a[i] = a[i] > b[15 - i] ? a[i] : b[15 - i];
; #pragma unroll
;     for (int stride = 8; stride > 0; stride >>= 1)
; #pragma unroll
;         for (int i = 0; i < 16; ++i) { const int j = i ^ stride; if (j > i) CE_DESC(a[i], a[j]); }
; }
; __device__ __forceinline__ void peer_tile(const Args& A, LAS unsigned char* lds, int tile) {
;     ...
;                 for (int msk = 16; msk <= 32; msk <<= 1) {
; #pragma unroll
;                     for (int i = 0; i < 16; ++i) k1[i] = (unsigned)__shfl_xor((int)k0[i], msk);
;                     merge16(k0, k1); }
	v_max_u32_e32 v43, v42, v45
	v_min_u32_e32 v42, v42, v45
	v_max_u32_e32 v45, v44, v41
	v_min_u32_e32 v41, v44, v41
	v_max_u32_e32 v44, v46, v56
	v_min_u32_e32 v46, v46, v56
	v_max_u32_e32 v56, v27, v37
	v_min_u32_e32 v27, v27, v37
	v_max_u32_e32 v37, v34, v35
	v_min_u32_e32 v34, v34, v35
	v_max_u32_e32 v35, v36, v39
	v_min_u32_e32 v36, v36, v39
	v_max_u32_e32 v39, v33, v32
	v_min_u32_e32 v32, v33, v32
	v_max_u32_e32 v49, v50, v53
	v_min_u32_e32 v50, v50, v53
	v_max_u32_e32 v53, v52, v54
	v_min_u32_e32 v52, v52, v54
	v_max_u32_e32 v54, v30, v51
	v_min_u32_e32 v30, v30, v51
	v_max_u32_e32 v51, v55, v64
	v_min_u32_e32 v55, v55, v64
	v_max_u32_e32 v64, v0, v31
	v_min_u32_e32 v0, v0, v31
	v_max_u32_e32 v31, v3, v48
	v_min_u32_e32 v3, v3, v48
	v_max_u32_e32 v48, v47, v1
	v_min_u32_e32 v1, v47, v1
	v_max_u32_e32 v47, v2, v29
	v_min_u32_e32 v2, v2, v29
	v_max_u32_e32 v33, v38, v45
	v_min_u32_e32 v38, v38, v45
	v_max_u32_e32 v45, v43, v44
	v_min_u32_e32 v43, v43, v44
	v_max_u32_e32 v44, v40, v41
	v_min_u32_e32 v40, v40, v41
	v_max_u32_e32 v41, v42, v46
	v_min_u32_e32 v42, v42, v46
	v_max_u32_e32 v46, v56, v35
	v_min_u32_e32 v35, v56, v35
	v_max_u32_e32 v56, v37, v39
	v_min_u32_e32 v37, v37, v39
	v_max_u32_e32 v39, v27, v36
	v_min_u32_e32 v27, v27, v36
	v_max_u32_e32 v36, v34, v32
	v_min_u32_e32 v32, v34, v32
	v_max_u32_e32 v29, v49, v54
	v_min_u32_e32 v49, v49, v54
	v_max_u32_e32 v54, v53, v51
	v_min_u32_e32 v51, v53, v51
	v_max_u32_e32 v53, v50, v30
	v_min_u32_e32 v30, v50, v30
	v_max_u32_e32 v50, v52, v55
	v_min_u32_e32 v52, v52, v55
	v_max_u32_e32 v55, v64, v48
	v_min_u32_e32 v48, v64, v48
	v_max_u32_e32 v64, v31, v47
	v_min_u32_e32 v31, v31, v47
	v_max_u32_e32 v47, v0, v1
	v_min_u32_e32 v0, v0, v1
	v_max_u32_e32 v1, v3, v2
	v_min_u32_e32 v2, v3, v2
	v_min_u32_e32 v34, v33, v45
	v_min_u32_e32 v57, v38, v43
	v_min_u32_e32 v58, v44, v41
	v_min_u32_e32 v59, v40, v42
	v_min_u32_e32 v60, v46, v56
	v_min_u32_e32 v61, v35, v37
	v_min_u32_e32 v62, v39, v36
	v_min_u32_e32 v63, v27, v32
	v_min_u32_e32 v3, v29, v54
	v_min_u32_e32 v65, v49, v51
	v_min_u32_e32 v66, v53, v50
	v_min_u32_e32 v67, v30, v52
	v_min_u32_e32 v68, v55, v64
	v_min_u32_e32 v69, v48, v31
	v_min_u32_e32 v70, v47, v1
	v_min_u32_e32 v71, v0, v2
	v_max3_u32 v33, v33, v45, v71
	v_max3_u32 v0, v34, v0, v2
	v_max3_u32 v2, v38, v43, v70
	v_max3_u32 v1, v57, v47, v1
	v_max3_u32 v34, v44, v41, v69
	v_max3_u32 v31, v58, v48, v31
	v_max3_u32 v38, v40, v42, v68
	v_max3_u32 v40, v59, v55, v64
	v_max3_u32 v41, v46, v56, v67
	v_max3_u32 v30, v60, v30, v52
	v_max3_u32 v35, v35, v37, v66
	v_max3_u32 v37, v61, v53, v50
	v_max3_u32 v36, v39, v36, v65
	v_max3_u32 v39, v62, v49, v51
	v_max3_u32 v3, v27, v32, v3
	v_max3_u32 v27, v63, v29, v54
	v_max_u32_e32 v29, v33, v41
	v_min_u32_e32 v32, v33, v41
	v_max_u32_e32 v33, v0, v30
	v_min_u32_e32 v0, v0, v30
	v_max_u32_e32 v30, v2, v35
	v_min_u32_e32 v2, v2, v35
	v_max_u32_e32 v35, v1, v37
	v_min_u32_e32 v1, v1, v37
	v_max_u32_e32 v37, v34, v36
	v_min_u32_e32 v34, v34, v36
	v_max_u32_e32 v36, v31, v39
	v_min_u32_e32 v31, v31, v39
	v_max_u32_e32 v39, v38, v3
	v_min_u32_e32 v3, v38, v3
	v_max_u32_e32 v38, v40, v27
	v_min_u32_e32 v27, v40, v27
	v_max_u32_e32 v40, v29, v37
	v_min_u32_e32 v29, v29, v37
	v_max_u32_e32 v37, v33, v36
	v_min_u32_e32 v33, v33, v36
	v_max_u32_e32 v36, v30, v39
	v_min_u32_e32 v30, v30, v39
	v_max_u32_e32 v39, v35, v38
	v_min_u32_e32 v35, v35, v38
	v_max_u32_e32 v38, v32, v34
	v_min_u32_e32 v32, v32, v34
	v_max_u32_e32 v34, v0, v31
	v_min_u32_e32 v0, v0, v31
	v_max_u32_e32 v31, v2, v3
	v_min_u32_e32 v2, v2, v3
	v_max_u32_e32 v3, v1, v27
	v_min_u32_e32 v1, v1, v27
	v_max_u32_e32 v27, v40, v36
	v_min_u32_e32 v36, v40, v36
	v_max_u32_e32 v40, v37, v39
	v_min_u32_e32 v37, v37, v39
	v_max_u32_e32 v39, v29, v30
	v_min_u32_e32 v29, v29, v30
	v_max_u32_e32 v30, v33, v35
	v_min_u32_e32 v33, v33, v35
	v_max_u32_e32 v35, v38, v31
	v_min_u32_e32 v31, v38, v31
	v_max_u32_e32 v38, v34, v3
	v_min_u32_e32 v3, v34, v3
	v_max_u32_e32 v34, v32, v2
	v_min_u32_e32 v2, v32, v2
	v_max_u32_e32 v32, v0, v1
	v_min_u32_e32 v0, v0, v1
	v_cmp_lt_i32_e32 vcc, v217, v216
	v_max_u32_e32 v41, v36, v37
	v_min_u32_e32 v36, v36, v37
	v_max_u32_e32 v37, v39, v30
	v_min_u32_e32 v30, v39, v30
	v_max_u32_e32 v39, v29, v33
	v_min_u32_e32 v29, v29, v33
	v_max_u32_e32 v33, v35, v38
	v_min_u32_e32 v35, v35, v38
	v_max_u32_e32 v38, v31, v3
	v_min_u32_e32 v3, v31, v3
	v_max_u32_e32 v31, v34, v32
	v_min_u32_e32 v32, v34, v32
	v_max_u32_e32 v34, v2, v0
	v_min_u32_e32 v0, v2, v0
	v_cndmask_b32_e32 v2, v215, v217, vcc
	v_max_u32_e32 v1, v27, v40
	v_min_u32_e32 v40, v27, v40
	v_lshlrev_b32_e32 v27, 2, v2
	ds_bpermute_b32 v2, v27, v1
	ds_bpermute_b32 v42, v27, v40
	ds_bpermute_b32 v43, v27, v41
	ds_bpermute_b32 v44, v27, v36
	ds_bpermute_b32 v45, v27, v37
	ds_bpermute_b32 v46, v27, v30
	ds_bpermute_b32 v47, v27, v39
	ds_bpermute_b32 v48, v27, v29
	ds_bpermute_b32 v49, v27, v33
	ds_bpermute_b32 v50, v27, v35
	ds_bpermute_b32 v51, v27, v38
	ds_bpermute_b32 v52, v27, v0
	ds_bpermute_b32 v53, v27, v34
	ds_bpermute_b32 v54, v27, v32
	ds_bpermute_b32 v55, v27, v31
	ds_bpermute_b32 v56, v27, v3
	s_waitcnt lgkmcnt(4)
	v_max_u32_e32 v1, v1, v52
	s_waitcnt lgkmcnt(3)
	v_max_u32_e32 v40, v40, v53
	s_waitcnt lgkmcnt(2)
	v_max_u32_e32 v41, v41, v54
	s_waitcnt lgkmcnt(1)
	v_max_u32_e32 v36, v36, v55
	s_waitcnt lgkmcnt(0)
; #define CE_DESC(a, b) do { const unsigned _mx = (a) > (b) ? (a) : (b), _mn = (a) > (b) ? (b) : (a); (a) = _mx; (b) = _mn; } while (0)
; __device__ __forceinline__ void merge16(unsigned (&a)[16], const unsigned (&b)[16]) {
; #pragma unroll
;     for (int i = 0; i < 16; ++i) a[i] = a[i] > b[15 - i] ? a[i] : b[15 - i];
; #pragma unroll
;     for (int stride = 8; stride > 0; stride >>= 1)
; #pragma unroll
;         for (int i = 0; i < 16; ++i) { const int j = i ^ stride; if (j > i) CE_DESC(a[i], a[j]); }
; }
; __device__ __forceinline__ void peer_tile(const Args& A, LAS unsigned char* lds, int tile) {
;     ...
;                 { const bf16_t* sp = QRY + m * 2048 + hp * 128 + 32 * g;
;                   const u32x4 s0 = *(const u32x4*)sp, s1 = *(const u32x4*)(sp + 8), s2 = *(const u32x4*)(sp + 16), s3 = *(const u32x4*)(sp + 24);
;     ...
;                 for (int msk = 16; msk <= 32; msk <<= 1) {
; #pragma unroll
;                     for (int i = 0; i < 16; ++i) k1[i] = (unsigned)__shfl_xor((int)k0[i], msk);
;                     merge16(k0, k1); }
	v_max_u32_e32 v37, v37, v56
	v_max_u32_e32 v30, v30, v51
	v_max_u32_e32 v39, v39, v50
	v_max_u32_e32 v29, v29, v49
	v_max_u32_e32 v33, v33, v48
	v_max_u32_e32 v35, v35, v47
	v_max_u32_e32 v38, v38, v46
	v_max_u32_e32 v3, v3, v45
	v_max_u32_e32 v31, v31, v44
	v_max_u32_e32 v32, v32, v43
	v_max_u32_e32 v34, v34, v42
	v_max_u32_e32 v0, v0, v2
	v_max_u32_e32 v2, v1, v33
	v_min_u32_e32 v1, v1, v33
	v_max_u32_e32 v33, v40, v35
	v_min_u32_e32 v35, v40, v35
	v_max_u32_e32 v40, v41, v38
	v_min_u32_e32 v38, v41, v38
	v_max_u32_e32 v41, v36, v3
	v_min_u32_e32 v3, v36, v3
	v_max_u32_e32 v36, v37, v31
	v_min_u32_e32 v31, v37, v31
	v_max_u32_e32 v37, v30, v32
	v_min_u32_e32 v30, v30, v32
	v_max_u32_e32 v32, v39, v34
	v_min_u32_e32 v34, v39, v34
	v_max_u32_e32 v39, v29, v0
	v_min_u32_e32 v0, v29, v0
	v_max_u32_e32 v29, v2, v36
	v_min_u32_e32 v2, v2, v36
	v_max_u32_e32 v36, v33, v37
	v_min_u32_e32 v33, v33, v37
	v_max_u32_e32 v37, v40, v32
	v_min_u32_e32 v32, v40, v32
	v_max_u32_e32 v40, v41, v39
	v_min_u32_e32 v39, v41, v39
	v_max_u32_e32 v41, v1, v31
	v_min_u32_e32 v1, v1, v31
	v_max_u32_e32 v31, v35, v30
	v_min_u32_e32 v30, v35, v30
	v_max_u32_e32 v35, v38, v34
	v_min_u32_e32 v34, v38, v34
	v_max_u32_e32 v38, v3, v0
	v_min_u32_e32 v0, v3, v0
	v_max_u32_e32 v3, v29, v37
	v_min_u32_e32 v29, v29, v37
	v_max_u32_e32 v37, v36, v40
	v_min_u32_e32 v36, v36, v40
	v_max_u32_e32 v40, v2, v32
	v_min_u32_e32 v2, v2, v32
	v_max_u32_e32 v32, v33, v39
	v_min_u32_e32 v33, v33, v39
	v_max_u32_e32 v39, v41, v35
	v_min_u32_e32 v35, v41, v35
	v_max_u32_e32 v41, v31, v38
	v_min_u32_e32 v31, v31, v38
	v_max_u32_e32 v38, v1, v34
	v_min_u32_e32 v1, v1, v34
	v_max_u32_e32 v34, v30, v0
	v_min_u32_e32 v0, v30, v0
	v_cmp_lt_i32_e32 vcc, v218, v216
	v_max_u32_e32 v42, v40, v32
	v_min_u32_e32 v32, v40, v32
	v_max_u32_e32 v40, v2, v33
	v_min_u32_e32 v2, v2, v33
	v_max_u32_e32 v33, v39, v41
	v_min_u32_e32 v39, v39, v41
	v_max_u32_e32 v41, v35, v31
	v_min_u32_e32 v31, v35, v31
	v_max_u32_e32 v35, v38, v34
	v_min_u32_e32 v34, v38, v34
	v_max_u32_e32 v38, v1, v0
	v_min_u32_e32 v0, v1, v0
	v_cndmask_b32_e32 v1, v215, v218, vcc
	v_max_u32_e32 v30, v3, v37
	v_min_u32_e32 v3, v3, v37
	v_max_u32_e32 v37, v29, v36
	v_min_u32_e32 v36, v29, v36
	v_lshlrev_b32_e32 v29, 2, v1
	ds_bpermute_b32 v46, v29, v0
	ds_bpermute_b32 v1, v29, v30
	ds_bpermute_b32 v43, v29, v3
	ds_bpermute_b32 v44, v29, v37
	ds_bpermute_b32 v45, v29, v36
	s_waitcnt lgkmcnt(4)
	v_max_u32_e32 v30, v30, v46
	global_load_dwordx4 v[46:49], v[4:5], off offset:272
	global_load_dwordx4 v[50:53], v[4:5], off offset:256
	ds_bpermute_b32 v54, v29, v42
	ds_bpermute_b32 v55, v29, v32
	ds_bpermute_b32 v56, v29, v40
	ds_bpermute_b32 v57, v29, v2
	ds_bpermute_b32 v58, v29, v33
	ds_bpermute_b32 v59, v29, v39
	ds_bpermute_b32 v60, v29, v41
	ds_bpermute_b32 v61, v29, v31
	ds_bpermute_b32 v62, v29, v35
	ds_bpermute_b32 v63, v29, v38
	ds_bpermute_b32 v64, v29, v34
	s_waitcnt lgkmcnt(4)
	v_max_u32_e32 v32, v32, v60
	s_waitcnt lgkmcnt(3)
	v_max_u32_e32 v42, v42, v61
	s_waitcnt lgkmcnt(2)
	v_max_u32_e32 v36, v36, v62
	s_waitcnt lgkmcnt(1)
	v_max_u32_e32 v3, v3, v63
	s_waitcnt lgkmcnt(0)
	v_max_u32_e32 v37, v37, v64
	v_max_u32_e32 v40, v40, v59
	v_max_u32_e32 v2, v2, v58
	v_max_u32_e32 v33, v33, v57
	v_max_u32_e32 v39, v39, v56
	v_max_u32_e32 v41, v41, v55
	v_max_u32_e32 v31, v31, v54
	v_max_u32_e32 v35, v35, v45
	v_max_u32_e32 v34, v34, v44
	v_max_u32_e32 v38, v38, v43
	v_max_u32_e32 v0, v0, v1
	v_max_u32_e32 v1, v30, v33
	v_min_u32_e32 v30, v30, v33
	v_max_u32_e32 v33, v3, v39
	v_min_u32_e32 v3, v3, v39
	v_max_u32_e32 v39, v37, v41
	v_min_u32_e32 v37, v37, v41
	v_max_u32_e32 v41, v36, v31
	v_min_u32_e32 v31, v36, v31
	v_max_u32_e32 v36, v42, v35
	v_min_u32_e32 v35, v42, v35
	v_max_u32_e32 v42, v32, v34
	v_min_u32_e32 v32, v32, v34
	v_max_u32_e32 v34, v40, v38
	v_min_u32_e32 v38, v40, v38
	v_max_u32_e32 v40, v2, v0
	v_min_u32_e32 v0, v2, v0
	v_max_u32_e32 v2, v1, v36
	v_min_u32_e32 v1, v1, v36
	v_max_u32_e32 v36, v33, v42
	v_min_u32_e32 v33, v33, v42
	v_max_u32_e32 v42, v39, v34
	v_min_u32_e32 v34, v39, v34
	v_max_u32_e32 v39, v41, v40
	v_min_u32_e32 v40, v41, v40
	v_max_u32_e32 v41, v30, v35
	v_min_u32_e32 v30, v30, v35
	v_max_u32_e32 v35, v3, v32
	v_min_u32_e32 v3, v3, v32
	v_max_u32_e32 v32, v37, v38
	v_min_u32_e32 v37, v37, v38
	v_max_u32_e32 v38, v31, v0
	v_min_u32_e32 v0, v31, v0
	v_max_u32_e32 v31, v2, v42
	v_min_u32_e32 v2, v2, v42
	v_max_u32_e32 v42, v36, v39
	v_min_u32_e32 v36, v36, v39
	v_max_u32_e32 v39, v1, v34
	v_min_u32_e32 v1, v1, v34
	v_max_u32_e32 v34, v33, v40
	v_min_u32_e32 v33, v33, v40
	v_max_u32_e32 v54, v41, v32
	v_min_u32_e32 v32, v41, v32
	v_max_u32_e32 v55, v35, v38
	v_min_u32_e32 v56, v35, v38
	v_max_u32_e32 v57, v30, v37
	v_min_u32_e32 v30, v30, v37
	v_max_u32_e32 v58, v3, v0
	v_min_u32_e32 v0, v3, v0
	v_max_u32_e32 v45, v31, v42
	v_min_u32_e32 v44, v31, v42
	v_max_u32_e32 v43, v2, v36
	v_min_u32_e32 v42, v2, v36
	v_max_u32_e32 v41, v39, v34
	v_min_u32_e32 v40, v39, v34
	v_max_u32_e32 v39, v1, v33
	v_min_u32_e32 v38, v1, v33
	v_max_u32_e32 v37, v54, v55
	v_min_u32_e32 v36, v54, v55
	v_max_u32_e32 v35, v32, v56
	v_min_u32_e32 v34, v32, v56
	v_max_u32_e32 v33, v57, v58
	v_min_u32_e32 v32, v57, v58
	v_max_u32_e32 v31, v30, v0
	v_min_u32_e32 v30, v30, v0
	global_load_dwordx4 v[0:3], v[4:5], off offset:304
	global_load_dwordx4 v[54:57], v[4:5], off offset:288
	s_waitcnt vmcnt(2)
; __device__ __forceinline__ unsigned f2key(float f) { const unsigned u = __float_as_uint(f); return (u & 0x80000000u) ? ~u : (u | 0x80000000u); }
; __device__ __forceinline__ void peer_tile(const Args& A, LAS unsigned char* lds, int tile) {
;     ...
;                   for (int i = 0; i < 16; ++i) {
;                       const float lo = (float)__builtin_bit_cast(_Float16, (unsigned short)(sw[i] & 0xffffu)), hi = (float)__builtin_bit_cast(_Float16, (unsigned short)(sw[i] >> 16));
;                       const unsigned klo = (f2key(lo) & ~127u) | (unsigned)(127 - (32 * g + 2 * i)), khi = (f2key(hi) & ~127u) | (unsigned)(127 - (32 * g + 2 * i + 1));
;                       if (i < 8) { k0[2 * i] = klo; k0[2 * i + 1] = khi; } else { k1[2 * (i - 8)] = klo; k1[2 * (i - 8) + 1] = khi; } } }
	v_cvt_f32_f16_sdwa v58, v50 dst_sel:DWORD dst_unused:UNUSED_PAD src0_sel:WORD_1
	v_cvt_f32_f16_e32 v50, v50
	v_not_b32_e32 v59, v58
	v_or_b32_e32 v60, 0x80000000, v58
	v_cmp_gt_i32_e32 vcc, 0, v58
	s_nop 1
	v_cndmask_b32_e32 v58, v60, v59, vcc
	v_not_b32_e32 v59, v50
	v_or_b32_e32 v60, 0x80000000, v50
	v_cmp_gt_i32_e32 vcc, 0, v50
	v_and_b32_e32 v58, 0xffffff80, v58
	v_sub_u32_e32 v58, v58, v15
	v_cndmask_b32_e32 v50, v60, v59, vcc
	v_cvt_f32_f16_sdwa v59, v51 dst_sel:DWORD dst_unused:UNUSED_PAD src0_sel:WORD_1
	v_cvt_f32_f16_e32 v51, v51
	v_and_b32_e32 v50, 0xffffff80, v50
	v_sub_u32_e32 v50, v50, v15
	v_not_b32_e32 v60, v59
	v_or_b32_e32 v61, 0x80000000, v59
	v_cmp_gt_i32_e32 vcc, 0, v59
	v_add_u32_e32 v58, 0x7e, v58
	v_add_u32_e32 v50, 0x7f, v50
	v_cndmask_b32_e32 v59, v61, v60, vcc
	v_not_b32_e32 v60, v51
	v_or_b32_e32 v61, 0x80000000, v51
	v_cmp_gt_i32_e32 vcc, 0, v51
	v_and_b32_e32 v59, 0xffffff80, v59
	v_sub_u32_e32 v59, v59, v14
	v_cndmask_b32_e32 v51, v61, v60, vcc
	v_cvt_f32_f16_sdwa v60, v52 dst_sel:DWORD dst_unused:UNUSED_PAD src0_sel:WORD_1
	v_cvt_f32_f16_e32 v52, v52
	v_and_b32_e32 v51, 0xffffff80, v51
	v_sub_u32_e32 v51, v51, v14
	v_not_b32_e32 v61, v60
	v_or_b32_e32 v62, 0x80000000, v60
	v_cmp_gt_i32_e32 vcc, 0, v60
	v_add_u32_e32 v59, 0x7e, v59
	v_add_u32_e32 v51, 0x7f, v51
	v_cndmask_b32_e32 v60, v62, v61, vcc
	v_not_b32_e32 v61, v52
	v_or_b32_e32 v62, 0x80000000, v52
	v_cmp_gt_i32_e32 vcc, 0, v52
	v_and_b32_e32 v60, 0xffffff80, v60
	v_sub_u32_e32 v60, v60, v12
	v_cndmask_b32_e32 v52, v62, v61, vcc
	v_cvt_f32_f16_sdwa v61, v53 dst_sel:DWORD dst_unused:UNUSED_PAD src0_sel:WORD_1
	v_cvt_f32_f16_e32 v53, v53
	v_and_b32_e32 v52, 0xffffff80, v52
	v_sub_u32_e32 v52, v52, v12
	v_not_b32_e32 v62, v61
	v_or_b32_e32 v63, 0x80000000, v61
	v_cmp_gt_i32_e32 vcc, 0, v61
	v_add_u32_e32 v60, 0x7e, v60
	v_add_u32_e32 v52, 0x7f, v52
	v_cndmask_b32_e32 v61, v63, v62, vcc
	v_not_b32_e32 v62, v53
	v_or_b32_e32 v63, 0x80000000, v53
	v_cmp_gt_i32_e32 vcc, 0, v53
	v_and_b32_e32 v61, 0xffffff80, v61
	v_sub_u32_e32 v61, v61, v10
	v_cndmask_b32_e32 v53, v63, v62, vcc
	v_cvt_f32_f16_sdwa v62, v46 dst_sel:DWORD dst_unused:UNUSED_PAD src0_sel:WORD_1
	v_cvt_f32_f16_e32 v46, v46
	v_and_b32_e32 v53, 0xffffff80, v53
	v_sub_u32_e32 v53, v53, v10
	v_not_b32_e32 v63, v62
	v_or_b32_e32 v64, 0x80000000, v62
	v_cmp_gt_i32_e32 vcc, 0, v62
	v_add_u32_e32 v61, 0x7e, v61
	v_add_u32_e32 v53, 0x7f, v53
	v_cndmask_b32_e32 v62, v64, v63, vcc
	v_not_b32_e32 v63, v46
	v_or_b32_e32 v64, 0x80000000, v46
	v_cmp_gt_i32_e32 vcc, 0, v46
	v_and_b32_e32 v62, 0xffffff80, v62
	v_sub_u32_e32 v62, v62, v8
	v_cndmask_b32_e32 v46, v64, v63, vcc
	v_cvt_f32_f16_sdwa v63, v47 dst_sel:DWORD dst_unused:UNUSED_PAD src0_sel:WORD_1
	v_cvt_f32_f16_e32 v47, v47
	v_and_b32_e32 v46, 0xffffff80, v46
	v_sub_u32_e32 v46, v46, v8
	v_not_b32_e32 v64, v63
	v_or_b32_e32 v65, 0x80000000, v63
	v_cmp_gt_i32_e32 vcc, 0, v63
	v_add_u32_e32 v62, 0x7e, v62
	v_add_u32_e32 v46, 0x7f, v46
	v_cndmask_b32_e32 v63, v65, v64, vcc
	v_not_b32_e32 v64, v47
	v_or_b32_e32 v65, 0x80000000, v47
	v_cmp_gt_i32_e32 vcc, 0, v47
	v_and_b32_e32 v63, 0xffffff80, v63
	v_sub_u32_e32 v63, v63, v16
	v_cndmask_b32_e32 v47, v65, v64, vcc
	v_cvt_f32_f16_sdwa v64, v48 dst_sel:DWORD dst_unused:UNUSED_PAD src0_sel:WORD_1
	v_cvt_f32_f16_e32 v48, v48
	v_and_b32_e32 v47, 0xffffff80, v47
	v_sub_u32_e32 v47, v47, v16
	v_not_b32_e32 v65, v64
	v_or_b32_e32 v66, 0x80000000, v64
	v_cmp_gt_i32_e32 vcc, 0, v64
	v_add_u32_e32 v63, 0x7e, v63
	v_add_u32_e32 v47, 0x7f, v47
	v_cndmask_b32_e32 v64, v66, v65, vcc
	v_not_b32_e32 v65, v48
	v_or_b32_e32 v66, 0x80000000, v48
	v_cmp_gt_i32_e32 vcc, 0, v48
	v_and_b32_e32 v64, 0xffffff80, v64
	v_sub_u32_e32 v64, v64, v17
	v_cndmask_b32_e32 v48, v66, v65, vcc
	v_cvt_f32_f16_sdwa v65, v49 dst_sel:DWORD dst_unused:UNUSED_PAD src0_sel:WORD_1
	v_cvt_f32_f16_e32 v49, v49
	v_and_b32_e32 v48, 0xffffff80, v48
	v_sub_u32_e32 v48, v48, v17
	v_not_b32_e32 v66, v65
	v_or_b32_e32 v67, 0x80000000, v65
	v_cmp_gt_i32_e32 vcc, 0, v65
	v_add_u32_e32 v64, 0x7e, v64
	v_add_u32_e32 v48, 0x7f, v48
	v_cndmask_b32_e32 v65, v67, v66, vcc
	v_not_b32_e32 v66, v49
	v_or_b32_e32 v67, 0x80000000, v49
	v_cmp_gt_i32_e32 vcc, 0, v49
	v_and_b32_e32 v65, 0xffffff80, v65
	v_sub_u32_e32 v65, v65, v18
	v_cndmask_b32_e32 v49, v67, v66, vcc
	s_waitcnt vmcnt(0)
; __device__ __forceinline__ unsigned f2key(float f) { const unsigned u = __float_as_uint(f); return (u & 0x80000000u) ? ~u : (u | 0x80000000u); }
; #define CE_DESC(a, b) do { const unsigned _mx = (a) > (b) ? (a) : (b), _mn = (a) > (b) ? (b) : (a); (a) = _mx; (b) = _mn; } while (0)
; __device__ __forceinline__ void sort16_desc(unsigned (&k)[16]) {
; #pragma unroll
;     for (int size = 2; size <= 16; size <<= 1)
; #pragma unroll
;         for (int stride = size >> 1; stride > 0; stride >>= 1)
; #pragma unroll
;             for (int i = 0; i < 16; ++i) { const int j = i ^ stride;
;                 if (j > i) { if ((i & size) == 0) CE_DESC(k[i], k[j]); else CE_DESC(k[j], k[i]); } }
; }
; __device__ __forceinline__ void peer_tile(const Args& A, LAS unsigned char* lds, int tile) {
;     ...
;                   for (int i = 0; i < 16; ++i) {
;                       const float lo = (float)__builtin_bit_cast(_Float16, (unsigned short)(sw[i] & 0xffffu)), hi = (float)__builtin_bit_cast(_Float16, (unsigned short)(sw[i] >> 16));
;                       const unsigned klo = (f2key(lo) & ~127u) | (unsigned)(127 - (32 * g + 2 * i)), khi = (f2key(hi) & ~127u) | (unsigned)(127 - (32 * g + 2 * i + 1));
;                       if (i < 8) { k0[2 * i] = klo; k0[2 * i + 1] = khi; } else { k1[2 * (i - 8)] = klo; k1[2 * (i - 8) + 1] = khi; } } }
	v_cvt_f32_f16_sdwa v66, v54 dst_sel:DWORD dst_unused:UNUSED_PAD src0_sel:WORD_1
	v_cvt_f32_f16_e32 v54, v54
	v_and_b32_e32 v49, 0xffffff80, v49
	v_sub_u32_e32 v49, v49, v18
	v_not_b32_e32 v67, v66
	v_or_b32_e32 v68, 0x80000000, v66
	v_cmp_gt_i32_e32 vcc, 0, v66
	v_add_u32_e32 v65, 0x7e, v65
	v_add_u32_e32 v49, 0x7f, v49
	v_cndmask_b32_e32 v66, v68, v67, vcc
	v_not_b32_e32 v67, v54
	v_or_b32_e32 v68, 0x80000000, v54
	v_cmp_gt_i32_e32 vcc, 0, v54
	v_and_b32_e32 v66, 0xffffff80, v66
	v_sub_u32_e32 v66, v66, v20
	v_cndmask_b32_e32 v54, v68, v67, vcc
	v_cvt_f32_f16_sdwa v67, v55 dst_sel:DWORD dst_unused:UNUSED_PAD src0_sel:WORD_1
	v_cvt_f32_f16_e32 v55, v55
	v_and_b32_e32 v54, 0xffffff80, v54
	v_sub_u32_e32 v54, v54, v20
	v_not_b32_e32 v68, v67
	v_or_b32_e32 v69, 0x80000000, v67
	v_cmp_gt_i32_e32 vcc, 0, v67
	v_add_u32_e32 v66, 0x7e, v66
	v_add_u32_e32 v54, 0x7f, v54
	v_cndmask_b32_e32 v67, v69, v68, vcc
	v_not_b32_e32 v68, v55
	v_or_b32_e32 v69, 0x80000000, v55
	v_cmp_gt_i32_e32 vcc, 0, v55
	v_and_b32_e32 v67, 0xffffff80, v67
	v_sub_u32_e32 v67, v67, v21
	v_cndmask_b32_e32 v55, v69, v68, vcc
	v_cvt_f32_f16_sdwa v68, v56 dst_sel:DWORD dst_unused:UNUSED_PAD src0_sel:WORD_1
	v_cvt_f32_f16_e32 v56, v56
	v_and_b32_e32 v55, 0xffffff80, v55
	v_sub_u32_e32 v55, v55, v21
	v_not_b32_e32 v69, v68
	v_or_b32_e32 v70, 0x80000000, v68
	v_cmp_gt_i32_e32 vcc, 0, v68
	v_add_u32_e32 v67, 0x7e, v67
	v_add_u32_e32 v55, 0x7f, v55
	v_cndmask_b32_e32 v68, v70, v69, vcc
	v_not_b32_e32 v69, v56
	v_or_b32_e32 v70, 0x80000000, v56
	v_cmp_gt_i32_e32 vcc, 0, v56
	v_and_b32_e32 v68, 0xffffff80, v68
	v_sub_u32_e32 v68, v68, v22
	v_cndmask_b32_e32 v56, v70, v69, vcc
	v_cvt_f32_f16_sdwa v69, v57 dst_sel:DWORD dst_unused:UNUSED_PAD src0_sel:WORD_1
	v_cvt_f32_f16_e32 v57, v57
	v_and_b32_e32 v56, 0xffffff80, v56
	v_sub_u32_e32 v56, v56, v22
	v_not_b32_e32 v70, v69
	v_or_b32_e32 v71, 0x80000000, v69
	v_cmp_gt_i32_e32 vcc, 0, v69
	v_add_u32_e32 v68, 0x7e, v68
	v_add_u32_e32 v56, 0x7f, v56
	v_cndmask_b32_e32 v69, v71, v70, vcc
	v_not_b32_e32 v70, v57
	v_or_b32_e32 v71, 0x80000000, v57
	v_cmp_gt_i32_e32 vcc, 0, v57
	v_and_b32_e32 v69, 0xffffff80, v69
	v_sub_u32_e32 v69, v69, v23
	v_cndmask_b32_e32 v57, v71, v70, vcc
	v_cvt_f32_f16_sdwa v70, v0 dst_sel:DWORD dst_unused:UNUSED_PAD src0_sel:WORD_1
	v_cvt_f32_f16_e32 v0, v0
	v_and_b32_e32 v57, 0xffffff80, v57
	v_sub_u32_e32 v57, v57, v23
	v_not_b32_e32 v71, v70
	v_or_b32_e32 v72, 0x80000000, v70
	v_cmp_gt_i32_e32 vcc, 0, v70
	v_add_u32_e32 v69, 0x7e, v69
	v_add_u32_e32 v57, 0x7f, v57
	v_cndmask_b32_e32 v70, v72, v71, vcc
	v_not_b32_e32 v71, v0
	v_or_b32_e32 v72, 0x80000000, v0
	v_cmp_gt_i32_e32 vcc, 0, v0
	v_and_b32_e32 v70, 0xffffff80, v70
	v_sub_u32_e32 v70, v70, v24
	v_cndmask_b32_e32 v0, v72, v71, vcc
	v_cvt_f32_f16_sdwa v71, v1 dst_sel:DWORD dst_unused:UNUSED_PAD src0_sel:WORD_1
	v_cvt_f32_f16_e32 v1, v1
	v_and_b32_e32 v0, 0xffffff80, v0
	v_sub_u32_e32 v0, v0, v24
	v_not_b32_e32 v72, v71
	v_or_b32_e32 v73, 0x80000000, v71
	v_cmp_gt_i32_e32 vcc, 0, v71
	v_add_u32_e32 v70, 0x7e, v70
	v_add_u32_e32 v0, 0x7f, v0
	v_cndmask_b32_e32 v71, v73, v72, vcc
	v_not_b32_e32 v72, v1
	v_or_b32_e32 v73, 0x80000000, v1
	v_cmp_gt_i32_e32 vcc, 0, v1
	v_and_b32_e32 v71, 0xffffff80, v71
	v_sub_u32_e32 v71, v71, v25
	v_cndmask_b32_e32 v1, v73, v72, vcc
	v_cvt_f32_f16_sdwa v72, v2 dst_sel:DWORD dst_unused:UNUSED_PAD src0_sel:WORD_1
	v_cvt_f32_f16_e32 v2, v2
	v_and_b32_e32 v1, 0xffffff80, v1
	v_sub_u32_e32 v1, v1, v25
	v_not_b32_e32 v73, v72
	v_or_b32_e32 v74, 0x80000000, v72
	v_cmp_gt_i32_e32 vcc, 0, v72
	v_add_u32_e32 v71, 0x7e, v71
	v_add_u32_e32 v1, 0x7f, v1
	v_cndmask_b32_e32 v72, v74, v73, vcc
	v_not_b32_e32 v73, v2
	v_or_b32_e32 v74, 0x80000000, v2
	v_cmp_gt_i32_e32 vcc, 0, v2
	v_and_b32_e32 v72, 0xffffff80, v72
	v_sub_u32_e32 v72, v72, v26
	v_cndmask_b32_e32 v2, v74, v73, vcc
	v_cvt_f32_f16_sdwa v73, v3 dst_sel:DWORD dst_unused:UNUSED_PAD src0_sel:WORD_1
	v_cvt_f32_f16_e32 v3, v3
	v_and_b32_e32 v2, 0xffffff80, v2
	v_sub_u32_e32 v2, v2, v26
	v_not_b32_e32 v74, v73
	v_or_b32_e32 v75, 0x80000000, v73
	v_cmp_gt_i32_e32 vcc, 0, v73
	v_add_u32_e32 v72, 0x7e, v72
	v_add_u32_e32 v2, 0x7f, v2
	v_cndmask_b32_e32 v73, v75, v74, vcc
	v_not_b32_e32 v74, v3
	v_or_b32_e32 v75, 0x80000000, v3
	v_cmp_gt_i32_e32 vcc, 0, v3
	v_and_b32_e32 v73, 0xffffff80, v73
	v_sub_u32_e32 v73, v73, v28
	v_cndmask_b32_e32 v3, v75, v74, vcc
	v_and_b32_e32 v3, 0xffffff80, v3
	v_sub_u32_e32 v3, v3, v28
	v_add_u32_e32 v73, 0x7e, v73
	v_add_u32_e32 v3, 0x7f, v3
	v_max_u32_e32 v74, v50, v58
	v_min_u32_e32 v50, v50, v58
	v_max_u32_e32 v58, v59, v51
	v_min_u32_e32 v51, v59, v51
	v_max_u32_e32 v59, v52, v60
	v_min_u32_e32 v52, v52, v60
	v_max_u32_e32 v60, v61, v53
	v_min_u32_e32 v53, v61, v53
	v_max_u32_e32 v61, v46, v62
	v_min_u32_e32 v46, v46, v62
	v_max_u32_e32 v62, v63, v47
	v_min_u32_e32 v47, v63, v47
	v_max_u32_e32 v63, v48, v64
	v_min_u32_e32 v48, v48, v64
	v_max_u32_e32 v64, v65, v49
	v_min_u32_e32 v49, v65, v49
	v_max_u32_e32 v82, v54, v66
	v_min_u32_e32 v54, v54, v66
	v_max_u32_e32 v66, v67, v55
	v_min_u32_e32 v55, v67, v55
	v_max_u32_e32 v67, v56, v68
	v_min_u32_e32 v56, v56, v68
	v_max_u32_e32 v68, v69, v57
	v_min_u32_e32 v57, v69, v57
	v_max_u32_e32 v69, v0, v70
	v_min_u32_e32 v0, v0, v70
	v_max_u32_e32 v70, v71, v1
	v_min_u32_e32 v1, v71, v1
	v_max_u32_e32 v71, v2, v72
	v_min_u32_e32 v2, v2, v72
	v_max_u32_e32 v72, v73, v3
	v_min_u32_e32 v3, v73, v3
	v_max_u32_e32 v65, v74, v51
	v_min_u32_e32 v51, v74, v51
	v_max_u32_e32 v74, v50, v58
	v_min_u32_e32 v50, v50, v58
	v_max_u32_e32 v58, v53, v59
	v_min_u32_e32 v53, v53, v59
	v_max_u32_e32 v59, v60, v52
	v_min_u32_e32 v52, v60, v52
; #define CE_DESC(a, b) do { const unsigned _mx = (a) > (b) ? (a) : (b), _mn = (a) > (b) ? (b) : (a); (a) = _mx; (b) = _mn; } while (0)
; __device__ __forceinline__ void sort16_desc(unsigned (&k)[16]) {
; #pragma unroll
;     for (int size = 2; size <= 16; size <<= 1)
; #pragma unroll
;         for (int stride = size >> 1; stride > 0; stride >>= 1)
; #pragma unroll
;             for (int i = 0; i < 16; ++i) { const int j = i ^ stride;
;                 if (j > i) { if ((i & size) == 0) CE_DESC(k[i], k[j]); else CE_DESC(k[j], k[i]); } }
; }
	v_max_u32_e32 v60, v61, v47
	v_min_u32_e32 v47, v61, v47
	v_max_u32_e32 v61, v46, v62
	v_min_u32_e32 v46, v46, v62
	v_max_u32_e32 v62, v49, v63
	v_min_u32_e32 v49, v49, v63
	v_max_u32_e32 v63, v64, v48
	v_min_u32_e32 v48, v64, v48
	v_max_u32_e32 v73, v82, v55
	v_min_u32_e32 v55, v82, v55
	v_max_u32_e32 v82, v54, v66
	v_min_u32_e32 v54, v54, v66
	v_max_u32_e32 v66, v57, v67
	v_min_u32_e32 v57, v57, v67
	v_max_u32_e32 v67, v68, v56
	v_min_u32_e32 v56, v68, v56
	v_max_u32_e32 v68, v69, v1
	v_min_u32_e32 v1, v69, v1
	v_max_u32_e32 v69, v0, v70
	v_min_u32_e32 v0, v0, v70
	v_max_u32_e32 v70, v3, v71
	v_min_u32_e32 v3, v3, v71
	v_max_u32_e32 v71, v72, v2
	v_min_u32_e32 v2, v72, v2
	v_max_u32_e32 v64, v65, v74
	v_min_u32_e32 v65, v65, v74
	v_max_u32_e32 v74, v51, v50
	v_min_u32_e32 v50, v51, v50
	v_max_u32_e32 v51, v52, v53
	v_min_u32_e32 v52, v52, v53
	v_max_u32_e32 v53, v59, v58
	v_min_u32_e32 v58, v59, v58
	v_max_u32_e32 v59, v60, v61
	v_min_u32_e32 v60, v60, v61
	v_max_u32_e32 v61, v47, v46
	v_min_u32_e32 v46, v47, v46
	v_max_u32_e32 v47, v48, v49
	v_min_u32_e32 v48, v48, v49
	v_max_u32_e32 v49, v63, v62
	v_min_u32_e32 v62, v63, v62
	v_max_u32_e32 v72, v73, v82
	v_min_u32_e32 v73, v73, v82
	v_max_u32_e32 v82, v55, v54
	v_min_u32_e32 v54, v55, v54
	v_max_u32_e32 v55, v56, v57
	v_min_u32_e32 v56, v56, v57
	v_max_u32_e32 v57, v67, v66
	v_min_u32_e32 v66, v67, v66
	v_max_u32_e32 v67, v68, v69
	v_min_u32_e32 v68, v68, v69
	v_max_u32_e32 v69, v1, v0
	v_min_u32_e32 v0, v1, v0
	v_max_u32_e32 v1, v2, v3
	v_min_u32_e32 v2, v2, v3
	v_max_u32_e32 v3, v71, v70
	v_min_u32_e32 v70, v71, v70
	v_max_u32_e32 v63, v64, v52
	v_min_u32_e32 v52, v64, v52
	v_max_u32_e32 v64, v65, v51
	v_min_u32_e32 v51, v65, v51
	v_max_u32_e32 v65, v74, v58
	v_min_u32_e32 v58, v74, v58
	v_max_u32_e32 v74, v50, v53
	v_min_u32_e32 v50, v50, v53
	v_max_u32_e32 v53, v48, v59
	v_min_u32_e32 v48, v48, v59
	v_max_u32_e32 v59, v47, v60
	v_min_u32_e32 v47, v47, v60
	v_max_u32_e32 v60, v62, v61
	v_min_u32_e32 v61, v62, v61
	v_max_u32_e32 v62, v49, v46
	v_min_u32_e32 v46, v49, v46
	v_max_u32_e32 v71, v72, v56
	v_min_u32_e32 v56, v72, v56
	v_max_u32_e32 v72, v73, v55
	v_min_u32_e32 v55, v73, v55
	v_max_u32_e32 v73, v82, v66
	v_min_u32_e32 v66, v82, v66
	v_max_u32_e32 v82, v54, v57
	v_min_u32_e32 v54, v54, v57
	v_max_u32_e32 v57, v2, v67
	v_min_u32_e32 v2, v2, v67
	v_max_u32_e32 v67, v1, v68
	v_min_u32_e32 v1, v1, v68
	v_max_u32_e32 v68, v70, v69
	v_min_u32_e32 v69, v70, v69
	v_max_u32_e32 v70, v3, v0
	v_min_u32_e32 v0, v3, v0
	v_max_u32_e32 v49, v63, v65
	v_min_u32_e32 v63, v63, v65
	v_max_u32_e32 v65, v64, v74
	v_min_u32_e32 v64, v64, v74
	v_max_u32_e32 v74, v52, v58
	v_min_u32_e32 v52, v52, v58
	v_max_u32_e32 v58, v51, v50
	v_min_u32_e32 v50, v51, v50
	v_max_u32_e32 v51, v61, v48
	v_min_u32_e32 v48, v61, v48
	v_max_u32_e32 v61, v46, v47
	v_min_u32_e32 v46, v46, v47
	v_max_u32_e32 v47, v60, v53
	v_min_u32_e32 v53, v60, v53
	v_max_u32_e32 v60, v62, v59
	v_min_u32_e32 v59, v62, v59
	v_max_u32_e32 v3, v71, v73
	v_min_u32_e32 v71, v71, v73
	v_max_u32_e32 v73, v72, v82
	v_min_u32_e32 v72, v72, v82
	v_max_u32_e32 v82, v56, v66
	v_min_u32_e32 v56, v56, v66
	v_max_u32_e32 v66, v55, v54
	v_min_u32_e32 v54, v55, v54
	v_max_u32_e32 v55, v69, v2
	v_min_u32_e32 v2, v69, v2
	v_max_u32_e32 v69, v0, v1
	v_min_u32_e32 v0, v0, v1
	v_max_u32_e32 v1, v68, v57
	v_min_u32_e32 v57, v68, v57
	v_max_u32_e32 v68, v70, v67
	v_min_u32_e32 v67, v70, v67
	v_max_u32_e32 v62, v49, v65
	v_min_u32_e32 v49, v49, v65
	v_max_u32_e32 v65, v63, v64
	v_min_u32_e32 v63, v63, v64
	v_max_u32_e32 v64, v74, v58
	v_min_u32_e32 v58, v74, v58
	v_max_u32_e32 v74, v52, v50
	v_min_u32_e32 v50, v52, v50
	v_max_u32_e32 v52, v46, v48
	v_min_u32_e32 v46, v46, v48
	v_max_u32_e32 v48, v61, v51
	v_min_u32_e32 v51, v61, v51
	v_max_u32_e32 v61, v59, v53
	v_min_u32_e32 v53, v59, v53
	v_max_u32_e32 v59, v60, v47
	v_min_u32_e32 v47, v60, v47
	v_max_u32_e32 v70, v3, v73
	v_min_u32_e32 v3, v3, v73
	v_max_u32_e32 v73, v71, v72
	v_min_u32_e32 v71, v71, v72
	v_max_u32_e32 v72, v82, v66
	v_min_u32_e32 v66, v82, v66
	v_max_u32_e32 v82, v56, v54
	v_min_u32_e32 v54, v56, v54
	v_max_u32_e32 v56, v0, v2
	v_min_u32_e32 v0, v0, v2
	v_max_u32_e32 v2, v69, v55
	v_min_u32_e32 v55, v69, v55
	v_max_u32_e32 v69, v67, v57
	v_min_u32_e32 v57, v67, v57
	v_max_u32_e32 v67, v68, v1
	v_min_u32_e32 v1, v68, v1
	v_max_u32_e32 v60, v62, v46
	v_min_u32_e32 v46, v62, v46
	v_max_u32_e32 v62, v49, v52
	v_min_u32_e32 v49, v49, v52
	v_max_u32_e32 v52, v65, v51
	v_min_u32_e32 v51, v65, v51
	v_max_u32_e32 v65, v63, v48
	v_min_u32_e32 v48, v63, v48
	v_max_u32_e32 v63, v64, v53
	v_min_u32_e32 v53, v64, v53
	v_max_u32_e32 v64, v58, v61
	v_min_u32_e32 v58, v58, v61
	v_max_u32_e32 v61, v74, v47
	v_min_u32_e32 v47, v74, v47
	v_max_u32_e32 v74, v50, v59
	v_min_u32_e32 v50, v50, v59
	v_max_u32_e32 v68, v70, v0
	v_min_u32_e32 v0, v70, v0
	v_max_u32_e32 v70, v3, v56
	v_min_u32_e32 v3, v3, v56
	v_max_u32_e32 v56, v73, v55
	v_min_u32_e32 v55, v73, v55
	v_max_u32_e32 v73, v71, v2
	v_min_u32_e32 v2, v71, v2
	v_max_u32_e32 v71, v72, v57
	v_min_u32_e32 v57, v72, v57
	v_max_u32_e32 v72, v66, v69
	v_min_u32_e32 v66, v66, v69
	v_max_u32_e32 v69, v82, v1
	v_min_u32_e32 v1, v82, v1
	v_max_u32_e32 v82, v54, v67
	v_min_u32_e32 v54, v54, v67
	v_max_u32_e32 v59, v60, v63
	v_min_u32_e32 v60, v60, v63
	v_max_u32_e32 v63, v62, v64
	v_min_u32_e32 v62, v62, v64
	v_max_u32_e32 v64, v52, v61
	v_min_u32_e32 v52, v52, v61
	v_max_u32_e32 v61, v65, v74
	v_min_u32_e32 v65, v65, v74
	v_max_u32_e32 v74, v46, v53
	v_min_u32_e32 v46, v46, v53
	v_max_u32_e32 v53, v49, v58
	v_min_u32_e32 v49, v49, v58
	v_max_u32_e32 v58, v51, v47
; #define CE_DESC(a, b) do { const unsigned _mx = (a) > (b) ? (a) : (b), _mn = (a) > (b) ? (b) : (a); (a) = _mx; (b) = _mn; } while (0)
; __device__ __forceinline__ void merge16(unsigned (&a)[16], const unsigned (&b)[16]) {
; #pragma unroll
;     for (int i = 0; i < 16; ++i) a[i] = a[i] > b[15 - i] ? a[i] : b[15 - i];
; #pragma unroll
;     for (int stride = 8; stride > 0; stride >>= 1)
; #pragma unroll
;         for (int i = 0; i < 16; ++i) { const int j = i ^ stride; if (j > i) CE_DESC(a[i], a[j]); }
; }
; __device__ __forceinline__ void peer_tile(const Args& A, LAS unsigned char* lds, int tile) {
;     ...
;                 sort16_desc(k0); sort16_desc(k1); merge16(k0, k1);
; #pragma unroll
;                 for (int msk = 16; msk <= 32; msk <<= 1) {
; #pragma unroll
;                     for (int i = 0; i < 16; ++i) k1[i] = (unsigned)__shfl_xor((int)k0[i], msk);
;                     merge16(k0, k1); }
	v_min_u32_e32 v47, v51, v47
	v_max_u32_e32 v51, v48, v50
	v_min_u32_e32 v48, v48, v50
	v_max_u32_e32 v67, v68, v71
	v_min_u32_e32 v68, v68, v71
	v_max_u32_e32 v71, v70, v72
	v_min_u32_e32 v70, v70, v72
	v_max_u32_e32 v72, v56, v69
	v_min_u32_e32 v56, v56, v69
	v_max_u32_e32 v69, v73, v82
	v_min_u32_e32 v73, v73, v82
	v_max_u32_e32 v82, v0, v57
	v_min_u32_e32 v0, v0, v57
	v_max_u32_e32 v57, v3, v66
	v_min_u32_e32 v3, v3, v66
	v_max_u32_e32 v66, v55, v1
	v_min_u32_e32 v1, v55, v1
	v_max_u32_e32 v55, v2, v54
	v_min_u32_e32 v2, v2, v54
	v_max_u32_e32 v50, v59, v64
	v_min_u32_e32 v59, v59, v64
	v_max_u32_e32 v64, v63, v61
	v_min_u32_e32 v61, v63, v61
	v_max_u32_e32 v63, v60, v52
	v_min_u32_e32 v52, v60, v52
	v_max_u32_e32 v60, v62, v65
	v_min_u32_e32 v62, v62, v65
	v_max_u32_e32 v65, v74, v58
	v_min_u32_e32 v58, v74, v58
	v_max_u32_e32 v74, v53, v51
	v_min_u32_e32 v51, v53, v51
	v_max_u32_e32 v53, v46, v47
	v_min_u32_e32 v46, v46, v47
	v_max_u32_e32 v47, v49, v48
	v_min_u32_e32 v48, v49, v48
	v_max_u32_e32 v54, v67, v72
	v_min_u32_e32 v67, v67, v72
	v_max_u32_e32 v72, v71, v69
	v_min_u32_e32 v69, v71, v69
	v_max_u32_e32 v71, v68, v56
	v_min_u32_e32 v56, v68, v56
	v_max_u32_e32 v68, v70, v73
	v_min_u32_e32 v70, v70, v73
	v_max_u32_e32 v73, v82, v66
	v_min_u32_e32 v66, v82, v66
	v_max_u32_e32 v82, v57, v55
	v_min_u32_e32 v55, v57, v55
	v_max_u32_e32 v57, v0, v1
	v_min_u32_e32 v0, v0, v1
	v_max_u32_e32 v1, v3, v2
	v_min_u32_e32 v2, v3, v2
	v_min_u32_e32 v49, v50, v64
	v_min_u32_e32 v75, v59, v61
	v_min_u32_e32 v76, v63, v60
	v_min_u32_e32 v77, v52, v62
	v_min_u32_e32 v78, v65, v74
	v_min_u32_e32 v79, v58, v51
	v_min_u32_e32 v80, v53, v47
	v_min_u32_e32 v81, v46, v48
	v_min_u32_e32 v3, v54, v72
	v_min_u32_e32 v83, v67, v69
	v_min_u32_e32 v84, v71, v68
	v_min_u32_e32 v85, v56, v70
	v_min_u32_e32 v86, v73, v82
	v_min_u32_e32 v87, v66, v55
	v_min_u32_e32 v88, v57, v1
	v_min_u32_e32 v89, v0, v2
	v_max3_u32 v50, v50, v64, v89
	v_max3_u32 v0, v49, v0, v2
	v_max3_u32 v2, v59, v61, v88
	v_max3_u32 v1, v75, v57, v1
	v_max3_u32 v49, v63, v60, v87
	v_max3_u32 v55, v76, v66, v55
	v_max3_u32 v52, v52, v62, v86
	v_max3_u32 v57, v77, v73, v82
	v_max3_u32 v59, v65, v74, v85
	v_max3_u32 v56, v78, v56, v70
	v_max3_u32 v51, v58, v51, v84
	v_max3_u32 v58, v79, v71, v68
	v_max3_u32 v47, v53, v47, v83
	v_max3_u32 v53, v80, v67, v69
	v_max3_u32 v3, v46, v48, v3
	v_max3_u32 v46, v81, v54, v72
	v_max_u32_e32 v48, v50, v59
	v_min_u32_e32 v50, v50, v59
	v_max_u32_e32 v54, v0, v56
	v_min_u32_e32 v0, v0, v56
	v_max_u32_e32 v56, v2, v51
	v_min_u32_e32 v2, v2, v51
	v_max_u32_e32 v51, v1, v58
	v_min_u32_e32 v1, v1, v58
	v_max_u32_e32 v58, v49, v47
	v_min_u32_e32 v47, v49, v47
	v_max_u32_e32 v49, v55, v53
	v_min_u32_e32 v53, v55, v53
	v_max_u32_e32 v55, v52, v3
	v_min_u32_e32 v3, v52, v3
	v_max_u32_e32 v52, v57, v46
	v_min_u32_e32 v46, v57, v46
	v_max_u32_e32 v57, v48, v58
	v_min_u32_e32 v48, v48, v58
	v_max_u32_e32 v58, v54, v49
	v_min_u32_e32 v49, v54, v49
	v_max_u32_e32 v54, v56, v55
	v_min_u32_e32 v55, v56, v55
	v_max_u32_e32 v56, v51, v52
	v_min_u32_e32 v51, v51, v52
	v_max_u32_e32 v52, v50, v47
	v_min_u32_e32 v47, v50, v47
	v_max_u32_e32 v50, v0, v53
	v_min_u32_e32 v0, v0, v53
	v_max_u32_e32 v53, v2, v3
	v_min_u32_e32 v2, v2, v3
	v_max_u32_e32 v3, v1, v46
	v_min_u32_e32 v1, v1, v46
	v_max_u32_e32 v46, v57, v54
	v_min_u32_e32 v54, v57, v54
	v_max_u32_e32 v57, v58, v56
	v_min_u32_e32 v56, v58, v56
	v_max_u32_e32 v58, v48, v55
	v_min_u32_e32 v48, v48, v55
	v_max_u32_e32 v55, v49, v51
	v_min_u32_e32 v49, v49, v51
	v_max_u32_e32 v51, v52, v53
	v_min_u32_e32 v52, v52, v53
	v_max_u32_e32 v53, v50, v3
	v_min_u32_e32 v3, v50, v3
	v_max_u32_e32 v50, v47, v2
	v_min_u32_e32 v2, v47, v2
	v_max_u32_e32 v47, v0, v1
	v_min_u32_e32 v0, v0, v1
	v_max_u32_e32 v1, v46, v57
	v_min_u32_e32 v46, v46, v57
	v_max_u32_e32 v57, v54, v56
	v_min_u32_e32 v54, v54, v56
	v_max_u32_e32 v56, v58, v55
	v_min_u32_e32 v55, v58, v55
	v_max_u32_e32 v58, v48, v49
	v_min_u32_e32 v48, v48, v49
	v_max_u32_e32 v49, v51, v53
	v_min_u32_e32 v51, v51, v53
	v_max_u32_e32 v53, v52, v3
	v_min_u32_e32 v3, v52, v3
	v_max_u32_e32 v52, v50, v47
	v_min_u32_e32 v47, v50, v47
	v_max_u32_e32 v50, v2, v0
	v_min_u32_e32 v0, v2, v0
	ds_bpermute_b32 v2, v27, v1
	ds_bpermute_b32 v59, v27, v46
	ds_bpermute_b32 v60, v27, v57
	ds_bpermute_b32 v61, v27, v54
	ds_bpermute_b32 v62, v27, v56
	ds_bpermute_b32 v63, v27, v55
	ds_bpermute_b32 v64, v27, v58
	ds_bpermute_b32 v65, v27, v48
	ds_bpermute_b32 v66, v27, v49
	ds_bpermute_b32 v67, v27, v51
	ds_bpermute_b32 v68, v27, v53
	ds_bpermute_b32 v69, v27, v0
	ds_bpermute_b32 v70, v27, v50
	ds_bpermute_b32 v71, v27, v47
	ds_bpermute_b32 v72, v27, v52
	ds_bpermute_b32 v73, v27, v3
	s_waitcnt lgkmcnt(4)
	v_max_u32_e32 v1, v1, v69
	s_waitcnt lgkmcnt(3)
	v_max_u32_e32 v46, v46, v70
	s_waitcnt lgkmcnt(2)
	v_max_u32_e32 v57, v57, v71
	s_waitcnt lgkmcnt(1)
	v_max_u32_e32 v54, v54, v72
	s_waitcnt lgkmcnt(0)
; #define CE_DESC(a, b) do { const unsigned _mx = (a) > (b) ? (a) : (b), _mn = (a) > (b) ? (b) : (a); (a) = _mx; (b) = _mn; } while (0)
; __device__ __forceinline__ void merge16(unsigned (&a)[16], const unsigned (&b)[16]) {
; #pragma unroll
;     for (int i = 0; i < 16; ++i) a[i] = a[i] > b[15 - i] ? a[i] : b[15 - i];
; #pragma unroll
;     for (int stride = 8; stride > 0; stride >>= 1)
; #pragma unroll
;         for (int i = 0; i < 16; ++i) { const int j = i ^ stride; if (j > i) CE_DESC(a[i], a[j]); }
; }
; __device__ __forceinline__ void peer_tile(const Args& A, LAS unsigned char* lds, int tile) {
;     ...
;                 { const bf16_t* sp = QRY + m * 2048 + hp * 128 + 32 * g;
;                   const u32x4 s0 = *(const u32x4*)sp, s1 = *(const u32x4*)(sp + 8), s2 = *(const u32x4*)(sp + 16), s3 = *(const u32x4*)(sp + 24);
;                   const unsigned sw[16] = {s0.x, s0.y, s0.z, s0.w, s1.x, s1.y, s1.z, s1.w, s2.x, s2.y, s2.z, s2.w, s3.x, s3.y, s3.z, s3.w};
;     ...
;                 for (int msk = 16; msk <= 32; msk <<= 1) {
; #pragma unroll
;                     for (int i = 0; i < 16; ++i) k1[i] = (unsigned)__shfl_xor((int)k0[i], msk);
;                     merge16(k0, k1); }
	v_max_u32_e32 v56, v56, v73
	v_max_u32_e32 v55, v55, v68
	v_max_u32_e32 v58, v58, v67
	v_max_u32_e32 v48, v48, v66
	v_max_u32_e32 v49, v49, v65
	v_max_u32_e32 v51, v51, v64
	v_max_u32_e32 v53, v53, v63
	v_max_u32_e32 v3, v3, v62
	v_max_u32_e32 v52, v52, v61
	v_max_u32_e32 v47, v47, v60
	v_max_u32_e32 v50, v50, v59
	v_max_u32_e32 v0, v0, v2
	v_max_u32_e32 v2, v1, v49
	v_min_u32_e32 v1, v1, v49
	v_max_u32_e32 v49, v46, v51
	v_min_u32_e32 v46, v46, v51
	v_max_u32_e32 v51, v57, v53
	v_min_u32_e32 v53, v57, v53
	v_max_u32_e32 v57, v54, v3
	v_min_u32_e32 v3, v54, v3
	v_max_u32_e32 v54, v56, v52
	v_min_u32_e32 v52, v56, v52
	v_max_u32_e32 v56, v55, v47
	v_min_u32_e32 v47, v55, v47
	v_max_u32_e32 v55, v58, v50
	v_min_u32_e32 v50, v58, v50
	v_max_u32_e32 v58, v48, v0
	v_min_u32_e32 v0, v48, v0
	v_max_u32_e32 v48, v2, v54
	v_min_u32_e32 v2, v2, v54
	v_max_u32_e32 v54, v49, v56
	v_min_u32_e32 v49, v49, v56
	v_max_u32_e32 v56, v51, v55
	v_min_u32_e32 v51, v51, v55
	v_max_u32_e32 v55, v57, v58
	v_min_u32_e32 v57, v57, v58
	v_max_u32_e32 v58, v1, v52
	v_min_u32_e32 v1, v1, v52
	v_max_u32_e32 v52, v46, v47
	v_min_u32_e32 v46, v46, v47
	v_max_u32_e32 v47, v53, v50
	v_min_u32_e32 v50, v53, v50
	v_max_u32_e32 v53, v3, v0
	v_min_u32_e32 v0, v3, v0
	v_max_u32_e32 v3, v48, v56
	v_min_u32_e32 v48, v48, v56
	v_max_u32_e32 v56, v54, v55
	v_min_u32_e32 v54, v54, v55
	v_max_u32_e32 v55, v2, v51
	v_min_u32_e32 v2, v2, v51
	v_max_u32_e32 v51, v49, v57
	v_min_u32_e32 v49, v49, v57
	v_max_u32_e32 v57, v58, v47
	v_min_u32_e32 v47, v58, v47
	v_max_u32_e32 v58, v52, v53
	v_min_u32_e32 v52, v52, v53
	v_max_u32_e32 v53, v1, v50
	v_min_u32_e32 v1, v1, v50
	v_max_u32_e32 v50, v46, v0
	v_min_u32_e32 v0, v46, v0
	v_max_u32_e32 v46, v3, v56
	v_min_u32_e32 v3, v3, v56
	v_max_u32_e32 v56, v48, v54
	v_min_u32_e32 v48, v48, v54
	v_max_u32_e32 v54, v55, v51
	v_min_u32_e32 v51, v55, v51
	v_max_u32_e32 v55, v2, v49
	v_min_u32_e32 v2, v2, v49
	v_max_u32_e32 v49, v57, v58
	v_min_u32_e32 v57, v57, v58
	v_max_u32_e32 v58, v47, v52
	v_min_u32_e32 v47, v47, v52
	v_max_u32_e32 v52, v53, v50
	v_min_u32_e32 v50, v53, v50
	v_max_u32_e32 v53, v1, v0
	v_min_u32_e32 v0, v1, v0
	ds_bpermute_b32 v62, v29, v0
	ds_bpermute_b32 v1, v29, v46
	ds_bpermute_b32 v59, v29, v3
	ds_bpermute_b32 v60, v29, v56
	ds_bpermute_b32 v61, v29, v48
	s_waitcnt lgkmcnt(4)
	v_max_u32_e32 v46, v46, v62
	global_load_dwordx4 v[62:65], v[4:5], off offset:528
	global_load_dwordx4 v[66:69], v[4:5], off offset:512
	ds_bpermute_b32 v70, v29, v54
	ds_bpermute_b32 v71, v29, v51
	ds_bpermute_b32 v72, v29, v55
	ds_bpermute_b32 v73, v29, v2
	ds_bpermute_b32 v74, v29, v49
	ds_bpermute_b32 v75, v29, v57
	ds_bpermute_b32 v76, v29, v58
	ds_bpermute_b32 v77, v29, v47
	ds_bpermute_b32 v78, v29, v52
	ds_bpermute_b32 v79, v29, v53
	ds_bpermute_b32 v80, v29, v50
	s_waitcnt lgkmcnt(4)
	v_max_u32_e32 v51, v51, v76
	s_waitcnt lgkmcnt(3)
	v_max_u32_e32 v54, v54, v77
	s_waitcnt lgkmcnt(2)
	v_max_u32_e32 v48, v48, v78
	s_waitcnt lgkmcnt(1)
	v_max_u32_e32 v3, v3, v79
	s_waitcnt lgkmcnt(0)
	v_max_u32_e32 v56, v56, v80
	v_max_u32_e32 v55, v55, v75
	v_max_u32_e32 v2, v2, v74
	v_max_u32_e32 v49, v49, v73
	v_max_u32_e32 v57, v57, v72
	v_max_u32_e32 v58, v58, v71
	v_max_u32_e32 v47, v47, v70
	v_max_u32_e32 v52, v52, v61
	v_max_u32_e32 v50, v50, v60
	v_max_u32_e32 v53, v53, v59
	v_max_u32_e32 v0, v0, v1
	v_max_u32_e32 v1, v46, v49
	v_min_u32_e32 v46, v46, v49
	v_max_u32_e32 v49, v3, v57
	v_min_u32_e32 v3, v3, v57
	v_max_u32_e32 v57, v56, v58
	v_min_u32_e32 v56, v56, v58
	v_max_u32_e32 v58, v48, v47
	v_min_u32_e32 v47, v48, v47
	v_max_u32_e32 v48, v54, v52
	v_min_u32_e32 v52, v54, v52
	v_max_u32_e32 v54, v51, v50
	v_min_u32_e32 v50, v51, v50
	v_max_u32_e32 v51, v55, v53
	v_min_u32_e32 v53, v55, v53
	v_max_u32_e32 v55, v2, v0
	v_min_u32_e32 v0, v2, v0
	v_max_u32_e32 v2, v1, v48
	v_min_u32_e32 v1, v1, v48
	v_max_u32_e32 v48, v49, v54
	v_min_u32_e32 v49, v49, v54
	v_max_u32_e32 v54, v57, v51
	v_min_u32_e32 v51, v57, v51
	v_max_u32_e32 v57, v58, v55
	v_min_u32_e32 v55, v58, v55
	v_max_u32_e32 v58, v46, v52
	v_min_u32_e32 v46, v46, v52
	v_max_u32_e32 v52, v3, v50
	v_min_u32_e32 v3, v3, v50
	v_max_u32_e32 v50, v56, v53
	v_min_u32_e32 v53, v56, v53
	v_max_u32_e32 v56, v47, v0
	v_min_u32_e32 v0, v47, v0
	v_max_u32_e32 v47, v2, v54
	v_min_u32_e32 v2, v2, v54
	v_max_u32_e32 v54, v48, v57
	v_min_u32_e32 v48, v48, v57
	v_max_u32_e32 v70, v1, v51
	v_min_u32_e32 v1, v1, v51
	v_max_u32_e32 v51, v49, v55
	v_min_u32_e32 v49, v49, v55
	v_max_u32_e32 v71, v58, v50
	v_min_u32_e32 v50, v58, v50
	v_max_u32_e32 v72, v52, v56
	v_min_u32_e32 v73, v52, v56
	v_max_u32_e32 v74, v46, v53
	v_min_u32_e32 v46, v46, v53
	v_max_u32_e32 v75, v3, v0
	v_min_u32_e32 v0, v3, v0
	v_max_u32_e32 v61, v47, v54
	v_min_u32_e32 v60, v47, v54
	v_max_u32_e32 v59, v2, v48
	v_min_u32_e32 v58, v2, v48
	v_max_u32_e32 v57, v70, v51
	v_min_u32_e32 v56, v70, v51
	v_max_u32_e32 v55, v1, v49
	v_min_u32_e32 v54, v1, v49
	v_max_u32_e32 v53, v71, v72
	v_min_u32_e32 v52, v71, v72
	v_max_u32_e32 v51, v50, v73
	v_min_u32_e32 v50, v50, v73
	v_max_u32_e32 v47, v46, v0
	v_min_u32_e32 v46, v46, v0
	global_load_dwordx4 v[0:3], v[4:5], off offset:560
	global_load_dwordx4 v[70:73], v[4:5], off offset:544
	v_max_u32_e32 v49, v74, v75
	v_min_u32_e32 v48, v74, v75
	s_waitcnt vmcnt(2)
; __device__ __forceinline__ unsigned f2key(float f) { const unsigned u = __float_as_uint(f); return (u & 0x80000000u) ? ~u : (u | 0x80000000u); }
; __device__ __forceinline__ void peer_tile(const Args& A, LAS unsigned char* lds, int tile) {
;     ...
;                 { const bf16_t* sp = QRY + m * 2048 + hp * 128 + 32 * g;
;                   const u32x4 s0 = *(const u32x4*)sp, s1 = *(const u32x4*)(sp + 8), s2 = *(const u32x4*)(sp + 16), s3 = *(const u32x4*)(sp + 24);
;                   const unsigned sw[16] = {s0.x, s0.y, s0.z, s0.w, s1.x, s1.y, s1.z, s1.w, s2.x, s2.y, s2.z, s2.w, s3.x, s3.y, s3.z, s3.w};
; #pragma unroll
;                   for (int i = 0; i < 16; ++i) {
;                       const float lo = (float)__builtin_bit_cast(_Float16, (unsigned short)(sw[i] & 0xffffu)), hi = (float)__builtin_bit_cast(_Float16, (unsigned short)(sw[i] >> 16));
;                       const unsigned klo = (f2key(lo) & ~127u) | (unsigned)(127 - (32 * g + 2 * i)), khi = (f2key(hi) & ~127u) | (unsigned)(127 - (32 * g + 2 * i + 1));
;                       if (i < 8) { k0[2 * i] = klo; k0[2 * i + 1] = khi; } else { k1[2 * (i - 8)] = klo; k1[2 * (i - 8) + 1] = khi; } } }
	v_cvt_f32_f16_sdwa v74, v66 dst_sel:DWORD dst_unused:UNUSED_PAD src0_sel:WORD_1
	v_cvt_f32_f16_e32 v66, v66
	v_not_b32_e32 v75, v74
	v_or_b32_e32 v76, 0x80000000, v74
	v_cmp_gt_i32_e32 vcc, 0, v74
	s_nop 1
	v_cndmask_b32_e32 v74, v76, v75, vcc
	v_not_b32_e32 v75, v66
	v_or_b32_e32 v76, 0x80000000, v66
	v_cmp_gt_i32_e32 vcc, 0, v66
	v_and_b32_e32 v74, 0xffffff80, v74
	v_sub_u32_e32 v74, v74, v15
	v_cndmask_b32_e32 v66, v76, v75, vcc
	v_cvt_f32_f16_sdwa v75, v67 dst_sel:DWORD dst_unused:UNUSED_PAD src0_sel:WORD_1
	v_cvt_f32_f16_e32 v67, v67
	v_and_b32_e32 v66, 0xffffff80, v66
	v_sub_u32_e32 v66, v66, v15
	v_not_b32_e32 v76, v75
	v_or_b32_e32 v77, 0x80000000, v75
	v_cmp_gt_i32_e32 vcc, 0, v75
	v_add_u32_e32 v74, 0x7e, v74
	v_add_u32_e32 v66, 0x7f, v66
	v_cndmask_b32_e32 v75, v77, v76, vcc
	v_not_b32_e32 v76, v67
	v_or_b32_e32 v77, 0x80000000, v67
	v_cmp_gt_i32_e32 vcc, 0, v67
	v_and_b32_e32 v75, 0xffffff80, v75
	v_sub_u32_e32 v75, v75, v14
	v_cndmask_b32_e32 v67, v77, v76, vcc
	v_cvt_f32_f16_sdwa v76, v68 dst_sel:DWORD dst_unused:UNUSED_PAD src0_sel:WORD_1
	v_cvt_f32_f16_e32 v68, v68
	v_and_b32_e32 v67, 0xffffff80, v67
	v_sub_u32_e32 v67, v67, v14
	v_not_b32_e32 v77, v76
	v_or_b32_e32 v78, 0x80000000, v76
	v_cmp_gt_i32_e32 vcc, 0, v76
	v_add_u32_e32 v75, 0x7e, v75
	v_add_u32_e32 v67, 0x7f, v67
	v_cndmask_b32_e32 v76, v78, v77, vcc
	v_not_b32_e32 v77, v68
	v_or_b32_e32 v78, 0x80000000, v68
	v_cmp_gt_i32_e32 vcc, 0, v68
	v_and_b32_e32 v76, 0xffffff80, v76
	v_sub_u32_e32 v76, v76, v12
	v_cndmask_b32_e32 v68, v78, v77, vcc
	v_cvt_f32_f16_sdwa v77, v69 dst_sel:DWORD dst_unused:UNUSED_PAD src0_sel:WORD_1
	v_cvt_f32_f16_e32 v69, v69
	v_and_b32_e32 v68, 0xffffff80, v68
	v_sub_u32_e32 v68, v68, v12
	v_not_b32_e32 v78, v77
	v_or_b32_e32 v79, 0x80000000, v77
	v_cmp_gt_i32_e32 vcc, 0, v77
	v_add_u32_e32 v76, 0x7e, v76
	v_add_u32_e32 v68, 0x7f, v68
	v_cndmask_b32_e32 v77, v79, v78, vcc
	v_not_b32_e32 v78, v69
	v_or_b32_e32 v79, 0x80000000, v69
	v_cmp_gt_i32_e32 vcc, 0, v69
	v_and_b32_e32 v77, 0xffffff80, v77
	v_sub_u32_e32 v77, v77, v10
	v_cndmask_b32_e32 v69, v79, v78, vcc
	v_cvt_f32_f16_sdwa v78, v62 dst_sel:DWORD dst_unused:UNUSED_PAD src0_sel:WORD_1
	v_cvt_f32_f16_e32 v62, v62
	v_and_b32_e32 v69, 0xffffff80, v69
	v_sub_u32_e32 v69, v69, v10
	v_not_b32_e32 v79, v78
	v_or_b32_e32 v80, 0x80000000, v78
	v_cmp_gt_i32_e32 vcc, 0, v78
	v_add_u32_e32 v77, 0x7e, v77
	v_add_u32_e32 v69, 0x7f, v69
	v_cndmask_b32_e32 v78, v80, v79, vcc
	v_not_b32_e32 v79, v62
	v_or_b32_e32 v80, 0x80000000, v62
	v_cmp_gt_i32_e32 vcc, 0, v62
	v_and_b32_e32 v78, 0xffffff80, v78
	v_sub_u32_e32 v78, v78, v8
	v_cndmask_b32_e32 v62, v80, v79, vcc
	v_cvt_f32_f16_sdwa v79, v63 dst_sel:DWORD dst_unused:UNUSED_PAD src0_sel:WORD_1
	v_cvt_f32_f16_e32 v63, v63
	v_and_b32_e32 v62, 0xffffff80, v62
	v_sub_u32_e32 v62, v62, v8
	v_not_b32_e32 v80, v79
	v_or_b32_e32 v81, 0x80000000, v79
	v_cmp_gt_i32_e32 vcc, 0, v79
	v_add_u32_e32 v78, 0x7e, v78
	v_add_u32_e32 v62, 0x7f, v62
	v_cndmask_b32_e32 v79, v81, v80, vcc
	v_not_b32_e32 v80, v63
	v_or_b32_e32 v81, 0x80000000, v63
	v_cmp_gt_i32_e32 vcc, 0, v63
	v_and_b32_e32 v79, 0xffffff80, v79
	v_sub_u32_e32 v79, v79, v16
	v_cndmask_b32_e32 v63, v81, v80, vcc
	v_cvt_f32_f16_sdwa v80, v64 dst_sel:DWORD dst_unused:UNUSED_PAD src0_sel:WORD_1
	v_cvt_f32_f16_e32 v64, v64
	v_and_b32_e32 v63, 0xffffff80, v63
	v_sub_u32_e32 v63, v63, v16
	v_not_b32_e32 v81, v80
	v_or_b32_e32 v82, 0x80000000, v80
	v_cmp_gt_i32_e32 vcc, 0, v80
	v_add_u32_e32 v79, 0x7e, v79
	v_add_u32_e32 v63, 0x7f, v63
	v_cndmask_b32_e32 v80, v82, v81, vcc
	v_not_b32_e32 v81, v64
	v_or_b32_e32 v82, 0x80000000, v64
	v_cmp_gt_i32_e32 vcc, 0, v64
	v_and_b32_e32 v80, 0xffffff80, v80
	v_sub_u32_e32 v80, v80, v17
	v_cndmask_b32_e32 v64, v82, v81, vcc
	v_cvt_f32_f16_sdwa v81, v65 dst_sel:DWORD dst_unused:UNUSED_PAD src0_sel:WORD_1
	v_cvt_f32_f16_e32 v65, v65
	v_and_b32_e32 v64, 0xffffff80, v64
	v_sub_u32_e32 v64, v64, v17
	v_not_b32_e32 v82, v81
	v_or_b32_e32 v83, 0x80000000, v81
	v_cmp_gt_i32_e32 vcc, 0, v81
	v_add_u32_e32 v80, 0x7e, v80
	v_add_u32_e32 v64, 0x7f, v64
	v_cndmask_b32_e32 v81, v83, v82, vcc
	v_not_b32_e32 v82, v65
	v_or_b32_e32 v83, 0x80000000, v65
	v_cmp_gt_i32_e32 vcc, 0, v65
	v_and_b32_e32 v81, 0xffffff80, v81
	v_sub_u32_e32 v81, v81, v18
	v_cndmask_b32_e32 v65, v83, v82, vcc
	s_waitcnt vmcnt(0)
; __device__ __forceinline__ unsigned f2key(float f) { const unsigned u = __float_as_uint(f); return (u & 0x80000000u) ? ~u : (u | 0x80000000u); }
; #define CE_DESC(a, b) do { const unsigned _mx = (a) > (b) ? (a) : (b), _mn = (a) > (b) ? (b) : (a); (a) = _mx; (b) = _mn; } while (0)
; __device__ __forceinline__ void sort16_desc(unsigned (&k)[16]) {
; #pragma unroll
;     for (int size = 2; size <= 16; size <<= 1)
; #pragma unroll
;         for (int stride = size >> 1; stride > 0; stride >>= 1)
; #pragma unroll
;             for (int i = 0; i < 16; ++i) { const int j = i ^ stride;
;                 if (j > i) { if ((i & size) == 0) CE_DESC(k[i], k[j]); else CE_DESC(k[j], k[i]); } }
; }
; __device__ __forceinline__ void peer_tile(const Args& A, LAS unsigned char* lds, int tile) {
;     ...
;                 { const bf16_t* sp = QRY + m * 2048 + hp * 128 + 32 * g;
;                   const u32x4 s0 = *(const u32x4*)sp, s1 = *(const u32x4*)(sp + 8), s2 = *(const u32x4*)(sp + 16), s3 = *(const u32x4*)(sp + 24);
;                   const unsigned sw[16] = {s0.x, s0.y, s0.z, s0.w, s1.x, s1.y, s1.z, s1.w, s2.x, s2.y, s2.z, s2.w, s3.x, s3.y, s3.z, s3.w};
; #pragma unroll
;                   for (int i = 0; i < 16; ++i) {
;                       const float lo = (float)__builtin_bit_cast(_Float16, (unsigned short)(sw[i] & 0xffffu)), hi = (float)__builtin_bit_cast(_Float16, (unsigned short)(sw[i] >> 16));
;                       const unsigned klo = (f2key(lo) & ~127u) | (unsigned)(127 - (32 * g + 2 * i)), khi = (f2key(hi) & ~127u) | (unsigned)(127 - (32 * g + 2 * i + 1));
;                       if (i < 8) { k0[2 * i] = klo; k0[2 * i + 1] = khi; } else { k1[2 * (i - 8)] = klo; k1[2 * (i - 8) + 1] = khi; } } }
	v_cvt_f32_f16_sdwa v82, v70 dst_sel:DWORD dst_unused:UNUSED_PAD src0_sel:WORD_1
	v_cvt_f32_f16_e32 v70, v70
	v_and_b32_e32 v65, 0xffffff80, v65
	v_sub_u32_e32 v65, v65, v18
	v_not_b32_e32 v83, v82
	v_or_b32_e32 v84, 0x80000000, v82
	v_cmp_gt_i32_e32 vcc, 0, v82
	v_add_u32_e32 v81, 0x7e, v81
	v_add_u32_e32 v65, 0x7f, v65
	v_cndmask_b32_e32 v82, v84, v83, vcc
	v_not_b32_e32 v83, v70
	v_or_b32_e32 v84, 0x80000000, v70
	v_cmp_gt_i32_e32 vcc, 0, v70
	v_and_b32_e32 v82, 0xffffff80, v82
	v_sub_u32_e32 v82, v82, v20
	v_cndmask_b32_e32 v70, v84, v83, vcc
	v_cvt_f32_f16_sdwa v83, v71 dst_sel:DWORD dst_unused:UNUSED_PAD src0_sel:WORD_1
	v_cvt_f32_f16_e32 v71, v71
	v_and_b32_e32 v70, 0xffffff80, v70
	v_sub_u32_e32 v70, v70, v20
	v_not_b32_e32 v84, v83
	v_or_b32_e32 v85, 0x80000000, v83
	v_cmp_gt_i32_e32 vcc, 0, v83
	v_add_u32_e32 v82, 0x7e, v82
	v_add_u32_e32 v70, 0x7f, v70
	v_cndmask_b32_e32 v83, v85, v84, vcc
	v_not_b32_e32 v84, v71
	v_or_b32_e32 v85, 0x80000000, v71
	v_cmp_gt_i32_e32 vcc, 0, v71
	v_and_b32_e32 v83, 0xffffff80, v83
	v_sub_u32_e32 v83, v83, v21
	v_cndmask_b32_e32 v71, v85, v84, vcc
	v_cvt_f32_f16_sdwa v84, v72 dst_sel:DWORD dst_unused:UNUSED_PAD src0_sel:WORD_1
	v_cvt_f32_f16_e32 v72, v72
	v_and_b32_e32 v71, 0xffffff80, v71
	v_sub_u32_e32 v71, v71, v21
	v_not_b32_e32 v85, v84
	v_or_b32_e32 v86, 0x80000000, v84
	v_cmp_gt_i32_e32 vcc, 0, v84
	v_add_u32_e32 v83, 0x7e, v83
	v_add_u32_e32 v71, 0x7f, v71
	v_cndmask_b32_e32 v84, v86, v85, vcc
	v_not_b32_e32 v85, v72
	v_or_b32_e32 v86, 0x80000000, v72
	v_cmp_gt_i32_e32 vcc, 0, v72
	v_and_b32_e32 v84, 0xffffff80, v84
	v_sub_u32_e32 v84, v84, v22
	v_cndmask_b32_e32 v72, v86, v85, vcc
	v_cvt_f32_f16_sdwa v85, v73 dst_sel:DWORD dst_unused:UNUSED_PAD src0_sel:WORD_1
	v_cvt_f32_f16_e32 v73, v73
	v_and_b32_e32 v72, 0xffffff80, v72
	v_sub_u32_e32 v72, v72, v22
	v_not_b32_e32 v86, v85
	v_or_b32_e32 v87, 0x80000000, v85
	v_cmp_gt_i32_e32 vcc, 0, v85
	v_add_u32_e32 v84, 0x7e, v84
	v_add_u32_e32 v72, 0x7f, v72
	v_cndmask_b32_e32 v85, v87, v86, vcc
	v_not_b32_e32 v86, v73
	v_or_b32_e32 v87, 0x80000000, v73
	v_cmp_gt_i32_e32 vcc, 0, v73
	v_and_b32_e32 v85, 0xffffff80, v85
	v_sub_u32_e32 v85, v85, v23
	v_cndmask_b32_e32 v73, v87, v86, vcc
	v_cvt_f32_f16_sdwa v86, v0 dst_sel:DWORD dst_unused:UNUSED_PAD src0_sel:WORD_1
	v_cvt_f32_f16_e32 v0, v0
	v_and_b32_e32 v73, 0xffffff80, v73
	v_sub_u32_e32 v73, v73, v23
	v_not_b32_e32 v87, v86
	v_or_b32_e32 v88, 0x80000000, v86
	v_cmp_gt_i32_e32 vcc, 0, v86
	v_add_u32_e32 v85, 0x7e, v85
	v_add_u32_e32 v73, 0x7f, v73
	v_cndmask_b32_e32 v86, v88, v87, vcc
	v_not_b32_e32 v87, v0
	v_or_b32_e32 v88, 0x80000000, v0
	v_cmp_gt_i32_e32 vcc, 0, v0
	v_and_b32_e32 v86, 0xffffff80, v86
	v_sub_u32_e32 v86, v86, v24
	v_cndmask_b32_e32 v0, v88, v87, vcc
	v_cvt_f32_f16_sdwa v87, v1 dst_sel:DWORD dst_unused:UNUSED_PAD src0_sel:WORD_1
	v_cvt_f32_f16_e32 v1, v1
	v_and_b32_e32 v0, 0xffffff80, v0
	v_sub_u32_e32 v0, v0, v24
	v_not_b32_e32 v88, v87
	v_or_b32_e32 v89, 0x80000000, v87
	v_cmp_gt_i32_e32 vcc, 0, v87
	v_add_u32_e32 v86, 0x7e, v86
	v_add_u32_e32 v0, 0x7f, v0
	v_cndmask_b32_e32 v87, v89, v88, vcc
	v_not_b32_e32 v88, v1
	v_or_b32_e32 v89, 0x80000000, v1
	v_cmp_gt_i32_e32 vcc, 0, v1
	v_and_b32_e32 v87, 0xffffff80, v87
	v_sub_u32_e32 v87, v87, v25
	v_cndmask_b32_e32 v1, v89, v88, vcc
	v_cvt_f32_f16_sdwa v88, v2 dst_sel:DWORD dst_unused:UNUSED_PAD src0_sel:WORD_1
	v_cvt_f32_f16_e32 v2, v2
	v_and_b32_e32 v1, 0xffffff80, v1
	v_sub_u32_e32 v1, v1, v25
	v_not_b32_e32 v89, v88
	v_or_b32_e32 v90, 0x80000000, v88
	v_cmp_gt_i32_e32 vcc, 0, v88
	v_add_u32_e32 v87, 0x7e, v87
	v_add_u32_e32 v1, 0x7f, v1
	v_cndmask_b32_e32 v88, v90, v89, vcc
	v_not_b32_e32 v89, v2
	v_or_b32_e32 v90, 0x80000000, v2
	v_cmp_gt_i32_e32 vcc, 0, v2
	v_and_b32_e32 v88, 0xffffff80, v88
	v_sub_u32_e32 v88, v88, v26
	v_cndmask_b32_e32 v2, v90, v89, vcc
	v_cvt_f32_f16_sdwa v89, v3 dst_sel:DWORD dst_unused:UNUSED_PAD src0_sel:WORD_1
	v_cvt_f32_f16_e32 v3, v3
	v_and_b32_e32 v2, 0xffffff80, v2
	v_sub_u32_e32 v2, v2, v26
	v_not_b32_e32 v90, v89
	v_or_b32_e32 v91, 0x80000000, v89
	v_cmp_gt_i32_e32 vcc, 0, v89
	v_add_u32_e32 v88, 0x7e, v88
	v_add_u32_e32 v2, 0x7f, v2
	v_cndmask_b32_e32 v89, v91, v90, vcc
	v_not_b32_e32 v90, v3
	v_or_b32_e32 v91, 0x80000000, v3
	v_cmp_gt_i32_e32 vcc, 0, v3
	v_and_b32_e32 v89, 0xffffff80, v89
	v_sub_u32_e32 v89, v89, v28
	v_cndmask_b32_e32 v3, v91, v90, vcc
	v_and_b32_e32 v3, 0xffffff80, v3
	v_sub_u32_e32 v3, v3, v28
	v_add_u32_e32 v89, 0x7e, v89
	v_add_u32_e32 v3, 0x7f, v3
	v_max_u32_e32 v90, v66, v74
	v_min_u32_e32 v66, v66, v74
	v_max_u32_e32 v74, v75, v67
	v_min_u32_e32 v67, v75, v67
	v_max_u32_e32 v75, v68, v76
	v_min_u32_e32 v68, v68, v76
	v_max_u32_e32 v76, v77, v69
	v_min_u32_e32 v69, v77, v69
	v_max_u32_e32 v77, v62, v78
	v_min_u32_e32 v62, v62, v78
	v_max_u32_e32 v78, v79, v63
	v_min_u32_e32 v63, v79, v63
	v_max_u32_e32 v79, v64, v80
	v_min_u32_e32 v64, v64, v80
	v_max_u32_e32 v80, v81, v65
	v_min_u32_e32 v65, v81, v65
	v_max_u32_e32 v98, v70, v82
	v_min_u32_e32 v70, v70, v82
	v_max_u32_e32 v82, v83, v71
	v_min_u32_e32 v71, v83, v71
	v_max_u32_e32 v83, v72, v84
	v_min_u32_e32 v72, v72, v84
	v_max_u32_e32 v84, v85, v73
	v_min_u32_e32 v73, v85, v73
	v_max_u32_e32 v85, v0, v86
	v_min_u32_e32 v0, v0, v86
	v_max_u32_e32 v86, v87, v1
	v_min_u32_e32 v1, v87, v1
	v_max_u32_e32 v87, v2, v88
	v_min_u32_e32 v2, v2, v88
	v_max_u32_e32 v88, v89, v3
	v_min_u32_e32 v3, v89, v3
	v_max_u32_e32 v81, v90, v67
	v_min_u32_e32 v67, v90, v67
	v_max_u32_e32 v90, v66, v74
	v_min_u32_e32 v66, v66, v74
	v_max_u32_e32 v74, v69, v75
	v_min_u32_e32 v69, v69, v75
	v_max_u32_e32 v75, v76, v68
	v_min_u32_e32 v68, v76, v68
; #define CE_DESC(a, b) do { const unsigned _mx = (a) > (b) ? (a) : (b), _mn = (a) > (b) ? (b) : (a); (a) = _mx; (b) = _mn; } while (0)
; __device__ __forceinline__ void sort16_desc(unsigned (&k)[16]) {
; #pragma unroll
;     for (int size = 2; size <= 16; size <<= 1)
; #pragma unroll
;         for (int stride = size >> 1; stride > 0; stride >>= 1)
; #pragma unroll
;             for (int i = 0; i < 16; ++i) { const int j = i ^ stride;
;                 if (j > i) { if ((i & size) == 0) CE_DESC(k[i], k[j]); else CE_DESC(k[j], k[i]); } }
; }
	v_max_u32_e32 v76, v77, v63
	v_min_u32_e32 v63, v77, v63
	v_max_u32_e32 v77, v62, v78
	v_min_u32_e32 v62, v62, v78
	v_max_u32_e32 v78, v65, v79
	v_min_u32_e32 v65, v65, v79
	v_max_u32_e32 v79, v80, v64
	v_min_u32_e32 v64, v80, v64
	v_max_u32_e32 v89, v98, v71
	v_min_u32_e32 v71, v98, v71
	v_max_u32_e32 v98, v70, v82
	v_min_u32_e32 v70, v70, v82
	v_max_u32_e32 v82, v73, v83
	v_min_u32_e32 v73, v73, v83
	v_max_u32_e32 v83, v84, v72
	v_min_u32_e32 v72, v84, v72
	v_max_u32_e32 v84, v85, v1
	v_min_u32_e32 v1, v85, v1
	v_max_u32_e32 v85, v0, v86
	v_min_u32_e32 v0, v0, v86
	v_max_u32_e32 v86, v3, v87
	v_min_u32_e32 v3, v3, v87
	v_max_u32_e32 v87, v88, v2
	v_min_u32_e32 v2, v88, v2
	v_max_u32_e32 v80, v81, v90
	v_min_u32_e32 v81, v81, v90
	v_max_u32_e32 v90, v67, v66
	v_min_u32_e32 v66, v67, v66
	v_max_u32_e32 v67, v68, v69
	v_min_u32_e32 v68, v68, v69
	v_max_u32_e32 v69, v75, v74
	v_min_u32_e32 v74, v75, v74
	v_max_u32_e32 v75, v76, v77
	v_min_u32_e32 v76, v76, v77
	v_max_u32_e32 v77, v63, v62
	v_min_u32_e32 v62, v63, v62
	v_max_u32_e32 v63, v64, v65
	v_min_u32_e32 v64, v64, v65
	v_max_u32_e32 v65, v79, v78
	v_min_u32_e32 v78, v79, v78
	v_max_u32_e32 v88, v89, v98
	v_min_u32_e32 v89, v89, v98
	v_max_u32_e32 v98, v71, v70
	v_min_u32_e32 v70, v71, v70
	v_max_u32_e32 v71, v72, v73
	v_min_u32_e32 v72, v72, v73
	v_max_u32_e32 v73, v83, v82
	v_min_u32_e32 v82, v83, v82
	v_max_u32_e32 v83, v84, v85
	v_min_u32_e32 v84, v84, v85
	v_max_u32_e32 v85, v1, v0
	v_min_u32_e32 v0, v1, v0
	v_max_u32_e32 v1, v2, v3
	v_min_u32_e32 v2, v2, v3
	v_max_u32_e32 v3, v87, v86
	v_min_u32_e32 v86, v87, v86
	v_max_u32_e32 v79, v80, v68
	v_min_u32_e32 v68, v80, v68
	v_max_u32_e32 v80, v81, v67
	v_min_u32_e32 v67, v81, v67
	v_max_u32_e32 v81, v90, v74
	v_min_u32_e32 v74, v90, v74
	v_max_u32_e32 v90, v66, v69
	v_min_u32_e32 v66, v66, v69
	v_max_u32_e32 v69, v64, v75
	v_min_u32_e32 v64, v64, v75
	v_max_u32_e32 v75, v63, v76
	v_min_u32_e32 v63, v63, v76
	v_max_u32_e32 v76, v78, v77
	v_min_u32_e32 v77, v78, v77
	v_max_u32_e32 v78, v65, v62
	v_min_u32_e32 v62, v65, v62
	v_max_u32_e32 v87, v88, v72
	v_min_u32_e32 v72, v88, v72
	v_max_u32_e32 v88, v89, v71
	v_min_u32_e32 v71, v89, v71
	v_max_u32_e32 v89, v98, v82
	v_min_u32_e32 v82, v98, v82
	v_max_u32_e32 v98, v70, v73
	v_min_u32_e32 v70, v70, v73
	v_max_u32_e32 v73, v2, v83
	v_min_u32_e32 v2, v2, v83
	v_max_u32_e32 v83, v1, v84
	v_min_u32_e32 v1, v1, v84
	v_max_u32_e32 v84, v86, v85
	v_min_u32_e32 v85, v86, v85
	v_max_u32_e32 v86, v3, v0
	v_min_u32_e32 v0, v3, v0
	v_max_u32_e32 v65, v79, v81
	v_min_u32_e32 v79, v79, v81
	v_max_u32_e32 v81, v80, v90
	v_min_u32_e32 v80, v80, v90
	v_max_u32_e32 v90, v68, v74
	v_min_u32_e32 v68, v68, v74
	v_max_u32_e32 v74, v67, v66
	v_min_u32_e32 v66, v67, v66
	v_max_u32_e32 v67, v77, v64
	v_min_u32_e32 v64, v77, v64
	v_max_u32_e32 v77, v62, v63
	v_min_u32_e32 v62, v62, v63
	v_max_u32_e32 v63, v76, v69
	v_min_u32_e32 v69, v76, v69
	v_max_u32_e32 v76, v78, v75
	v_min_u32_e32 v75, v78, v75
	v_max_u32_e32 v3, v87, v89
	v_min_u32_e32 v87, v87, v89
	v_max_u32_e32 v89, v88, v98
	v_min_u32_e32 v88, v88, v98
	v_max_u32_e32 v98, v72, v82
	v_min_u32_e32 v72, v72, v82
	v_max_u32_e32 v82, v71, v70
	v_min_u32_e32 v70, v71, v70
	v_max_u32_e32 v71, v85, v2
	v_min_u32_e32 v2, v85, v2
	v_max_u32_e32 v85, v0, v1
	v_min_u32_e32 v0, v0, v1
	v_max_u32_e32 v1, v84, v73
	v_min_u32_e32 v73, v84, v73
	v_max_u32_e32 v84, v86, v83
	v_min_u32_e32 v83, v86, v83
	v_max_u32_e32 v78, v65, v81
	v_min_u32_e32 v65, v65, v81
	v_max_u32_e32 v81, v79, v80
	v_min_u32_e32 v79, v79, v80
	v_max_u32_e32 v80, v90, v74
	v_min_u32_e32 v74, v90, v74
	v_max_u32_e32 v90, v68, v66
	v_min_u32_e32 v66, v68, v66
	v_max_u32_e32 v68, v62, v64
	v_min_u32_e32 v62, v62, v64
	v_max_u32_e32 v64, v77, v67
	v_min_u32_e32 v67, v77, v67
	v_max_u32_e32 v77, v75, v69
	v_min_u32_e32 v69, v75, v69
	v_max_u32_e32 v75, v76, v63
	v_min_u32_e32 v63, v76, v63
	v_max_u32_e32 v86, v3, v89
	v_min_u32_e32 v3, v3, v89
	v_max_u32_e32 v89, v87, v88
	v_min_u32_e32 v87, v87, v88
	v_max_u32_e32 v88, v98, v82
	v_min_u32_e32 v82, v98, v82
	v_max_u32_e32 v98, v72, v70
	v_min_u32_e32 v70, v72, v70
	v_max_u32_e32 v72, v0, v2
	v_min_u32_e32 v0, v0, v2
	v_max_u32_e32 v2, v85, v71
	v_min_u32_e32 v71, v85, v71
	v_max_u32_e32 v85, v83, v73
	v_min_u32_e32 v73, v83, v73
	v_max_u32_e32 v83, v84, v1
	v_min_u32_e32 v1, v84, v1
	v_max_u32_e32 v76, v78, v62
	v_min_u32_e32 v62, v78, v62
	v_max_u32_e32 v78, v65, v68
	v_min_u32_e32 v65, v65, v68
	v_max_u32_e32 v68, v81, v67
	v_min_u32_e32 v67, v81, v67
	v_max_u32_e32 v81, v79, v64
	v_min_u32_e32 v64, v79, v64
	v_max_u32_e32 v79, v80, v69
	v_min_u32_e32 v69, v80, v69
	v_max_u32_e32 v80, v74, v77
	v_min_u32_e32 v74, v74, v77
	v_max_u32_e32 v77, v90, v63
	v_min_u32_e32 v63, v90, v63
	v_max_u32_e32 v90, v66, v75
	v_min_u32_e32 v66, v66, v75
	v_max_u32_e32 v84, v86, v0
	v_min_u32_e32 v0, v86, v0
	v_max_u32_e32 v86, v3, v72
	v_min_u32_e32 v3, v3, v72
	v_max_u32_e32 v72, v89, v71
	v_min_u32_e32 v71, v89, v71
	v_max_u32_e32 v89, v87, v2
	v_min_u32_e32 v2, v87, v2
	v_max_u32_e32 v87, v88, v73
	v_min_u32_e32 v73, v88, v73
	v_max_u32_e32 v88, v82, v85
	v_min_u32_e32 v82, v82, v85
	v_max_u32_e32 v85, v98, v1
	v_min_u32_e32 v1, v98, v1
	v_max_u32_e32 v98, v70, v83
	v_min_u32_e32 v70, v70, v83
	v_max_u32_e32 v75, v76, v79
	v_min_u32_e32 v76, v76, v79
	v_max_u32_e32 v79, v78, v80
	v_min_u32_e32 v78, v78, v80
	v_max_u32_e32 v80, v68, v77
	v_min_u32_e32 v68, v68, v77
	v_max_u32_e32 v77, v81, v90
	v_min_u32_e32 v81, v81, v90
	v_max_u32_e32 v90, v62, v69
	v_min_u32_e32 v62, v62, v69
	v_max_u32_e32 v69, v65, v74
	v_min_u32_e32 v65, v65, v74
	v_max_u32_e32 v74, v67, v63
; #define CE_DESC(a, b) do { const unsigned _mx = (a) > (b) ? (a) : (b), _mn = (a) > (b) ? (b) : (a); (a) = _mx; (b) = _mn; } while (0)
; __device__ __forceinline__ void sort16_desc(unsigned (&k)[16]) {
; #pragma unroll
;     for (int size = 2; size <= 16; size <<= 1)
; #pragma unroll
;         for (int stride = size >> 1; stride > 0; stride >>= 1)
; #pragma unroll
;             for (int i = 0; i < 16; ++i) { const int j = i ^ stride;
;                 if (j > i) { if ((i & size) == 0) CE_DESC(k[i], k[j]); else CE_DESC(k[j], k[i]); } }
; }
; __device__ __forceinline__ void merge16(unsigned (&a)[16], const unsigned (&b)[16]) {
; #pragma unroll
;     for (int i = 0; i < 16; ++i) a[i] = a[i] > b[15 - i] ? a[i] : b[15 - i];
; #pragma unroll
;     for (int stride = 8; stride > 0; stride >>= 1)
; #pragma unroll
;         for (int i = 0; i < 16; ++i) { const int j = i ^ stride; if (j > i) CE_DESC(a[i], a[j]); }
; }
; __device__ __forceinline__ void peer_tile(const Args& A, LAS unsigned char* lds, int tile) {
;     ...
;                 for (int msk = 16; msk <= 32; msk <<= 1) {
; #pragma unroll
;                     for (int i = 0; i < 16; ++i) k1[i] = (unsigned)__shfl_xor((int)k0[i], msk);
;                     merge16(k0, k1); }
	v_min_u32_e32 v63, v67, v63
	v_max_u32_e32 v67, v64, v66
	v_min_u32_e32 v64, v64, v66
	v_max_u32_e32 v83, v84, v87
	v_min_u32_e32 v84, v84, v87
	v_max_u32_e32 v87, v86, v88
	v_min_u32_e32 v86, v86, v88
	v_max_u32_e32 v88, v72, v85
	v_min_u32_e32 v72, v72, v85
	v_max_u32_e32 v85, v89, v98
	v_min_u32_e32 v89, v89, v98
	v_max_u32_e32 v98, v0, v73
	v_min_u32_e32 v0, v0, v73
	v_max_u32_e32 v73, v3, v82
	v_min_u32_e32 v3, v3, v82
	v_max_u32_e32 v82, v71, v1
	v_min_u32_e32 v1, v71, v1
	v_max_u32_e32 v71, v2, v70
	v_min_u32_e32 v2, v2, v70
	v_max_u32_e32 v66, v75, v80
	v_min_u32_e32 v75, v75, v80
	v_max_u32_e32 v80, v79, v77
	v_min_u32_e32 v77, v79, v77
	v_max_u32_e32 v79, v76, v68
	v_min_u32_e32 v68, v76, v68
	v_max_u32_e32 v76, v78, v81
	v_min_u32_e32 v78, v78, v81
	v_max_u32_e32 v81, v90, v74
	v_min_u32_e32 v74, v90, v74
	v_max_u32_e32 v90, v69, v67
	v_min_u32_e32 v67, v69, v67
	v_max_u32_e32 v69, v62, v63
	v_min_u32_e32 v62, v62, v63
	v_max_u32_e32 v63, v65, v64
	v_min_u32_e32 v64, v65, v64
	v_max_u32_e32 v70, v83, v88
	v_min_u32_e32 v83, v83, v88
	v_max_u32_e32 v88, v87, v85
	v_min_u32_e32 v85, v87, v85
	v_max_u32_e32 v87, v84, v72
	v_min_u32_e32 v72, v84, v72
	v_max_u32_e32 v84, v86, v89
	v_min_u32_e32 v86, v86, v89
	v_max_u32_e32 v89, v98, v82
	v_min_u32_e32 v82, v98, v82
	v_max_u32_e32 v98, v73, v71
	v_min_u32_e32 v71, v73, v71
	v_max_u32_e32 v73, v0, v1
	v_min_u32_e32 v0, v0, v1
	v_max_u32_e32 v1, v3, v2
	v_min_u32_e32 v2, v3, v2
	v_min_u32_e32 v65, v66, v80
	v_min_u32_e32 v91, v75, v77
	v_min_u32_e32 v92, v79, v76
	v_min_u32_e32 v93, v68, v78
	v_min_u32_e32 v94, v81, v90
	v_min_u32_e32 v95, v74, v67
	v_min_u32_e32 v96, v69, v63
	v_min_u32_e32 v97, v62, v64
	v_min_u32_e32 v3, v70, v88
	v_min_u32_e32 v99, v83, v85
	v_min_u32_e32 v100, v87, v84
	v_min_u32_e32 v101, v72, v86
	v_min_u32_e32 v102, v89, v98
	v_min_u32_e32 v103, v82, v71
	v_min_u32_e32 v104, v73, v1
	v_min_u32_e32 v105, v0, v2
	v_max3_u32 v66, v66, v80, v105
	v_max3_u32 v0, v65, v0, v2
	v_max3_u32 v2, v75, v77, v104
	v_max3_u32 v1, v91, v73, v1
	v_max3_u32 v65, v79, v76, v103
	v_max3_u32 v71, v92, v82, v71
	v_max3_u32 v68, v68, v78, v102
	v_max3_u32 v73, v93, v89, v98
	v_max3_u32 v75, v81, v90, v101
	v_max3_u32 v72, v94, v72, v86
	v_max3_u32 v67, v74, v67, v100
	v_max3_u32 v74, v95, v87, v84
	v_max3_u32 v63, v69, v63, v99
	v_max3_u32 v69, v96, v83, v85
	v_max3_u32 v3, v62, v64, v3
	v_max3_u32 v62, v97, v70, v88
	v_max_u32_e32 v64, v66, v75
	v_min_u32_e32 v66, v66, v75
	v_max_u32_e32 v70, v0, v72
	v_min_u32_e32 v0, v0, v72
	v_max_u32_e32 v72, v2, v67
	v_min_u32_e32 v2, v2, v67
	v_max_u32_e32 v67, v1, v74
	v_min_u32_e32 v1, v1, v74
	v_max_u32_e32 v74, v65, v63
	v_min_u32_e32 v63, v65, v63
	v_max_u32_e32 v65, v71, v69
	v_min_u32_e32 v69, v71, v69
	v_max_u32_e32 v71, v68, v3
	v_min_u32_e32 v3, v68, v3
	v_max_u32_e32 v68, v73, v62
	v_min_u32_e32 v62, v73, v62
	v_max_u32_e32 v73, v64, v74
	v_min_u32_e32 v64, v64, v74
	v_max_u32_e32 v74, v70, v65
	v_min_u32_e32 v65, v70, v65
	v_max_u32_e32 v70, v72, v71
	v_min_u32_e32 v71, v72, v71
	v_max_u32_e32 v72, v67, v68
	v_min_u32_e32 v67, v67, v68
	v_max_u32_e32 v68, v66, v63
	v_min_u32_e32 v63, v66, v63
	v_max_u32_e32 v66, v0, v69
	v_min_u32_e32 v0, v0, v69
	v_max_u32_e32 v69, v2, v3
	v_min_u32_e32 v2, v2, v3
	v_max_u32_e32 v3, v1, v62
	v_min_u32_e32 v1, v1, v62
	v_max_u32_e32 v62, v73, v70
	v_min_u32_e32 v70, v73, v70
	v_max_u32_e32 v73, v74, v72
	v_min_u32_e32 v72, v74, v72
	v_max_u32_e32 v74, v64, v71
	v_min_u32_e32 v64, v64, v71
	v_max_u32_e32 v71, v65, v67
	v_min_u32_e32 v65, v65, v67
	v_max_u32_e32 v67, v68, v69
	v_min_u32_e32 v68, v68, v69
	v_max_u32_e32 v69, v66, v3
	v_min_u32_e32 v3, v66, v3
	v_max_u32_e32 v66, v63, v2
	v_min_u32_e32 v2, v63, v2
	v_max_u32_e32 v63, v0, v1
	v_min_u32_e32 v0, v0, v1
	v_max_u32_e32 v1, v62, v73
	v_min_u32_e32 v62, v62, v73
	v_max_u32_e32 v73, v70, v72
	v_min_u32_e32 v70, v70, v72
	v_max_u32_e32 v72, v74, v71
	v_min_u32_e32 v71, v74, v71
	v_max_u32_e32 v74, v64, v65
	v_min_u32_e32 v64, v64, v65
	v_max_u32_e32 v65, v67, v69
	v_min_u32_e32 v67, v67, v69
	v_max_u32_e32 v69, v68, v3
	v_min_u32_e32 v3, v68, v3
	v_max_u32_e32 v68, v66, v63
	v_min_u32_e32 v63, v66, v63
	v_max_u32_e32 v66, v2, v0
	v_min_u32_e32 v0, v2, v0
	ds_bpermute_b32 v2, v27, v1
	ds_bpermute_b32 v75, v27, v62
	ds_bpermute_b32 v76, v27, v73
	ds_bpermute_b32 v77, v27, v70
	ds_bpermute_b32 v78, v27, v72
	ds_bpermute_b32 v79, v27, v71
	ds_bpermute_b32 v80, v27, v74
	ds_bpermute_b32 v81, v27, v64
	ds_bpermute_b32 v82, v27, v65
	ds_bpermute_b32 v83, v27, v67
	ds_bpermute_b32 v84, v27, v69
	ds_bpermute_b32 v85, v27, v0
	ds_bpermute_b32 v86, v27, v66
	ds_bpermute_b32 v87, v27, v63
	ds_bpermute_b32 v88, v27, v68
	ds_bpermute_b32 v89, v27, v3
	s_waitcnt lgkmcnt(4)
	v_max_u32_e32 v1, v1, v85
	s_waitcnt lgkmcnt(3)
	v_max_u32_e32 v62, v62, v86
	s_waitcnt lgkmcnt(2)
	v_max_u32_e32 v73, v73, v87
	s_waitcnt lgkmcnt(1)
	v_max_u32_e32 v70, v70, v88
	s_waitcnt lgkmcnt(0)
; #define CE_DESC(a, b) do { const unsigned _mx = (a) > (b) ? (a) : (b), _mn = (a) > (b) ? (b) : (a); (a) = _mx; (b) = _mn; } while (0)
; __device__ __forceinline__ void merge16(unsigned (&a)[16], const unsigned (&b)[16]) {
; #pragma unroll
;     for (int i = 0; i < 16; ++i) a[i] = a[i] > b[15 - i] ? a[i] : b[15 - i];
; #pragma unroll
;     for (int stride = 8; stride > 0; stride >>= 1)
; #pragma unroll
;         for (int i = 0; i < 16; ++i) { const int j = i ^ stride; if (j > i) CE_DESC(a[i], a[j]); }
; }
; __device__ __forceinline__ void peer_tile(const Args& A, LAS unsigned char* lds, int tile) {
;     ...
;                 { const bf16_t* sp = QRY + m * 2048 + hp * 128 + 32 * g;
;                   const u32x4 s0 = *(const u32x4*)sp, s1 = *(const u32x4*)(sp + 8), s2 = *(const u32x4*)(sp + 16), s3 = *(const u32x4*)(sp + 24);
;                   const unsigned sw[16] = {s0.x, s0.y, s0.z, s0.w, s1.x, s1.y, s1.z, s1.w, s2.x, s2.y, s2.z, s2.w, s3.x, s3.y, s3.z, s3.w};
;     ...
;                 for (int msk = 16; msk <= 32; msk <<= 1) {
; #pragma unroll
;                     for (int i = 0; i < 16; ++i) k1[i] = (unsigned)__shfl_xor((int)k0[i], msk);
;                     merge16(k0, k1); }
	v_max_u32_e32 v72, v72, v89
	v_max_u32_e32 v71, v71, v84
	v_max_u32_e32 v74, v74, v83
	v_max_u32_e32 v64, v64, v82
	v_max_u32_e32 v65, v65, v81
	v_max_u32_e32 v67, v67, v80
	v_max_u32_e32 v69, v69, v79
	v_max_u32_e32 v3, v3, v78
	v_max_u32_e32 v68, v68, v77
	v_max_u32_e32 v63, v63, v76
	v_max_u32_e32 v66, v66, v75
	v_max_u32_e32 v0, v0, v2
	v_max_u32_e32 v2, v1, v65
	v_min_u32_e32 v1, v1, v65
	v_max_u32_e32 v65, v62, v67
	v_min_u32_e32 v62, v62, v67
	v_max_u32_e32 v67, v73, v69
	v_min_u32_e32 v69, v73, v69
	v_max_u32_e32 v73, v70, v3
	v_min_u32_e32 v3, v70, v3
	v_max_u32_e32 v70, v72, v68
	v_min_u32_e32 v68, v72, v68
	v_max_u32_e32 v72, v71, v63
	v_min_u32_e32 v63, v71, v63
	v_max_u32_e32 v71, v74, v66
	v_min_u32_e32 v66, v74, v66
	v_max_u32_e32 v74, v64, v0
	v_min_u32_e32 v0, v64, v0
	v_max_u32_e32 v64, v2, v70
	v_min_u32_e32 v2, v2, v70
	v_max_u32_e32 v70, v65, v72
	v_min_u32_e32 v65, v65, v72
	v_max_u32_e32 v72, v67, v71
	v_min_u32_e32 v67, v67, v71
	v_max_u32_e32 v71, v73, v74
	v_min_u32_e32 v73, v73, v74
	v_max_u32_e32 v74, v1, v68
	v_min_u32_e32 v1, v1, v68
	v_max_u32_e32 v68, v62, v63
	v_min_u32_e32 v62, v62, v63
	v_max_u32_e32 v63, v69, v66
	v_min_u32_e32 v66, v69, v66
	v_max_u32_e32 v69, v3, v0
	v_min_u32_e32 v0, v3, v0
	v_max_u32_e32 v3, v64, v72
	v_min_u32_e32 v64, v64, v72
	v_max_u32_e32 v72, v70, v71
	v_min_u32_e32 v70, v70, v71
	v_max_u32_e32 v71, v2, v67
	v_min_u32_e32 v2, v2, v67
	v_max_u32_e32 v67, v65, v73
	v_min_u32_e32 v65, v65, v73
	v_max_u32_e32 v73, v74, v63
	v_min_u32_e32 v63, v74, v63
	v_max_u32_e32 v74, v68, v69
	v_min_u32_e32 v68, v68, v69
	v_max_u32_e32 v69, v1, v66
	v_min_u32_e32 v1, v1, v66
	v_max_u32_e32 v66, v62, v0
	v_min_u32_e32 v0, v62, v0
	v_max_u32_e32 v62, v3, v72
	v_min_u32_e32 v3, v3, v72
	v_max_u32_e32 v72, v64, v70
	v_min_u32_e32 v64, v64, v70
	v_max_u32_e32 v70, v71, v67
	v_min_u32_e32 v67, v71, v67
	v_max_u32_e32 v71, v2, v65
	v_min_u32_e32 v2, v2, v65
	v_max_u32_e32 v65, v73, v74
	v_min_u32_e32 v73, v73, v74
	v_max_u32_e32 v74, v63, v68
	v_min_u32_e32 v63, v63, v68
	v_max_u32_e32 v68, v69, v66
	v_min_u32_e32 v66, v69, v66
	v_max_u32_e32 v69, v1, v0
	v_min_u32_e32 v0, v1, v0
	ds_bpermute_b32 v78, v29, v0
	ds_bpermute_b32 v1, v29, v62
	ds_bpermute_b32 v75, v29, v3
	ds_bpermute_b32 v76, v29, v72
	ds_bpermute_b32 v77, v29, v64
	s_waitcnt lgkmcnt(4)
	v_max_u32_e32 v62, v62, v78
	global_load_dwordx4 v[78:81], v[4:5], off offset:784
	global_load_dwordx4 v[82:85], v[4:5], off offset:768
	ds_bpermute_b32 v86, v29, v70
	ds_bpermute_b32 v87, v29, v67
	ds_bpermute_b32 v88, v29, v71
	ds_bpermute_b32 v89, v29, v2
	ds_bpermute_b32 v90, v29, v65
	ds_bpermute_b32 v91, v29, v73
	ds_bpermute_b32 v92, v29, v74
	ds_bpermute_b32 v93, v29, v63
	ds_bpermute_b32 v94, v29, v68
	ds_bpermute_b32 v95, v29, v69
	ds_bpermute_b32 v96, v29, v66
	s_waitcnt lgkmcnt(4)
	v_max_u32_e32 v67, v67, v92
	s_waitcnt lgkmcnt(3)
	v_max_u32_e32 v70, v70, v93
	s_waitcnt lgkmcnt(2)
	v_max_u32_e32 v64, v64, v94
	s_waitcnt lgkmcnt(1)
	v_max_u32_e32 v3, v3, v95
	s_waitcnt lgkmcnt(0)
	v_max_u32_e32 v72, v72, v96
	v_max_u32_e32 v71, v71, v91
	v_max_u32_e32 v2, v2, v90
	v_max_u32_e32 v65, v65, v89
	v_max_u32_e32 v73, v73, v88
	v_max_u32_e32 v74, v74, v87
	v_max_u32_e32 v63, v63, v86
	v_max_u32_e32 v68, v68, v77
	v_max_u32_e32 v66, v66, v76
	v_max_u32_e32 v69, v69, v75
	v_max_u32_e32 v0, v0, v1
	v_max_u32_e32 v1, v62, v65
	v_min_u32_e32 v62, v62, v65
	v_max_u32_e32 v65, v3, v73
	v_min_u32_e32 v3, v3, v73
	v_max_u32_e32 v73, v72, v74
	v_min_u32_e32 v72, v72, v74
	v_max_u32_e32 v74, v64, v63
	v_min_u32_e32 v63, v64, v63
	v_max_u32_e32 v64, v70, v68
	v_min_u32_e32 v68, v70, v68
	v_max_u32_e32 v70, v67, v66
	v_min_u32_e32 v66, v67, v66
	v_max_u32_e32 v67, v71, v69
	v_min_u32_e32 v69, v71, v69
	v_max_u32_e32 v71, v2, v0
	v_min_u32_e32 v0, v2, v0
	v_max_u32_e32 v2, v1, v64
	v_min_u32_e32 v1, v1, v64
	v_max_u32_e32 v64, v65, v70
	v_min_u32_e32 v65, v65, v70
	v_max_u32_e32 v70, v73, v67
	v_min_u32_e32 v67, v73, v67
	v_max_u32_e32 v73, v74, v71
	v_min_u32_e32 v71, v74, v71
	v_max_u32_e32 v74, v62, v68
	v_min_u32_e32 v62, v62, v68
	v_max_u32_e32 v68, v3, v66
	v_min_u32_e32 v3, v3, v66
	v_max_u32_e32 v66, v72, v69
	v_min_u32_e32 v69, v72, v69
	v_max_u32_e32 v72, v63, v0
	v_min_u32_e32 v0, v63, v0
	v_max_u32_e32 v63, v2, v70
	v_min_u32_e32 v2, v2, v70
	v_max_u32_e32 v70, v64, v73
	v_min_u32_e32 v64, v64, v73
	v_max_u32_e32 v86, v1, v67
	v_min_u32_e32 v1, v1, v67
	v_max_u32_e32 v67, v65, v71
	v_min_u32_e32 v65, v65, v71
	v_max_u32_e32 v87, v74, v66
	v_min_u32_e32 v66, v74, v66
	v_max_u32_e32 v88, v68, v72
	v_min_u32_e32 v89, v68, v72
	v_max_u32_e32 v90, v62, v69
	v_min_u32_e32 v62, v62, v69
	v_max_u32_e32 v91, v3, v0
	v_min_u32_e32 v0, v3, v0
	v_max_u32_e32 v77, v63, v70
	v_min_u32_e32 v76, v63, v70
	v_max_u32_e32 v75, v2, v64
	v_min_u32_e32 v74, v2, v64
	v_max_u32_e32 v73, v86, v67
	v_min_u32_e32 v72, v86, v67
	v_max_u32_e32 v71, v1, v65
	v_min_u32_e32 v70, v1, v65
	v_max_u32_e32 v69, v87, v88
	v_min_u32_e32 v68, v87, v88
	v_max_u32_e32 v67, v66, v89
	v_min_u32_e32 v66, v66, v89
	v_max_u32_e32 v63, v62, v0
	v_min_u32_e32 v62, v62, v0
	global_load_dwordx4 v[0:3], v[4:5], off offset:816
	global_load_dwordx4 v[86:89], v[4:5], off offset:800
	v_max_u32_e32 v65, v90, v91
	v_min_u32_e32 v64, v90, v91
	s_waitcnt vmcnt(2)
; __device__ __forceinline__ unsigned f2key(float f) { const unsigned u = __float_as_uint(f); return (u & 0x80000000u) ? ~u : (u | 0x80000000u); }
; __device__ __forceinline__ void peer_tile(const Args& A, LAS unsigned char* lds, int tile) {
;     ...
;                 { const bf16_t* sp = QRY + m * 2048 + hp * 128 + 32 * g;
;                   const u32x4 s0 = *(const u32x4*)sp, s1 = *(const u32x4*)(sp + 8), s2 = *(const u32x4*)(sp + 16), s3 = *(const u32x4*)(sp + 24);
;                   const unsigned sw[16] = {s0.x, s0.y, s0.z, s0.w, s1.x, s1.y, s1.z, s1.w, s2.x, s2.y, s2.z, s2.w, s3.x, s3.y, s3.z, s3.w};
; #pragma unroll
;                   for (int i = 0; i < 16; ++i) {
;                       const float lo = (float)__builtin_bit_cast(_Float16, (unsigned short)(sw[i] & 0xffffu)), hi = (float)__builtin_bit_cast(_Float16, (unsigned short)(sw[i] >> 16));
;                       const unsigned klo = (f2key(lo) & ~127u) | (unsigned)(127 - (32 * g + 2 * i)), khi = (f2key(hi) & ~127u) | (unsigned)(127 - (32 * g + 2 * i + 1));
;                       if (i < 8) { k0[2 * i] = klo; k0[2 * i + 1] = khi; } else { k1[2 * (i - 8)] = klo; k1[2 * (i - 8) + 1] = khi; } } }
;     ...
;                 for (int i = 0; i < 16; ++i) L2[p][i] = (g & 2) ? ((g & 1) ? LA[3][p][i] : LA[2][p][i]) : ((g & 1) ? LA[1][p][i] : LA[0][p][i]);
	v_cvt_f32_f16_sdwa v90, v82 dst_sel:DWORD dst_unused:UNUSED_PAD src0_sel:WORD_1
	v_cvt_f32_f16_e32 v82, v82
	v_cndmask_b32_e64 v38, v70, v38, s[0:1]
	v_cndmask_b32_e64 v37, v69, v37, s[0:1]
	v_not_b32_e32 v91, v90
	v_or_b32_e32 v92, 0x80000000, v90
	v_cmp_gt_i32_e32 vcc, 0, v90
	v_cndmask_b32_e64 v36, v68, v36, s[0:1]
	v_cndmask_b32_e64 v35, v67, v35, s[0:1]
	v_cndmask_b32_e32 v90, v92, v91, vcc
	v_not_b32_e32 v91, v82
	v_or_b32_e32 v92, 0x80000000, v82
	v_cmp_gt_i32_e32 vcc, 0, v82
	v_and_b32_e32 v90, 0xffffff80, v90
	v_sub_u32_e32 v90, v90, v15
	v_cndmask_b32_e32 v82, v92, v91, vcc
	v_cvt_f32_f16_sdwa v91, v83 dst_sel:DWORD dst_unused:UNUSED_PAD src0_sel:WORD_1
	v_cvt_f32_f16_e32 v83, v83
	v_and_b32_e32 v82, 0xffffff80, v82
	v_sub_u32_e32 v82, v82, v15
	v_not_b32_e32 v92, v91
	v_or_b32_e32 v93, 0x80000000, v91
	v_cmp_gt_i32_e32 vcc, 0, v91
	v_add_u32_e32 v90, 0x7e, v90
	v_add_u32_e32 v82, 0x7f, v82
	v_cndmask_b32_e32 v91, v93, v92, vcc
	v_not_b32_e32 v92, v83
	v_or_b32_e32 v93, 0x80000000, v83
	v_cmp_gt_i32_e32 vcc, 0, v83
	v_and_b32_e32 v91, 0xffffff80, v91
	v_sub_u32_e32 v91, v91, v14
	v_cndmask_b32_e32 v83, v93, v92, vcc
	v_cvt_f32_f16_sdwa v92, v84 dst_sel:DWORD dst_unused:UNUSED_PAD src0_sel:WORD_1
	v_cvt_f32_f16_e32 v84, v84
	v_and_b32_e32 v83, 0xffffff80, v83
	v_sub_u32_e32 v83, v83, v14
	v_not_b32_e32 v93, v92
	v_or_b32_e32 v94, 0x80000000, v92
	v_cmp_gt_i32_e32 vcc, 0, v92
	v_add_u32_e32 v91, 0x7e, v91
	v_add_u32_e32 v83, 0x7f, v83
	v_cndmask_b32_e32 v92, v94, v93, vcc
	v_not_b32_e32 v93, v84
	v_or_b32_e32 v94, 0x80000000, v84
	v_cmp_gt_i32_e32 vcc, 0, v84
	v_and_b32_e32 v92, 0xffffff80, v92
	v_sub_u32_e32 v92, v92, v12
	v_cndmask_b32_e32 v84, v94, v93, vcc
	v_cvt_f32_f16_sdwa v93, v85 dst_sel:DWORD dst_unused:UNUSED_PAD src0_sel:WORD_1
	v_cvt_f32_f16_e32 v85, v85
	v_and_b32_e32 v84, 0xffffff80, v84
	v_sub_u32_e32 v84, v84, v12
	v_not_b32_e32 v94, v93
	v_or_b32_e32 v95, 0x80000000, v93
	v_cmp_gt_i32_e32 vcc, 0, v93
	v_add_u32_e32 v92, 0x7e, v92
	v_add_u32_e32 v84, 0x7f, v84
	v_cndmask_b32_e32 v93, v95, v94, vcc
	v_not_b32_e32 v94, v85
	v_or_b32_e32 v95, 0x80000000, v85
	v_cmp_gt_i32_e32 vcc, 0, v85
	v_and_b32_e32 v93, 0xffffff80, v93
	v_sub_u32_e32 v93, v93, v10
	v_cndmask_b32_e32 v85, v95, v94, vcc
	v_cvt_f32_f16_sdwa v94, v78 dst_sel:DWORD dst_unused:UNUSED_PAD src0_sel:WORD_1
	v_cvt_f32_f16_e32 v78, v78
	v_and_b32_e32 v85, 0xffffff80, v85
	v_sub_u32_e32 v85, v85, v10
	v_not_b32_e32 v95, v94
	v_or_b32_e32 v96, 0x80000000, v94
	v_cmp_gt_i32_e32 vcc, 0, v94
	v_add_u32_e32 v93, 0x7e, v93
	v_add_u32_e32 v85, 0x7f, v85
	v_cndmask_b32_e32 v94, v96, v95, vcc
	v_not_b32_e32 v95, v78
	v_or_b32_e32 v96, 0x80000000, v78
	v_cmp_gt_i32_e32 vcc, 0, v78
	v_and_b32_e32 v94, 0xffffff80, v94
	v_sub_u32_e32 v94, v94, v8
	v_cndmask_b32_e32 v78, v96, v95, vcc
	v_cvt_f32_f16_sdwa v95, v79 dst_sel:DWORD dst_unused:UNUSED_PAD src0_sel:WORD_1
	v_cvt_f32_f16_e32 v79, v79
	v_and_b32_e32 v78, 0xffffff80, v78
	v_sub_u32_e32 v78, v78, v8
	v_not_b32_e32 v96, v95
	v_or_b32_e32 v97, 0x80000000, v95
	v_cmp_gt_i32_e32 vcc, 0, v95
	v_add_u32_e32 v94, 0x7e, v94
	v_add_u32_e32 v78, 0x7f, v78
	v_cndmask_b32_e32 v95, v97, v96, vcc
	v_not_b32_e32 v96, v79
	v_or_b32_e32 v97, 0x80000000, v79
	v_cmp_gt_i32_e32 vcc, 0, v79
	v_and_b32_e32 v95, 0xffffff80, v95
	v_sub_u32_e32 v95, v95, v16
	v_cndmask_b32_e32 v79, v97, v96, vcc
	v_cvt_f32_f16_sdwa v96, v80 dst_sel:DWORD dst_unused:UNUSED_PAD src0_sel:WORD_1
	v_cvt_f32_f16_e32 v80, v80
	v_and_b32_e32 v79, 0xffffff80, v79
	v_sub_u32_e32 v79, v79, v16
	v_not_b32_e32 v97, v96
	v_or_b32_e32 v98, 0x80000000, v96
	v_cmp_gt_i32_e32 vcc, 0, v96
	v_add_u32_e32 v95, 0x7e, v95
	v_add_u32_e32 v79, 0x7f, v79
	v_cndmask_b32_e32 v96, v98, v97, vcc
	v_not_b32_e32 v97, v80
	v_or_b32_e32 v98, 0x80000000, v80
	v_cmp_gt_i32_e32 vcc, 0, v80
	v_and_b32_e32 v96, 0xffffff80, v96
	v_sub_u32_e32 v96, v96, v17
	v_cndmask_b32_e32 v80, v98, v97, vcc
	v_cvt_f32_f16_sdwa v97, v81 dst_sel:DWORD dst_unused:UNUSED_PAD src0_sel:WORD_1
	v_cvt_f32_f16_e32 v81, v81
	v_and_b32_e32 v80, 0xffffff80, v80
	v_sub_u32_e32 v80, v80, v17
	v_not_b32_e32 v98, v97
	v_or_b32_e32 v99, 0x80000000, v97
	v_cmp_gt_i32_e32 vcc, 0, v97
	v_add_u32_e32 v96, 0x7e, v96
	v_add_u32_e32 v80, 0x7f, v80
	v_cndmask_b32_e32 v97, v99, v98, vcc
	v_not_b32_e32 v98, v81
	v_or_b32_e32 v99, 0x80000000, v81
	v_cmp_gt_i32_e32 vcc, 0, v81
	v_and_b32_e32 v97, 0xffffff80, v97
	v_sub_u32_e32 v97, v97, v18
	v_cndmask_b32_e32 v81, v99, v98, vcc
	s_waitcnt vmcnt(0)
; __device__ __forceinline__ unsigned f2key(float f) { const unsigned u = __float_as_uint(f); return (u & 0x80000000u) ? ~u : (u | 0x80000000u); }
; #define CE_DESC(a, b) do { const unsigned _mx = (a) > (b) ? (a) : (b), _mn = (a) > (b) ? (b) : (a); (a) = _mx; (b) = _mn; } while (0)
; __device__ __forceinline__ void sort16_desc(unsigned (&k)[16]) {
; #pragma unroll
;     for (int size = 2; size <= 16; size <<= 1)
; #pragma unroll
;         for (int stride = size >> 1; stride > 0; stride >>= 1)
; #pragma unroll
;             for (int i = 0; i < 16; ++i) { const int j = i ^ stride;
;                 if (j > i) { if ((i & size) == 0) CE_DESC(k[i], k[j]); else CE_DESC(k[j], k[i]); } }
; }
; __device__ __forceinline__ void peer_tile(const Args& A, LAS unsigned char* lds, int tile) {
;     ...
;                 { const bf16_t* sp = QRY + m * 2048 + hp * 128 + 32 * g;
;                   const u32x4 s0 = *(const u32x4*)sp, s1 = *(const u32x4*)(sp + 8), s2 = *(const u32x4*)(sp + 16), s3 = *(const u32x4*)(sp + 24);
;                   const unsigned sw[16] = {s0.x, s0.y, s0.z, s0.w, s1.x, s1.y, s1.z, s1.w, s2.x, s2.y, s2.z, s2.w, s3.x, s3.y, s3.z, s3.w};
; #pragma unroll
;                   for (int i = 0; i < 16; ++i) {
;                       const float lo = (float)__builtin_bit_cast(_Float16, (unsigned short)(sw[i] & 0xffffu)), hi = (float)__builtin_bit_cast(_Float16, (unsigned short)(sw[i] >> 16));
;                       const unsigned klo = (f2key(lo) & ~127u) | (unsigned)(127 - (32 * g + 2 * i)), khi = (f2key(hi) & ~127u) | (unsigned)(127 - (32 * g + 2 * i + 1));
;                       if (i < 8) { k0[2 * i] = klo; k0[2 * i + 1] = khi; } else { k1[2 * (i - 8)] = klo; k1[2 * (i - 8) + 1] = khi; } } }
	v_cvt_f32_f16_sdwa v98, v86 dst_sel:DWORD dst_unused:UNUSED_PAD src0_sel:WORD_1
	v_cvt_f32_f16_e32 v86, v86
	v_and_b32_e32 v81, 0xffffff80, v81
	v_sub_u32_e32 v81, v81, v18
	v_not_b32_e32 v99, v98
	v_or_b32_e32 v100, 0x80000000, v98
	v_cmp_gt_i32_e32 vcc, 0, v98
	v_add_u32_e32 v97, 0x7e, v97
	v_add_u32_e32 v81, 0x7f, v81
	v_cndmask_b32_e32 v98, v100, v99, vcc
	v_not_b32_e32 v99, v86
	v_or_b32_e32 v100, 0x80000000, v86
	v_cmp_gt_i32_e32 vcc, 0, v86
	v_and_b32_e32 v98, 0xffffff80, v98
	v_sub_u32_e32 v98, v98, v20
	v_cndmask_b32_e32 v86, v100, v99, vcc
	v_cvt_f32_f16_sdwa v99, v87 dst_sel:DWORD dst_unused:UNUSED_PAD src0_sel:WORD_1
	v_cvt_f32_f16_e32 v87, v87
	v_and_b32_e32 v86, 0xffffff80, v86
	v_sub_u32_e32 v86, v86, v20
	v_not_b32_e32 v100, v99
	v_or_b32_e32 v101, 0x80000000, v99
	v_cmp_gt_i32_e32 vcc, 0, v99
	v_add_u32_e32 v98, 0x7e, v98
	v_add_u32_e32 v86, 0x7f, v86
	v_cndmask_b32_e32 v99, v101, v100, vcc
	v_not_b32_e32 v100, v87
	v_or_b32_e32 v101, 0x80000000, v87
	v_cmp_gt_i32_e32 vcc, 0, v87
	v_and_b32_e32 v99, 0xffffff80, v99
	v_sub_u32_e32 v99, v99, v21
	v_cndmask_b32_e32 v87, v101, v100, vcc
	v_cvt_f32_f16_sdwa v100, v88 dst_sel:DWORD dst_unused:UNUSED_PAD src0_sel:WORD_1
	v_cvt_f32_f16_e32 v88, v88
	v_and_b32_e32 v87, 0xffffff80, v87
	v_sub_u32_e32 v87, v87, v21
	v_not_b32_e32 v101, v100
	v_or_b32_e32 v102, 0x80000000, v100
	v_cmp_gt_i32_e32 vcc, 0, v100
	v_add_u32_e32 v99, 0x7e, v99
	v_add_u32_e32 v87, 0x7f, v87
	v_cndmask_b32_e32 v100, v102, v101, vcc
	v_not_b32_e32 v101, v88
	v_or_b32_e32 v102, 0x80000000, v88
	v_cmp_gt_i32_e32 vcc, 0, v88
	v_and_b32_e32 v100, 0xffffff80, v100
	v_sub_u32_e32 v100, v100, v22
	v_cndmask_b32_e32 v88, v102, v101, vcc
	v_cvt_f32_f16_sdwa v101, v89 dst_sel:DWORD dst_unused:UNUSED_PAD src0_sel:WORD_1
	v_cvt_f32_f16_e32 v89, v89
	v_and_b32_e32 v88, 0xffffff80, v88
	v_sub_u32_e32 v88, v88, v22
	v_not_b32_e32 v102, v101
	v_or_b32_e32 v103, 0x80000000, v101
	v_cmp_gt_i32_e32 vcc, 0, v101
	v_add_u32_e32 v100, 0x7e, v100
	v_add_u32_e32 v88, 0x7f, v88
	v_cndmask_b32_e32 v101, v103, v102, vcc
	v_not_b32_e32 v102, v89
	v_or_b32_e32 v103, 0x80000000, v89
	v_cmp_gt_i32_e32 vcc, 0, v89
	v_and_b32_e32 v101, 0xffffff80, v101
	v_sub_u32_e32 v101, v101, v23
	v_cndmask_b32_e32 v89, v103, v102, vcc
	v_cvt_f32_f16_sdwa v102, v0 dst_sel:DWORD dst_unused:UNUSED_PAD src0_sel:WORD_1
	v_cvt_f32_f16_e32 v0, v0
	v_and_b32_e32 v89, 0xffffff80, v89
	v_sub_u32_e32 v89, v89, v23
	v_not_b32_e32 v103, v102
	v_or_b32_e32 v104, 0x80000000, v102
	v_cmp_gt_i32_e32 vcc, 0, v102
	v_add_u32_e32 v101, 0x7e, v101
	v_add_u32_e32 v89, 0x7f, v89
	v_cndmask_b32_e32 v102, v104, v103, vcc
	v_not_b32_e32 v103, v0
	v_or_b32_e32 v104, 0x80000000, v0
	v_cmp_gt_i32_e32 vcc, 0, v0
	v_and_b32_e32 v102, 0xffffff80, v102
	v_sub_u32_e32 v102, v102, v24
	v_cndmask_b32_e32 v0, v104, v103, vcc
	v_cvt_f32_f16_sdwa v103, v1 dst_sel:DWORD dst_unused:UNUSED_PAD src0_sel:WORD_1
	v_cvt_f32_f16_e32 v1, v1
	v_and_b32_e32 v0, 0xffffff80, v0
	v_sub_u32_e32 v0, v0, v24
	v_not_b32_e32 v104, v103
	v_or_b32_e32 v105, 0x80000000, v103
	v_cmp_gt_i32_e32 vcc, 0, v103
	v_add_u32_e32 v102, 0x7e, v102
	v_add_u32_e32 v0, 0x7f, v0
	v_cndmask_b32_e32 v103, v105, v104, vcc
	v_not_b32_e32 v104, v1
	v_or_b32_e32 v105, 0x80000000, v1
	v_cmp_gt_i32_e32 vcc, 0, v1
	v_and_b32_e32 v103, 0xffffff80, v103
	v_sub_u32_e32 v103, v103, v25
	v_cndmask_b32_e32 v1, v105, v104, vcc
	v_cvt_f32_f16_sdwa v104, v2 dst_sel:DWORD dst_unused:UNUSED_PAD src0_sel:WORD_1
	v_cvt_f32_f16_e32 v2, v2
	v_and_b32_e32 v1, 0xffffff80, v1
	v_sub_u32_e32 v1, v1, v25
	v_not_b32_e32 v105, v104
	v_or_b32_e32 v106, 0x80000000, v104
	v_cmp_gt_i32_e32 vcc, 0, v104
	v_add_u32_e32 v103, 0x7e, v103
	v_add_u32_e32 v1, 0x7f, v1
	v_cndmask_b32_e32 v104, v106, v105, vcc
	v_not_b32_e32 v105, v2
	v_or_b32_e32 v106, 0x80000000, v2
	v_cmp_gt_i32_e32 vcc, 0, v2
	v_and_b32_e32 v104, 0xffffff80, v104
	v_sub_u32_e32 v104, v104, v26
	v_cndmask_b32_e32 v2, v106, v105, vcc
	v_cvt_f32_f16_sdwa v105, v3 dst_sel:DWORD dst_unused:UNUSED_PAD src0_sel:WORD_1
	v_cvt_f32_f16_e32 v3, v3
	v_and_b32_e32 v2, 0xffffff80, v2
	v_sub_u32_e32 v2, v2, v26
	v_not_b32_e32 v106, v105
	v_or_b32_e32 v107, 0x80000000, v105
	v_cmp_gt_i32_e32 vcc, 0, v105
	v_add_u32_e32 v104, 0x7e, v104
	v_add_u32_e32 v2, 0x7f, v2
	v_cndmask_b32_e32 v105, v107, v106, vcc
	v_not_b32_e32 v106, v3
	v_or_b32_e32 v107, 0x80000000, v3
	v_cmp_gt_i32_e32 vcc, 0, v3
	v_and_b32_e32 v105, 0xffffff80, v105
	v_sub_u32_e32 v105, v105, v28
	v_cndmask_b32_e32 v3, v107, v106, vcc
	v_and_b32_e32 v3, 0xffffff80, v3
	v_sub_u32_e32 v3, v3, v28
	v_add_u32_e32 v105, 0x7e, v105
	v_add_u32_e32 v3, 0x7f, v3
	v_max_u32_e32 v106, v82, v90
	v_min_u32_e32 v82, v82, v90
	v_max_u32_e32 v90, v91, v83
	v_min_u32_e32 v83, v91, v83
	v_max_u32_e32 v91, v84, v92
	v_min_u32_e32 v84, v84, v92
	v_max_u32_e32 v92, v93, v85
	v_min_u32_e32 v85, v93, v85
	v_max_u32_e32 v93, v78, v94
	v_min_u32_e32 v78, v78, v94
	v_max_u32_e32 v94, v95, v79
	v_min_u32_e32 v79, v95, v79
	v_max_u32_e32 v95, v80, v96
	v_min_u32_e32 v80, v80, v96
	v_max_u32_e32 v96, v97, v81
	v_min_u32_e32 v81, v97, v81
	v_max_u32_e32 v115, v86, v98
	v_min_u32_e32 v86, v86, v98
	v_max_u32_e32 v98, v99, v87
	v_min_u32_e32 v87, v99, v87
	v_max_u32_e32 v99, v88, v100
	v_min_u32_e32 v88, v88, v100
	v_max_u32_e32 v100, v101, v89
	v_min_u32_e32 v89, v101, v89
	v_max_u32_e32 v101, v0, v102
	v_min_u32_e32 v0, v0, v102
	v_max_u32_e32 v102, v103, v1
	v_min_u32_e32 v1, v103, v1
	v_max_u32_e32 v103, v2, v104
	v_min_u32_e32 v2, v2, v104
	v_max_u32_e32 v104, v105, v3
	v_min_u32_e32 v3, v105, v3
	v_max_u32_e32 v97, v106, v83
	v_min_u32_e32 v83, v106, v83
	v_max_u32_e32 v106, v82, v90
; #define CE_DESC(a, b) do { const unsigned _mx = (a) > (b) ? (a) : (b), _mn = (a) > (b) ? (b) : (a); (a) = _mx; (b) = _mn; } while (0)
; __device__ __forceinline__ void sort16_desc(unsigned (&k)[16]) {
; #pragma unroll
;     for (int size = 2; size <= 16; size <<= 1)
; #pragma unroll
;         for (int stride = size >> 1; stride > 0; stride >>= 1)
; #pragma unroll
;             for (int i = 0; i < 16; ++i) { const int j = i ^ stride;
;                 if (j > i) { if ((i & size) == 0) CE_DESC(k[i], k[j]); else CE_DESC(k[j], k[i]); } }
; }
	v_min_u32_e32 v82, v82, v90
	v_max_u32_e32 v90, v85, v91
	v_min_u32_e32 v85, v85, v91
	v_max_u32_e32 v91, v92, v84
	v_min_u32_e32 v84, v92, v84
	v_max_u32_e32 v92, v93, v79
	v_min_u32_e32 v79, v93, v79
	v_max_u32_e32 v93, v78, v94
	v_min_u32_e32 v78, v78, v94
	v_max_u32_e32 v94, v81, v95
	v_min_u32_e32 v81, v81, v95
	v_max_u32_e32 v95, v96, v80
	v_min_u32_e32 v80, v96, v80
	v_max_u32_e32 v105, v115, v87
	v_min_u32_e32 v87, v115, v87
	v_max_u32_e32 v115, v86, v98
	v_min_u32_e32 v86, v86, v98
	v_max_u32_e32 v98, v89, v99
	v_min_u32_e32 v89, v89, v99
	v_max_u32_e32 v99, v100, v88
	v_min_u32_e32 v88, v100, v88
	v_max_u32_e32 v100, v101, v1
	v_min_u32_e32 v1, v101, v1
	v_max_u32_e32 v101, v0, v102
	v_min_u32_e32 v0, v0, v102
	v_max_u32_e32 v102, v3, v103
	v_min_u32_e32 v3, v3, v103
	v_max_u32_e32 v103, v104, v2
	v_min_u32_e32 v2, v104, v2
	v_max_u32_e32 v96, v97, v106
	v_min_u32_e32 v97, v97, v106
	v_max_u32_e32 v106, v83, v82
	v_min_u32_e32 v82, v83, v82
	v_max_u32_e32 v83, v84, v85
	v_min_u32_e32 v84, v84, v85
	v_max_u32_e32 v85, v91, v90
	v_min_u32_e32 v90, v91, v90
	v_max_u32_e32 v91, v92, v93
	v_min_u32_e32 v92, v92, v93
	v_max_u32_e32 v93, v79, v78
	v_min_u32_e32 v78, v79, v78
	v_max_u32_e32 v79, v80, v81
	v_min_u32_e32 v80, v80, v81
	v_max_u32_e32 v81, v95, v94
	v_min_u32_e32 v94, v95, v94
	v_max_u32_e32 v104, v105, v115
	v_min_u32_e32 v105, v105, v115
	v_max_u32_e32 v115, v87, v86
	v_min_u32_e32 v86, v87, v86
	v_max_u32_e32 v87, v88, v89
	v_min_u32_e32 v88, v88, v89
	v_max_u32_e32 v89, v99, v98
	v_min_u32_e32 v98, v99, v98
	v_max_u32_e32 v99, v100, v101
	v_min_u32_e32 v100, v100, v101
	v_max_u32_e32 v101, v1, v0
	v_min_u32_e32 v0, v1, v0
	v_max_u32_e32 v1, v2, v3
	v_min_u32_e32 v2, v2, v3
	v_max_u32_e32 v3, v103, v102
	v_min_u32_e32 v102, v103, v102
	v_max_u32_e32 v95, v96, v84
	v_min_u32_e32 v84, v96, v84
	v_max_u32_e32 v96, v97, v83
	v_min_u32_e32 v83, v97, v83
	v_max_u32_e32 v97, v106, v90
	v_min_u32_e32 v90, v106, v90
	v_max_u32_e32 v106, v82, v85
	v_min_u32_e32 v82, v82, v85
	v_max_u32_e32 v85, v80, v91
	v_min_u32_e32 v80, v80, v91
	v_max_u32_e32 v91, v79, v92
	v_min_u32_e32 v79, v79, v92
	v_max_u32_e32 v92, v94, v93
	v_min_u32_e32 v93, v94, v93
	v_max_u32_e32 v94, v81, v78
	v_min_u32_e32 v78, v81, v78
	v_max_u32_e32 v103, v104, v88
	v_min_u32_e32 v88, v104, v88
	v_max_u32_e32 v104, v105, v87
	v_min_u32_e32 v87, v105, v87
	v_max_u32_e32 v105, v115, v98
	v_min_u32_e32 v98, v115, v98
	v_max_u32_e32 v115, v86, v89
	v_min_u32_e32 v86, v86, v89
	v_max_u32_e32 v89, v2, v99
	v_min_u32_e32 v2, v2, v99
	v_max_u32_e32 v99, v1, v100
	v_min_u32_e32 v1, v1, v100
	v_max_u32_e32 v100, v102, v101
	v_min_u32_e32 v101, v102, v101
	v_max_u32_e32 v102, v3, v0
	v_min_u32_e32 v0, v3, v0
	v_max_u32_e32 v81, v95, v97
	v_min_u32_e32 v95, v95, v97
	v_max_u32_e32 v97, v96, v106
	v_min_u32_e32 v96, v96, v106
	v_max_u32_e32 v106, v84, v90
	v_min_u32_e32 v84, v84, v90
	v_max_u32_e32 v90, v83, v82
	v_min_u32_e32 v82, v83, v82
	v_max_u32_e32 v83, v93, v80
	v_min_u32_e32 v80, v93, v80
	v_max_u32_e32 v93, v78, v79
	v_min_u32_e32 v78, v78, v79
	v_max_u32_e32 v79, v92, v85
	v_min_u32_e32 v85, v92, v85
	v_max_u32_e32 v92, v94, v91
	v_min_u32_e32 v91, v94, v91
	v_max_u32_e32 v3, v103, v105
	v_min_u32_e32 v103, v103, v105
	v_max_u32_e32 v105, v104, v115
	v_min_u32_e32 v104, v104, v115
	v_max_u32_e32 v115, v88, v98
	v_min_u32_e32 v88, v88, v98
	v_max_u32_e32 v98, v87, v86
	v_min_u32_e32 v86, v87, v86
	v_max_u32_e32 v87, v101, v2
	v_min_u32_e32 v2, v101, v2
	v_max_u32_e32 v101, v0, v1
	v_min_u32_e32 v0, v0, v1
	v_max_u32_e32 v1, v100, v89
	v_min_u32_e32 v89, v100, v89
	v_max_u32_e32 v100, v102, v99
	v_min_u32_e32 v99, v102, v99
	v_max_u32_e32 v94, v81, v97
	v_min_u32_e32 v81, v81, v97
	v_max_u32_e32 v97, v95, v96
	v_min_u32_e32 v95, v95, v96
	v_max_u32_e32 v96, v106, v90
	v_min_u32_e32 v90, v106, v90
	v_max_u32_e32 v106, v84, v82
	v_min_u32_e32 v82, v84, v82
	v_max_u32_e32 v84, v78, v80
	v_min_u32_e32 v78, v78, v80
	v_max_u32_e32 v80, v93, v83
	v_min_u32_e32 v83, v93, v83
	v_max_u32_e32 v93, v91, v85
	v_min_u32_e32 v85, v91, v85
	v_max_u32_e32 v91, v92, v79
	v_min_u32_e32 v79, v92, v79
	v_max_u32_e32 v102, v3, v105
	v_min_u32_e32 v3, v3, v105
	v_max_u32_e32 v105, v103, v104
	v_min_u32_e32 v103, v103, v104
	v_max_u32_e32 v104, v115, v98
	v_min_u32_e32 v98, v115, v98
	v_max_u32_e32 v115, v88, v86
	v_min_u32_e32 v86, v88, v86
	v_max_u32_e32 v88, v0, v2
	v_min_u32_e32 v0, v0, v2
	v_max_u32_e32 v2, v101, v87
	v_min_u32_e32 v87, v101, v87
	v_max_u32_e32 v101, v99, v89
	v_min_u32_e32 v89, v99, v89
	v_max_u32_e32 v99, v100, v1
	v_min_u32_e32 v1, v100, v1
	v_max_u32_e32 v92, v94, v78
	v_min_u32_e32 v78, v94, v78
	v_max_u32_e32 v94, v81, v84
	v_min_u32_e32 v81, v81, v84
	v_max_u32_e32 v84, v97, v83
	v_min_u32_e32 v83, v97, v83
	v_max_u32_e32 v97, v95, v80
	v_min_u32_e32 v80, v95, v80
	v_max_u32_e32 v95, v96, v85
	v_min_u32_e32 v85, v96, v85
	v_max_u32_e32 v96, v90, v93
	v_min_u32_e32 v90, v90, v93
	v_max_u32_e32 v93, v106, v79
	v_min_u32_e32 v79, v106, v79
	v_max_u32_e32 v106, v82, v91
	v_min_u32_e32 v82, v82, v91
	v_max_u32_e32 v100, v102, v0
	v_min_u32_e32 v0, v102, v0
	v_max_u32_e32 v102, v3, v88
	v_min_u32_e32 v3, v3, v88
	v_max_u32_e32 v88, v105, v87
	v_min_u32_e32 v87, v105, v87
	v_max_u32_e32 v105, v103, v2
	v_min_u32_e32 v2, v103, v2
	v_max_u32_e32 v103, v104, v89
	v_min_u32_e32 v89, v104, v89
	v_max_u32_e32 v104, v98, v101
	v_min_u32_e32 v98, v98, v101
	v_max_u32_e32 v101, v115, v1
	v_min_u32_e32 v1, v115, v1
	v_max_u32_e32 v115, v86, v99
	v_min_u32_e32 v86, v86, v99
	v_max_u32_e32 v91, v92, v95
	v_min_u32_e32 v92, v92, v95
	v_max_u32_e32 v95, v94, v96
; #define CE_DESC(a, b) do { const unsigned _mx = (a) > (b) ? (a) : (b), _mn = (a) > (b) ? (b) : (a); (a) = _mx; (b) = _mn; } while (0)
; __device__ __forceinline__ void sort16_desc(unsigned (&k)[16]) {
; #pragma unroll
;     for (int size = 2; size <= 16; size <<= 1)
; #pragma unroll
;         for (int stride = size >> 1; stride > 0; stride >>= 1)
; #pragma unroll
;             for (int i = 0; i < 16; ++i) { const int j = i ^ stride;
;                 if (j > i) { if ((i & size) == 0) CE_DESC(k[i], k[j]); else CE_DESC(k[j], k[i]); } }
; }
; __device__ __forceinline__ void merge16(unsigned (&a)[16], const unsigned (&b)[16]) {
; #pragma unroll
;     for (int i = 0; i < 16; ++i) a[i] = a[i] > b[15 - i] ? a[i] : b[15 - i];
; #pragma unroll
;     for (int stride = 8; stride > 0; stride >>= 1)
; #pragma unroll
;         for (int i = 0; i < 16; ++i) { const int j = i ^ stride; if (j > i) CE_DESC(a[i], a[j]); }
; }
; __device__ __forceinline__ void peer_tile(const Args& A, LAS unsigned char* lds, int tile) {
;     ...
;                 for (int msk = 16; msk <= 32; msk <<= 1) {
; #pragma unroll
;                     for (int i = 0; i < 16; ++i) k1[i] = (unsigned)__shfl_xor((int)k0[i], msk);
;                     merge16(k0, k1); }
	v_min_u32_e32 v94, v94, v96
	v_max_u32_e32 v96, v84, v93
	v_min_u32_e32 v84, v84, v93
	v_max_u32_e32 v93, v97, v106
	v_min_u32_e32 v97, v97, v106
	v_max_u32_e32 v106, v78, v85
	v_min_u32_e32 v78, v78, v85
	v_max_u32_e32 v85, v81, v90
	v_min_u32_e32 v81, v81, v90
	v_max_u32_e32 v90, v83, v79
	v_min_u32_e32 v79, v83, v79
	v_max_u32_e32 v83, v80, v82
	v_min_u32_e32 v80, v80, v82
	v_max_u32_e32 v99, v100, v103
	v_min_u32_e32 v100, v100, v103
	v_max_u32_e32 v103, v102, v104
	v_min_u32_e32 v102, v102, v104
	v_max_u32_e32 v104, v88, v101
	v_min_u32_e32 v88, v88, v101
	v_max_u32_e32 v101, v105, v115
	v_min_u32_e32 v105, v105, v115
	v_max_u32_e32 v115, v0, v89
	v_min_u32_e32 v0, v0, v89
	v_max_u32_e32 v89, v3, v98
	v_min_u32_e32 v3, v3, v98
	v_max_u32_e32 v98, v87, v1
	v_min_u32_e32 v1, v87, v1
	v_max_u32_e32 v87, v2, v86
	v_min_u32_e32 v2, v2, v86
	v_max_u32_e32 v82, v91, v96
	v_min_u32_e32 v91, v91, v96
	v_max_u32_e32 v96, v95, v93
	v_min_u32_e32 v93, v95, v93
	v_max_u32_e32 v95, v92, v84
	v_min_u32_e32 v84, v92, v84
	v_max_u32_e32 v92, v94, v97
	v_min_u32_e32 v94, v94, v97
	v_max_u32_e32 v97, v106, v90
	v_min_u32_e32 v90, v106, v90
	v_max_u32_e32 v106, v85, v83
	v_min_u32_e32 v83, v85, v83
	v_max_u32_e32 v85, v78, v79
	v_min_u32_e32 v78, v78, v79
	v_max_u32_e32 v79, v81, v80
	v_min_u32_e32 v80, v81, v80
	v_max_u32_e32 v86, v99, v104
	v_min_u32_e32 v99, v99, v104
	v_max_u32_e32 v104, v103, v101
	v_min_u32_e32 v101, v103, v101
	v_max_u32_e32 v103, v100, v88
	v_min_u32_e32 v88, v100, v88
	v_max_u32_e32 v100, v102, v105
	v_min_u32_e32 v102, v102, v105
	v_max_u32_e32 v105, v115, v98
	v_min_u32_e32 v98, v115, v98
	v_max_u32_e32 v115, v89, v87
	v_min_u32_e32 v87, v89, v87
	v_max_u32_e32 v89, v0, v1
	v_min_u32_e32 v0, v0, v1
	v_max_u32_e32 v1, v3, v2
	v_min_u32_e32 v2, v3, v2
	v_min_u32_e32 v81, v82, v96
	v_min_u32_e32 v107, v91, v93
	v_min_u32_e32 v108, v95, v92
	v_min_u32_e32 v109, v84, v94
	v_min_u32_e32 v110, v97, v106
	v_min_u32_e32 v111, v90, v83
	v_min_u32_e32 v112, v85, v79
	v_min_u32_e32 v114, v78, v80
	v_min_u32_e32 v3, v86, v104
	v_min_u32_e32 v116, v99, v101
	v_min_u32_e32 v117, v103, v100
	v_min_u32_e32 v118, v88, v102
	v_min_u32_e32 v119, v105, v115
	v_min_u32_e32 v120, v98, v87
	v_min_u32_e32 v121, v89, v1
	v_min_u32_e32 v122, v0, v2
	v_max3_u32 v82, v82, v96, v122
	v_max3_u32 v0, v81, v0, v2
	v_max3_u32 v2, v91, v93, v121
	v_max3_u32 v1, v107, v89, v1
	v_max3_u32 v81, v95, v92, v120
	v_max3_u32 v87, v108, v98, v87
	v_max3_u32 v84, v84, v94, v119
	v_max3_u32 v89, v109, v105, v115
	v_max3_u32 v91, v97, v106, v118
	v_max3_u32 v88, v110, v88, v102
	v_max3_u32 v83, v90, v83, v117
	v_max3_u32 v90, v111, v103, v100
	v_max3_u32 v79, v85, v79, v116
	v_max3_u32 v85, v112, v99, v101
	v_max3_u32 v3, v78, v80, v3
	v_max3_u32 v78, v114, v86, v104
	v_max_u32_e32 v80, v82, v91
	v_min_u32_e32 v82, v82, v91
	v_max_u32_e32 v86, v0, v88
	v_min_u32_e32 v0, v0, v88
	v_max_u32_e32 v88, v2, v83
	v_min_u32_e32 v2, v2, v83
	v_max_u32_e32 v83, v1, v90
	v_min_u32_e32 v1, v1, v90
	v_max_u32_e32 v90, v81, v79
	v_min_u32_e32 v79, v81, v79
	v_max_u32_e32 v81, v87, v85
	v_min_u32_e32 v85, v87, v85
	v_max_u32_e32 v87, v84, v3
	v_min_u32_e32 v3, v84, v3
	v_max_u32_e32 v84, v89, v78
	v_min_u32_e32 v78, v89, v78
	v_max_u32_e32 v89, v80, v90
	v_min_u32_e32 v80, v80, v90
	v_max_u32_e32 v90, v86, v81
	v_min_u32_e32 v81, v86, v81
	v_max_u32_e32 v86, v88, v87
	v_min_u32_e32 v87, v88, v87
	v_max_u32_e32 v88, v83, v84
	v_min_u32_e32 v83, v83, v84
	v_max_u32_e32 v84, v82, v79
	v_min_u32_e32 v79, v82, v79
	v_max_u32_e32 v82, v0, v85
	v_min_u32_e32 v0, v0, v85
	v_max_u32_e32 v85, v2, v3
	v_min_u32_e32 v2, v2, v3
	v_max_u32_e32 v3, v1, v78
	v_min_u32_e32 v1, v1, v78
	v_max_u32_e32 v78, v89, v86
	v_min_u32_e32 v86, v89, v86
	v_max_u32_e32 v89, v90, v88
	v_min_u32_e32 v88, v90, v88
	v_max_u32_e32 v90, v80, v87
	v_min_u32_e32 v80, v80, v87
	v_max_u32_e32 v87, v81, v83
	v_min_u32_e32 v81, v81, v83
	v_max_u32_e32 v83, v84, v85
	v_min_u32_e32 v84, v84, v85
	v_max_u32_e32 v85, v82, v3
	v_min_u32_e32 v3, v82, v3
	v_max_u32_e32 v82, v79, v2
	v_min_u32_e32 v2, v79, v2
	v_max_u32_e32 v79, v0, v1
	v_min_u32_e32 v0, v0, v1
	v_max_u32_e32 v1, v78, v89
	v_min_u32_e32 v78, v78, v89
	v_max_u32_e32 v89, v86, v88
	v_min_u32_e32 v86, v86, v88
	v_max_u32_e32 v88, v90, v87
	v_min_u32_e32 v87, v90, v87
	v_max_u32_e32 v90, v80, v81
	v_min_u32_e32 v80, v80, v81
	v_max_u32_e32 v81, v83, v85
	v_min_u32_e32 v83, v83, v85
	v_max_u32_e32 v85, v84, v3
	v_min_u32_e32 v3, v84, v3
	v_max_u32_e32 v84, v82, v79
	v_min_u32_e32 v79, v82, v79
	v_max_u32_e32 v82, v2, v0
	v_min_u32_e32 v0, v2, v0
	ds_bpermute_b32 v2, v27, v1
	ds_bpermute_b32 v91, v27, v78
	ds_bpermute_b32 v92, v27, v89
	ds_bpermute_b32 v93, v27, v86
	ds_bpermute_b32 v94, v27, v88
	ds_bpermute_b32 v95, v27, v87
	ds_bpermute_b32 v96, v27, v90
	ds_bpermute_b32 v97, v27, v80
	ds_bpermute_b32 v98, v27, v81
	ds_bpermute_b32 v99, v27, v83
	ds_bpermute_b32 v100, v27, v85
	ds_bpermute_b32 v101, v27, v0
	ds_bpermute_b32 v102, v27, v82
	ds_bpermute_b32 v103, v27, v79
	ds_bpermute_b32 v104, v27, v84
	ds_bpermute_b32 v105, v27, v3
	s_waitcnt lgkmcnt(4)
	v_max_u32_e32 v1, v1, v101
	s_waitcnt lgkmcnt(3)
	v_max_u32_e32 v78, v78, v102
	s_waitcnt lgkmcnt(2)
	v_max_u32_e32 v89, v89, v103
	s_waitcnt lgkmcnt(1)
	v_max_u32_e32 v86, v86, v104
	s_waitcnt lgkmcnt(0)
; #define CE_DESC(a, b) do { const unsigned _mx = (a) > (b) ? (a) : (b), _mn = (a) > (b) ? (b) : (a); (a) = _mx; (b) = _mn; } while (0)
; __device__ __forceinline__ void merge16(unsigned (&a)[16], const unsigned (&b)[16]) {
; #pragma unroll
;     for (int i = 0; i < 16; ++i) a[i] = a[i] > b[15 - i] ? a[i] : b[15 - i];
; #pragma unroll
;     for (int stride = 8; stride > 0; stride >>= 1)
; #pragma unroll
;         for (int i = 0; i < 16; ++i) { const int j = i ^ stride; if (j > i) CE_DESC(a[i], a[j]); }
; }
; __device__ __forceinline__ void peer_tile(const Args& A, LAS unsigned char* lds, int tile) {
;     ...
;                 { const bf16_t* sp = QRY + m * 2048 + hp * 128 + 32 * g;
;                   const u32x4 s0 = *(const u32x4*)sp, s1 = *(const u32x4*)(sp + 8), s2 = *(const u32x4*)(sp + 16), s3 = *(const u32x4*)(sp + 24);
;                   const unsigned sw[16] = {s0.x, s0.y, s0.z, s0.w, s1.x, s1.y, s1.z, s1.w, s2.x, s2.y, s2.z, s2.w, s3.x, s3.y, s3.z, s3.w};
;     ...
;                 for (int msk = 16; msk <= 32; msk <<= 1) {
; #pragma unroll
;                     for (int i = 0; i < 16; ++i) k1[i] = (unsigned)__shfl_xor((int)k0[i], msk);
;                     merge16(k0, k1); }
	v_max_u32_e32 v88, v88, v105
	v_max_u32_e32 v87, v87, v100
	v_max_u32_e32 v90, v90, v99
	v_max_u32_e32 v80, v80, v98
	v_max_u32_e32 v81, v81, v97
	v_max_u32_e32 v83, v83, v96
	v_max_u32_e32 v85, v85, v95
	v_max_u32_e32 v3, v3, v94
	v_max_u32_e32 v84, v84, v93
	v_max_u32_e32 v79, v79, v92
	v_max_u32_e32 v82, v82, v91
	v_max_u32_e32 v0, v0, v2
	v_max_u32_e32 v2, v1, v81
	v_min_u32_e32 v1, v1, v81
	v_max_u32_e32 v81, v78, v83
	v_min_u32_e32 v78, v78, v83
	v_max_u32_e32 v83, v89, v85
	v_min_u32_e32 v85, v89, v85
	v_max_u32_e32 v89, v86, v3
	v_min_u32_e32 v3, v86, v3
	v_max_u32_e32 v86, v88, v84
	v_min_u32_e32 v84, v88, v84
	v_max_u32_e32 v88, v87, v79
	v_min_u32_e32 v79, v87, v79
	v_max_u32_e32 v87, v90, v82
	v_min_u32_e32 v82, v90, v82
	v_max_u32_e32 v90, v80, v0
	v_min_u32_e32 v0, v80, v0
	v_max_u32_e32 v80, v2, v86
	v_min_u32_e32 v2, v2, v86
	v_max_u32_e32 v86, v81, v88
	v_min_u32_e32 v81, v81, v88
	v_max_u32_e32 v88, v83, v87
	v_min_u32_e32 v83, v83, v87
	v_max_u32_e32 v87, v89, v90
	v_min_u32_e32 v89, v89, v90
	v_max_u32_e32 v90, v1, v84
	v_min_u32_e32 v1, v1, v84
	v_max_u32_e32 v84, v78, v79
	v_min_u32_e32 v78, v78, v79
	v_max_u32_e32 v79, v85, v82
	v_min_u32_e32 v82, v85, v82
	v_max_u32_e32 v85, v3, v0
	v_min_u32_e32 v0, v3, v0
	v_max_u32_e32 v3, v80, v88
	v_min_u32_e32 v80, v80, v88
	v_max_u32_e32 v88, v86, v87
	v_min_u32_e32 v86, v86, v87
	v_max_u32_e32 v87, v2, v83
	v_min_u32_e32 v2, v2, v83
	v_max_u32_e32 v83, v81, v89
	v_min_u32_e32 v81, v81, v89
	v_max_u32_e32 v89, v90, v79
	v_min_u32_e32 v79, v90, v79
	v_max_u32_e32 v90, v84, v85
	v_min_u32_e32 v84, v84, v85
	v_max_u32_e32 v85, v1, v82
	v_min_u32_e32 v1, v1, v82
	v_max_u32_e32 v82, v78, v0
	v_min_u32_e32 v0, v78, v0
	v_max_u32_e32 v78, v3, v88
	v_min_u32_e32 v3, v3, v88
	v_max_u32_e32 v88, v80, v86
	v_min_u32_e32 v80, v80, v86
	v_max_u32_e32 v86, v87, v83
	v_min_u32_e32 v83, v87, v83
	v_max_u32_e32 v87, v2, v81
	v_min_u32_e32 v2, v2, v81
	v_max_u32_e32 v81, v89, v90
	v_min_u32_e32 v89, v89, v90
	v_max_u32_e32 v90, v79, v84
	v_min_u32_e32 v79, v79, v84
	v_max_u32_e32 v84, v85, v82
	v_min_u32_e32 v82, v85, v82
	v_max_u32_e32 v85, v1, v0
	v_min_u32_e32 v0, v1, v0
	ds_bpermute_b32 v94, v29, v0
	ds_bpermute_b32 v1, v29, v78
	ds_bpermute_b32 v91, v29, v3
	ds_bpermute_b32 v92, v29, v88
	ds_bpermute_b32 v93, v29, v80
	s_waitcnt lgkmcnt(4)
	v_max_u32_e32 v78, v78, v94
	global_load_dwordx4 v[94:97], v[4:5], off offset:1040
	global_load_dwordx4 v[98:101], v[4:5], off offset:1024
	ds_bpermute_b32 v102, v29, v86
	ds_bpermute_b32 v103, v29, v83
	ds_bpermute_b32 v104, v29, v87
	ds_bpermute_b32 v105, v29, v2
	ds_bpermute_b32 v106, v29, v81
	ds_bpermute_b32 v107, v29, v89
	ds_bpermute_b32 v108, v29, v90
	ds_bpermute_b32 v109, v29, v79
	ds_bpermute_b32 v110, v29, v84
	ds_bpermute_b32 v111, v29, v85
	ds_bpermute_b32 v112, v29, v82
	s_waitcnt lgkmcnt(4)
	v_max_u32_e32 v83, v83, v108
	s_waitcnt lgkmcnt(3)
	v_max_u32_e32 v86, v86, v109
	s_waitcnt lgkmcnt(2)
	v_max_u32_e32 v80, v80, v110
	s_waitcnt lgkmcnt(1)
	v_max_u32_e32 v3, v3, v111
	s_waitcnt lgkmcnt(0)
	v_max_u32_e32 v88, v88, v112
	v_max_u32_e32 v87, v87, v107
	v_max_u32_e32 v2, v2, v106
	v_max_u32_e32 v81, v81, v105
	v_max_u32_e32 v89, v89, v104
	v_max_u32_e32 v90, v90, v103
	v_max_u32_e32 v79, v79, v102
	v_max_u32_e32 v84, v84, v93
	v_max_u32_e32 v82, v82, v92
	v_max_u32_e32 v85, v85, v91
	v_max_u32_e32 v0, v0, v1
	v_max_u32_e32 v1, v78, v81
	v_min_u32_e32 v78, v78, v81
	v_max_u32_e32 v81, v3, v89
	v_min_u32_e32 v3, v3, v89
	v_max_u32_e32 v89, v88, v90
	v_min_u32_e32 v88, v88, v90
	v_max_u32_e32 v90, v80, v79
	v_min_u32_e32 v79, v80, v79
	v_max_u32_e32 v80, v86, v84
	v_min_u32_e32 v84, v86, v84
	v_max_u32_e32 v86, v83, v82
	v_min_u32_e32 v82, v83, v82
	v_max_u32_e32 v83, v87, v85
	v_min_u32_e32 v85, v87, v85
	v_max_u32_e32 v87, v2, v0
	v_min_u32_e32 v0, v2, v0
	v_max_u32_e32 v2, v1, v80
	v_min_u32_e32 v1, v1, v80
	v_max_u32_e32 v80, v81, v86
	v_min_u32_e32 v81, v81, v86
	v_max_u32_e32 v86, v89, v83
	v_min_u32_e32 v83, v89, v83
	v_max_u32_e32 v89, v90, v87
	v_min_u32_e32 v87, v90, v87
	v_max_u32_e32 v90, v78, v84
	v_min_u32_e32 v78, v78, v84
	v_max_u32_e32 v84, v3, v82
	v_min_u32_e32 v3, v3, v82
	v_max_u32_e32 v82, v88, v85
	v_min_u32_e32 v85, v88, v85
	v_max_u32_e32 v88, v79, v0
	v_min_u32_e32 v0, v79, v0
	v_max_u32_e32 v79, v2, v86
	v_min_u32_e32 v2, v2, v86
	v_max_u32_e32 v86, v80, v89
	v_min_u32_e32 v80, v80, v89
	v_max_u32_e32 v102, v1, v83
	v_min_u32_e32 v1, v1, v83
	v_max_u32_e32 v83, v81, v87
	v_min_u32_e32 v81, v81, v87
	v_max_u32_e32 v103, v90, v82
	v_min_u32_e32 v82, v90, v82
	v_max_u32_e32 v104, v84, v88
	v_min_u32_e32 v105, v84, v88
	v_max_u32_e32 v106, v78, v85
	v_min_u32_e32 v78, v78, v85
	v_max_u32_e32 v107, v3, v0
	v_min_u32_e32 v0, v3, v0
	v_max_u32_e32 v93, v79, v86
	v_min_u32_e32 v92, v79, v86
	v_max_u32_e32 v91, v2, v80
	v_min_u32_e32 v90, v2, v80
	v_max_u32_e32 v89, v102, v83
	v_min_u32_e32 v88, v102, v83
	v_max_u32_e32 v87, v1, v81
	v_min_u32_e32 v86, v1, v81
	v_max_u32_e32 v85, v103, v104
	v_min_u32_e32 v84, v103, v104
	v_max_u32_e32 v83, v82, v105
	v_min_u32_e32 v82, v82, v105
	v_max_u32_e32 v79, v78, v0
	v_min_u32_e32 v78, v78, v0
	global_load_dwordx4 v[0:3], v[4:5], off offset:1072
	global_load_dwordx4 v[102:105], v[4:5], off offset:1056
	v_max_u32_e32 v81, v106, v107
	v_min_u32_e32 v80, v106, v107
	s_waitcnt vmcnt(2)
; __device__ __forceinline__ unsigned f2key(float f) { const unsigned u = __float_as_uint(f); return (u & 0x80000000u) ? ~u : (u | 0x80000000u); }
; __device__ __forceinline__ void peer_tile(const Args& A, LAS unsigned char* lds, int tile) {
;     ...
;                 { const bf16_t* sp = QRY + m * 2048 + hp * 128 + 32 * g;
;                   const u32x4 s0 = *(const u32x4*)sp, s1 = *(const u32x4*)(sp + 8), s2 = *(const u32x4*)(sp + 16), s3 = *(const u32x4*)(sp + 24);
;                   const unsigned sw[16] = {s0.x, s0.y, s0.z, s0.w, s1.x, s1.y, s1.z, s1.w, s2.x, s2.y, s2.z, s2.w, s3.x, s3.y, s3.z, s3.w};
; #pragma unroll
;                   for (int i = 0; i < 16; ++i) {
;                       const float lo = (float)__builtin_bit_cast(_Float16, (unsigned short)(sw[i] & 0xffffu)), hi = (float)__builtin_bit_cast(_Float16, (unsigned short)(sw[i] >> 16));
;                       const unsigned klo = (f2key(lo) & ~127u) | (unsigned)(127 - (32 * g + 2 * i)), khi = (f2key(hi) & ~127u) | (unsigned)(127 - (32 * g + 2 * i + 1));
;                       if (i < 8) { k0[2 * i] = klo; k0[2 * i + 1] = khi; } else { k1[2 * (i - 8)] = klo; k1[2 * (i - 8) + 1] = khi; } } }
;     ...
;                 for (int i = 0; i < 16; ++i) L2[p][i] = (g & 2) ? ((g & 1) ? LA[3][p][i] : LA[2][p][i]) : ((g & 1) ? LA[1][p][i] : LA[0][p][i]);
	v_cvt_f32_f16_sdwa v106, v98 dst_sel:DWORD dst_unused:UNUSED_PAD src0_sel:WORD_1
	v_cvt_f32_f16_e32 v98, v98
	v_cndmask_b32_e64 v34, v66, v34, s[0:1]
	v_cndmask_b32_e64 v33, v65, v33, s[0:1]
	v_not_b32_e32 v107, v106
	v_or_b32_e32 v108, 0x80000000, v106
	v_cmp_gt_i32_e32 vcc, 0, v106
	v_cndmask_b32_e64 v32, v64, v32, s[0:1]
	v_cndmask_b32_e64 v31, v63, v31, s[0:1]
	v_cndmask_b32_e32 v106, v108, v107, vcc
	v_not_b32_e32 v107, v98
	v_or_b32_e32 v108, 0x80000000, v98
	v_cmp_gt_i32_e32 vcc, 0, v98
	v_and_b32_e32 v106, 0xffffff80, v106
	v_sub_u32_e32 v106, v106, v15
	v_cndmask_b32_e32 v98, v108, v107, vcc
	v_cvt_f32_f16_sdwa v107, v99 dst_sel:DWORD dst_unused:UNUSED_PAD src0_sel:WORD_1
	v_cvt_f32_f16_e32 v99, v99
	v_and_b32_e32 v98, 0xffffff80, v98
	v_sub_u32_e32 v98, v98, v15
	v_not_b32_e32 v108, v107
	v_or_b32_e32 v109, 0x80000000, v107
	v_cmp_gt_i32_e32 vcc, 0, v107
	v_add_u32_e32 v106, 0x7e, v106
	v_add_u32_e32 v98, 0x7f, v98
	v_cndmask_b32_e32 v107, v109, v108, vcc
	v_not_b32_e32 v108, v99
	v_or_b32_e32 v109, 0x80000000, v99
	v_cmp_gt_i32_e32 vcc, 0, v99
	v_and_b32_e32 v107, 0xffffff80, v107
	v_sub_u32_e32 v107, v107, v14
	v_cndmask_b32_e32 v99, v109, v108, vcc
	v_cvt_f32_f16_sdwa v108, v100 dst_sel:DWORD dst_unused:UNUSED_PAD src0_sel:WORD_1
	v_cvt_f32_f16_e32 v100, v100
	v_and_b32_e32 v99, 0xffffff80, v99
	v_sub_u32_e32 v99, v99, v14
	v_not_b32_e32 v109, v108
	v_or_b32_e32 v110, 0x80000000, v108
	v_cmp_gt_i32_e32 vcc, 0, v108
	v_add_u32_e32 v107, 0x7e, v107
	v_add_u32_e32 v99, 0x7f, v99
	v_cndmask_b32_e32 v108, v110, v109, vcc
	v_not_b32_e32 v109, v100
	v_or_b32_e32 v110, 0x80000000, v100
	v_cmp_gt_i32_e32 vcc, 0, v100
	v_and_b32_e32 v108, 0xffffff80, v108
	v_sub_u32_e32 v108, v108, v12
	v_cndmask_b32_e32 v100, v110, v109, vcc
	v_cvt_f32_f16_sdwa v109, v101 dst_sel:DWORD dst_unused:UNUSED_PAD src0_sel:WORD_1
	v_cvt_f32_f16_e32 v101, v101
	v_and_b32_e32 v100, 0xffffff80, v100
	v_sub_u32_e32 v100, v100, v12
	v_not_b32_e32 v110, v109
	v_or_b32_e32 v111, 0x80000000, v109
	v_cmp_gt_i32_e32 vcc, 0, v109
	v_add_u32_e32 v108, 0x7e, v108
	v_add_u32_e32 v100, 0x7f, v100
	v_cndmask_b32_e32 v109, v111, v110, vcc
	v_not_b32_e32 v110, v101
	v_or_b32_e32 v111, 0x80000000, v101
	v_cmp_gt_i32_e32 vcc, 0, v101
	v_and_b32_e32 v109, 0xffffff80, v109
	v_sub_u32_e32 v109, v109, v10
	v_cndmask_b32_e32 v101, v111, v110, vcc
	v_cvt_f32_f16_sdwa v110, v94 dst_sel:DWORD dst_unused:UNUSED_PAD src0_sel:WORD_1
	v_cvt_f32_f16_e32 v94, v94
	v_and_b32_e32 v101, 0xffffff80, v101
	v_sub_u32_e32 v101, v101, v10
	v_not_b32_e32 v111, v110
	v_or_b32_e32 v112, 0x80000000, v110
	v_cmp_gt_i32_e32 vcc, 0, v110
	v_add_u32_e32 v109, 0x7e, v109
	v_add_u32_e32 v101, 0x7f, v101
	v_cndmask_b32_e32 v110, v112, v111, vcc
	v_not_b32_e32 v111, v94
	v_or_b32_e32 v112, 0x80000000, v94
	v_cmp_gt_i32_e32 vcc, 0, v94
	v_and_b32_e32 v110, 0xffffff80, v110
	v_sub_u32_e32 v110, v110, v8
	v_cndmask_b32_e32 v94, v112, v111, vcc
	v_cvt_f32_f16_sdwa v111, v95 dst_sel:DWORD dst_unused:UNUSED_PAD src0_sel:WORD_1
	v_cvt_f32_f16_e32 v95, v95
	v_and_b32_e32 v94, 0xffffff80, v94
	v_sub_u32_e32 v94, v94, v8
	v_not_b32_e32 v112, v111
	v_or_b32_e32 v114, 0x80000000, v111
	v_cmp_gt_i32_e32 vcc, 0, v111
	v_add_u32_e32 v110, 0x7e, v110
	v_add_u32_e32 v94, 0x7f, v94
	v_cndmask_b32_e32 v111, v114, v112, vcc
	v_not_b32_e32 v112, v95
	v_or_b32_e32 v114, 0x80000000, v95
	v_cmp_gt_i32_e32 vcc, 0, v95
	v_and_b32_e32 v111, 0xffffff80, v111
	v_sub_u32_e32 v111, v111, v16
	v_cndmask_b32_e32 v95, v114, v112, vcc
	v_cvt_f32_f16_sdwa v112, v96 dst_sel:DWORD dst_unused:UNUSED_PAD src0_sel:WORD_1
	v_cvt_f32_f16_e32 v96, v96
	v_and_b32_e32 v95, 0xffffff80, v95
	v_sub_u32_e32 v95, v95, v16
	v_not_b32_e32 v114, v112
	v_or_b32_e32 v115, 0x80000000, v112
	v_cmp_gt_i32_e32 vcc, 0, v112
	v_add_u32_e32 v111, 0x7e, v111
	v_add_u32_e32 v95, 0x7f, v95
	v_cndmask_b32_e32 v112, v115, v114, vcc
	v_not_b32_e32 v114, v96
	v_or_b32_e32 v115, 0x80000000, v96
	v_cmp_gt_i32_e32 vcc, 0, v96
	v_and_b32_e32 v112, 0xffffff80, v112
	v_sub_u32_e32 v112, v112, v17
	v_cndmask_b32_e32 v96, v115, v114, vcc
	v_cvt_f32_f16_sdwa v114, v97 dst_sel:DWORD dst_unused:UNUSED_PAD src0_sel:WORD_1
	v_cvt_f32_f16_e32 v97, v97
	v_and_b32_e32 v96, 0xffffff80, v96
	v_sub_u32_e32 v96, v96, v17
	v_not_b32_e32 v115, v114
	v_or_b32_e32 v116, 0x80000000, v114
	v_cmp_gt_i32_e32 vcc, 0, v114
	v_add_u32_e32 v112, 0x7e, v112
	v_add_u32_e32 v96, 0x7f, v96
	v_cndmask_b32_e32 v114, v116, v115, vcc
	v_not_b32_e32 v115, v97
	v_or_b32_e32 v116, 0x80000000, v97
	v_cmp_gt_i32_e32 vcc, 0, v97
	v_and_b32_e32 v114, 0xffffff80, v114
	v_sub_u32_e32 v114, v114, v18
	v_cndmask_b32_e32 v97, v116, v115, vcc
	s_waitcnt vmcnt(0)
; __device__ __forceinline__ unsigned f2key(float f) { const unsigned u = __float_as_uint(f); return (u & 0x80000000u) ? ~u : (u | 0x80000000u); }
; #define CE_DESC(a, b) do { const unsigned _mx = (a) > (b) ? (a) : (b), _mn = (a) > (b) ? (b) : (a); (a) = _mx; (b) = _mn; } while (0)
; __device__ __forceinline__ void sort16_desc(unsigned (&k)[16]) {
; #pragma unroll
;     for (int size = 2; size <= 16; size <<= 1)
; #pragma unroll
;         for (int stride = size >> 1; stride > 0; stride >>= 1)
; #pragma unroll
;             for (int i = 0; i < 16; ++i) { const int j = i ^ stride;
;                 if (j > i) { if ((i & size) == 0) CE_DESC(k[i], k[j]); else CE_DESC(k[j], k[i]); } }
; }
; __device__ __forceinline__ void peer_tile(const Args& A, LAS unsigned char* lds, int tile) {
;     ...
;                 { const bf16_t* sp = QRY + m * 2048 + hp * 128 + 32 * g;
;                   const u32x4 s0 = *(const u32x4*)sp, s1 = *(const u32x4*)(sp + 8), s2 = *(const u32x4*)(sp + 16), s3 = *(const u32x4*)(sp + 24);
;                   const unsigned sw[16] = {s0.x, s0.y, s0.z, s0.w, s1.x, s1.y, s1.z, s1.w, s2.x, s2.y, s2.z, s2.w, s3.x, s3.y, s3.z, s3.w};
; #pragma unroll
;                   for (int i = 0; i < 16; ++i) {
;                       const float lo = (float)__builtin_bit_cast(_Float16, (unsigned short)(sw[i] & 0xffffu)), hi = (float)__builtin_bit_cast(_Float16, (unsigned short)(sw[i] >> 16));
;                       const unsigned klo = (f2key(lo) & ~127u) | (unsigned)(127 - (32 * g + 2 * i)), khi = (f2key(hi) & ~127u) | (unsigned)(127 - (32 * g + 2 * i + 1));
;                       if (i < 8) { k0[2 * i] = klo; k0[2 * i + 1] = khi; } else { k1[2 * (i - 8)] = klo; k1[2 * (i - 8) + 1] = khi; } } }
	v_cvt_f32_f16_sdwa v115, v102 dst_sel:DWORD dst_unused:UNUSED_PAD src0_sel:WORD_1
	v_cvt_f32_f16_e32 v102, v102
	v_and_b32_e32 v97, 0xffffff80, v97
	v_sub_u32_e32 v97, v97, v18
	v_not_b32_e32 v116, v115
	v_or_b32_e32 v117, 0x80000000, v115
	v_cmp_gt_i32_e32 vcc, 0, v115
	v_add_u32_e32 v114, 0x7e, v114
	v_add_u32_e32 v97, 0x7f, v97
	v_cndmask_b32_e32 v115, v117, v116, vcc
	v_not_b32_e32 v116, v102
	v_or_b32_e32 v117, 0x80000000, v102
	v_cmp_gt_i32_e32 vcc, 0, v102
	v_and_b32_e32 v115, 0xffffff80, v115
	v_sub_u32_e32 v115, v115, v20
	v_cndmask_b32_e32 v102, v117, v116, vcc
	v_cvt_f32_f16_sdwa v116, v103 dst_sel:DWORD dst_unused:UNUSED_PAD src0_sel:WORD_1
	v_cvt_f32_f16_e32 v103, v103
	v_and_b32_e32 v102, 0xffffff80, v102
	v_sub_u32_e32 v102, v102, v20
	v_not_b32_e32 v117, v116
	v_or_b32_e32 v118, 0x80000000, v116
	v_cmp_gt_i32_e32 vcc, 0, v116
	v_add_u32_e32 v115, 0x7e, v115
	v_add_u32_e32 v102, 0x7f, v102
	v_cndmask_b32_e32 v116, v118, v117, vcc
	v_not_b32_e32 v117, v103
	v_or_b32_e32 v118, 0x80000000, v103
	v_cmp_gt_i32_e32 vcc, 0, v103
	v_and_b32_e32 v116, 0xffffff80, v116
	v_sub_u32_e32 v116, v116, v21
	v_cndmask_b32_e32 v103, v118, v117, vcc
	v_cvt_f32_f16_sdwa v117, v104 dst_sel:DWORD dst_unused:UNUSED_PAD src0_sel:WORD_1
	v_cvt_f32_f16_e32 v104, v104
	v_and_b32_e32 v103, 0xffffff80, v103
	v_sub_u32_e32 v103, v103, v21
	v_not_b32_e32 v118, v117
	v_or_b32_e32 v119, 0x80000000, v117
	v_cmp_gt_i32_e32 vcc, 0, v117
	v_add_u32_e32 v116, 0x7e, v116
	v_add_u32_e32 v103, 0x7f, v103
	v_cndmask_b32_e32 v117, v119, v118, vcc
	v_not_b32_e32 v118, v104
	v_or_b32_e32 v119, 0x80000000, v104
	v_cmp_gt_i32_e32 vcc, 0, v104
	v_and_b32_e32 v117, 0xffffff80, v117
	v_sub_u32_e32 v117, v117, v22
	v_cndmask_b32_e32 v104, v119, v118, vcc
	v_cvt_f32_f16_sdwa v118, v105 dst_sel:DWORD dst_unused:UNUSED_PAD src0_sel:WORD_1
	v_cvt_f32_f16_e32 v105, v105
	v_and_b32_e32 v104, 0xffffff80, v104
	v_sub_u32_e32 v104, v104, v22
	v_not_b32_e32 v119, v118
	v_or_b32_e32 v120, 0x80000000, v118
	v_cmp_gt_i32_e32 vcc, 0, v118
	v_add_u32_e32 v117, 0x7e, v117
	v_add_u32_e32 v104, 0x7f, v104
	v_cndmask_b32_e32 v118, v120, v119, vcc
	v_not_b32_e32 v119, v105
	v_or_b32_e32 v120, 0x80000000, v105
	v_cmp_gt_i32_e32 vcc, 0, v105
	v_and_b32_e32 v118, 0xffffff80, v118
	v_sub_u32_e32 v118, v118, v23
	v_cndmask_b32_e32 v105, v120, v119, vcc
	v_cvt_f32_f16_sdwa v119, v0 dst_sel:DWORD dst_unused:UNUSED_PAD src0_sel:WORD_1
	v_cvt_f32_f16_e32 v0, v0
	v_and_b32_e32 v105, 0xffffff80, v105
	v_sub_u32_e32 v105, v105, v23
	v_not_b32_e32 v120, v119
	v_or_b32_e32 v121, 0x80000000, v119
	v_cmp_gt_i32_e32 vcc, 0, v119
	v_add_u32_e32 v118, 0x7e, v118
	v_add_u32_e32 v105, 0x7f, v105
	v_cndmask_b32_e32 v119, v121, v120, vcc
	v_not_b32_e32 v120, v0
	v_or_b32_e32 v121, 0x80000000, v0
	v_cmp_gt_i32_e32 vcc, 0, v0
	v_and_b32_e32 v119, 0xffffff80, v119
	v_sub_u32_e32 v119, v119, v24
	v_cndmask_b32_e32 v0, v121, v120, vcc
	v_cvt_f32_f16_sdwa v120, v1 dst_sel:DWORD dst_unused:UNUSED_PAD src0_sel:WORD_1
	v_cvt_f32_f16_e32 v1, v1
	v_and_b32_e32 v0, 0xffffff80, v0
	v_sub_u32_e32 v0, v0, v24
	v_not_b32_e32 v121, v120
	v_or_b32_e32 v122, 0x80000000, v120
	v_cmp_gt_i32_e32 vcc, 0, v120
	v_add_u32_e32 v119, 0x7e, v119
	v_add_u32_e32 v0, 0x7f, v0
	v_cndmask_b32_e32 v120, v122, v121, vcc
	v_not_b32_e32 v121, v1
	v_or_b32_e32 v122, 0x80000000, v1
	v_cmp_gt_i32_e32 vcc, 0, v1
	v_and_b32_e32 v120, 0xffffff80, v120
	v_sub_u32_e32 v120, v120, v25
	v_cndmask_b32_e32 v1, v122, v121, vcc
	v_cvt_f32_f16_sdwa v121, v2 dst_sel:DWORD dst_unused:UNUSED_PAD src0_sel:WORD_1
	v_cvt_f32_f16_e32 v2, v2
	v_and_b32_e32 v1, 0xffffff80, v1
	v_sub_u32_e32 v1, v1, v25
	v_not_b32_e32 v122, v121
	v_or_b32_e32 v123, 0x80000000, v121
	v_cmp_gt_i32_e32 vcc, 0, v121
	v_add_u32_e32 v120, 0x7e, v120
	v_add_u32_e32 v1, 0x7f, v1
	v_cndmask_b32_e32 v121, v123, v122, vcc
	v_not_b32_e32 v122, v2
	v_or_b32_e32 v123, 0x80000000, v2
	v_cmp_gt_i32_e32 vcc, 0, v2
	v_and_b32_e32 v121, 0xffffff80, v121
	v_sub_u32_e32 v121, v121, v26
	v_cndmask_b32_e32 v2, v123, v122, vcc
	v_cvt_f32_f16_sdwa v122, v3 dst_sel:DWORD dst_unused:UNUSED_PAD src0_sel:WORD_1
	v_cvt_f32_f16_e32 v3, v3
	v_and_b32_e32 v2, 0xffffff80, v2
	v_sub_u32_e32 v2, v2, v26
	v_not_b32_e32 v123, v122
	v_or_b32_e32 v124, 0x80000000, v122
	v_cmp_gt_i32_e32 vcc, 0, v122
	v_add_u32_e32 v121, 0x7e, v121
	v_add_u32_e32 v2, 0x7f, v2
	v_cndmask_b32_e32 v122, v124, v123, vcc
	v_not_b32_e32 v123, v3
	v_or_b32_e32 v124, 0x80000000, v3
	v_cmp_gt_i32_e32 vcc, 0, v3
	v_and_b32_e32 v122, 0xffffff80, v122
	v_sub_u32_e32 v122, v122, v28
	v_cndmask_b32_e32 v3, v124, v123, vcc
	v_and_b32_e32 v3, 0xffffff80, v3
	v_sub_u32_e32 v3, v3, v28
	v_add_u32_e32 v122, 0x7e, v122
	v_add_u32_e32 v3, 0x7f, v3
	v_max_u32_e32 v123, v98, v106
	v_min_u32_e32 v98, v98, v106
	v_max_u32_e32 v106, v107, v99
	v_min_u32_e32 v99, v107, v99
	v_max_u32_e32 v107, v100, v108
	v_min_u32_e32 v100, v100, v108
	v_max_u32_e32 v108, v109, v101
	v_min_u32_e32 v101, v109, v101
	v_max_u32_e32 v109, v94, v110
	v_min_u32_e32 v94, v94, v110
	v_max_u32_e32 v110, v111, v95
	v_min_u32_e32 v95, v111, v95
	v_max_u32_e32 v111, v96, v112
	v_min_u32_e32 v96, v96, v112
	v_max_u32_e32 v112, v114, v97
	v_min_u32_e32 v97, v114, v97
	v_max_u32_e32 v131, v102, v115
	v_min_u32_e32 v102, v102, v115
	v_max_u32_e32 v115, v116, v103
	v_min_u32_e32 v103, v116, v103
	v_max_u32_e32 v116, v104, v117
	v_min_u32_e32 v104, v104, v117
	v_max_u32_e32 v117, v118, v105
	v_min_u32_e32 v105, v118, v105
	v_max_u32_e32 v118, v0, v119
	v_min_u32_e32 v0, v0, v119
	v_max_u32_e32 v119, v120, v1
	v_min_u32_e32 v1, v120, v1
	v_max_u32_e32 v120, v2, v121
	v_min_u32_e32 v2, v2, v121
; #define CE_DESC(a, b) do { const unsigned _mx = (a) > (b) ? (a) : (b), _mn = (a) > (b) ? (b) : (a); (a) = _mx; (b) = _mn; } while (0)
; __device__ __forceinline__ void sort16_desc(unsigned (&k)[16]) {
; #pragma unroll
;     for (int size = 2; size <= 16; size <<= 1)
; #pragma unroll
;         for (int stride = size >> 1; stride > 0; stride >>= 1)
; #pragma unroll
;             for (int i = 0; i < 16; ++i) { const int j = i ^ stride;
;                 if (j > i) { if ((i & size) == 0) CE_DESC(k[i], k[j]); else CE_DESC(k[j], k[i]); } }
; }
	v_max_u32_e32 v121, v122, v3
	v_min_u32_e32 v3, v122, v3
	v_max_u32_e32 v114, v123, v99
	v_min_u32_e32 v99, v123, v99
	v_max_u32_e32 v123, v98, v106
	v_min_u32_e32 v98, v98, v106
	v_max_u32_e32 v106, v101, v107
	v_min_u32_e32 v101, v101, v107
	v_max_u32_e32 v107, v108, v100
	v_min_u32_e32 v100, v108, v100
	v_max_u32_e32 v108, v109, v95
	v_min_u32_e32 v95, v109, v95
	v_max_u32_e32 v109, v94, v110
	v_min_u32_e32 v94, v94, v110
	v_max_u32_e32 v110, v97, v111
	v_min_u32_e32 v97, v97, v111
	v_max_u32_e32 v111, v112, v96
	v_min_u32_e32 v96, v112, v96
	v_max_u32_e32 v122, v131, v103
	v_min_u32_e32 v103, v131, v103
	v_max_u32_e32 v131, v102, v115
	v_min_u32_e32 v102, v102, v115
	v_max_u32_e32 v115, v105, v116
	v_min_u32_e32 v105, v105, v116
	v_max_u32_e32 v116, v117, v104
	v_min_u32_e32 v104, v117, v104
	v_max_u32_e32 v117, v118, v1
	v_min_u32_e32 v1, v118, v1
	v_max_u32_e32 v118, v0, v119
	v_min_u32_e32 v0, v0, v119
	v_max_u32_e32 v119, v3, v120
	v_min_u32_e32 v3, v3, v120
	v_max_u32_e32 v120, v121, v2
	v_min_u32_e32 v2, v121, v2
	v_max_u32_e32 v112, v114, v123
	v_min_u32_e32 v114, v114, v123
	v_max_u32_e32 v123, v99, v98
	v_min_u32_e32 v98, v99, v98
	v_max_u32_e32 v99, v100, v101
	v_min_u32_e32 v100, v100, v101
	v_max_u32_e32 v101, v107, v106
	v_min_u32_e32 v106, v107, v106
	v_max_u32_e32 v107, v108, v109
	v_min_u32_e32 v108, v108, v109
	v_max_u32_e32 v109, v95, v94
	v_min_u32_e32 v94, v95, v94
	v_max_u32_e32 v95, v96, v97
	v_min_u32_e32 v96, v96, v97
	v_max_u32_e32 v97, v111, v110
	v_min_u32_e32 v110, v111, v110
	v_max_u32_e32 v121, v122, v131
	v_min_u32_e32 v122, v122, v131
	v_max_u32_e32 v131, v103, v102
	v_min_u32_e32 v102, v103, v102
	v_max_u32_e32 v103, v104, v105
	v_min_u32_e32 v104, v104, v105
	v_max_u32_e32 v105, v116, v115
	v_min_u32_e32 v115, v116, v115
	v_max_u32_e32 v116, v117, v118
	v_min_u32_e32 v117, v117, v118
	v_max_u32_e32 v118, v1, v0
	v_min_u32_e32 v0, v1, v0
	v_max_u32_e32 v1, v2, v3
	v_min_u32_e32 v2, v2, v3
	v_max_u32_e32 v3, v120, v119
	v_min_u32_e32 v119, v120, v119
	v_max_u32_e32 v111, v112, v100
	v_min_u32_e32 v100, v112, v100
	v_max_u32_e32 v112, v114, v99
	v_min_u32_e32 v99, v114, v99
	v_max_u32_e32 v114, v123, v106
	v_min_u32_e32 v106, v123, v106
	v_max_u32_e32 v123, v98, v101
	v_min_u32_e32 v98, v98, v101
	v_max_u32_e32 v101, v96, v107
	v_min_u32_e32 v96, v96, v107
	v_max_u32_e32 v107, v95, v108
	v_min_u32_e32 v95, v95, v108
	v_max_u32_e32 v108, v110, v109
	v_min_u32_e32 v109, v110, v109
	v_max_u32_e32 v110, v97, v94
	v_min_u32_e32 v94, v97, v94
	v_max_u32_e32 v120, v121, v104
	v_min_u32_e32 v104, v121, v104
	v_max_u32_e32 v121, v122, v103
	v_min_u32_e32 v103, v122, v103
	v_max_u32_e32 v122, v131, v115
	v_min_u32_e32 v115, v131, v115
	v_max_u32_e32 v131, v102, v105
	v_min_u32_e32 v102, v102, v105
	v_max_u32_e32 v105, v2, v116
	v_min_u32_e32 v2, v2, v116
	v_max_u32_e32 v116, v1, v117
	v_min_u32_e32 v1, v1, v117
	v_max_u32_e32 v117, v119, v118
	v_min_u32_e32 v118, v119, v118
	v_max_u32_e32 v119, v3, v0
	v_min_u32_e32 v0, v3, v0
	v_max_u32_e32 v97, v111, v114
	v_min_u32_e32 v111, v111, v114
	v_max_u32_e32 v114, v112, v123
	v_min_u32_e32 v112, v112, v123
	v_max_u32_e32 v123, v100, v106
	v_min_u32_e32 v100, v100, v106
	v_max_u32_e32 v106, v99, v98
	v_min_u32_e32 v98, v99, v98
	v_max_u32_e32 v99, v109, v96
	v_min_u32_e32 v96, v109, v96
	v_max_u32_e32 v109, v94, v95
	v_min_u32_e32 v94, v94, v95
	v_max_u32_e32 v95, v108, v101
	v_min_u32_e32 v101, v108, v101
	v_max_u32_e32 v108, v110, v107
	v_min_u32_e32 v107, v110, v107
	v_max_u32_e32 v3, v120, v122
	v_min_u32_e32 v120, v120, v122
	v_max_u32_e32 v122, v121, v131
	v_min_u32_e32 v121, v121, v131
	v_max_u32_e32 v131, v104, v115
	v_min_u32_e32 v104, v104, v115
	v_max_u32_e32 v115, v103, v102
	v_min_u32_e32 v102, v103, v102
	v_max_u32_e32 v103, v118, v2
	v_min_u32_e32 v2, v118, v2
	v_max_u32_e32 v118, v0, v1
	v_min_u32_e32 v0, v0, v1
	v_max_u32_e32 v1, v117, v105
	v_min_u32_e32 v105, v117, v105
	v_max_u32_e32 v117, v119, v116
	v_min_u32_e32 v116, v119, v116
	v_max_u32_e32 v110, v97, v114
	v_min_u32_e32 v97, v97, v114
	v_max_u32_e32 v114, v111, v112
	v_min_u32_e32 v111, v111, v112
	v_max_u32_e32 v112, v123, v106
	v_min_u32_e32 v106, v123, v106
	v_max_u32_e32 v123, v100, v98
	v_min_u32_e32 v98, v100, v98
	v_max_u32_e32 v100, v94, v96
	v_min_u32_e32 v94, v94, v96
	v_max_u32_e32 v96, v109, v99
	v_min_u32_e32 v99, v109, v99
	v_max_u32_e32 v109, v107, v101
	v_min_u32_e32 v101, v107, v101
	v_max_u32_e32 v107, v108, v95
	v_min_u32_e32 v95, v108, v95
	v_max_u32_e32 v119, v3, v122
	v_min_u32_e32 v3, v3, v122
	v_max_u32_e32 v122, v120, v121
	v_min_u32_e32 v120, v120, v121
	v_max_u32_e32 v121, v131, v115
	v_min_u32_e32 v115, v131, v115
	v_max_u32_e32 v131, v104, v102
	v_min_u32_e32 v102, v104, v102
	v_max_u32_e32 v104, v0, v2
	v_min_u32_e32 v0, v0, v2
	v_max_u32_e32 v2, v118, v103
	v_min_u32_e32 v103, v118, v103
	v_max_u32_e32 v118, v116, v105
	v_min_u32_e32 v105, v116, v105
	v_max_u32_e32 v116, v117, v1
	v_min_u32_e32 v1, v117, v1
	v_max_u32_e32 v108, v110, v94
	v_min_u32_e32 v94, v110, v94
	v_max_u32_e32 v110, v97, v100
	v_min_u32_e32 v97, v97, v100
	v_max_u32_e32 v100, v114, v99
	v_min_u32_e32 v99, v114, v99
	v_max_u32_e32 v114, v111, v96
	v_min_u32_e32 v96, v111, v96
	v_max_u32_e32 v111, v112, v101
	v_min_u32_e32 v101, v112, v101
	v_max_u32_e32 v112, v106, v109
	v_min_u32_e32 v106, v106, v109
	v_max_u32_e32 v109, v123, v95
	v_min_u32_e32 v95, v123, v95
	v_max_u32_e32 v123, v98, v107
	v_min_u32_e32 v98, v98, v107
	v_max_u32_e32 v117, v119, v0
	v_min_u32_e32 v0, v119, v0
	v_max_u32_e32 v119, v3, v104
	v_min_u32_e32 v3, v3, v104
	v_max_u32_e32 v104, v122, v103
	v_min_u32_e32 v103, v122, v103
; #define CE_DESC(a, b) do { const unsigned _mx = (a) > (b) ? (a) : (b), _mn = (a) > (b) ? (b) : (a); (a) = _mx; (b) = _mn; } while (0)
; __device__ __forceinline__ void sort16_desc(unsigned (&k)[16]) {
; #pragma unroll
;     for (int size = 2; size <= 16; size <<= 1)
; #pragma unroll
;         for (int stride = size >> 1; stride > 0; stride >>= 1)
; #pragma unroll
;             for (int i = 0; i < 16; ++i) { const int j = i ^ stride;
;                 if (j > i) { if ((i & size) == 0) CE_DESC(k[i], k[j]); else CE_DESC(k[j], k[i]); } }
; }
; __device__ __forceinline__ void merge16(unsigned (&a)[16], const unsigned (&b)[16]) {
; #pragma unroll
;     for (int i = 0; i < 16; ++i) a[i] = a[i] > b[15 - i] ? a[i] : b[15 - i];
; #pragma unroll
;     for (int stride = 8; stride > 0; stride >>= 1)
; #pragma unroll
;         for (int i = 0; i < 16; ++i) { const int j = i ^ stride; if (j > i) CE_DESC(a[i], a[j]); }
; }
; __device__ __forceinline__ void peer_tile(const Args& A, LAS unsigned char* lds, int tile) {
;     ...
;                 for (int msk = 16; msk <= 32; msk <<= 1) {
; #pragma unroll
;                     for (int i = 0; i < 16; ++i) k1[i] = (unsigned)__shfl_xor((int)k0[i], msk);
;                     merge16(k0, k1); }
	v_max_u32_e32 v122, v120, v2
	v_min_u32_e32 v2, v120, v2
	v_max_u32_e32 v120, v121, v105
	v_min_u32_e32 v105, v121, v105
	v_max_u32_e32 v121, v115, v118
	v_min_u32_e32 v115, v115, v118
	v_max_u32_e32 v118, v131, v1
	v_min_u32_e32 v1, v131, v1
	v_max_u32_e32 v131, v102, v116
	v_min_u32_e32 v102, v102, v116
	v_max_u32_e32 v107, v108, v111
	v_min_u32_e32 v108, v108, v111
	v_max_u32_e32 v111, v110, v112
	v_min_u32_e32 v110, v110, v112
	v_max_u32_e32 v112, v100, v109
	v_min_u32_e32 v100, v100, v109
	v_max_u32_e32 v109, v114, v123
	v_min_u32_e32 v114, v114, v123
	v_max_u32_e32 v123, v94, v101
	v_min_u32_e32 v94, v94, v101
	v_max_u32_e32 v101, v97, v106
	v_min_u32_e32 v97, v97, v106
	v_max_u32_e32 v106, v99, v95
	v_min_u32_e32 v95, v99, v95
	v_max_u32_e32 v99, v96, v98
	v_min_u32_e32 v96, v96, v98
	v_max_u32_e32 v116, v117, v120
	v_min_u32_e32 v117, v117, v120
	v_max_u32_e32 v120, v119, v121
	v_min_u32_e32 v119, v119, v121
	v_max_u32_e32 v121, v104, v118
	v_min_u32_e32 v104, v104, v118
	v_max_u32_e32 v118, v122, v131
	v_min_u32_e32 v122, v122, v131
	v_max_u32_e32 v131, v0, v105
	v_min_u32_e32 v0, v0, v105
	v_max_u32_e32 v105, v3, v115
	v_min_u32_e32 v3, v3, v115
	v_max_u32_e32 v115, v103, v1
	v_min_u32_e32 v1, v103, v1
	v_max_u32_e32 v103, v2, v102
	v_min_u32_e32 v2, v2, v102
	v_max_u32_e32 v98, v107, v112
	v_min_u32_e32 v107, v107, v112
	v_max_u32_e32 v112, v111, v109
	v_min_u32_e32 v109, v111, v109
	v_max_u32_e32 v111, v108, v100
	v_min_u32_e32 v100, v108, v100
	v_max_u32_e32 v108, v110, v114
	v_min_u32_e32 v110, v110, v114
	v_max_u32_e32 v114, v123, v106
	v_min_u32_e32 v106, v123, v106
	v_max_u32_e32 v123, v101, v99
	v_min_u32_e32 v99, v101, v99
	v_max_u32_e32 v101, v94, v95
	v_min_u32_e32 v94, v94, v95
	v_max_u32_e32 v95, v97, v96
	v_min_u32_e32 v96, v97, v96
	v_max_u32_e32 v102, v116, v121
	v_min_u32_e32 v116, v116, v121
	v_max_u32_e32 v121, v120, v118
	v_min_u32_e32 v118, v120, v118
	v_max_u32_e32 v120, v117, v104
	v_min_u32_e32 v104, v117, v104
	v_max_u32_e32 v117, v119, v122
	v_min_u32_e32 v119, v119, v122
	v_max_u32_e32 v122, v131, v115
	v_min_u32_e32 v115, v131, v115
	v_max_u32_e32 v131, v105, v103
	v_min_u32_e32 v103, v105, v103
	v_max_u32_e32 v105, v0, v1
	v_min_u32_e32 v0, v0, v1
	v_max_u32_e32 v1, v3, v2
	v_min_u32_e32 v2, v3, v2
	v_min_u32_e32 v97, v98, v112
	v_min_u32_e32 v124, v107, v109
	v_min_u32_e32 v125, v111, v108
	v_min_u32_e32 v126, v100, v110
	v_min_u32_e32 v127, v114, v123
	v_min_u32_e32 v128, v106, v99
	v_min_u32_e32 v129, v101, v95
	v_min_u32_e32 v130, v94, v96
	v_min_u32_e32 v3, v102, v121
	v_min_u32_e32 v132, v116, v118
	v_min_u32_e32 v133, v120, v117
	v_min_u32_e32 v134, v104, v119
	v_min_u32_e32 v135, v122, v131
	v_min_u32_e32 v136, v115, v103
	v_min_u32_e32 v137, v105, v1
	v_min_u32_e32 v138, v0, v2
	v_max3_u32 v98, v98, v112, v138
	v_max3_u32 v0, v97, v0, v2
	v_max3_u32 v2, v107, v109, v137
	v_max3_u32 v1, v124, v105, v1
	v_max3_u32 v97, v111, v108, v136
	v_max3_u32 v103, v125, v115, v103
	v_max3_u32 v100, v100, v110, v135
	v_max3_u32 v105, v126, v122, v131
	v_max3_u32 v107, v114, v123, v134
	v_max3_u32 v104, v127, v104, v119
	v_max3_u32 v99, v106, v99, v133
	v_max3_u32 v106, v128, v120, v117
	v_max3_u32 v95, v101, v95, v132
	v_max3_u32 v101, v129, v116, v118
	v_max3_u32 v3, v94, v96, v3
	v_max3_u32 v94, v130, v102, v121
	v_max_u32_e32 v96, v98, v107
	v_min_u32_e32 v98, v98, v107
	v_max_u32_e32 v102, v0, v104
	v_min_u32_e32 v0, v0, v104
	v_max_u32_e32 v104, v2, v99
	v_min_u32_e32 v2, v2, v99
	v_max_u32_e32 v99, v1, v106
	v_min_u32_e32 v1, v1, v106
	v_max_u32_e32 v106, v97, v95
	v_min_u32_e32 v95, v97, v95
	v_max_u32_e32 v97, v103, v101
	v_min_u32_e32 v101, v103, v101
	v_max_u32_e32 v103, v100, v3
	v_min_u32_e32 v3, v100, v3
	v_max_u32_e32 v100, v105, v94
	v_min_u32_e32 v94, v105, v94
	v_max_u32_e32 v105, v96, v106
	v_min_u32_e32 v96, v96, v106
	v_max_u32_e32 v106, v102, v97
	v_min_u32_e32 v97, v102, v97
	v_max_u32_e32 v102, v104, v103
	v_min_u32_e32 v103, v104, v103
	v_max_u32_e32 v104, v99, v100
	v_min_u32_e32 v99, v99, v100
	v_max_u32_e32 v100, v98, v95
	v_min_u32_e32 v95, v98, v95
	v_max_u32_e32 v98, v0, v101
	v_min_u32_e32 v0, v0, v101
	v_max_u32_e32 v101, v2, v3
	v_min_u32_e32 v2, v2, v3
	v_max_u32_e32 v3, v1, v94
	v_min_u32_e32 v1, v1, v94
	v_max_u32_e32 v94, v105, v102
	v_min_u32_e32 v102, v105, v102
	v_max_u32_e32 v105, v106, v104
	v_min_u32_e32 v104, v106, v104
	v_max_u32_e32 v106, v96, v103
	v_min_u32_e32 v96, v96, v103
	v_max_u32_e32 v103, v97, v99
	v_min_u32_e32 v97, v97, v99
	v_max_u32_e32 v99, v100, v101
	v_min_u32_e32 v100, v100, v101
	v_max_u32_e32 v101, v98, v3
	v_min_u32_e32 v3, v98, v3
	v_max_u32_e32 v98, v95, v2
	v_min_u32_e32 v2, v95, v2
	v_max_u32_e32 v95, v0, v1
	v_min_u32_e32 v0, v0, v1
	v_max_u32_e32 v1, v94, v105
	v_min_u32_e32 v94, v94, v105
	v_max_u32_e32 v105, v102, v104
	v_min_u32_e32 v102, v102, v104
	v_max_u32_e32 v104, v106, v103
	v_min_u32_e32 v103, v106, v103
	v_max_u32_e32 v106, v96, v97
	v_min_u32_e32 v96, v96, v97
	v_max_u32_e32 v97, v99, v101
	v_min_u32_e32 v99, v99, v101
	v_max_u32_e32 v101, v100, v3
	v_min_u32_e32 v3, v100, v3
	v_max_u32_e32 v100, v98, v95
	v_min_u32_e32 v95, v98, v95
	v_max_u32_e32 v98, v2, v0
	v_min_u32_e32 v0, v2, v0
	ds_bpermute_b32 v2, v27, v1
	ds_bpermute_b32 v107, v27, v94
	ds_bpermute_b32 v108, v27, v105
	ds_bpermute_b32 v109, v27, v102
	ds_bpermute_b32 v110, v27, v104
	ds_bpermute_b32 v111, v27, v103
	ds_bpermute_b32 v112, v27, v106
	ds_bpermute_b32 v114, v27, v96
	ds_bpermute_b32 v115, v27, v97
	ds_bpermute_b32 v116, v27, v99
	ds_bpermute_b32 v117, v27, v101
	ds_bpermute_b32 v118, v27, v0
	ds_bpermute_b32 v119, v27, v98
	ds_bpermute_b32 v120, v27, v95
	ds_bpermute_b32 v121, v27, v100
	ds_bpermute_b32 v122, v27, v3
	s_waitcnt lgkmcnt(4)
; #define CE_DESC(a, b) do { const unsigned _mx = (a) > (b) ? (a) : (b), _mn = (a) > (b) ? (b) : (a); (a) = _mx; (b) = _mn; } while (0)
; __device__ __forceinline__ void merge16(unsigned (&a)[16], const unsigned (&b)[16]) {
; #pragma unroll
;     for (int i = 0; i < 16; ++i) a[i] = a[i] > b[15 - i] ? a[i] : b[15 - i];
; #pragma unroll
;     for (int stride = 8; stride > 0; stride >>= 1)
; #pragma unroll
;         for (int i = 0; i < 16; ++i) { const int j = i ^ stride; if (j > i) CE_DESC(a[i], a[j]); }
; }
; __device__ __forceinline__ void peer_tile(const Args& A, LAS unsigned char* lds, int tile) {
;     ...
;                 { const bf16_t* sp = QRY + m * 2048 + hp * 128 + 32 * g;
;                   const u32x4 s0 = *(const u32x4*)sp, s1 = *(const u32x4*)(sp + 8), s2 = *(const u32x4*)(sp + 16), s3 = *(const u32x4*)(sp + 24);
;                   const unsigned sw[16] = {s0.x, s0.y, s0.z, s0.w, s1.x, s1.y, s1.z, s1.w, s2.x, s2.y, s2.z, s2.w, s3.x, s3.y, s3.z, s3.w};
;     ...
;                 for (int msk = 16; msk <= 32; msk <<= 1) {
; #pragma unroll
;                     for (int i = 0; i < 16; ++i) k1[i] = (unsigned)__shfl_xor((int)k0[i], msk);
;                     merge16(k0, k1); }
	v_max_u32_e32 v1, v1, v118
	s_waitcnt lgkmcnt(3)
	v_max_u32_e32 v94, v94, v119
	s_waitcnt lgkmcnt(2)
	v_max_u32_e32 v105, v105, v120
	s_waitcnt lgkmcnt(1)
	v_max_u32_e32 v102, v102, v121
	s_waitcnt lgkmcnt(0)
	v_max_u32_e32 v104, v104, v122
	v_max_u32_e32 v103, v103, v117
	v_max_u32_e32 v106, v106, v116
	v_max_u32_e32 v96, v96, v115
	v_max_u32_e32 v97, v97, v114
	v_max_u32_e32 v99, v99, v112
	v_max_u32_e32 v101, v101, v111
	v_max_u32_e32 v3, v3, v110
	v_max_u32_e32 v100, v100, v109
	v_max_u32_e32 v95, v95, v108
	v_max_u32_e32 v98, v98, v107
	v_max_u32_e32 v0, v0, v2
	v_max_u32_e32 v2, v1, v97
	v_min_u32_e32 v1, v1, v97
	v_max_u32_e32 v97, v94, v99
	v_min_u32_e32 v94, v94, v99
	v_max_u32_e32 v99, v105, v101
	v_min_u32_e32 v101, v105, v101
	v_max_u32_e32 v105, v102, v3
	v_min_u32_e32 v3, v102, v3
	v_max_u32_e32 v102, v104, v100
	v_min_u32_e32 v100, v104, v100
	v_max_u32_e32 v104, v103, v95
	v_min_u32_e32 v95, v103, v95
	v_max_u32_e32 v103, v106, v98
	v_min_u32_e32 v98, v106, v98
	v_max_u32_e32 v106, v96, v0
	v_min_u32_e32 v0, v96, v0
	v_max_u32_e32 v96, v2, v102
	v_min_u32_e32 v2, v2, v102
	v_max_u32_e32 v102, v97, v104
	v_min_u32_e32 v97, v97, v104
	v_max_u32_e32 v104, v99, v103
	v_min_u32_e32 v99, v99, v103
	v_max_u32_e32 v103, v105, v106
	v_min_u32_e32 v105, v105, v106
	v_max_u32_e32 v106, v1, v100
	v_min_u32_e32 v1, v1, v100
	v_max_u32_e32 v100, v94, v95
	v_min_u32_e32 v94, v94, v95
	v_max_u32_e32 v95, v101, v98
	v_min_u32_e32 v98, v101, v98
	v_max_u32_e32 v101, v3, v0
	v_min_u32_e32 v0, v3, v0
	v_max_u32_e32 v3, v96, v104
	v_min_u32_e32 v96, v96, v104
	v_max_u32_e32 v104, v102, v103
	v_min_u32_e32 v102, v102, v103
	v_max_u32_e32 v103, v2, v99
	v_min_u32_e32 v2, v2, v99
	v_max_u32_e32 v99, v97, v105
	v_min_u32_e32 v97, v97, v105
	v_max_u32_e32 v105, v106, v95
	v_min_u32_e32 v95, v106, v95
	v_max_u32_e32 v106, v100, v101
	v_min_u32_e32 v100, v100, v101
	v_max_u32_e32 v101, v1, v98
	v_min_u32_e32 v1, v1, v98
	v_max_u32_e32 v98, v94, v0
	v_min_u32_e32 v0, v94, v0
	v_max_u32_e32 v94, v3, v104
	v_min_u32_e32 v3, v3, v104
	v_max_u32_e32 v104, v96, v102
	v_min_u32_e32 v96, v96, v102
	v_max_u32_e32 v102, v103, v99
	v_min_u32_e32 v99, v103, v99
	v_max_u32_e32 v103, v2, v97
	v_min_u32_e32 v2, v2, v97
	v_max_u32_e32 v97, v105, v106
	v_min_u32_e32 v105, v105, v106
	v_max_u32_e32 v106, v95, v100
	v_min_u32_e32 v95, v95, v100
	v_max_u32_e32 v100, v101, v98
	v_min_u32_e32 v98, v101, v98
	v_max_u32_e32 v101, v1, v0
	v_min_u32_e32 v0, v1, v0
	ds_bpermute_b32 v114, v29, v0
	ds_bpermute_b32 v1, v29, v94
	ds_bpermute_b32 v107, v29, v3
	ds_bpermute_b32 v108, v29, v104
	ds_bpermute_b32 v109, v29, v96
	s_waitcnt lgkmcnt(4)
	v_max_u32_e32 v94, v94, v114
	global_load_dwordx4 v[114:117], v[4:5], off offset:1296
	global_load_dwordx4 v[118:121], v[4:5], off offset:1280
	ds_bpermute_b32 v110, v29, v102
	ds_bpermute_b32 v111, v29, v99
	ds_bpermute_b32 v112, v29, v103
	ds_bpermute_b32 v122, v29, v2
	ds_bpermute_b32 v123, v29, v97
	ds_bpermute_b32 v124, v29, v105
	ds_bpermute_b32 v125, v29, v106
	ds_bpermute_b32 v126, v29, v95
	ds_bpermute_b32 v127, v29, v100
	ds_bpermute_b32 v128, v29, v101
	ds_bpermute_b32 v129, v29, v98
	s_waitcnt lgkmcnt(4)
	v_max_u32_e32 v99, v99, v125
	s_waitcnt lgkmcnt(3)
	v_max_u32_e32 v102, v102, v126
	s_waitcnt lgkmcnt(2)
	v_max_u32_e32 v96, v96, v127
	s_waitcnt lgkmcnt(1)
	v_max_u32_e32 v3, v3, v128
	s_waitcnt lgkmcnt(0)
	v_max_u32_e32 v104, v104, v129
	v_max_u32_e32 v103, v103, v124
	v_max_u32_e32 v2, v2, v123
	v_max_u32_e32 v97, v97, v122
	v_max_u32_e32 v105, v105, v112
	v_max_u32_e32 v106, v106, v111
	v_max_u32_e32 v95, v95, v110
	v_max_u32_e32 v100, v100, v109
	v_max_u32_e32 v98, v98, v108
	v_max_u32_e32 v101, v101, v107
	v_max_u32_e32 v0, v0, v1
	v_max_u32_e32 v1, v94, v97
	v_min_u32_e32 v94, v94, v97
	v_max_u32_e32 v97, v3, v105
	v_min_u32_e32 v3, v3, v105
	v_max_u32_e32 v105, v104, v106
	v_min_u32_e32 v104, v104, v106
	v_max_u32_e32 v106, v96, v95
	v_min_u32_e32 v95, v96, v95
	v_max_u32_e32 v96, v102, v100
	v_min_u32_e32 v100, v102, v100
	v_max_u32_e32 v102, v99, v98
	v_min_u32_e32 v98, v99, v98
	v_max_u32_e32 v99, v103, v101
	v_min_u32_e32 v101, v103, v101
	v_max_u32_e32 v103, v2, v0
	v_min_u32_e32 v0, v2, v0
	v_max_u32_e32 v2, v1, v96
	v_min_u32_e32 v1, v1, v96
	v_max_u32_e32 v96, v97, v102
	v_min_u32_e32 v97, v97, v102
	v_max_u32_e32 v102, v105, v99
	v_min_u32_e32 v99, v105, v99
	v_max_u32_e32 v105, v106, v103
	v_min_u32_e32 v103, v106, v103
	v_max_u32_e32 v106, v94, v100
	v_min_u32_e32 v94, v94, v100
	v_max_u32_e32 v100, v3, v98
	v_min_u32_e32 v3, v3, v98
	v_max_u32_e32 v98, v104, v101
	v_min_u32_e32 v101, v104, v101
	v_max_u32_e32 v104, v95, v0
	v_min_u32_e32 v0, v95, v0
	v_max_u32_e32 v95, v2, v102
	v_min_u32_e32 v2, v2, v102
	v_max_u32_e32 v102, v96, v105
	v_min_u32_e32 v96, v96, v105
	v_max_u32_e32 v110, v1, v99
	v_min_u32_e32 v1, v1, v99
	v_max_u32_e32 v99, v97, v103
	v_min_u32_e32 v97, v97, v103
	v_max_u32_e32 v111, v106, v98
	v_min_u32_e32 v98, v106, v98
	v_min_u32_e32 v122, v100, v104
	v_max_u32_e32 v123, v94, v101
	v_min_u32_e32 v94, v94, v101
	v_max_u32_e32 v124, v3, v0
	v_min_u32_e32 v0, v3, v0
	v_max_u32_e32 v112, v100, v104
	v_max_u32_e32 v109, v95, v102
	v_min_u32_e32 v108, v95, v102
	v_max_u32_e32 v107, v2, v96
	v_min_u32_e32 v106, v2, v96
	v_max_u32_e32 v105, v110, v99
	v_min_u32_e32 v104, v110, v99
	v_max_u32_e32 v103, v1, v97
	v_min_u32_e32 v102, v1, v97
	v_max_u32_e32 v99, v98, v122
	v_min_u32_e32 v98, v98, v122
	v_max_u32_e32 v97, v123, v124
	v_min_u32_e32 v96, v123, v124
	v_max_u32_e32 v95, v94, v0
	v_min_u32_e32 v94, v94, v0
	global_load_dwordx4 v[0:3], v[4:5], off offset:1328
	global_load_dwordx4 v[122:125], v[4:5], off offset:1312
	s_waitcnt vmcnt(2)
; __device__ __forceinline__ unsigned f2key(float f) { const unsigned u = __float_as_uint(f); return (u & 0x80000000u) ? ~u : (u | 0x80000000u); }
; __device__ __forceinline__ void peer_tile(const Args& A, LAS unsigned char* lds, int tile) {
;     ...
;                 { const bf16_t* sp = QRY + m * 2048 + hp * 128 + 32 * g;
;                   const u32x4 s0 = *(const u32x4*)sp, s1 = *(const u32x4*)(sp + 8), s2 = *(const u32x4*)(sp + 16), s3 = *(const u32x4*)(sp + 24);
;                   const unsigned sw[16] = {s0.x, s0.y, s0.z, s0.w, s1.x, s1.y, s1.z, s1.w, s2.x, s2.y, s2.z, s2.w, s3.x, s3.y, s3.z, s3.w};
; #pragma unroll
;                   for (int i = 0; i < 16; ++i) {
;                       const float lo = (float)__builtin_bit_cast(_Float16, (unsigned short)(sw[i] & 0xffffu)), hi = (float)__builtin_bit_cast(_Float16, (unsigned short)(sw[i] >> 16));
;                       const unsigned klo = (f2key(lo) & ~127u) | (unsigned)(127 - (32 * g + 2 * i)), khi = (f2key(hi) & ~127u) | (unsigned)(127 - (32 * g + 2 * i + 1));
;                       if (i < 8) { k0[2 * i] = klo; k0[2 * i + 1] = khi; } else { k1[2 * (i - 8)] = klo; k1[2 * (i - 8) + 1] = khi; } } }
;     ...
;                 for (int i = 0; i < 16; ++i) L2[p][i] = (g & 2) ? ((g & 1) ? LA[3][p][i] : LA[2][p][i]) : ((g & 1) ? LA[1][p][i] : LA[0][p][i]);
	v_cvt_f32_f16_sdwa v110, v118 dst_sel:DWORD dst_unused:UNUSED_PAD src0_sel:WORD_1
	v_max_u32_e32 v101, v111, v112
	v_min_u32_e32 v100, v111, v112
	v_cvt_f32_f16_e32 v111, v118
	v_not_b32_e32 v112, v110
	v_or_b32_e32 v118, 0x80000000, v110
	v_cmp_gt_i32_e32 vcc, 0, v110
	v_cndmask_b32_e64 v30, v62, v30, s[0:1]
	s_nop 0
	v_cndmask_b32_e32 v110, v118, v112, vcc
	v_not_b32_e32 v112, v111
	v_or_b32_e32 v118, 0x80000000, v111
	v_cmp_gt_i32_e32 vcc, 0, v111
	v_and_b32_e32 v110, 0xffffff80, v110
	v_sub_u32_e32 v110, v110, v15
	v_cndmask_b32_e32 v111, v118, v112, vcc
	v_cvt_f32_f16_sdwa v112, v119 dst_sel:DWORD dst_unused:UNUSED_PAD src0_sel:WORD_1
	v_cvt_f32_f16_e32 v118, v119
	v_and_b32_e32 v111, 0xffffff80, v111
	v_sub_u32_e32 v111, v111, v15
	v_not_b32_e32 v119, v112
	v_or_b32_e32 v126, 0x80000000, v112
	v_cmp_gt_i32_e32 vcc, 0, v112
	v_add_u32_e32 v110, 0x7e, v110
	v_add_u32_e32 v111, 0x7f, v111
	v_cndmask_b32_e32 v112, v126, v119, vcc
	v_not_b32_e32 v119, v118
	v_or_b32_e32 v126, 0x80000000, v118
	v_cmp_gt_i32_e32 vcc, 0, v118
	v_and_b32_e32 v112, 0xffffff80, v112
	v_sub_u32_e32 v112, v112, v14
	v_cndmask_b32_e32 v118, v126, v119, vcc
	v_cvt_f32_f16_sdwa v119, v120 dst_sel:DWORD dst_unused:UNUSED_PAD src0_sel:WORD_1
	v_cvt_f32_f16_e32 v120, v120
	v_and_b32_e32 v118, 0xffffff80, v118
	v_sub_u32_e32 v118, v118, v14
	v_not_b32_e32 v126, v119
	v_or_b32_e32 v127, 0x80000000, v119
	v_cmp_gt_i32_e32 vcc, 0, v119
	v_add_u32_e32 v112, 0x7e, v112
	v_add_u32_e32 v118, 0x7f, v118
	v_cndmask_b32_e32 v119, v127, v126, vcc
	v_not_b32_e32 v126, v120
	v_or_b32_e32 v127, 0x80000000, v120
	v_cmp_gt_i32_e32 vcc, 0, v120
	v_and_b32_e32 v119, 0xffffff80, v119
	v_sub_u32_e32 v119, v119, v12
	v_cndmask_b32_e32 v120, v127, v126, vcc
	v_cvt_f32_f16_sdwa v126, v121 dst_sel:DWORD dst_unused:UNUSED_PAD src0_sel:WORD_1
	v_cvt_f32_f16_e32 v121, v121
	v_and_b32_e32 v120, 0xffffff80, v120
	v_sub_u32_e32 v120, v120, v12
	v_not_b32_e32 v127, v126
	v_or_b32_e32 v128, 0x80000000, v126
	v_cmp_gt_i32_e32 vcc, 0, v126
	v_add_u32_e32 v119, 0x7e, v119
	v_add_u32_e32 v120, 0x7f, v120
	v_cndmask_b32_e32 v126, v128, v127, vcc
	v_not_b32_e32 v127, v121
	v_or_b32_e32 v128, 0x80000000, v121
	v_cmp_gt_i32_e32 vcc, 0, v121
	v_and_b32_e32 v126, 0xffffff80, v126
	v_sub_u32_e32 v126, v126, v10
	v_cndmask_b32_e32 v121, v128, v127, vcc
	v_cvt_f32_f16_sdwa v127, v114 dst_sel:DWORD dst_unused:UNUSED_PAD src0_sel:WORD_1
	v_cvt_f32_f16_e32 v114, v114
	v_and_b32_e32 v121, 0xffffff80, v121
	v_sub_u32_e32 v121, v121, v10
	v_not_b32_e32 v128, v127
	v_or_b32_e32 v129, 0x80000000, v127
	v_cmp_gt_i32_e32 vcc, 0, v127
	v_add_u32_e32 v126, 0x7e, v126
	v_add_u32_e32 v121, 0x7f, v121
	v_cndmask_b32_e32 v127, v129, v128, vcc
	v_not_b32_e32 v128, v114
	v_or_b32_e32 v129, 0x80000000, v114
	v_cmp_gt_i32_e32 vcc, 0, v114
	v_and_b32_e32 v127, 0xffffff80, v127
	v_sub_u32_e32 v127, v127, v8
	v_cndmask_b32_e32 v114, v129, v128, vcc
	v_cvt_f32_f16_sdwa v128, v115 dst_sel:DWORD dst_unused:UNUSED_PAD src0_sel:WORD_1
	v_cvt_f32_f16_e32 v115, v115
	v_and_b32_e32 v114, 0xffffff80, v114
	v_sub_u32_e32 v114, v114, v8
	v_not_b32_e32 v129, v128
	v_or_b32_e32 v130, 0x80000000, v128
	v_cmp_gt_i32_e32 vcc, 0, v128
	v_add_u32_e32 v127, 0x7e, v127
	v_add_u32_e32 v114, 0x7f, v114
	v_cndmask_b32_e32 v128, v130, v129, vcc
	v_not_b32_e32 v129, v115
	v_or_b32_e32 v130, 0x80000000, v115
	v_cmp_gt_i32_e32 vcc, 0, v115
	v_and_b32_e32 v128, 0xffffff80, v128
	v_sub_u32_e32 v128, v128, v16
	v_cndmask_b32_e32 v115, v130, v129, vcc
	v_cvt_f32_f16_sdwa v129, v116 dst_sel:DWORD dst_unused:UNUSED_PAD src0_sel:WORD_1
	v_cvt_f32_f16_e32 v116, v116
	v_and_b32_e32 v115, 0xffffff80, v115
	v_sub_u32_e32 v115, v115, v16
	v_not_b32_e32 v130, v129
	v_or_b32_e32 v131, 0x80000000, v129
	v_cmp_gt_i32_e32 vcc, 0, v129
	v_add_u32_e32 v128, 0x7e, v128
	v_add_u32_e32 v115, 0x7f, v115
	v_cndmask_b32_e32 v129, v131, v130, vcc
	v_not_b32_e32 v130, v116
	v_or_b32_e32 v131, 0x80000000, v116
	v_cmp_gt_i32_e32 vcc, 0, v116
	v_and_b32_e32 v129, 0xffffff80, v129
	v_sub_u32_e32 v129, v129, v17
	v_cndmask_b32_e32 v116, v131, v130, vcc
	v_cvt_f32_f16_sdwa v130, v117 dst_sel:DWORD dst_unused:UNUSED_PAD src0_sel:WORD_1
	v_cvt_f32_f16_e32 v117, v117
	v_and_b32_e32 v116, 0xffffff80, v116
	v_sub_u32_e32 v116, v116, v17
	v_not_b32_e32 v131, v130
	v_or_b32_e32 v132, 0x80000000, v130
	v_cmp_gt_i32_e32 vcc, 0, v130
	v_add_u32_e32 v129, 0x7e, v129
	v_add_u32_e32 v116, 0x7f, v116
	v_cndmask_b32_e32 v130, v132, v131, vcc
	v_not_b32_e32 v131, v117
	v_or_b32_e32 v132, 0x80000000, v117
	v_cmp_gt_i32_e32 vcc, 0, v117
	v_and_b32_e32 v130, 0xffffff80, v130
	v_sub_u32_e32 v130, v130, v18
	v_cndmask_b32_e32 v117, v132, v131, vcc
	s_waitcnt vmcnt(0)
; __device__ __forceinline__ unsigned f2key(float f) { const unsigned u = __float_as_uint(f); return (u & 0x80000000u) ? ~u : (u | 0x80000000u); }
; #define CE_DESC(a, b) do { const unsigned _mx = (a) > (b) ? (a) : (b), _mn = (a) > (b) ? (b) : (a); (a) = _mx; (b) = _mn; } while (0)
; __device__ __forceinline__ void sort16_desc(unsigned (&k)[16]) {
; #pragma unroll
;     for (int size = 2; size <= 16; size <<= 1)
; #pragma unroll
;         for (int stride = size >> 1; stride > 0; stride >>= 1)
; #pragma unroll
;             for (int i = 0; i < 16; ++i) { const int j = i ^ stride;
;                 if (j > i) { if ((i & size) == 0) CE_DESC(k[i], k[j]); else CE_DESC(k[j], k[i]); } }
; }
; __device__ __forceinline__ void peer_tile(const Args& A, LAS unsigned char* lds, int tile) {
;     ...
;                 { const bf16_t* sp = QRY + m * 2048 + hp * 128 + 32 * g;
;                   const u32x4 s0 = *(const u32x4*)sp, s1 = *(const u32x4*)(sp + 8), s2 = *(const u32x4*)(sp + 16), s3 = *(const u32x4*)(sp + 24);
;                   const unsigned sw[16] = {s0.x, s0.y, s0.z, s0.w, s1.x, s1.y, s1.z, s1.w, s2.x, s2.y, s2.z, s2.w, s3.x, s3.y, s3.z, s3.w};
; #pragma unroll
;                   for (int i = 0; i < 16; ++i) {
;                       const float lo = (float)__builtin_bit_cast(_Float16, (unsigned short)(sw[i] & 0xffffu)), hi = (float)__builtin_bit_cast(_Float16, (unsigned short)(sw[i] >> 16));
;                       const unsigned klo = (f2key(lo) & ~127u) | (unsigned)(127 - (32 * g + 2 * i)), khi = (f2key(hi) & ~127u) | (unsigned)(127 - (32 * g + 2 * i + 1));
;                       if (i < 8) { k0[2 * i] = klo; k0[2 * i + 1] = khi; } else { k1[2 * (i - 8)] = klo; k1[2 * (i - 8) + 1] = khi; } } }
	v_cvt_f32_f16_sdwa v131, v122 dst_sel:DWORD dst_unused:UNUSED_PAD src0_sel:WORD_1
	v_cvt_f32_f16_e32 v122, v122
	v_and_b32_e32 v117, 0xffffff80, v117
	v_sub_u32_e32 v117, v117, v18
	v_not_b32_e32 v132, v131
	v_or_b32_e32 v133, 0x80000000, v131
	v_cmp_gt_i32_e32 vcc, 0, v131
	v_add_u32_e32 v130, 0x7e, v130
	v_add_u32_e32 v117, 0x7f, v117
	v_cndmask_b32_e32 v131, v133, v132, vcc
	v_not_b32_e32 v132, v122
	v_or_b32_e32 v133, 0x80000000, v122
	v_cmp_gt_i32_e32 vcc, 0, v122
	v_and_b32_e32 v131, 0xffffff80, v131
	v_sub_u32_e32 v131, v131, v20
	v_cndmask_b32_e32 v122, v133, v132, vcc
	v_cvt_f32_f16_sdwa v132, v123 dst_sel:DWORD dst_unused:UNUSED_PAD src0_sel:WORD_1
	v_cvt_f32_f16_e32 v123, v123
	v_and_b32_e32 v122, 0xffffff80, v122
	v_sub_u32_e32 v122, v122, v20
	v_not_b32_e32 v133, v132
	v_or_b32_e32 v134, 0x80000000, v132
	v_cmp_gt_i32_e32 vcc, 0, v132
	v_add_u32_e32 v131, 0x7e, v131
	v_add_u32_e32 v122, 0x7f, v122
	v_cndmask_b32_e32 v132, v134, v133, vcc
	v_not_b32_e32 v133, v123
	v_or_b32_e32 v134, 0x80000000, v123
	v_cmp_gt_i32_e32 vcc, 0, v123
	v_and_b32_e32 v132, 0xffffff80, v132
	v_sub_u32_e32 v132, v132, v21
	v_cndmask_b32_e32 v123, v134, v133, vcc
	v_cvt_f32_f16_sdwa v133, v124 dst_sel:DWORD dst_unused:UNUSED_PAD src0_sel:WORD_1
	v_cvt_f32_f16_e32 v124, v124
	v_and_b32_e32 v123, 0xffffff80, v123
	v_sub_u32_e32 v123, v123, v21
	v_not_b32_e32 v134, v133
	v_or_b32_e32 v135, 0x80000000, v133
	v_cmp_gt_i32_e32 vcc, 0, v133
	v_add_u32_e32 v132, 0x7e, v132
	v_add_u32_e32 v123, 0x7f, v123
	v_cndmask_b32_e32 v133, v135, v134, vcc
	v_not_b32_e32 v134, v124
	v_or_b32_e32 v135, 0x80000000, v124
	v_cmp_gt_i32_e32 vcc, 0, v124
	v_and_b32_e32 v133, 0xffffff80, v133
	v_sub_u32_e32 v133, v133, v22
	v_cndmask_b32_e32 v124, v135, v134, vcc
	v_cvt_f32_f16_sdwa v134, v125 dst_sel:DWORD dst_unused:UNUSED_PAD src0_sel:WORD_1
	v_cvt_f32_f16_e32 v125, v125
	v_and_b32_e32 v124, 0xffffff80, v124
	v_sub_u32_e32 v124, v124, v22
	v_not_b32_e32 v135, v134
	v_or_b32_e32 v136, 0x80000000, v134
	v_cmp_gt_i32_e32 vcc, 0, v134
	v_add_u32_e32 v133, 0x7e, v133
	v_add_u32_e32 v124, 0x7f, v124
	v_cndmask_b32_e32 v134, v136, v135, vcc
	v_not_b32_e32 v135, v125
	v_or_b32_e32 v136, 0x80000000, v125
	v_cmp_gt_i32_e32 vcc, 0, v125
	v_and_b32_e32 v134, 0xffffff80, v134
	v_sub_u32_e32 v134, v134, v23
	v_cndmask_b32_e32 v125, v136, v135, vcc
	v_cvt_f32_f16_sdwa v135, v0 dst_sel:DWORD dst_unused:UNUSED_PAD src0_sel:WORD_1
	v_cvt_f32_f16_e32 v0, v0
	v_and_b32_e32 v125, 0xffffff80, v125
	v_sub_u32_e32 v125, v125, v23
	v_not_b32_e32 v136, v135
	v_or_b32_e32 v137, 0x80000000, v135
	v_cmp_gt_i32_e32 vcc, 0, v135
	v_add_u32_e32 v134, 0x7e, v134
	v_add_u32_e32 v125, 0x7f, v125
	v_cndmask_b32_e32 v135, v137, v136, vcc
	v_not_b32_e32 v136, v0
	v_or_b32_e32 v137, 0x80000000, v0
	v_cmp_gt_i32_e32 vcc, 0, v0
	v_and_b32_e32 v135, 0xffffff80, v135
	v_sub_u32_e32 v135, v135, v24
	v_cndmask_b32_e32 v0, v137, v136, vcc
	v_cvt_f32_f16_sdwa v136, v1 dst_sel:DWORD dst_unused:UNUSED_PAD src0_sel:WORD_1
	v_cvt_f32_f16_e32 v1, v1
	v_and_b32_e32 v0, 0xffffff80, v0
	v_sub_u32_e32 v0, v0, v24
	v_not_b32_e32 v137, v136
	v_or_b32_e32 v138, 0x80000000, v136
	v_cmp_gt_i32_e32 vcc, 0, v136
	v_add_u32_e32 v135, 0x7e, v135
	v_add_u32_e32 v0, 0x7f, v0
	v_cndmask_b32_e32 v136, v138, v137, vcc
	v_not_b32_e32 v137, v1
	v_or_b32_e32 v138, 0x80000000, v1
	v_cmp_gt_i32_e32 vcc, 0, v1
	v_and_b32_e32 v136, 0xffffff80, v136
	v_sub_u32_e32 v136, v136, v25
	v_cndmask_b32_e32 v1, v138, v137, vcc
	v_cvt_f32_f16_sdwa v137, v2 dst_sel:DWORD dst_unused:UNUSED_PAD src0_sel:WORD_1
	v_cvt_f32_f16_e32 v2, v2
	v_and_b32_e32 v1, 0xffffff80, v1
	v_sub_u32_e32 v1, v1, v25
	v_not_b32_e32 v138, v137
	v_or_b32_e32 v139, 0x80000000, v137
	v_cmp_gt_i32_e32 vcc, 0, v137
	v_add_u32_e32 v136, 0x7e, v136
	v_add_u32_e32 v1, 0x7f, v1
	v_cndmask_b32_e32 v137, v139, v138, vcc
	v_not_b32_e32 v138, v2
	v_or_b32_e32 v139, 0x80000000, v2
	v_cmp_gt_i32_e32 vcc, 0, v2
	v_and_b32_e32 v137, 0xffffff80, v137
	v_sub_u32_e32 v137, v137, v26
	v_cndmask_b32_e32 v2, v139, v138, vcc
	v_cvt_f32_f16_sdwa v138, v3 dst_sel:DWORD dst_unused:UNUSED_PAD src0_sel:WORD_1
	v_cvt_f32_f16_e32 v3, v3
	v_and_b32_e32 v2, 0xffffff80, v2
	v_sub_u32_e32 v2, v2, v26
	v_not_b32_e32 v139, v138
	v_or_b32_e32 v140, 0x80000000, v138
	v_cmp_gt_i32_e32 vcc, 0, v138
	v_add_u32_e32 v137, 0x7e, v137
	v_add_u32_e32 v2, 0x7f, v2
	v_cndmask_b32_e32 v138, v140, v139, vcc
	v_not_b32_e32 v139, v3
	v_or_b32_e32 v140, 0x80000000, v3
	v_cmp_gt_i32_e32 vcc, 0, v3
	v_and_b32_e32 v138, 0xffffff80, v138
	v_sub_u32_e32 v138, v138, v28
	v_cndmask_b32_e32 v3, v140, v139, vcc
	v_and_b32_e32 v3, 0xffffff80, v3
	v_sub_u32_e32 v3, v3, v28
	v_add_u32_e32 v138, 0x7e, v138
	v_add_u32_e32 v3, 0x7f, v3
	v_max_u32_e32 v139, v111, v110
	v_min_u32_e32 v110, v111, v110
	v_max_u32_e32 v111, v112, v118
	v_min_u32_e32 v112, v112, v118
	v_max_u32_e32 v118, v120, v119
	v_min_u32_e32 v119, v120, v119
	v_max_u32_e32 v120, v126, v121
	v_min_u32_e32 v121, v126, v121
	v_max_u32_e32 v126, v114, v127
	v_min_u32_e32 v114, v114, v127
	v_max_u32_e32 v127, v128, v115
	v_min_u32_e32 v115, v128, v115
	v_max_u32_e32 v128, v116, v129
	v_min_u32_e32 v116, v116, v129
	v_max_u32_e32 v129, v130, v117
	v_min_u32_e32 v117, v130, v117
	v_max_u32_e32 v147, v122, v131
	v_min_u32_e32 v122, v122, v131
	v_max_u32_e32 v131, v132, v123
	v_min_u32_e32 v123, v132, v123
	v_max_u32_e32 v132, v124, v133
	v_min_u32_e32 v124, v124, v133
	v_max_u32_e32 v133, v134, v125
	v_min_u32_e32 v125, v134, v125
	v_max_u32_e32 v134, v0, v135
	v_min_u32_e32 v0, v0, v135
	v_max_u32_e32 v135, v136, v1
	v_min_u32_e32 v1, v136, v1
	v_max_u32_e32 v136, v2, v137
	v_min_u32_e32 v2, v2, v137
; #define CE_DESC(a, b) do { const unsigned _mx = (a) > (b) ? (a) : (b), _mn = (a) > (b) ? (b) : (a); (a) = _mx; (b) = _mn; } while (0)
; __device__ __forceinline__ void sort16_desc(unsigned (&k)[16]) {
; #pragma unroll
;     for (int size = 2; size <= 16; size <<= 1)
; #pragma unroll
;         for (int stride = size >> 1; stride > 0; stride >>= 1)
; #pragma unroll
;             for (int i = 0; i < 16; ++i) { const int j = i ^ stride;
;                 if (j > i) { if ((i & size) == 0) CE_DESC(k[i], k[j]); else CE_DESC(k[j], k[i]); } }
; }
	v_max_u32_e32 v137, v138, v3
	v_min_u32_e32 v3, v138, v3
	v_max_u32_e32 v130, v139, v112
	v_min_u32_e32 v112, v139, v112
	v_max_u32_e32 v139, v110, v111
	v_min_u32_e32 v110, v110, v111
	v_max_u32_e32 v111, v121, v118
	v_min_u32_e32 v118, v121, v118
	v_max_u32_e32 v121, v120, v119
	v_min_u32_e32 v119, v120, v119
	v_max_u32_e32 v120, v126, v115
	v_min_u32_e32 v115, v126, v115
	v_max_u32_e32 v126, v114, v127
	v_min_u32_e32 v114, v114, v127
	v_max_u32_e32 v127, v117, v128
	v_min_u32_e32 v117, v117, v128
	v_max_u32_e32 v128, v129, v116
	v_min_u32_e32 v116, v129, v116
	v_max_u32_e32 v138, v147, v123
	v_min_u32_e32 v123, v147, v123
	v_max_u32_e32 v147, v122, v131
	v_min_u32_e32 v122, v122, v131
	v_max_u32_e32 v131, v125, v132
	v_min_u32_e32 v125, v125, v132
	v_max_u32_e32 v132, v133, v124
	v_min_u32_e32 v124, v133, v124
	v_max_u32_e32 v133, v134, v1
	v_min_u32_e32 v1, v134, v1
	v_max_u32_e32 v134, v0, v135
	v_min_u32_e32 v0, v0, v135
	v_max_u32_e32 v135, v3, v136
	v_min_u32_e32 v3, v3, v136
	v_max_u32_e32 v136, v137, v2
	v_min_u32_e32 v2, v137, v2
	v_max_u32_e32 v129, v130, v139
	v_min_u32_e32 v130, v130, v139
	v_max_u32_e32 v139, v112, v110
	v_min_u32_e32 v110, v112, v110
	v_max_u32_e32 v112, v119, v118
	v_min_u32_e32 v118, v119, v118
	v_max_u32_e32 v119, v121, v111
	v_min_u32_e32 v111, v121, v111
	v_max_u32_e32 v121, v120, v126
	v_min_u32_e32 v120, v120, v126
	v_max_u32_e32 v126, v115, v114
	v_min_u32_e32 v114, v115, v114
	v_max_u32_e32 v115, v116, v117
	v_min_u32_e32 v116, v116, v117
	v_max_u32_e32 v117, v128, v127
	v_min_u32_e32 v127, v128, v127
	v_max_u32_e32 v137, v138, v147
	v_min_u32_e32 v138, v138, v147
	v_max_u32_e32 v147, v123, v122
	v_min_u32_e32 v122, v123, v122
	v_max_u32_e32 v123, v124, v125
	v_min_u32_e32 v124, v124, v125
	v_max_u32_e32 v125, v132, v131
	v_min_u32_e32 v131, v132, v131
	v_max_u32_e32 v132, v133, v134
	v_min_u32_e32 v133, v133, v134
	v_max_u32_e32 v134, v1, v0
	v_min_u32_e32 v0, v1, v0
	v_max_u32_e32 v1, v2, v3
	v_min_u32_e32 v2, v2, v3
	v_max_u32_e32 v3, v136, v135
	v_min_u32_e32 v135, v136, v135
	v_max_u32_e32 v128, v129, v118
	v_min_u32_e32 v118, v129, v118
	v_max_u32_e32 v129, v130, v112
	v_min_u32_e32 v112, v130, v112
	v_max_u32_e32 v130, v139, v111
	v_min_u32_e32 v111, v139, v111
	v_max_u32_e32 v139, v110, v119
	v_min_u32_e32 v110, v110, v119
	v_max_u32_e32 v119, v116, v121
	v_min_u32_e32 v116, v116, v121
	v_max_u32_e32 v121, v115, v120
	v_min_u32_e32 v115, v115, v120
	v_max_u32_e32 v120, v127, v126
	v_min_u32_e32 v126, v127, v126
	v_max_u32_e32 v127, v117, v114
	v_min_u32_e32 v114, v117, v114
	v_max_u32_e32 v136, v137, v124
	v_min_u32_e32 v124, v137, v124
	v_max_u32_e32 v137, v138, v123
	v_min_u32_e32 v123, v138, v123
	v_max_u32_e32 v138, v147, v131
	v_min_u32_e32 v131, v147, v131
	v_max_u32_e32 v147, v122, v125
	v_min_u32_e32 v122, v122, v125
	v_max_u32_e32 v125, v2, v132
	v_min_u32_e32 v2, v2, v132
	v_max_u32_e32 v132, v1, v133
	v_min_u32_e32 v1, v1, v133
	v_max_u32_e32 v133, v135, v134
	v_min_u32_e32 v134, v135, v134
	v_max_u32_e32 v135, v3, v0
	v_min_u32_e32 v0, v3, v0
	v_max_u32_e32 v117, v128, v130
	v_min_u32_e32 v128, v128, v130
	v_max_u32_e32 v130, v129, v139
	v_min_u32_e32 v129, v129, v139
	v_max_u32_e32 v139, v118, v111
	v_min_u32_e32 v111, v118, v111
	v_max_u32_e32 v118, v112, v110
	v_min_u32_e32 v110, v112, v110
	v_max_u32_e32 v112, v126, v116
	v_min_u32_e32 v116, v126, v116
	v_max_u32_e32 v126, v114, v115
	v_min_u32_e32 v114, v114, v115
	v_max_u32_e32 v115, v120, v119
	v_min_u32_e32 v119, v120, v119
	v_max_u32_e32 v120, v127, v121
	v_min_u32_e32 v121, v127, v121
	v_max_u32_e32 v3, v136, v138
	v_min_u32_e32 v136, v136, v138
	v_max_u32_e32 v138, v137, v147
	v_min_u32_e32 v137, v137, v147
	v_max_u32_e32 v147, v124, v131
	v_min_u32_e32 v124, v124, v131
	v_max_u32_e32 v131, v123, v122
	v_min_u32_e32 v122, v123, v122
	v_max_u32_e32 v123, v134, v2
	v_min_u32_e32 v2, v134, v2
	v_max_u32_e32 v134, v0, v1
	v_min_u32_e32 v0, v0, v1
	v_max_u32_e32 v1, v133, v125
	v_min_u32_e32 v125, v133, v125
	v_max_u32_e32 v133, v135, v132
	v_min_u32_e32 v132, v135, v132
	v_max_u32_e32 v127, v117, v130
	v_min_u32_e32 v117, v117, v130
	v_max_u32_e32 v130, v128, v129
	v_min_u32_e32 v128, v128, v129
	v_max_u32_e32 v129, v139, v118
	v_min_u32_e32 v118, v139, v118
	v_max_u32_e32 v139, v111, v110
	v_min_u32_e32 v110, v111, v110
	v_max_u32_e32 v111, v114, v116
	v_min_u32_e32 v114, v114, v116
	v_max_u32_e32 v116, v126, v112
	v_min_u32_e32 v112, v126, v112
	v_max_u32_e32 v126, v121, v119
	v_min_u32_e32 v119, v121, v119
	v_max_u32_e32 v121, v120, v115
	v_min_u32_e32 v115, v120, v115
	v_max_u32_e32 v135, v3, v138
	v_min_u32_e32 v3, v3, v138
	v_max_u32_e32 v138, v136, v137
	v_min_u32_e32 v136, v136, v137
	v_max_u32_e32 v137, v147, v131
	v_min_u32_e32 v131, v147, v131
	v_max_u32_e32 v147, v124, v122
	v_min_u32_e32 v122, v124, v122
	v_max_u32_e32 v124, v0, v2
	v_min_u32_e32 v0, v0, v2
	v_max_u32_e32 v2, v134, v123
	v_min_u32_e32 v123, v134, v123
	v_max_u32_e32 v134, v132, v125
	v_min_u32_e32 v125, v132, v125
	v_max_u32_e32 v132, v133, v1
	v_min_u32_e32 v1, v133, v1
	v_max_u32_e32 v120, v127, v114
	v_min_u32_e32 v114, v127, v114
	v_max_u32_e32 v127, v117, v111
	v_min_u32_e32 v111, v117, v111
	v_max_u32_e32 v117, v130, v112
	v_min_u32_e32 v112, v130, v112
	v_max_u32_e32 v130, v128, v116
	v_min_u32_e32 v116, v128, v116
	v_max_u32_e32 v128, v129, v119
	v_min_u32_e32 v119, v129, v119
	v_max_u32_e32 v129, v118, v126
	v_min_u32_e32 v118, v118, v126
	v_max_u32_e32 v126, v139, v115
	v_min_u32_e32 v115, v139, v115
	v_max_u32_e32 v139, v110, v121
	v_min_u32_e32 v110, v110, v121
	v_max_u32_e32 v133, v135, v0
	v_min_u32_e32 v0, v135, v0
; #define CE_DESC(a, b) do { const unsigned _mx = (a) > (b) ? (a) : (b), _mn = (a) > (b) ? (b) : (a); (a) = _mx; (b) = _mn; } while (0)
; __device__ __forceinline__ void sort16_desc(unsigned (&k)[16]) {
; #pragma unroll
;     for (int size = 2; size <= 16; size <<= 1)
; #pragma unroll
;         for (int stride = size >> 1; stride > 0; stride >>= 1)
; #pragma unroll
;             for (int i = 0; i < 16; ++i) { const int j = i ^ stride;
;                 if (j > i) { if ((i & size) == 0) CE_DESC(k[i], k[j]); else CE_DESC(k[j], k[i]); } }
; }
; __device__ __forceinline__ void merge16(unsigned (&a)[16], const unsigned (&b)[16]) {
; #pragma unroll
;     for (int i = 0; i < 16; ++i) a[i] = a[i] > b[15 - i] ? a[i] : b[15 - i];
; #pragma unroll
;     for (int stride = 8; stride > 0; stride >>= 1)
; #pragma unroll
;         for (int i = 0; i < 16; ++i) { const int j = i ^ stride; if (j > i) CE_DESC(a[i], a[j]); }
; }
; __device__ __forceinline__ void peer_tile(const Args& A, LAS unsigned char* lds, int tile) {
;     ...
;                 for (int msk = 16; msk <= 32; msk <<= 1) {
; #pragma unroll
;                     for (int i = 0; i < 16; ++i) k1[i] = (unsigned)__shfl_xor((int)k0[i], msk);
;                     merge16(k0, k1); }
	v_max_u32_e32 v135, v3, v124
	v_min_u32_e32 v3, v3, v124
	v_max_u32_e32 v124, v138, v123
	v_min_u32_e32 v123, v138, v123
	v_max_u32_e32 v138, v136, v2
	v_min_u32_e32 v2, v136, v2
	v_max_u32_e32 v136, v137, v125
	v_min_u32_e32 v125, v137, v125
	v_max_u32_e32 v137, v131, v134
	v_min_u32_e32 v131, v131, v134
	v_max_u32_e32 v134, v147, v1
	v_min_u32_e32 v1, v147, v1
	v_max_u32_e32 v147, v122, v132
	v_min_u32_e32 v122, v122, v132
	v_max_u32_e32 v121, v120, v128
	v_min_u32_e32 v120, v120, v128
	v_max_u32_e32 v128, v127, v129
	v_min_u32_e32 v127, v127, v129
	v_max_u32_e32 v129, v117, v126
	v_min_u32_e32 v117, v117, v126
	v_max_u32_e32 v126, v130, v139
	v_min_u32_e32 v130, v130, v139
	v_max_u32_e32 v139, v114, v119
	v_min_u32_e32 v114, v114, v119
	v_max_u32_e32 v119, v111, v118
	v_min_u32_e32 v111, v111, v118
	v_max_u32_e32 v118, v112, v115
	v_min_u32_e32 v112, v112, v115
	v_max_u32_e32 v115, v116, v110
	v_min_u32_e32 v110, v116, v110
	v_max_u32_e32 v132, v133, v136
	v_min_u32_e32 v133, v133, v136
	v_max_u32_e32 v136, v135, v137
	v_min_u32_e32 v135, v135, v137
	v_max_u32_e32 v137, v124, v134
	v_min_u32_e32 v124, v124, v134
	v_max_u32_e32 v134, v138, v147
	v_min_u32_e32 v138, v138, v147
	v_max_u32_e32 v147, v0, v125
	v_min_u32_e32 v0, v0, v125
	v_max_u32_e32 v125, v3, v131
	v_min_u32_e32 v3, v3, v131
	v_max_u32_e32 v131, v123, v1
	v_min_u32_e32 v1, v123, v1
	v_max_u32_e32 v123, v2, v122
	v_min_u32_e32 v2, v2, v122
	v_max_u32_e32 v116, v121, v129
	v_min_u32_e32 v121, v121, v129
	v_max_u32_e32 v129, v128, v126
	v_min_u32_e32 v126, v128, v126
	v_max_u32_e32 v128, v120, v117
	v_min_u32_e32 v117, v120, v117
	v_max_u32_e32 v120, v127, v130
	v_min_u32_e32 v127, v127, v130
	v_max_u32_e32 v130, v139, v118
	v_min_u32_e32 v118, v139, v118
	v_max_u32_e32 v139, v119, v115
	v_min_u32_e32 v115, v119, v115
	v_max_u32_e32 v119, v114, v112
	v_min_u32_e32 v112, v114, v112
	v_max_u32_e32 v114, v111, v110
	v_min_u32_e32 v110, v111, v110
	v_max_u32_e32 v122, v132, v137
	v_min_u32_e32 v132, v132, v137
	v_max_u32_e32 v137, v136, v134
	v_min_u32_e32 v134, v136, v134
	v_max_u32_e32 v136, v133, v124
	v_min_u32_e32 v124, v133, v124
	v_max_u32_e32 v133, v135, v138
	v_min_u32_e32 v135, v135, v138
	v_max_u32_e32 v138, v147, v131
	v_min_u32_e32 v131, v147, v131
	v_max_u32_e32 v147, v125, v123
	v_min_u32_e32 v123, v125, v123
	v_max_u32_e32 v125, v0, v1
	v_min_u32_e32 v0, v0, v1
	v_max_u32_e32 v1, v3, v2
	v_min_u32_e32 v2, v3, v2
	v_min_u32_e32 v111, v116, v129
	v_min_u32_e32 v140, v121, v126
	v_min_u32_e32 v141, v128, v120
	v_min_u32_e32 v142, v117, v127
	v_min_u32_e32 v143, v130, v139
	v_min_u32_e32 v144, v118, v115
	v_min_u32_e32 v145, v119, v114
	v_min_u32_e32 v146, v112, v110
	v_min_u32_e32 v3, v122, v137
	v_min_u32_e32 v148, v132, v134
	v_min_u32_e32 v149, v136, v133
	v_min_u32_e32 v150, v124, v135
	v_min_u32_e32 v151, v138, v147
	v_min_u32_e32 v152, v131, v123
	v_min_u32_e32 v153, v125, v1
	v_min_u32_e32 v154, v0, v2
	v_max3_u32 v116, v116, v129, v154
	v_max3_u32 v0, v111, v0, v2
	v_max3_u32 v2, v121, v126, v153
	v_max3_u32 v1, v140, v125, v1
	v_max3_u32 v111, v128, v120, v152
	v_max3_u32 v120, v141, v131, v123
	v_max3_u32 v117, v117, v127, v151
	v_max3_u32 v121, v142, v138, v147
	v_max3_u32 v123, v130, v139, v150
	v_max3_u32 v124, v143, v124, v135
	v_max3_u32 v115, v118, v115, v149
	v_max3_u32 v118, v144, v136, v133
	v_max3_u32 v114, v119, v114, v148
	v_max3_u32 v119, v145, v132, v134
	v_max3_u32 v3, v112, v110, v3
	v_max3_u32 v110, v146, v122, v137
	v_max_u32_e32 v112, v116, v123
	v_min_u32_e32 v116, v116, v123
	v_max_u32_e32 v122, v0, v124
	v_min_u32_e32 v0, v0, v124
	v_max_u32_e32 v123, v2, v115
	v_min_u32_e32 v2, v2, v115
	v_max_u32_e32 v115, v1, v118
	v_min_u32_e32 v1, v1, v118
	v_max_u32_e32 v118, v111, v114
	v_min_u32_e32 v111, v111, v114
	v_max_u32_e32 v114, v120, v119
	v_min_u32_e32 v119, v120, v119
	v_max_u32_e32 v120, v117, v3
	v_min_u32_e32 v3, v117, v3
	v_max_u32_e32 v117, v121, v110
	v_min_u32_e32 v110, v121, v110
	v_max_u32_e32 v121, v112, v118
	v_min_u32_e32 v112, v112, v118
	v_max_u32_e32 v118, v122, v114
	v_min_u32_e32 v114, v122, v114
	v_max_u32_e32 v122, v123, v120
	v_min_u32_e32 v120, v123, v120
	v_max_u32_e32 v123, v115, v117
	v_min_u32_e32 v115, v115, v117
	v_max_u32_e32 v117, v116, v111
	v_min_u32_e32 v111, v116, v111
	v_max_u32_e32 v116, v0, v119
	v_min_u32_e32 v0, v0, v119
	v_max_u32_e32 v119, v2, v3
	v_min_u32_e32 v2, v2, v3
	v_max_u32_e32 v3, v1, v110
	v_min_u32_e32 v1, v1, v110
	v_max_u32_e32 v110, v121, v122
	v_min_u32_e32 v121, v121, v122
	v_max_u32_e32 v122, v118, v123
	v_min_u32_e32 v118, v118, v123
	v_max_u32_e32 v123, v112, v120
	v_min_u32_e32 v112, v112, v120
	v_max_u32_e32 v120, v114, v115
	v_min_u32_e32 v114, v114, v115
	v_max_u32_e32 v115, v117, v119
	v_min_u32_e32 v117, v117, v119
	v_max_u32_e32 v119, v116, v3
	v_min_u32_e32 v3, v116, v3
	v_max_u32_e32 v116, v111, v2
	v_min_u32_e32 v2, v111, v2
	v_max_u32_e32 v111, v0, v1
	v_min_u32_e32 v0, v0, v1
	v_max_u32_e32 v1, v110, v122
	v_min_u32_e32 v110, v110, v122
	v_max_u32_e32 v122, v121, v118
	v_min_u32_e32 v118, v121, v118
	v_max_u32_e32 v121, v123, v120
	v_min_u32_e32 v120, v123, v120
	v_max_u32_e32 v123, v112, v114
	v_min_u32_e32 v112, v112, v114
	v_max_u32_e32 v114, v115, v119
	v_min_u32_e32 v115, v115, v119
	v_max_u32_e32 v119, v117, v3
	v_min_u32_e32 v3, v117, v3
	v_max_u32_e32 v117, v116, v111
	v_min_u32_e32 v111, v116, v111
	v_max_u32_e32 v116, v2, v0
	v_min_u32_e32 v0, v2, v0
	ds_bpermute_b32 v2, v27, v1
	ds_bpermute_b32 v124, v27, v110
	ds_bpermute_b32 v125, v27, v122
	ds_bpermute_b32 v126, v27, v118
	ds_bpermute_b32 v127, v27, v121
	ds_bpermute_b32 v128, v27, v120
	ds_bpermute_b32 v129, v27, v123
	ds_bpermute_b32 v130, v27, v112
	ds_bpermute_b32 v131, v27, v114
	ds_bpermute_b32 v132, v27, v115
	ds_bpermute_b32 v133, v27, v119
	ds_bpermute_b32 v134, v27, v0
	ds_bpermute_b32 v135, v27, v116
	ds_bpermute_b32 v136, v27, v111
	ds_bpermute_b32 v137, v27, v117
	ds_bpermute_b32 v138, v27, v3
	s_waitcnt lgkmcnt(4)
; #define CE_DESC(a, b) do { const unsigned _mx = (a) > (b) ? (a) : (b), _mn = (a) > (b) ? (b) : (a); (a) = _mx; (b) = _mn; } while (0)
; __device__ __forceinline__ void merge16(unsigned (&a)[16], const unsigned (&b)[16]) {
; #pragma unroll
;     for (int i = 0; i < 16; ++i) a[i] = a[i] > b[15 - i] ? a[i] : b[15 - i];
; #pragma unroll
;     for (int stride = 8; stride > 0; stride >>= 1)
; #pragma unroll
;         for (int i = 0; i < 16; ++i) { const int j = i ^ stride; if (j > i) CE_DESC(a[i], a[j]); }
; }
; __device__ __forceinline__ void peer_tile(const Args& A, LAS unsigned char* lds, int tile) {
;     ...
;                 { const bf16_t* sp = QRY + m * 2048 + hp * 128 + 32 * g;
;                   const u32x4 s0 = *(const u32x4*)sp, s1 = *(const u32x4*)(sp + 8), s2 = *(const u32x4*)(sp + 16), s3 = *(const u32x4*)(sp + 24);
;                   const unsigned sw[16] = {s0.x, s0.y, s0.z, s0.w, s1.x, s1.y, s1.z, s1.w, s2.x, s2.y, s2.z, s2.w, s3.x, s3.y, s3.z, s3.w};
;     ...
;                 for (int msk = 16; msk <= 32; msk <<= 1) {
; #pragma unroll
;                     for (int i = 0; i < 16; ++i) k1[i] = (unsigned)__shfl_xor((int)k0[i], msk);
;                     merge16(k0, k1); }
	v_max_u32_e32 v1, v1, v134
	s_waitcnt lgkmcnt(3)
	v_max_u32_e32 v110, v110, v135
	s_waitcnt lgkmcnt(2)
	v_max_u32_e32 v122, v122, v136
	s_waitcnt lgkmcnt(1)
	v_max_u32_e32 v118, v118, v137
	s_waitcnt lgkmcnt(0)
	v_max_u32_e32 v121, v121, v138
	v_max_u32_e32 v120, v120, v133
	v_max_u32_e32 v123, v123, v132
	v_max_u32_e32 v112, v112, v131
	v_max_u32_e32 v114, v114, v130
	v_max_u32_e32 v115, v115, v129
	v_max_u32_e32 v119, v119, v128
	v_max_u32_e32 v3, v3, v127
	v_max_u32_e32 v117, v117, v126
	v_max_u32_e32 v111, v111, v125
	v_max_u32_e32 v116, v116, v124
	v_max_u32_e32 v0, v0, v2
	v_max_u32_e32 v2, v1, v114
	v_min_u32_e32 v1, v1, v114
	v_max_u32_e32 v114, v110, v115
	v_min_u32_e32 v110, v110, v115
	v_max_u32_e32 v115, v122, v119
	v_min_u32_e32 v119, v122, v119
	v_max_u32_e32 v122, v118, v3
	v_min_u32_e32 v3, v118, v3
	v_max_u32_e32 v118, v121, v117
	v_min_u32_e32 v117, v121, v117
	v_max_u32_e32 v121, v120, v111
	v_min_u32_e32 v111, v120, v111
	v_max_u32_e32 v120, v123, v116
	v_min_u32_e32 v116, v123, v116
	v_max_u32_e32 v123, v112, v0
	v_min_u32_e32 v0, v112, v0
	v_max_u32_e32 v112, v2, v118
	v_min_u32_e32 v2, v2, v118
	v_max_u32_e32 v118, v114, v121
	v_min_u32_e32 v114, v114, v121
	v_max_u32_e32 v121, v115, v120
	v_min_u32_e32 v115, v115, v120
	v_max_u32_e32 v120, v122, v123
	v_min_u32_e32 v122, v122, v123
	v_max_u32_e32 v123, v1, v117
	v_min_u32_e32 v1, v1, v117
	v_max_u32_e32 v117, v110, v111
	v_min_u32_e32 v110, v110, v111
	v_max_u32_e32 v111, v119, v116
	v_min_u32_e32 v116, v119, v116
	v_max_u32_e32 v119, v3, v0
	v_min_u32_e32 v0, v3, v0
	v_max_u32_e32 v3, v112, v121
	v_min_u32_e32 v112, v112, v121
	v_max_u32_e32 v121, v118, v120
	v_min_u32_e32 v118, v118, v120
	v_max_u32_e32 v120, v2, v115
	v_min_u32_e32 v2, v2, v115
	v_max_u32_e32 v115, v114, v122
	v_min_u32_e32 v114, v114, v122
	v_max_u32_e32 v122, v123, v111
	v_min_u32_e32 v111, v123, v111
	v_max_u32_e32 v123, v117, v119
	v_min_u32_e32 v117, v117, v119
	v_max_u32_e32 v119, v1, v116
	v_min_u32_e32 v1, v1, v116
	v_max_u32_e32 v116, v110, v0
	v_min_u32_e32 v0, v110, v0
	v_max_u32_e32 v110, v3, v121
	v_min_u32_e32 v3, v3, v121
	v_max_u32_e32 v121, v112, v118
	v_min_u32_e32 v112, v112, v118
	v_max_u32_e32 v118, v120, v115
	v_min_u32_e32 v115, v120, v115
	v_max_u32_e32 v120, v2, v114
	v_min_u32_e32 v2, v2, v114
	v_max_u32_e32 v114, v122, v123
	v_min_u32_e32 v122, v122, v123
	v_max_u32_e32 v123, v111, v117
	v_min_u32_e32 v111, v111, v117
	v_max_u32_e32 v117, v119, v116
	v_min_u32_e32 v116, v119, v116
	v_max_u32_e32 v119, v1, v0
	v_min_u32_e32 v0, v1, v0
	ds_bpermute_b32 v128, v29, v0
	ds_bpermute_b32 v1, v29, v110
	ds_bpermute_b32 v124, v29, v3
	ds_bpermute_b32 v125, v29, v121
	ds_bpermute_b32 v126, v29, v112
	s_waitcnt lgkmcnt(4)
	v_max_u32_e32 v110, v110, v128
	global_load_dwordx4 v[128:131], v[4:5], off offset:1552
	global_load_dwordx4 v[132:135], v[4:5], off offset:1536
	ds_bpermute_b32 v127, v29, v118
	ds_bpermute_b32 v136, v29, v115
	ds_bpermute_b32 v137, v29, v120
	ds_bpermute_b32 v138, v29, v2
	ds_bpermute_b32 v139, v29, v114
	ds_bpermute_b32 v140, v29, v122
	ds_bpermute_b32 v141, v29, v123
	ds_bpermute_b32 v142, v29, v111
	ds_bpermute_b32 v143, v29, v117
	ds_bpermute_b32 v144, v29, v119
	ds_bpermute_b32 v145, v29, v116
	s_waitcnt lgkmcnt(4)
	v_max_u32_e32 v115, v115, v141
	s_waitcnt lgkmcnt(3)
	v_max_u32_e32 v118, v118, v142
	s_waitcnt lgkmcnt(2)
	v_max_u32_e32 v112, v112, v143
	s_waitcnt lgkmcnt(1)
	v_max_u32_e32 v3, v3, v144
	s_waitcnt lgkmcnt(0)
	v_max_u32_e32 v121, v121, v145
	v_max_u32_e32 v120, v120, v140
	v_max_u32_e32 v2, v2, v139
	v_max_u32_e32 v114, v114, v138
	v_max_u32_e32 v122, v122, v137
	v_max_u32_e32 v123, v123, v136
	v_max_u32_e32 v111, v111, v127
	v_max_u32_e32 v117, v117, v126
	v_max_u32_e32 v116, v116, v125
	v_max_u32_e32 v119, v119, v124
	v_max_u32_e32 v0, v0, v1
	v_max_u32_e32 v1, v110, v114
	v_min_u32_e32 v110, v110, v114
	v_max_u32_e32 v114, v3, v122
	v_min_u32_e32 v3, v3, v122
	v_max_u32_e32 v122, v121, v123
	v_min_u32_e32 v121, v121, v123
	v_max_u32_e32 v123, v112, v111
	v_min_u32_e32 v111, v112, v111
	v_max_u32_e32 v112, v118, v117
	v_min_u32_e32 v117, v118, v117
	v_max_u32_e32 v118, v115, v116
	v_min_u32_e32 v115, v115, v116
	v_max_u32_e32 v116, v120, v119
	v_min_u32_e32 v119, v120, v119
	v_max_u32_e32 v120, v2, v0
	v_min_u32_e32 v0, v2, v0
	v_max_u32_e32 v2, v1, v112
	v_min_u32_e32 v1, v1, v112
	v_max_u32_e32 v112, v114, v118
	v_min_u32_e32 v114, v114, v118
	v_max_u32_e32 v118, v122, v116
	v_min_u32_e32 v116, v122, v116
	v_max_u32_e32 v122, v123, v120
	v_min_u32_e32 v120, v123, v120
	v_max_u32_e32 v123, v110, v117
	v_min_u32_e32 v110, v110, v117
	v_max_u32_e32 v117, v3, v115
	v_min_u32_e32 v3, v3, v115
	v_max_u32_e32 v115, v121, v119
	v_min_u32_e32 v119, v121, v119
	v_max_u32_e32 v121, v111, v0
	v_min_u32_e32 v0, v111, v0
	v_max_u32_e32 v111, v2, v118
	v_min_u32_e32 v2, v2, v118
	v_max_u32_e32 v118, v112, v122
	v_min_u32_e32 v112, v112, v122
	v_max_u32_e32 v127, v1, v116
	v_min_u32_e32 v1, v1, v116
	v_max_u32_e32 v116, v114, v120
	v_min_u32_e32 v114, v114, v120
	v_max_u32_e32 v136, v123, v115
	v_min_u32_e32 v115, v123, v115
	v_max_u32_e32 v137, v117, v121
	v_min_u32_e32 v138, v117, v121
	v_max_u32_e32 v139, v110, v119
	v_min_u32_e32 v110, v110, v119
	v_max_u32_e32 v140, v3, v0
	v_min_u32_e32 v0, v3, v0
	v_max_u32_e32 v126, v111, v118
	v_min_u32_e32 v125, v111, v118
	v_max_u32_e32 v124, v2, v112
	v_min_u32_e32 v123, v2, v112
	v_max_u32_e32 v122, v127, v116
	v_min_u32_e32 v121, v127, v116
	v_max_u32_e32 v120, v1, v114
	v_min_u32_e32 v119, v1, v114
	v_max_u32_e32 v118, v136, v137
	v_min_u32_e32 v117, v136, v137
	v_max_u32_e32 v116, v115, v138
	v_min_u32_e32 v115, v115, v138
	v_max_u32_e32 v114, v139, v140
	v_min_u32_e32 v112, v139, v140
	v_max_u32_e32 v111, v110, v0
	v_min_u32_e32 v110, v110, v0
	global_load_dwordx4 v[0:3], v[4:5], off offset:1584
	global_load_dwordx4 v[136:139], v[4:5], off offset:1568
	s_waitcnt vmcnt(2)
; __device__ __forceinline__ unsigned f2key(float f) { const unsigned u = __float_as_uint(f); return (u & 0x80000000u) ? ~u : (u | 0x80000000u); }
; __device__ __forceinline__ void peer_tile(const Args& A, LAS unsigned char* lds, int tile) {
;     ...
;                 { const bf16_t* sp = QRY + m * 2048 + hp * 128 + 32 * g;
;                   const u32x4 s0 = *(const u32x4*)sp, s1 = *(const u32x4*)(sp + 8), s2 = *(const u32x4*)(sp + 16), s3 = *(const u32x4*)(sp + 24);
;                   const unsigned sw[16] = {s0.x, s0.y, s0.z, s0.w, s1.x, s1.y, s1.z, s1.w, s2.x, s2.y, s2.z, s2.w, s3.x, s3.y, s3.z, s3.w};
; #pragma unroll
;                   for (int i = 0; i < 16; ++i) {
;                       const float lo = (float)__builtin_bit_cast(_Float16, (unsigned short)(sw[i] & 0xffffu)), hi = (float)__builtin_bit_cast(_Float16, (unsigned short)(sw[i] >> 16));
;                       const unsigned klo = (f2key(lo) & ~127u) | (unsigned)(127 - (32 * g + 2 * i)), khi = (f2key(hi) & ~127u) | (unsigned)(127 - (32 * g + 2 * i + 1));
;                       if (i < 8) { k0[2 * i] = klo; k0[2 * i + 1] = khi; } else { k1[2 * (i - 8)] = klo; k1[2 * (i - 8) + 1] = khi; } } }
	v_cvt_f32_f16_sdwa v127, v132 dst_sel:DWORD dst_unused:UNUSED_PAD src0_sel:WORD_1
	v_cvt_f32_f16_e32 v132, v132
	v_not_b32_e32 v140, v127
	v_or_b32_e32 v141, 0x80000000, v127
	v_cmp_gt_i32_e32 vcc, 0, v127
	s_nop 1
	v_cndmask_b32_e32 v127, v141, v140, vcc
	v_not_b32_e32 v140, v132
	v_or_b32_e32 v141, 0x80000000, v132
	v_cmp_gt_i32_e32 vcc, 0, v132
	v_and_b32_e32 v127, 0xffffff80, v127
	v_sub_u32_e32 v127, v127, v15
	v_cndmask_b32_e32 v132, v141, v140, vcc
	v_cvt_f32_f16_sdwa v140, v133 dst_sel:DWORD dst_unused:UNUSED_PAD src0_sel:WORD_1
	v_cvt_f32_f16_e32 v133, v133
	v_and_b32_e32 v132, 0xffffff80, v132
	v_sub_u32_e32 v132, v132, v15
	v_not_b32_e32 v141, v140
	v_or_b32_e32 v142, 0x80000000, v140
	v_cmp_gt_i32_e32 vcc, 0, v140
	v_add_u32_e32 v127, 0x7e, v127
	v_add_u32_e32 v132, 0x7f, v132
	v_cndmask_b32_e32 v140, v142, v141, vcc
	v_not_b32_e32 v141, v133
	v_or_b32_e32 v142, 0x80000000, v133
	v_cmp_gt_i32_e32 vcc, 0, v133
	v_and_b32_e32 v140, 0xffffff80, v140
	v_sub_u32_e32 v140, v140, v14
	v_cndmask_b32_e32 v133, v142, v141, vcc
	v_cvt_f32_f16_sdwa v141, v134 dst_sel:DWORD dst_unused:UNUSED_PAD src0_sel:WORD_1
	v_cvt_f32_f16_e32 v134, v134
	v_and_b32_e32 v133, 0xffffff80, v133
	v_sub_u32_e32 v133, v133, v14
	v_not_b32_e32 v142, v141
	v_or_b32_e32 v143, 0x80000000, v141
	v_cmp_gt_i32_e32 vcc, 0, v141
	v_add_u32_e32 v140, 0x7e, v140
	v_add_u32_e32 v133, 0x7f, v133
	v_cndmask_b32_e32 v141, v143, v142, vcc
	v_not_b32_e32 v142, v134
	v_or_b32_e32 v143, 0x80000000, v134
	v_cmp_gt_i32_e32 vcc, 0, v134
	v_and_b32_e32 v141, 0xffffff80, v141
	v_sub_u32_e32 v141, v141, v12
	v_cndmask_b32_e32 v134, v143, v142, vcc
	v_cvt_f32_f16_sdwa v142, v135 dst_sel:DWORD dst_unused:UNUSED_PAD src0_sel:WORD_1
	v_cvt_f32_f16_e32 v135, v135
	v_and_b32_e32 v134, 0xffffff80, v134
	v_sub_u32_e32 v134, v134, v12
	v_not_b32_e32 v143, v142
	v_or_b32_e32 v144, 0x80000000, v142
	v_cmp_gt_i32_e32 vcc, 0, v142
	v_add_u32_e32 v141, 0x7e, v141
	v_add_u32_e32 v134, 0x7f, v134
	v_cndmask_b32_e32 v142, v144, v143, vcc
	v_not_b32_e32 v143, v135
	v_or_b32_e32 v144, 0x80000000, v135
	v_cmp_gt_i32_e32 vcc, 0, v135
	v_and_b32_e32 v142, 0xffffff80, v142
	v_sub_u32_e32 v142, v142, v10
	v_cndmask_b32_e32 v135, v144, v143, vcc
	v_cvt_f32_f16_sdwa v143, v128 dst_sel:DWORD dst_unused:UNUSED_PAD src0_sel:WORD_1
	v_cvt_f32_f16_e32 v128, v128
	v_and_b32_e32 v135, 0xffffff80, v135
	v_sub_u32_e32 v135, v135, v10
	v_not_b32_e32 v144, v143
	v_or_b32_e32 v145, 0x80000000, v143
	v_cmp_gt_i32_e32 vcc, 0, v143
	v_add_u32_e32 v142, 0x7e, v142
	v_add_u32_e32 v135, 0x7f, v135
	v_cndmask_b32_e32 v143, v145, v144, vcc
	v_not_b32_e32 v144, v128
	v_or_b32_e32 v145, 0x80000000, v128
	v_cmp_gt_i32_e32 vcc, 0, v128
	v_and_b32_e32 v143, 0xffffff80, v143
	v_sub_u32_e32 v143, v143, v8
	v_cndmask_b32_e32 v128, v145, v144, vcc
	v_cvt_f32_f16_sdwa v144, v129 dst_sel:DWORD dst_unused:UNUSED_PAD src0_sel:WORD_1
	v_cvt_f32_f16_e32 v129, v129
	v_and_b32_e32 v128, 0xffffff80, v128
	v_sub_u32_e32 v128, v128, v8
	v_not_b32_e32 v145, v144
	v_or_b32_e32 v146, 0x80000000, v144
	v_cmp_gt_i32_e32 vcc, 0, v144
	v_add_u32_e32 v143, 0x7e, v143
	v_add_u32_e32 v128, 0x7f, v128
	v_cndmask_b32_e32 v144, v146, v145, vcc
	v_not_b32_e32 v145, v129
	v_or_b32_e32 v146, 0x80000000, v129
	v_cmp_gt_i32_e32 vcc, 0, v129
	v_and_b32_e32 v144, 0xffffff80, v144
	v_sub_u32_e32 v144, v144, v16
	v_cndmask_b32_e32 v129, v146, v145, vcc
	v_cvt_f32_f16_sdwa v145, v130 dst_sel:DWORD dst_unused:UNUSED_PAD src0_sel:WORD_1
	v_cvt_f32_f16_e32 v130, v130
	v_and_b32_e32 v129, 0xffffff80, v129
	v_sub_u32_e32 v129, v129, v16
	v_not_b32_e32 v146, v145
	v_or_b32_e32 v147, 0x80000000, v145
	v_cmp_gt_i32_e32 vcc, 0, v145
	v_add_u32_e32 v144, 0x7e, v144
	v_add_u32_e32 v129, 0x7f, v129
	v_cndmask_b32_e32 v145, v147, v146, vcc
	v_not_b32_e32 v146, v130
	v_or_b32_e32 v147, 0x80000000, v130
	v_cmp_gt_i32_e32 vcc, 0, v130
	v_and_b32_e32 v145, 0xffffff80, v145
	v_sub_u32_e32 v145, v145, v17
	v_cndmask_b32_e32 v130, v147, v146, vcc
	v_cvt_f32_f16_sdwa v146, v131 dst_sel:DWORD dst_unused:UNUSED_PAD src0_sel:WORD_1
	v_cvt_f32_f16_e32 v131, v131
	v_and_b32_e32 v130, 0xffffff80, v130
	v_sub_u32_e32 v130, v130, v17
	v_not_b32_e32 v147, v146
	v_or_b32_e32 v148, 0x80000000, v146
	v_cmp_gt_i32_e32 vcc, 0, v146
	v_add_u32_e32 v145, 0x7e, v145
	v_add_u32_e32 v130, 0x7f, v130
	v_cndmask_b32_e32 v146, v148, v147, vcc
	v_not_b32_e32 v147, v131
	v_or_b32_e32 v148, 0x80000000, v131
	v_cmp_gt_i32_e32 vcc, 0, v131
	v_and_b32_e32 v146, 0xffffff80, v146
	v_sub_u32_e32 v146, v146, v18
	v_cndmask_b32_e32 v131, v148, v147, vcc
	s_waitcnt vmcnt(0)
; __device__ __forceinline__ unsigned f2key(float f) { const unsigned u = __float_as_uint(f); return (u & 0x80000000u) ? ~u : (u | 0x80000000u); }
; #define CE_DESC(a, b) do { const unsigned _mx = (a) > (b) ? (a) : (b), _mn = (a) > (b) ? (b) : (a); (a) = _mx; (b) = _mn; } while (0)
; __device__ __forceinline__ void sort16_desc(unsigned (&k)[16]) {
; #pragma unroll
;     for (int size = 2; size <= 16; size <<= 1)
; #pragma unroll
;         for (int stride = size >> 1; stride > 0; stride >>= 1)
; #pragma unroll
;             for (int i = 0; i < 16; ++i) { const int j = i ^ stride;
;                 if (j > i) { if ((i & size) == 0) CE_DESC(k[i], k[j]); else CE_DESC(k[j], k[i]); } }
; __device__ __forceinline__ void peer_tile(const Args& A, LAS unsigned char* lds, int tile) {
;     ...
;                       const float lo = (float)__builtin_bit_cast(_Float16, (unsigned short)(sw[i] & 0xffffu)), hi = (float)__builtin_bit_cast(_Float16, (unsigned short)(sw[i] >> 16));
;                       const unsigned klo = (f2key(lo) & ~127u) | (unsigned)(127 - (32 * g + 2 * i)), khi = (f2key(hi) & ~127u) | (unsigned)(127 - (32 * g + 2 * i + 1));
;                       if (i < 8) { k0[2 * i] = klo; k0[2 * i + 1] = khi; } else { k1[2 * (i - 8)] = klo; k1[2 * (i - 8) + 1] = khi; } } }
;                 sort16_desc(k0); sort16_desc(k1); merge16(k0, k1);
	v_cvt_f32_f16_sdwa v147, v136 dst_sel:DWORD dst_unused:UNUSED_PAD src0_sel:WORD_1
	v_cvt_f32_f16_e32 v136, v136
	v_and_b32_e32 v131, 0xffffff80, v131
	v_sub_u32_e32 v131, v131, v18
	v_not_b32_e32 v148, v147
	v_or_b32_e32 v149, 0x80000000, v147
	v_cmp_gt_i32_e32 vcc, 0, v147
	v_add_u32_e32 v146, 0x7e, v146
	v_add_u32_e32 v131, 0x7f, v131
	v_cndmask_b32_e32 v147, v149, v148, vcc
	v_not_b32_e32 v148, v136
	v_or_b32_e32 v149, 0x80000000, v136
	v_cmp_gt_i32_e32 vcc, 0, v136
	v_and_b32_e32 v147, 0xffffff80, v147
	v_sub_u32_e32 v147, v147, v20
	v_cndmask_b32_e32 v136, v149, v148, vcc
	v_cvt_f32_f16_sdwa v148, v137 dst_sel:DWORD dst_unused:UNUSED_PAD src0_sel:WORD_1
	v_cvt_f32_f16_e32 v137, v137
	v_and_b32_e32 v136, 0xffffff80, v136
	v_sub_u32_e32 v136, v136, v20
	v_not_b32_e32 v149, v148
	v_or_b32_e32 v150, 0x80000000, v148
	v_cmp_gt_i32_e32 vcc, 0, v148
	v_add_u32_e32 v147, 0x7e, v147
	v_add_u32_e32 v136, 0x7f, v136
	v_cndmask_b32_e32 v148, v150, v149, vcc
	v_not_b32_e32 v149, v137
	v_or_b32_e32 v150, 0x80000000, v137
	v_cmp_gt_i32_e32 vcc, 0, v137
	v_and_b32_e32 v148, 0xffffff80, v148
	v_sub_u32_e32 v148, v148, v21
	v_cndmask_b32_e32 v137, v150, v149, vcc
	v_cvt_f32_f16_sdwa v149, v138 dst_sel:DWORD dst_unused:UNUSED_PAD src0_sel:WORD_1
	v_cvt_f32_f16_e32 v138, v138
	v_and_b32_e32 v137, 0xffffff80, v137
	v_sub_u32_e32 v137, v137, v21
	v_not_b32_e32 v150, v149
	v_or_b32_e32 v151, 0x80000000, v149
	v_cmp_gt_i32_e32 vcc, 0, v149
	v_add_u32_e32 v148, 0x7e, v148
	v_add_u32_e32 v137, 0x7f, v137
	v_cndmask_b32_e32 v149, v151, v150, vcc
	v_not_b32_e32 v150, v138
	v_or_b32_e32 v151, 0x80000000, v138
	v_cmp_gt_i32_e32 vcc, 0, v138
	v_and_b32_e32 v149, 0xffffff80, v149
	v_sub_u32_e32 v149, v149, v22
	v_cndmask_b32_e32 v138, v151, v150, vcc
	v_cvt_f32_f16_sdwa v150, v139 dst_sel:DWORD dst_unused:UNUSED_PAD src0_sel:WORD_1
	v_cvt_f32_f16_e32 v139, v139
	v_and_b32_e32 v138, 0xffffff80, v138
	v_sub_u32_e32 v138, v138, v22
	v_not_b32_e32 v151, v150
	v_or_b32_e32 v152, 0x80000000, v150
	v_cmp_gt_i32_e32 vcc, 0, v150
	v_add_u32_e32 v149, 0x7e, v149
	v_add_u32_e32 v138, 0x7f, v138
	v_cndmask_b32_e32 v150, v152, v151, vcc
	v_not_b32_e32 v151, v139
	v_or_b32_e32 v152, 0x80000000, v139
	v_cmp_gt_i32_e32 vcc, 0, v139
	v_and_b32_e32 v150, 0xffffff80, v150
	v_sub_u32_e32 v150, v150, v23
	v_cndmask_b32_e32 v139, v152, v151, vcc
	v_cvt_f32_f16_sdwa v151, v0 dst_sel:DWORD dst_unused:UNUSED_PAD src0_sel:WORD_1
	v_cvt_f32_f16_e32 v0, v0
	v_and_b32_e32 v139, 0xffffff80, v139
	v_sub_u32_e32 v139, v139, v23
	v_not_b32_e32 v152, v151
	v_or_b32_e32 v153, 0x80000000, v151
	v_cmp_gt_i32_e32 vcc, 0, v151
	v_add_u32_e32 v150, 0x7e, v150
	v_add_u32_e32 v139, 0x7f, v139
	v_cndmask_b32_e32 v151, v153, v152, vcc
	v_not_b32_e32 v152, v0
	v_or_b32_e32 v153, 0x80000000, v0
	v_cmp_gt_i32_e32 vcc, 0, v0
	v_and_b32_e32 v151, 0xffffff80, v151
	v_sub_u32_e32 v151, v151, v24
	v_cndmask_b32_e32 v0, v153, v152, vcc
	v_cvt_f32_f16_sdwa v152, v1 dst_sel:DWORD dst_unused:UNUSED_PAD src0_sel:WORD_1
	v_cvt_f32_f16_e32 v1, v1
	v_and_b32_e32 v0, 0xffffff80, v0
	v_sub_u32_e32 v0, v0, v24
	v_not_b32_e32 v153, v152
	v_or_b32_e32 v154, 0x80000000, v152
	v_cmp_gt_i32_e32 vcc, 0, v152
	v_add_u32_e32 v151, 0x7e, v151
	v_add_u32_e32 v0, 0x7f, v0
	v_cndmask_b32_e32 v152, v154, v153, vcc
	v_not_b32_e32 v153, v1
	v_or_b32_e32 v154, 0x80000000, v1
	v_cmp_gt_i32_e32 vcc, 0, v1
	v_and_b32_e32 v152, 0xffffff80, v152
	v_sub_u32_e32 v152, v152, v25
	v_cndmask_b32_e32 v1, v154, v153, vcc
	v_cvt_f32_f16_sdwa v153, v2 dst_sel:DWORD dst_unused:UNUSED_PAD src0_sel:WORD_1
	v_cvt_f32_f16_e32 v2, v2
	v_and_b32_e32 v1, 0xffffff80, v1
	v_sub_u32_e32 v1, v1, v25
	v_not_b32_e32 v154, v153
	v_or_b32_e32 v155, 0x80000000, v153
	v_cmp_gt_i32_e32 vcc, 0, v153
	v_add_u32_e32 v152, 0x7e, v152
	v_add_u32_e32 v1, 0x7f, v1
	v_cndmask_b32_e32 v153, v155, v154, vcc
	v_not_b32_e32 v154, v2
	v_or_b32_e32 v155, 0x80000000, v2
	v_cmp_gt_i32_e32 vcc, 0, v2
	v_and_b32_e32 v153, 0xffffff80, v153
	v_sub_u32_e32 v153, v153, v26
	v_cndmask_b32_e32 v2, v155, v154, vcc
	v_cvt_f32_f16_sdwa v154, v3 dst_sel:DWORD dst_unused:UNUSED_PAD src0_sel:WORD_1
	v_cvt_f32_f16_e32 v3, v3
	v_and_b32_e32 v2, 0xffffff80, v2
	v_sub_u32_e32 v2, v2, v26
	v_not_b32_e32 v155, v154
	v_or_b32_e32 v156, 0x80000000, v154
	v_cmp_gt_i32_e32 vcc, 0, v154
	v_add_u32_e32 v153, 0x7e, v153
	v_add_u32_e32 v2, 0x7f, v2
	v_cndmask_b32_e32 v154, v156, v155, vcc
	v_not_b32_e32 v155, v3
	v_or_b32_e32 v156, 0x80000000, v3
	v_cmp_gt_i32_e32 vcc, 0, v3
	v_and_b32_e32 v154, 0xffffff80, v154
	v_sub_u32_e32 v154, v154, v28
	v_cndmask_b32_e32 v3, v156, v155, vcc
	v_and_b32_e32 v3, 0xffffff80, v3
	v_sub_u32_e32 v3, v3, v28
	v_add_u32_e32 v154, 0x7e, v154
	v_add_u32_e32 v3, 0x7f, v3
	v_max_u32_e32 v155, v132, v127
	v_min_u32_e32 v127, v132, v127
	v_max_u32_e32 v132, v140, v133
	v_min_u32_e32 v133, v140, v133
	v_max_u32_e32 v140, v134, v141
	v_min_u32_e32 v134, v134, v141
	v_max_u32_e32 v141, v142, v135
	v_min_u32_e32 v135, v142, v135
	v_max_u32_e32 v142, v128, v143
	v_min_u32_e32 v128, v128, v143
	v_max_u32_e32 v143, v144, v129
	v_min_u32_e32 v129, v144, v129
	v_max_u32_e32 v144, v130, v145
	v_min_u32_e32 v130, v130, v145
	v_max_u32_e32 v145, v146, v131
	v_min_u32_e32 v131, v146, v131
	v_max_u32_e32 v163, v136, v147
	v_min_u32_e32 v136, v136, v147
	v_max_u32_e32 v147, v148, v137
	v_min_u32_e32 v137, v148, v137
	v_max_u32_e32 v148, v138, v149
	v_min_u32_e32 v138, v138, v149
	v_max_u32_e32 v149, v150, v139
	v_min_u32_e32 v139, v150, v139
	v_max_u32_e32 v150, v0, v151
	v_min_u32_e32 v0, v0, v151
	v_max_u32_e32 v151, v152, v1
	v_min_u32_e32 v1, v152, v1
	v_max_u32_e32 v152, v2, v153
	v_min_u32_e32 v2, v2, v153
; #define CE_DESC(a, b) do { const unsigned _mx = (a) > (b) ? (a) : (b), _mn = (a) > (b) ? (b) : (a); (a) = _mx; (b) = _mn; } while (0)
; __device__ __forceinline__ void sort16_desc(unsigned (&k)[16]) {
; #pragma unroll
;     for (int size = 2; size <= 16; size <<= 1)
; #pragma unroll
;         for (int stride = size >> 1; stride > 0; stride >>= 1)
; #pragma unroll
;             for (int i = 0; i < 16; ++i) { const int j = i ^ stride;
;                 if (j > i) { if ((i & size) == 0) CE_DESC(k[i], k[j]); else CE_DESC(k[j], k[i]); } }
; }
	v_max_u32_e32 v153, v154, v3
	v_min_u32_e32 v3, v154, v3
	v_max_u32_e32 v146, v155, v133
	v_min_u32_e32 v133, v155, v133
	v_max_u32_e32 v155, v127, v132
	v_min_u32_e32 v127, v127, v132
	v_max_u32_e32 v132, v135, v140
	v_min_u32_e32 v135, v135, v140
	v_max_u32_e32 v140, v141, v134
	v_min_u32_e32 v134, v141, v134
	v_max_u32_e32 v141, v142, v129
	v_min_u32_e32 v129, v142, v129
	v_max_u32_e32 v142, v128, v143
	v_min_u32_e32 v128, v128, v143
	v_max_u32_e32 v143, v131, v144
	v_min_u32_e32 v131, v131, v144
	v_max_u32_e32 v144, v145, v130
	v_min_u32_e32 v130, v145, v130
	v_max_u32_e32 v154, v163, v137
	v_min_u32_e32 v137, v163, v137
	v_max_u32_e32 v163, v136, v147
	v_min_u32_e32 v136, v136, v147
	v_max_u32_e32 v147, v139, v148
	v_min_u32_e32 v139, v139, v148
	v_max_u32_e32 v148, v149, v138
	v_min_u32_e32 v138, v149, v138
	v_max_u32_e32 v149, v150, v1
	v_min_u32_e32 v1, v150, v1
	v_max_u32_e32 v150, v0, v151
	v_min_u32_e32 v0, v0, v151
	v_max_u32_e32 v151, v3, v152
	v_min_u32_e32 v3, v3, v152
	v_max_u32_e32 v152, v153, v2
	v_min_u32_e32 v2, v153, v2
	v_max_u32_e32 v145, v146, v155
	v_min_u32_e32 v146, v146, v155
	v_max_u32_e32 v155, v133, v127
	v_min_u32_e32 v127, v133, v127
	v_max_u32_e32 v133, v134, v135
	v_min_u32_e32 v134, v134, v135
	v_max_u32_e32 v135, v140, v132
	v_min_u32_e32 v132, v140, v132
	v_max_u32_e32 v140, v141, v142
	v_min_u32_e32 v141, v141, v142
	v_max_u32_e32 v142, v129, v128
	v_min_u32_e32 v128, v129, v128
	v_max_u32_e32 v129, v130, v131
	v_min_u32_e32 v130, v130, v131
	v_max_u32_e32 v131, v144, v143
	v_min_u32_e32 v143, v144, v143
	v_max_u32_e32 v153, v154, v163
	v_min_u32_e32 v154, v154, v163
	v_max_u32_e32 v163, v137, v136
	v_min_u32_e32 v136, v137, v136
	v_max_u32_e32 v137, v138, v139
	v_min_u32_e32 v138, v138, v139
	v_max_u32_e32 v139, v148, v147
	v_min_u32_e32 v147, v148, v147
	v_max_u32_e32 v148, v149, v150
	v_min_u32_e32 v149, v149, v150
	v_max_u32_e32 v150, v1, v0
	v_min_u32_e32 v0, v1, v0
	v_max_u32_e32 v1, v2, v3
	v_min_u32_e32 v2, v2, v3
	v_max_u32_e32 v3, v152, v151
	v_min_u32_e32 v151, v152, v151
	v_max_u32_e32 v144, v145, v134
	v_min_u32_e32 v134, v145, v134
	v_max_u32_e32 v145, v146, v133
	v_min_u32_e32 v133, v146, v133
	v_max_u32_e32 v146, v155, v132
	v_min_u32_e32 v132, v155, v132
	v_max_u32_e32 v155, v127, v135
	v_min_u32_e32 v127, v127, v135
	v_max_u32_e32 v135, v130, v140
	v_min_u32_e32 v130, v130, v140
	v_max_u32_e32 v140, v129, v141
	v_min_u32_e32 v129, v129, v141
	v_max_u32_e32 v141, v143, v142
	v_min_u32_e32 v142, v143, v142
	v_max_u32_e32 v143, v131, v128
	v_min_u32_e32 v128, v131, v128
	v_max_u32_e32 v152, v153, v138
	v_min_u32_e32 v138, v153, v138
	v_max_u32_e32 v153, v154, v137
	v_min_u32_e32 v137, v154, v137
	v_max_u32_e32 v154, v163, v147
	v_min_u32_e32 v147, v163, v147
	v_max_u32_e32 v163, v136, v139
	v_min_u32_e32 v136, v136, v139
	v_max_u32_e32 v139, v2, v148
	v_min_u32_e32 v2, v2, v148
	v_max_u32_e32 v148, v1, v149
	v_min_u32_e32 v1, v1, v149
	v_max_u32_e32 v149, v151, v150
	v_min_u32_e32 v150, v151, v150
	v_max_u32_e32 v151, v3, v0
	v_min_u32_e32 v0, v3, v0
	v_max_u32_e32 v131, v144, v146
	v_min_u32_e32 v144, v144, v146
	v_max_u32_e32 v146, v145, v155
	v_min_u32_e32 v145, v145, v155
	v_max_u32_e32 v155, v134, v132
	v_min_u32_e32 v132, v134, v132
	v_max_u32_e32 v134, v133, v127
	v_min_u32_e32 v127, v133, v127
	v_max_u32_e32 v133, v142, v130
	v_min_u32_e32 v130, v142, v130
	v_max_u32_e32 v142, v128, v129
	v_min_u32_e32 v128, v128, v129
	v_max_u32_e32 v129, v141, v135
	v_min_u32_e32 v135, v141, v135
	v_max_u32_e32 v141, v143, v140
	v_min_u32_e32 v140, v143, v140
	v_max_u32_e32 v3, v152, v154
	v_min_u32_e32 v152, v152, v154
	v_max_u32_e32 v154, v153, v163
	v_min_u32_e32 v153, v153, v163
	v_max_u32_e32 v163, v138, v147
	v_min_u32_e32 v138, v138, v147
	v_max_u32_e32 v147, v137, v136
	v_min_u32_e32 v136, v137, v136
	v_max_u32_e32 v137, v150, v2
	v_min_u32_e32 v2, v150, v2
	v_max_u32_e32 v150, v0, v1
	v_min_u32_e32 v0, v0, v1
	v_max_u32_e32 v1, v149, v139
	v_min_u32_e32 v139, v149, v139
	v_max_u32_e32 v149, v151, v148
	v_min_u32_e32 v148, v151, v148
	v_max_u32_e32 v143, v131, v146
	v_min_u32_e32 v131, v131, v146
	v_max_u32_e32 v146, v144, v145
	v_min_u32_e32 v144, v144, v145
	v_max_u32_e32 v145, v155, v134
	v_min_u32_e32 v134, v155, v134
	v_max_u32_e32 v155, v132, v127
	v_min_u32_e32 v127, v132, v127
	v_max_u32_e32 v132, v128, v130
	v_min_u32_e32 v128, v128, v130
	v_max_u32_e32 v130, v142, v133
	v_min_u32_e32 v133, v142, v133
	v_max_u32_e32 v142, v140, v135
	v_min_u32_e32 v135, v140, v135
	v_max_u32_e32 v140, v141, v129
	v_min_u32_e32 v129, v141, v129
	v_max_u32_e32 v151, v3, v154
	v_min_u32_e32 v3, v3, v154
	v_max_u32_e32 v154, v152, v153
	v_min_u32_e32 v152, v152, v153
	v_max_u32_e32 v153, v163, v147
	v_min_u32_e32 v147, v163, v147
	v_max_u32_e32 v163, v138, v136
	v_min_u32_e32 v136, v138, v136
	v_max_u32_e32 v138, v0, v2
	v_min_u32_e32 v0, v0, v2
	v_max_u32_e32 v2, v150, v137
	v_min_u32_e32 v137, v150, v137
	v_max_u32_e32 v150, v148, v139
	v_min_u32_e32 v139, v148, v139
	v_max_u32_e32 v148, v149, v1
	v_min_u32_e32 v1, v149, v1
	v_max_u32_e32 v141, v143, v128
	v_min_u32_e32 v128, v143, v128
	v_max_u32_e32 v143, v131, v132
	v_min_u32_e32 v131, v131, v132
	v_max_u32_e32 v132, v146, v133
	v_min_u32_e32 v133, v146, v133
	v_max_u32_e32 v146, v144, v130
	v_min_u32_e32 v130, v144, v130
	v_max_u32_e32 v144, v145, v135
	v_min_u32_e32 v135, v145, v135
	v_max_u32_e32 v145, v134, v142
	v_min_u32_e32 v134, v134, v142
	v_max_u32_e32 v142, v155, v129
	v_min_u32_e32 v129, v155, v129
	v_max_u32_e32 v155, v127, v140
	v_min_u32_e32 v127, v127, v140
	v_max_u32_e32 v149, v151, v0
	v_min_u32_e32 v0, v151, v0
; #define CE_DESC(a, b) do { const unsigned _mx = (a) > (b) ? (a) : (b), _mn = (a) > (b) ? (b) : (a); (a) = _mx; (b) = _mn; } while (0)
; __device__ __forceinline__ void merge16(unsigned (&a)[16], const unsigned (&b)[16]) {
; #pragma unroll
;     for (int i = 0; i < 16; ++i) a[i] = a[i] > b[15 - i] ? a[i] : b[15 - i];
; #pragma unroll
;     for (int stride = 8; stride > 0; stride >>= 1)
; #pragma unroll
;         for (int i = 0; i < 16; ++i) { const int j = i ^ stride; if (j > i) CE_DESC(a[i], a[j]); }
; }
; __device__ __forceinline__ void peer_tile(const Args& A, LAS unsigned char* lds, int tile) {
;     ...
;                 for (int msk = 16; msk <= 32; msk <<= 1) {
; #pragma unroll
;                     for (int i = 0; i < 16; ++i) k1[i] = (unsigned)__shfl_xor((int)k0[i], msk);
;                     merge16(k0, k1); }
	v_max_u32_e32 v151, v3, v138
	v_min_u32_e32 v3, v3, v138
	v_max_u32_e32 v138, v154, v137
	v_min_u32_e32 v137, v154, v137
	v_max_u32_e32 v154, v152, v2
	v_min_u32_e32 v2, v152, v2
	v_max_u32_e32 v152, v153, v139
	v_min_u32_e32 v139, v153, v139
	v_max_u32_e32 v153, v147, v150
	v_min_u32_e32 v147, v147, v150
	v_max_u32_e32 v150, v163, v1
	v_min_u32_e32 v1, v163, v1
	v_max_u32_e32 v163, v136, v148
	v_min_u32_e32 v136, v136, v148
	v_max_u32_e32 v140, v141, v144
	v_min_u32_e32 v141, v141, v144
	v_max_u32_e32 v144, v143, v145
	v_min_u32_e32 v143, v143, v145
	v_max_u32_e32 v145, v132, v142
	v_min_u32_e32 v132, v132, v142
	v_max_u32_e32 v142, v146, v155
	v_min_u32_e32 v146, v146, v155
	v_max_u32_e32 v155, v128, v135
	v_min_u32_e32 v128, v128, v135
	v_max_u32_e32 v135, v131, v134
	v_min_u32_e32 v131, v131, v134
	v_max_u32_e32 v134, v133, v129
	v_min_u32_e32 v129, v133, v129
	v_max_u32_e32 v133, v130, v127
	v_min_u32_e32 v127, v130, v127
	v_max_u32_e32 v148, v149, v152
	v_min_u32_e32 v149, v149, v152
	v_max_u32_e32 v152, v151, v153
	v_min_u32_e32 v151, v151, v153
	v_max_u32_e32 v153, v138, v150
	v_min_u32_e32 v138, v138, v150
	v_max_u32_e32 v150, v154, v163
	v_min_u32_e32 v154, v154, v163
	v_max_u32_e32 v163, v0, v139
	v_min_u32_e32 v0, v0, v139
	v_max_u32_e32 v139, v3, v147
	v_min_u32_e32 v3, v3, v147
	v_max_u32_e32 v147, v137, v1
	v_min_u32_e32 v1, v137, v1
	v_max_u32_e32 v137, v2, v136
	v_min_u32_e32 v2, v2, v136
	v_max_u32_e32 v130, v140, v145
	v_min_u32_e32 v140, v140, v145
	v_max_u32_e32 v145, v144, v142
	v_min_u32_e32 v142, v144, v142
	v_max_u32_e32 v144, v141, v132
	v_min_u32_e32 v132, v141, v132
	v_max_u32_e32 v141, v143, v146
	v_min_u32_e32 v143, v143, v146
	v_max_u32_e32 v146, v155, v134
	v_min_u32_e32 v134, v155, v134
	v_max_u32_e32 v155, v135, v133
	v_min_u32_e32 v133, v135, v133
	v_max_u32_e32 v135, v128, v129
	v_min_u32_e32 v128, v128, v129
	v_max_u32_e32 v129, v131, v127
	v_min_u32_e32 v127, v131, v127
	v_max_u32_e32 v136, v148, v153
	v_min_u32_e32 v148, v148, v153
	v_max_u32_e32 v153, v152, v150
	v_min_u32_e32 v150, v152, v150
	v_max_u32_e32 v152, v149, v138
	v_min_u32_e32 v138, v149, v138
	v_max_u32_e32 v149, v151, v154
	v_min_u32_e32 v151, v151, v154
	v_max_u32_e32 v154, v163, v147
	v_min_u32_e32 v147, v163, v147
	v_max_u32_e32 v163, v139, v137
	v_min_u32_e32 v137, v139, v137
	v_max_u32_e32 v139, v0, v1
	v_min_u32_e32 v0, v0, v1
	v_max_u32_e32 v1, v3, v2
	v_min_u32_e32 v2, v3, v2
	v_min_u32_e32 v131, v130, v145
	v_min_u32_e32 v156, v140, v142
	v_min_u32_e32 v157, v144, v141
	v_min_u32_e32 v158, v132, v143
	v_min_u32_e32 v159, v146, v155
	v_min_u32_e32 v160, v134, v133
	v_min_u32_e32 v161, v135, v129
	v_min_u32_e32 v162, v128, v127
	v_min_u32_e32 v3, v136, v153
	v_min_u32_e32 v164, v148, v150
	v_min_u32_e32 v165, v152, v149
	v_min_u32_e32 v166, v138, v151
	v_min_u32_e32 v167, v154, v163
	v_min_u32_e32 v168, v147, v137
	v_min_u32_e32 v169, v139, v1
	v_min_u32_e32 v170, v0, v2
	v_max3_u32 v130, v130, v145, v170
	v_max3_u32 v0, v131, v0, v2
	v_max3_u32 v2, v140, v142, v169
	v_max3_u32 v1, v156, v139, v1
	v_max3_u32 v131, v144, v141, v168
	v_max3_u32 v137, v157, v147, v137
	v_max3_u32 v132, v132, v143, v167
	v_max3_u32 v139, v158, v154, v163
	v_max3_u32 v140, v146, v155, v166
	v_max3_u32 v138, v159, v138, v151
	v_max3_u32 v133, v134, v133, v165
	v_max3_u32 v134, v160, v152, v149
	v_max3_u32 v129, v135, v129, v164
	v_max3_u32 v135, v161, v148, v150
	v_max3_u32 v3, v128, v127, v3
	v_max3_u32 v127, v162, v136, v153
	v_max_u32_e32 v128, v130, v140
	v_min_u32_e32 v130, v130, v140
	v_max_u32_e32 v136, v0, v138
	v_min_u32_e32 v0, v0, v138
	v_max_u32_e32 v138, v2, v133
	v_min_u32_e32 v2, v2, v133
	v_max_u32_e32 v133, v1, v134
	v_min_u32_e32 v1, v1, v134
	v_max_u32_e32 v134, v131, v129
	v_min_u32_e32 v129, v131, v129
	v_max_u32_e32 v131, v137, v135
	v_min_u32_e32 v135, v137, v135
	v_max_u32_e32 v137, v132, v3
	v_min_u32_e32 v3, v132, v3
	v_max_u32_e32 v132, v139, v127
	v_min_u32_e32 v127, v139, v127
	v_max_u32_e32 v139, v128, v134
	v_min_u32_e32 v128, v128, v134
	v_max_u32_e32 v134, v136, v131
	v_min_u32_e32 v131, v136, v131
	v_max_u32_e32 v136, v138, v137
	v_min_u32_e32 v137, v138, v137
	v_max_u32_e32 v138, v133, v132
	v_min_u32_e32 v132, v133, v132
	v_max_u32_e32 v133, v130, v129
	v_min_u32_e32 v129, v130, v129
	v_max_u32_e32 v130, v0, v135
	v_min_u32_e32 v0, v0, v135
	v_max_u32_e32 v135, v2, v3
	v_min_u32_e32 v2, v2, v3
	v_max_u32_e32 v3, v1, v127
	v_min_u32_e32 v1, v1, v127
	v_max_u32_e32 v127, v139, v136
	v_min_u32_e32 v136, v139, v136
	v_max_u32_e32 v139, v134, v138
	v_min_u32_e32 v134, v134, v138
	v_max_u32_e32 v138, v128, v137
	v_min_u32_e32 v128, v128, v137
	v_max_u32_e32 v137, v131, v132
	v_min_u32_e32 v131, v131, v132
	v_max_u32_e32 v132, v133, v135
	v_min_u32_e32 v133, v133, v135
	v_max_u32_e32 v135, v130, v3
	v_min_u32_e32 v3, v130, v3
	v_max_u32_e32 v130, v129, v2
	v_min_u32_e32 v2, v129, v2
	v_max_u32_e32 v129, v0, v1
	v_min_u32_e32 v0, v0, v1
	v_max_u32_e32 v1, v127, v139
	v_min_u32_e32 v127, v127, v139
	v_max_u32_e32 v139, v136, v134
	v_min_u32_e32 v134, v136, v134
	v_max_u32_e32 v136, v138, v137
	v_min_u32_e32 v137, v138, v137
	v_max_u32_e32 v138, v128, v131
	v_min_u32_e32 v128, v128, v131
	v_max_u32_e32 v131, v132, v135
	v_min_u32_e32 v132, v132, v135
	v_max_u32_e32 v135, v133, v3
	v_min_u32_e32 v3, v133, v3
	v_max_u32_e32 v133, v130, v129
	v_min_u32_e32 v129, v130, v129
	v_max_u32_e32 v130, v2, v0
	v_min_u32_e32 v0, v2, v0
	ds_bpermute_b32 v2, v27, v1
	ds_bpermute_b32 v140, v27, v127
	ds_bpermute_b32 v141, v27, v139
	ds_bpermute_b32 v142, v27, v134
	ds_bpermute_b32 v143, v27, v136
	ds_bpermute_b32 v144, v27, v137
	ds_bpermute_b32 v145, v27, v138
	ds_bpermute_b32 v146, v27, v128
	ds_bpermute_b32 v147, v27, v131
	ds_bpermute_b32 v148, v27, v132
	ds_bpermute_b32 v149, v27, v135
	ds_bpermute_b32 v150, v27, v0
	ds_bpermute_b32 v151, v27, v130
	ds_bpermute_b32 v152, v27, v129
	ds_bpermute_b32 v153, v27, v133
	ds_bpermute_b32 v154, v27, v3
	s_waitcnt lgkmcnt(4)
; __device__ __forceinline__ void peer_tile(const Args& A, LAS unsigned char* lds, int tile) {
;     ...
;                 { const bf16_t* sp = QRY + m * 2048 + hp * 128 + 32 * g;
;                   const u32x4 s0 = *(const u32x4*)sp, s1 = *(const u32x4*)(sp + 8), s2 = *(const u32x4*)(sp + 16), s3 = *(const u32x4*)(sp + 24);
;                   const unsigned sw[16] = {s0.x, s0.y, s0.z, s0.w, s1.x, s1.y, s1.z, s1.w, s2.x, s2.y, s2.z, s2.w, s3.x, s3.y, s3.z, s3.w};
;     ...
;                 for (int msk = 16; msk <= 32; msk <<= 1) {
; #pragma unroll
;                     for (int i = 0; i < 16; ++i) k1[i] = (unsigned)__shfl_xor((int)k0[i], msk);
;                     merge16(k0, k1); }
	v_max_u32_e32 v1, v1, v150
	s_waitcnt lgkmcnt(3)
	v_max_u32_e32 v127, v127, v151
	s_waitcnt lgkmcnt(2)
	v_max_u32_e32 v139, v139, v152
	s_waitcnt lgkmcnt(1)
	v_max_u32_e32 v134, v134, v153
	s_waitcnt lgkmcnt(0)
	v_max_u32_e32 v136, v136, v154
	v_max_u32_e32 v137, v137, v149
	v_max_u32_e32 v138, v138, v148
	v_max_u32_e32 v128, v128, v147
	v_max_u32_e32 v131, v131, v146
	v_max_u32_e32 v132, v132, v145
	v_max_u32_e32 v135, v135, v144
	v_max_u32_e32 v3, v3, v143
	v_max_u32_e32 v133, v133, v142
	v_max_u32_e32 v129, v129, v141
	v_max_u32_e32 v130, v130, v140
	v_max_u32_e32 v0, v0, v2
	v_max_u32_e32 v2, v1, v131
	v_min_u32_e32 v1, v1, v131
	v_max_u32_e32 v131, v127, v132
	v_min_u32_e32 v127, v127, v132
	v_max_u32_e32 v132, v139, v135
	v_min_u32_e32 v135, v139, v135
	v_max_u32_e32 v139, v134, v3
	v_min_u32_e32 v3, v134, v3
	v_max_u32_e32 v134, v136, v133
	v_min_u32_e32 v133, v136, v133
	v_max_u32_e32 v136, v137, v129
	v_min_u32_e32 v129, v137, v129
	v_max_u32_e32 v137, v138, v130
	v_min_u32_e32 v130, v138, v130
	v_max_u32_e32 v138, v128, v0
	v_min_u32_e32 v0, v128, v0
	v_max_u32_e32 v128, v2, v134
	v_min_u32_e32 v2, v2, v134
	v_max_u32_e32 v134, v131, v136
	v_min_u32_e32 v131, v131, v136
	v_max_u32_e32 v136, v132, v137
	v_min_u32_e32 v132, v132, v137
	v_max_u32_e32 v137, v139, v138
	v_min_u32_e32 v138, v139, v138
	v_max_u32_e32 v139, v1, v133
	v_min_u32_e32 v1, v1, v133
	v_max_u32_e32 v133, v127, v129
	v_min_u32_e32 v127, v127, v129
	v_max_u32_e32 v129, v135, v130
	v_min_u32_e32 v130, v135, v130
	v_max_u32_e32 v135, v3, v0
	v_min_u32_e32 v0, v3, v0
	v_max_u32_e32 v3, v128, v136
	v_min_u32_e32 v128, v128, v136
	v_max_u32_e32 v136, v134, v137
	v_min_u32_e32 v134, v134, v137
	v_max_u32_e32 v137, v2, v132
	v_min_u32_e32 v2, v2, v132
	v_max_u32_e32 v132, v131, v138
	v_min_u32_e32 v131, v131, v138
	v_max_u32_e32 v138, v139, v129
	v_min_u32_e32 v129, v139, v129
	v_max_u32_e32 v139, v133, v135
	v_min_u32_e32 v133, v133, v135
	v_max_u32_e32 v135, v1, v130
	v_min_u32_e32 v1, v1, v130
	v_max_u32_e32 v130, v127, v0
	v_min_u32_e32 v0, v127, v0
	v_max_u32_e32 v127, v3, v136
	v_min_u32_e32 v3, v3, v136
	v_max_u32_e32 v136, v128, v134
	v_min_u32_e32 v128, v128, v134
	v_max_u32_e32 v134, v137, v132
	v_min_u32_e32 v132, v137, v132
	v_max_u32_e32 v137, v2, v131
	v_min_u32_e32 v2, v2, v131
	v_max_u32_e32 v131, v138, v139
	v_min_u32_e32 v138, v138, v139
	v_max_u32_e32 v139, v129, v133
	v_min_u32_e32 v129, v129, v133
	v_max_u32_e32 v133, v135, v130
	v_min_u32_e32 v130, v135, v130
	v_max_u32_e32 v135, v1, v0
	v_min_u32_e32 v0, v1, v0
	ds_bpermute_b32 v144, v29, v0
	ds_bpermute_b32 v1, v29, v127
	ds_bpermute_b32 v140, v29, v3
	ds_bpermute_b32 v141, v29, v136
	ds_bpermute_b32 v142, v29, v128
	s_waitcnt lgkmcnt(4)
	v_max_u32_e32 v127, v127, v144
	global_load_dwordx4 v[144:147], v[4:5], off offset:1808
	global_load_dwordx4 v[148:151], v[4:5], off offset:1792
	ds_bpermute_b32 v143, v29, v134
	ds_bpermute_b32 v152, v29, v132
	ds_bpermute_b32 v153, v29, v137
	ds_bpermute_b32 v154, v29, v2
	ds_bpermute_b32 v155, v29, v131
	ds_bpermute_b32 v156, v29, v138
	ds_bpermute_b32 v157, v29, v139
	ds_bpermute_b32 v158, v29, v129
	ds_bpermute_b32 v159, v29, v133
	ds_bpermute_b32 v160, v29, v135
	ds_bpermute_b32 v161, v29, v130
	s_waitcnt lgkmcnt(4)
	v_max_u32_e32 v132, v132, v157
	s_waitcnt lgkmcnt(3)
	v_max_u32_e32 v134, v134, v158
	s_waitcnt lgkmcnt(2)
	v_max_u32_e32 v128, v128, v159
	s_waitcnt lgkmcnt(1)
	v_max_u32_e32 v3, v3, v160
	s_waitcnt lgkmcnt(0)
	v_max_u32_e32 v136, v136, v161
	v_max_u32_e32 v137, v137, v156
	v_max_u32_e32 v2, v2, v155
	v_max_u32_e32 v131, v131, v154
	v_max_u32_e32 v138, v138, v153
	v_max_u32_e32 v139, v139, v152
	v_max_u32_e32 v129, v129, v143
	v_max_u32_e32 v133, v133, v142
	v_max_u32_e32 v130, v130, v141
	v_max_u32_e32 v135, v135, v140
	v_max_u32_e32 v0, v0, v1
	v_max_u32_e32 v1, v127, v131
	v_min_u32_e32 v127, v127, v131
	v_max_u32_e32 v131, v3, v138
	v_min_u32_e32 v3, v3, v138
	v_max_u32_e32 v138, v136, v139
	v_min_u32_e32 v136, v136, v139
	v_max_u32_e32 v139, v128, v129
	v_min_u32_e32 v128, v128, v129
	v_max_u32_e32 v129, v134, v133
	v_min_u32_e32 v133, v134, v133
	v_max_u32_e32 v134, v132, v130
	v_min_u32_e32 v130, v132, v130
	v_max_u32_e32 v132, v137, v135
	v_min_u32_e32 v135, v137, v135
	v_max_u32_e32 v137, v2, v0
	v_min_u32_e32 v0, v2, v0
	v_max_u32_e32 v2, v1, v129
	v_min_u32_e32 v1, v1, v129
	v_max_u32_e32 v129, v131, v134
	v_min_u32_e32 v131, v131, v134
	v_max_u32_e32 v134, v138, v132
	v_min_u32_e32 v132, v138, v132
	v_max_u32_e32 v138, v139, v137
	v_min_u32_e32 v137, v139, v137
	v_max_u32_e32 v139, v127, v133
	v_min_u32_e32 v127, v127, v133
	v_max_u32_e32 v133, v3, v130
	v_min_u32_e32 v3, v3, v130
	v_max_u32_e32 v130, v136, v135
	v_min_u32_e32 v135, v136, v135
	v_max_u32_e32 v136, v128, v0
	v_min_u32_e32 v0, v128, v0
	v_max_u32_e32 v128, v2, v134
	v_min_u32_e32 v2, v2, v134
	v_max_u32_e32 v134, v129, v138
	v_min_u32_e32 v129, v129, v138
	v_max_u32_e32 v143, v1, v132
	v_min_u32_e32 v1, v1, v132
	v_max_u32_e32 v132, v131, v137
	v_min_u32_e32 v131, v131, v137
	v_max_u32_e32 v152, v139, v130
	v_min_u32_e32 v130, v139, v130
	v_max_u32_e32 v153, v133, v136
	v_min_u32_e32 v154, v133, v136
	v_max_u32_e32 v155, v127, v135
	v_min_u32_e32 v127, v127, v135
	v_max_u32_e32 v156, v3, v0
	v_min_u32_e32 v0, v3, v0
	v_max_u32_e32 v142, v128, v134
	v_min_u32_e32 v141, v128, v134
	v_max_u32_e32 v140, v2, v129
	v_min_u32_e32 v139, v2, v129
	v_max_u32_e32 v138, v143, v132
	v_min_u32_e32 v137, v143, v132
	v_max_u32_e32 v136, v1, v131
	v_min_u32_e32 v135, v1, v131
	v_max_u32_e32 v134, v152, v153
	v_min_u32_e32 v133, v152, v153
	v_max_u32_e32 v132, v130, v154
	v_min_u32_e32 v131, v130, v154
	v_max_u32_e32 v130, v155, v156
	v_min_u32_e32 v129, v155, v156
	v_max_u32_e32 v128, v127, v0
	v_min_u32_e32 v127, v127, v0
	global_load_dwordx4 v[0:3], v[4:5], off offset:1840
	global_load_dwordx4 v[152:155], v[4:5], off offset:1824
	s_waitcnt vmcnt(2)
; __device__ __forceinline__ unsigned f2key(float f) { const unsigned u = __float_as_uint(f); return (u & 0x80000000u) ? ~u : (u | 0x80000000u); }
; __device__ __forceinline__ void peer_tile(const Args& A, LAS unsigned char* lds, int tile) {
;     ...
;                 { const bf16_t* sp = QRY + m * 2048 + hp * 128 + 32 * g;
;                   const u32x4 s0 = *(const u32x4*)sp, s1 = *(const u32x4*)(sp + 8), s2 = *(const u32x4*)(sp + 16), s3 = *(const u32x4*)(sp + 24);
;                   const unsigned sw[16] = {s0.x, s0.y, s0.z, s0.w, s1.x, s1.y, s1.z, s1.w, s2.x, s2.y, s2.z, s2.w, s3.x, s3.y, s3.z, s3.w};
; #pragma unroll
;                   for (int i = 0; i < 16; ++i) {
;                       const float lo = (float)__builtin_bit_cast(_Float16, (unsigned short)(sw[i] & 0xffffu)), hi = (float)__builtin_bit_cast(_Float16, (unsigned short)(sw[i] >> 16));
;                       const unsigned klo = (f2key(lo) & ~127u) | (unsigned)(127 - (32 * g + 2 * i)), khi = (f2key(hi) & ~127u) | (unsigned)(127 - (32 * g + 2 * i + 1));
;                       if (i < 8) { k0[2 * i] = klo; k0[2 * i + 1] = khi; } else { k1[2 * (i - 8)] = klo; k1[2 * (i - 8) + 1] = khi; } } }
	v_cvt_f32_f16_sdwa v143, v148 dst_sel:DWORD dst_unused:UNUSED_PAD src0_sel:WORD_1
	v_cvt_f32_f16_e32 v4, v148
	v_not_b32_e32 v5, v143
	v_or_b32_e32 v148, 0x80000000, v143
	v_cmp_gt_i32_e32 vcc, 0, v143
	v_not_b32_e32 v143, v4
	s_nop 0
	v_cndmask_b32_e32 v5, v148, v5, vcc
	v_or_b32_e32 v148, 0x80000000, v4
	v_cmp_gt_i32_e32 vcc, 0, v4
	v_and_b32_e32 v5, 0xffffff80, v5
	v_sub_u32_e32 v5, v5, v15
	v_cndmask_b32_e32 v4, v148, v143, vcc
	v_and_b32_e32 v4, 0xffffff80, v4
	v_cvt_f32_f16_sdwa v143, v149 dst_sel:DWORD dst_unused:UNUSED_PAD src0_sel:WORD_1
	v_sub_u32_e32 v4, v4, v15
	v_cvt_f32_f16_e32 v15, v149
	v_add_u32_e32 v5, 0x7e, v5
	v_not_b32_e32 v148, v143
	v_or_b32_e32 v149, 0x80000000, v143
	v_cmp_gt_i32_e32 vcc, 0, v143
	v_add_u32_e32 v4, 0x7f, v4
	s_nop 0
	v_cndmask_b32_e32 v143, v149, v148, vcc
	v_not_b32_e32 v148, v15
	v_or_b32_e32 v149, 0x80000000, v15
	v_cmp_gt_i32_e32 vcc, 0, v15
	v_and_b32_e32 v143, 0xffffff80, v143
	v_sub_u32_e32 v143, v143, v14
	v_cndmask_b32_e32 v15, v149, v148, vcc
	v_and_b32_e32 v15, 0xffffff80, v15
	v_cvt_f32_f16_sdwa v148, v150 dst_sel:DWORD dst_unused:UNUSED_PAD src0_sel:WORD_1
	v_sub_u32_e32 v14, v15, v14
	v_cvt_f32_f16_e32 v15, v150
	v_add_u32_e32 v143, 0x7e, v143
	v_not_b32_e32 v149, v148
	v_or_b32_e32 v150, 0x80000000, v148
	v_cmp_gt_i32_e32 vcc, 0, v148
	v_add_u32_e32 v14, 0x7f, v14
	s_nop 0
	v_cndmask_b32_e32 v148, v150, v149, vcc
	v_not_b32_e32 v149, v15
	v_or_b32_e32 v150, 0x80000000, v15
	v_cmp_gt_i32_e32 vcc, 0, v15
	v_and_b32_e32 v148, 0xffffff80, v148
	v_sub_u32_e32 v148, v148, v12
	v_cndmask_b32_e32 v15, v150, v149, vcc
	v_and_b32_e32 v15, 0xffffff80, v15
	v_cvt_f32_f16_sdwa v149, v151 dst_sel:DWORD dst_unused:UNUSED_PAD src0_sel:WORD_1
	v_sub_u32_e32 v12, v15, v12
	v_cvt_f32_f16_e32 v15, v151
	v_add_u32_e32 v148, 0x7e, v148
	v_not_b32_e32 v150, v149
	v_or_b32_e32 v151, 0x80000000, v149
	v_cmp_gt_i32_e32 vcc, 0, v149
	v_add_u32_e32 v12, 0x7f, v12
	s_nop 0
	v_cndmask_b32_e32 v149, v151, v150, vcc
	v_not_b32_e32 v150, v15
	v_or_b32_e32 v151, 0x80000000, v15
	v_cmp_gt_i32_e32 vcc, 0, v15
	v_and_b32_e32 v149, 0xffffff80, v149
	v_sub_u32_e32 v149, v149, v10
	v_cndmask_b32_e32 v15, v151, v150, vcc
	v_and_b32_e32 v15, 0xffffff80, v15
	v_cvt_f32_f16_sdwa v150, v144 dst_sel:DWORD dst_unused:UNUSED_PAD src0_sel:WORD_1
	v_sub_u32_e32 v10, v15, v10
	v_cvt_f32_f16_e32 v15, v144
	v_add_u32_e32 v149, 0x7e, v149
	v_not_b32_e32 v144, v150
	v_or_b32_e32 v151, 0x80000000, v150
	v_cmp_gt_i32_e32 vcc, 0, v150
	v_not_b32_e32 v150, v15
	v_add_u32_e32 v10, 0x7f, v10
	v_cndmask_b32_e32 v144, v151, v144, vcc
	v_or_b32_e32 v151, 0x80000000, v15
	v_cmp_gt_i32_e32 vcc, 0, v15
	v_and_b32_e32 v144, 0xffffff80, v144
	v_sub_u32_e32 v144, v144, v8
	v_cndmask_b32_e32 v15, v151, v150, vcc
	v_and_b32_e32 v15, 0xffffff80, v15
	v_cvt_f32_f16_sdwa v150, v145 dst_sel:DWORD dst_unused:UNUSED_PAD src0_sel:WORD_1
	v_sub_u32_e32 v8, v15, v8
	v_cvt_f32_f16_e32 v15, v145
	v_add_u32_e32 v144, 0x7e, v144
	v_not_b32_e32 v145, v150
	v_or_b32_e32 v151, 0x80000000, v150
	v_cmp_gt_i32_e32 vcc, 0, v150
	v_not_b32_e32 v150, v15
	v_add_u32_e32 v8, 0x7f, v8
	v_cndmask_b32_e32 v145, v151, v145, vcc
	v_or_b32_e32 v151, 0x80000000, v15
	v_cmp_gt_i32_e32 vcc, 0, v15
	v_and_b32_e32 v145, 0xffffff80, v145
	v_sub_u32_e32 v145, v145, v16
	v_cndmask_b32_e32 v15, v151, v150, vcc
	v_and_b32_e32 v15, 0xffffff80, v15
	v_cvt_f32_f16_sdwa v150, v146 dst_sel:DWORD dst_unused:UNUSED_PAD src0_sel:WORD_1
	v_sub_u32_e32 v15, v15, v16
	v_cvt_f32_f16_e32 v16, v146
	v_add_u32_e32 v145, 0x7e, v145
	v_not_b32_e32 v146, v150
	v_or_b32_e32 v151, 0x80000000, v150
	v_cmp_gt_i32_e32 vcc, 0, v150
	v_not_b32_e32 v150, v16
	v_add_u32_e32 v15, 0x7f, v15
	v_cndmask_b32_e32 v146, v151, v146, vcc
	v_or_b32_e32 v151, 0x80000000, v16
	v_cmp_gt_i32_e32 vcc, 0, v16
	v_and_b32_e32 v146, 0xffffff80, v146
	v_sub_u32_e32 v146, v146, v17
	v_cndmask_b32_e32 v16, v151, v150, vcc
	v_and_b32_e32 v16, 0xffffff80, v16
	v_cvt_f32_f16_sdwa v150, v147 dst_sel:DWORD dst_unused:UNUSED_PAD src0_sel:WORD_1
	v_sub_u32_e32 v16, v16, v17
	v_cvt_f32_f16_e32 v17, v147
	v_add_u32_e32 v146, 0x7e, v146
	v_not_b32_e32 v147, v150
	v_or_b32_e32 v151, 0x80000000, v150
	v_cmp_gt_i32_e32 vcc, 0, v150
	v_not_b32_e32 v150, v17
	v_add_u32_e32 v16, 0x7f, v16
	v_cndmask_b32_e32 v147, v151, v147, vcc
	v_or_b32_e32 v151, 0x80000000, v17
	v_cmp_gt_i32_e32 vcc, 0, v17
	v_and_b32_e32 v147, 0xffffff80, v147
	v_sub_u32_e32 v147, v147, v18
	v_cndmask_b32_e32 v17, v151, v150, vcc
	v_and_b32_e32 v17, 0xffffff80, v17
	s_waitcnt vmcnt(0)
; __device__ __forceinline__ unsigned f2key(float f) { const unsigned u = __float_as_uint(f); return (u & 0x80000000u) ? ~u : (u | 0x80000000u); }
; #define CE_DESC(a, b) do { const unsigned _mx = (a) > (b) ? (a) : (b), _mn = (a) > (b) ? (b) : (a); (a) = _mx; (b) = _mn; } while (0)
; __device__ __forceinline__ void sort16_desc(unsigned (&k)[16]) {
; #pragma unroll
;     for (int size = 2; size <= 16; size <<= 1)
; #pragma unroll
;         for (int stride = size >> 1; stride > 0; stride >>= 1)
; #pragma unroll
;             for (int i = 0; i < 16; ++i) { const int j = i ^ stride;
;                 if (j > i) { if ((i & size) == 0) CE_DESC(k[i], k[j]); else CE_DESC(k[j], k[i]); } }
; __device__ __forceinline__ void peer_tile(const Args& A, LAS unsigned char* lds, int tile) {
;     ...
;                       const float lo = (float)__builtin_bit_cast(_Float16, (unsigned short)(sw[i] & 0xffffu)), hi = (float)__builtin_bit_cast(_Float16, (unsigned short)(sw[i] >> 16));
;                       const unsigned klo = (f2key(lo) & ~127u) | (unsigned)(127 - (32 * g + 2 * i)), khi = (f2key(hi) & ~127u) | (unsigned)(127 - (32 * g + 2 * i + 1));
;                       if (i < 8) { k0[2 * i] = klo; k0[2 * i + 1] = khi; } else { k1[2 * (i - 8)] = klo; k1[2 * (i - 8) + 1] = khi; } } }
;                 sort16_desc(k0); sort16_desc(k1); merge16(k0, k1);
	v_cvt_f32_f16_sdwa v150, v152 dst_sel:DWORD dst_unused:UNUSED_PAD src0_sel:WORD_1
	v_sub_u32_e32 v17, v17, v18
	v_cvt_f32_f16_e32 v18, v152
	v_add_u32_e32 v147, 0x7e, v147
	v_not_b32_e32 v151, v150
	v_or_b32_e32 v152, 0x80000000, v150
	v_cmp_gt_i32_e32 vcc, 0, v150
	v_add_u32_e32 v17, 0x7f, v17
	s_nop 0
	v_cndmask_b32_e32 v150, v152, v151, vcc
	v_not_b32_e32 v151, v18
	v_or_b32_e32 v152, 0x80000000, v18
	v_cmp_gt_i32_e32 vcc, 0, v18
	v_and_b32_e32 v150, 0xffffff80, v150
	v_sub_u32_e32 v150, v150, v20
	v_cndmask_b32_e32 v18, v152, v151, vcc
	v_and_b32_e32 v18, 0xffffff80, v18
	v_cvt_f32_f16_sdwa v151, v153 dst_sel:DWORD dst_unused:UNUSED_PAD src0_sel:WORD_1
	v_sub_u32_e32 v18, v18, v20
	v_cvt_f32_f16_e32 v20, v153
	v_add_u32_e32 v150, 0x7e, v150
	v_not_b32_e32 v152, v151
	v_or_b32_e32 v153, 0x80000000, v151
	v_cmp_gt_i32_e32 vcc, 0, v151
	v_add_u32_e32 v18, 0x7f, v18
	v_max_u32_e32 v161, v18, v150
	v_cndmask_b32_e32 v151, v153, v152, vcc
	v_not_b32_e32 v152, v20
	v_or_b32_e32 v153, 0x80000000, v20
	v_cmp_gt_i32_e32 vcc, 0, v20
	v_and_b32_e32 v151, 0xffffff80, v151
	v_sub_u32_e32 v151, v151, v21
	v_cndmask_b32_e32 v20, v153, v152, vcc
	v_and_b32_e32 v20, 0xffffff80, v20
	v_cvt_f32_f16_sdwa v152, v154 dst_sel:DWORD dst_unused:UNUSED_PAD src0_sel:WORD_1
	v_sub_u32_e32 v20, v20, v21
	v_cvt_f32_f16_e32 v21, v154
	v_add_u32_e32 v151, 0x7e, v151
	v_not_b32_e32 v153, v152
	v_or_b32_e32 v154, 0x80000000, v152
	v_cmp_gt_i32_e32 vcc, 0, v152
	v_add_u32_e32 v20, 0x7f, v20
	v_min_u32_e32 v18, v18, v150
	v_cndmask_b32_e32 v152, v154, v153, vcc
	v_not_b32_e32 v153, v21
	v_or_b32_e32 v154, 0x80000000, v21
	v_cmp_gt_i32_e32 vcc, 0, v21
	v_and_b32_e32 v152, 0xffffff80, v152
	v_sub_u32_e32 v152, v152, v22
	v_cndmask_b32_e32 v21, v154, v153, vcc
	v_and_b32_e32 v21, 0xffffff80, v21
	v_cvt_f32_f16_sdwa v153, v155 dst_sel:DWORD dst_unused:UNUSED_PAD src0_sel:WORD_1
	v_sub_u32_e32 v21, v21, v22
	v_cvt_f32_f16_e32 v22, v155
	v_add_u32_e32 v152, 0x7e, v152
	v_not_b32_e32 v154, v153
	v_or_b32_e32 v155, 0x80000000, v153
	v_cmp_gt_i32_e32 vcc, 0, v153
	v_add_u32_e32 v21, 0x7f, v21
	v_max_u32_e32 v150, v151, v20
	v_cndmask_b32_e32 v153, v155, v154, vcc
	v_not_b32_e32 v154, v22
	v_or_b32_e32 v155, 0x80000000, v22
	v_cmp_gt_i32_e32 vcc, 0, v22
	v_and_b32_e32 v153, 0xffffff80, v153
	v_sub_u32_e32 v153, v153, v23
	v_cndmask_b32_e32 v22, v155, v154, vcc
	v_cvt_f32_f16_sdwa v154, v0 dst_sel:DWORD dst_unused:UNUSED_PAD src0_sel:WORD_1
	v_cvt_f32_f16_e32 v0, v0
	v_and_b32_e32 v22, 0xffffff80, v22
	v_sub_u32_e32 v22, v22, v23
	v_not_b32_e32 v23, v154
	v_or_b32_e32 v155, 0x80000000, v154
	v_cmp_gt_i32_e32 vcc, 0, v154
	v_not_b32_e32 v154, v0
	v_add_u32_e32 v153, 0x7e, v153
	v_cndmask_b32_e32 v23, v155, v23, vcc
	v_or_b32_e32 v155, 0x80000000, v0
	v_cmp_gt_i32_e32 vcc, 0, v0
	v_and_b32_e32 v23, 0xffffff80, v23
	v_sub_u32_e32 v23, v23, v24
	v_cndmask_b32_e32 v0, v155, v154, vcc
	v_cvt_f32_f16_sdwa v154, v1 dst_sel:DWORD dst_unused:UNUSED_PAD src0_sel:WORD_1
	v_cvt_f32_f16_e32 v1, v1
	v_and_b32_e32 v0, 0xffffff80, v0
	v_sub_u32_e32 v0, v0, v24
	v_not_b32_e32 v24, v154
	v_or_b32_e32 v155, 0x80000000, v154
	v_cmp_gt_i32_e32 vcc, 0, v154
	v_not_b32_e32 v154, v1
	v_add_u32_e32 v22, 0x7f, v22
	v_cndmask_b32_e32 v24, v155, v24, vcc
	v_or_b32_e32 v155, 0x80000000, v1
	v_cmp_gt_i32_e32 vcc, 0, v1
	v_and_b32_e32 v24, 0xffffff80, v24
	v_sub_u32_e32 v24, v24, v25
	v_cndmask_b32_e32 v1, v155, v154, vcc
	v_cvt_f32_f16_sdwa v154, v2 dst_sel:DWORD dst_unused:UNUSED_PAD src0_sel:WORD_1
	v_cvt_f32_f16_e32 v2, v2
	v_and_b32_e32 v1, 0xffffff80, v1
	v_sub_u32_e32 v1, v1, v25
	v_not_b32_e32 v25, v154
	v_or_b32_e32 v155, 0x80000000, v154
	v_cmp_gt_i32_e32 vcc, 0, v154
	v_not_b32_e32 v154, v2
	v_add_u32_e32 v23, 0x7e, v23
	v_cndmask_b32_e32 v25, v155, v25, vcc
	v_or_b32_e32 v155, 0x80000000, v2
	v_cmp_gt_i32_e32 vcc, 0, v2
	v_and_b32_e32 v25, 0xffffff80, v25
	v_sub_u32_e32 v25, v25, v26
	v_cndmask_b32_e32 v2, v155, v154, vcc
	v_cvt_f32_f16_sdwa v154, v3 dst_sel:DWORD dst_unused:UNUSED_PAD src0_sel:WORD_1
	v_cvt_f32_f16_e32 v3, v3
	v_and_b32_e32 v2, 0xffffff80, v2
	v_sub_u32_e32 v2, v2, v26
	v_not_b32_e32 v26, v154
	v_or_b32_e32 v155, 0x80000000, v154
	v_cmp_gt_i32_e32 vcc, 0, v154
	v_not_b32_e32 v154, v3
	v_add_u32_e32 v0, 0x7f, v0
	v_cndmask_b32_e32 v26, v155, v26, vcc
	v_or_b32_e32 v155, 0x80000000, v3
	v_cmp_gt_i32_e32 vcc, 0, v3
	v_and_b32_e32 v26, 0xffffff80, v26
	v_sub_u32_e32 v26, v26, v28
	v_cndmask_b32_e32 v3, v155, v154, vcc
	v_and_b32_e32 v3, 0xffffff80, v3
	v_sub_u32_e32 v3, v3, v28
	v_add_u32_e32 v24, 0x7e, v24
	v_add_u32_e32 v1, 0x7f, v1
	v_add_u32_e32 v25, 0x7e, v25
	v_add_u32_e32 v2, 0x7f, v2
	v_add_u32_e32 v26, 0x7e, v26
	v_add_u32_e32 v3, 0x7f, v3
	v_max_u32_e32 v28, v4, v5
	v_min_u32_e32 v4, v4, v5
	v_max_u32_e32 v5, v143, v14
	v_min_u32_e32 v14, v143, v14
	v_max_u32_e32 v143, v12, v148
	v_min_u32_e32 v12, v12, v148
	v_max_u32_e32 v148, v149, v10
	v_min_u32_e32 v10, v149, v10
	v_max_u32_e32 v149, v8, v144
	v_min_u32_e32 v8, v8, v144
	v_max_u32_e32 v144, v145, v15
	v_min_u32_e32 v15, v145, v15
	v_max_u32_e32 v145, v16, v146
	v_min_u32_e32 v16, v16, v146
	v_max_u32_e32 v146, v147, v17
	v_min_u32_e32 v17, v147, v17
	v_min_u32_e32 v20, v151, v20
	v_max_u32_e32 v151, v21, v152
	v_min_u32_e32 v21, v21, v152
	v_max_u32_e32 v152, v153, v22
	v_min_u32_e32 v22, v153, v22
	v_max_u32_e32 v153, v0, v23
	v_min_u32_e32 v0, v0, v23
	v_max_u32_e32 v23, v24, v1
	v_min_u32_e32 v1, v24, v1
	v_max_u32_e32 v24, v2, v25
	v_min_u32_e32 v2, v2, v25
	v_max_u32_e32 v25, v26, v3
	v_min_u32_e32 v3, v26, v3
	v_max_u32_e32 v147, v28, v14
	v_min_u32_e32 v14, v28, v14
	v_max_u32_e32 v28, v4, v5
	v_min_u32_e32 v4, v4, v5
; #define CE_DESC(a, b) do { const unsigned _mx = (a) > (b) ? (a) : (b), _mn = (a) > (b) ? (b) : (a); (a) = _mx; (b) = _mn; } while (0)
; __device__ __forceinline__ void sort16_desc(unsigned (&k)[16]) {
; #pragma unroll
;     for (int size = 2; size <= 16; size <<= 1)
; #pragma unroll
;         for (int stride = size >> 1; stride > 0; stride >>= 1)
; #pragma unroll
;             for (int i = 0; i < 16; ++i) { const int j = i ^ stride;
;                 if (j > i) { if ((i & size) == 0) CE_DESC(k[i], k[j]); else CE_DESC(k[j], k[i]); } }
; }
	v_max_u32_e32 v5, v10, v143
	v_min_u32_e32 v10, v10, v143
	v_max_u32_e32 v143, v148, v12
	v_min_u32_e32 v12, v148, v12
	v_max_u32_e32 v148, v149, v15
	v_min_u32_e32 v15, v149, v15
	v_max_u32_e32 v149, v8, v144
	v_min_u32_e32 v8, v8, v144
	v_max_u32_e32 v144, v17, v145
	v_min_u32_e32 v17, v17, v145
	v_max_u32_e32 v145, v146, v16
	v_min_u32_e32 v16, v146, v16
	v_max_u32_e32 v26, v161, v20
	v_min_u32_e32 v20, v161, v20
	v_max_u32_e32 v161, v18, v150
	v_min_u32_e32 v18, v18, v150
	v_max_u32_e32 v150, v22, v151
	v_min_u32_e32 v22, v22, v151
	v_max_u32_e32 v151, v152, v21
	v_min_u32_e32 v21, v152, v21
	v_max_u32_e32 v152, v153, v1
	v_min_u32_e32 v1, v153, v1
	v_max_u32_e32 v153, v0, v23
	v_min_u32_e32 v0, v0, v23
	v_max_u32_e32 v23, v3, v24
	v_min_u32_e32 v3, v3, v24
	v_max_u32_e32 v24, v25, v2
	v_min_u32_e32 v2, v25, v2
	v_max_u32_e32 v146, v147, v28
	v_min_u32_e32 v28, v147, v28
	v_max_u32_e32 v147, v14, v4
	v_min_u32_e32 v4, v14, v4
	v_max_u32_e32 v14, v12, v10
	v_min_u32_e32 v10, v12, v10
	v_max_u32_e32 v12, v143, v5
	v_min_u32_e32 v5, v143, v5
	v_max_u32_e32 v143, v148, v149
	v_min_u32_e32 v148, v148, v149
	v_max_u32_e32 v149, v15, v8
	v_min_u32_e32 v8, v15, v8
	v_max_u32_e32 v15, v16, v17
	v_min_u32_e32 v16, v16, v17
	v_max_u32_e32 v17, v145, v144
	v_min_u32_e32 v144, v145, v144
	v_max_u32_e32 v25, v26, v161
	v_min_u32_e32 v26, v26, v161
	v_max_u32_e32 v161, v20, v18
	v_min_u32_e32 v18, v20, v18
	v_max_u32_e32 v20, v21, v22
	v_min_u32_e32 v21, v21, v22
	v_max_u32_e32 v22, v151, v150
	v_min_u32_e32 v150, v151, v150
	v_max_u32_e32 v151, v152, v153
	v_min_u32_e32 v152, v152, v153
	v_max_u32_e32 v153, v1, v0
	v_min_u32_e32 v0, v1, v0
	v_max_u32_e32 v1, v2, v3
	v_min_u32_e32 v2, v2, v3
	v_max_u32_e32 v3, v24, v23
	v_min_u32_e32 v23, v24, v23
	v_max_u32_e32 v145, v146, v10
	v_min_u32_e32 v10, v146, v10
	v_max_u32_e32 v146, v28, v14
	v_min_u32_e32 v14, v28, v14
	v_max_u32_e32 v28, v147, v5
	v_min_u32_e32 v5, v147, v5
	v_max_u32_e32 v147, v4, v12
	v_min_u32_e32 v4, v4, v12
	v_max_u32_e32 v12, v16, v143
	v_min_u32_e32 v16, v16, v143
	v_max_u32_e32 v143, v15, v148
	v_min_u32_e32 v15, v15, v148
	v_max_u32_e32 v148, v144, v149
	v_min_u32_e32 v144, v144, v149
	v_max_u32_e32 v149, v17, v8
	v_min_u32_e32 v8, v17, v8
	v_max_u32_e32 v24, v25, v21
	v_min_u32_e32 v21, v25, v21
	v_max_u32_e32 v25, v26, v20
	v_min_u32_e32 v20, v26, v20
	v_max_u32_e32 v26, v161, v150
	v_min_u32_e32 v150, v161, v150
	v_max_u32_e32 v161, v18, v22
	v_min_u32_e32 v18, v18, v22
	v_max_u32_e32 v22, v2, v151
	v_min_u32_e32 v2, v2, v151
	v_max_u32_e32 v151, v1, v152
	v_min_u32_e32 v1, v1, v152
	v_max_u32_e32 v152, v23, v153
	v_min_u32_e32 v23, v23, v153
	v_max_u32_e32 v153, v3, v0
	v_min_u32_e32 v0, v3, v0
	v_max_u32_e32 v17, v145, v28
	v_min_u32_e32 v28, v145, v28
	v_max_u32_e32 v145, v146, v147
	v_min_u32_e32 v146, v146, v147
	v_max_u32_e32 v147, v10, v5
	v_min_u32_e32 v5, v10, v5
	v_max_u32_e32 v10, v14, v4
	v_min_u32_e32 v4, v14, v4
	v_max_u32_e32 v14, v144, v16
	v_min_u32_e32 v16, v144, v16
	v_max_u32_e32 v144, v8, v15
	v_min_u32_e32 v8, v8, v15
	v_max_u32_e32 v15, v148, v12
	v_min_u32_e32 v12, v148, v12
	v_max_u32_e32 v148, v149, v143
	v_min_u32_e32 v143, v149, v143
	v_max_u32_e32 v3, v24, v26
	v_min_u32_e32 v24, v24, v26
	v_max_u32_e32 v26, v25, v161
	v_min_u32_e32 v25, v25, v161
	v_max_u32_e32 v161, v21, v150
	v_min_u32_e32 v21, v21, v150
	v_max_u32_e32 v150, v20, v18
	v_min_u32_e32 v18, v20, v18
	v_max_u32_e32 v20, v23, v2
	v_min_u32_e32 v2, v23, v2
	v_max_u32_e32 v23, v0, v1
	v_min_u32_e32 v0, v0, v1
	v_max_u32_e32 v1, v152, v22
	v_min_u32_e32 v22, v152, v22
	v_max_u32_e32 v152, v153, v151
	v_min_u32_e32 v151, v153, v151
	v_max_u32_e32 v149, v17, v145
	v_min_u32_e32 v17, v17, v145
	v_max_u32_e32 v145, v28, v146
	v_min_u32_e32 v28, v28, v146
	v_max_u32_e32 v146, v147, v10
	v_min_u32_e32 v10, v147, v10
	v_max_u32_e32 v147, v5, v4
	v_min_u32_e32 v4, v5, v4
	v_max_u32_e32 v5, v8, v16
	v_min_u32_e32 v8, v8, v16
	v_max_u32_e32 v16, v144, v14
	v_min_u32_e32 v14, v144, v14
	v_max_u32_e32 v144, v143, v12
	v_min_u32_e32 v12, v143, v12
	v_max_u32_e32 v143, v148, v15
	v_min_u32_e32 v15, v148, v15
	v_max_u32_e32 v153, v3, v26
	v_min_u32_e32 v3, v3, v26
	v_max_u32_e32 v26, v24, v25
	v_min_u32_e32 v24, v24, v25
	v_max_u32_e32 v25, v161, v150
	v_min_u32_e32 v150, v161, v150
	v_max_u32_e32 v161, v21, v18
	v_min_u32_e32 v18, v21, v18
	v_max_u32_e32 v21, v0, v2
	v_min_u32_e32 v0, v0, v2
	v_max_u32_e32 v2, v23, v20
	v_min_u32_e32 v20, v23, v20
	v_max_u32_e32 v23, v151, v22
	v_min_u32_e32 v22, v151, v22
	v_max_u32_e32 v151, v152, v1
	v_min_u32_e32 v1, v152, v1
	v_max_u32_e32 v148, v149, v8
	v_min_u32_e32 v8, v149, v8
	v_max_u32_e32 v149, v17, v5
	v_min_u32_e32 v5, v17, v5
	v_max_u32_e32 v17, v145, v14
	v_min_u32_e32 v14, v145, v14
	v_max_u32_e32 v145, v28, v16
	v_min_u32_e32 v16, v28, v16
	v_max_u32_e32 v28, v146, v12
	v_min_u32_e32 v12, v146, v12
	v_max_u32_e32 v146, v10, v144
	v_min_u32_e32 v10, v10, v144
	v_max_u32_e32 v144, v147, v15
	v_min_u32_e32 v15, v147, v15
	v_max_u32_e32 v147, v4, v143
	v_min_u32_e32 v4, v4, v143
	v_max_u32_e32 v152, v153, v0
	v_min_u32_e32 v0, v153, v0
	v_max_u32_e32 v153, v3, v21
	v_min_u32_e32 v3, v3, v21
	v_max_u32_e32 v21, v26, v20
	v_min_u32_e32 v20, v26, v20
	v_max_u32_e32 v26, v24, v2
	v_min_u32_e32 v2, v24, v2
	v_max_u32_e32 v24, v25, v22
	v_min_u32_e32 v22, v25, v22
	v_max_u32_e32 v25, v150, v23
	v_min_u32_e32 v23, v150, v23
	v_max_u32_e32 v150, v161, v1
	v_min_u32_e32 v1, v161, v1
	v_max_u32_e32 v161, v18, v151
	v_min_u32_e32 v18, v18, v151
	v_max_u32_e32 v143, v148, v28
	v_min_u32_e32 v28, v148, v28
	v_max_u32_e32 v148, v149, v146
	v_min_u32_e32 v146, v149, v146
; #define CE_DESC(a, b) do { const unsigned _mx = (a) > (b) ? (a) : (b), _mn = (a) > (b) ? (b) : (a); (a) = _mx; (b) = _mn; } while (0)
; __device__ __forceinline__ void merge16(unsigned (&a)[16], const unsigned (&b)[16]) {
; #pragma unroll
;     for (int i = 0; i < 16; ++i) a[i] = a[i] > b[15 - i] ? a[i] : b[15 - i];
; #pragma unroll
;     for (int stride = 8; stride > 0; stride >>= 1)
; #pragma unroll
;         for (int i = 0; i < 16; ++i) { const int j = i ^ stride; if (j > i) CE_DESC(a[i], a[j]); }
; }
; __device__ __forceinline__ void peer_tile(const Args& A, LAS unsigned char* lds, int tile) {
;     ...
;                 for (int msk = 16; msk <= 32; msk <<= 1) {
; #pragma unroll
;                     for (int i = 0; i < 16; ++i) k1[i] = (unsigned)__shfl_xor((int)k0[i], msk);
;                     merge16(k0, k1); }
	v_max_u32_e32 v149, v17, v144
	v_min_u32_e32 v17, v17, v144
	v_max_u32_e32 v144, v145, v147
	v_min_u32_e32 v145, v145, v147
	v_max_u32_e32 v147, v8, v12
	v_min_u32_e32 v8, v8, v12
	v_max_u32_e32 v12, v5, v10
	v_min_u32_e32 v5, v5, v10
	v_max_u32_e32 v10, v14, v15
	v_min_u32_e32 v14, v14, v15
	v_max_u32_e32 v15, v16, v4
	v_min_u32_e32 v4, v16, v4
	v_max_u32_e32 v151, v152, v24
	v_min_u32_e32 v24, v152, v24
	v_max_u32_e32 v152, v153, v25
	v_min_u32_e32 v25, v153, v25
	v_max_u32_e32 v153, v21, v150
	v_min_u32_e32 v21, v21, v150
	v_max_u32_e32 v150, v26, v161
	v_min_u32_e32 v26, v26, v161
	v_max_u32_e32 v161, v0, v22
	v_min_u32_e32 v0, v0, v22
	v_max_u32_e32 v22, v3, v23
	v_min_u32_e32 v3, v3, v23
	v_max_u32_e32 v23, v20, v1
	v_min_u32_e32 v1, v20, v1
	v_max_u32_e32 v20, v2, v18
	v_min_u32_e32 v2, v2, v18
	v_max_u32_e32 v16, v143, v149
	v_min_u32_e32 v143, v143, v149
	v_max_u32_e32 v149, v148, v144
	v_min_u32_e32 v144, v148, v144
	v_max_u32_e32 v148, v28, v17
	v_min_u32_e32 v17, v28, v17
	v_max_u32_e32 v28, v146, v145
	v_min_u32_e32 v145, v146, v145
	v_max_u32_e32 v146, v147, v10
	v_min_u32_e32 v10, v147, v10
	v_max_u32_e32 v147, v12, v15
	v_min_u32_e32 v12, v12, v15
	v_max_u32_e32 v15, v8, v14
	v_min_u32_e32 v8, v8, v14
	v_max_u32_e32 v14, v5, v4
	v_min_u32_e32 v4, v5, v4
	v_max_u32_e32 v18, v151, v153
	v_min_u32_e32 v151, v151, v153
	v_max_u32_e32 v153, v152, v150
	v_min_u32_e32 v150, v152, v150
	v_max_u32_e32 v152, v24, v21
	v_min_u32_e32 v21, v24, v21
	v_max_u32_e32 v24, v25, v26
	v_min_u32_e32 v25, v25, v26
	v_max_u32_e32 v26, v161, v23
	v_min_u32_e32 v23, v161, v23
	v_max_u32_e32 v161, v22, v20
	v_min_u32_e32 v20, v22, v20
	v_max_u32_e32 v22, v0, v1
	v_min_u32_e32 v0, v0, v1
	v_max_u32_e32 v1, v3, v2
	v_min_u32_e32 v2, v3, v2
	v_min_u32_e32 v5, v16, v149
	v_min_u32_e32 v154, v143, v144
	v_min_u32_e32 v155, v148, v28
	v_min_u32_e32 v156, v17, v145
	v_min_u32_e32 v157, v146, v147
	v_min_u32_e32 v158, v10, v12
	v_min_u32_e32 v159, v15, v14
	v_min_u32_e32 v160, v8, v4
	v_min_u32_e32 v3, v18, v153
	v_min_u32_e32 v162, v151, v150
	v_min_u32_e32 v163, v152, v24
	v_min_u32_e32 v164, v21, v25
	v_min_u32_e32 v165, v26, v161
	v_min_u32_e32 v166, v23, v20
	v_min_u32_e32 v167, v22, v1
	v_min_u32_e32 v168, v0, v2
	v_max3_u32 v16, v16, v149, v168
	v_max3_u32 v0, v5, v0, v2
	v_max3_u32 v2, v143, v144, v167
	v_max3_u32 v1, v154, v22, v1
	v_max3_u32 v5, v148, v28, v166
	v_max3_u32 v20, v155, v23, v20
	v_max3_u32 v17, v17, v145, v165
	v_max3_u32 v22, v156, v26, v161
	v_max3_u32 v23, v146, v147, v164
	v_max3_u32 v21, v157, v21, v25
	v_max3_u32 v10, v10, v12, v163
	v_max3_u32 v12, v158, v152, v24
	v_max3_u32 v14, v15, v14, v162
	v_max3_u32 v15, v159, v151, v150
	v_max3_u32 v3, v8, v4, v3
	v_max3_u32 v4, v160, v18, v153
	v_max_u32_e32 v8, v16, v23
	v_min_u32_e32 v16, v16, v23
	v_max_u32_e32 v18, v0, v21
	v_min_u32_e32 v0, v0, v21
	v_max_u32_e32 v21, v2, v10
	v_min_u32_e32 v2, v2, v10
	v_max_u32_e32 v10, v1, v12
	v_min_u32_e32 v1, v1, v12
	v_max_u32_e32 v12, v5, v14
	v_min_u32_e32 v5, v5, v14
	v_max_u32_e32 v14, v20, v15
	v_min_u32_e32 v15, v20, v15
	v_max_u32_e32 v20, v17, v3
	v_min_u32_e32 v3, v17, v3
	v_max_u32_e32 v17, v22, v4
	v_min_u32_e32 v4, v22, v4
	v_max_u32_e32 v22, v8, v12
	v_min_u32_e32 v8, v8, v12
	v_max_u32_e32 v12, v18, v14
	v_min_u32_e32 v14, v18, v14
	v_max_u32_e32 v18, v21, v20
	v_min_u32_e32 v20, v21, v20
	v_max_u32_e32 v21, v10, v17
	v_min_u32_e32 v10, v10, v17
	v_max_u32_e32 v17, v16, v5
	v_min_u32_e32 v5, v16, v5
	v_max_u32_e32 v16, v0, v15
	v_min_u32_e32 v0, v0, v15
	v_max_u32_e32 v15, v2, v3
	v_min_u32_e32 v2, v2, v3
	v_max_u32_e32 v3, v1, v4
	v_min_u32_e32 v1, v1, v4
	v_max_u32_e32 v4, v22, v18
	v_min_u32_e32 v18, v22, v18
	v_max_u32_e32 v22, v12, v21
	v_min_u32_e32 v12, v12, v21
	v_max_u32_e32 v21, v8, v20
	v_min_u32_e32 v8, v8, v20
	v_max_u32_e32 v20, v14, v10
	v_min_u32_e32 v10, v14, v10
	v_max_u32_e32 v14, v17, v15
	v_min_u32_e32 v15, v17, v15
	v_max_u32_e32 v17, v16, v3
	v_min_u32_e32 v3, v16, v3
	v_max_u32_e32 v16, v5, v2
	v_min_u32_e32 v2, v5, v2
	v_max_u32_e32 v5, v0, v1
	v_min_u32_e32 v0, v0, v1
	v_max_u32_e32 v1, v4, v22
	v_min_u32_e32 v4, v4, v22
	v_max_u32_e32 v22, v18, v12
	v_min_u32_e32 v12, v18, v12
	v_max_u32_e32 v18, v21, v20
	v_min_u32_e32 v20, v21, v20
	v_max_u32_e32 v21, v8, v10
	v_min_u32_e32 v8, v8, v10
	v_max_u32_e32 v10, v14, v17
	v_min_u32_e32 v14, v14, v17
	v_max_u32_e32 v17, v15, v3
	v_min_u32_e32 v3, v15, v3
	v_max_u32_e32 v15, v16, v5
	v_min_u32_e32 v5, v16, v5
	v_max_u32_e32 v16, v2, v0
	v_min_u32_e32 v0, v2, v0
	ds_bpermute_b32 v2, v27, v1
	ds_bpermute_b32 v23, v27, v4
	ds_bpermute_b32 v24, v27, v22
	ds_bpermute_b32 v25, v27, v12
	ds_bpermute_b32 v26, v27, v18
	ds_bpermute_b32 v28, v27, v20
	ds_bpermute_b32 v143, v27, v21
	ds_bpermute_b32 v144, v27, v8
	ds_bpermute_b32 v145, v27, v10
	ds_bpermute_b32 v146, v27, v14
	ds_bpermute_b32 v147, v27, v17
	ds_bpermute_b32 v148, v27, v0
	ds_bpermute_b32 v149, v27, v16
	ds_bpermute_b32 v150, v27, v5
	ds_bpermute_b32 v151, v27, v15
	ds_bpermute_b32 v27, v27, v3
	s_waitcnt lgkmcnt(4)
	v_max_u32_e32 v1, v1, v148
	s_waitcnt lgkmcnt(3)
	v_max_u32_e32 v4, v4, v149
	s_waitcnt lgkmcnt(2)
	v_max_u32_e32 v22, v22, v150
	s_waitcnt lgkmcnt(1)
	v_max_u32_e32 v12, v12, v151
	s_waitcnt lgkmcnt(0)
; __device__ __forceinline__ float key2f(unsigned k) { const unsigned u = (k & 0x80000000u) ? (k & 0x7fffffffu) : ~k; return __uint_as_float(u); }
; __device__ __forceinline__ void peer_tile(const Args& A, LAS unsigned char* lds, int tile) {
;     ...
;                 for (int msk = 16; msk <= 32; msk <<= 1) {
; #pragma unroll
;                     for (int i = 0; i < 16; ++i) k1[i] = (unsigned)__shfl_xor((int)k0[i], msk);
;                     merge16(k0, k1); }
;     ...
;             const int h = 4 * hg + g;
;             unsigned L2[2][16];
; #pragma unroll
;             for (int p = 0; p < 2; ++p)
; #pragma unroll
;                 for (int i = 0; i < 16; ++i) L2[p][i] = (g & 2) ? ((g & 1) ? LA[3][p][i] : LA[2][p][i]) : ((g & 1) ? LA[1][p][i] : LA[0][p][i]);
;             float va[16], vb[16];
; #pragma unroll
;             for (int i = 0; i < 16; ++i) { va[i] = key2f(L2[0][i] & ~127u); vb[i] = key2f(L2[1][i] & ~127u); idx[i] = 127u - (L2[0][i] & 127u); idx[16 + i] = 127u - (L2[1][i] & 127u); }
	v_max_u32_e32 v18, v18, v27
	v_max_u32_e32 v20, v20, v147
	v_max_u32_e32 v21, v21, v146
	v_max_u32_e32 v8, v8, v145
	v_max_u32_e32 v10, v10, v144
	v_max_u32_e32 v14, v14, v143
	v_max_u32_e32 v17, v17, v28
	v_max_u32_e32 v3, v3, v26
	v_max_u32_e32 v15, v15, v25
	v_max_u32_e32 v5, v5, v24
	v_max_u32_e32 v16, v16, v23
	v_max_u32_e32 v0, v0, v2
	v_max_u32_e32 v2, v1, v10
	v_min_u32_e32 v1, v1, v10
	v_max_u32_e32 v10, v4, v14
	v_min_u32_e32 v4, v4, v14
	v_max_u32_e32 v14, v22, v17
	v_min_u32_e32 v17, v22, v17
	v_max_u32_e32 v22, v12, v3
	v_min_u32_e32 v3, v12, v3
	v_max_u32_e32 v12, v18, v15
	v_min_u32_e32 v15, v18, v15
	v_max_u32_e32 v18, v20, v5
	v_min_u32_e32 v5, v20, v5
	v_max_u32_e32 v20, v21, v16
	v_min_u32_e32 v16, v21, v16
	v_max_u32_e32 v21, v8, v0
	v_min_u32_e32 v0, v8, v0
	v_max_u32_e32 v8, v2, v12
	v_min_u32_e32 v2, v2, v12
	v_max_u32_e32 v12, v10, v18
	v_min_u32_e32 v10, v10, v18
	v_max_u32_e32 v18, v14, v20
	v_min_u32_e32 v14, v14, v20
	v_max_u32_e32 v20, v22, v21
	v_min_u32_e32 v21, v22, v21
	v_max_u32_e32 v22, v1, v15
	v_min_u32_e32 v1, v1, v15
	v_max_u32_e32 v15, v4, v5
	v_min_u32_e32 v4, v4, v5
	v_max_u32_e32 v5, v17, v16
	v_min_u32_e32 v16, v17, v16
	v_max_u32_e32 v17, v3, v0
	v_min_u32_e32 v0, v3, v0
	v_max_u32_e32 v3, v8, v18
	v_min_u32_e32 v8, v8, v18
	v_max_u32_e32 v18, v12, v20
	v_min_u32_e32 v12, v12, v20
	v_max_u32_e32 v20, v2, v14
	v_min_u32_e32 v2, v2, v14
	v_max_u32_e32 v14, v10, v21
	v_min_u32_e32 v10, v10, v21
	v_max_u32_e32 v21, v22, v5
	v_min_u32_e32 v5, v22, v5
	v_max_u32_e32 v22, v15, v17
	v_min_u32_e32 v15, v15, v17
	v_max_u32_e32 v17, v1, v16
	v_min_u32_e32 v1, v1, v16
	v_max_u32_e32 v16, v4, v0
	v_min_u32_e32 v0, v4, v0
	v_max_u32_e32 v4, v3, v18
	v_min_u32_e32 v3, v3, v18
	v_max_u32_e32 v18, v8, v12
	v_min_u32_e32 v8, v8, v12
	v_max_u32_e32 v12, v20, v14
	v_min_u32_e32 v14, v20, v14
	v_max_u32_e32 v20, v2, v10
	v_min_u32_e32 v2, v2, v10
	v_max_u32_e32 v10, v21, v22
	v_min_u32_e32 v21, v21, v22
	v_max_u32_e32 v22, v5, v15
	v_min_u32_e32 v5, v5, v15
	v_max_u32_e32 v15, v17, v16
	v_min_u32_e32 v16, v17, v16
	v_max_u32_e32 v17, v1, v0
	v_min_u32_e32 v0, v1, v0
	ds_bpermute_b32 v1, v29, v4
	ds_bpermute_b32 v23, v29, v3
	ds_bpermute_b32 v24, v29, v18
	ds_bpermute_b32 v25, v29, v8
	ds_bpermute_b32 v26, v29, v12
	ds_bpermute_b32 v27, v29, v14
	ds_bpermute_b32 v28, v29, v20
	ds_bpermute_b32 v143, v29, v2
	ds_bpermute_b32 v144, v29, v10
	ds_bpermute_b32 v145, v29, v21
	ds_bpermute_b32 v146, v29, v22
	ds_bpermute_b32 v147, v29, v0
	ds_bpermute_b32 v148, v29, v17
	ds_bpermute_b32 v149, v29, v16
	ds_bpermute_b32 v150, v29, v15
	ds_bpermute_b32 v29, v29, v5
	s_waitcnt lgkmcnt(4)
	v_max_u32_e32 v4, v4, v147
	s_waitcnt lgkmcnt(3)
	v_max_u32_e32 v3, v3, v148
	s_waitcnt lgkmcnt(2)
	v_max_u32_e32 v18, v18, v149
	s_waitcnt lgkmcnt(1)
	v_max_u32_e32 v8, v8, v150
	s_waitcnt lgkmcnt(0)
	v_max_u32_e32 v12, v12, v29
	v_max_u32_e32 v14, v14, v146
	v_max_u32_e32 v20, v20, v145
	v_max_u32_e32 v2, v2, v144
	v_max_u32_e32 v10, v10, v143
	v_max_u32_e32 v21, v21, v28
	v_max_u32_e32 v22, v22, v27
	v_max_u32_e32 v5, v5, v26
	v_max_u32_e32 v15, v15, v25
	v_max_u32_e32 v16, v16, v24
	v_max_u32_e32 v17, v17, v23
	v_max_u32_e32 v0, v0, v1
	v_max_u32_e32 v1, v4, v10
	v_min_u32_e32 v4, v4, v10
	v_max_u32_e32 v10, v3, v21
	v_min_u32_e32 v3, v3, v21
	v_max_u32_e32 v21, v18, v22
	v_min_u32_e32 v18, v18, v22
	v_max_u32_e32 v22, v8, v5
	v_min_u32_e32 v5, v8, v5
	v_max_u32_e32 v8, v12, v15
	v_min_u32_e32 v12, v12, v15
	v_max_u32_e32 v15, v14, v16
	v_min_u32_e32 v14, v14, v16
	v_max_u32_e32 v16, v20, v17
	v_min_u32_e32 v17, v20, v17
	v_max_u32_e32 v20, v2, v0
	v_min_u32_e32 v0, v2, v0
	v_max_u32_e32 v2, v1, v8
	v_min_u32_e32 v1, v1, v8
	v_max_u32_e32 v8, v10, v15
	v_min_u32_e32 v10, v10, v15
	v_max_u32_e32 v15, v21, v16
	v_min_u32_e32 v16, v21, v16
	v_max_u32_e32 v21, v22, v20
	v_min_u32_e32 v20, v22, v20
	v_max_u32_e32 v22, v4, v12
	v_min_u32_e32 v4, v4, v12
	v_max_u32_e32 v12, v3, v14
	v_min_u32_e32 v3, v3, v14
	v_max_u32_e32 v14, v18, v17
	v_min_u32_e32 v17, v18, v17
	v_max_u32_e32 v18, v5, v0
	v_min_u32_e32 v0, v5, v0
	v_max_u32_e32 v5, v2, v15
	v_min_u32_e32 v2, v2, v15
	v_max_u32_e32 v15, v8, v21
	v_min_u32_e32 v8, v8, v21
	v_max_u32_e32 v21, v1, v16
	v_min_u32_e32 v1, v1, v16
	v_max_u32_e32 v16, v10, v20
	v_min_u32_e32 v10, v10, v20
	v_max_u32_e32 v20, v22, v14
	v_min_u32_e32 v14, v22, v14
	v_max_u32_e32 v22, v12, v18
	v_min_u32_e32 v12, v12, v18
	v_max_u32_e32 v18, v4, v17
	v_min_u32_e32 v4, v4, v17
	v_max_u32_e32 v17, v3, v0
	v_min_u32_e32 v0, v3, v0
	v_max_u32_e32 v3, v5, v15
	v_min_u32_e32 v5, v5, v15
	v_max_u32_e32 v15, v2, v8
	v_min_u32_e32 v2, v2, v8
	v_max_u32_e32 v8, v21, v16
	v_min_u32_e32 v16, v21, v16
	v_max_u32_e32 v21, v1, v10
	v_min_u32_e32 v1, v1, v10
	v_max_u32_e32 v10, v20, v22
	v_min_u32_e32 v20, v20, v22
	v_max_u32_e32 v22, v14, v12
	v_min_u32_e32 v12, v14, v12
	v_max_u32_e32 v14, v18, v17
	v_min_u32_e32 v17, v18, v17
	v_max_u32_e32 v18, v4, v0
	v_min_u32_e32 v0, v4, v0
	v_and_b32_e32 v4, 16, v19
	v_cmp_eq_u32_e32 vcc, 0, v4
	v_cndmask_b32_e64 v23, v77, v45, s[0:1]
	v_cndmask_b32_e64 v24, v76, v44, s[0:1]
	v_cndmask_b32_e32 v4, v142, v109, vcc
	v_cndmask_b32_e64 v4, v4, v23, s[4:5]
	v_cndmask_b32_e32 v23, v141, v108, vcc
	v_cndmask_b32_e64 v23, v23, v24, s[4:5]
	v_cndmask_b32_e32 v24, v140, v107, vcc
	v_cndmask_b32_e64 v25, v75, v43, s[0:1]
	v_cndmask_b32_e64 v24, v24, v25, s[4:5]
	v_cndmask_b32_e32 v25, v139, v106, vcc
	v_cndmask_b32_e64 v26, v74, v42, s[0:1]
	v_cndmask_b32_e64 v25, v25, v26, s[4:5]
	v_cndmask_b32_e32 v26, v138, v105, vcc
	v_cndmask_b32_e64 v27, v73, v41, s[0:1]
	v_cndmask_b32_e64 v26, v26, v27, s[4:5]
; __device__ __forceinline__ float key2f(unsigned k) { const unsigned u = (k & 0x80000000u) ? (k & 0x7fffffffu) : ~k; return __uint_as_float(u); }
; __device__ __forceinline__ void peer_tile(const Args& A, LAS unsigned char* lds, int tile) {
;     ...
;                 for (int i = 0; i < 16; ++i) L2[p][i] = (g & 2) ? ((g & 1) ? LA[3][p][i] : LA[2][p][i]) : ((g & 1) ? LA[1][p][i] : LA[0][p][i]);
;             float va[16], vb[16];
; #pragma unroll
;             for (int i = 0; i < 16; ++i) { va[i] = key2f(L2[0][i] & ~127u); vb[i] = key2f(L2[1][i] & ~127u); idx[i] = 127u - (L2[0][i] & 127u); idx[16 + i] = 127u - (L2[1][i] & 127u); }
	v_cndmask_b32_e32 v27, v137, v104, vcc
	v_cndmask_b32_e64 v28, v72, v40, s[0:1]
	v_cndmask_b32_e64 v27, v27, v28, s[4:5]
	v_cndmask_b32_e32 v28, v136, v103, vcc
	v_cndmask_b32_e64 v29, v71, v39, s[0:1]
	v_cndmask_b32_e64 v28, v28, v29, s[4:5]
	v_cndmask_b32_e32 v29, v135, v102, vcc
	v_cndmask_b32_e64 v29, v29, v38, s[4:5]
	v_cndmask_b32_e32 v38, v134, v101, vcc
	v_cndmask_b32_e64 v37, v38, v37, s[4:5]
	v_cndmask_b32_e32 v38, v133, v100, vcc
	v_cndmask_b32_e64 v36, v38, v36, s[4:5]
	v_cndmask_b32_e32 v38, v132, v99, vcc
	v_cndmask_b32_e64 v38, v38, v35, s[4:5]
	v_cndmask_b32_e32 v35, v131, v98, vcc
	v_cndmask_b32_e64 v39, v35, v34, s[4:5]
	v_cndmask_b32_e32 v34, v130, v97, vcc
	v_cndmask_b32_e64 v33, v34, v33, s[4:5]
	v_cndmask_b32_e32 v34, v129, v96, vcc
	v_cndmask_b32_e64 v40, v34, v32, s[4:5]
	v_cndmask_b32_e32 v32, v128, v95, vcc
	v_cndmask_b32_e64 v42, v32, v31, s[4:5]
	v_cndmask_b32_e32 v31, v127, v94, vcc
	v_cndmask_b32_e64 v43, v31, v30, s[4:5]
	v_cndmask_b32_e32 v3, v3, v126, vcc
	v_cndmask_b32_e64 v30, v93, v61, s[0:1]
	v_cndmask_b32_e64 v3, v3, v30, s[4:5]
	v_cndmask_b32_e32 v5, v5, v125, vcc
	v_cndmask_b32_e64 v30, v92, v60, s[0:1]
	v_cndmask_b32_e64 v30, v5, v30, s[4:5]
	v_cndmask_b32_e32 v5, v15, v124, vcc
	v_cndmask_b32_e64 v15, v91, v59, s[0:1]
	v_cndmask_b32_e64 v15, v5, v15, s[4:5]
	v_cndmask_b32_e32 v2, v2, v123, vcc
	v_cndmask_b32_e64 v5, v90, v58, s[0:1]
	v_cndmask_b32_e64 v31, v2, v5, s[4:5]
	v_cndmask_b32_e32 v2, v8, v122, vcc
	v_cndmask_b32_e64 v5, v89, v57, s[0:1]
	v_cndmask_b32_e64 v8, v2, v5, s[4:5]
	v_cndmask_b32_e32 v2, v16, v121, vcc
	v_cndmask_b32_e64 v5, v88, v56, s[0:1]
	v_cndmask_b32_e64 v32, v2, v5, s[4:5]
	v_cndmask_b32_e32 v2, v21, v120, vcc
	v_cndmask_b32_e64 v5, v87, v55, s[0:1]
	v_cndmask_b32_e64 v21, v2, v5, s[4:5]
	v_cndmask_b32_e32 v1, v1, v119, vcc
	v_cndmask_b32_e64 v2, v86, v54, s[0:1]
	v_cndmask_b32_e64 v34, v1, v2, s[4:5]
	v_cndmask_b32_e32 v1, v10, v118, vcc
	v_cndmask_b32_e64 v2, v85, v53, s[0:1]
	v_cndmask_b32_e64 v41, v1, v2, s[4:5]
	v_cndmask_b32_e32 v1, v20, v117, vcc
	v_cndmask_b32_e64 v2, v84, v52, s[0:1]
	v_cndmask_b32_e64 v44, v1, v2, s[4:5]
	v_cndmask_b32_e32 v1, v22, v116, vcc
	v_cndmask_b32_e64 v2, v83, v51, s[0:1]
	v_cndmask_b32_e64 v45, v1, v2, s[4:5]
	v_cndmask_b32_e32 v1, v12, v115, vcc
	v_cndmask_b32_e64 v2, v82, v50, s[0:1]
	v_cndmask_b32_e64 v50, v1, v2, s[4:5]
	v_cndmask_b32_e32 v1, v14, v114, vcc
	v_cndmask_b32_e64 v2, v81, v49, s[0:1]
	v_cndmask_b32_e64 v49, v1, v2, s[4:5]
	v_cndmask_b32_e32 v1, v17, v112, vcc
	v_cndmask_b32_e64 v2, v80, v48, s[0:1]
	v_cndmask_b32_e64 v48, v1, v2, s[4:5]
	v_cndmask_b32_e32 v1, v18, v111, vcc
	v_cndmask_b32_e64 v2, v79, v47, s[0:1]
	v_cndmask_b32_e64 v47, v1, v2, s[4:5]
	v_cndmask_b32_e32 v0, v0, v110, vcc
	v_cndmask_b32_e64 v1, v78, v46, s[0:1]
	v_cndmask_b32_e64 v46, v0, v1, s[4:5]
	v_and_b32_e32 v0, 0x7fffff80, v4
	v_bitop3_b32 v1, v4, s19, v4 bitop3:0xcf
	v_cmp_gt_i32_e32 vcc, 0, v4
	v_bitop3_b32 v2, v4, s19, v4 bitop3:0xc
	v_bitop3_b32 v4, v23, s19, v23 bitop3:0xcf
	v_cndmask_b32_e32 v20, v1, v0, vcc
	v_and_b32_e32 v0, 0x7fffff80, v3
	v_bitop3_b32 v1, v3, s19, v3 bitop3:0xcf
	v_cmp_gt_i32_e32 vcc, 0, v3
	v_add_u32_e32 v5, 0, v6
	v_bitop3_b32 v3, v3, s19, v3 bitop3:0xc
	v_cndmask_b32_e32 v1, v1, v0, vcc
	v_and_b32_e32 v0, 0x7fffff80, v23
	v_cmp_gt_i32_e32 vcc, 0, v23
	v_bitop3_b32 v14, v31, s19, v31 bitop3:0xcf
	v_bitop3_b32 v6, v24, s19, v24 bitop3:0xc
	v_cndmask_b32_e32 v18, v4, v0, vcc
	v_and_b32_e32 v0, 0x7fffff80, v30
	v_bitop3_b32 v4, v30, s19, v30 bitop3:0xcf
	v_cmp_gt_i32_e32 vcc, 0, v30
	v_bitop3_b32 v10, v15, s19, v15 bitop3:0xc
	v_bitop3_b32 v16, v32, s19, v32 bitop3:0xcf
	v_cndmask_b32_e32 v0, v4, v0, vcc
	v_bitop3_b32 v4, v23, s19, v23 bitop3:0xc
	ds_write2_b32 v5, v2, v4 offset1:1
	v_bitop3_b32 v2, v30, s19, v30 bitop3:0xc
	ds_write2_b32 v5, v3, v2 offset0:16 offset1:17
	v_and_b32_e32 v2, 0x7fffff80, v24
	v_bitop3_b32 v3, v24, s19, v24 bitop3:0xcf
	v_cmp_gt_i32_e32 vcc, 0, v24
	v_bitop3_b32 v4, v25, s19, v25 bitop3:0xcf
	v_bitop3_b32 v22, v29, s19, v29 bitop3:0xcf
	v_cndmask_b32_e32 v12, v3, v2, vcc
	v_and_b32_e32 v2, 0x7fffff80, v15
	v_bitop3_b32 v3, v15, s19, v15 bitop3:0xcf
	v_cmp_gt_i32_e32 vcc, 0, v15
	v_bitop3_b32 v15, v27, s19, v27 bitop3:0xcf
	v_bitop3_b32 v24, v34, s19, v34 bitop3:0xcf
	v_cndmask_b32_e32 v3, v3, v2, vcc
	v_and_b32_e32 v2, 0x7fffff80, v25
	v_cmp_gt_i32_e32 vcc, 0, v25
	s_nop 1
	v_cndmask_b32_e32 v4, v4, v2, vcc
	v_and_b32_e32 v2, 0x7fffff80, v31
	v_cmp_gt_i32_e32 vcc, 0, v31
	s_nop 1
	v_cndmask_b32_e32 v2, v14, v2, vcc
	v_bitop3_b32 v14, v25, s19, v25 bitop3:0xc
	ds_write2_b32 v5, v6, v14 offset0:2 offset1:3
	v_bitop3_b32 v6, v31, s19, v31 bitop3:0xc
	ds_write2_b32 v5, v10, v6 offset0:18 offset1:19
	v_and_b32_e32 v6, 0x7fffff80, v26
	v_bitop3_b32 v10, v26, s19, v26 bitop3:0xcf
	v_cmp_gt_i32_e32 vcc, 0, v26
	v_bitop3_b32 v25, v36, s19, v36 bitop3:0xcf
	s_nop 0
	v_cndmask_b32_e32 v14, v10, v6, vcc
	v_and_b32_e32 v6, 0x7fffff80, v8
	v_bitop3_b32 v10, v8, s19, v8 bitop3:0xcf
	v_cmp_gt_i32_e32 vcc, 0, v8
	v_bitop3_b32 v8, v8, s19, v8 bitop3:0xc
	s_nop 0
	v_cndmask_b32_e32 v17, v10, v6, vcc
	v_and_b32_e32 v10, 0x7fffff80, v27
	v_cmp_gt_i32_e32 vcc, 0, v27
	v_bitop3_b32 v6, v26, s19, v26 bitop3:0xc
	v_bitop3_b32 v26, v43, s19, v43 bitop3:0xcf
	v_cndmask_b32_e32 v10, v15, v10, vcc
	v_and_b32_e32 v15, 0x7fffff80, v32
	v_cmp_gt_i32_e32 vcc, 0, v32
	s_nop 1
	v_cndmask_b32_e32 v16, v16, v15, vcc
	v_bitop3_b32 v15, v27, s19, v27 bitop3:0xc
	ds_write2_b32 v5, v6, v15 offset0:4 offset1:5
	v_bitop3_b32 v6, v32, s19, v32 bitop3:0xc
	ds_write2_b32 v5, v8, v6 offset0:20 offset1:21
	v_and_b32_e32 v6, 0x7fffff80, v28
; __device__ __forceinline__ float key2f(unsigned k) { const unsigned u = (k & 0x80000000u) ? (k & 0x7fffffffu) : ~k; return __uint_as_float(u); }
; #define CK(i, j) ((f2key(va[i] + vb[j]) & ~255u) | (unsigned)(255 - (16 * (i) + (j))))
; __device__ __forceinline__ void peer_tile(const Args& A, LAS unsigned char* lds, int tile) {
;     ...
;             for (int i = 0; i < 16; ++i) { va[i] = key2f(L2[0][i] & ~127u); vb[i] = key2f(L2[1][i] & ~127u); idx[i] = 127u - (L2[0][i] & 127u); idx[16 + i] = 127u - (L2[1][i] & 127u); }
;     ...
;             unsigned Lf[16], Bt[16];
; #pragma unroll
;             for (int j = 0; j < 16; ++j) Lf[j] = CK(0, j);
	v_bitop3_b32 v8, v28, s19, v28 bitop3:0xcf
	v_cmp_gt_i32_e32 vcc, 0, v28
	v_bitop3_b32 v15, v21, s19, v21 bitop3:0xcf
	s_nop 0
	v_cndmask_b32_e32 v8, v8, v6, vcc
	v_and_b32_e32 v6, 0x7fffff80, v21
	v_cmp_gt_i32_e32 vcc, 0, v21
	v_bitop3_b32 v21, v21, s19, v21 bitop3:0xc
	s_nop 0
	v_cndmask_b32_e32 v23, v15, v6, vcc
	v_and_b32_e32 v6, 0x7fffff80, v29
	v_cmp_gt_i32_e32 vcc, 0, v29
	v_bitop3_b32 v15, v28, s19, v28 bitop3:0xc
	s_nop 0
	v_cndmask_b32_e32 v6, v22, v6, vcc
	v_and_b32_e32 v22, 0x7fffff80, v34
	v_cmp_gt_i32_e32 vcc, 0, v34
	s_nop 1
	v_cndmask_b32_e32 v22, v24, v22, vcc
	v_bitop3_b32 v24, v29, s19, v29 bitop3:0xc
	ds_write2_b32 v5, v15, v24 offset0:6 offset1:7
	v_bitop3_b32 v15, v34, s19, v34 bitop3:0xc
	ds_write2_b32 v5, v21, v15 offset0:22 offset1:23
	v_and_b32_e32 v15, 0x7fffff80, v37
	v_bitop3_b32 v21, v37, s19, v37 bitop3:0xcf
	v_cmp_gt_i32_e32 vcc, 0, v37
	v_and_b32_e32 v24, 0x7fffff80, v36
	s_nop 0
	v_cndmask_b32_e32 v27, v21, v15, vcc
	v_and_b32_e32 v15, 0x7fffff80, v41
	v_bitop3_b32 v21, v41, s19, v41 bitop3:0xcf
	v_cmp_gt_i32_e32 vcc, 0, v41
	s_nop 1
	v_cndmask_b32_e32 v35, v21, v15, vcc
	v_cmp_gt_i32_e32 vcc, 0, v36
	v_bitop3_b32 v15, v37, s19, v37 bitop3:0xc
	v_bitop3_b32 v21, v41, s19, v41 bitop3:0xc
	v_cndmask_b32_e32 v28, v25, v24, vcc
	v_and_b32_e32 v24, 0x7fffff80, v44
	v_bitop3_b32 v25, v44, s19, v44 bitop3:0xcf
	v_cmp_gt_i32_e32 vcc, 0, v44
	s_nop 1
	v_cndmask_b32_e32 v34, v25, v24, vcc
	v_bitop3_b32 v24, v36, s19, v36 bitop3:0xc
	ds_write2_b32 v5, v15, v24 offset0:8 offset1:9
	v_bitop3_b32 v15, v44, s19, v44 bitop3:0xc
	ds_write2_b32 v5, v21, v15 offset0:24 offset1:25
	v_and_b32_e32 v15, 0x7fffff80, v38
	v_bitop3_b32 v21, v38, s19, v38 bitop3:0xcf
	v_cmp_gt_i32_e32 vcc, 0, v38
	v_and_b32_e32 v24, 0x7fffff80, v39
	v_bitop3_b32 v25, v39, s19, v39 bitop3:0xcf
	v_cndmask_b32_e32 v29, v21, v15, vcc
	v_and_b32_e32 v15, 0x7fffff80, v45
	v_bitop3_b32 v21, v45, s19, v45 bitop3:0xcf
	v_cmp_gt_i32_e32 vcc, 0, v45
	s_nop 1
	v_cndmask_b32_e32 v37, v21, v15, vcc
	v_cmp_gt_i32_e32 vcc, 0, v39
	v_bitop3_b32 v15, v38, s19, v38 bitop3:0xc
	v_bitop3_b32 v21, v45, s19, v45 bitop3:0xc
	v_cndmask_b32_e32 v30, v25, v24, vcc
	v_and_b32_e32 v24, 0x7fffff80, v50
	v_bitop3_b32 v25, v50, s19, v50 bitop3:0xcf
	v_cmp_gt_i32_e32 vcc, 0, v50
	s_nop 1
	v_cndmask_b32_e32 v36, v25, v24, vcc
	v_bitop3_b32 v24, v39, s19, v39 bitop3:0xc
	ds_write2_b32 v5, v15, v24 offset0:10 offset1:11
	v_bitop3_b32 v15, v50, s19, v50 bitop3:0xc
	ds_write2_b32 v5, v21, v15 offset0:26 offset1:27
	v_and_b32_e32 v15, 0x7fffff80, v33
	v_bitop3_b32 v21, v33, s19, v33 bitop3:0xcf
	v_cmp_gt_i32_e32 vcc, 0, v33
	v_and_b32_e32 v24, 0x7fffff80, v40
	v_bitop3_b32 v25, v40, s19, v40 bitop3:0xcf
	v_cndmask_b32_e32 v31, v21, v15, vcc
	v_and_b32_e32 v15, 0x7fffff80, v49
	v_bitop3_b32 v21, v49, s19, v49 bitop3:0xcf
	v_cmp_gt_i32_e32 vcc, 0, v49
	s_nop 1
	v_cndmask_b32_e32 v39, v21, v15, vcc
	v_cmp_gt_i32_e32 vcc, 0, v40
	v_bitop3_b32 v15, v33, s19, v33 bitop3:0xc
	v_bitop3_b32 v21, v49, s19, v49 bitop3:0xc
	v_cndmask_b32_e32 v32, v25, v24, vcc
	v_and_b32_e32 v24, 0x7fffff80, v48
	v_bitop3_b32 v25, v48, s19, v48 bitop3:0xcf
	v_cmp_gt_i32_e32 vcc, 0, v48
	v_bitop3_b32 v33, v46, s19, v46 bitop3:0xcf
	s_nop 0
	v_cndmask_b32_e32 v38, v25, v24, vcc
	v_bitop3_b32 v24, v40, s19, v40 bitop3:0xc
	ds_write2_b32 v5, v15, v24 offset0:12 offset1:13
	v_bitop3_b32 v15, v48, s19, v48 bitop3:0xc
	ds_write2_b32 v5, v21, v15 offset0:28 offset1:29
	v_and_b32_e32 v15, 0x7fffff80, v42
	v_bitop3_b32 v21, v42, s19, v42 bitop3:0xcf
	v_cmp_gt_i32_e32 vcc, 0, v42
	v_and_b32_e32 v24, 0x7fffff80, v43
	s_nop 0
	v_cndmask_b32_e32 v25, v21, v15, vcc
	v_and_b32_e32 v15, 0x7fffff80, v47
	v_bitop3_b32 v21, v47, s19, v47 bitop3:0xcf
	v_cmp_gt_i32_e32 vcc, 0, v47
	s_nop 1
	v_cndmask_b32_e32 v41, v21, v15, vcc
	v_cmp_gt_i32_e32 vcc, 0, v43
	v_bitop3_b32 v21, v47, s19, v47 bitop3:0xc
	v_bitop3_b32 v15, v42, s19, v42 bitop3:0xc
	v_cndmask_b32_e32 v26, v26, v24, vcc
	v_and_b32_e32 v24, 0x7fffff80, v46
	v_cmp_gt_i32_e32 vcc, 0, v46
	v_pk_add_f32 v[34:35], v[20:21], v[34:35] op_sel_hi:[0,1]
	s_nop 0
	v_cndmask_b32_e32 v40, v33, v24, vcc
	v_bitop3_b32 v24, v43, s19, v43 bitop3:0xc
	v_pk_add_f32 v[42:43], v[20:21], v[0:1] op_sel_hi:[0,1]
	ds_write2_b32 v5, v15, v24 offset0:14 offset1:15
	v_not_b32_e32 v15, v43
	v_or_b32_e32 v33, 0x80000000, v43
	v_cmp_gt_i32_e32 vcc, 0, v43
	v_or_b32_e32 v43, 0x80000000, v42
	v_bitop3_b32 v24, v46, s19, v46 bitop3:0xc
	v_cndmask_b32_e32 v15, v33, v15, vcc
	v_or_b32_e32 v33, 0xff, v15
	v_not_b32_e32 v15, v42
	v_cmp_gt_i32_e32 vcc, 0, v42
	ds_write2_b32 v5, v21, v24 offset0:30 offset1:31
	s_waitcnt lgkmcnt(0)
; #define CK(i, j) ((f2key(va[i] + vb[j]) & ~255u) | (unsigned)(255 - (16 * (i) + (j))))
; __device__ __forceinline__ void peer_tile(const Args& A, LAS unsigned char* lds, int tile) {
;     ...
;             unsigned Lf[16], Bt[16];
; #pragma unroll
;             for (int j = 0; j < 16; ++j) Lf[j] = CK(0, j);
; #pragma unroll
;             for (int j = 0; j < 8; ++j) Bt[j] = CK(1, j);
; #pragma unroll
;             for (int j = 0; j < 5; ++j) Bt[8 + j] = CK(2, j);
; #pragma unroll
;             for (int j = 0; j < 3; ++j) Bt[13 + j] = CK(4, j);
	s_nop 0
	v_cndmask_b32_e32 v15, v43, v15, vcc
	v_and_b32_e32 v15, 0xffffff00, v15
	v_pk_add_f32 v[42:43], v[20:21], v[2:3] op_sel_hi:[0,1]
	v_or_b32_e32 v44, 0xfe, v15
	v_not_b32_e32 v15, v43
	v_or_b32_e32 v45, 0x80000000, v43
	v_cmp_gt_i32_e32 vcc, 0, v43
	v_or_b32_e32 v43, 0x80000000, v42
	s_nop 0
	v_cndmask_b32_e32 v15, v45, v15, vcc
	v_and_b32_e32 v15, 0xffffff00, v15
	v_or_b32_e32 v45, 0xfd, v15
	v_not_b32_e32 v15, v42
	v_cmp_gt_i32_e32 vcc, 0, v42
	s_nop 1
	v_cndmask_b32_e32 v15, v43, v15, vcc
	v_and_b32_e32 v15, 0xffffff00, v15
	v_pk_add_f32 v[42:43], v[20:21], v[16:17] op_sel_hi:[0,1]
	v_or_b32_e32 v46, 0xfc, v15
	v_not_b32_e32 v15, v43
	v_or_b32_e32 v47, 0x80000000, v43
	v_cmp_gt_i32_e32 vcc, 0, v43
	v_or_b32_e32 v43, 0x80000000, v42
	s_nop 0
	v_cndmask_b32_e32 v15, v47, v15, vcc
	v_and_b32_e32 v15, 0xffffff00, v15
	v_or_b32_e32 v47, 0xfb, v15
	v_not_b32_e32 v15, v42
	v_cmp_gt_i32_e32 vcc, 0, v42
	s_nop 1
	v_cndmask_b32_e32 v15, v43, v15, vcc
	v_and_b32_e32 v15, 0xffffff00, v15
	v_pk_add_f32 v[42:43], v[20:21], v[22:23] op_sel_hi:[0,1]
	v_or_b32_e32 v48, 0xfa, v15
	v_not_b32_e32 v15, v43
	v_or_b32_e32 v49, 0x80000000, v43
	v_cmp_gt_i32_e32 vcc, 0, v43
	v_pk_add_f32 v[22:23], v[18:19], v[22:23] op_sel_hi:[0,1]
	s_nop 0
	v_cndmask_b32_e32 v15, v49, v15, vcc
	v_and_b32_e32 v15, 0xffffff00, v15
	v_or_b32_e32 v43, 0xf9, v15
	v_not_b32_e32 v15, v42
	v_or_b32_e32 v49, 0x80000000, v42
	v_cmp_gt_i32_e32 vcc, 0, v42
	s_nop 1
	v_cndmask_b32_e32 v15, v49, v15, vcc
	v_and_b32_e32 v15, 0xffffff00, v15
	v_or_b32_e32 v42, 0xf8, v15
	v_not_b32_e32 v15, v35
	v_or_b32_e32 v49, 0x80000000, v35
	v_cmp_gt_i32_e32 vcc, 0, v35
	v_or_b32_e32 v35, 0x80000000, v34
	s_nop 0
	v_cndmask_b32_e32 v15, v49, v15, vcc
	v_and_b32_e32 v15, 0xffffff00, v15
	v_or_b32_e32 v49, 0xf7, v15
	v_not_b32_e32 v15, v34
	v_cmp_gt_i32_e32 vcc, 0, v34
	s_nop 1
	v_cndmask_b32_e32 v15, v35, v15, vcc
	v_and_b32_e32 v15, 0xffffff00, v15
	v_pk_add_f32 v[34:35], v[20:21], v[36:37] op_sel_hi:[0,1]
	v_or_b32_e32 v50, 0xf6, v15
	v_not_b32_e32 v15, v35
	v_or_b32_e32 v36, 0x80000000, v35
	v_cmp_gt_i32_e32 vcc, 0, v35
	v_or_b32_e32 v35, 0x80000000, v34
	s_nop 0
	v_cndmask_b32_e32 v15, v36, v15, vcc
	v_and_b32_e32 v15, 0xffffff00, v15
	v_or_b32_e32 v36, 0xf5, v15
	v_not_b32_e32 v15, v34
	v_cmp_gt_i32_e32 vcc, 0, v34
	s_nop 1
	v_cndmask_b32_e32 v15, v35, v15, vcc
	v_and_b32_e32 v15, 0xffffff00, v15
	v_pk_add_f32 v[34:35], v[20:21], v[38:39] op_sel_hi:[0,1]
	v_or_b32_e32 v37, 0xf4, v15
	v_not_b32_e32 v15, v35
	v_or_b32_e32 v38, 0x80000000, v35
	v_cmp_gt_i32_e32 vcc, 0, v35
	v_or_b32_e32 v35, 0x80000000, v34
	s_nop 0
	v_cndmask_b32_e32 v15, v38, v15, vcc
	v_and_b32_e32 v15, 0xffffff00, v15
	v_or_b32_e32 v38, 0xf3, v15
	v_not_b32_e32 v15, v34
	v_cmp_gt_i32_e32 vcc, 0, v34
	s_nop 1
	v_cndmask_b32_e32 v15, v35, v15, vcc
	v_and_b32_e32 v15, 0xffffff00, v15
	v_pk_add_f32 v[34:35], v[20:21], v[40:41] op_sel_hi:[0,1]
	v_or_b32_e32 v39, 0xf2, v15
	v_not_b32_e32 v15, v35
	v_or_b32_e32 v20, 0x80000000, v35
	v_cmp_gt_i32_e32 vcc, 0, v35
	v_or_b32_e32 v35, 0x80000000, v34
	s_nop 0
	v_cndmask_b32_e32 v15, v20, v15, vcc
	v_and_b32_e32 v15, 0xffffff00, v15
	v_or_b32_e32 v20, 0xf1, v15
	v_not_b32_e32 v15, v34
	v_cmp_gt_i32_e32 vcc, 0, v34
	s_nop 1
	v_cndmask_b32_e32 v15, v35, v15, vcc
	v_and_b32_e32 v15, 0xffffff00, v15
	v_pk_add_f32 v[34:35], v[18:19], v[0:1] op_sel_hi:[0,1]
	v_or_b32_e32 v40, 0xf0, v15
	v_not_b32_e32 v15, v35
	v_or_b32_e32 v41, 0x80000000, v35
	v_cmp_gt_i32_e32 vcc, 0, v35
	v_or_b32_e32 v35, 0x80000000, v34
	s_nop 0
	v_cndmask_b32_e32 v15, v41, v15, vcc
	v_and_b32_e32 v15, 0xffffff00, v15
	v_or_b32_e32 v41, 0xef, v15
	v_not_b32_e32 v15, v34
	v_cmp_gt_i32_e32 vcc, 0, v34
	s_nop 1
	v_cndmask_b32_e32 v15, v35, v15, vcc
	v_and_b32_e32 v15, 0xffffff00, v15
	v_pk_add_f32 v[34:35], v[18:19], v[2:3] op_sel_hi:[0,1]
	v_or_b32_e32 v51, 0xee, v15
	v_not_b32_e32 v15, v35
	v_or_b32_e32 v52, 0x80000000, v35
	v_cmp_gt_i32_e32 vcc, 0, v35
	v_or_b32_e32 v35, 0x80000000, v34
	s_nop 0
	v_cndmask_b32_e32 v15, v52, v15, vcc
	v_and_b32_e32 v15, 0xffffff00, v15
	v_or_b32_e32 v52, 0xed, v15
	v_not_b32_e32 v15, v34
	v_cmp_gt_i32_e32 vcc, 0, v34
	s_nop 1
	v_cndmask_b32_e32 v15, v35, v15, vcc
	v_and_b32_e32 v15, 0xffffff00, v15
	v_pk_add_f32 v[34:35], v[18:19], v[16:17] op_sel_hi:[0,1]
	v_or_b32_e32 v53, 0xec, v15
	v_not_b32_e32 v15, v35
	v_or_b32_e32 v16, 0x80000000, v35
	v_cmp_gt_i32_e32 vcc, 0, v35
	s_nop 1
	v_cndmask_b32_e32 v15, v16, v15, vcc
	v_and_b32_e32 v15, 0xffffff00, v15
	v_or_b32_e32 v35, 0xeb, v15
	v_not_b32_e32 v15, v34
	v_or_b32_e32 v16, 0x80000000, v34
	v_cmp_gt_i32_e32 vcc, 0, v34
	s_nop 1
	v_cndmask_b32_e32 v15, v16, v15, vcc
	v_and_b32_e32 v15, 0xffffff00, v15
	v_or_b32_e32 v34, 0xea, v15
	v_not_b32_e32 v15, v23
	v_or_b32_e32 v16, 0x80000000, v23
	v_cmp_gt_i32_e32 vcc, 0, v23
	s_nop 1
	v_cndmask_b32_e32 v15, v16, v15, vcc
	v_and_b32_e32 v15, 0xffffff00, v15
	v_or_b32_e32 v18, 0xe9, v15
	v_not_b32_e32 v15, v22
	v_or_b32_e32 v16, 0x80000000, v22
	v_cmp_gt_i32_e32 vcc, 0, v22
	v_pk_add_f32 v[22:23], v[12:13], v[0:1] op_sel_hi:[0,1]
	s_nop 0
	v_cndmask_b32_e32 v15, v16, v15, vcc
	v_and_b32_e32 v15, 0xffffff00, v15
	v_or_b32_e32 v54, 0xe8, v15
	v_not_b32_e32 v15, v23
	v_or_b32_e32 v16, 0x80000000, v23
	v_cmp_gt_i32_e32 vcc, 0, v23
	s_nop 1
	v_cndmask_b32_e32 v15, v16, v15, vcc
	v_and_b32_e32 v15, 0xffffff00, v15
	v_or_b32_e32 v55, 0xdf, v15
	v_not_b32_e32 v15, v22
	v_or_b32_e32 v16, 0x80000000, v22
	v_cmp_gt_i32_e32 vcc, 0, v22
	v_pk_add_f32 v[22:23], v[12:13], v[2:3] op_sel_hi:[0,1]
	v_lshl_add_u32 v13, v13, 10, s35
	v_cndmask_b32_e32 v15, v16, v15, vcc
	v_and_b32_e32 v15, 0xffffff00, v15
; #define CE_DESC(a, b) do { const unsigned _mx = (a) > (b) ? (a) : (b), _mn = (a) > (b) ? (b) : (a); (a) = _mx; (b) = _mn; } while (0)
; #define CK(i, j) ((f2key(va[i] + vb[j]) & ~255u) | (unsigned)(255 - (16 * (i) + (j))))
; __device__ __forceinline__ void sort16_desc(unsigned (&k)[16]) {
; #pragma unroll
;     for (int size = 2; size <= 16; size <<= 1)
; #pragma unroll
;         for (int stride = size >> 1; stride > 0; stride >>= 1)
; #pragma unroll
;             for (int i = 0; i < 16; ++i) { const int j = i ^ stride;
;                 if (j > i) { if ((i & size) == 0) CE_DESC(k[i], k[j]); else CE_DESC(k[j], k[i]); } }
; }
; __device__ __forceinline__ void peer_tile(const Args& A, LAS unsigned char* lds, int tile) {
;     ...
;             unsigned Lf[16], Bt[16];
; #pragma unroll
;             for (int j = 0; j < 16; ++j) Lf[j] = CK(0, j);
; #pragma unroll
;             for (int j = 0; j < 8; ++j) Bt[j] = CK(1, j);
; #pragma unroll
;             for (int j = 0; j < 5; ++j) Bt[8 + j] = CK(2, j);
; #pragma unroll
;             for (int j = 0; j < 3; ++j) Bt[13 + j] = CK(4, j);
;             sort16_desc(Bt); merge16(Lf, Bt);
	v_or_b32_e32 v56, 0xde, v15
	v_not_b32_e32 v15, v23
	v_or_b32_e32 v16, 0x80000000, v23
	v_cmp_gt_i32_e32 vcc, 0, v23
	s_nop 1
	v_cndmask_b32_e32 v15, v16, v15, vcc
	v_and_b32_e32 v15, 0xffffff00, v15
	v_or_b32_e32 v23, 0xdd, v15
	v_not_b32_e32 v15, v22
	v_or_b32_e32 v16, 0x80000000, v22
	v_cmp_gt_i32_e32 vcc, 0, v22
	s_nop 1
	v_cndmask_b32_e32 v15, v16, v15, vcc
	v_and_b32_e32 v15, 0xffffff00, v15
	v_or_b32_e32 v22, 0xdc, v15
	v_mov_b32_e32 v15, v12
	v_mov_b32_e32 v16, v1
	v_pk_add_f32 v[16:17], v[14:15], v[16:17]
	s_nop 0
	v_not_b32_e32 v12, v17
	v_or_b32_e32 v15, 0x80000000, v17
	v_cmp_gt_i32_e32 vcc, 0, v17
	v_or_b32_e32 v17, 0x80000000, v16
	s_nop 0
	v_cndmask_b32_e32 v12, v15, v12, vcc
	v_not_b32_e32 v15, v16
	v_cmp_gt_i32_e32 vcc, 0, v16
	v_mov_b32_e32 v16, v3
	v_and_b32_e32 v12, 0xffffff00, v12
	v_cndmask_b32_e32 v15, v17, v15, vcc
	v_and_b32_e32 v15, 0xffffff00, v15
	v_mov_b32_e32 v17, v0
	v_or_b32_e32 v57, 0xbf, v15
	v_pk_add_f32 v[14:15], v[14:15], v[16:17] op_sel_hi:[0,1]
	v_not_b32_e32 v16, v15
	v_or_b32_e32 v17, 0x80000000, v15
	v_cmp_gt_i32_e32 vcc, 0, v15
	v_or_b32_e32 v12, 0xdb, v12
	v_pk_add_f32 v[2:3], v[4:5], v[2:3] op_sel_hi:[0,1]
	v_cndmask_b32_e32 v15, v17, v16, vcc
	v_not_b32_e32 v16, v14
	v_or_b32_e32 v17, 0x80000000, v14
	v_cmp_gt_i32_e32 vcc, 0, v14
	v_and_b32_e32 v15, 0xffffff00, v15
	v_or_b32_e32 v15, 0xbe, v15
	v_cndmask_b32_e32 v14, v17, v16, vcc
	v_and_b32_e32 v14, 0xffffff00, v14
	v_or_b32_e32 v14, 0xbd, v14
	v_max_u32_e32 v16, v41, v51
	v_min_u32_e32 v17, v41, v51
	v_max_u32_e32 v41, v53, v52
	v_min_u32_e32 v51, v53, v52
	v_max_u32_e32 v52, v35, v34
	v_min_u32_e32 v34, v35, v34
	v_max_u32_e32 v35, v54, v18
	v_min_u32_e32 v18, v54, v18
	v_max_u32_e32 v53, v55, v56
	v_min_u32_e32 v54, v55, v56
	v_max_u32_e32 v55, v22, v23
	v_min_u32_e32 v22, v22, v23
	v_max_u32_e32 v23, v12, v57
	v_min_u32_e32 v12, v12, v57
	v_max_u32_e32 v56, v14, v15
	v_min_u32_e32 v14, v14, v15
	v_max_u32_e32 v15, v16, v51
	v_min_u32_e32 v16, v16, v51
	v_max_u32_e32 v51, v17, v41
	v_min_u32_e32 v17, v17, v41
	v_max_u32_e32 v41, v18, v52
	v_min_u32_e32 v18, v18, v52
	v_max_u32_e32 v52, v35, v34
	v_min_u32_e32 v34, v35, v34
	v_max_u32_e32 v35, v53, v22
	v_min_u32_e32 v22, v53, v22
	v_max_u32_e32 v53, v54, v55
	v_min_u32_e32 v54, v54, v55
	v_max_u32_e32 v55, v14, v23
	v_min_u32_e32 v14, v14, v23
	v_max_u32_e32 v23, v56, v12
	v_min_u32_e32 v12, v56, v12
	v_max_u32_e32 v56, v15, v51
	v_min_u32_e32 v15, v15, v51
	v_max_u32_e32 v51, v16, v17
	v_min_u32_e32 v16, v16, v17
	v_max_u32_e32 v17, v34, v18
	v_min_u32_e32 v18, v34, v18
	v_max_u32_e32 v34, v52, v41
	v_min_u32_e32 v41, v52, v41
	v_max_u32_e32 v52, v35, v53
	v_min_u32_e32 v35, v35, v53
	v_max_u32_e32 v53, v22, v54
	v_min_u32_e32 v22, v22, v54
	v_max_u32_e32 v54, v12, v14
	v_min_u32_e32 v12, v12, v14
	v_max_u32_e32 v14, v23, v55
	v_min_u32_e32 v23, v23, v55
	v_max_u32_e32 v55, v56, v18
	v_min_u32_e32 v18, v56, v18
	v_max_u32_e32 v56, v15, v17
	v_min_u32_e32 v15, v15, v17
	v_max_u32_e32 v17, v51, v41
	v_min_u32_e32 v41, v51, v41
	v_max_u32_e32 v51, v16, v34
	v_min_u32_e32 v16, v16, v34
	v_max_u32_e32 v34, v12, v52
	v_min_u32_e32 v12, v12, v52
	v_max_u32_e32 v52, v54, v35
	v_min_u32_e32 v35, v54, v35
	v_max_u32_e32 v54, v23, v53
	v_min_u32_e32 v23, v23, v53
	v_max_u32_e32 v53, v14, v22
	v_min_u32_e32 v14, v14, v22
	v_max_u32_e32 v22, v55, v17
	v_min_u32_e32 v17, v55, v17
	v_max_u32_e32 v55, v56, v51
	v_min_u32_e32 v51, v56, v51
	v_max_u32_e32 v56, v18, v41
	v_min_u32_e32 v18, v18, v41
	v_max_u32_e32 v41, v15, v16
	v_min_u32_e32 v15, v15, v16
	v_max_u32_e32 v16, v23, v12
	v_min_u32_e32 v12, v23, v12
	v_max_u32_e32 v23, v14, v35
	v_min_u32_e32 v14, v14, v35
	v_max_u32_e32 v35, v54, v34
	v_min_u32_e32 v34, v54, v34
	v_max_u32_e32 v54, v53, v52
	v_min_u32_e32 v52, v53, v52
	v_max_u32_e32 v53, v22, v55
	v_min_u32_e32 v22, v22, v55
	v_max_u32_e32 v55, v17, v51
	v_min_u32_e32 v17, v17, v51
	v_max_u32_e32 v51, v56, v41
	v_min_u32_e32 v41, v56, v41
	v_max_u32_e32 v56, v18, v15
	v_min_u32_e32 v15, v18, v15
	v_max_u32_e32 v18, v14, v12
	v_min_u32_e32 v12, v14, v12
	v_max_u32_e32 v14, v23, v16
	v_min_u32_e32 v16, v23, v16
	v_max_u32_e32 v23, v52, v34
	v_min_u32_e32 v34, v52, v34
	v_max_u32_e32 v52, v54, v35
	v_min_u32_e32 v35, v54, v35
	v_max_u32_e32 v54, v53, v12
	v_min_u32_e32 v12, v53, v12
	v_max_u32_e32 v53, v22, v18
	v_min_u32_e32 v18, v22, v18
	v_max_u32_e32 v22, v55, v16
	v_min_u32_e32 v16, v55, v16
	v_max_u32_e32 v55, v17, v14
	v_min_u32_e32 v14, v17, v14
	v_max_u32_e32 v17, v51, v34
	v_min_u32_e32 v34, v51, v34
	v_max_u32_e32 v51, v41, v23
	v_min_u32_e32 v23, v41, v23
	v_max_u32_e32 v41, v56, v35
	v_min_u32_e32 v35, v56, v35
	v_max_u32_e32 v56, v15, v52
	v_min_u32_e32 v15, v15, v52
	v_max_u32_e32 v52, v54, v17
	v_min_u32_e32 v17, v54, v17
	v_max_u32_e32 v54, v53, v51
	v_min_u32_e32 v51, v53, v51
	v_max_u32_e32 v53, v22, v41
	v_min_u32_e32 v22, v22, v41
	v_max_u32_e32 v41, v55, v56
	v_min_u32_e32 v55, v55, v56
	v_max_u32_e32 v56, v12, v34
	v_min_u32_e32 v12, v12, v34
	v_max_u32_e32 v34, v18, v23
	v_min_u32_e32 v18, v18, v23
	v_max_u32_e32 v23, v16, v35
	v_min_u32_e32 v16, v16, v35
	v_max_u32_e32 v35, v14, v15
	v_min_u32_e32 v14, v14, v15
	v_max_u32_e32 v15, v52, v53
	v_min_u32_e32 v52, v52, v53
	v_max_u32_e32 v53, v54, v41
	v_min_u32_e32 v41, v54, v41
	v_max_u32_e32 v54, v17, v22
	v_min_u32_e32 v17, v17, v22
	v_max_u32_e32 v22, v51, v55
	v_min_u32_e32 v51, v51, v55
	v_max_u32_e32 v55, v56, v23
	v_min_u32_e32 v23, v56, v23
	v_max_u32_e32 v56, v34, v35
	v_min_u32_e32 v34, v34, v35
	v_max_u32_e32 v35, v12, v16
	v_min_u32_e32 v12, v12, v16
	v_max_u32_e32 v16, v18, v14
	v_min_u32_e32 v14, v18, v14
; #define CE_DESC(a, b) do { const unsigned _mx = (a) > (b) ? (a) : (b), _mn = (a) > (b) ? (b) : (a); (a) = _mx; (b) = _mn; } while (0)
; #define CK(i, j) ((f2key(va[i] + vb[j]) & ~255u) | (unsigned)(255 - (16 * (i) + (j))))
; __device__ __forceinline__ void merge16(unsigned (&a)[16], const unsigned (&b)[16]) {
; #pragma unroll
;     for (int i = 0; i < 16; ++i) a[i] = a[i] > b[15 - i] ? a[i] : b[15 - i];
; #pragma unroll
;     for (int stride = 8; stride > 0; stride >>= 1)
; #pragma unroll
;         for (int i = 0; i < 16; ++i) { const int j = i ^ stride; if (j > i) CE_DESC(a[i], a[j]); }
; }
; __device__ __forceinline__ void peer_tile(const Args& A, LAS unsigned char* lds, int tile) {
;     ...
;             for (int j = 0; j < 4; ++j) Bt[j] = CK(3, j);
;             Bt[4] = CK(5, 0); Bt[5] = CK(5, 1); Bt[6] = CK(6, 0); Bt[7] = CK(6, 1); Bt[8] = CK(7, 0); Bt[9] = CK(7, 1);
;             Bt[10] = CK(8, 0); Bt[11] = CK(9, 0); Bt[12] = CK(10, 0); Bt[13] = CK(11, 0); Bt[14] = CK(12, 0); Bt[15] = CK(13, 0);
	v_min_u32_e32 v18, v15, v53
	v_min_u32_e32 v57, v52, v41
	v_min_u32_e32 v58, v54, v22
	v_min_u32_e32 v59, v17, v51
	v_min_u32_e32 v60, v55, v56
	v_min_u32_e32 v61, v23, v34
	v_min_u32_e32 v62, v35, v16
	v_min_u32_e32 v63, v12, v14
	v_max_u32_e32 v33, v33, v63
	v_max3_u32 v12, v44, v12, v14
	v_max_u32_e32 v14, v45, v62
	v_max3_u32 v16, v46, v35, v16
	v_max_u32_e32 v35, v47, v61
	v_max3_u32 v23, v48, v23, v34
	v_max_u32_e32 v34, v43, v60
	v_max3_u32 v42, v42, v55, v56
	v_max_u32_e32 v43, v49, v59
	v_max3_u32 v17, v50, v17, v51
	v_max_u32_e32 v36, v36, v58
	v_max3_u32 v22, v37, v54, v22
	v_max_u32_e32 v37, v38, v57
	v_max3_u32 v38, v39, v52, v41
	v_max_u32_e32 v18, v20, v18
	v_max3_u32 v15, v40, v15, v53
	v_max_u32_e32 v20, v33, v43
	v_min_u32_e32 v33, v33, v43
	v_max_u32_e32 v39, v12, v17
	v_min_u32_e32 v12, v12, v17
	v_max_u32_e32 v17, v14, v36
	v_min_u32_e32 v14, v14, v36
	v_max_u32_e32 v36, v16, v22
	v_min_u32_e32 v16, v16, v22
	v_max_u32_e32 v22, v35, v37
	v_min_u32_e32 v35, v35, v37
	v_max_u32_e32 v37, v23, v38
	v_min_u32_e32 v23, v23, v38
	v_max_u32_e32 v38, v34, v18
	v_min_u32_e32 v18, v34, v18
	v_max_u32_e32 v34, v42, v15
	v_min_u32_e32 v15, v42, v15
	v_max_u32_e32 v40, v20, v22
	v_min_u32_e32 v20, v20, v22
	v_max_u32_e32 v22, v39, v37
	v_min_u32_e32 v37, v39, v37
	v_max_u32_e32 v39, v17, v38
	v_min_u32_e32 v17, v17, v38
	v_max_u32_e32 v38, v36, v34
	v_min_u32_e32 v34, v36, v34
	v_max_u32_e32 v36, v33, v35
	v_min_u32_e32 v33, v33, v35
	v_max_u32_e32 v35, v12, v23
	v_min_u32_e32 v12, v12, v23
	v_max_u32_e32 v23, v14, v18
	v_min_u32_e32 v14, v14, v18
	v_max_u32_e32 v18, v16, v15
	v_min_u32_e32 v15, v16, v15
	v_max_u32_e32 v16, v40, v39
	v_min_u32_e32 v39, v40, v39
	v_max_u32_e32 v40, v22, v38
	v_min_u32_e32 v22, v22, v38
	v_max_u32_e32 v38, v20, v17
	v_min_u32_e32 v17, v20, v17
	v_max_u32_e32 v20, v37, v34
	v_min_u32_e32 v34, v37, v34
	v_max_u32_e32 v37, v36, v23
	v_min_u32_e32 v23, v36, v23
	v_max_u32_e32 v36, v35, v18
	v_min_u32_e32 v18, v35, v18
	v_max_u32_e32 v35, v33, v14
	v_min_u32_e32 v33, v33, v14
	v_max_u32_e32 v41, v12, v15
	v_min_u32_e32 v12, v12, v15
	v_pk_add_f32 v[14:15], v[4:5], v[0:1] op_sel_hi:[0,1]
	v_not_b32_e32 v50, v15
	v_or_b32_e32 v51, 0x80000000, v15
	v_cmp_gt_i32_e32 vcc, 0, v15
	v_not_b32_e32 v4, v3
	v_min_u32_e32 v42, v16, v40
	v_cndmask_b32_e32 v15, v51, v50, vcc
	v_not_b32_e32 v50, v14
	v_or_b32_e32 v51, 0x80000000, v14
	v_cmp_gt_i32_e32 vcc, 0, v14
	v_and_b32_e32 v15, 0xffffff00, v15
	v_or_b32_e32 v15, 0xcf, v15
	v_cndmask_b32_e32 v14, v51, v50, vcc
	v_or_b32_e32 v50, 0x80000000, v3
	v_cmp_gt_i32_e32 vcc, 0, v3
	v_and_b32_e32 v14, 0xffffff00, v14
	v_or_b32_e32 v14, 0xce, v14
	v_cndmask_b32_e32 v3, v50, v4, vcc
	v_and_b32_e32 v3, 0xffffff00, v3
	v_or_b32_e32 v4, 0xcd, v3
	v_not_b32_e32 v3, v2
	v_or_b32_e32 v50, 0x80000000, v2
	v_cmp_gt_i32_e32 vcc, 0, v2
	v_min_u32_e32 v43, v39, v22
	v_min_u32_e32 v44, v38, v20
	v_cndmask_b32_e32 v2, v50, v3, vcc
	v_and_b32_e32 v2, 0xffffff00, v2
	v_or_b32_e32 v50, 0xcc, v2
	v_pk_add_f32 v[2:3], v[10:11], v[0:1] op_sel_hi:[0,1]
	v_not_b32_e32 v10, v3
	v_or_b32_e32 v51, 0x80000000, v3
	v_cmp_gt_i32_e32 vcc, 0, v3
	v_min_u32_e32 v45, v17, v34
	v_min_u32_e32 v46, v37, v36
	v_cndmask_b32_e32 v3, v51, v10, vcc
	v_and_b32_e32 v3, 0xffffff00, v3
	v_or_b32_e32 v10, 0xaf, v3
	v_not_b32_e32 v3, v2
	v_or_b32_e32 v51, 0x80000000, v2
	v_cmp_gt_i32_e32 vcc, 0, v2
	v_min_u32_e32 v47, v23, v18
	v_min_u32_e32 v48, v35, v41
	v_cndmask_b32_e32 v2, v51, v3, vcc
	v_and_b32_e32 v2, 0xffffff00, v2
	v_or_b32_e32 v51, 0xae, v2
	v_pk_add_f32 v[2:3], v[8:9], v[0:1] op_sel_hi:[0,1]
	v_not_b32_e32 v8, v3
	v_or_b32_e32 v52, 0x80000000, v3
	v_cmp_gt_i32_e32 vcc, 0, v3
	v_min_u32_e32 v49, v33, v12
	v_lshlrev_b32_e32 v11, 9, v11
	v_cndmask_b32_e32 v3, v52, v8, vcc
	v_and_b32_e32 v3, 0xffffff00, v3
	v_or_b32_e32 v8, 0x9f, v3
	v_not_b32_e32 v3, v2
	v_or_b32_e32 v52, 0x80000000, v2
	v_cmp_gt_i32_e32 vcc, 0, v2
	s_nop 1
	v_cndmask_b32_e32 v2, v52, v3, vcc
	v_and_b32_e32 v2, 0xffffff00, v2
	v_or_b32_e32 v52, 0x9e, v2
	v_pk_add_f32 v[2:3], v[6:7], v[0:1] op_sel_hi:[0,1]
	v_not_b32_e32 v0, v3
	v_or_b32_e32 v6, 0x80000000, v3
	v_cmp_gt_i32_e32 vcc, 0, v3
	v_not_b32_e32 v3, v2
	s_nop 0
	v_cndmask_b32_e32 v0, v6, v0, vcc
	v_or_b32_e32 v6, 0x80000000, v2
	v_cmp_gt_i32_e32 vcc, 0, v2
	v_and_b32_e32 v0, 0xffffff00, v0
	v_or_b32_e32 v0, 0x8f, v0
	v_cndmask_b32_e32 v2, v6, v3, vcc
	v_add_f32_e32 v3, v27, v1
	v_not_b32_e32 v6, v3
	v_or_b32_e32 v27, 0x80000000, v3
	v_cmp_gt_i32_e32 vcc, 0, v3
	v_and_b32_e32 v2, 0xffffff00, v2
	v_or_b32_e32 v2, 0x8e, v2
	v_cndmask_b32_e32 v3, v27, v6, vcc
	v_add_f32_e32 v6, v28, v1
	v_not_b32_e32 v27, v6
	v_or_b32_e32 v28, 0x80000000, v6
	v_cmp_gt_i32_e32 vcc, 0, v6
	v_and_b32_e32 v3, 0xffffff00, v3
	v_or_b32_e32 v3, 0x7f, v3
	v_cndmask_b32_e32 v6, v28, v27, vcc
	v_add_f32_e32 v27, v29, v1
	v_not_b32_e32 v28, v27
	v_or_b32_e32 v29, 0x80000000, v27
	v_cmp_gt_i32_e32 vcc, 0, v27
	v_and_b32_e32 v6, 0xffffff00, v6
	v_or_b32_e32 v6, 0x6f, v6
	v_cndmask_b32_e32 v27, v29, v28, vcc
	v_add_f32_e32 v28, v30, v1
	v_not_b32_e32 v29, v28
	v_or_b32_e32 v30, 0x80000000, v28
	v_cmp_gt_i32_e32 vcc, 0, v28
	v_and_b32_e32 v27, 0xffffff00, v27
	v_or_b32_e32 v27, 0x5f, v27
	v_cndmask_b32_e32 v28, v30, v29, vcc
	v_add_f32_e32 v29, v31, v1
	v_not_b32_e32 v30, v29
	v_or_b32_e32 v31, 0x80000000, v29
	v_cmp_gt_i32_e32 vcc, 0, v29
	v_and_b32_e32 v28, 0xffffff00, v28
	v_or_b32_e32 v28, 0x4f, v28
	v_cndmask_b32_e32 v29, v31, v30, vcc
	v_add_f32_e32 v30, v32, v1
	v_not_b32_e32 v31, v30
	v_or_b32_e32 v32, 0x80000000, v30
	v_cmp_gt_i32_e32 vcc, 0, v30
	v_and_or_b32 v29, v29, s34, 63
	s_nop 0
	v_cndmask_b32_e32 v30, v32, v31, vcc
; #define CE_DESC(a, b) do { const unsigned _mx = (a) > (b) ? (a) : (b), _mn = (a) > (b) ? (b) : (a); (a) = _mx; (b) = _mn; } while (0)
; __device__ __forceinline__ void sort16_desc(unsigned (&k)[16]) {
; #pragma unroll
;     for (int size = 2; size <= 16; size <<= 1)
; #pragma unroll
;         for (int stride = size >> 1; stride > 0; stride >>= 1)
; #pragma unroll
;             for (int i = 0; i < 16; ++i) { const int j = i ^ stride;
;                 if (j > i) { if ((i & size) == 0) CE_DESC(k[i], k[j]); else CE_DESC(k[j], k[i]); } }
; }
; __device__ __forceinline__ void merge16(unsigned (&a)[16], const unsigned (&b)[16]) {
; #pragma unroll
;     for (int i = 0; i < 16; ++i) a[i] = a[i] > b[15 - i] ? a[i] : b[15 - i];
; #pragma unroll
;     for (int stride = 8; stride > 0; stride >>= 1)
; #pragma unroll
;         for (int i = 0; i < 16; ++i) { const int j = i ^ stride; if (j > i) CE_DESC(a[i], a[j]); }
; }
	v_and_or_b32 v30, v30, s34, 47
	v_max_u32_e32 v31, v15, v14
	v_min_u32_e32 v14, v15, v14
	v_max_u32_e32 v15, v50, v4
	v_min_u32_e32 v4, v50, v4
	v_max_u32_e32 v32, v10, v51
	v_min_u32_e32 v10, v10, v51
	v_max_u32_e32 v50, v52, v8
	v_min_u32_e32 v8, v52, v8
	v_max_u32_e32 v51, v0, v2
	v_min_u32_e32 v0, v0, v2
	v_max_u32_e32 v2, v6, v3
	v_min_u32_e32 v3, v6, v3
	v_max_u32_e32 v6, v27, v28
	v_min_u32_e32 v27, v27, v28
	v_max_u32_e32 v28, v30, v29
	v_min_u32_e32 v29, v30, v29
	v_max_u32_e32 v30, v31, v4
	v_min_u32_e32 v4, v31, v4
	v_max_u32_e32 v31, v14, v15
	v_min_u32_e32 v14, v14, v15
	v_max_u32_e32 v15, v8, v32
	v_min_u32_e32 v8, v8, v32
	v_max_u32_e32 v32, v50, v10
	v_min_u32_e32 v10, v50, v10
	v_max_u32_e32 v50, v51, v3
	v_min_u32_e32 v3, v51, v3
	v_max_u32_e32 v51, v0, v2
	v_min_u32_e32 v0, v0, v2
	v_max_u32_e32 v2, v29, v6
	v_min_u32_e32 v6, v29, v6
	v_max_u32_e32 v29, v28, v27
	v_min_u32_e32 v27, v28, v27
	v_max_u32_e32 v28, v30, v31
	v_min_u32_e32 v30, v30, v31
	v_max_u32_e32 v31, v4, v14
	v_min_u32_e32 v4, v4, v14
	v_max_u32_e32 v14, v10, v8
	v_min_u32_e32 v8, v10, v8
	v_max_u32_e32 v10, v32, v15
	v_min_u32_e32 v15, v32, v15
	v_max_u32_e32 v32, v50, v51
	v_min_u32_e32 v50, v50, v51
	v_max_u32_e32 v51, v3, v0
	v_min_u32_e32 v0, v3, v0
	v_max_u32_e32 v3, v27, v6
	v_min_u32_e32 v6, v27, v6
	v_max_u32_e32 v27, v29, v2
	v_min_u32_e32 v2, v29, v2
	v_max_u32_e32 v29, v28, v8
	v_min_u32_e32 v8, v28, v8
	v_max_u32_e32 v28, v30, v14
	v_min_u32_e32 v14, v30, v14
	v_max_u32_e32 v30, v31, v15
	v_min_u32_e32 v15, v31, v15
	v_max_u32_e32 v31, v4, v10
	v_min_u32_e32 v4, v4, v10
	v_max_u32_e32 v10, v6, v32
	v_min_u32_e32 v6, v6, v32
	v_max_u32_e32 v32, v3, v50
	v_min_u32_e32 v3, v3, v50
	v_max_u32_e32 v50, v2, v51
	v_min_u32_e32 v2, v2, v51
	v_max_u32_e32 v51, v27, v0
	v_min_u32_e32 v0, v27, v0
	v_max_u32_e32 v27, v29, v30
	v_min_u32_e32 v29, v29, v30
	v_max_u32_e32 v30, v28, v31
	v_min_u32_e32 v28, v28, v31
	v_max_u32_e32 v31, v8, v15
	v_min_u32_e32 v8, v8, v15
	v_max_u32_e32 v15, v14, v4
	v_min_u32_e32 v4, v14, v4
	v_max_u32_e32 v14, v2, v6
	v_min_u32_e32 v2, v2, v6
	v_max_u32_e32 v6, v0, v3
	v_min_u32_e32 v0, v0, v3
	v_max_u32_e32 v3, v50, v10
	v_min_u32_e32 v10, v50, v10
	v_max_u32_e32 v50, v51, v32
	v_min_u32_e32 v32, v51, v32
	v_max_u32_e32 v51, v27, v30
	v_min_u32_e32 v27, v27, v30
	v_max_u32_e32 v30, v29, v28
	v_min_u32_e32 v28, v29, v28
	v_max_u32_e32 v29, v31, v15
	v_min_u32_e32 v15, v31, v15
	v_max_u32_e32 v31, v8, v4
	v_min_u32_e32 v4, v8, v4
	v_max_u32_e32 v8, v0, v2
	v_min_u32_e32 v0, v0, v2
	v_max_u32_e32 v2, v6, v14
	v_min_u32_e32 v6, v6, v14
	v_max_u32_e32 v14, v32, v10
	v_min_u32_e32 v10, v32, v10
	v_max_u32_e32 v32, v50, v3
	v_min_u32_e32 v3, v50, v3
	v_max_u32_e32 v50, v51, v0
	v_min_u32_e32 v0, v51, v0
	v_max_u32_e32 v51, v27, v8
	v_min_u32_e32 v8, v27, v8
	v_max_u32_e32 v27, v30, v6
	v_min_u32_e32 v6, v30, v6
	v_max_u32_e32 v30, v28, v2
	v_min_u32_e32 v2, v28, v2
	v_max_u32_e32 v28, v29, v10
	v_min_u32_e32 v10, v29, v10
	v_max_u32_e32 v29, v15, v14
	v_min_u32_e32 v14, v15, v14
	v_max_u32_e32 v15, v31, v3
	v_min_u32_e32 v3, v31, v3
	v_max_u32_e32 v31, v4, v32
	v_min_u32_e32 v4, v4, v32
	v_max_u32_e32 v32, v50, v28
	v_min_u32_e32 v28, v50, v28
	v_max_u32_e32 v50, v51, v29
	v_min_u32_e32 v29, v51, v29
	v_max_u32_e32 v51, v27, v15
	v_min_u32_e32 v15, v27, v15
	v_max_u32_e32 v27, v30, v31
	v_min_u32_e32 v30, v30, v31
	v_max_u32_e32 v31, v0, v10
	v_min_u32_e32 v0, v0, v10
	v_max_u32_e32 v10, v8, v14
	v_min_u32_e32 v8, v8, v14
	v_max_u32_e32 v14, v6, v3
	v_min_u32_e32 v3, v6, v3
	v_max_u32_e32 v6, v2, v4
	v_min_u32_e32 v2, v2, v4
	v_max_u32_e32 v4, v32, v51
	v_min_u32_e32 v32, v32, v51
	v_max_u32_e32 v51, v50, v27
	v_min_u32_e32 v27, v50, v27
	v_max_u32_e32 v50, v28, v15
	v_min_u32_e32 v15, v28, v15
	v_max_u32_e32 v28, v29, v30
	v_min_u32_e32 v29, v29, v30
	v_max_u32_e32 v30, v31, v14
	v_min_u32_e32 v14, v31, v14
	v_max_u32_e32 v31, v10, v6
	v_min_u32_e32 v6, v10, v6
	v_max_u32_e32 v10, v0, v3
	v_min_u32_e32 v0, v0, v3
	v_max_u32_e32 v3, v8, v2
	v_min_u32_e32 v2, v8, v2
	v_min_u32_e32 v8, v4, v51
	v_min_u32_e32 v52, v32, v27
	v_min_u32_e32 v53, v50, v28
	v_min_u32_e32 v54, v15, v29
	v_min_u32_e32 v55, v30, v31
	v_min_u32_e32 v56, v14, v6
	v_min_u32_e32 v57, v10, v3
	v_min_u32_e32 v58, v0, v2
	v_max3_u32 v16, v16, v40, v58
	v_max3_u32 v0, v42, v0, v2
	v_max3_u32 v2, v39, v22, v57
	v_max3_u32 v3, v43, v10, v3
	v_max3_u32 v10, v38, v20, v56
	v_max3_u32 v6, v44, v14, v6
	v_max3_u32 v14, v17, v34, v55
	v_max3_u32 v17, v45, v30, v31
	v_max3_u32 v20, v37, v36, v54
	v_max3_u32 v15, v46, v15, v29
	v_max3_u32 v18, v23, v18, v53
	v_max3_u32 v22, v47, v50, v28
	v_max3_u32 v23, v35, v41, v52
	v_max3_u32 v27, v48, v32, v27
	v_max3_u32 v8, v33, v12, v8
	v_max3_u32 v4, v49, v4, v51
	v_max_u32_e32 v12, v16, v20
	v_min_u32_e32 v16, v16, v20
	v_max_u32_e32 v20, v0, v15
	v_min_u32_e32 v0, v0, v15
	v_max_u32_e32 v15, v2, v18
	v_min_u32_e32 v2, v2, v18
	v_max_u32_e32 v18, v3, v22
	v_min_u32_e32 v3, v3, v22
	v_max_u32_e32 v22, v10, v23
	v_min_u32_e32 v10, v10, v23
	v_max_u32_e32 v23, v6, v27
	v_min_u32_e32 v6, v6, v27
	v_max_u32_e32 v27, v14, v8
	v_min_u32_e32 v8, v14, v8
	v_max_u32_e32 v14, v17, v4
	v_min_u32_e32 v4, v17, v4
	v_max_u32_e32 v17, v12, v22
	v_min_u32_e32 v12, v12, v22
	v_max_u32_e32 v22, v20, v23
	v_min_u32_e32 v20, v20, v23
	v_max_u32_e32 v23, v15, v27
	v_min_u32_e32 v15, v15, v27
	v_max_u32_e32 v27, v18, v14
	v_min_u32_e32 v14, v18, v14
	v_max_u32_e32 v18, v16, v10
	v_min_u32_e32 v10, v16, v10
	v_max_u32_e32 v16, v0, v6
	v_min_u32_e32 v0, v0, v6
	v_max_u32_e32 v6, v2, v8
	v_min_u32_e32 v2, v2, v8
	v_max_u32_e32 v8, v3, v4
; __device__ __forceinline__ float key2f(unsigned k) { const unsigned u = (k & 0x80000000u) ? (k & 0x7fffffffu) : ~k; return __uint_as_float(u); }
; #define CE_DESC(a, b) do { const unsigned _mx = (a) > (b) ? (a) : (b), _mn = (a) > (b) ? (b) : (a); (a) = _mx; (b) = _mn; } while (0)
; #define CK(i, j) ((f2key(va[i] + vb[j]) & ~255u) | (unsigned)(255 - (16 * (i) + (j))))
; __device__ __forceinline__ void peer_tile(const Args& A, LAS unsigned char* lds, int tile) {
;     ...
;             sort16_desc(Bt); merge16(Lf, Bt);
;             { unsigned x0 = CK(14, 0), x1 = CK(15, 0);
; #pragma unroll
;               for (int i = 0; i < 16; ++i) CE_DESC(Lf[i], x0);
; #pragma unroll
;               for (int i = 0; i < 16; ++i) CE_DESC(Lf[i], x1); }
;     ...
;             float fv[16], den = 0.f; const float f0 = key2f(Lf[0] & ~255u);
; #pragma unroll
;             for (int k = 0; k < 16; ++k) { fv[k] = __expf(key2f(Lf[k] & ~255u) - f0); den += fv[k]; }
	v_min_u32_e32 v3, v3, v4
	v_max_u32_e32 v4, v17, v23
	v_min_u32_e32 v17, v17, v23
	v_max_u32_e32 v23, v22, v27
	v_min_u32_e32 v22, v22, v27
	v_max_u32_e32 v27, v12, v15
	v_min_u32_e32 v12, v12, v15
	v_max_u32_e32 v15, v20, v14
	v_min_u32_e32 v14, v20, v14
	v_max_u32_e32 v20, v18, v6
	v_min_u32_e32 v6, v18, v6
	v_max_u32_e32 v18, v16, v8
	v_min_u32_e32 v8, v16, v8
	v_max_u32_e32 v16, v10, v2
	v_min_u32_e32 v2, v10, v2
	v_max_u32_e32 v10, v0, v3
	v_min_u32_e32 v0, v0, v3
	v_max_u32_e32 v41, v2, v0
	v_min_u32_e32 v0, v2, v0
	v_add_f32_e32 v2, v25, v1
	v_not_b32_e32 v25, v2
	v_or_b32_e32 v42, 0x80000000, v2
	v_cmp_gt_i32_e32 vcc, 0, v2
	v_add_f32_e32 v1, v26, v1
	v_max_u32_e32 v3, v4, v23
	v_cndmask_b32_e32 v2, v42, v25, vcc
	v_and_or_b32 v2, v2, s34, 31
	v_not_b32_e32 v25, v1
	v_or_b32_e32 v26, 0x80000000, v1
	v_cmp_gt_i32_e32 vcc, 0, v1
	v_min_u32_e32 v28, v4, v23
	v_max_u32_e32 v29, v17, v22
	v_cndmask_b32_e32 v1, v26, v25, vcc
	v_max_u32_e32 v25, v3, v2
	v_min_u32_e32 v3, v3, v2
	v_min_u32_e32 v3, v28, v3
	v_min_u32_e32 v30, v17, v22
	v_med3_u32 v2, v4, v23, v2
	v_min_u32_e32 v23, v29, v3
	v_max_u32_e32 v31, v27, v15
	v_max_u32_e32 v4, v29, v3
	v_med3_u32 v3, v17, v22, v3
	v_min_u32_e32 v17, v30, v23
	v_min_u32_e32 v32, v27, v15
	v_min_u32_e32 v23, v31, v17
	v_max_u32_e32 v33, v12, v14
	v_max_u32_e32 v22, v31, v17
	v_med3_u32 v15, v27, v15, v17
	v_min_u32_e32 v17, v32, v23
	v_min_u32_e32 v34, v12, v14
	v_min_u32_e32 v26, v33, v17
	v_max_u32_e32 v35, v20, v18
	v_med3_u32 v12, v12, v14, v17
	v_min_u32_e32 v14, v34, v26
	v_min_u32_e32 v36, v20, v18
	v_min_u32_e32 v26, v35, v14
	v_max_u32_e32 v37, v6, v8
	v_max_u32_e32 v23, v33, v17
	v_max_u32_e32 v17, v35, v14
	v_med3_u32 v14, v20, v18, v14
	v_min_u32_e32 v18, v36, v26
	v_min_u32_e32 v38, v6, v8
	v_min_u32_e32 v26, v37, v18
	v_max_u32_e32 v39, v16, v10
	v_med3_u32 v6, v6, v8, v18
	v_min_u32_e32 v8, v38, v26
	v_min_u32_e32 v40, v16, v10
	v_min_u32_e32 v26, v39, v8
	v_and_or_b32 v1, v1, s34, 15
	v_max_u32_e32 v20, v37, v18
	v_max_u32_e32 v18, v39, v8
	v_med3_u32 v8, v16, v10, v8
	v_min_u32_e32 v10, v40, v26
	v_max_u32_e32 v26, v25, v1
	v_min_u32_e32 v1, v25, v1
	v_max_u32_e32 v25, v2, v1
	v_min_u32_e32 v1, v2, v1
	v_max_u32_e32 v2, v4, v1
	v_min_u32_e32 v1, v4, v1
	v_max_u32_e32 v4, v3, v1
	v_min_u32_e32 v1, v3, v1
	v_max_u32_e32 v3, v22, v1
	v_min_u32_e32 v1, v22, v1
	v_max_u32_e32 v22, v15, v1
	v_min_u32_e32 v1, v15, v1
	v_max_u32_e32 v15, v23, v1
	v_min_u32_e32 v1, v23, v1
	v_max_u32_e32 v23, v12, v1
	v_min_u32_e32 v1, v12, v1
	v_max_u32_e32 v12, v17, v1
	v_min_u32_e32 v1, v17, v1
	v_max_u32_e32 v17, v14, v1
	v_min_u32_e32 v1, v14, v1
	v_max_u32_e32 v14, v20, v1
	v_min_u32_e32 v1, v20, v1
	v_max_u32_e32 v20, v6, v1
	v_min_u32_e32 v1, v6, v1
	v_max_u32_e32 v6, v18, v1
	v_min_u32_e32 v1, v18, v1
	v_max_u32_e32 v16, v41, v10
	v_max_u32_e32 v18, v8, v1
	v_min_u32_e32 v1, v8, v1
	v_min_u32_e32 v10, v41, v10
	v_max_u32_e32 v8, v16, v1
	v_min_u32_e32 v1, v16, v1
	v_max3_u32 v10, v0, v10, v1
	v_and_b32_e32 v0, 0x7fffff00, v26
	v_bitop3_b32 v1, v26, s33, v26 bitop3:0xcf
	v_cmp_gt_i32_e32 vcc, 0, v26
	v_and_b32_e32 v16, 0x7fffff00, v25
	v_bitop3_b32 v27, v25, s33, v25 bitop3:0xcf
	v_cndmask_b32_e32 v0, v1, v0, vcc
	v_cmp_gt_i32_e32 vcc, 0, v25
	v_sub_f32_e32 v1, v0, v0
	v_bitop3_b32 v28, v2, s33, v2 bitop3:0xcf
	v_cndmask_b32_e32 v16, v27, v16, vcc
	v_and_b32_e32 v27, 0x7fffff00, v2
	v_cmp_gt_i32_e32 vcc, 0, v2
	v_mul_f32_e32 v1, 0x3fb8aa3b, v1
	v_sub_f32_e32 v16, v16, v0
	v_cndmask_b32_e32 v27, v28, v27, vcc
	v_and_b32_e32 v28, 0x7fffff00, v4
	v_bitop3_b32 v29, v4, s33, v4 bitop3:0xcf
	v_cmp_gt_i32_e32 vcc, 0, v4
	v_exp_f32_e32 v1, v1
	v_mul_f32_e32 v16, 0x3fb8aa3b, v16
	v_sub_f32_e32 v27, v27, v0
	v_cndmask_b32_e32 v28, v29, v28, vcc
	v_and_b32_e32 v30, 0x7fffff00, v3
	v_bitop3_b32 v31, v3, s33, v3 bitop3:0xcf
	v_cmp_gt_i32_e32 vcc, 0, v3
	v_exp_f32_e32 v16, v16
	v_mul_f32_e32 v27, 0x3fb8aa3b, v27
	v_sub_f32_e32 v28, v28, v0
	v_cndmask_b32_e32 v30, v31, v30, vcc
	v_and_b32_e32 v31, 0x7fffff00, v22
	v_bitop3_b32 v32, v22, s33, v22 bitop3:0xcf
	v_cmp_gt_i32_e32 vcc, 0, v22
	v_exp_f32_e32 v27, v27
	v_mul_f32_e32 v28, 0x3fb8aa3b, v28
	v_sub_f32_e32 v30, v30, v0
	v_cndmask_b32_e32 v31, v32, v31, vcc
	v_and_b32_e32 v32, 0x7fffff00, v15
	v_bitop3_b32 v33, v15, s33, v15 bitop3:0xcf
	v_cmp_gt_i32_e32 vcc, 0, v15
	v_exp_f32_e32 v28, v28
	v_mul_f32_e32 v30, 0x3fb8aa3b, v30
	v_sub_f32_e32 v31, v31, v0
	v_cndmask_b32_e32 v32, v33, v32, vcc
	v_and_b32_e32 v33, 0x7fffff00, v23
	v_bitop3_b32 v34, v23, s33, v23 bitop3:0xcf
	v_cmp_gt_i32_e32 vcc, 0, v23
	v_add_f32_e32 v29, 0, v1
	v_exp_f32_e32 v30, v30
	v_mul_f32_e32 v31, 0x3fb8aa3b, v31
	v_sub_f32_e32 v32, v32, v0
	v_cndmask_b32_e32 v33, v34, v33, vcc
	v_and_b32_e32 v34, 0x7fffff00, v12
	v_bitop3_b32 v35, v12, s33, v12 bitop3:0xcf
	v_cmp_gt_i32_e32 vcc, 0, v12
	v_add_f32_e32 v29, v29, v16
	v_exp_f32_e32 v31, v31
	v_mul_f32_e32 v32, 0x3fb8aa3b, v32
	v_sub_f32_e32 v33, v33, v0
	v_cndmask_b32_e32 v34, v35, v34, vcc
	v_and_b32_e32 v35, 0x7fffff00, v17
	v_bitop3_b32 v36, v17, s33, v17 bitop3:0xcf
	v_cmp_gt_i32_e32 vcc, 0, v17
	v_add_f32_e32 v29, v29, v27
	v_exp_f32_e32 v32, v32
	v_mul_f32_e32 v33, 0x3fb8aa3b, v33
	v_sub_f32_e32 v34, v34, v0
	v_cndmask_b32_e32 v35, v36, v35, vcc
	v_and_b32_e32 v36, 0x7fffff00, v14
	v_bitop3_b32 v37, v14, s33, v14 bitop3:0xcf
	v_cmp_gt_i32_e32 vcc, 0, v14
	v_add_f32_e32 v29, v29, v28
	v_exp_f32_e32 v33, v33
	v_mul_f32_e32 v34, 0x3fb8aa3b, v34
	v_sub_f32_e32 v35, v35, v0
	v_cndmask_b32_e32 v36, v37, v36, vcc
	v_and_b32_e32 v37, 0x7fffff00, v20
	v_bitop3_b32 v38, v20, s33, v20 bitop3:0xcf
	v_cmp_gt_i32_e32 vcc, 0, v20
	v_add_f32_e32 v29, v29, v30
; #define LDS_WAIT() asm volatile("s_waitcnt lgkmcnt(0)" ::: "memory")
; __device__ __forceinline__ float key2f(unsigned k) { const unsigned u = (k & 0x80000000u) ? (k & 0x7fffffffu) : ~k; return __uint_as_float(u); }
; __device__ __forceinline__ void peer_tile(const Args& A, LAS unsigned char* lds, int tile) {
;     ...
;             for (int k = 0; k < 16; ++k) { fv[k] = __expf(key2f(Lf[k] & ~255u) - f0); den += fv[k]; }
;             const float rden = 1.f / den;
;             LDS_WAIT();
; #pragma unroll
;             for (int k = 0; k < 16; ++k) { const unsigned code = 255u - (Lf[k] & 255u); const unsigned e = idx[code >> 4] * 128u + idx[16 + (code & 15u)];
;                 u32x2 sv; sv.x = e; sv.y = __float_as_uint(fv[k] * rden); SEL[(tl * 8 + h) * 16 + k] = sv; }
	v_exp_f32_e32 v34, v34
	v_mul_f32_e32 v35, 0x3fb8aa3b, v35
	v_sub_f32_e32 v36, v36, v0
	v_cndmask_b32_e32 v37, v38, v37, vcc
	v_and_b32_e32 v38, 0x7fffff00, v6
	v_bitop3_b32 v39, v6, s33, v6 bitop3:0xcf
	v_cmp_gt_i32_e32 vcc, 0, v6
	v_add_f32_e32 v29, v29, v31
	v_exp_f32_e32 v35, v35
	v_mul_f32_e32 v36, 0x3fb8aa3b, v36
	v_sub_f32_e32 v37, v37, v0
	v_cndmask_b32_e32 v38, v39, v38, vcc
	v_and_b32_e32 v39, 0x7fffff00, v18
	v_bitop3_b32 v40, v18, s33, v18 bitop3:0xcf
	v_cmp_gt_i32_e32 vcc, 0, v18
	v_add_f32_e32 v29, v29, v32
	v_exp_f32_e32 v36, v36
	v_mul_f32_e32 v37, 0x3fb8aa3b, v37
	v_sub_f32_e32 v38, v38, v0
	v_cndmask_b32_e32 v39, v40, v39, vcc
	v_and_b32_e32 v40, 0x7fffff00, v8
	v_bitop3_b32 v41, v8, s33, v8 bitop3:0xcf
	v_cmp_gt_i32_e32 vcc, 0, v8
	v_add_f32_e32 v29, v29, v33
	v_exp_f32_e32 v37, v37
	v_mul_f32_e32 v38, 0x3fb8aa3b, v38
	v_sub_f32_e32 v39, v39, v0
	v_cndmask_b32_e32 v40, v41, v40, vcc
	v_and_b32_e32 v41, 0x7fffff00, v10
	v_bitop3_b32 v42, v10, s33, v10 bitop3:0xcf
	v_cmp_gt_i32_e32 vcc, 0, v10
	v_add_f32_e32 v29, v29, v34
	v_exp_f32_e32 v38, v38
	v_mul_f32_e32 v39, 0x3fb8aa3b, v39
	v_sub_f32_e32 v40, v40, v0
	v_cndmask_b32_e32 v41, v42, v41, vcc
	v_add_f32_e32 v29, v29, v35
	v_exp_f32_e32 v39, v39
	v_mul_f32_e32 v40, 0x3fb8aa3b, v40
	v_sub_f32_e32 v0, v41, v0
	v_add_f32_e32 v29, v29, v36
	v_exp_f32_e32 v40, v40
	v_mul_f32_e32 v0, 0x3fb8aa3b, v0
	v_add_f32_e32 v29, v29, v37
	v_exp_f32_e32 v41, v0
	v_add_f32_e32 v0, v29, v38
	v_add_f32_e32 v0, v0, v39
	v_add_f32_e32 v0, v0, v40
	v_add_f32_e32 v0, v0, v41
	v_div_scale_f32 v29, s[0:1], v0, v0, 1.0
	v_rcp_f32_e32 v42, v29
	v_not_b32_e32 v21, v26
	v_not_b32_e32 v24, v25
	v_fma_f32 v43, -v29, v42, 1.0
	v_fmac_f32_e32 v42, v43, v42
	v_div_scale_f32 v43, vcc, 1.0, v0, 1.0
	v_mul_f32_e32 v44, v43, v42
	v_fma_f32 v45, -v29, v44, v43
	v_fmac_f32_e32 v44, v45, v42
	v_fma_f32 v29, -v29, v44, v43
	v_div_fmas_f32 v29, v29, v42, v44
	v_div_fixup_f32 v29, v29, v0, 1.0
	v_and_b32_e32 v0, 48, v19
	v_lshrrev_b32_e32 v19, 2, v21
	v_and_b32_e32 v19, 60, v19
	v_bitop3_b32 v21, v26, 15, v26 bitop3:0xc
	v_add_u32_e32 v19, v5, v19
	v_lshl_add_u32 v21, v21, 2, v5
	ds_read_b32 v19, v19
	ds_read_b32 v21, v21 offset:64
	v_lshlrev_b32_e32 v0, 3, v0
	v_add3_u32 v11, v13, v11, v0
	v_mul_f32_e32 v1, v1, v29
	v_not_b32_e32 v13, v2
	s_waitcnt lgkmcnt(0)
	v_lshl_add_u32 v0, v19, 7, v21
	ds_write_b64 v11, v[0:1]
	v_lshrrev_b32_e32 v0, 2, v24
	v_and_b32_e32 v0, 60, v0
	v_bitop3_b32 v1, v25, 15, v25 bitop3:0xc
	v_add_u32_e32 v0, v5, v0
	v_lshl_add_u32 v1, v1, 2, v5
	ds_read_b32 v0, v0
	ds_read_b32 v1, v1 offset:64
	v_cmp_eq_u32_e32 vcc, 0, v9
	s_waitcnt lgkmcnt(0)
	v_lshl_add_u32 v0, v0, 7, v1
	v_mul_f32_e32 v1, v16, v29
	ds_write_b64 v11, v[0:1] offset:8
	v_lshrrev_b32_e32 v0, 2, v13
	v_and_b32_e32 v0, 60, v0
	v_bitop3_b32 v1, v2, 15, v2 bitop3:0xc
	v_add_u32_e32 v0, v5, v0
	v_lshl_add_u32 v1, v1, 2, v5
	ds_read_b32 v0, v0
	ds_read_b32 v1, v1 offset:64
	v_not_b32_e32 v2, v4
	s_waitcnt lgkmcnt(0)
	v_lshl_add_u32 v0, v0, 7, v1
	v_mul_f32_e32 v1, v27, v29
	ds_write_b64 v11, v[0:1] offset:16
	v_lshrrev_b32_e32 v0, 2, v2
	v_and_b32_e32 v0, 60, v0
	v_bitop3_b32 v1, v4, 15, v4 bitop3:0xc
	v_add_u32_e32 v0, v5, v0
	v_lshl_add_u32 v1, v1, 2, v5
	ds_read_b32 v0, v0
	ds_read_b32 v1, v1 offset:64
	v_not_b32_e32 v2, v3
	v_mul_lo_u32 v4, v7, s36
	s_waitcnt lgkmcnt(0)
	v_lshl_add_u32 v0, v0, 7, v1
	v_mul_f32_e32 v1, v28, v29
	ds_write_b64 v11, v[0:1] offset:24
	v_lshrrev_b32_e32 v0, 2, v2
	v_and_b32_e32 v0, 60, v0
	v_bitop3_b32 v1, v3, 15, v3 bitop3:0xc
	v_add_u32_e32 v0, v5, v0
	v_lshl_add_u32 v1, v1, 2, v5
	ds_read_b32 v0, v0
	ds_read_b32 v1, v1 offset:64
	v_not_b32_e32 v2, v22
	s_waitcnt lgkmcnt(0)
	v_lshl_add_u32 v0, v0, 7, v1
	v_mul_f32_e32 v1, v30, v29
	ds_write_b64 v11, v[0:1] offset:32
	v_lshrrev_b32_e32 v0, 2, v2
	v_and_b32_e32 v0, 60, v0
	v_bitop3_b32 v1, v22, 15, v22 bitop3:0xc
	v_add_u32_e32 v0, v5, v0
	v_lshl_add_u32 v1, v1, 2, v5
	ds_read_b32 v0, v0
	ds_read_b32 v1, v1 offset:64
	v_not_b32_e32 v2, v15
	s_waitcnt lgkmcnt(0)
	v_lshl_add_u32 v0, v0, 7, v1
	v_mul_f32_e32 v1, v31, v29
	ds_write_b64 v11, v[0:1] offset:40
	v_lshrrev_b32_e32 v0, 2, v2
	v_and_b32_e32 v0, 60, v0
	v_bitop3_b32 v1, v15, 15, v15 bitop3:0xc
	v_add_u32_e32 v0, v5, v0
	v_lshl_add_u32 v1, v1, 2, v5
	ds_read_b32 v0, v0
	ds_read_b32 v1, v1 offset:64
	v_not_b32_e32 v2, v23
	s_waitcnt lgkmcnt(0)
	v_lshl_add_u32 v0, v0, 7, v1
	v_mul_f32_e32 v1, v32, v29
	ds_write_b64 v11, v[0:1] offset:48
	v_lshrrev_b32_e32 v0, 2, v2
	v_and_b32_e32 v0, 60, v0
	v_bitop3_b32 v1, v23, 15, v23 bitop3:0xc
	v_add_u32_e32 v0, v5, v0
	v_lshl_add_u32 v1, v1, 2, v5
	ds_read_b32 v0, v0
	ds_read_b32 v1, v1 offset:64
	v_not_b32_e32 v2, v12
	s_waitcnt lgkmcnt(0)
	v_lshl_add_u32 v0, v0, 7, v1
	v_mul_f32_e32 v1, v33, v29
	ds_write_b64 v11, v[0:1] offset:56
	v_lshrrev_b32_e32 v0, 2, v2
	v_and_b32_e32 v0, 60, v0
	v_bitop3_b32 v1, v12, 15, v12 bitop3:0xc
	v_add_u32_e32 v0, v5, v0
	v_lshl_add_u32 v1, v1, 2, v5
	ds_read_b32 v0, v0
	ds_read_b32 v1, v1 offset:64
	v_not_b32_e32 v2, v17
	s_waitcnt lgkmcnt(0)
	v_lshl_add_u32 v0, v0, 7, v1
	v_mul_f32_e32 v1, v34, v29
	ds_write_b64 v11, v[0:1] offset:64
	v_lshrrev_b32_e32 v0, 2, v2
	v_and_b32_e32 v0, 60, v0
	v_bitop3_b32 v1, v17, 15, v17 bitop3:0xc
	v_add_u32_e32 v0, v5, v0
	v_lshl_add_u32 v1, v1, 2, v5
	ds_read_b32 v0, v0
	ds_read_b32 v1, v1 offset:64
	v_not_b32_e32 v2, v14
	s_waitcnt lgkmcnt(0)
	v_lshl_add_u32 v0, v0, 7, v1
	v_mul_f32_e32 v1, v35, v29
	ds_write_b64 v11, v[0:1] offset:72
	v_lshrrev_b32_e32 v0, 2, v2
	v_and_b32_e32 v0, 60, v0
	v_bitop3_b32 v1, v14, 15, v14 bitop3:0xc
	v_add_u32_e32 v0, v5, v0
	v_lshl_add_u32 v1, v1, 2, v5
	ds_read_b32 v0, v0
	ds_read_b32 v1, v1 offset:64
	v_not_b32_e32 v2, v20
	s_waitcnt lgkmcnt(0)
; __device__ __forceinline__ unsigned pk2(float lo, float hi) { const f32x2 v = {lo, hi}; const bf16x2_t b = __builtin_convertvector(v, bf16x2_t); return __builtin_bit_cast(unsigned, b); }
; __device__ __forceinline__ float bflo(unsigned u) { return __uint_as_float(u << 16); }
; __device__ __forceinline__ float bfhi(unsigned u) { return __uint_as_float(u & 0xffff0000u); }
; __device__ __forceinline__ void peer_tile(const Args& A, LAS unsigned char* lds, int tile) {
;     ...
;             for (int k = 0; k < 16; ++k) { const unsigned code = 255u - (Lf[k] & 255u); const unsigned e = idx[code >> 4] * 128u + idx[16 + (code & 15u)];
;                 u32x2 sv; sv.x = e; sv.y = __float_as_uint(fv[k] * rden); SEL[(tl * 8 + h) * 16 + k] = sv; }
;         }
;     }
;     __syncthreads();
;     ...
;     for (int pass = 0; pass < 2; ++pass) {
;         const int tb = 8 * w + 4 * pass;
;         u32x4 xpa[4], xpb[4]; f32x2 oacc[4][8];
; #pragma unroll
;         for (int tk = 0; tk < 4; ++tk) { const size_t m = (size_t)tile * 64 + tb + tk;
;             { const u32x4 ra = *(const u32x4*)(A3 + m * 1024 + 16 * lane), rb = *(const u32x4*)(A3 + m * 1024 + 16 * lane + 8);
;               float xr_; { const f32x4 p0 = *(const f32x4*)(RSq + m * 16), p1 = *(const f32x4*)(RSq + m * 16 + 4), p2 = *(const f32x4*)(RSq + m * 16 + 8), p3 = *(const f32x4*)(RSq + m * 16 + 12);
;                 const f32x4 ps = (p0 + p1) + (p2 + p3); xr_ = rsqrtf(((ps[0] + ps[1]) + (ps[2] + ps[3])) * (1.f / 1024.f) + 1e-6f); }
;               const unsigned rr[8] = {ra.x, ra.y, ra.z, ra.w, rb.x, rb.y, rb.z, rb.w}; unsigned hh[8];
;               const float* sp = MOD + (int)(m >> 11) * 6144 + 3072 + 16 * lane;
; #pragma unroll
;               for (int q = 0; q < 8; ++q) { const f32x2 sh = *(const f32x2*)(sp + 2 * q); hh[q] = pk2(bflo(rr[q]) * xr_ + sh[0], bfhi(rr[q]) * xr_ + sh[1]); }
;               xpa[tk] = (u32x4){hh[0], hh[1], hh[2], hh[3]}; xpb[tk] = (u32x4){hh[4], hh[5], hh[6], hh[7]}; }
	v_lshl_add_u32 v0, v0, 7, v1
	v_mul_f32_e32 v1, v36, v29
	ds_write_b64 v11, v[0:1] offset:80
	v_lshrrev_b32_e32 v0, 2, v2
	v_and_b32_e32 v0, 60, v0
	v_bitop3_b32 v1, v20, 15, v20 bitop3:0xc
	v_add_u32_e32 v0, v5, v0
	v_lshl_add_u32 v1, v1, 2, v5
	ds_read_b32 v0, v0
	ds_read_b32 v1, v1 offset:64
	v_not_b32_e32 v2, v6
	s_waitcnt lgkmcnt(0)
	v_lshl_add_u32 v0, v0, 7, v1
	v_mul_f32_e32 v1, v37, v29
	ds_write_b64 v11, v[0:1] offset:88
	v_lshrrev_b32_e32 v0, 2, v2
	v_and_b32_e32 v0, 60, v0
	v_bitop3_b32 v1, v6, 15, v6 bitop3:0xc
	v_add_u32_e32 v0, v5, v0
	v_lshl_add_u32 v1, v1, 2, v5
	ds_read_b32 v0, v0
	ds_read_b32 v1, v1 offset:64
	v_not_b32_e32 v2, v18
	s_waitcnt lgkmcnt(0)
	v_lshl_add_u32 v0, v0, 7, v1
	v_mul_f32_e32 v1, v38, v29
	ds_write_b64 v11, v[0:1] offset:96
	v_lshrrev_b32_e32 v0, 2, v2
	v_and_b32_e32 v0, 60, v0
	v_bitop3_b32 v1, v18, 15, v18 bitop3:0xc
	v_add_u32_e32 v0, v5, v0
	v_lshl_add_u32 v1, v1, 2, v5
	ds_read_b32 v0, v0
	ds_read_b32 v1, v1 offset:64
	v_not_b32_e32 v2, v8
	s_waitcnt lgkmcnt(0)
	v_lshl_add_u32 v0, v0, 7, v1
	v_mul_f32_e32 v1, v39, v29
	ds_write_b64 v11, v[0:1] offset:104
	v_lshrrev_b32_e32 v0, 2, v2
	v_and_b32_e32 v0, 60, v0
	v_bitop3_b32 v1, v8, 15, v8 bitop3:0xc
	v_add_u32_e32 v0, v5, v0
	v_lshl_add_u32 v1, v1, 2, v5
	ds_read_b32 v0, v0
	ds_read_b32 v1, v1 offset:64
	v_not_b32_e32 v2, v10
	s_waitcnt lgkmcnt(0)
	v_lshl_add_u32 v0, v0, 7, v1
	v_mul_f32_e32 v1, v40, v29
	ds_write_b64 v11, v[0:1] offset:112
	v_lshrrev_b32_e32 v0, 2, v2
	v_and_b32_e32 v0, 60, v0
	v_bitop3_b32 v1, v10, 15, v10 bitop3:0xc
	v_add_u32_e32 v0, v5, v0
	v_lshl_add_u32 v1, v1, 2, v5
	ds_read_b32 v0, v0
	ds_read_b32 v1, v1 offset:64
	v_lshlrev_b32_e32 v5, 13, v7
	v_lshl_or_b32 v6, v9, 3, v5
	s_waitcnt lgkmcnt(0)
	v_lshl_add_u32 v0, v0, 7, v1
	v_mul_f32_e32 v1, v41, v29
	ds_write_b64 v11, v[0:1] offset:120
	s_waitcnt lgkmcnt(0)
	s_barrier
	s_mov_b64 exec, -1
	v_and_b32_e32 v240, 63, v214
	v_lshrrev_b32_e32 v242, 6, v214
	v_lshlrev_b32_e32 v240, 4, v240
	v_readfirstlane_b32 s16, v242
	v_lshlrev_b32_e32 v245, 1, v240
	v_lshlrev_b32_e32 v246, 2, v240
	v_lshrrev_b32_e32 v247, 4, v240
	v_and_b32_e32 v247, 48, v247
	v_mov_b32_e32 v244, 0
	v_mov_b32_e32 v243, 0x358637bd
	v_mov_b32_e32 v242, 0xbf3a00e3
	s_add_u32 s4, s50, 0x1000000
	s_addc_u32 s5, s51, 0
	s_add_u32 s6, s50, 0x2000000
	s_addc_u32 s7, s51, 0
	s_add_u32 s8, s50, 0x3000000
	s_addc_u32 s9, s51, 0
	s_add_u32 s52, s50, 0x3010000
	s_addc_u32 s53, s51, 0
	s_add_u32 s12, s50, 0xb000000
	s_addc_u32 s13, s51, 0
	s_add_u32 s14, s50, 0xd000000
	s_addc_u32 s15, s51, 0
	s_lshr_b32 s0, s2, 5
	s_mul_i32 s0, s0, 0x6000
	s_add_u32 s10, s50, s0
	s_addc_u32 s11, s51, 0
	s_add_u32 s80, s10, 0x4000
	s_addc_u32 s81, s11, 0
	s_add_u32 s82, s10, 0x6000
	s_addc_u32 s83, s11, 0
	s_mul_i32 s22, s16, 9920
	s_cmp_eq_u32 s16, 7
	s_cselect_b32 s22, 0x21000, s22
	s_mov_b32 s85, 0xfffffc00
	s_mov_b32 s72, 0x3e6d3388
	s_lshl_b32 s76, s16, 3
	s_lshl_b32 s0, s2, 6
	s_add_i32 s77, s0, s76
	global_load_dwordx4 v[192:195], v246, s[80:81] offset:0
	global_load_dwordx4 v[196:199], v246, s[80:81] offset:16
	global_load_dwordx4 v[200:203], v246, s[80:81] offset:32
	global_load_dwordx4 v[204:207], v246, s[80:81] offset:48
	s_add_i32 s0, s77, 0
	s_lshl_b32 s1, s0, 11
	s_add_u32 s78, s12, s1
	s_addc_u32 s79, s13, 0
	global_load_dwordx4 v[128:131], v245, s[78:79]
	global_load_dwordx4 v[132:135], v245, s[78:79] offset:16
	global_load_dwordx4 v[136:139], v245, s[78:79] offset:2048
	global_load_dwordx4 v[140:143], v245, s[78:79] offset:2064
	s_lshl_b32 s1, s0, 6
	s_add_u32 s78, s14, s1
	s_addc_u32 s79, s15, 0
	global_load_dwordx4 v[144:147], v244, s[78:79] offset:0
	global_load_dwordx4 v[148:151], v244, s[78:79] offset:16
	global_load_dwordx4 v[152:155], v244, s[78:79] offset:32
	global_load_dwordx4 v[156:159], v244, s[78:79] offset:48
	global_load_dwordx4 v[160:163], v244, s[78:79] offset:64
	global_load_dwordx4 v[164:167], v244, s[78:79] offset:80
	global_load_dwordx4 v[168:171], v244, s[78:79] offset:96
	global_load_dwordx4 v[172:175], v244, s[78:79] offset:112
	s_waitcnt vmcnt(0)
	v_pk_add_f32 v[144:145], v[144:145], v[148:149]
	v_pk_add_f32 v[146:147], v[146:147], v[150:151]
	v_pk_add_f32 v[152:153], v[152:153], v[156:157]
	v_pk_add_f32 v[154:155], v[154:155], v[158:159]
	v_pk_add_f32 v[144:145], v[144:145], v[152:153]
	v_pk_add_f32 v[146:147], v[146:147], v[154:155]
	v_add_f32_e32 v144, v144, v145
	v_add_f32_e32 v146, v146, v147
	v_add_f32_e32 v144, v144, v146
	v_fmamk_f32 v144, v144, 0x3a800000, v243
	v_rsq_f32_e32 v144, v144
	v_pk_add_f32 v[160:161], v[160:161], v[164:165]
	v_pk_add_f32 v[162:163], v[162:163], v[166:167]
	v_pk_add_f32 v[168:169], v[168:169], v[172:173]
	v_pk_add_f32 v[170:171], v[170:171], v[174:175]
	v_pk_add_f32 v[160:161], v[160:161], v[168:169]
	v_pk_add_f32 v[162:163], v[162:163], v[170:171]
	v_add_f32_e32 v160, v160, v161
	v_add_f32_e32 v162, v162, v163
	v_add_f32_e32 v160, v160, v162
	v_fmamk_f32 v160, v160, 0x3a800000, v243
	v_rsq_f32_e32 v160, v160
	v_lshlrev_b32_e32 v208, 16, v128
	v_and_b32_e32 v209, 0xffff0000, v128
	v_fma_f32 v208, v208, v144, v192
	v_fma_f32 v209, v209, v144, v193
	v_cvt_pk_bf16_f32 v210, v208, v209
	v_lshlrev_b32_e32 v0, 16, v210
	v_and_b32_e32 v1, 0xffff0000, v210
	v_lshlrev_b32_e32 v208, 16, v129
	v_and_b32_e32 v209, 0xffff0000, v129
	v_fma_f32 v208, v208, v144, v194
	v_fma_f32 v209, v209, v144, v195
	v_cvt_pk_bf16_f32 v210, v208, v209
	v_lshlrev_b32_e32 v2, 16, v210
	v_and_b32_e32 v3, 0xffff0000, v210
	v_lshlrev_b32_e32 v208, 16, v130
	v_and_b32_e32 v209, 0xffff0000, v130
	v_fma_f32 v208, v208, v144, v196
	v_fma_f32 v209, v209, v144, v197
	v_cvt_pk_bf16_f32 v210, v208, v209
; __device__ __forceinline__ unsigned pk2(float lo, float hi) { const f32x2 v = {lo, hi}; const bf16x2_t b = __builtin_convertvector(v, bf16x2_t); return __builtin_bit_cast(unsigned, b); }
; __device__ __forceinline__ float bflo(unsigned u) { return __uint_as_float(u << 16); }
; __device__ __forceinline__ float bfhi(unsigned u) { return __uint_as_float(u & 0xffff0000u); }
; __device__ __forceinline__ void peer_tile(const Args& A, LAS unsigned char* lds, int tile) {
;     ...
;         for (int tk = 0; tk < 4; ++tk) { const size_t m = (size_t)tile * 64 + tb + tk;
;             { const u32x4 ra = *(const u32x4*)(A3 + m * 1024 + 16 * lane), rb = *(const u32x4*)(A3 + m * 1024 + 16 * lane + 8);
;               float xr_; { const f32x4 p0 = *(const f32x4*)(RSq + m * 16), p1 = *(const f32x4*)(RSq + m * 16 + 4), p2 = *(const f32x4*)(RSq + m * 16 + 8), p3 = *(const f32x4*)(RSq + m * 16 + 12);
;                 const f32x4 ps = (p0 + p1) + (p2 + p3); xr_ = rsqrtf(((ps[0] + ps[1]) + (ps[2] + ps[3])) * (1.f / 1024.f) + 1e-6f); }
;               const unsigned rr[8] = {ra.x, ra.y, ra.z, ra.w, rb.x, rb.y, rb.z, rb.w}; unsigned hh[8];
;               const float* sp = MOD + (int)(m >> 11) * 6144 + 3072 + 16 * lane;
; #pragma unroll
;               for (int q = 0; q < 8; ++q) { const f32x2 sh = *(const f32x2*)(sp + 2 * q); hh[q] = pk2(bflo(rr[q]) * xr_ + sh[0], bfhi(rr[q]) * xr_ + sh[1]); }
;               xpa[tk] = (u32x4){hh[0], hh[1], hh[2], hh[3]}; xpb[tk] = (u32x4){hh[4], hh[5], hh[6], hh[7]}; }
	v_lshlrev_b32_e32 v4, 16, v210
	v_and_b32_e32 v5, 0xffff0000, v210
	v_lshlrev_b32_e32 v208, 16, v131
	v_and_b32_e32 v209, 0xffff0000, v131
	v_fma_f32 v208, v208, v144, v198
	v_fma_f32 v209, v209, v144, v199
	v_cvt_pk_bf16_f32 v210, v208, v209
	v_lshlrev_b32_e32 v6, 16, v210
	v_and_b32_e32 v7, 0xffff0000, v210
	v_lshlrev_b32_e32 v208, 16, v132
	v_and_b32_e32 v209, 0xffff0000, v132
	v_fma_f32 v208, v208, v144, v200
	v_fma_f32 v209, v209, v144, v201
	v_cvt_pk_bf16_f32 v210, v208, v209
	v_lshlrev_b32_e32 v8, 16, v210
	v_and_b32_e32 v9, 0xffff0000, v210
	v_lshlrev_b32_e32 v208, 16, v133
	v_and_b32_e32 v209, 0xffff0000, v133
	v_fma_f32 v208, v208, v144, v202
	v_fma_f32 v209, v209, v144, v203
	v_cvt_pk_bf16_f32 v210, v208, v209
	v_lshlrev_b32_e32 v10, 16, v210
	v_and_b32_e32 v11, 0xffff0000, v210
	v_lshlrev_b32_e32 v208, 16, v134
	v_and_b32_e32 v209, 0xffff0000, v134
	v_fma_f32 v208, v208, v144, v204
	v_fma_f32 v209, v209, v144, v205
	v_cvt_pk_bf16_f32 v210, v208, v209
	v_lshlrev_b32_e32 v12, 16, v210
	v_and_b32_e32 v13, 0xffff0000, v210
	v_lshlrev_b32_e32 v208, 16, v135
	v_and_b32_e32 v209, 0xffff0000, v135
	v_fma_f32 v208, v208, v144, v206
	v_fma_f32 v209, v209, v144, v207
	v_cvt_pk_bf16_f32 v210, v208, v209
	v_lshlrev_b32_e32 v14, 16, v210
	v_and_b32_e32 v15, 0xffff0000, v210
	v_lshlrev_b32_e32 v208, 16, v136
	v_and_b32_e32 v209, 0xffff0000, v136
	v_fma_f32 v208, v208, v160, v192
	v_fma_f32 v209, v209, v160, v193
	v_cvt_pk_bf16_f32 v210, v208, v209
	v_lshlrev_b32_e32 v16, 16, v210
	v_and_b32_e32 v17, 0xffff0000, v210
	v_lshlrev_b32_e32 v208, 16, v137
	v_and_b32_e32 v209, 0xffff0000, v137
	v_fma_f32 v208, v208, v160, v194
	v_fma_f32 v209, v209, v160, v195
	v_cvt_pk_bf16_f32 v210, v208, v209
	v_lshlrev_b32_e32 v18, 16, v210
	v_and_b32_e32 v19, 0xffff0000, v210
	v_lshlrev_b32_e32 v208, 16, v138
	v_and_b32_e32 v209, 0xffff0000, v138
	v_fma_f32 v208, v208, v160, v196
	v_fma_f32 v209, v209, v160, v197
	v_cvt_pk_bf16_f32 v210, v208, v209
	v_lshlrev_b32_e32 v20, 16, v210
	v_and_b32_e32 v21, 0xffff0000, v210
	v_lshlrev_b32_e32 v208, 16, v139
	v_and_b32_e32 v209, 0xffff0000, v139
	v_fma_f32 v208, v208, v160, v198
	v_fma_f32 v209, v209, v160, v199
	v_cvt_pk_bf16_f32 v210, v208, v209
	v_lshlrev_b32_e32 v22, 16, v210
	v_and_b32_e32 v23, 0xffff0000, v210
	v_lshlrev_b32_e32 v208, 16, v140
	v_and_b32_e32 v209, 0xffff0000, v140
	v_fma_f32 v208, v208, v160, v200
	v_fma_f32 v209, v209, v160, v201
	v_cvt_pk_bf16_f32 v210, v208, v209
	v_lshlrev_b32_e32 v24, 16, v210
	v_and_b32_e32 v25, 0xffff0000, v210
	v_lshlrev_b32_e32 v208, 16, v141
	v_and_b32_e32 v209, 0xffff0000, v141
	v_fma_f32 v208, v208, v160, v202
	v_fma_f32 v209, v209, v160, v203
	v_cvt_pk_bf16_f32 v210, v208, v209
	v_lshlrev_b32_e32 v26, 16, v210
	v_and_b32_e32 v27, 0xffff0000, v210
	v_lshlrev_b32_e32 v208, 16, v142
	v_and_b32_e32 v209, 0xffff0000, v142
	v_fma_f32 v208, v208, v160, v204
	v_fma_f32 v209, v209, v160, v205
	v_cvt_pk_bf16_f32 v210, v208, v209
	v_lshlrev_b32_e32 v28, 16, v210
	v_and_b32_e32 v29, 0xffff0000, v210
	v_lshlrev_b32_e32 v208, 16, v143
	v_and_b32_e32 v209, 0xffff0000, v143
	v_fma_f32 v208, v208, v160, v206
	v_fma_f32 v209, v209, v160, v207
	v_cvt_pk_bf16_f32 v210, v208, v209
	v_lshlrev_b32_e32 v30, 16, v210
	v_and_b32_e32 v31, 0xffff0000, v210
	s_add_i32 s0, s77, 2
	s_lshl_b32 s1, s0, 11
	s_add_u32 s78, s12, s1
	s_addc_u32 s79, s13, 0
	global_load_dwordx4 v[128:131], v245, s[78:79]
	global_load_dwordx4 v[132:135], v245, s[78:79] offset:16
	global_load_dwordx4 v[136:139], v245, s[78:79] offset:2048
	global_load_dwordx4 v[140:143], v245, s[78:79] offset:2064
	s_lshl_b32 s1, s0, 6
	s_add_u32 s78, s14, s1
	s_addc_u32 s79, s15, 0
	global_load_dwordx4 v[144:147], v244, s[78:79] offset:0
	global_load_dwordx4 v[148:151], v244, s[78:79] offset:16
	global_load_dwordx4 v[152:155], v244, s[78:79] offset:32
	global_load_dwordx4 v[156:159], v244, s[78:79] offset:48
	global_load_dwordx4 v[160:163], v244, s[78:79] offset:64
	global_load_dwordx4 v[164:167], v244, s[78:79] offset:80
	global_load_dwordx4 v[168:171], v244, s[78:79] offset:96
	global_load_dwordx4 v[172:175], v244, s[78:79] offset:112
	s_waitcnt vmcnt(0)
	v_pk_add_f32 v[144:145], v[144:145], v[148:149]
	v_pk_add_f32 v[146:147], v[146:147], v[150:151]
	v_pk_add_f32 v[152:153], v[152:153], v[156:157]
	v_pk_add_f32 v[154:155], v[154:155], v[158:159]
	v_pk_add_f32 v[144:145], v[144:145], v[152:153]
	v_pk_add_f32 v[146:147], v[146:147], v[154:155]
	v_add_f32_e32 v144, v144, v145
	v_add_f32_e32 v146, v146, v147
	v_add_f32_e32 v144, v144, v146
	v_fmamk_f32 v144, v144, 0x3a800000, v243
	v_rsq_f32_e32 v144, v144
	v_pk_add_f32 v[160:161], v[160:161], v[164:165]
	v_pk_add_f32 v[162:163], v[162:163], v[166:167]
	v_pk_add_f32 v[168:169], v[168:169], v[172:173]
	v_pk_add_f32 v[170:171], v[170:171], v[174:175]
	v_pk_add_f32 v[160:161], v[160:161], v[168:169]
	v_pk_add_f32 v[162:163], v[162:163], v[170:171]
	v_add_f32_e32 v160, v160, v161
	v_add_f32_e32 v162, v162, v163
	v_add_f32_e32 v160, v160, v162
	v_fmamk_f32 v160, v160, 0x3a800000, v243
	v_rsq_f32_e32 v160, v160
	v_lshlrev_b32_e32 v208, 16, v128
	v_and_b32_e32 v209, 0xffff0000, v128
	v_fma_f32 v208, v208, v144, v192
	v_fma_f32 v209, v209, v144, v193
	v_cvt_pk_bf16_f32 v210, v208, v209
	v_lshlrev_b32_e32 v32, 16, v210
	v_and_b32_e32 v33, 0xffff0000, v210
	v_lshlrev_b32_e32 v208, 16, v129
	v_and_b32_e32 v209, 0xffff0000, v129
	v_fma_f32 v208, v208, v144, v194
	v_fma_f32 v209, v209, v144, v195
	v_cvt_pk_bf16_f32 v210, v208, v209
	v_lshlrev_b32_e32 v34, 16, v210
	v_and_b32_e32 v35, 0xffff0000, v210
	v_lshlrev_b32_e32 v208, 16, v130
	v_and_b32_e32 v209, 0xffff0000, v130
	v_fma_f32 v208, v208, v144, v196
; __device__ __forceinline__ unsigned pk2(float lo, float hi) { const f32x2 v = {lo, hi}; const bf16x2_t b = __builtin_convertvector(v, bf16x2_t); return __builtin_bit_cast(unsigned, b); }
; __device__ __forceinline__ float bflo(unsigned u) { return __uint_as_float(u << 16); }
; __device__ __forceinline__ float bfhi(unsigned u) { return __uint_as_float(u & 0xffff0000u); }
; __device__ __forceinline__ void peer_tile(const Args& A, LAS unsigned char* lds, int tile) {
;     ...
;         for (int tk = 0; tk < 4; ++tk) { const size_t m = (size_t)tile * 64 + tb + tk;
;             { const u32x4 ra = *(const u32x4*)(A3 + m * 1024 + 16 * lane), rb = *(const u32x4*)(A3 + m * 1024 + 16 * lane + 8);
;               float xr_; { const f32x4 p0 = *(const f32x4*)(RSq + m * 16), p1 = *(const f32x4*)(RSq + m * 16 + 4), p2 = *(const f32x4*)(RSq + m * 16 + 8), p3 = *(const f32x4*)(RSq + m * 16 + 12);
;                 const f32x4 ps = (p0 + p1) + (p2 + p3); xr_ = rsqrtf(((ps[0] + ps[1]) + (ps[2] + ps[3])) * (1.f / 1024.f) + 1e-6f); }
;               const unsigned rr[8] = {ra.x, ra.y, ra.z, ra.w, rb.x, rb.y, rb.z, rb.w}; unsigned hh[8];
;               const float* sp = MOD + (int)(m >> 11) * 6144 + 3072 + 16 * lane;
; #pragma unroll
;               for (int q = 0; q < 8; ++q) { const f32x2 sh = *(const f32x2*)(sp + 2 * q); hh[q] = pk2(bflo(rr[q]) * xr_ + sh[0], bfhi(rr[q]) * xr_ + sh[1]); }
;               xpa[tk] = (u32x4){hh[0], hh[1], hh[2], hh[3]}; xpb[tk] = (u32x4){hh[4], hh[5], hh[6], hh[7]}; }
	v_fma_f32 v209, v209, v144, v197
	v_cvt_pk_bf16_f32 v210, v208, v209
	v_lshlrev_b32_e32 v36, 16, v210
	v_and_b32_e32 v37, 0xffff0000, v210
	v_lshlrev_b32_e32 v208, 16, v131
	v_and_b32_e32 v209, 0xffff0000, v131
	v_fma_f32 v208, v208, v144, v198
	v_fma_f32 v209, v209, v144, v199
	v_cvt_pk_bf16_f32 v210, v208, v209
	v_lshlrev_b32_e32 v38, 16, v210
	v_and_b32_e32 v39, 0xffff0000, v210
	v_lshlrev_b32_e32 v208, 16, v132
	v_and_b32_e32 v209, 0xffff0000, v132
	v_fma_f32 v208, v208, v144, v200
	v_fma_f32 v209, v209, v144, v201
	v_cvt_pk_bf16_f32 v210, v208, v209
	v_lshlrev_b32_e32 v40, 16, v210
	v_and_b32_e32 v41, 0xffff0000, v210
	v_lshlrev_b32_e32 v208, 16, v133
	v_and_b32_e32 v209, 0xffff0000, v133
	v_fma_f32 v208, v208, v144, v202
	v_fma_f32 v209, v209, v144, v203
	v_cvt_pk_bf16_f32 v210, v208, v209
	v_lshlrev_b32_e32 v42, 16, v210
	v_and_b32_e32 v43, 0xffff0000, v210
	v_lshlrev_b32_e32 v208, 16, v134
	v_and_b32_e32 v209, 0xffff0000, v134
	v_fma_f32 v208, v208, v144, v204
	v_fma_f32 v209, v209, v144, v205
	v_cvt_pk_bf16_f32 v210, v208, v209
	v_lshlrev_b32_e32 v44, 16, v210
	v_and_b32_e32 v45, 0xffff0000, v210
	v_lshlrev_b32_e32 v208, 16, v135
	v_and_b32_e32 v209, 0xffff0000, v135
	v_fma_f32 v208, v208, v144, v206
	v_fma_f32 v209, v209, v144, v207
	v_cvt_pk_bf16_f32 v210, v208, v209
	v_lshlrev_b32_e32 v46, 16, v210
	v_and_b32_e32 v47, 0xffff0000, v210
	v_lshlrev_b32_e32 v208, 16, v136
	v_and_b32_e32 v209, 0xffff0000, v136
	v_fma_f32 v208, v208, v160, v192
	v_fma_f32 v209, v209, v160, v193
	v_cvt_pk_bf16_f32 v210, v208, v209
	v_lshlrev_b32_e32 v48, 16, v210
	v_and_b32_e32 v49, 0xffff0000, v210
	v_lshlrev_b32_e32 v208, 16, v137
	v_and_b32_e32 v209, 0xffff0000, v137
	v_fma_f32 v208, v208, v160, v194
	v_fma_f32 v209, v209, v160, v195
	v_cvt_pk_bf16_f32 v210, v208, v209
	v_lshlrev_b32_e32 v50, 16, v210
	v_and_b32_e32 v51, 0xffff0000, v210
	v_lshlrev_b32_e32 v208, 16, v138
	v_and_b32_e32 v209, 0xffff0000, v138
	v_fma_f32 v208, v208, v160, v196
	v_fma_f32 v209, v209, v160, v197
	v_cvt_pk_bf16_f32 v210, v208, v209
	v_lshlrev_b32_e32 v52, 16, v210
	v_and_b32_e32 v53, 0xffff0000, v210
	v_lshlrev_b32_e32 v208, 16, v139
	v_and_b32_e32 v209, 0xffff0000, v139
	v_fma_f32 v208, v208, v160, v198
	v_fma_f32 v209, v209, v160, v199
	v_cvt_pk_bf16_f32 v210, v208, v209
	v_lshlrev_b32_e32 v54, 16, v210
	v_and_b32_e32 v55, 0xffff0000, v210
	v_lshlrev_b32_e32 v208, 16, v140
	v_and_b32_e32 v209, 0xffff0000, v140
	v_fma_f32 v208, v208, v160, v200
	v_fma_f32 v209, v209, v160, v201
	v_cvt_pk_bf16_f32 v210, v208, v209
	v_lshlrev_b32_e32 v56, 16, v210
	v_and_b32_e32 v57, 0xffff0000, v210
	v_lshlrev_b32_e32 v208, 16, v141
	v_and_b32_e32 v209, 0xffff0000, v141
	v_fma_f32 v208, v208, v160, v202
	v_fma_f32 v209, v209, v160, v203
	v_cvt_pk_bf16_f32 v210, v208, v209
	v_lshlrev_b32_e32 v58, 16, v210
	v_and_b32_e32 v59, 0xffff0000, v210
	v_lshlrev_b32_e32 v208, 16, v142
	v_and_b32_e32 v209, 0xffff0000, v142
	v_fma_f32 v208, v208, v160, v204
	v_fma_f32 v209, v209, v160, v205
	v_cvt_pk_bf16_f32 v210, v208, v209
	v_lshlrev_b32_e32 v60, 16, v210
	v_and_b32_e32 v61, 0xffff0000, v210
	v_lshlrev_b32_e32 v208, 16, v143
	v_and_b32_e32 v209, 0xffff0000, v143
	v_fma_f32 v208, v208, v160, v206
	v_fma_f32 v209, v209, v160, v207
	v_cvt_pk_bf16_f32 v210, v208, v209
	v_lshlrev_b32_e32 v62, 16, v210
	v_and_b32_e32 v63, 0xffff0000, v210
	s_add_i32 s0, s77, 4
	s_lshl_b32 s1, s0, 11
	s_add_u32 s78, s12, s1
	s_addc_u32 s79, s13, 0
	global_load_dwordx4 v[128:131], v245, s[78:79]
	global_load_dwordx4 v[132:135], v245, s[78:79] offset:16
	global_load_dwordx4 v[136:139], v245, s[78:79] offset:2048
	global_load_dwordx4 v[140:143], v245, s[78:79] offset:2064
	s_lshl_b32 s1, s0, 6
	s_add_u32 s78, s14, s1
	s_addc_u32 s79, s15, 0
	global_load_dwordx4 v[144:147], v244, s[78:79] offset:0
	global_load_dwordx4 v[148:151], v244, s[78:79] offset:16
	global_load_dwordx4 v[152:155], v244, s[78:79] offset:32
	global_load_dwordx4 v[156:159], v244, s[78:79] offset:48
	global_load_dwordx4 v[160:163], v244, s[78:79] offset:64
	global_load_dwordx4 v[164:167], v244, s[78:79] offset:80
	global_load_dwordx4 v[168:171], v244, s[78:79] offset:96
	global_load_dwordx4 v[172:175], v244, s[78:79] offset:112
	s_waitcnt vmcnt(0)
	v_pk_add_f32 v[144:145], v[144:145], v[148:149]
	v_pk_add_f32 v[146:147], v[146:147], v[150:151]
	v_pk_add_f32 v[152:153], v[152:153], v[156:157]
	v_pk_add_f32 v[154:155], v[154:155], v[158:159]
	v_pk_add_f32 v[144:145], v[144:145], v[152:153]
	v_pk_add_f32 v[146:147], v[146:147], v[154:155]
	v_add_f32_e32 v144, v144, v145
	v_add_f32_e32 v146, v146, v147
	v_add_f32_e32 v144, v144, v146
	v_fmamk_f32 v144, v144, 0x3a800000, v243
	v_rsq_f32_e32 v144, v144
	v_pk_add_f32 v[160:161], v[160:161], v[164:165]
	v_pk_add_f32 v[162:163], v[162:163], v[166:167]
	v_pk_add_f32 v[168:169], v[168:169], v[172:173]
	v_pk_add_f32 v[170:171], v[170:171], v[174:175]
	v_pk_add_f32 v[160:161], v[160:161], v[168:169]
	v_pk_add_f32 v[162:163], v[162:163], v[170:171]
	v_add_f32_e32 v160, v160, v161
	v_add_f32_e32 v162, v162, v163
	v_add_f32_e32 v160, v160, v162
	v_fmamk_f32 v160, v160, 0x3a800000, v243
	v_rsq_f32_e32 v160, v160
	v_lshlrev_b32_e32 v208, 16, v128
	v_and_b32_e32 v209, 0xffff0000, v128
	v_fma_f32 v208, v208, v144, v192
	v_fma_f32 v209, v209, v144, v193
	v_cvt_pk_bf16_f32 v210, v208, v209
	v_lshlrev_b32_e32 v64, 16, v210
	v_and_b32_e32 v65, 0xffff0000, v210
	v_lshlrev_b32_e32 v208, 16, v129
	v_and_b32_e32 v209, 0xffff0000, v129
	v_fma_f32 v208, v208, v144, v194
	v_fma_f32 v209, v209, v144, v195
	v_cvt_pk_bf16_f32 v210, v208, v209
	v_lshlrev_b32_e32 v66, 16, v210
	v_and_b32_e32 v67, 0xffff0000, v210
	v_lshlrev_b32_e32 v208, 16, v130
; __device__ __forceinline__ unsigned pk2(float lo, float hi) { const f32x2 v = {lo, hi}; const bf16x2_t b = __builtin_convertvector(v, bf16x2_t); return __builtin_bit_cast(unsigned, b); }
; __device__ __forceinline__ float bflo(unsigned u) { return __uint_as_float(u << 16); }
; __device__ __forceinline__ float bfhi(unsigned u) { return __uint_as_float(u & 0xffff0000u); }
; __device__ __forceinline__ void peer_tile(const Args& A, LAS unsigned char* lds, int tile) {
;     ...
;         for (int tk = 0; tk < 4; ++tk) { const size_t m = (size_t)tile * 64 + tb + tk;
;             { const u32x4 ra = *(const u32x4*)(A3 + m * 1024 + 16 * lane), rb = *(const u32x4*)(A3 + m * 1024 + 16 * lane + 8);
;               float xr_; { const f32x4 p0 = *(const f32x4*)(RSq + m * 16), p1 = *(const f32x4*)(RSq + m * 16 + 4), p2 = *(const f32x4*)(RSq + m * 16 + 8), p3 = *(const f32x4*)(RSq + m * 16 + 12);
;                 const f32x4 ps = (p0 + p1) + (p2 + p3); xr_ = rsqrtf(((ps[0] + ps[1]) + (ps[2] + ps[3])) * (1.f / 1024.f) + 1e-6f); }
;               const unsigned rr[8] = {ra.x, ra.y, ra.z, ra.w, rb.x, rb.y, rb.z, rb.w}; unsigned hh[8];
;               const float* sp = MOD + (int)(m >> 11) * 6144 + 3072 + 16 * lane;
; #pragma unroll
;               for (int q = 0; q < 8; ++q) { const f32x2 sh = *(const f32x2*)(sp + 2 * q); hh[q] = pk2(bflo(rr[q]) * xr_ + sh[0], bfhi(rr[q]) * xr_ + sh[1]); }
;               xpa[tk] = (u32x4){hh[0], hh[1], hh[2], hh[3]}; xpb[tk] = (u32x4){hh[4], hh[5], hh[6], hh[7]}; }
	v_and_b32_e32 v209, 0xffff0000, v130
	v_fma_f32 v208, v208, v144, v196
	v_fma_f32 v209, v209, v144, v197
	v_cvt_pk_bf16_f32 v210, v208, v209
	v_lshlrev_b32_e32 v68, 16, v210
	v_and_b32_e32 v69, 0xffff0000, v210
	v_lshlrev_b32_e32 v208, 16, v131
	v_and_b32_e32 v209, 0xffff0000, v131
	v_fma_f32 v208, v208, v144, v198
	v_fma_f32 v209, v209, v144, v199
	v_cvt_pk_bf16_f32 v210, v208, v209
	v_lshlrev_b32_e32 v70, 16, v210
	v_and_b32_e32 v71, 0xffff0000, v210
	v_lshlrev_b32_e32 v208, 16, v132
	v_and_b32_e32 v209, 0xffff0000, v132
	v_fma_f32 v208, v208, v144, v200
	v_fma_f32 v209, v209, v144, v201
	v_cvt_pk_bf16_f32 v210, v208, v209
	v_lshlrev_b32_e32 v72, 16, v210
	v_and_b32_e32 v73, 0xffff0000, v210
	v_lshlrev_b32_e32 v208, 16, v133
	v_and_b32_e32 v209, 0xffff0000, v133
	v_fma_f32 v208, v208, v144, v202
	v_fma_f32 v209, v209, v144, v203
	v_cvt_pk_bf16_f32 v210, v208, v209
	v_lshlrev_b32_e32 v74, 16, v210
	v_and_b32_e32 v75, 0xffff0000, v210
	v_lshlrev_b32_e32 v208, 16, v134
	v_and_b32_e32 v209, 0xffff0000, v134
	v_fma_f32 v208, v208, v144, v204
	v_fma_f32 v209, v209, v144, v205
	v_cvt_pk_bf16_f32 v210, v208, v209
	v_lshlrev_b32_e32 v76, 16, v210
	v_and_b32_e32 v77, 0xffff0000, v210
	v_lshlrev_b32_e32 v208, 16, v135
	v_and_b32_e32 v209, 0xffff0000, v135
	v_fma_f32 v208, v208, v144, v206
	v_fma_f32 v209, v209, v144, v207
	v_cvt_pk_bf16_f32 v210, v208, v209
	v_lshlrev_b32_e32 v78, 16, v210
	v_and_b32_e32 v79, 0xffff0000, v210
	v_lshlrev_b32_e32 v208, 16, v136
	v_and_b32_e32 v209, 0xffff0000, v136
	v_fma_f32 v208, v208, v160, v192
	v_fma_f32 v209, v209, v160, v193
	v_cvt_pk_bf16_f32 v210, v208, v209
	v_lshlrev_b32_e32 v80, 16, v210
	v_and_b32_e32 v81, 0xffff0000, v210
	v_lshlrev_b32_e32 v208, 16, v137
	v_and_b32_e32 v209, 0xffff0000, v137
	v_fma_f32 v208, v208, v160, v194
	v_fma_f32 v209, v209, v160, v195
	v_cvt_pk_bf16_f32 v210, v208, v209
	v_lshlrev_b32_e32 v82, 16, v210
	v_and_b32_e32 v83, 0xffff0000, v210
	v_lshlrev_b32_e32 v208, 16, v138
	v_and_b32_e32 v209, 0xffff0000, v138
	v_fma_f32 v208, v208, v160, v196
	v_fma_f32 v209, v209, v160, v197
	v_cvt_pk_bf16_f32 v210, v208, v209
	v_lshlrev_b32_e32 v84, 16, v210
	v_and_b32_e32 v85, 0xffff0000, v210
	v_lshlrev_b32_e32 v208, 16, v139
	v_and_b32_e32 v209, 0xffff0000, v139
	v_fma_f32 v208, v208, v160, v198
	v_fma_f32 v209, v209, v160, v199
	v_cvt_pk_bf16_f32 v210, v208, v209
	v_lshlrev_b32_e32 v86, 16, v210
	v_and_b32_e32 v87, 0xffff0000, v210
	v_lshlrev_b32_e32 v208, 16, v140
	v_and_b32_e32 v209, 0xffff0000, v140
	v_fma_f32 v208, v208, v160, v200
	v_fma_f32 v209, v209, v160, v201
	v_cvt_pk_bf16_f32 v210, v208, v209
	v_lshlrev_b32_e32 v88, 16, v210
	v_and_b32_e32 v89, 0xffff0000, v210
	v_lshlrev_b32_e32 v208, 16, v141
	v_and_b32_e32 v209, 0xffff0000, v141
	v_fma_f32 v208, v208, v160, v202
	v_fma_f32 v209, v209, v160, v203
	v_cvt_pk_bf16_f32 v210, v208, v209
	v_lshlrev_b32_e32 v90, 16, v210
	v_and_b32_e32 v91, 0xffff0000, v210
	v_lshlrev_b32_e32 v208, 16, v142
	v_and_b32_e32 v209, 0xffff0000, v142
	v_fma_f32 v208, v208, v160, v204
	v_fma_f32 v209, v209, v160, v205
	v_cvt_pk_bf16_f32 v210, v208, v209
	v_lshlrev_b32_e32 v92, 16, v210
	v_and_b32_e32 v93, 0xffff0000, v210
	v_lshlrev_b32_e32 v208, 16, v143
	v_and_b32_e32 v209, 0xffff0000, v143
	v_fma_f32 v208, v208, v160, v206
	v_fma_f32 v209, v209, v160, v207
	v_cvt_pk_bf16_f32 v210, v208, v209
	v_lshlrev_b32_e32 v94, 16, v210
	v_and_b32_e32 v95, 0xffff0000, v210
	s_add_i32 s0, s77, 6
	s_lshl_b32 s1, s0, 11
	s_add_u32 s78, s12, s1
	s_addc_u32 s79, s13, 0
	global_load_dwordx4 v[128:131], v245, s[78:79]
	global_load_dwordx4 v[132:135], v245, s[78:79] offset:16
	global_load_dwordx4 v[136:139], v245, s[78:79] offset:2048
	global_load_dwordx4 v[140:143], v245, s[78:79] offset:2064
	s_lshl_b32 s1, s0, 6
	s_add_u32 s78, s14, s1
	s_addc_u32 s79, s15, 0
	global_load_dwordx4 v[144:147], v244, s[78:79] offset:0
	global_load_dwordx4 v[148:151], v244, s[78:79] offset:16
	global_load_dwordx4 v[152:155], v244, s[78:79] offset:32
	global_load_dwordx4 v[156:159], v244, s[78:79] offset:48
	global_load_dwordx4 v[160:163], v244, s[78:79] offset:64
	global_load_dwordx4 v[164:167], v244, s[78:79] offset:80
	global_load_dwordx4 v[168:171], v244, s[78:79] offset:96
	global_load_dwordx4 v[172:175], v244, s[78:79] offset:112
	s_waitcnt vmcnt(0)
; __device__ __forceinline__ unsigned pk2(float lo, float hi) { const f32x2 v = {lo, hi}; const bf16x2_t b = __builtin_convertvector(v, bf16x2_t); return __builtin_bit_cast(unsigned, b); }
; __device__ __forceinline__ float bflo(unsigned u) { return __uint_as_float(u << 16); }
; __device__ __forceinline__ float bfhi(unsigned u) { return __uint_as_float(u & 0xffff0000u); }
; __device__ __forceinline__ void peer_tile(const Args& A, LAS unsigned char* lds, int tile) {
;     ...
;     for (int ti = 0; ti < 8; ++ti) {
;         const int tl = 8 * w + ti;
;         const u32x2 e0 = SEL[tl * 128 + lane], e1 = SEL[tl * 128 + 64 + lane];
;     ...
;         for (int tk = 0; tk < 4; ++tk) { const size_t m = (size_t)tile * 64 + tb + tk;
;             { const u32x4 ra = *(const u32x4*)(A3 + m * 1024 + 16 * lane), rb = *(const u32x4*)(A3 + m * 1024 + 16 * lane + 8);
;               float xr_; { const f32x4 p0 = *(const f32x4*)(RSq + m * 16), p1 = *(const f32x4*)(RSq + m * 16 + 4), p2 = *(const f32x4*)(RSq + m * 16 + 8), p3 = *(const f32x4*)(RSq + m * 16 + 12);
;                 const f32x4 ps = (p0 + p1) + (p2 + p3); xr_ = rsqrtf(((ps[0] + ps[1]) + (ps[2] + ps[3])) * (1.f / 1024.f) + 1e-6f); }
;               const unsigned rr[8] = {ra.x, ra.y, ra.z, ra.w, rb.x, rb.y, rb.z, rb.w}; unsigned hh[8];
;               const float* sp = MOD + (int)(m >> 11) * 6144 + 3072 + 16 * lane;
; #pragma unroll
;               for (int q = 0; q < 8; ++q) { const f32x2 sh = *(const f32x2*)(sp + 2 * q); hh[q] = pk2(bflo(rr[q]) * xr_ + sh[0], bfhi(rr[q]) * xr_ + sh[1]); }
;               xpa[tk] = (u32x4){hh[0], hh[1], hh[2], hh[3]}; xpb[tk] = (u32x4){hh[4], hh[5], hh[6], hh[7]}; }
	v_pk_add_f32 v[144:145], v[144:145], v[148:149]
	v_pk_add_f32 v[146:147], v[146:147], v[150:151]
	v_pk_add_f32 v[152:153], v[152:153], v[156:157]
	v_pk_add_f32 v[154:155], v[154:155], v[158:159]
	v_pk_add_f32 v[144:145], v[144:145], v[152:153]
	v_pk_add_f32 v[146:147], v[146:147], v[154:155]
	v_add_f32_e32 v144, v144, v145
	v_add_f32_e32 v146, v146, v147
	v_add_f32_e32 v144, v144, v146
	v_fmamk_f32 v144, v144, 0x3a800000, v243
	v_rsq_f32_e32 v144, v144
	v_pk_add_f32 v[160:161], v[160:161], v[164:165]
	v_pk_add_f32 v[162:163], v[162:163], v[166:167]
	v_pk_add_f32 v[168:169], v[168:169], v[172:173]
	v_pk_add_f32 v[170:171], v[170:171], v[174:175]
	v_pk_add_f32 v[160:161], v[160:161], v[168:169]
	v_pk_add_f32 v[162:163], v[162:163], v[170:171]
	v_add_f32_e32 v160, v160, v161
	v_add_f32_e32 v162, v162, v163
	v_add_f32_e32 v160, v160, v162
	v_fmamk_f32 v160, v160, 0x3a800000, v243
	v_rsq_f32_e32 v160, v160
	v_lshlrev_b32_e32 v208, 16, v128
	v_and_b32_e32 v209, 0xffff0000, v128
	v_fma_f32 v208, v208, v144, v192
	v_fma_f32 v209, v209, v144, v193
	v_cvt_pk_bf16_f32 v210, v208, v209
	v_lshlrev_b32_e32 v96, 16, v210
	v_and_b32_e32 v97, 0xffff0000, v210
	v_lshlrev_b32_e32 v208, 16, v129
	v_and_b32_e32 v209, 0xffff0000, v129
	v_fma_f32 v208, v208, v144, v194
	v_fma_f32 v209, v209, v144, v195
	v_cvt_pk_bf16_f32 v210, v208, v209
	v_lshlrev_b32_e32 v98, 16, v210
	v_and_b32_e32 v99, 0xffff0000, v210
	v_lshlrev_b32_e32 v208, 16, v130
	v_and_b32_e32 v209, 0xffff0000, v130
	v_fma_f32 v208, v208, v144, v196
	v_fma_f32 v209, v209, v144, v197
	v_cvt_pk_bf16_f32 v210, v208, v209
	v_lshlrev_b32_e32 v100, 16, v210
	v_and_b32_e32 v101, 0xffff0000, v210
	v_lshlrev_b32_e32 v208, 16, v131
	v_and_b32_e32 v209, 0xffff0000, v131
	v_fma_f32 v208, v208, v144, v198
	v_fma_f32 v209, v209, v144, v199
	v_cvt_pk_bf16_f32 v210, v208, v209
	v_lshlrev_b32_e32 v102, 16, v210
	v_and_b32_e32 v103, 0xffff0000, v210
	v_lshlrev_b32_e32 v208, 16, v132
	v_and_b32_e32 v209, 0xffff0000, v132
	v_fma_f32 v208, v208, v144, v200
	v_fma_f32 v209, v209, v144, v201
	v_cvt_pk_bf16_f32 v210, v208, v209
	v_lshlrev_b32_e32 v104, 16, v210
	v_and_b32_e32 v105, 0xffff0000, v210
	v_lshlrev_b32_e32 v208, 16, v133
	v_and_b32_e32 v209, 0xffff0000, v133
	v_fma_f32 v208, v208, v144, v202
	v_fma_f32 v209, v209, v144, v203
	v_cvt_pk_bf16_f32 v210, v208, v209
	v_lshlrev_b32_e32 v106, 16, v210
	v_and_b32_e32 v107, 0xffff0000, v210
	v_lshlrev_b32_e32 v208, 16, v134
	v_and_b32_e32 v209, 0xffff0000, v134
	v_fma_f32 v208, v208, v144, v204
	v_fma_f32 v209, v209, v144, v205
	v_cvt_pk_bf16_f32 v210, v208, v209
	v_lshlrev_b32_e32 v108, 16, v210
	v_and_b32_e32 v109, 0xffff0000, v210
	v_lshlrev_b32_e32 v208, 16, v135
	v_and_b32_e32 v209, 0xffff0000, v135
	v_fma_f32 v208, v208, v144, v206
	v_fma_f32 v209, v209, v144, v207
	v_cvt_pk_bf16_f32 v210, v208, v209
	v_lshlrev_b32_e32 v110, 16, v210
	v_and_b32_e32 v111, 0xffff0000, v210
	v_lshlrev_b32_e32 v208, 16, v136
	v_and_b32_e32 v209, 0xffff0000, v136
	v_fma_f32 v208, v208, v160, v192
	v_fma_f32 v209, v209, v160, v193
	v_cvt_pk_bf16_f32 v210, v208, v209
	v_lshlrev_b32_e32 v112, 16, v210
	v_and_b32_e32 v113, 0xffff0000, v210
	v_lshlrev_b32_e32 v208, 16, v137
	v_and_b32_e32 v209, 0xffff0000, v137
	v_fma_f32 v208, v208, v160, v194
	v_fma_f32 v209, v209, v160, v195
	v_cvt_pk_bf16_f32 v210, v208, v209
	v_lshlrev_b32_e32 v114, 16, v210
	v_and_b32_e32 v115, 0xffff0000, v210
	v_lshlrev_b32_e32 v208, 16, v138
	v_and_b32_e32 v209, 0xffff0000, v138
	v_fma_f32 v208, v208, v160, v196
	v_fma_f32 v209, v209, v160, v197
	v_cvt_pk_bf16_f32 v210, v208, v209
	v_lshlrev_b32_e32 v116, 16, v210
	v_and_b32_e32 v117, 0xffff0000, v210
	v_lshlrev_b32_e32 v208, 16, v139
	v_and_b32_e32 v209, 0xffff0000, v139
	v_fma_f32 v208, v208, v160, v198
	v_fma_f32 v209, v209, v160, v199
	v_cvt_pk_bf16_f32 v210, v208, v209
	v_lshlrev_b32_e32 v118, 16, v210
	v_and_b32_e32 v119, 0xffff0000, v210
	v_lshlrev_b32_e32 v208, 16, v140
	v_and_b32_e32 v209, 0xffff0000, v140
	v_fma_f32 v208, v208, v160, v200
	v_fma_f32 v209, v209, v160, v201
	v_cvt_pk_bf16_f32 v210, v208, v209
	v_lshlrev_b32_e32 v120, 16, v210
	v_and_b32_e32 v121, 0xffff0000, v210
	v_lshlrev_b32_e32 v208, 16, v141
	v_and_b32_e32 v209, 0xffff0000, v141
	v_fma_f32 v208, v208, v160, v202
	v_fma_f32 v209, v209, v160, v203
	v_cvt_pk_bf16_f32 v210, v208, v209
	v_lshlrev_b32_e32 v122, 16, v210
	v_and_b32_e32 v123, 0xffff0000, v210
	v_lshlrev_b32_e32 v208, 16, v142
	v_and_b32_e32 v209, 0xffff0000, v142
	v_fma_f32 v208, v208, v160, v204
	v_fma_f32 v209, v209, v160, v205
	v_cvt_pk_bf16_f32 v210, v208, v209
	v_lshlrev_b32_e32 v124, 16, v210
	v_and_b32_e32 v125, 0xffff0000, v210
	v_lshlrev_b32_e32 v208, 16, v143
	v_and_b32_e32 v209, 0xffff0000, v143
	v_fma_f32 v208, v208, v160, v206
	v_fma_f32 v209, v209, v160, v207
	v_cvt_pk_bf16_f32 v210, v208, v209
	v_lshlrev_b32_e32 v126, 16, v210
	v_and_b32_e32 v127, 0xffff0000, v210
	v_mov_b32_e32 v216, 0
	v_mov_b32_e32 v217, 0
	v_mov_b32_e32 v218, 0
	v_mov_b32_e32 v219, 0
	v_add_u32_e32 v220, s22, v240
	ds_write_b128 v220, v[216:219] offset:0
	ds_write_b128 v220, v[216:219] offset:1024
	ds_write_b128 v220, v[216:219] offset:2048
	ds_write_b128 v220, v[216:219] offset:3072
	ds_write_b128 v220, v[216:219] offset:4096
	ds_write_b128 v220, v[216:219] offset:5120
	ds_write_b128 v220, v[216:219] offset:6144
	ds_write_b128 v220, v[216:219] offset:7168
	ds_write_b128 v220, v[216:219] offset:8192
	s_mov_b32 exec_hi, 0xfff
	ds_write_b128 v220, v[216:219] offset:9216
	s_mov_b64 exec, -1
	v_lshrrev_b32_e32 v222, 1, v240
	s_lshl_b32 s0, s76, 10
	s_add_i32 s0, s0, 0x11000
	v_add_u32_e32 v221, s0, v222
	ds_read_b64 v[128:129], v221 offset:0
	ds_read_b64 v[130:131], v221 offset:512
	ds_read_b64 v[132:133], v221 offset:1024
	ds_read_b64 v[134:135], v221 offset:1536
	ds_read_b64 v[136:137], v221 offset:2048
	ds_read_b64 v[138:139], v221 offset:2560
	ds_read_b64 v[140:141], v221 offset:3072
	ds_read_b64 v[142:143], v221 offset:3584
	ds_read_b64 v[144:145], v221 offset:4096
	ds_read_b64 v[146:147], v221 offset:4608
	ds_read_b64 v[148:149], v221 offset:5120
	ds_read_b64 v[150:151], v221 offset:5632
	ds_read_b64 v[152:153], v221 offset:6144
	ds_read_b64 v[154:155], v221 offset:6656
	ds_read_b64 v[156:157], v221 offset:7168
	ds_read_b64 v[158:159], v221 offset:7680
	v_mov_b32_e32 v212, 0
	s_waitcnt lgkmcnt(0)
; __device__ __forceinline__ void peer_tile(const Args& A, LAS unsigned char* lds, int tile) {
;     ...
;     for (int ti = 0; ti < 8; ++ti) {
;         const int tl = 8 * w + ti;
;         const u32x2 e0 = SEL[tl * 128 + lane], e1 = SEL[tl * 128 + 64 + lane];
;         const int p0 = (int)(e0.x >> 10), p1 = (int)(e1.x >> 10);
;         int off = 0;
;         for (int p = 0; p < 16; ++p) {
;             const unsigned long long m0 = __ballot(p0 == p), m1 = __ballot(p1 == p);
;             const int c0 = __popcll(m0), c1 = __popcll(m1);
;             const int r0 = __builtin_amdgcn_mbcnt_hi((unsigned)(m0 >> 32), __builtin_amdgcn_mbcnt_lo((unsigned)m0, 0u));
;             const int r1 = __builtin_amdgcn_mbcnt_hi((unsigned)(m1 >> 32), __builtin_amdgcn_mbcnt_lo((unsigned)m1, 0u));
;             if (p0 == p) SORT[tl * 128 + off + r0] = e0;
;             if (p1 == p) SORT[tl * 128 + off + c0 + r1] = e1;
;             if (lane == 0) OFFS[tl * 17 + p] = off;
;             off += c0 + c1;
;         }
;         if (lane == 0) OFFS[tl * 17 + 16] = off;
;     }
	v_lshrrev_b32_e32 v160, 11, v128
	v_lshlrev_b32_e32 v128, 10, v128
	v_lshrrev_b32_e32 v161, 11, v130
	v_lshlrev_b32_e32 v130, 10, v130
	v_lshrrev_b32_e32 v162, 11, v132
	v_lshlrev_b32_e32 v132, 10, v132
	v_lshrrev_b32_e32 v163, 11, v134
	v_lshlrev_b32_e32 v134, 10, v134
	v_lshrrev_b32_e32 v164, 11, v136
	v_lshlrev_b32_e32 v136, 10, v136
	v_lshrrev_b32_e32 v165, 11, v138
	v_lshlrev_b32_e32 v138, 10, v138
	v_lshrrev_b32_e32 v166, 11, v140
	v_lshlrev_b32_e32 v140, 10, v140
	v_lshrrev_b32_e32 v167, 11, v142
	v_lshlrev_b32_e32 v142, 10, v142
	v_lshrrev_b32_e32 v168, 11, v144
	v_lshlrev_b32_e32 v144, 10, v144
	v_lshrrev_b32_e32 v169, 11, v146
	v_lshlrev_b32_e32 v146, 10, v146
	v_lshrrev_b32_e32 v170, 11, v148
	v_lshlrev_b32_e32 v148, 10, v148
	v_lshrrev_b32_e32 v171, 11, v150
	v_lshlrev_b32_e32 v150, 10, v150
	v_lshrrev_b32_e32 v172, 11, v152
	v_lshlrev_b32_e32 v152, 10, v152
	v_lshrrev_b32_e32 v173, 11, v154
	v_lshlrev_b32_e32 v154, 10, v154
	v_lshrrev_b32_e32 v174, 11, v156
	v_lshlrev_b32_e32 v156, 10, v156
	v_lshrrev_b32_e32 v175, 11, v158
	v_lshlrev_b32_e32 v158, 10, v158
	s_mov_b32 s74, 0
	s_mov_b32 s75, 0
	s_mov_b32 s37, 0
.Lbuild_c:
	v_cmp_eq_u32_e64 s[68:69], s74, v160
	v_cmp_eq_u32_e64 s[70:71], s74, v161
	s_nop 0
	s_lshl_b32 s3, s75, 4
	s_add_i32 s3, s3, s22
	s_bcnt1_i32_b64 s0, s[68:69]
	s_bcnt1_i32_b64 s1, s[70:71]
	v_mbcnt_lo_u32_b32 v222, s68, 0
	v_mbcnt_hi_u32_b32 v222, s69, v222
	v_mbcnt_lo_u32_b32 v223, s70, 0
	v_mbcnt_hi_u32_b32 v223, s71, v223
	v_add_u32_e32 v223, s0, v223
	v_lshl_add_u32 v222, v222, 2, s3
	v_lshl_add_u32 v223, v223, 2, s3
	s_mov_b64 exec, s[68:69]
	ds_write_b32 v222, v128
	ds_write_b32 v222, v129 offset:4992
	s_mov_b64 exec, s[70:71]
	ds_write_b32 v223, v130
	ds_write_b32 v223, v131 offset:4992
	s_add_i32 s0, s0, s1
	s_add_i32 s0, s0, 3
	s_lshr_b32 s0, s0, 2
	s_lshl_b64 s[38:39], 1, s37
	s_mov_b64 exec, s[38:39]
	v_mov_b32_e32 v212, s0
	s_mov_b64 exec, -1
	s_add_i32 s75, s75, s0
	s_add_i32 s37, s37, 1
	v_cmp_eq_u32_e64 s[68:69], s74, v162
	v_cmp_eq_u32_e64 s[70:71], s74, v163
	s_nop 0
	s_lshl_b32 s3, s75, 4
	s_add_i32 s3, s3, s22
	s_bcnt1_i32_b64 s0, s[68:69]
	s_bcnt1_i32_b64 s1, s[70:71]
	v_mbcnt_lo_u32_b32 v222, s68, 0
	v_mbcnt_hi_u32_b32 v222, s69, v222
	v_mbcnt_lo_u32_b32 v223, s70, 0
	v_mbcnt_hi_u32_b32 v223, s71, v223
	v_add_u32_e32 v223, s0, v223
	v_lshl_add_u32 v222, v222, 2, s3
	v_lshl_add_u32 v223, v223, 2, s3
	s_mov_b64 exec, s[68:69]
	ds_write_b32 v222, v132
	ds_write_b32 v222, v133 offset:4992
	s_mov_b64 exec, s[70:71]
	ds_write_b32 v223, v134
	ds_write_b32 v223, v135 offset:4992
	s_add_i32 s0, s0, s1
	s_add_i32 s0, s0, 3
	s_lshr_b32 s0, s0, 2
	s_lshl_b64 s[38:39], 1, s37
	s_mov_b64 exec, s[38:39]
	v_mov_b32_e32 v212, s0
	s_mov_b64 exec, -1
	s_add_i32 s75, s75, s0
	s_add_i32 s37, s37, 1
	v_cmp_eq_u32_e64 s[68:69], s74, v164
	v_cmp_eq_u32_e64 s[70:71], s74, v165
	s_nop 0
	s_lshl_b32 s3, s75, 4
	s_add_i32 s3, s3, s22
	s_bcnt1_i32_b64 s0, s[68:69]
	s_bcnt1_i32_b64 s1, s[70:71]
	v_mbcnt_lo_u32_b32 v222, s68, 0
	v_mbcnt_hi_u32_b32 v222, s69, v222
	v_mbcnt_lo_u32_b32 v223, s70, 0
	v_mbcnt_hi_u32_b32 v223, s71, v223
	v_add_u32_e32 v223, s0, v223
	v_lshl_add_u32 v222, v222, 2, s3
	v_lshl_add_u32 v223, v223, 2, s3
	s_mov_b64 exec, s[68:69]
	ds_write_b32 v222, v136
	ds_write_b32 v222, v137 offset:4992
	s_mov_b64 exec, s[70:71]
	ds_write_b32 v223, v138
	ds_write_b32 v223, v139 offset:4992
	s_add_i32 s0, s0, s1
	s_add_i32 s0, s0, 3
	s_lshr_b32 s0, s0, 2
	s_lshl_b64 s[38:39], 1, s37
	s_mov_b64 exec, s[38:39]
	v_mov_b32_e32 v212, s0
	s_mov_b64 exec, -1
	s_add_i32 s75, s75, s0
	s_add_i32 s37, s37, 1
	v_cmp_eq_u32_e64 s[68:69], s74, v166
	v_cmp_eq_u32_e64 s[70:71], s74, v167
	s_nop 0
	s_lshl_b32 s3, s75, 4
	s_add_i32 s3, s3, s22
	s_bcnt1_i32_b64 s0, s[68:69]
	s_bcnt1_i32_b64 s1, s[70:71]
	v_mbcnt_lo_u32_b32 v222, s68, 0
	v_mbcnt_hi_u32_b32 v222, s69, v222
	v_mbcnt_lo_u32_b32 v223, s70, 0
	v_mbcnt_hi_u32_b32 v223, s71, v223
	v_add_u32_e32 v223, s0, v223
	v_lshl_add_u32 v222, v222, 2, s3
	v_lshl_add_u32 v223, v223, 2, s3
	s_mov_b64 exec, s[68:69]
	ds_write_b32 v222, v140
	ds_write_b32 v222, v141 offset:4992
	s_mov_b64 exec, s[70:71]
	ds_write_b32 v223, v142
	ds_write_b32 v223, v143 offset:4992
	s_add_i32 s0, s0, s1
	s_add_i32 s0, s0, 3
	s_lshr_b32 s0, s0, 2
	s_lshl_b64 s[38:39], 1, s37
	s_mov_b64 exec, s[38:39]
	v_mov_b32_e32 v212, s0
	s_mov_b64 exec, -1
	s_add_i32 s75, s75, s0
	s_add_i32 s37, s37, 1
	v_cmp_eq_u32_e64 s[68:69], s74, v168
	v_cmp_eq_u32_e64 s[70:71], s74, v169
	s_nop 0
	s_lshl_b32 s3, s75, 4
	s_add_i32 s3, s3, s22
	s_bcnt1_i32_b64 s0, s[68:69]
	s_bcnt1_i32_b64 s1, s[70:71]
	v_mbcnt_lo_u32_b32 v222, s68, 0
	v_mbcnt_hi_u32_b32 v222, s69, v222
	v_mbcnt_lo_u32_b32 v223, s70, 0
; #define IT_ADVANCE() do { it_j += 4; while (it_j >= it_end) { if (it_done) break; ++it_tk; if (it_tk == 4) { it_tk = 0; ++it_p; if (it_p == 16) { it_done = true; it_p = 15; it_j = 0; it_end = 1; break; } } \
;             it_j = __builtin_amdgcn_readfirstlane(OFFS[(tb + it_tk) * 17 + it_p]); it_end = __builtin_amdgcn_readfirstlane(OFFS[(tb + it_tk) * 17 + it_p + 1]); } } while (0)
; __device__ __forceinline__ void peer_tile(const Args& A, LAS unsigned char* lds, int tile) {
;     ...
;         for (int p = 0; p < 16; ++p) {
;             const unsigned long long m0 = __ballot(p0 == p), m1 = __ballot(p1 == p);
;             const int c0 = __popcll(m0), c1 = __popcll(m1);
;             const int r0 = __builtin_amdgcn_mbcnt_hi((unsigned)(m0 >> 32), __builtin_amdgcn_mbcnt_lo((unsigned)m0, 0u));
;             const int r1 = __builtin_amdgcn_mbcnt_hi((unsigned)(m1 >> 32), __builtin_amdgcn_mbcnt_lo((unsigned)m1, 0u));
;             if (p0 == p) SORT[tl * 128 + off + r0] = e0;
;             if (p1 == p) SORT[tl * 128 + off + c0 + r1] = e1;
;             if (lane == 0) OFFS[tl * 17 + p] = off;
;             off += c0 + c1;
;         }
;         if (lane == 0) OFFS[tl * 17 + 16] = off;
;     }
;     ...
;         u32x4 uA[4], vA[4], uB[4], vB[4]; float cgA = 0.f, suA = 0.f, svA = 0.f, cgB = 0.f, suB = 0.f, svB = 0.f;
; #pragma unroll
;         for (int k = 0; k < 4; ++k) { uA[k] = (u32x4){0u, 0u, 0u, 0u}; vA[k] = uA[k]; uB[k] = uA[k]; vB[k] = uA[k]; }
;         IT_ADVANCE();
;         LOAD_SET(uA, vA, cgA, suA, svA);
	v_mbcnt_hi_u32_b32 v223, s71, v223
	v_add_u32_e32 v223, s0, v223
	v_lshl_add_u32 v222, v222, 2, s3
	v_lshl_add_u32 v223, v223, 2, s3
	s_mov_b64 exec, s[68:69]
	ds_write_b32 v222, v144
	ds_write_b32 v222, v145 offset:4992
	s_mov_b64 exec, s[70:71]
	ds_write_b32 v223, v146
	ds_write_b32 v223, v147 offset:4992
	s_add_i32 s0, s0, s1
	s_add_i32 s0, s0, 3
	s_lshr_b32 s0, s0, 2
	s_lshl_b64 s[38:39], 1, s37
	s_mov_b64 exec, s[38:39]
	v_mov_b32_e32 v212, s0
	s_mov_b64 exec, -1
	s_add_i32 s75, s75, s0
	s_add_i32 s37, s37, 1
	v_cmp_eq_u32_e64 s[68:69], s74, v170
	v_cmp_eq_u32_e64 s[70:71], s74, v171
	s_nop 0
	s_lshl_b32 s3, s75, 4
	s_add_i32 s3, s3, s22
	s_bcnt1_i32_b64 s0, s[68:69]
	s_bcnt1_i32_b64 s1, s[70:71]
	v_mbcnt_lo_u32_b32 v222, s68, 0
	v_mbcnt_hi_u32_b32 v222, s69, v222
	v_mbcnt_lo_u32_b32 v223, s70, 0
	v_mbcnt_hi_u32_b32 v223, s71, v223
	v_add_u32_e32 v223, s0, v223
	v_lshl_add_u32 v222, v222, 2, s3
	v_lshl_add_u32 v223, v223, 2, s3
	s_mov_b64 exec, s[68:69]
	ds_write_b32 v222, v148
	ds_write_b32 v222, v149 offset:4992
	s_mov_b64 exec, s[70:71]
	ds_write_b32 v223, v150
	ds_write_b32 v223, v151 offset:4992
	s_add_i32 s0, s0, s1
	s_add_i32 s0, s0, 3
	s_lshr_b32 s0, s0, 2
	s_lshl_b64 s[38:39], 1, s37
	s_mov_b64 exec, s[38:39]
	v_mov_b32_e32 v212, s0
	s_mov_b64 exec, -1
	s_add_i32 s75, s75, s0
	s_add_i32 s37, s37, 1
	v_cmp_eq_u32_e64 s[68:69], s74, v172
	v_cmp_eq_u32_e64 s[70:71], s74, v173
	s_nop 0
	s_lshl_b32 s3, s75, 4
	s_add_i32 s3, s3, s22
	s_bcnt1_i32_b64 s0, s[68:69]
	s_bcnt1_i32_b64 s1, s[70:71]
	v_mbcnt_lo_u32_b32 v222, s68, 0
	v_mbcnt_hi_u32_b32 v222, s69, v222
	v_mbcnt_lo_u32_b32 v223, s70, 0
	v_mbcnt_hi_u32_b32 v223, s71, v223
	v_add_u32_e32 v223, s0, v223
	v_lshl_add_u32 v222, v222, 2, s3
	v_lshl_add_u32 v223, v223, 2, s3
	s_mov_b64 exec, s[68:69]
	ds_write_b32 v222, v152
	ds_write_b32 v222, v153 offset:4992
	s_mov_b64 exec, s[70:71]
	ds_write_b32 v223, v154
	ds_write_b32 v223, v155 offset:4992
	s_add_i32 s0, s0, s1
	s_add_i32 s0, s0, 3
	s_lshr_b32 s0, s0, 2
	s_lshl_b64 s[38:39], 1, s37
	s_mov_b64 exec, s[38:39]
	v_mov_b32_e32 v212, s0
	s_mov_b64 exec, -1
	s_add_i32 s75, s75, s0
	s_add_i32 s37, s37, 1
	v_cmp_eq_u32_e64 s[68:69], s74, v174
	v_cmp_eq_u32_e64 s[70:71], s74, v175
	s_nop 0
	s_lshl_b32 s3, s75, 4
	s_add_i32 s3, s3, s22
	s_bcnt1_i32_b64 s0, s[68:69]
	s_bcnt1_i32_b64 s1, s[70:71]
	v_mbcnt_lo_u32_b32 v222, s68, 0
	v_mbcnt_hi_u32_b32 v222, s69, v222
	v_mbcnt_lo_u32_b32 v223, s70, 0
	v_mbcnt_hi_u32_b32 v223, s71, v223
	v_add_u32_e32 v223, s0, v223
	v_lshl_add_u32 v222, v222, 2, s3
	v_lshl_add_u32 v223, v223, 2, s3
	s_mov_b64 exec, s[68:69]
	ds_write_b32 v222, v156
	ds_write_b32 v222, v157 offset:4992
	s_mov_b64 exec, s[70:71]
	ds_write_b32 v223, v158
	ds_write_b32 v223, v159 offset:4992
	s_add_i32 s0, s0, s1
	s_add_i32 s0, s0, 3
	s_lshr_b32 s0, s0, 2
	s_lshl_b64 s[38:39], 1, s37
	s_mov_b64 exec, s[38:39]
	v_mov_b32_e32 v212, s0
	s_mov_b64 exec, -1
	s_add_i32 s75, s75, s0
	s_add_i32 s37, s37, 1
	s_add_i32 s74, s74, 1
	s_cmp_lt_u32 s74, 8
	s_cbranch_scc1 .Lbuild_c
	s_mov_b32 s91, s75
	s_add_i32 s20, s91, 3
	s_and_b32 s20, s20, -4
	s_waitcnt vmcnt(0) lgkmcnt(0)
	v_mov_b32_e32 v213, s22
	ds_read_b128 v[232:235], v213 offset:0
	s_waitcnt lgkmcnt(0)
	v_add_u32_e32 v236, v232, v240
	v_add_u32_e32 v237, v233, v240
	v_add_u32_e32 v238, v234, v240
	v_add_u32_e32 v239, v235, v240
	global_load_dwordx4 v[128:131], v236, s[4:5]
	global_load_dwordx4 v[132:135], v237, s[4:5]
	global_load_dwordx4 v[136:139], v238, s[4:5]
	global_load_dwordx4 v[140:143], v239, s[4:5]
	ds_read_b128 v[232:235], v213 offset:16
	s_waitcnt lgkmcnt(0)
	v_add_u32_e32 v236, v232, v240
	v_add_u32_e32 v237, v233, v240
	v_add_u32_e32 v238, v234, v240
	v_add_u32_e32 v239, v235, v240
	global_load_dwordx4 v[144:147], v236, s[4:5]
	global_load_dwordx4 v[148:151], v237, s[4:5]
	global_load_dwordx4 v[152:155], v238, s[4:5]
	global_load_dwordx4 v[156:159], v239, s[4:5]
	ds_read_b128 v[232:235], v213 offset:32
	s_waitcnt lgkmcnt(0)
	v_add_u32_e32 v236, v232, v240
	v_add_u32_e32 v237, v233, v240
	v_add_u32_e32 v238, v234, v240
	v_add_u32_e32 v239, v235, v240
	global_load_dwordx4 v[160:163], v236, s[4:5]
	global_load_dwordx4 v[164:167], v237, s[4:5]
	global_load_dwordx4 v[168:171], v238, s[4:5]
	global_load_dwordx4 v[172:175], v239, s[4:5]
	ds_read_b128 v[232:235], v213 offset:48
	s_mov_b32 s21, 0
	s_mov_b32 s89, -1
	v_lshrrev_b32_e32 v208, 6, v240
	v_and_b32_e32 v208, 3, v208
	v_lshrrev_b32_e32 v209, 1, v208
	v_lshlrev_b32_e32 v208, 1, v208
	v_and_b32_e32 v208, 2, v208
	v_or_b32_e32 v208, v208, v209
	v_lshlrev_b32_e32 v208, 2, v208
	v_add3_u32 v211, v208, v247, s22
	ds_read_b32 v248, v211
	ds_read_b32 v249, v211 offset:4992
	s_branch .LU_sw0

.LU_t0_s3:
	s_waitcnt lgkmcnt(0)
	v_add_u32_e32 v236, v232, v240
	v_add_u32_e32 v237, v233, v240
	v_add_u32_e32 v238, v234, v240
	v_add_u32_e32 v239, v235, v240
	global_load_dwordx4 v[160:163], v236, s[4:5]
	global_load_dwordx4 v[164:167], v237, s[4:5]
	global_load_dwordx4 v[168:171], v238, s[4:5]
	global_load_dwordx4 v[172:175], v239, s[4:5]
	ds_read_b128 v[232:235], v213 offset:112
	s_waitcnt vmcnt(12)
	v_cvt_pk_f32_fp8_e32 v[224:225], v176
	v_cvt_pk_f32_fp8_e32 v[226:227], v180
	v_cvt_pk_f32_fp8_e32 v[228:229], v184
	v_cvt_pk_f32_fp8_e32 v[230:231], v188
	v_pk_mul_f32 v[216:217], v[224:225], v[0:1]
	v_pk_mul_f32 v[218:219], v[226:227], v[0:1]
	v_pk_mul_f32 v[220:221], v[228:229], v[0:1]
	v_pk_mul_f32 v[222:223], v[230:231], v[0:1]
	v_cvt_pk_f32_fp8_sdwa v[224:225], v176 src0_sel:WORD_1
	v_cvt_pk_f32_fp8_sdwa v[226:227], v180 src0_sel:WORD_1
	v_cvt_pk_f32_fp8_sdwa v[228:229], v184 src0_sel:WORD_1
	v_cvt_pk_f32_fp8_sdwa v[230:231], v188 src0_sel:WORD_1
	v_pk_fma_f32 v[216:217], v[224:225], v[2:3], v[216:217]
	v_pk_fma_f32 v[218:219], v[226:227], v[2:3], v[218:219]
	v_pk_fma_f32 v[220:221], v[228:229], v[2:3], v[220:221]
	v_pk_fma_f32 v[222:223], v[230:231], v[2:3], v[222:223]
	v_cvt_pk_f32_fp8_e32 v[224:225], v177
	v_cvt_pk_f32_fp8_e32 v[226:227], v181
	v_cvt_pk_f32_fp8_e32 v[228:229], v185
	v_cvt_pk_f32_fp8_e32 v[230:231], v189
	v_pk_fma_f32 v[216:217], v[224:225], v[4:5], v[216:217]
	v_pk_fma_f32 v[218:219], v[226:227], v[4:5], v[218:219]
	v_pk_fma_f32 v[220:221], v[228:229], v[4:5], v[220:221]
	v_pk_fma_f32 v[222:223], v[230:231], v[4:5], v[222:223]
	v_cvt_pk_f32_fp8_sdwa v[224:225], v177 src0_sel:WORD_1
	v_cvt_pk_f32_fp8_sdwa v[226:227], v181 src0_sel:WORD_1
	v_cvt_pk_f32_fp8_sdwa v[228:229], v185 src0_sel:WORD_1
	v_cvt_pk_f32_fp8_sdwa v[230:231], v189 src0_sel:WORD_1
	v_pk_fma_f32 v[216:217], v[224:225], v[6:7], v[216:217]
	v_pk_fma_f32 v[218:219], v[226:227], v[6:7], v[218:219]
	v_pk_fma_f32 v[220:221], v[228:229], v[6:7], v[220:221]
	v_pk_fma_f32 v[222:223], v[230:231], v[6:7], v[222:223]
	v_cvt_pk_f32_fp8_e32 v[224:225], v178
	v_cvt_pk_f32_fp8_e32 v[226:227], v182
	v_cvt_pk_f32_fp8_e32 v[228:229], v186
	v_cvt_pk_f32_fp8_e32 v[230:231], v190
	v_pk_fma_f32 v[216:217], v[224:225], v[8:9], v[216:217]
	v_pk_fma_f32 v[218:219], v[226:227], v[8:9], v[218:219]
	v_pk_fma_f32 v[220:221], v[228:229], v[8:9], v[220:221]
	v_pk_fma_f32 v[222:223], v[230:231], v[8:9], v[222:223]
	v_cvt_pk_f32_fp8_sdwa v[224:225], v178 src0_sel:WORD_1
	v_cvt_pk_f32_fp8_sdwa v[226:227], v182 src0_sel:WORD_1
	v_cvt_pk_f32_fp8_sdwa v[228:229], v186 src0_sel:WORD_1
	v_cvt_pk_f32_fp8_sdwa v[230:231], v190 src0_sel:WORD_1
	v_pk_fma_f32 v[216:217], v[224:225], v[10:11], v[216:217]
	v_pk_fma_f32 v[218:219], v[226:227], v[10:11], v[218:219]
	v_pk_fma_f32 v[220:221], v[228:229], v[10:11], v[220:221]
	v_pk_fma_f32 v[222:223], v[230:231], v[10:11], v[222:223]
	v_cvt_pk_f32_fp8_e32 v[224:225], v179
	v_cvt_pk_f32_fp8_e32 v[226:227], v183
	v_cvt_pk_f32_fp8_e32 v[228:229], v187
	v_cvt_pk_f32_fp8_e32 v[230:231], v191
	v_pk_fma_f32 v[216:217], v[224:225], v[12:13], v[216:217]
	v_pk_fma_f32 v[218:219], v[226:227], v[12:13], v[218:219]
	v_pk_fma_f32 v[220:221], v[228:229], v[12:13], v[220:221]
	v_pk_fma_f32 v[222:223], v[230:231], v[12:13], v[222:223]
	v_cvt_pk_f32_fp8_sdwa v[224:225], v179 src0_sel:WORD_1
	v_cvt_pk_f32_fp8_sdwa v[226:227], v183 src0_sel:WORD_1
	v_cvt_pk_f32_fp8_sdwa v[228:229], v187 src0_sel:WORD_1
	v_cvt_pk_f32_fp8_sdwa v[230:231], v191 src0_sel:WORD_1
	v_pk_fma_f32 v[216:217], v[224:225], v[14:15], v[216:217]
	v_pk_fma_f32 v[218:219], v[226:227], v[14:15], v[218:219]
	v_pk_fma_f32 v[220:221], v[228:229], v[14:15], v[220:221]
	v_pk_fma_f32 v[222:223], v[230:231], v[14:15], v[222:223]
	v_add_f32_e32 v204, v216, v217
	v_add_f32_e32 v205, v218, v219
	v_add_f32_e32 v206, v220, v221
	v_add_f32_e32 v207, v222, v223
	s_nop 0
	v_permlane32_swap_b32_e32 v192, v200
	v_permlane32_swap_b32_e32 v193, v201
	v_permlane32_swap_b32_e32 v194, v202
	v_permlane32_swap_b32_e32 v195, v203
	v_permlane32_swap_b32_e32 v196, v204
	v_permlane32_swap_b32_e32 v197, v205
	v_permlane32_swap_b32_e32 v198, v206
	v_permlane32_swap_b32_e32 v199, v207
	v_add_f32_e32 v192, v192, v200
	v_add_f32_e32 v193, v193, v201
	v_add_f32_e32 v194, v194, v202
	v_add_f32_e32 v195, v195, v203
	v_add_f32_e32 v196, v196, v204
	v_add_f32_e32 v197, v197, v205
	v_add_f32_e32 v198, v198, v206
	v_add_f32_e32 v199, v199, v207
	v_permlane16_swap_b32_e32 v192, v196
	v_permlane16_swap_b32_e32 v193, v197
	v_permlane16_swap_b32_e32 v194, v198
	v_permlane16_swap_b32_e32 v195, v199
	v_add_f32_e32 v192, v192, v196
	v_add_f32_e32 v193, v193, v197
	v_add_f32_e32 v194, v194, v198
	v_add_f32_e32 v195, v195, v199
	v_add_f32_dpp v216, v192, v192 row_ror:8 row_mask:0xf bank_mask:0xf
	v_add_f32_dpp v218, v194, v194 row_ror:8 row_mask:0xf bank_mask:0xf
	v_add_f32_dpp v216, v193, v193 row_ror:8 row_mask:0xf bank_mask:0xc
	v_add_f32_dpp v218, v195, v195 row_ror:8 row_mask:0xf bank_mask:0xc
	s_nop 1
	v_add_f32_dpp v220, v216, v216 row_half_mirror row_mask:0xf bank_mask:0xf
	v_add_f32_dpp v220, v218, v218 row_half_mirror row_mask:0xf bank_mask:0xa
	s_nop 1
	v_add_f32_dpp v220, v220, v220 quad_perm:[1,0,3,2] row_mask:0xf bank_mask:0xf
	s_nop 1
	v_add_f32_dpp v220, v220, v220 quad_perm:[2,3,0,1] row_mask:0xf bank_mask:0xf
	v_mul_f32_e32 v216, v252, v220
	v_fma_f32 v218, |v216|, s72, 1.0
	v_mul_f32_e32 v222, v216, v216
	v_rcp_f32_e32 v218, v218
	v_mul_f32_e32 v222, 0xbf38aa3b, v222
	v_exp_f32_e32 v222, v222
	v_fmamk_f32 v224, v218, 0x3f07dc22, v242
	v_fmaak_f32 v224, v218, v224, 0x3f35f0e3
	v_fmaak_f32 v224, v218, v224, 0xbe11a98e
	v_fmaak_f32 v224, v218, v224, 0x3e027906
	v_mul_f32_e32 v224, v218, v224
	v_mul_f32_e32 v224, v222, v224
	v_mul_f32_e32 v226, v216, v224
	v_fma_f32 v224, -v216, v224, v216
	v_cmp_gt_f32_e32 vcc, 0, v216
	s_nop 1
	v_cndmask_b32_e32 v224, v224, v226, vcc
	v_mul_f32_e32 v224, v249, v224
	v_mul_f32_e32 v224, v253, v224
	ds_write_b32 v211, v224 offset:4992
	v_add_u32_e32 v211, 64, v211
	v_add_u32_e32 v213, 64, v213
	ds_read_b32 v248, v211
	ds_read_b32 v249, v211 offset:4992
	s_add_i32 s21, s21, 4
	s_sub_i32 s90, s90, 1
	s_cmp_eq_u32 s90, 0
	s_cbranch_scc1 .LU_sw0
	s_branch .LU_t0_s0

.LU_t1_s3:
	s_waitcnt lgkmcnt(0)
	v_add_u32_e32 v236, v232, v240
	v_add_u32_e32 v237, v233, v240
	v_add_u32_e32 v238, v234, v240
	v_add_u32_e32 v239, v235, v240
	global_load_dwordx4 v[160:163], v236, s[4:5]
	global_load_dwordx4 v[164:167], v237, s[4:5]
	global_load_dwordx4 v[168:171], v238, s[4:5]
	global_load_dwordx4 v[172:175], v239, s[4:5]
	ds_read_b128 v[232:235], v213 offset:112
	s_waitcnt vmcnt(12)
	v_cvt_pk_f32_fp8_e32 v[224:225], v176
	v_cvt_pk_f32_fp8_e32 v[226:227], v180
	v_cvt_pk_f32_fp8_e32 v[228:229], v184
	v_cvt_pk_f32_fp8_e32 v[230:231], v188
	v_pk_mul_f32 v[216:217], v[224:225], v[16:17]
	v_pk_mul_f32 v[218:219], v[226:227], v[16:17]
	v_pk_mul_f32 v[220:221], v[228:229], v[16:17]
	v_pk_mul_f32 v[222:223], v[230:231], v[16:17]
	v_cvt_pk_f32_fp8_sdwa v[224:225], v176 src0_sel:WORD_1
	v_cvt_pk_f32_fp8_sdwa v[226:227], v180 src0_sel:WORD_1
	v_cvt_pk_f32_fp8_sdwa v[228:229], v184 src0_sel:WORD_1
	v_cvt_pk_f32_fp8_sdwa v[230:231], v188 src0_sel:WORD_1
	v_pk_fma_f32 v[216:217], v[224:225], v[18:19], v[216:217]
	v_pk_fma_f32 v[218:219], v[226:227], v[18:19], v[218:219]
	v_pk_fma_f32 v[220:221], v[228:229], v[18:19], v[220:221]
	v_pk_fma_f32 v[222:223], v[230:231], v[18:19], v[222:223]
	v_cvt_pk_f32_fp8_e32 v[224:225], v177
	v_cvt_pk_f32_fp8_e32 v[226:227], v181
	v_cvt_pk_f32_fp8_e32 v[228:229], v185
	v_cvt_pk_f32_fp8_e32 v[230:231], v189
	v_pk_fma_f32 v[216:217], v[224:225], v[20:21], v[216:217]
	v_pk_fma_f32 v[218:219], v[226:227], v[20:21], v[218:219]
	v_pk_fma_f32 v[220:221], v[228:229], v[20:21], v[220:221]
	v_pk_fma_f32 v[222:223], v[230:231], v[20:21], v[222:223]
	v_cvt_pk_f32_fp8_sdwa v[224:225], v177 src0_sel:WORD_1
	v_cvt_pk_f32_fp8_sdwa v[226:227], v181 src0_sel:WORD_1
	v_cvt_pk_f32_fp8_sdwa v[228:229], v185 src0_sel:WORD_1
	v_cvt_pk_f32_fp8_sdwa v[230:231], v189 src0_sel:WORD_1
	v_pk_fma_f32 v[216:217], v[224:225], v[22:23], v[216:217]
	v_pk_fma_f32 v[218:219], v[226:227], v[22:23], v[218:219]
	v_pk_fma_f32 v[220:221], v[228:229], v[22:23], v[220:221]
	v_pk_fma_f32 v[222:223], v[230:231], v[22:23], v[222:223]
	v_cvt_pk_f32_fp8_e32 v[224:225], v178
	v_cvt_pk_f32_fp8_e32 v[226:227], v182
	v_cvt_pk_f32_fp8_e32 v[228:229], v186
	v_cvt_pk_f32_fp8_e32 v[230:231], v190
	v_pk_fma_f32 v[216:217], v[224:225], v[24:25], v[216:217]
	v_pk_fma_f32 v[218:219], v[226:227], v[24:25], v[218:219]
	v_pk_fma_f32 v[220:221], v[228:229], v[24:25], v[220:221]
	v_pk_fma_f32 v[222:223], v[230:231], v[24:25], v[222:223]
	v_cvt_pk_f32_fp8_sdwa v[224:225], v178 src0_sel:WORD_1
	v_cvt_pk_f32_fp8_sdwa v[226:227], v182 src0_sel:WORD_1
	v_cvt_pk_f32_fp8_sdwa v[228:229], v186 src0_sel:WORD_1
	v_cvt_pk_f32_fp8_sdwa v[230:231], v190 src0_sel:WORD_1
	v_pk_fma_f32 v[216:217], v[224:225], v[26:27], v[216:217]
	v_pk_fma_f32 v[218:219], v[226:227], v[26:27], v[218:219]
	v_pk_fma_f32 v[220:221], v[228:229], v[26:27], v[220:221]
	v_pk_fma_f32 v[222:223], v[230:231], v[26:27], v[222:223]
	v_cvt_pk_f32_fp8_e32 v[224:225], v179
	v_cvt_pk_f32_fp8_e32 v[226:227], v183
	v_cvt_pk_f32_fp8_e32 v[228:229], v187
	v_cvt_pk_f32_fp8_e32 v[230:231], v191
	v_pk_fma_f32 v[216:217], v[224:225], v[28:29], v[216:217]
	v_pk_fma_f32 v[218:219], v[226:227], v[28:29], v[218:219]
	v_pk_fma_f32 v[220:221], v[228:229], v[28:29], v[220:221]
	v_pk_fma_f32 v[222:223], v[230:231], v[28:29], v[222:223]
	v_cvt_pk_f32_fp8_sdwa v[224:225], v179 src0_sel:WORD_1
	v_cvt_pk_f32_fp8_sdwa v[226:227], v183 src0_sel:WORD_1
	v_cvt_pk_f32_fp8_sdwa v[228:229], v187 src0_sel:WORD_1
	v_cvt_pk_f32_fp8_sdwa v[230:231], v191 src0_sel:WORD_1
	v_pk_fma_f32 v[216:217], v[224:225], v[30:31], v[216:217]
	v_pk_fma_f32 v[218:219], v[226:227], v[30:31], v[218:219]
	v_pk_fma_f32 v[220:221], v[228:229], v[30:31], v[220:221]
	v_pk_fma_f32 v[222:223], v[230:231], v[30:31], v[222:223]
	v_add_f32_e32 v204, v216, v217
	v_add_f32_e32 v205, v218, v219
	v_add_f32_e32 v206, v220, v221
	v_add_f32_e32 v207, v222, v223
	s_nop 0
	v_permlane32_swap_b32_e32 v192, v200
	v_permlane32_swap_b32_e32 v193, v201
	v_permlane32_swap_b32_e32 v194, v202
	v_permlane32_swap_b32_e32 v195, v203
	v_permlane32_swap_b32_e32 v196, v204
	v_permlane32_swap_b32_e32 v197, v205
	v_permlane32_swap_b32_e32 v198, v206
	v_permlane32_swap_b32_e32 v199, v207
	v_add_f32_e32 v192, v192, v200
	v_add_f32_e32 v193, v193, v201
	v_add_f32_e32 v194, v194, v202
	v_add_f32_e32 v195, v195, v203
	v_add_f32_e32 v196, v196, v204
	v_add_f32_e32 v197, v197, v205
	v_add_f32_e32 v198, v198, v206
	v_add_f32_e32 v199, v199, v207
	v_permlane16_swap_b32_e32 v192, v196
	v_permlane16_swap_b32_e32 v193, v197
	v_permlane16_swap_b32_e32 v194, v198
	v_permlane16_swap_b32_e32 v195, v199
	v_add_f32_e32 v192, v192, v196
	v_add_f32_e32 v193, v193, v197
	v_add_f32_e32 v194, v194, v198
	v_add_f32_e32 v195, v195, v199
	v_add_f32_dpp v216, v192, v192 row_ror:8 row_mask:0xf bank_mask:0xf
	v_add_f32_dpp v218, v194, v194 row_ror:8 row_mask:0xf bank_mask:0xf
	v_add_f32_dpp v216, v193, v193 row_ror:8 row_mask:0xf bank_mask:0xc
	v_add_f32_dpp v218, v195, v195 row_ror:8 row_mask:0xf bank_mask:0xc
	s_nop 1
	v_add_f32_dpp v220, v216, v216 row_half_mirror row_mask:0xf bank_mask:0xf
	v_add_f32_dpp v220, v218, v218 row_half_mirror row_mask:0xf bank_mask:0xa
	s_nop 1
	v_add_f32_dpp v220, v220, v220 quad_perm:[1,0,3,2] row_mask:0xf bank_mask:0xf
	s_nop 1
	v_add_f32_dpp v220, v220, v220 quad_perm:[2,3,0,1] row_mask:0xf bank_mask:0xf
	v_mul_f32_e32 v216, v252, v220
	v_fma_f32 v218, |v216|, s72, 1.0
	v_mul_f32_e32 v222, v216, v216
	v_rcp_f32_e32 v218, v218
	v_mul_f32_e32 v222, 0xbf38aa3b, v222
	v_exp_f32_e32 v222, v222
	v_fmamk_f32 v224, v218, 0x3f07dc22, v242
	v_fmaak_f32 v224, v218, v224, 0x3f35f0e3
	v_fmaak_f32 v224, v218, v224, 0xbe11a98e
	v_fmaak_f32 v224, v218, v224, 0x3e027906
	v_mul_f32_e32 v224, v218, v224
	v_mul_f32_e32 v224, v222, v224
	v_mul_f32_e32 v226, v216, v224
	v_fma_f32 v224, -v216, v224, v216
	v_cmp_gt_f32_e32 vcc, 0, v216
	s_nop 1
	v_cndmask_b32_e32 v224, v224, v226, vcc
	v_mul_f32_e32 v224, v249, v224
	v_mul_f32_e32 v224, v253, v224
	ds_write_b32 v211, v224 offset:4992
	v_add_u32_e32 v211, 64, v211
	v_add_u32_e32 v213, 64, v213
	ds_read_b32 v248, v211
	ds_read_b32 v249, v211 offset:4992
	s_add_i32 s21, s21, 4
	s_sub_i32 s90, s90, 1
	s_cmp_eq_u32 s90, 0
	s_cbranch_scc1 .LU_sw0
	s_branch .LU_t1_s0

.LU_t2_s3:
	s_waitcnt lgkmcnt(0)
	v_add_u32_e32 v236, v232, v240
	v_add_u32_e32 v237, v233, v240
	v_add_u32_e32 v238, v234, v240
	v_add_u32_e32 v239, v235, v240
	global_load_dwordx4 v[160:163], v236, s[4:5]
	global_load_dwordx4 v[164:167], v237, s[4:5]
	global_load_dwordx4 v[168:171], v238, s[4:5]
	global_load_dwordx4 v[172:175], v239, s[4:5]
	ds_read_b128 v[232:235], v213 offset:112
	s_waitcnt vmcnt(12)
	v_cvt_pk_f32_fp8_e32 v[224:225], v176
	v_cvt_pk_f32_fp8_e32 v[226:227], v180
	v_cvt_pk_f32_fp8_e32 v[228:229], v184
	v_cvt_pk_f32_fp8_e32 v[230:231], v188
	v_pk_mul_f32 v[216:217], v[224:225], v[32:33]
	v_pk_mul_f32 v[218:219], v[226:227], v[32:33]
	v_pk_mul_f32 v[220:221], v[228:229], v[32:33]
	v_pk_mul_f32 v[222:223], v[230:231], v[32:33]
	v_cvt_pk_f32_fp8_sdwa v[224:225], v176 src0_sel:WORD_1
	v_cvt_pk_f32_fp8_sdwa v[226:227], v180 src0_sel:WORD_1
	v_cvt_pk_f32_fp8_sdwa v[228:229], v184 src0_sel:WORD_1
	v_cvt_pk_f32_fp8_sdwa v[230:231], v188 src0_sel:WORD_1
	v_pk_fma_f32 v[216:217], v[224:225], v[34:35], v[216:217]
	v_pk_fma_f32 v[218:219], v[226:227], v[34:35], v[218:219]
	v_pk_fma_f32 v[220:221], v[228:229], v[34:35], v[220:221]
	v_pk_fma_f32 v[222:223], v[230:231], v[34:35], v[222:223]
	v_cvt_pk_f32_fp8_e32 v[224:225], v177
	v_cvt_pk_f32_fp8_e32 v[226:227], v181
	v_cvt_pk_f32_fp8_e32 v[228:229], v185
	v_cvt_pk_f32_fp8_e32 v[230:231], v189
	v_pk_fma_f32 v[216:217], v[224:225], v[36:37], v[216:217]
	v_pk_fma_f32 v[218:219], v[226:227], v[36:37], v[218:219]
	v_pk_fma_f32 v[220:221], v[228:229], v[36:37], v[220:221]
	v_pk_fma_f32 v[222:223], v[230:231], v[36:37], v[222:223]
	v_cvt_pk_f32_fp8_sdwa v[224:225], v177 src0_sel:WORD_1
	v_cvt_pk_f32_fp8_sdwa v[226:227], v181 src0_sel:WORD_1
	v_cvt_pk_f32_fp8_sdwa v[228:229], v185 src0_sel:WORD_1
	v_cvt_pk_f32_fp8_sdwa v[230:231], v189 src0_sel:WORD_1
	v_pk_fma_f32 v[216:217], v[224:225], v[38:39], v[216:217]
	v_pk_fma_f32 v[218:219], v[226:227], v[38:39], v[218:219]
	v_pk_fma_f32 v[220:221], v[228:229], v[38:39], v[220:221]
	v_pk_fma_f32 v[222:223], v[230:231], v[38:39], v[222:223]
	v_cvt_pk_f32_fp8_e32 v[224:225], v178
	v_cvt_pk_f32_fp8_e32 v[226:227], v182
	v_cvt_pk_f32_fp8_e32 v[228:229], v186
	v_cvt_pk_f32_fp8_e32 v[230:231], v190
	v_pk_fma_f32 v[216:217], v[224:225], v[40:41], v[216:217]
	v_pk_fma_f32 v[218:219], v[226:227], v[40:41], v[218:219]
	v_pk_fma_f32 v[220:221], v[228:229], v[40:41], v[220:221]
	v_pk_fma_f32 v[222:223], v[230:231], v[40:41], v[222:223]
	v_cvt_pk_f32_fp8_sdwa v[224:225], v178 src0_sel:WORD_1
	v_cvt_pk_f32_fp8_sdwa v[226:227], v182 src0_sel:WORD_1
	v_cvt_pk_f32_fp8_sdwa v[228:229], v186 src0_sel:WORD_1
	v_cvt_pk_f32_fp8_sdwa v[230:231], v190 src0_sel:WORD_1
	v_pk_fma_f32 v[216:217], v[224:225], v[42:43], v[216:217]
	v_pk_fma_f32 v[218:219], v[226:227], v[42:43], v[218:219]
	v_pk_fma_f32 v[220:221], v[228:229], v[42:43], v[220:221]
	v_pk_fma_f32 v[222:223], v[230:231], v[42:43], v[222:223]
	v_cvt_pk_f32_fp8_e32 v[224:225], v179
	v_cvt_pk_f32_fp8_e32 v[226:227], v183
	v_cvt_pk_f32_fp8_e32 v[228:229], v187
	v_cvt_pk_f32_fp8_e32 v[230:231], v191
	v_pk_fma_f32 v[216:217], v[224:225], v[44:45], v[216:217]
	v_pk_fma_f32 v[218:219], v[226:227], v[44:45], v[218:219]
	v_pk_fma_f32 v[220:221], v[228:229], v[44:45], v[220:221]
	v_pk_fma_f32 v[222:223], v[230:231], v[44:45], v[222:223]
	v_cvt_pk_f32_fp8_sdwa v[224:225], v179 src0_sel:WORD_1
	v_cvt_pk_f32_fp8_sdwa v[226:227], v183 src0_sel:WORD_1
	v_cvt_pk_f32_fp8_sdwa v[228:229], v187 src0_sel:WORD_1
	v_cvt_pk_f32_fp8_sdwa v[230:231], v191 src0_sel:WORD_1
	v_pk_fma_f32 v[216:217], v[224:225], v[46:47], v[216:217]
	v_pk_fma_f32 v[218:219], v[226:227], v[46:47], v[218:219]
	v_pk_fma_f32 v[220:221], v[228:229], v[46:47], v[220:221]
	v_pk_fma_f32 v[222:223], v[230:231], v[46:47], v[222:223]
	v_add_f32_e32 v204, v216, v217
	v_add_f32_e32 v205, v218, v219
	v_add_f32_e32 v206, v220, v221
	v_add_f32_e32 v207, v222, v223
	s_nop 0
	v_permlane32_swap_b32_e32 v192, v200
	v_permlane32_swap_b32_e32 v193, v201
	v_permlane32_swap_b32_e32 v194, v202
	v_permlane32_swap_b32_e32 v195, v203
	v_permlane32_swap_b32_e32 v196, v204
	v_permlane32_swap_b32_e32 v197, v205
	v_permlane32_swap_b32_e32 v198, v206
	v_permlane32_swap_b32_e32 v199, v207
	v_add_f32_e32 v192, v192, v200
	v_add_f32_e32 v193, v193, v201
	v_add_f32_e32 v194, v194, v202
	v_add_f32_e32 v195, v195, v203
	v_add_f32_e32 v196, v196, v204
	v_add_f32_e32 v197, v197, v205
	v_add_f32_e32 v198, v198, v206
	v_add_f32_e32 v199, v199, v207
	v_permlane16_swap_b32_e32 v192, v196
	v_permlane16_swap_b32_e32 v193, v197
	v_permlane16_swap_b32_e32 v194, v198
	v_permlane16_swap_b32_e32 v195, v199
	v_add_f32_e32 v192, v192, v196
	v_add_f32_e32 v193, v193, v197
	v_add_f32_e32 v194, v194, v198
	v_add_f32_e32 v195, v195, v199
	v_add_f32_dpp v216, v192, v192 row_ror:8 row_mask:0xf bank_mask:0xf
	v_add_f32_dpp v218, v194, v194 row_ror:8 row_mask:0xf bank_mask:0xf
	v_add_f32_dpp v216, v193, v193 row_ror:8 row_mask:0xf bank_mask:0xc
	v_add_f32_dpp v218, v195, v195 row_ror:8 row_mask:0xf bank_mask:0xc
	s_nop 1
	v_add_f32_dpp v220, v216, v216 row_half_mirror row_mask:0xf bank_mask:0xf
	v_add_f32_dpp v220, v218, v218 row_half_mirror row_mask:0xf bank_mask:0xa
	s_nop 1
	v_add_f32_dpp v220, v220, v220 quad_perm:[1,0,3,2] row_mask:0xf bank_mask:0xf
	s_nop 1
	v_add_f32_dpp v220, v220, v220 quad_perm:[2,3,0,1] row_mask:0xf bank_mask:0xf
	v_mul_f32_e32 v216, v252, v220
	v_fma_f32 v218, |v216|, s72, 1.0
	v_mul_f32_e32 v222, v216, v216
	v_rcp_f32_e32 v218, v218
	v_mul_f32_e32 v222, 0xbf38aa3b, v222
	v_exp_f32_e32 v222, v222
	v_fmamk_f32 v224, v218, 0x3f07dc22, v242
	v_fmaak_f32 v224, v218, v224, 0x3f35f0e3
	v_fmaak_f32 v224, v218, v224, 0xbe11a98e
	v_fmaak_f32 v224, v218, v224, 0x3e027906
	v_mul_f32_e32 v224, v218, v224
	v_mul_f32_e32 v224, v222, v224
	v_mul_f32_e32 v226, v216, v224
	v_fma_f32 v224, -v216, v224, v216
	v_cmp_gt_f32_e32 vcc, 0, v216
	s_nop 1
	v_cndmask_b32_e32 v224, v224, v226, vcc
	v_mul_f32_e32 v224, v249, v224
	v_mul_f32_e32 v224, v253, v224
	ds_write_b32 v211, v224 offset:4992
	v_add_u32_e32 v211, 64, v211
	v_add_u32_e32 v213, 64, v213
	ds_read_b32 v248, v211
	ds_read_b32 v249, v211 offset:4992
	s_add_i32 s21, s21, 4
	s_sub_i32 s90, s90, 1
	s_cmp_eq_u32 s90, 0
	s_cbranch_scc1 .LU_sw0
	s_branch .LU_t2_s0

.LU_t3_s3:
	s_waitcnt lgkmcnt(0)
	v_add_u32_e32 v236, v232, v240
	v_add_u32_e32 v237, v233, v240
	v_add_u32_e32 v238, v234, v240
	v_add_u32_e32 v239, v235, v240
	global_load_dwordx4 v[160:163], v236, s[4:5]
	global_load_dwordx4 v[164:167], v237, s[4:5]
	global_load_dwordx4 v[168:171], v238, s[4:5]
	global_load_dwordx4 v[172:175], v239, s[4:5]
	ds_read_b128 v[232:235], v213 offset:112
	s_waitcnt vmcnt(12)
	v_cvt_pk_f32_fp8_e32 v[224:225], v176
	v_cvt_pk_f32_fp8_e32 v[226:227], v180
	v_cvt_pk_f32_fp8_e32 v[228:229], v184
	v_cvt_pk_f32_fp8_e32 v[230:231], v188
	v_pk_mul_f32 v[216:217], v[224:225], v[48:49]
	v_pk_mul_f32 v[218:219], v[226:227], v[48:49]
	v_pk_mul_f32 v[220:221], v[228:229], v[48:49]
	v_pk_mul_f32 v[222:223], v[230:231], v[48:49]
	v_cvt_pk_f32_fp8_sdwa v[224:225], v176 src0_sel:WORD_1
	v_cvt_pk_f32_fp8_sdwa v[226:227], v180 src0_sel:WORD_1
	v_cvt_pk_f32_fp8_sdwa v[228:229], v184 src0_sel:WORD_1
	v_cvt_pk_f32_fp8_sdwa v[230:231], v188 src0_sel:WORD_1
	v_pk_fma_f32 v[216:217], v[224:225], v[50:51], v[216:217]
	v_pk_fma_f32 v[218:219], v[226:227], v[50:51], v[218:219]
	v_pk_fma_f32 v[220:221], v[228:229], v[50:51], v[220:221]
	v_pk_fma_f32 v[222:223], v[230:231], v[50:51], v[222:223]
	v_cvt_pk_f32_fp8_e32 v[224:225], v177
	v_cvt_pk_f32_fp8_e32 v[226:227], v181
	v_cvt_pk_f32_fp8_e32 v[228:229], v185
	v_cvt_pk_f32_fp8_e32 v[230:231], v189
	v_pk_fma_f32 v[216:217], v[224:225], v[52:53], v[216:217]
	v_pk_fma_f32 v[218:219], v[226:227], v[52:53], v[218:219]
	v_pk_fma_f32 v[220:221], v[228:229], v[52:53], v[220:221]
	v_pk_fma_f32 v[222:223], v[230:231], v[52:53], v[222:223]
	v_cvt_pk_f32_fp8_sdwa v[224:225], v177 src0_sel:WORD_1
	v_cvt_pk_f32_fp8_sdwa v[226:227], v181 src0_sel:WORD_1
	v_cvt_pk_f32_fp8_sdwa v[228:229], v185 src0_sel:WORD_1
	v_cvt_pk_f32_fp8_sdwa v[230:231], v189 src0_sel:WORD_1
	v_pk_fma_f32 v[216:217], v[224:225], v[54:55], v[216:217]
	v_pk_fma_f32 v[218:219], v[226:227], v[54:55], v[218:219]
	v_pk_fma_f32 v[220:221], v[228:229], v[54:55], v[220:221]
	v_pk_fma_f32 v[222:223], v[230:231], v[54:55], v[222:223]
	v_cvt_pk_f32_fp8_e32 v[224:225], v178
	v_cvt_pk_f32_fp8_e32 v[226:227], v182
	v_cvt_pk_f32_fp8_e32 v[228:229], v186
	v_cvt_pk_f32_fp8_e32 v[230:231], v190
	v_pk_fma_f32 v[216:217], v[224:225], v[56:57], v[216:217]
	v_pk_fma_f32 v[218:219], v[226:227], v[56:57], v[218:219]
	v_pk_fma_f32 v[220:221], v[228:229], v[56:57], v[220:221]
	v_pk_fma_f32 v[222:223], v[230:231], v[56:57], v[222:223]
	v_cvt_pk_f32_fp8_sdwa v[224:225], v178 src0_sel:WORD_1
	v_cvt_pk_f32_fp8_sdwa v[226:227], v182 src0_sel:WORD_1
	v_cvt_pk_f32_fp8_sdwa v[228:229], v186 src0_sel:WORD_1
	v_cvt_pk_f32_fp8_sdwa v[230:231], v190 src0_sel:WORD_1
	v_pk_fma_f32 v[216:217], v[224:225], v[58:59], v[216:217]
	v_pk_fma_f32 v[218:219], v[226:227], v[58:59], v[218:219]
	v_pk_fma_f32 v[220:221], v[228:229], v[58:59], v[220:221]
	v_pk_fma_f32 v[222:223], v[230:231], v[58:59], v[222:223]
	v_cvt_pk_f32_fp8_e32 v[224:225], v179
	v_cvt_pk_f32_fp8_e32 v[226:227], v183
	v_cvt_pk_f32_fp8_e32 v[228:229], v187
	v_cvt_pk_f32_fp8_e32 v[230:231], v191
	v_pk_fma_f32 v[216:217], v[224:225], v[60:61], v[216:217]
	v_pk_fma_f32 v[218:219], v[226:227], v[60:61], v[218:219]
	v_pk_fma_f32 v[220:221], v[228:229], v[60:61], v[220:221]
	v_pk_fma_f32 v[222:223], v[230:231], v[60:61], v[222:223]
	v_cvt_pk_f32_fp8_sdwa v[224:225], v179 src0_sel:WORD_1
	v_cvt_pk_f32_fp8_sdwa v[226:227], v183 src0_sel:WORD_1
	v_cvt_pk_f32_fp8_sdwa v[228:229], v187 src0_sel:WORD_1
	v_cvt_pk_f32_fp8_sdwa v[230:231], v191 src0_sel:WORD_1
	v_pk_fma_f32 v[216:217], v[224:225], v[62:63], v[216:217]
	v_pk_fma_f32 v[218:219], v[226:227], v[62:63], v[218:219]
	v_pk_fma_f32 v[220:221], v[228:229], v[62:63], v[220:221]
	v_pk_fma_f32 v[222:223], v[230:231], v[62:63], v[222:223]
	v_add_f32_e32 v204, v216, v217
	v_add_f32_e32 v205, v218, v219
	v_add_f32_e32 v206, v220, v221
	v_add_f32_e32 v207, v222, v223
	s_nop 0
	v_permlane32_swap_b32_e32 v192, v200
	v_permlane32_swap_b32_e32 v193, v201
	v_permlane32_swap_b32_e32 v194, v202
	v_permlane32_swap_b32_e32 v195, v203
	v_permlane32_swap_b32_e32 v196, v204
	v_permlane32_swap_b32_e32 v197, v205
	v_permlane32_swap_b32_e32 v198, v206
	v_permlane32_swap_b32_e32 v199, v207
	v_add_f32_e32 v192, v192, v200
	v_add_f32_e32 v193, v193, v201
	v_add_f32_e32 v194, v194, v202
	v_add_f32_e32 v195, v195, v203
	v_add_f32_e32 v196, v196, v204
	v_add_f32_e32 v197, v197, v205
	v_add_f32_e32 v198, v198, v206
	v_add_f32_e32 v199, v199, v207
	v_permlane16_swap_b32_e32 v192, v196
	v_permlane16_swap_b32_e32 v193, v197
	v_permlane16_swap_b32_e32 v194, v198
	v_permlane16_swap_b32_e32 v195, v199
	v_add_f32_e32 v192, v192, v196
	v_add_f32_e32 v193, v193, v197
	v_add_f32_e32 v194, v194, v198
	v_add_f32_e32 v195, v195, v199
	v_add_f32_dpp v216, v192, v192 row_ror:8 row_mask:0xf bank_mask:0xf
	v_add_f32_dpp v218, v194, v194 row_ror:8 row_mask:0xf bank_mask:0xf
	v_add_f32_dpp v216, v193, v193 row_ror:8 row_mask:0xf bank_mask:0xc
	v_add_f32_dpp v218, v195, v195 row_ror:8 row_mask:0xf bank_mask:0xc
	s_nop 1
	v_add_f32_dpp v220, v216, v216 row_half_mirror row_mask:0xf bank_mask:0xf
	v_add_f32_dpp v220, v218, v218 row_half_mirror row_mask:0xf bank_mask:0xa
	s_nop 1
	v_add_f32_dpp v220, v220, v220 quad_perm:[1,0,3,2] row_mask:0xf bank_mask:0xf
	s_nop 1
	v_add_f32_dpp v220, v220, v220 quad_perm:[2,3,0,1] row_mask:0xf bank_mask:0xf
	v_mul_f32_e32 v216, v252, v220
	v_fma_f32 v218, |v216|, s72, 1.0
	v_mul_f32_e32 v222, v216, v216
	v_rcp_f32_e32 v218, v218
	v_mul_f32_e32 v222, 0xbf38aa3b, v222
	v_exp_f32_e32 v222, v222
	v_fmamk_f32 v224, v218, 0x3f07dc22, v242
	v_fmaak_f32 v224, v218, v224, 0x3f35f0e3
	v_fmaak_f32 v224, v218, v224, 0xbe11a98e
	v_fmaak_f32 v224, v218, v224, 0x3e027906
	v_mul_f32_e32 v224, v218, v224
	v_mul_f32_e32 v224, v222, v224
	v_mul_f32_e32 v226, v216, v224
	v_fma_f32 v224, -v216, v224, v216
	v_cmp_gt_f32_e32 vcc, 0, v216
	s_nop 1
	v_cndmask_b32_e32 v224, v224, v226, vcc
	v_mul_f32_e32 v224, v249, v224
	v_mul_f32_e32 v224, v253, v224
	ds_write_b32 v211, v224 offset:4992
	v_add_u32_e32 v211, 64, v211
	v_add_u32_e32 v213, 64, v213
	ds_read_b32 v248, v211
	ds_read_b32 v249, v211 offset:4992
	s_add_i32 s21, s21, 4
	s_sub_i32 s90, s90, 1
	s_cmp_eq_u32 s90, 0
	s_cbranch_scc1 .LU_sw0
	s_branch .LU_t3_s0

.LU_t4_s3:
	s_waitcnt lgkmcnt(0)
	v_add_u32_e32 v236, v232, v240
	v_add_u32_e32 v237, v233, v240
	v_add_u32_e32 v238, v234, v240
	v_add_u32_e32 v239, v235, v240
	global_load_dwordx4 v[160:163], v236, s[4:5]
	global_load_dwordx4 v[164:167], v237, s[4:5]
	global_load_dwordx4 v[168:171], v238, s[4:5]
	global_load_dwordx4 v[172:175], v239, s[4:5]
	ds_read_b128 v[232:235], v213 offset:112
	s_waitcnt vmcnt(12)
	v_cvt_pk_f32_fp8_e32 v[224:225], v176
	v_cvt_pk_f32_fp8_e32 v[226:227], v180
	v_cvt_pk_f32_fp8_e32 v[228:229], v184
	v_cvt_pk_f32_fp8_e32 v[230:231], v188
	v_pk_mul_f32 v[216:217], v[224:225], v[64:65]
	v_pk_mul_f32 v[218:219], v[226:227], v[64:65]
	v_pk_mul_f32 v[220:221], v[228:229], v[64:65]
	v_pk_mul_f32 v[222:223], v[230:231], v[64:65]
	v_cvt_pk_f32_fp8_sdwa v[224:225], v176 src0_sel:WORD_1
	v_cvt_pk_f32_fp8_sdwa v[226:227], v180 src0_sel:WORD_1
	v_cvt_pk_f32_fp8_sdwa v[228:229], v184 src0_sel:WORD_1
	v_cvt_pk_f32_fp8_sdwa v[230:231], v188 src0_sel:WORD_1
	v_pk_fma_f32 v[216:217], v[224:225], v[66:67], v[216:217]
	v_pk_fma_f32 v[218:219], v[226:227], v[66:67], v[218:219]
	v_pk_fma_f32 v[220:221], v[228:229], v[66:67], v[220:221]
	v_pk_fma_f32 v[222:223], v[230:231], v[66:67], v[222:223]
	v_cvt_pk_f32_fp8_e32 v[224:225], v177
	v_cvt_pk_f32_fp8_e32 v[226:227], v181
	v_cvt_pk_f32_fp8_e32 v[228:229], v185
	v_cvt_pk_f32_fp8_e32 v[230:231], v189
	v_pk_fma_f32 v[216:217], v[224:225], v[68:69], v[216:217]
	v_pk_fma_f32 v[218:219], v[226:227], v[68:69], v[218:219]
	v_pk_fma_f32 v[220:221], v[228:229], v[68:69], v[220:221]
	v_pk_fma_f32 v[222:223], v[230:231], v[68:69], v[222:223]
	v_cvt_pk_f32_fp8_sdwa v[224:225], v177 src0_sel:WORD_1
	v_cvt_pk_f32_fp8_sdwa v[226:227], v181 src0_sel:WORD_1
	v_cvt_pk_f32_fp8_sdwa v[228:229], v185 src0_sel:WORD_1
	v_cvt_pk_f32_fp8_sdwa v[230:231], v189 src0_sel:WORD_1
	v_pk_fma_f32 v[216:217], v[224:225], v[70:71], v[216:217]
	v_pk_fma_f32 v[218:219], v[226:227], v[70:71], v[218:219]
	v_pk_fma_f32 v[220:221], v[228:229], v[70:71], v[220:221]
	v_pk_fma_f32 v[222:223], v[230:231], v[70:71], v[222:223]
	v_cvt_pk_f32_fp8_e32 v[224:225], v178
	v_cvt_pk_f32_fp8_e32 v[226:227], v182
	v_cvt_pk_f32_fp8_e32 v[228:229], v186
	v_cvt_pk_f32_fp8_e32 v[230:231], v190
	v_pk_fma_f32 v[216:217], v[224:225], v[72:73], v[216:217]
	v_pk_fma_f32 v[218:219], v[226:227], v[72:73], v[218:219]
	v_pk_fma_f32 v[220:221], v[228:229], v[72:73], v[220:221]
	v_pk_fma_f32 v[222:223], v[230:231], v[72:73], v[222:223]
	v_cvt_pk_f32_fp8_sdwa v[224:225], v178 src0_sel:WORD_1
	v_cvt_pk_f32_fp8_sdwa v[226:227], v182 src0_sel:WORD_1
	v_cvt_pk_f32_fp8_sdwa v[228:229], v186 src0_sel:WORD_1
	v_cvt_pk_f32_fp8_sdwa v[230:231], v190 src0_sel:WORD_1
	v_pk_fma_f32 v[216:217], v[224:225], v[74:75], v[216:217]
	v_pk_fma_f32 v[218:219], v[226:227], v[74:75], v[218:219]
	v_pk_fma_f32 v[220:221], v[228:229], v[74:75], v[220:221]
	v_pk_fma_f32 v[222:223], v[230:231], v[74:75], v[222:223]
	v_cvt_pk_f32_fp8_e32 v[224:225], v179
	v_cvt_pk_f32_fp8_e32 v[226:227], v183
	v_cvt_pk_f32_fp8_e32 v[228:229], v187
	v_cvt_pk_f32_fp8_e32 v[230:231], v191
	v_pk_fma_f32 v[216:217], v[224:225], v[76:77], v[216:217]
	v_pk_fma_f32 v[218:219], v[226:227], v[76:77], v[218:219]
	v_pk_fma_f32 v[220:221], v[228:229], v[76:77], v[220:221]
	v_pk_fma_f32 v[222:223], v[230:231], v[76:77], v[222:223]
	v_cvt_pk_f32_fp8_sdwa v[224:225], v179 src0_sel:WORD_1
	v_cvt_pk_f32_fp8_sdwa v[226:227], v183 src0_sel:WORD_1
	v_cvt_pk_f32_fp8_sdwa v[228:229], v187 src0_sel:WORD_1
	v_cvt_pk_f32_fp8_sdwa v[230:231], v191 src0_sel:WORD_1
	v_pk_fma_f32 v[216:217], v[224:225], v[78:79], v[216:217]
	v_pk_fma_f32 v[218:219], v[226:227], v[78:79], v[218:219]
	v_pk_fma_f32 v[220:221], v[228:229], v[78:79], v[220:221]
	v_pk_fma_f32 v[222:223], v[230:231], v[78:79], v[222:223]
	v_add_f32_e32 v204, v216, v217
	v_add_f32_e32 v205, v218, v219
	v_add_f32_e32 v206, v220, v221
	v_add_f32_e32 v207, v222, v223
	s_nop 0
	v_permlane32_swap_b32_e32 v192, v200
	v_permlane32_swap_b32_e32 v193, v201
	v_permlane32_swap_b32_e32 v194, v202
	v_permlane32_swap_b32_e32 v195, v203
	v_permlane32_swap_b32_e32 v196, v204
	v_permlane32_swap_b32_e32 v197, v205
	v_permlane32_swap_b32_e32 v198, v206
	v_permlane32_swap_b32_e32 v199, v207
	v_add_f32_e32 v192, v192, v200
	v_add_f32_e32 v193, v193, v201
	v_add_f32_e32 v194, v194, v202
	v_add_f32_e32 v195, v195, v203
	v_add_f32_e32 v196, v196, v204
	v_add_f32_e32 v197, v197, v205
	v_add_f32_e32 v198, v198, v206
	v_add_f32_e32 v199, v199, v207
	v_permlane16_swap_b32_e32 v192, v196
	v_permlane16_swap_b32_e32 v193, v197
	v_permlane16_swap_b32_e32 v194, v198
	v_permlane16_swap_b32_e32 v195, v199
	v_add_f32_e32 v192, v192, v196
	v_add_f32_e32 v193, v193, v197
	v_add_f32_e32 v194, v194, v198
	v_add_f32_e32 v195, v195, v199
	v_add_f32_dpp v216, v192, v192 row_ror:8 row_mask:0xf bank_mask:0xf
	v_add_f32_dpp v218, v194, v194 row_ror:8 row_mask:0xf bank_mask:0xf
	v_add_f32_dpp v216, v193, v193 row_ror:8 row_mask:0xf bank_mask:0xc
	v_add_f32_dpp v218, v195, v195 row_ror:8 row_mask:0xf bank_mask:0xc
	s_nop 1
	v_add_f32_dpp v220, v216, v216 row_half_mirror row_mask:0xf bank_mask:0xf
	v_add_f32_dpp v220, v218, v218 row_half_mirror row_mask:0xf bank_mask:0xa
	s_nop 1
	v_add_f32_dpp v220, v220, v220 quad_perm:[1,0,3,2] row_mask:0xf bank_mask:0xf
	s_nop 1
	v_add_f32_dpp v220, v220, v220 quad_perm:[2,3,0,1] row_mask:0xf bank_mask:0xf
	v_mul_f32_e32 v216, v252, v220
	v_fma_f32 v218, |v216|, s72, 1.0
	v_mul_f32_e32 v222, v216, v216
	v_rcp_f32_e32 v218, v218
	v_mul_f32_e32 v222, 0xbf38aa3b, v222
	v_exp_f32_e32 v222, v222
	v_fmamk_f32 v224, v218, 0x3f07dc22, v242
	v_fmaak_f32 v224, v218, v224, 0x3f35f0e3
	v_fmaak_f32 v224, v218, v224, 0xbe11a98e
	v_fmaak_f32 v224, v218, v224, 0x3e027906
	v_mul_f32_e32 v224, v218, v224
	v_mul_f32_e32 v224, v222, v224
	v_mul_f32_e32 v226, v216, v224
	v_fma_f32 v224, -v216, v224, v216
	v_cmp_gt_f32_e32 vcc, 0, v216
	s_nop 1
	v_cndmask_b32_e32 v224, v224, v226, vcc
	v_mul_f32_e32 v224, v249, v224
	v_mul_f32_e32 v224, v253, v224
	ds_write_b32 v211, v224 offset:4992
	v_add_u32_e32 v211, 64, v211
	v_add_u32_e32 v213, 64, v213
	ds_read_b32 v248, v211
	ds_read_b32 v249, v211 offset:4992
	s_add_i32 s21, s21, 4
	s_sub_i32 s90, s90, 1
	s_cmp_eq_u32 s90, 0
	s_cbranch_scc1 .LU_sw0
	s_branch .LU_t4_s0

.LU_t5_s3:
	s_waitcnt lgkmcnt(0)
	v_add_u32_e32 v236, v232, v240
	v_add_u32_e32 v237, v233, v240
	v_add_u32_e32 v238, v234, v240
	v_add_u32_e32 v239, v235, v240
	global_load_dwordx4 v[160:163], v236, s[4:5]
	global_load_dwordx4 v[164:167], v237, s[4:5]
	global_load_dwordx4 v[168:171], v238, s[4:5]
	global_load_dwordx4 v[172:175], v239, s[4:5]
	ds_read_b128 v[232:235], v213 offset:112
	s_waitcnt vmcnt(12)
	v_cvt_pk_f32_fp8_e32 v[224:225], v176
	v_cvt_pk_f32_fp8_e32 v[226:227], v180
	v_cvt_pk_f32_fp8_e32 v[228:229], v184
	v_cvt_pk_f32_fp8_e32 v[230:231], v188
	v_pk_mul_f32 v[216:217], v[224:225], v[80:81]
	v_pk_mul_f32 v[218:219], v[226:227], v[80:81]
	v_pk_mul_f32 v[220:221], v[228:229], v[80:81]
	v_pk_mul_f32 v[222:223], v[230:231], v[80:81]
	v_cvt_pk_f32_fp8_sdwa v[224:225], v176 src0_sel:WORD_1
	v_cvt_pk_f32_fp8_sdwa v[226:227], v180 src0_sel:WORD_1
	v_cvt_pk_f32_fp8_sdwa v[228:229], v184 src0_sel:WORD_1
	v_cvt_pk_f32_fp8_sdwa v[230:231], v188 src0_sel:WORD_1
	v_pk_fma_f32 v[216:217], v[224:225], v[82:83], v[216:217]
	v_pk_fma_f32 v[218:219], v[226:227], v[82:83], v[218:219]
	v_pk_fma_f32 v[220:221], v[228:229], v[82:83], v[220:221]
	v_pk_fma_f32 v[222:223], v[230:231], v[82:83], v[222:223]
	v_cvt_pk_f32_fp8_e32 v[224:225], v177
	v_cvt_pk_f32_fp8_e32 v[226:227], v181
	v_cvt_pk_f32_fp8_e32 v[228:229], v185
	v_cvt_pk_f32_fp8_e32 v[230:231], v189
	v_pk_fma_f32 v[216:217], v[224:225], v[84:85], v[216:217]
	v_pk_fma_f32 v[218:219], v[226:227], v[84:85], v[218:219]
	v_pk_fma_f32 v[220:221], v[228:229], v[84:85], v[220:221]
	v_pk_fma_f32 v[222:223], v[230:231], v[84:85], v[222:223]
	v_cvt_pk_f32_fp8_sdwa v[224:225], v177 src0_sel:WORD_1
	v_cvt_pk_f32_fp8_sdwa v[226:227], v181 src0_sel:WORD_1
	v_cvt_pk_f32_fp8_sdwa v[228:229], v185 src0_sel:WORD_1
	v_cvt_pk_f32_fp8_sdwa v[230:231], v189 src0_sel:WORD_1
	v_pk_fma_f32 v[216:217], v[224:225], v[86:87], v[216:217]
	v_pk_fma_f32 v[218:219], v[226:227], v[86:87], v[218:219]
	v_pk_fma_f32 v[220:221], v[228:229], v[86:87], v[220:221]
	v_pk_fma_f32 v[222:223], v[230:231], v[86:87], v[222:223]
	v_cvt_pk_f32_fp8_e32 v[224:225], v178
	v_cvt_pk_f32_fp8_e32 v[226:227], v182
	v_cvt_pk_f32_fp8_e32 v[228:229], v186
	v_cvt_pk_f32_fp8_e32 v[230:231], v190
	v_pk_fma_f32 v[216:217], v[224:225], v[88:89], v[216:217]
	v_pk_fma_f32 v[218:219], v[226:227], v[88:89], v[218:219]
	v_pk_fma_f32 v[220:221], v[228:229], v[88:89], v[220:221]
	v_pk_fma_f32 v[222:223], v[230:231], v[88:89], v[222:223]
	v_cvt_pk_f32_fp8_sdwa v[224:225], v178 src0_sel:WORD_1
	v_cvt_pk_f32_fp8_sdwa v[226:227], v182 src0_sel:WORD_1
	v_cvt_pk_f32_fp8_sdwa v[228:229], v186 src0_sel:WORD_1
	v_cvt_pk_f32_fp8_sdwa v[230:231], v190 src0_sel:WORD_1
	v_pk_fma_f32 v[216:217], v[224:225], v[90:91], v[216:217]
	v_pk_fma_f32 v[218:219], v[226:227], v[90:91], v[218:219]
	v_pk_fma_f32 v[220:221], v[228:229], v[90:91], v[220:221]
	v_pk_fma_f32 v[222:223], v[230:231], v[90:91], v[222:223]
	v_cvt_pk_f32_fp8_e32 v[224:225], v179
	v_cvt_pk_f32_fp8_e32 v[226:227], v183
	v_cvt_pk_f32_fp8_e32 v[228:229], v187
	v_cvt_pk_f32_fp8_e32 v[230:231], v191
	v_pk_fma_f32 v[216:217], v[224:225], v[92:93], v[216:217]
	v_pk_fma_f32 v[218:219], v[226:227], v[92:93], v[218:219]
	v_pk_fma_f32 v[220:221], v[228:229], v[92:93], v[220:221]
	v_pk_fma_f32 v[222:223], v[230:231], v[92:93], v[222:223]
	v_cvt_pk_f32_fp8_sdwa v[224:225], v179 src0_sel:WORD_1
	v_cvt_pk_f32_fp8_sdwa v[226:227], v183 src0_sel:WORD_1
	v_cvt_pk_f32_fp8_sdwa v[228:229], v187 src0_sel:WORD_1
	v_cvt_pk_f32_fp8_sdwa v[230:231], v191 src0_sel:WORD_1
	v_pk_fma_f32 v[216:217], v[224:225], v[94:95], v[216:217]
	v_pk_fma_f32 v[218:219], v[226:227], v[94:95], v[218:219]
	v_pk_fma_f32 v[220:221], v[228:229], v[94:95], v[220:221]
	v_pk_fma_f32 v[222:223], v[230:231], v[94:95], v[222:223]
	v_add_f32_e32 v204, v216, v217
	v_add_f32_e32 v205, v218, v219
	v_add_f32_e32 v206, v220, v221
	v_add_f32_e32 v207, v222, v223
	s_nop 0
	v_permlane32_swap_b32_e32 v192, v200
	v_permlane32_swap_b32_e32 v193, v201
	v_permlane32_swap_b32_e32 v194, v202
	v_permlane32_swap_b32_e32 v195, v203
	v_permlane32_swap_b32_e32 v196, v204
	v_permlane32_swap_b32_e32 v197, v205
	v_permlane32_swap_b32_e32 v198, v206
	v_permlane32_swap_b32_e32 v199, v207
	v_add_f32_e32 v192, v192, v200
	v_add_f32_e32 v193, v193, v201
	v_add_f32_e32 v194, v194, v202
	v_add_f32_e32 v195, v195, v203
	v_add_f32_e32 v196, v196, v204
	v_add_f32_e32 v197, v197, v205
	v_add_f32_e32 v198, v198, v206
	v_add_f32_e32 v199, v199, v207
	v_permlane16_swap_b32_e32 v192, v196
	v_permlane16_swap_b32_e32 v193, v197
	v_permlane16_swap_b32_e32 v194, v198
	v_permlane16_swap_b32_e32 v195, v199
	v_add_f32_e32 v192, v192, v196
	v_add_f32_e32 v193, v193, v197
	v_add_f32_e32 v194, v194, v198
	v_add_f32_e32 v195, v195, v199
	v_add_f32_dpp v216, v192, v192 row_ror:8 row_mask:0xf bank_mask:0xf
	v_add_f32_dpp v218, v194, v194 row_ror:8 row_mask:0xf bank_mask:0xf
	v_add_f32_dpp v216, v193, v193 row_ror:8 row_mask:0xf bank_mask:0xc
	v_add_f32_dpp v218, v195, v195 row_ror:8 row_mask:0xf bank_mask:0xc
	s_nop 1
	v_add_f32_dpp v220, v216, v216 row_half_mirror row_mask:0xf bank_mask:0xf
	v_add_f32_dpp v220, v218, v218 row_half_mirror row_mask:0xf bank_mask:0xa
	s_nop 1
	v_add_f32_dpp v220, v220, v220 quad_perm:[1,0,3,2] row_mask:0xf bank_mask:0xf
	s_nop 1
	v_add_f32_dpp v220, v220, v220 quad_perm:[2,3,0,1] row_mask:0xf bank_mask:0xf
	v_mul_f32_e32 v216, v252, v220
	v_fma_f32 v218, |v216|, s72, 1.0
	v_mul_f32_e32 v222, v216, v216
	v_rcp_f32_e32 v218, v218
	v_mul_f32_e32 v222, 0xbf38aa3b, v222
	v_exp_f32_e32 v222, v222
	v_fmamk_f32 v224, v218, 0x3f07dc22, v242
	v_fmaak_f32 v224, v218, v224, 0x3f35f0e3
	v_fmaak_f32 v224, v218, v224, 0xbe11a98e
	v_fmaak_f32 v224, v218, v224, 0x3e027906
	v_mul_f32_e32 v224, v218, v224
	v_mul_f32_e32 v224, v222, v224
	v_mul_f32_e32 v226, v216, v224
	v_fma_f32 v224, -v216, v224, v216
	v_cmp_gt_f32_e32 vcc, 0, v216
	s_nop 1
	v_cndmask_b32_e32 v224, v224, v226, vcc
	v_mul_f32_e32 v224, v249, v224
	v_mul_f32_e32 v224, v253, v224
	ds_write_b32 v211, v224 offset:4992
	v_add_u32_e32 v211, 64, v211
	v_add_u32_e32 v213, 64, v213
	ds_read_b32 v248, v211
	ds_read_b32 v249, v211 offset:4992
	s_add_i32 s21, s21, 4
	s_sub_i32 s90, s90, 1
	s_cmp_eq_u32 s90, 0
	s_cbranch_scc1 .LU_sw0
	s_branch .LU_t5_s0

.LU_t6_s3:
	s_waitcnt lgkmcnt(0)
	v_add_u32_e32 v236, v232, v240
	v_add_u32_e32 v237, v233, v240
	v_add_u32_e32 v238, v234, v240
	v_add_u32_e32 v239, v235, v240
	global_load_dwordx4 v[160:163], v236, s[4:5]
	global_load_dwordx4 v[164:167], v237, s[4:5]
	global_load_dwordx4 v[168:171], v238, s[4:5]
	global_load_dwordx4 v[172:175], v239, s[4:5]
	ds_read_b128 v[232:235], v213 offset:112
	s_waitcnt vmcnt(12)
	v_cvt_pk_f32_fp8_e32 v[224:225], v176
	v_cvt_pk_f32_fp8_e32 v[226:227], v180
	v_cvt_pk_f32_fp8_e32 v[228:229], v184
	v_cvt_pk_f32_fp8_e32 v[230:231], v188
	v_pk_mul_f32 v[216:217], v[224:225], v[96:97]
	v_pk_mul_f32 v[218:219], v[226:227], v[96:97]
	v_pk_mul_f32 v[220:221], v[228:229], v[96:97]
	v_pk_mul_f32 v[222:223], v[230:231], v[96:97]
	v_cvt_pk_f32_fp8_sdwa v[224:225], v176 src0_sel:WORD_1
	v_cvt_pk_f32_fp8_sdwa v[226:227], v180 src0_sel:WORD_1
	v_cvt_pk_f32_fp8_sdwa v[228:229], v184 src0_sel:WORD_1
	v_cvt_pk_f32_fp8_sdwa v[230:231], v188 src0_sel:WORD_1
	v_pk_fma_f32 v[216:217], v[224:225], v[98:99], v[216:217]
	v_pk_fma_f32 v[218:219], v[226:227], v[98:99], v[218:219]
	v_pk_fma_f32 v[220:221], v[228:229], v[98:99], v[220:221]
	v_pk_fma_f32 v[222:223], v[230:231], v[98:99], v[222:223]
	v_cvt_pk_f32_fp8_e32 v[224:225], v177
	v_cvt_pk_f32_fp8_e32 v[226:227], v181
	v_cvt_pk_f32_fp8_e32 v[228:229], v185
	v_cvt_pk_f32_fp8_e32 v[230:231], v189
	v_pk_fma_f32 v[216:217], v[224:225], v[100:101], v[216:217]
	v_pk_fma_f32 v[218:219], v[226:227], v[100:101], v[218:219]
	v_pk_fma_f32 v[220:221], v[228:229], v[100:101], v[220:221]
	v_pk_fma_f32 v[222:223], v[230:231], v[100:101], v[222:223]
	v_cvt_pk_f32_fp8_sdwa v[224:225], v177 src0_sel:WORD_1
	v_cvt_pk_f32_fp8_sdwa v[226:227], v181 src0_sel:WORD_1
	v_cvt_pk_f32_fp8_sdwa v[228:229], v185 src0_sel:WORD_1
	v_cvt_pk_f32_fp8_sdwa v[230:231], v189 src0_sel:WORD_1
	v_pk_fma_f32 v[216:217], v[224:225], v[102:103], v[216:217]
	v_pk_fma_f32 v[218:219], v[226:227], v[102:103], v[218:219]
	v_pk_fma_f32 v[220:221], v[228:229], v[102:103], v[220:221]
	v_pk_fma_f32 v[222:223], v[230:231], v[102:103], v[222:223]
	v_cvt_pk_f32_fp8_e32 v[224:225], v178
	v_cvt_pk_f32_fp8_e32 v[226:227], v182
	v_cvt_pk_f32_fp8_e32 v[228:229], v186
	v_cvt_pk_f32_fp8_e32 v[230:231], v190
	v_pk_fma_f32 v[216:217], v[224:225], v[104:105], v[216:217]
	v_pk_fma_f32 v[218:219], v[226:227], v[104:105], v[218:219]
	v_pk_fma_f32 v[220:221], v[228:229], v[104:105], v[220:221]
	v_pk_fma_f32 v[222:223], v[230:231], v[104:105], v[222:223]
	v_cvt_pk_f32_fp8_sdwa v[224:225], v178 src0_sel:WORD_1
	v_cvt_pk_f32_fp8_sdwa v[226:227], v182 src0_sel:WORD_1
	v_cvt_pk_f32_fp8_sdwa v[228:229], v186 src0_sel:WORD_1
	v_cvt_pk_f32_fp8_sdwa v[230:231], v190 src0_sel:WORD_1
	v_pk_fma_f32 v[216:217], v[224:225], v[106:107], v[216:217]
	v_pk_fma_f32 v[218:219], v[226:227], v[106:107], v[218:219]
	v_pk_fma_f32 v[220:221], v[228:229], v[106:107], v[220:221]
	v_pk_fma_f32 v[222:223], v[230:231], v[106:107], v[222:223]
	v_cvt_pk_f32_fp8_e32 v[224:225], v179
	v_cvt_pk_f32_fp8_e32 v[226:227], v183
	v_cvt_pk_f32_fp8_e32 v[228:229], v187
	v_cvt_pk_f32_fp8_e32 v[230:231], v191
	v_pk_fma_f32 v[216:217], v[224:225], v[108:109], v[216:217]
	v_pk_fma_f32 v[218:219], v[226:227], v[108:109], v[218:219]
	v_pk_fma_f32 v[220:221], v[228:229], v[108:109], v[220:221]
	v_pk_fma_f32 v[222:223], v[230:231], v[108:109], v[222:223]
	v_cvt_pk_f32_fp8_sdwa v[224:225], v179 src0_sel:WORD_1
	v_cvt_pk_f32_fp8_sdwa v[226:227], v183 src0_sel:WORD_1
	v_cvt_pk_f32_fp8_sdwa v[228:229], v187 src0_sel:WORD_1
	v_cvt_pk_f32_fp8_sdwa v[230:231], v191 src0_sel:WORD_1
	v_pk_fma_f32 v[216:217], v[224:225], v[110:111], v[216:217]
	v_pk_fma_f32 v[218:219], v[226:227], v[110:111], v[218:219]
	v_pk_fma_f32 v[220:221], v[228:229], v[110:111], v[220:221]
	v_pk_fma_f32 v[222:223], v[230:231], v[110:111], v[222:223]
	v_add_f32_e32 v204, v216, v217
	v_add_f32_e32 v205, v218, v219
	v_add_f32_e32 v206, v220, v221
	v_add_f32_e32 v207, v222, v223
	s_nop 0
	v_permlane32_swap_b32_e32 v192, v200
	v_permlane32_swap_b32_e32 v193, v201
	v_permlane32_swap_b32_e32 v194, v202
	v_permlane32_swap_b32_e32 v195, v203
	v_permlane32_swap_b32_e32 v196, v204
	v_permlane32_swap_b32_e32 v197, v205
	v_permlane32_swap_b32_e32 v198, v206
	v_permlane32_swap_b32_e32 v199, v207
	v_add_f32_e32 v192, v192, v200
	v_add_f32_e32 v193, v193, v201
	v_add_f32_e32 v194, v194, v202
	v_add_f32_e32 v195, v195, v203
	v_add_f32_e32 v196, v196, v204
	v_add_f32_e32 v197, v197, v205
	v_add_f32_e32 v198, v198, v206
	v_add_f32_e32 v199, v199, v207
	v_permlane16_swap_b32_e32 v192, v196
	v_permlane16_swap_b32_e32 v193, v197
	v_permlane16_swap_b32_e32 v194, v198
	v_permlane16_swap_b32_e32 v195, v199
	v_add_f32_e32 v192, v192, v196
	v_add_f32_e32 v193, v193, v197
	v_add_f32_e32 v194, v194, v198
	v_add_f32_e32 v195, v195, v199
	v_add_f32_dpp v216, v192, v192 row_ror:8 row_mask:0xf bank_mask:0xf
	v_add_f32_dpp v218, v194, v194 row_ror:8 row_mask:0xf bank_mask:0xf
	v_add_f32_dpp v216, v193, v193 row_ror:8 row_mask:0xf bank_mask:0xc
	v_add_f32_dpp v218, v195, v195 row_ror:8 row_mask:0xf bank_mask:0xc
	s_nop 1
	v_add_f32_dpp v220, v216, v216 row_half_mirror row_mask:0xf bank_mask:0xf
	v_add_f32_dpp v220, v218, v218 row_half_mirror row_mask:0xf bank_mask:0xa
	s_nop 1
	v_add_f32_dpp v220, v220, v220 quad_perm:[1,0,3,2] row_mask:0xf bank_mask:0xf
	s_nop 1
	v_add_f32_dpp v220, v220, v220 quad_perm:[2,3,0,1] row_mask:0xf bank_mask:0xf
	v_mul_f32_e32 v216, v252, v220
	v_fma_f32 v218, |v216|, s72, 1.0
	v_mul_f32_e32 v222, v216, v216
	v_rcp_f32_e32 v218, v218
	v_mul_f32_e32 v222, 0xbf38aa3b, v222
	v_exp_f32_e32 v222, v222
	v_fmamk_f32 v224, v218, 0x3f07dc22, v242
	v_fmaak_f32 v224, v218, v224, 0x3f35f0e3
	v_fmaak_f32 v224, v218, v224, 0xbe11a98e
	v_fmaak_f32 v224, v218, v224, 0x3e027906
	v_mul_f32_e32 v224, v218, v224
	v_mul_f32_e32 v224, v222, v224
	v_mul_f32_e32 v226, v216, v224
	v_fma_f32 v224, -v216, v224, v216
	v_cmp_gt_f32_e32 vcc, 0, v216
	s_nop 1
	v_cndmask_b32_e32 v224, v224, v226, vcc
	v_mul_f32_e32 v224, v249, v224
	v_mul_f32_e32 v224, v253, v224
	ds_write_b32 v211, v224 offset:4992
	v_add_u32_e32 v211, 64, v211
	v_add_u32_e32 v213, 64, v213
	ds_read_b32 v248, v211
	ds_read_b32 v249, v211 offset:4992
	s_add_i32 s21, s21, 4
	s_sub_i32 s90, s90, 1
	s_cmp_eq_u32 s90, 0
	s_cbranch_scc1 .LU_sw0
	s_branch .LU_t6_s0

.LU_t7_s3:
	s_waitcnt lgkmcnt(0)
	v_add_u32_e32 v236, v232, v240
	v_add_u32_e32 v237, v233, v240
	v_add_u32_e32 v238, v234, v240
	v_add_u32_e32 v239, v235, v240
	global_load_dwordx4 v[160:163], v236, s[4:5]
	global_load_dwordx4 v[164:167], v237, s[4:5]
	global_load_dwordx4 v[168:171], v238, s[4:5]
	global_load_dwordx4 v[172:175], v239, s[4:5]
	ds_read_b128 v[232:235], v213 offset:112
	s_waitcnt vmcnt(12)
	v_cvt_pk_f32_fp8_e32 v[224:225], v176
	v_cvt_pk_f32_fp8_e32 v[226:227], v180
	v_cvt_pk_f32_fp8_e32 v[228:229], v184
	v_cvt_pk_f32_fp8_e32 v[230:231], v188
	v_pk_mul_f32 v[216:217], v[224:225], v[112:113]
	v_pk_mul_f32 v[218:219], v[226:227], v[112:113]
	v_pk_mul_f32 v[220:221], v[228:229], v[112:113]
	v_pk_mul_f32 v[222:223], v[230:231], v[112:113]
	v_cvt_pk_f32_fp8_sdwa v[224:225], v176 src0_sel:WORD_1
	v_cvt_pk_f32_fp8_sdwa v[226:227], v180 src0_sel:WORD_1
	v_cvt_pk_f32_fp8_sdwa v[228:229], v184 src0_sel:WORD_1
	v_cvt_pk_f32_fp8_sdwa v[230:231], v188 src0_sel:WORD_1
	v_pk_fma_f32 v[216:217], v[224:225], v[114:115], v[216:217]
	v_pk_fma_f32 v[218:219], v[226:227], v[114:115], v[218:219]
	v_pk_fma_f32 v[220:221], v[228:229], v[114:115], v[220:221]
	v_pk_fma_f32 v[222:223], v[230:231], v[114:115], v[222:223]
	v_cvt_pk_f32_fp8_e32 v[224:225], v177
	v_cvt_pk_f32_fp8_e32 v[226:227], v181
	v_cvt_pk_f32_fp8_e32 v[228:229], v185
	v_cvt_pk_f32_fp8_e32 v[230:231], v189
	v_pk_fma_f32 v[216:217], v[224:225], v[116:117], v[216:217]
	v_pk_fma_f32 v[218:219], v[226:227], v[116:117], v[218:219]
	v_pk_fma_f32 v[220:221], v[228:229], v[116:117], v[220:221]
	v_pk_fma_f32 v[222:223], v[230:231], v[116:117], v[222:223]
	v_cvt_pk_f32_fp8_sdwa v[224:225], v177 src0_sel:WORD_1
	v_cvt_pk_f32_fp8_sdwa v[226:227], v181 src0_sel:WORD_1
	v_cvt_pk_f32_fp8_sdwa v[228:229], v185 src0_sel:WORD_1
	v_cvt_pk_f32_fp8_sdwa v[230:231], v189 src0_sel:WORD_1
	v_pk_fma_f32 v[216:217], v[224:225], v[118:119], v[216:217]
	v_pk_fma_f32 v[218:219], v[226:227], v[118:119], v[218:219]
	v_pk_fma_f32 v[220:221], v[228:229], v[118:119], v[220:221]
	v_pk_fma_f32 v[222:223], v[230:231], v[118:119], v[222:223]
	v_cvt_pk_f32_fp8_e32 v[224:225], v178
	v_cvt_pk_f32_fp8_e32 v[226:227], v182
	v_cvt_pk_f32_fp8_e32 v[228:229], v186
	v_cvt_pk_f32_fp8_e32 v[230:231], v190
	v_pk_fma_f32 v[216:217], v[224:225], v[120:121], v[216:217]
	v_pk_fma_f32 v[218:219], v[226:227], v[120:121], v[218:219]
	v_pk_fma_f32 v[220:221], v[228:229], v[120:121], v[220:221]
	v_pk_fma_f32 v[222:223], v[230:231], v[120:121], v[222:223]
	v_cvt_pk_f32_fp8_sdwa v[224:225], v178 src0_sel:WORD_1
	v_cvt_pk_f32_fp8_sdwa v[226:227], v182 src0_sel:WORD_1
	v_cvt_pk_f32_fp8_sdwa v[228:229], v186 src0_sel:WORD_1
	v_cvt_pk_f32_fp8_sdwa v[230:231], v190 src0_sel:WORD_1
	v_pk_fma_f32 v[216:217], v[224:225], v[122:123], v[216:217]
	v_pk_fma_f32 v[218:219], v[226:227], v[122:123], v[218:219]
	v_pk_fma_f32 v[220:221], v[228:229], v[122:123], v[220:221]
	v_pk_fma_f32 v[222:223], v[230:231], v[122:123], v[222:223]
	v_cvt_pk_f32_fp8_e32 v[224:225], v179
	v_cvt_pk_f32_fp8_e32 v[226:227], v183
	v_cvt_pk_f32_fp8_e32 v[228:229], v187
	v_cvt_pk_f32_fp8_e32 v[230:231], v191
	v_pk_fma_f32 v[216:217], v[224:225], v[124:125], v[216:217]
	v_pk_fma_f32 v[218:219], v[226:227], v[124:125], v[218:219]
	v_pk_fma_f32 v[220:221], v[228:229], v[124:125], v[220:221]
	v_pk_fma_f32 v[222:223], v[230:231], v[124:125], v[222:223]
	v_cvt_pk_f32_fp8_sdwa v[224:225], v179 src0_sel:WORD_1
	v_cvt_pk_f32_fp8_sdwa v[226:227], v183 src0_sel:WORD_1
	v_cvt_pk_f32_fp8_sdwa v[228:229], v187 src0_sel:WORD_1
	v_cvt_pk_f32_fp8_sdwa v[230:231], v191 src0_sel:WORD_1
	v_pk_fma_f32 v[216:217], v[224:225], v[126:127], v[216:217]
	v_pk_fma_f32 v[218:219], v[226:227], v[126:127], v[218:219]
	v_pk_fma_f32 v[220:221], v[228:229], v[126:127], v[220:221]
	v_pk_fma_f32 v[222:223], v[230:231], v[126:127], v[222:223]
	v_add_f32_e32 v204, v216, v217
	v_add_f32_e32 v205, v218, v219
	v_add_f32_e32 v206, v220, v221
	v_add_f32_e32 v207, v222, v223
	s_nop 0
	v_permlane32_swap_b32_e32 v192, v200
	v_permlane32_swap_b32_e32 v193, v201
	v_permlane32_swap_b32_e32 v194, v202
	v_permlane32_swap_b32_e32 v195, v203
	v_permlane32_swap_b32_e32 v196, v204
	v_permlane32_swap_b32_e32 v197, v205
	v_permlane32_swap_b32_e32 v198, v206
	v_permlane32_swap_b32_e32 v199, v207
	v_add_f32_e32 v192, v192, v200
	v_add_f32_e32 v193, v193, v201
	v_add_f32_e32 v194, v194, v202
	v_add_f32_e32 v195, v195, v203
	v_add_f32_e32 v196, v196, v204
	v_add_f32_e32 v197, v197, v205
	v_add_f32_e32 v198, v198, v206
	v_add_f32_e32 v199, v199, v207
	v_permlane16_swap_b32_e32 v192, v196
	v_permlane16_swap_b32_e32 v193, v197
	v_permlane16_swap_b32_e32 v194, v198
	v_permlane16_swap_b32_e32 v195, v199
	v_add_f32_e32 v192, v192, v196
	v_add_f32_e32 v193, v193, v197
	v_add_f32_e32 v194, v194, v198
	v_add_f32_e32 v195, v195, v199
	v_add_f32_dpp v216, v192, v192 row_ror:8 row_mask:0xf bank_mask:0xf
	v_add_f32_dpp v218, v194, v194 row_ror:8 row_mask:0xf bank_mask:0xf
	v_add_f32_dpp v216, v193, v193 row_ror:8 row_mask:0xf bank_mask:0xc
	v_add_f32_dpp v218, v195, v195 row_ror:8 row_mask:0xf bank_mask:0xc
	s_nop 1
	v_add_f32_dpp v220, v216, v216 row_half_mirror row_mask:0xf bank_mask:0xf
	v_add_f32_dpp v220, v218, v218 row_half_mirror row_mask:0xf bank_mask:0xa
	s_nop 1
	v_add_f32_dpp v220, v220, v220 quad_perm:[1,0,3,2] row_mask:0xf bank_mask:0xf
	s_nop 1
	v_add_f32_dpp v220, v220, v220 quad_perm:[2,3,0,1] row_mask:0xf bank_mask:0xf
	v_mul_f32_e32 v216, v252, v220
	v_fma_f32 v218, |v216|, s72, 1.0
	v_mul_f32_e32 v222, v216, v216
	v_rcp_f32_e32 v218, v218
	v_mul_f32_e32 v222, 0xbf38aa3b, v222
	v_exp_f32_e32 v222, v222
	v_fmamk_f32 v224, v218, 0x3f07dc22, v242
	v_fmaak_f32 v224, v218, v224, 0x3f35f0e3
	v_fmaak_f32 v224, v218, v224, 0xbe11a98e
	v_fmaak_f32 v224, v218, v224, 0x3e027906
	v_mul_f32_e32 v224, v218, v224
	v_mul_f32_e32 v224, v222, v224
	v_mul_f32_e32 v226, v216, v224
	v_fma_f32 v224, -v216, v224, v216
	v_cmp_gt_f32_e32 vcc, 0, v216
	s_nop 1
	v_cndmask_b32_e32 v224, v224, v226, vcc
	v_mul_f32_e32 v224, v249, v224
	v_mul_f32_e32 v224, v253, v224
	ds_write_b32 v211, v224 offset:4992
	v_add_u32_e32 v211, 64, v211
	v_add_u32_e32 v213, 64, v213
	ds_read_b32 v248, v211
	ds_read_b32 v249, v211 offset:4992
	s_add_i32 s21, s21, 4
	s_sub_i32 s90, s90, 1
	s_cmp_eq_u32 s90, 0
	s_cbranch_scc1 .LU_sw0
	s_branch .LU_t7_s0
.LU_sw0:
	s_add_i32 s89, s89, 1
	s_cmp_ge_u32 s89, 64
	s_cbranch_scc1 .LU_sw0_end
	s_nop 0
	v_readlane_b32 s90, v212, s89
	s_and_b32 s23, s89, 7
	s_cmp_eq_u32 s90, 0
	s_cbranch_scc1 .LU_sw0
	s_cmp_ge_u32 s23, 4
	s_cbranch_scc1 .LU_sw0_h
	s_cmp_ge_u32 s23, 2
	s_cbranch_scc1 .LU_sw0_23
	s_cmp_eq_u32 s23, 0
	s_cbranch_scc1 .LU_t0_s0
	s_branch .LU_t1_s0

; __device__ __forceinline__ void peer_tile(const Args& A, LAS unsigned char* lds, int tile) {
;     ...
;             for (int q = 0; q < 8; ++q) oacc[tk][q] = (f32x2){0.f, 0.f}; }
.LU_done:
	s_waitcnt vmcnt(0) lgkmcnt(0)
	v_mov_b64_e32 v[0:1], 0
	v_mov_b64_e32 v[2:3], 0
	v_mov_b64_e32 v[4:5], 0
	v_mov_b64_e32 v[6:7], 0
	v_mov_b64_e32 v[8:9], 0
	v_mov_b64_e32 v[10:11], 0
	v_mov_b64_e32 v[12:13], 0
	v_mov_b64_e32 v[14:15], 0
	v_mov_b64_e32 v[16:17], 0
	v_mov_b64_e32 v[18:19], 0
	v_mov_b64_e32 v[20:21], 0
	v_mov_b64_e32 v[22:23], 0
	v_mov_b64_e32 v[24:25], 0
	v_mov_b64_e32 v[26:27], 0
	v_mov_b64_e32 v[28:29], 0
	v_mov_b64_e32 v[30:31], 0
	v_mov_b64_e32 v[32:33], 0
	v_mov_b64_e32 v[34:35], 0
	v_mov_b64_e32 v[36:37], 0
	v_mov_b64_e32 v[38:39], 0
	v_mov_b64_e32 v[40:41], 0
	v_mov_b64_e32 v[42:43], 0
	v_mov_b64_e32 v[44:45], 0
	v_mov_b64_e32 v[46:47], 0
	v_mov_b64_e32 v[48:49], 0
	v_mov_b64_e32 v[50:51], 0
	v_mov_b64_e32 v[52:53], 0
	v_mov_b64_e32 v[54:55], 0
	v_mov_b64_e32 v[56:57], 0
	v_mov_b64_e32 v[58:59], 0
	v_mov_b64_e32 v[60:61], 0
	v_mov_b64_e32 v[62:63], 0
	v_mov_b64_e32 v[64:65], 0
	v_mov_b64_e32 v[66:67], 0
	v_mov_b64_e32 v[68:69], 0
	v_mov_b64_e32 v[70:71], 0
	v_mov_b64_e32 v[72:73], 0
	v_mov_b64_e32 v[74:75], 0
	v_mov_b64_e32 v[76:77], 0
	v_mov_b64_e32 v[78:79], 0
	v_mov_b64_e32 v[80:81], 0
	v_mov_b64_e32 v[82:83], 0
	v_mov_b64_e32 v[84:85], 0
	v_mov_b64_e32 v[86:87], 0
	v_mov_b64_e32 v[88:89], 0
	v_mov_b64_e32 v[90:91], 0
	v_mov_b64_e32 v[92:93], 0
	v_mov_b64_e32 v[94:95], 0
	v_mov_b64_e32 v[96:97], 0
	v_mov_b64_e32 v[98:99], 0
	v_mov_b64_e32 v[100:101], 0
	v_mov_b64_e32 v[102:103], 0
	v_mov_b64_e32 v[104:105], 0
	v_mov_b64_e32 v[106:107], 0
	v_mov_b64_e32 v[108:109], 0
	v_mov_b64_e32 v[110:111], 0
	v_mov_b64_e32 v[112:113], 0
	v_mov_b64_e32 v[114:115], 0
	v_mov_b64_e32 v[116:117], 0
	v_mov_b64_e32 v[118:119], 0
	v_mov_b64_e32 v[120:121], 0
	v_mov_b64_e32 v[122:123], 0
	v_mov_b64_e32 v[124:125], 0
	v_mov_b64_e32 v[126:127], 0
	s_add_i32 s20, s91, 3
	s_and_b32 s20, s20, -4
	s_waitcnt vmcnt(0) lgkmcnt(0)
	v_mov_b32_e32 v213, s22
	ds_read_b128 v[232:235], v213 offset:0
	s_waitcnt lgkmcnt(0)
	v_add_u32_e32 v236, v232, v240
	v_add_u32_e32 v237, v233, v240
	v_add_u32_e32 v238, v234, v240
	v_add_u32_e32 v239, v235, v240
	global_load_dwordx4 v[128:131], v236, s[6:7]
	global_load_dwordx4 v[132:135], v237, s[6:7]
	global_load_dwordx4 v[136:139], v238, s[6:7]
	global_load_dwordx4 v[140:143], v239, s[6:7]
	ds_read_b128 v[232:235], v213 offset:16
	s_waitcnt lgkmcnt(0)
	v_add_u32_e32 v236, v232, v240
	v_add_u32_e32 v237, v233, v240
	v_add_u32_e32 v238, v234, v240
	v_add_u32_e32 v239, v235, v240
	global_load_dwordx4 v[144:147], v236, s[6:7]
	global_load_dwordx4 v[148:151], v237, s[6:7]
	global_load_dwordx4 v[152:155], v238, s[6:7]
	global_load_dwordx4 v[156:159], v239, s[6:7]
	ds_read_b128 v[232:235], v213 offset:32
	s_waitcnt lgkmcnt(0)
	v_add_u32_e32 v236, v232, v240
	v_add_u32_e32 v237, v233, v240
	v_add_u32_e32 v238, v234, v240
	v_add_u32_e32 v239, v235, v240
	global_load_dwordx4 v[160:163], v236, s[6:7]
	global_load_dwordx4 v[164:167], v237, s[6:7]
	global_load_dwordx4 v[168:171], v238, s[6:7]
	global_load_dwordx4 v[172:175], v239, s[6:7]
	ds_read_b128 v[232:235], v213 offset:48
	s_mov_b32 s21, 0
	s_mov_b32 s89, -1
	ds_read_b128 v[248:251], v213 offset:4992
	s_branch .LV_sw0
.LV_t0_s0:
	s_cmp_ge_u32 s21, s20
	s_cbranch_scc1 .LV_done
	s_waitcnt lgkmcnt(0)
	v_add_u32_e32 v236, v232, v240
	v_add_u32_e32 v237, v233, v240
	v_add_u32_e32 v238, v234, v240
	v_add_u32_e32 v239, v235, v240
	global_load_dwordx4 v[176:179], v236, s[6:7]
	global_load_dwordx4 v[180:183], v237, s[6:7]
	global_load_dwordx4 v[184:187], v238, s[6:7]
	global_load_dwordx4 v[188:191], v239, s[6:7]
	ds_read_b128 v[232:235], v213 offset:64
	ds_read_b128 v[252:255], v213 offset:5008
	s_waitcnt vmcnt(12)
	v_cvt_pk_f32_fp8_e32 v[224:225], v128
	v_cvt_pk_f32_fp8_sdwa v[226:227], v128 src0_sel:WORD_1
	v_cvt_pk_f32_fp8_e32 v[228:229], v129
	v_cvt_pk_f32_fp8_sdwa v[230:231], v129 src0_sel:WORD_1
	v_pk_fma_f32 v[0:1], v[224:225], v[248:249], v[0:1] op_sel_hi:[1,0,1]
	v_pk_fma_f32 v[2:3], v[226:227], v[248:249], v[2:3] op_sel_hi:[1,0,1]
	v_pk_fma_f32 v[4:5], v[228:229], v[248:249], v[4:5] op_sel_hi:[1,0,1]
	v_pk_fma_f32 v[6:7], v[230:231], v[248:249], v[6:7] op_sel_hi:[1,0,1]
	v_cvt_pk_f32_fp8_e32 v[224:225], v130
	v_cvt_pk_f32_fp8_sdwa v[226:227], v130 src0_sel:WORD_1
	v_cvt_pk_f32_fp8_e32 v[228:229], v131
	v_cvt_pk_f32_fp8_sdwa v[230:231], v131 src0_sel:WORD_1
	v_pk_fma_f32 v[8:9], v[224:225], v[248:249], v[8:9] op_sel_hi:[1,0,1]
	v_pk_fma_f32 v[10:11], v[226:227], v[248:249], v[10:11] op_sel_hi:[1,0,1]
	v_pk_fma_f32 v[12:13], v[228:229], v[248:249], v[12:13] op_sel_hi:[1,0,1]
	v_pk_fma_f32 v[14:15], v[230:231], v[248:249], v[14:15] op_sel_hi:[1,0,1]
	v_cvt_pk_f32_fp8_e32 v[224:225], v132
	v_cvt_pk_f32_fp8_sdwa v[226:227], v132 src0_sel:WORD_1
	v_cvt_pk_f32_fp8_e32 v[228:229], v133
	v_cvt_pk_f32_fp8_sdwa v[230:231], v133 src0_sel:WORD_1
	v_pk_fma_f32 v[0:1], v[224:225], v[248:249], v[0:1] op_sel:[0,1,0] op_sel_hi:[1,1,1]
	v_pk_fma_f32 v[2:3], v[226:227], v[248:249], v[2:3] op_sel:[0,1,0] op_sel_hi:[1,1,1]
	v_pk_fma_f32 v[4:5], v[228:229], v[248:249], v[4:5] op_sel:[0,1,0] op_sel_hi:[1,1,1]
	v_pk_fma_f32 v[6:7], v[230:231], v[248:249], v[6:7] op_sel:[0,1,0] op_sel_hi:[1,1,1]
	v_cvt_pk_f32_fp8_e32 v[224:225], v134
	v_cvt_pk_f32_fp8_sdwa v[226:227], v134 src0_sel:WORD_1
	v_cvt_pk_f32_fp8_e32 v[228:229], v135
	v_cvt_pk_f32_fp8_sdwa v[230:231], v135 src0_sel:WORD_1
	v_pk_fma_f32 v[8:9], v[224:225], v[248:249], v[8:9] op_sel:[0,1,0] op_sel_hi:[1,1,1]
	v_pk_fma_f32 v[10:11], v[226:227], v[248:249], v[10:11] op_sel:[0,1,0] op_sel_hi:[1,1,1]
	v_pk_fma_f32 v[12:13], v[228:229], v[248:249], v[12:13] op_sel:[0,1,0] op_sel_hi:[1,1,1]
	v_pk_fma_f32 v[14:15], v[230:231], v[248:249], v[14:15] op_sel:[0,1,0] op_sel_hi:[1,1,1]
	v_cvt_pk_f32_fp8_e32 v[224:225], v136
	v_cvt_pk_f32_fp8_sdwa v[226:227], v136 src0_sel:WORD_1
	v_cvt_pk_f32_fp8_e32 v[228:229], v137
	v_cvt_pk_f32_fp8_sdwa v[230:231], v137 src0_sel:WORD_1
	v_pk_fma_f32 v[0:1], v[224:225], v[250:251], v[0:1] op_sel_hi:[1,0,1]
	v_pk_fma_f32 v[2:3], v[226:227], v[250:251], v[2:3] op_sel_hi:[1,0,1]
	v_pk_fma_f32 v[4:5], v[228:229], v[250:251], v[4:5] op_sel_hi:[1,0,1]
	v_pk_fma_f32 v[6:7], v[230:231], v[250:251], v[6:7] op_sel_hi:[1,0,1]
	v_cvt_pk_f32_fp8_e32 v[224:225], v138
	v_cvt_pk_f32_fp8_sdwa v[226:227], v138 src0_sel:WORD_1
	v_cvt_pk_f32_fp8_e32 v[228:229], v139
	v_cvt_pk_f32_fp8_sdwa v[230:231], v139 src0_sel:WORD_1
	v_pk_fma_f32 v[8:9], v[224:225], v[250:251], v[8:9] op_sel_hi:[1,0,1]
	v_pk_fma_f32 v[10:11], v[226:227], v[250:251], v[10:11] op_sel_hi:[1,0,1]
	v_pk_fma_f32 v[12:13], v[228:229], v[250:251], v[12:13] op_sel_hi:[1,0,1]
	v_pk_fma_f32 v[14:15], v[230:231], v[250:251], v[14:15] op_sel_hi:[1,0,1]
	v_cvt_pk_f32_fp8_e32 v[224:225], v140
	v_cvt_pk_f32_fp8_sdwa v[226:227], v140 src0_sel:WORD_1
	v_cvt_pk_f32_fp8_e32 v[228:229], v141
	v_cvt_pk_f32_fp8_sdwa v[230:231], v141 src0_sel:WORD_1
	v_pk_fma_f32 v[0:1], v[224:225], v[250:251], v[0:1] op_sel:[0,1,0] op_sel_hi:[1,1,1]
	v_pk_fma_f32 v[2:3], v[226:227], v[250:251], v[2:3] op_sel:[0,1,0] op_sel_hi:[1,1,1]
	v_pk_fma_f32 v[4:5], v[228:229], v[250:251], v[4:5] op_sel:[0,1,0] op_sel_hi:[1,1,1]
	v_pk_fma_f32 v[6:7], v[230:231], v[250:251], v[6:7] op_sel:[0,1,0] op_sel_hi:[1,1,1]
	v_cvt_pk_f32_fp8_e32 v[224:225], v142
	v_cvt_pk_f32_fp8_sdwa v[226:227], v142 src0_sel:WORD_1
	v_cvt_pk_f32_fp8_e32 v[228:229], v143
	v_cvt_pk_f32_fp8_sdwa v[230:231], v143 src0_sel:WORD_1
	v_pk_fma_f32 v[8:9], v[224:225], v[250:251], v[8:9] op_sel:[0,1,0] op_sel_hi:[1,1,1]
	v_pk_fma_f32 v[10:11], v[226:227], v[250:251], v[10:11] op_sel:[0,1,0] op_sel_hi:[1,1,1]
	v_pk_fma_f32 v[12:13], v[228:229], v[250:251], v[12:13] op_sel:[0,1,0] op_sel_hi:[1,1,1]
	v_pk_fma_f32 v[14:15], v[230:231], v[250:251], v[14:15] op_sel:[0,1,0] op_sel_hi:[1,1,1]
	s_sub_i32 s90, s90, 1
	s_cmp_eq_u32 s90, 0
	s_cbranch_scc1 .LV_sw1
.LV_t0_s1:
	s_waitcnt lgkmcnt(0)
	v_add_u32_e32 v236, v232, v240
	v_add_u32_e32 v237, v233, v240
	v_add_u32_e32 v238, v234, v240
	v_add_u32_e32 v239, v235, v240
	global_load_dwordx4 v[128:131], v236, s[6:7]
	global_load_dwordx4 v[132:135], v237, s[6:7]
	global_load_dwordx4 v[136:139], v238, s[6:7]
	global_load_dwordx4 v[140:143], v239, s[6:7]
	ds_read_b128 v[232:235], v213 offset:80
	ds_read_b128 v[248:251], v213 offset:5024
	s_waitcnt vmcnt(12)
	v_cvt_pk_f32_fp8_e32 v[224:225], v144
	v_cvt_pk_f32_fp8_sdwa v[226:227], v144 src0_sel:WORD_1
	v_cvt_pk_f32_fp8_e32 v[228:229], v145
	v_cvt_pk_f32_fp8_sdwa v[230:231], v145 src0_sel:WORD_1
	v_pk_fma_f32 v[0:1], v[224:225], v[252:253], v[0:1] op_sel_hi:[1,0,1]
	v_pk_fma_f32 v[2:3], v[226:227], v[252:253], v[2:3] op_sel_hi:[1,0,1]
	v_pk_fma_f32 v[4:5], v[228:229], v[252:253], v[4:5] op_sel_hi:[1,0,1]
	v_pk_fma_f32 v[6:7], v[230:231], v[252:253], v[6:7] op_sel_hi:[1,0,1]
	v_cvt_pk_f32_fp8_e32 v[224:225], v146
	v_cvt_pk_f32_fp8_sdwa v[226:227], v146 src0_sel:WORD_1
	v_cvt_pk_f32_fp8_e32 v[228:229], v147
	v_cvt_pk_f32_fp8_sdwa v[230:231], v147 src0_sel:WORD_1
	v_pk_fma_f32 v[8:9], v[224:225], v[252:253], v[8:9] op_sel_hi:[1,0,1]
	v_pk_fma_f32 v[10:11], v[226:227], v[252:253], v[10:11] op_sel_hi:[1,0,1]
	v_pk_fma_f32 v[12:13], v[228:229], v[252:253], v[12:13] op_sel_hi:[1,0,1]
	v_pk_fma_f32 v[14:15], v[230:231], v[252:253], v[14:15] op_sel_hi:[1,0,1]
	v_cvt_pk_f32_fp8_e32 v[224:225], v148
	v_cvt_pk_f32_fp8_sdwa v[226:227], v148 src0_sel:WORD_1
	v_cvt_pk_f32_fp8_e32 v[228:229], v149
	v_cvt_pk_f32_fp8_sdwa v[230:231], v149 src0_sel:WORD_1
	v_pk_fma_f32 v[0:1], v[224:225], v[252:253], v[0:1] op_sel:[0,1,0] op_sel_hi:[1,1,1]
	v_pk_fma_f32 v[2:3], v[226:227], v[252:253], v[2:3] op_sel:[0,1,0] op_sel_hi:[1,1,1]
	v_pk_fma_f32 v[4:5], v[228:229], v[252:253], v[4:5] op_sel:[0,1,0] op_sel_hi:[1,1,1]
	v_pk_fma_f32 v[6:7], v[230:231], v[252:253], v[6:7] op_sel:[0,1,0] op_sel_hi:[1,1,1]
	v_cvt_pk_f32_fp8_e32 v[224:225], v150
	v_cvt_pk_f32_fp8_sdwa v[226:227], v150 src0_sel:WORD_1
	v_cvt_pk_f32_fp8_e32 v[228:229], v151
	v_cvt_pk_f32_fp8_sdwa v[230:231], v151 src0_sel:WORD_1
	v_pk_fma_f32 v[8:9], v[224:225], v[252:253], v[8:9] op_sel:[0,1,0] op_sel_hi:[1,1,1]
	v_pk_fma_f32 v[10:11], v[226:227], v[252:253], v[10:11] op_sel:[0,1,0] op_sel_hi:[1,1,1]
	v_pk_fma_f32 v[12:13], v[228:229], v[252:253], v[12:13] op_sel:[0,1,0] op_sel_hi:[1,1,1]
	v_pk_fma_f32 v[14:15], v[230:231], v[252:253], v[14:15] op_sel:[0,1,0] op_sel_hi:[1,1,1]
	v_cvt_pk_f32_fp8_e32 v[224:225], v152
	v_cvt_pk_f32_fp8_sdwa v[226:227], v152 src0_sel:WORD_1
	v_cvt_pk_f32_fp8_e32 v[228:229], v153
	v_cvt_pk_f32_fp8_sdwa v[230:231], v153 src0_sel:WORD_1
	v_pk_fma_f32 v[0:1], v[224:225], v[254:255], v[0:1] op_sel_hi:[1,0,1]
	v_pk_fma_f32 v[2:3], v[226:227], v[254:255], v[2:3] op_sel_hi:[1,0,1]
	v_pk_fma_f32 v[4:5], v[228:229], v[254:255], v[4:5] op_sel_hi:[1,0,1]
	v_pk_fma_f32 v[6:7], v[230:231], v[254:255], v[6:7] op_sel_hi:[1,0,1]
	v_cvt_pk_f32_fp8_e32 v[224:225], v154
	v_cvt_pk_f32_fp8_sdwa v[226:227], v154 src0_sel:WORD_1
	v_cvt_pk_f32_fp8_e32 v[228:229], v155
	v_cvt_pk_f32_fp8_sdwa v[230:231], v155 src0_sel:WORD_1
	v_pk_fma_f32 v[8:9], v[224:225], v[254:255], v[8:9] op_sel_hi:[1,0,1]
	v_pk_fma_f32 v[10:11], v[226:227], v[254:255], v[10:11] op_sel_hi:[1,0,1]
	v_pk_fma_f32 v[12:13], v[228:229], v[254:255], v[12:13] op_sel_hi:[1,0,1]
	v_pk_fma_f32 v[14:15], v[230:231], v[254:255], v[14:15] op_sel_hi:[1,0,1]
	v_cvt_pk_f32_fp8_e32 v[224:225], v156
	v_cvt_pk_f32_fp8_sdwa v[226:227], v156 src0_sel:WORD_1
	v_cvt_pk_f32_fp8_e32 v[228:229], v157
	v_cvt_pk_f32_fp8_sdwa v[230:231], v157 src0_sel:WORD_1
	v_pk_fma_f32 v[0:1], v[224:225], v[254:255], v[0:1] op_sel:[0,1,0] op_sel_hi:[1,1,1]
	v_pk_fma_f32 v[2:3], v[226:227], v[254:255], v[2:3] op_sel:[0,1,0] op_sel_hi:[1,1,1]
	v_pk_fma_f32 v[4:5], v[228:229], v[254:255], v[4:5] op_sel:[0,1,0] op_sel_hi:[1,1,1]
	v_pk_fma_f32 v[6:7], v[230:231], v[254:255], v[6:7] op_sel:[0,1,0] op_sel_hi:[1,1,1]
	v_cvt_pk_f32_fp8_e32 v[224:225], v158
	v_cvt_pk_f32_fp8_sdwa v[226:227], v158 src0_sel:WORD_1
	v_cvt_pk_f32_fp8_e32 v[228:229], v159
	v_cvt_pk_f32_fp8_sdwa v[230:231], v159 src0_sel:WORD_1
	v_pk_fma_f32 v[8:9], v[224:225], v[254:255], v[8:9] op_sel:[0,1,0] op_sel_hi:[1,1,1]
	v_pk_fma_f32 v[10:11], v[226:227], v[254:255], v[10:11] op_sel:[0,1,0] op_sel_hi:[1,1,1]
	v_pk_fma_f32 v[12:13], v[228:229], v[254:255], v[12:13] op_sel:[0,1,0] op_sel_hi:[1,1,1]
	v_pk_fma_f32 v[14:15], v[230:231], v[254:255], v[14:15] op_sel:[0,1,0] op_sel_hi:[1,1,1]
	s_sub_i32 s90, s90, 1
	s_cmp_eq_u32 s90, 0
	s_cbranch_scc1 .LV_sw2
.LV_t0_s2:
	s_waitcnt lgkmcnt(0)
	v_add_u32_e32 v236, v232, v240
	v_add_u32_e32 v237, v233, v240
	v_add_u32_e32 v238, v234, v240
	v_add_u32_e32 v239, v235, v240
	global_load_dwordx4 v[144:147], v236, s[6:7]
	global_load_dwordx4 v[148:151], v237, s[6:7]
	global_load_dwordx4 v[152:155], v238, s[6:7]
	global_load_dwordx4 v[156:159], v239, s[6:7]
	ds_read_b128 v[232:235], v213 offset:96
	ds_read_b128 v[252:255], v213 offset:5040
	s_waitcnt vmcnt(12)
	v_cvt_pk_f32_fp8_e32 v[224:225], v160
	v_cvt_pk_f32_fp8_sdwa v[226:227], v160 src0_sel:WORD_1
	v_cvt_pk_f32_fp8_e32 v[228:229], v161
	v_cvt_pk_f32_fp8_sdwa v[230:231], v161 src0_sel:WORD_1
	v_pk_fma_f32 v[0:1], v[224:225], v[248:249], v[0:1] op_sel_hi:[1,0,1]
	v_pk_fma_f32 v[2:3], v[226:227], v[248:249], v[2:3] op_sel_hi:[1,0,1]
	v_pk_fma_f32 v[4:5], v[228:229], v[248:249], v[4:5] op_sel_hi:[1,0,1]
	v_pk_fma_f32 v[6:7], v[230:231], v[248:249], v[6:7] op_sel_hi:[1,0,1]
	v_cvt_pk_f32_fp8_e32 v[224:225], v162
	v_cvt_pk_f32_fp8_sdwa v[226:227], v162 src0_sel:WORD_1
	v_cvt_pk_f32_fp8_e32 v[228:229], v163
	v_cvt_pk_f32_fp8_sdwa v[230:231], v163 src0_sel:WORD_1
	v_pk_fma_f32 v[8:9], v[224:225], v[248:249], v[8:9] op_sel_hi:[1,0,1]
	v_pk_fma_f32 v[10:11], v[226:227], v[248:249], v[10:11] op_sel_hi:[1,0,1]
	v_pk_fma_f32 v[12:13], v[228:229], v[248:249], v[12:13] op_sel_hi:[1,0,1]
	v_pk_fma_f32 v[14:15], v[230:231], v[248:249], v[14:15] op_sel_hi:[1,0,1]
	v_cvt_pk_f32_fp8_e32 v[224:225], v164
	v_cvt_pk_f32_fp8_sdwa v[226:227], v164 src0_sel:WORD_1
	v_cvt_pk_f32_fp8_e32 v[228:229], v165
	v_cvt_pk_f32_fp8_sdwa v[230:231], v165 src0_sel:WORD_1
	v_pk_fma_f32 v[0:1], v[224:225], v[248:249], v[0:1] op_sel:[0,1,0] op_sel_hi:[1,1,1]
	v_pk_fma_f32 v[2:3], v[226:227], v[248:249], v[2:3] op_sel:[0,1,0] op_sel_hi:[1,1,1]
	v_pk_fma_f32 v[4:5], v[228:229], v[248:249], v[4:5] op_sel:[0,1,0] op_sel_hi:[1,1,1]
	v_pk_fma_f32 v[6:7], v[230:231], v[248:249], v[6:7] op_sel:[0,1,0] op_sel_hi:[1,1,1]
	v_cvt_pk_f32_fp8_e32 v[224:225], v166
	v_cvt_pk_f32_fp8_sdwa v[226:227], v166 src0_sel:WORD_1
	v_cvt_pk_f32_fp8_e32 v[228:229], v167
	v_cvt_pk_f32_fp8_sdwa v[230:231], v167 src0_sel:WORD_1
	v_pk_fma_f32 v[8:9], v[224:225], v[248:249], v[8:9] op_sel:[0,1,0] op_sel_hi:[1,1,1]
	v_pk_fma_f32 v[10:11], v[226:227], v[248:249], v[10:11] op_sel:[0,1,0] op_sel_hi:[1,1,1]
	v_pk_fma_f32 v[12:13], v[228:229], v[248:249], v[12:13] op_sel:[0,1,0] op_sel_hi:[1,1,1]
	v_pk_fma_f32 v[14:15], v[230:231], v[248:249], v[14:15] op_sel:[0,1,0] op_sel_hi:[1,1,1]
	v_cvt_pk_f32_fp8_e32 v[224:225], v168
	v_cvt_pk_f32_fp8_sdwa v[226:227], v168 src0_sel:WORD_1
	v_cvt_pk_f32_fp8_e32 v[228:229], v169
	v_cvt_pk_f32_fp8_sdwa v[230:231], v169 src0_sel:WORD_1
	v_pk_fma_f32 v[0:1], v[224:225], v[250:251], v[0:1] op_sel_hi:[1,0,1]
	v_pk_fma_f32 v[2:3], v[226:227], v[250:251], v[2:3] op_sel_hi:[1,0,1]
	v_pk_fma_f32 v[4:5], v[228:229], v[250:251], v[4:5] op_sel_hi:[1,0,1]
	v_pk_fma_f32 v[6:7], v[230:231], v[250:251], v[6:7] op_sel_hi:[1,0,1]
	v_cvt_pk_f32_fp8_e32 v[224:225], v170
	v_cvt_pk_f32_fp8_sdwa v[226:227], v170 src0_sel:WORD_1
	v_cvt_pk_f32_fp8_e32 v[228:229], v171
	v_cvt_pk_f32_fp8_sdwa v[230:231], v171 src0_sel:WORD_1
	v_pk_fma_f32 v[8:9], v[224:225], v[250:251], v[8:9] op_sel_hi:[1,0,1]
	v_pk_fma_f32 v[10:11], v[226:227], v[250:251], v[10:11] op_sel_hi:[1,0,1]
	v_pk_fma_f32 v[12:13], v[228:229], v[250:251], v[12:13] op_sel_hi:[1,0,1]
	v_pk_fma_f32 v[14:15], v[230:231], v[250:251], v[14:15] op_sel_hi:[1,0,1]
	v_cvt_pk_f32_fp8_e32 v[224:225], v172
	v_cvt_pk_f32_fp8_sdwa v[226:227], v172 src0_sel:WORD_1
	v_cvt_pk_f32_fp8_e32 v[228:229], v173
	v_cvt_pk_f32_fp8_sdwa v[230:231], v173 src0_sel:WORD_1
	v_pk_fma_f32 v[0:1], v[224:225], v[250:251], v[0:1] op_sel:[0,1,0] op_sel_hi:[1,1,1]
	v_pk_fma_f32 v[2:3], v[226:227], v[250:251], v[2:3] op_sel:[0,1,0] op_sel_hi:[1,1,1]
	v_pk_fma_f32 v[4:5], v[228:229], v[250:251], v[4:5] op_sel:[0,1,0] op_sel_hi:[1,1,1]
	v_pk_fma_f32 v[6:7], v[230:231], v[250:251], v[6:7] op_sel:[0,1,0] op_sel_hi:[1,1,1]
	v_cvt_pk_f32_fp8_e32 v[224:225], v174
	v_cvt_pk_f32_fp8_sdwa v[226:227], v174 src0_sel:WORD_1
	v_cvt_pk_f32_fp8_e32 v[228:229], v175
	v_cvt_pk_f32_fp8_sdwa v[230:231], v175 src0_sel:WORD_1
	v_pk_fma_f32 v[8:9], v[224:225], v[250:251], v[8:9] op_sel:[0,1,0] op_sel_hi:[1,1,1]
	v_pk_fma_f32 v[10:11], v[226:227], v[250:251], v[10:11] op_sel:[0,1,0] op_sel_hi:[1,1,1]
	v_pk_fma_f32 v[12:13], v[228:229], v[250:251], v[12:13] op_sel:[0,1,0] op_sel_hi:[1,1,1]
	v_pk_fma_f32 v[14:15], v[230:231], v[250:251], v[14:15] op_sel:[0,1,0] op_sel_hi:[1,1,1]
	s_sub_i32 s90, s90, 1
	s_cmp_eq_u32 s90, 0
	s_cbranch_scc1 .LV_sw3
.LV_t0_s3:
	s_waitcnt lgkmcnt(0)
	v_add_u32_e32 v236, v232, v240
	v_add_u32_e32 v237, v233, v240
	v_add_u32_e32 v238, v234, v240
	v_add_u32_e32 v239, v235, v240
	global_load_dwordx4 v[160:163], v236, s[6:7]
	global_load_dwordx4 v[164:167], v237, s[6:7]
	global_load_dwordx4 v[168:171], v238, s[6:7]
	global_load_dwordx4 v[172:175], v239, s[6:7]
	ds_read_b128 v[232:235], v213 offset:112
	ds_read_b128 v[248:251], v213 offset:5056
	s_waitcnt vmcnt(12)
	v_cvt_pk_f32_fp8_e32 v[224:225], v176
	v_cvt_pk_f32_fp8_sdwa v[226:227], v176 src0_sel:WORD_1
	v_cvt_pk_f32_fp8_e32 v[228:229], v177
	v_cvt_pk_f32_fp8_sdwa v[230:231], v177 src0_sel:WORD_1
	v_pk_fma_f32 v[0:1], v[224:225], v[252:253], v[0:1] op_sel_hi:[1,0,1]
	v_pk_fma_f32 v[2:3], v[226:227], v[252:253], v[2:3] op_sel_hi:[1,0,1]
	v_pk_fma_f32 v[4:5], v[228:229], v[252:253], v[4:5] op_sel_hi:[1,0,1]
	v_pk_fma_f32 v[6:7], v[230:231], v[252:253], v[6:7] op_sel_hi:[1,0,1]
	v_cvt_pk_f32_fp8_e32 v[224:225], v178
	v_cvt_pk_f32_fp8_sdwa v[226:227], v178 src0_sel:WORD_1
	v_cvt_pk_f32_fp8_e32 v[228:229], v179
	v_cvt_pk_f32_fp8_sdwa v[230:231], v179 src0_sel:WORD_1
	v_pk_fma_f32 v[8:9], v[224:225], v[252:253], v[8:9] op_sel_hi:[1,0,1]
	v_pk_fma_f32 v[10:11], v[226:227], v[252:253], v[10:11] op_sel_hi:[1,0,1]
	v_pk_fma_f32 v[12:13], v[228:229], v[252:253], v[12:13] op_sel_hi:[1,0,1]
	v_pk_fma_f32 v[14:15], v[230:231], v[252:253], v[14:15] op_sel_hi:[1,0,1]
	v_cvt_pk_f32_fp8_e32 v[224:225], v180
	v_cvt_pk_f32_fp8_sdwa v[226:227], v180 src0_sel:WORD_1
	v_cvt_pk_f32_fp8_e32 v[228:229], v181
	v_cvt_pk_f32_fp8_sdwa v[230:231], v181 src0_sel:WORD_1
	v_pk_fma_f32 v[0:1], v[224:225], v[252:253], v[0:1] op_sel:[0,1,0] op_sel_hi:[1,1,1]
	v_pk_fma_f32 v[2:3], v[226:227], v[252:253], v[2:3] op_sel:[0,1,0] op_sel_hi:[1,1,1]
	v_pk_fma_f32 v[4:5], v[228:229], v[252:253], v[4:5] op_sel:[0,1,0] op_sel_hi:[1,1,1]
	v_pk_fma_f32 v[6:7], v[230:231], v[252:253], v[6:7] op_sel:[0,1,0] op_sel_hi:[1,1,1]
	v_cvt_pk_f32_fp8_e32 v[224:225], v182
	v_cvt_pk_f32_fp8_sdwa v[226:227], v182 src0_sel:WORD_1
	v_cvt_pk_f32_fp8_e32 v[228:229], v183
	v_cvt_pk_f32_fp8_sdwa v[230:231], v183 src0_sel:WORD_1
	v_pk_fma_f32 v[8:9], v[224:225], v[252:253], v[8:9] op_sel:[0,1,0] op_sel_hi:[1,1,1]
	v_pk_fma_f32 v[10:11], v[226:227], v[252:253], v[10:11] op_sel:[0,1,0] op_sel_hi:[1,1,1]
	v_pk_fma_f32 v[12:13], v[228:229], v[252:253], v[12:13] op_sel:[0,1,0] op_sel_hi:[1,1,1]
	v_pk_fma_f32 v[14:15], v[230:231], v[252:253], v[14:15] op_sel:[0,1,0] op_sel_hi:[1,1,1]
	v_cvt_pk_f32_fp8_e32 v[224:225], v184
	v_cvt_pk_f32_fp8_sdwa v[226:227], v184 src0_sel:WORD_1
	v_cvt_pk_f32_fp8_e32 v[228:229], v185
	v_cvt_pk_f32_fp8_sdwa v[230:231], v185 src0_sel:WORD_1
	v_pk_fma_f32 v[0:1], v[224:225], v[254:255], v[0:1] op_sel_hi:[1,0,1]
	v_pk_fma_f32 v[2:3], v[226:227], v[254:255], v[2:3] op_sel_hi:[1,0,1]
	v_pk_fma_f32 v[4:5], v[228:229], v[254:255], v[4:5] op_sel_hi:[1,0,1]
	v_pk_fma_f32 v[6:7], v[230:231], v[254:255], v[6:7] op_sel_hi:[1,0,1]
	v_cvt_pk_f32_fp8_e32 v[224:225], v186
	v_cvt_pk_f32_fp8_sdwa v[226:227], v186 src0_sel:WORD_1
	v_cvt_pk_f32_fp8_e32 v[228:229], v187
	v_cvt_pk_f32_fp8_sdwa v[230:231], v187 src0_sel:WORD_1
	v_pk_fma_f32 v[8:9], v[224:225], v[254:255], v[8:9] op_sel_hi:[1,0,1]
	v_pk_fma_f32 v[10:11], v[226:227], v[254:255], v[10:11] op_sel_hi:[1,0,1]
	v_pk_fma_f32 v[12:13], v[228:229], v[254:255], v[12:13] op_sel_hi:[1,0,1]
	v_pk_fma_f32 v[14:15], v[230:231], v[254:255], v[14:15] op_sel_hi:[1,0,1]
	v_cvt_pk_f32_fp8_e32 v[224:225], v188
	v_cvt_pk_f32_fp8_sdwa v[226:227], v188 src0_sel:WORD_1
	v_cvt_pk_f32_fp8_e32 v[228:229], v189
	v_cvt_pk_f32_fp8_sdwa v[230:231], v189 src0_sel:WORD_1
	v_pk_fma_f32 v[0:1], v[224:225], v[254:255], v[0:1] op_sel:[0,1,0] op_sel_hi:[1,1,1]
	v_pk_fma_f32 v[2:3], v[226:227], v[254:255], v[2:3] op_sel:[0,1,0] op_sel_hi:[1,1,1]
	v_pk_fma_f32 v[4:5], v[228:229], v[254:255], v[4:5] op_sel:[0,1,0] op_sel_hi:[1,1,1]
	v_pk_fma_f32 v[6:7], v[230:231], v[254:255], v[6:7] op_sel:[0,1,0] op_sel_hi:[1,1,1]
	v_cvt_pk_f32_fp8_e32 v[224:225], v190
	v_cvt_pk_f32_fp8_sdwa v[226:227], v190 src0_sel:WORD_1
	v_cvt_pk_f32_fp8_e32 v[228:229], v191
	v_cvt_pk_f32_fp8_sdwa v[230:231], v191 src0_sel:WORD_1
	v_pk_fma_f32 v[8:9], v[224:225], v[254:255], v[8:9] op_sel:[0,1,0] op_sel_hi:[1,1,1]
	v_pk_fma_f32 v[10:11], v[226:227], v[254:255], v[10:11] op_sel:[0,1,0] op_sel_hi:[1,1,1]
	v_pk_fma_f32 v[12:13], v[228:229], v[254:255], v[12:13] op_sel:[0,1,0] op_sel_hi:[1,1,1]
	v_pk_fma_f32 v[14:15], v[230:231], v[254:255], v[14:15] op_sel:[0,1,0] op_sel_hi:[1,1,1]
	v_add_u32_e32 v213, 64, v213
	s_add_i32 s21, s21, 4
	s_sub_i32 s90, s90, 1
	s_cmp_eq_u32 s90, 0
	s_cbranch_scc1 .LV_sw0
	s_branch .LV_t0_s0
.LV_t1_s0:
	s_cmp_ge_u32 s21, s20
	s_cbranch_scc1 .LV_done
	s_waitcnt lgkmcnt(0)
	v_add_u32_e32 v236, v232, v240
	v_add_u32_e32 v237, v233, v240
	v_add_u32_e32 v238, v234, v240
	v_add_u32_e32 v239, v235, v240
	global_load_dwordx4 v[176:179], v236, s[6:7]
	global_load_dwordx4 v[180:183], v237, s[6:7]
	global_load_dwordx4 v[184:187], v238, s[6:7]
	global_load_dwordx4 v[188:191], v239, s[6:7]
	ds_read_b128 v[232:235], v213 offset:64
	ds_read_b128 v[252:255], v213 offset:5008
	s_waitcnt vmcnt(12)
	v_cvt_pk_f32_fp8_e32 v[224:225], v128
	v_cvt_pk_f32_fp8_sdwa v[226:227], v128 src0_sel:WORD_1
	v_cvt_pk_f32_fp8_e32 v[228:229], v129
	v_cvt_pk_f32_fp8_sdwa v[230:231], v129 src0_sel:WORD_1
	v_pk_fma_f32 v[16:17], v[224:225], v[248:249], v[16:17] op_sel_hi:[1,0,1]
	v_pk_fma_f32 v[18:19], v[226:227], v[248:249], v[18:19] op_sel_hi:[1,0,1]
	v_pk_fma_f32 v[20:21], v[228:229], v[248:249], v[20:21] op_sel_hi:[1,0,1]
	v_pk_fma_f32 v[22:23], v[230:231], v[248:249], v[22:23] op_sel_hi:[1,0,1]
	v_cvt_pk_f32_fp8_e32 v[224:225], v130
	v_cvt_pk_f32_fp8_sdwa v[226:227], v130 src0_sel:WORD_1
	v_cvt_pk_f32_fp8_e32 v[228:229], v131
	v_cvt_pk_f32_fp8_sdwa v[230:231], v131 src0_sel:WORD_1
	v_pk_fma_f32 v[24:25], v[224:225], v[248:249], v[24:25] op_sel_hi:[1,0,1]
	v_pk_fma_f32 v[26:27], v[226:227], v[248:249], v[26:27] op_sel_hi:[1,0,1]
	v_pk_fma_f32 v[28:29], v[228:229], v[248:249], v[28:29] op_sel_hi:[1,0,1]
	v_pk_fma_f32 v[30:31], v[230:231], v[248:249], v[30:31] op_sel_hi:[1,0,1]
	v_cvt_pk_f32_fp8_e32 v[224:225], v132
	v_cvt_pk_f32_fp8_sdwa v[226:227], v132 src0_sel:WORD_1
	v_cvt_pk_f32_fp8_e32 v[228:229], v133
	v_cvt_pk_f32_fp8_sdwa v[230:231], v133 src0_sel:WORD_1
	v_pk_fma_f32 v[16:17], v[224:225], v[248:249], v[16:17] op_sel:[0,1,0] op_sel_hi:[1,1,1]
	v_pk_fma_f32 v[18:19], v[226:227], v[248:249], v[18:19] op_sel:[0,1,0] op_sel_hi:[1,1,1]
	v_pk_fma_f32 v[20:21], v[228:229], v[248:249], v[20:21] op_sel:[0,1,0] op_sel_hi:[1,1,1]
	v_pk_fma_f32 v[22:23], v[230:231], v[248:249], v[22:23] op_sel:[0,1,0] op_sel_hi:[1,1,1]
	v_cvt_pk_f32_fp8_e32 v[224:225], v134
	v_cvt_pk_f32_fp8_sdwa v[226:227], v134 src0_sel:WORD_1
	v_cvt_pk_f32_fp8_e32 v[228:229], v135
	v_cvt_pk_f32_fp8_sdwa v[230:231], v135 src0_sel:WORD_1
	v_pk_fma_f32 v[24:25], v[224:225], v[248:249], v[24:25] op_sel:[0,1,0] op_sel_hi:[1,1,1]
	v_pk_fma_f32 v[26:27], v[226:227], v[248:249], v[26:27] op_sel:[0,1,0] op_sel_hi:[1,1,1]
	v_pk_fma_f32 v[28:29], v[228:229], v[248:249], v[28:29] op_sel:[0,1,0] op_sel_hi:[1,1,1]
	v_pk_fma_f32 v[30:31], v[230:231], v[248:249], v[30:31] op_sel:[0,1,0] op_sel_hi:[1,1,1]
	v_cvt_pk_f32_fp8_e32 v[224:225], v136
	v_cvt_pk_f32_fp8_sdwa v[226:227], v136 src0_sel:WORD_1
	v_cvt_pk_f32_fp8_e32 v[228:229], v137
	v_cvt_pk_f32_fp8_sdwa v[230:231], v137 src0_sel:WORD_1
	v_pk_fma_f32 v[16:17], v[224:225], v[250:251], v[16:17] op_sel_hi:[1,0,1]
	v_pk_fma_f32 v[18:19], v[226:227], v[250:251], v[18:19] op_sel_hi:[1,0,1]
	v_pk_fma_f32 v[20:21], v[228:229], v[250:251], v[20:21] op_sel_hi:[1,0,1]
	v_pk_fma_f32 v[22:23], v[230:231], v[250:251], v[22:23] op_sel_hi:[1,0,1]
	v_cvt_pk_f32_fp8_e32 v[224:225], v138
	v_cvt_pk_f32_fp8_sdwa v[226:227], v138 src0_sel:WORD_1
	v_cvt_pk_f32_fp8_e32 v[228:229], v139
	v_cvt_pk_f32_fp8_sdwa v[230:231], v139 src0_sel:WORD_1
	v_pk_fma_f32 v[24:25], v[224:225], v[250:251], v[24:25] op_sel_hi:[1,0,1]
	v_pk_fma_f32 v[26:27], v[226:227], v[250:251], v[26:27] op_sel_hi:[1,0,1]
	v_pk_fma_f32 v[28:29], v[228:229], v[250:251], v[28:29] op_sel_hi:[1,0,1]
	v_pk_fma_f32 v[30:31], v[230:231], v[250:251], v[30:31] op_sel_hi:[1,0,1]
	v_cvt_pk_f32_fp8_e32 v[224:225], v140
	v_cvt_pk_f32_fp8_sdwa v[226:227], v140 src0_sel:WORD_1
	v_cvt_pk_f32_fp8_e32 v[228:229], v141
	v_cvt_pk_f32_fp8_sdwa v[230:231], v141 src0_sel:WORD_1
	v_pk_fma_f32 v[16:17], v[224:225], v[250:251], v[16:17] op_sel:[0,1,0] op_sel_hi:[1,1,1]
	v_pk_fma_f32 v[18:19], v[226:227], v[250:251], v[18:19] op_sel:[0,1,0] op_sel_hi:[1,1,1]
	v_pk_fma_f32 v[20:21], v[228:229], v[250:251], v[20:21] op_sel:[0,1,0] op_sel_hi:[1,1,1]
	v_pk_fma_f32 v[22:23], v[230:231], v[250:251], v[22:23] op_sel:[0,1,0] op_sel_hi:[1,1,1]
	v_cvt_pk_f32_fp8_e32 v[224:225], v142
	v_cvt_pk_f32_fp8_sdwa v[226:227], v142 src0_sel:WORD_1
	v_cvt_pk_f32_fp8_e32 v[228:229], v143
	v_cvt_pk_f32_fp8_sdwa v[230:231], v143 src0_sel:WORD_1
	v_pk_fma_f32 v[24:25], v[224:225], v[250:251], v[24:25] op_sel:[0,1,0] op_sel_hi:[1,1,1]
	v_pk_fma_f32 v[26:27], v[226:227], v[250:251], v[26:27] op_sel:[0,1,0] op_sel_hi:[1,1,1]
	v_pk_fma_f32 v[28:29], v[228:229], v[250:251], v[28:29] op_sel:[0,1,0] op_sel_hi:[1,1,1]
	v_pk_fma_f32 v[30:31], v[230:231], v[250:251], v[30:31] op_sel:[0,1,0] op_sel_hi:[1,1,1]
	s_sub_i32 s90, s90, 1
	s_cmp_eq_u32 s90, 0
	s_cbranch_scc1 .LV_sw1
.LV_t1_s1:
	s_waitcnt lgkmcnt(0)
	v_add_u32_e32 v236, v232, v240
	v_add_u32_e32 v237, v233, v240
	v_add_u32_e32 v238, v234, v240
	v_add_u32_e32 v239, v235, v240
	global_load_dwordx4 v[128:131], v236, s[6:7]
	global_load_dwordx4 v[132:135], v237, s[6:7]
	global_load_dwordx4 v[136:139], v238, s[6:7]
	global_load_dwordx4 v[140:143], v239, s[6:7]
	ds_read_b128 v[232:235], v213 offset:80
	ds_read_b128 v[248:251], v213 offset:5024
	s_waitcnt vmcnt(12)
	v_cvt_pk_f32_fp8_e32 v[224:225], v144
	v_cvt_pk_f32_fp8_sdwa v[226:227], v144 src0_sel:WORD_1
	v_cvt_pk_f32_fp8_e32 v[228:229], v145
	v_cvt_pk_f32_fp8_sdwa v[230:231], v145 src0_sel:WORD_1
	v_pk_fma_f32 v[16:17], v[224:225], v[252:253], v[16:17] op_sel_hi:[1,0,1]
	v_pk_fma_f32 v[18:19], v[226:227], v[252:253], v[18:19] op_sel_hi:[1,0,1]
	v_pk_fma_f32 v[20:21], v[228:229], v[252:253], v[20:21] op_sel_hi:[1,0,1]
	v_pk_fma_f32 v[22:23], v[230:231], v[252:253], v[22:23] op_sel_hi:[1,0,1]
	v_cvt_pk_f32_fp8_e32 v[224:225], v146
	v_cvt_pk_f32_fp8_sdwa v[226:227], v146 src0_sel:WORD_1
	v_cvt_pk_f32_fp8_e32 v[228:229], v147
	v_cvt_pk_f32_fp8_sdwa v[230:231], v147 src0_sel:WORD_1
	v_pk_fma_f32 v[24:25], v[224:225], v[252:253], v[24:25] op_sel_hi:[1,0,1]
	v_pk_fma_f32 v[26:27], v[226:227], v[252:253], v[26:27] op_sel_hi:[1,0,1]
	v_pk_fma_f32 v[28:29], v[228:229], v[252:253], v[28:29] op_sel_hi:[1,0,1]
	v_pk_fma_f32 v[30:31], v[230:231], v[252:253], v[30:31] op_sel_hi:[1,0,1]
	v_cvt_pk_f32_fp8_e32 v[224:225], v148
	v_cvt_pk_f32_fp8_sdwa v[226:227], v148 src0_sel:WORD_1
	v_cvt_pk_f32_fp8_e32 v[228:229], v149
	v_cvt_pk_f32_fp8_sdwa v[230:231], v149 src0_sel:WORD_1
	v_pk_fma_f32 v[16:17], v[224:225], v[252:253], v[16:17] op_sel:[0,1,0] op_sel_hi:[1,1,1]
	v_pk_fma_f32 v[18:19], v[226:227], v[252:253], v[18:19] op_sel:[0,1,0] op_sel_hi:[1,1,1]
	v_pk_fma_f32 v[20:21], v[228:229], v[252:253], v[20:21] op_sel:[0,1,0] op_sel_hi:[1,1,1]
	v_pk_fma_f32 v[22:23], v[230:231], v[252:253], v[22:23] op_sel:[0,1,0] op_sel_hi:[1,1,1]
	v_cvt_pk_f32_fp8_e32 v[224:225], v150
	v_cvt_pk_f32_fp8_sdwa v[226:227], v150 src0_sel:WORD_1
	v_cvt_pk_f32_fp8_e32 v[228:229], v151
	v_cvt_pk_f32_fp8_sdwa v[230:231], v151 src0_sel:WORD_1
	v_pk_fma_f32 v[24:25], v[224:225], v[252:253], v[24:25] op_sel:[0,1,0] op_sel_hi:[1,1,1]
	v_pk_fma_f32 v[26:27], v[226:227], v[252:253], v[26:27] op_sel:[0,1,0] op_sel_hi:[1,1,1]
	v_pk_fma_f32 v[28:29], v[228:229], v[252:253], v[28:29] op_sel:[0,1,0] op_sel_hi:[1,1,1]
	v_pk_fma_f32 v[30:31], v[230:231], v[252:253], v[30:31] op_sel:[0,1,0] op_sel_hi:[1,1,1]
	v_cvt_pk_f32_fp8_e32 v[224:225], v152
	v_cvt_pk_f32_fp8_sdwa v[226:227], v152 src0_sel:WORD_1
	v_cvt_pk_f32_fp8_e32 v[228:229], v153
	v_cvt_pk_f32_fp8_sdwa v[230:231], v153 src0_sel:WORD_1
	v_pk_fma_f32 v[16:17], v[224:225], v[254:255], v[16:17] op_sel_hi:[1,0,1]
	v_pk_fma_f32 v[18:19], v[226:227], v[254:255], v[18:19] op_sel_hi:[1,0,1]
	v_pk_fma_f32 v[20:21], v[228:229], v[254:255], v[20:21] op_sel_hi:[1,0,1]
	v_pk_fma_f32 v[22:23], v[230:231], v[254:255], v[22:23] op_sel_hi:[1,0,1]
	v_cvt_pk_f32_fp8_e32 v[224:225], v154
	v_cvt_pk_f32_fp8_sdwa v[226:227], v154 src0_sel:WORD_1
	v_cvt_pk_f32_fp8_e32 v[228:229], v155
	v_cvt_pk_f32_fp8_sdwa v[230:231], v155 src0_sel:WORD_1
	v_pk_fma_f32 v[24:25], v[224:225], v[254:255], v[24:25] op_sel_hi:[1,0,1]
	v_pk_fma_f32 v[26:27], v[226:227], v[254:255], v[26:27] op_sel_hi:[1,0,1]
	v_pk_fma_f32 v[28:29], v[228:229], v[254:255], v[28:29] op_sel_hi:[1,0,1]
	v_pk_fma_f32 v[30:31], v[230:231], v[254:255], v[30:31] op_sel_hi:[1,0,1]
	v_cvt_pk_f32_fp8_e32 v[224:225], v156
	v_cvt_pk_f32_fp8_sdwa v[226:227], v156 src0_sel:WORD_1
	v_cvt_pk_f32_fp8_e32 v[228:229], v157
	v_cvt_pk_f32_fp8_sdwa v[230:231], v157 src0_sel:WORD_1
	v_pk_fma_f32 v[16:17], v[224:225], v[254:255], v[16:17] op_sel:[0,1,0] op_sel_hi:[1,1,1]
	v_pk_fma_f32 v[18:19], v[226:227], v[254:255], v[18:19] op_sel:[0,1,0] op_sel_hi:[1,1,1]
	v_pk_fma_f32 v[20:21], v[228:229], v[254:255], v[20:21] op_sel:[0,1,0] op_sel_hi:[1,1,1]
	v_pk_fma_f32 v[22:23], v[230:231], v[254:255], v[22:23] op_sel:[0,1,0] op_sel_hi:[1,1,1]
	v_cvt_pk_f32_fp8_e32 v[224:225], v158
	v_cvt_pk_f32_fp8_sdwa v[226:227], v158 src0_sel:WORD_1
	v_cvt_pk_f32_fp8_e32 v[228:229], v159
	v_cvt_pk_f32_fp8_sdwa v[230:231], v159 src0_sel:WORD_1
	v_pk_fma_f32 v[24:25], v[224:225], v[254:255], v[24:25] op_sel:[0,1,0] op_sel_hi:[1,1,1]
	v_pk_fma_f32 v[26:27], v[226:227], v[254:255], v[26:27] op_sel:[0,1,0] op_sel_hi:[1,1,1]
	v_pk_fma_f32 v[28:29], v[228:229], v[254:255], v[28:29] op_sel:[0,1,0] op_sel_hi:[1,1,1]
	v_pk_fma_f32 v[30:31], v[230:231], v[254:255], v[30:31] op_sel:[0,1,0] op_sel_hi:[1,1,1]
	s_sub_i32 s90, s90, 1
	s_cmp_eq_u32 s90, 0
	s_cbranch_scc1 .LV_sw2
.LV_t1_s2:
	s_waitcnt lgkmcnt(0)
	v_add_u32_e32 v236, v232, v240
	v_add_u32_e32 v237, v233, v240
	v_add_u32_e32 v238, v234, v240
	v_add_u32_e32 v239, v235, v240
	global_load_dwordx4 v[144:147], v236, s[6:7]
	global_load_dwordx4 v[148:151], v237, s[6:7]
	global_load_dwordx4 v[152:155], v238, s[6:7]
	global_load_dwordx4 v[156:159], v239, s[6:7]
	ds_read_b128 v[232:235], v213 offset:96
	ds_read_b128 v[252:255], v213 offset:5040
	s_waitcnt vmcnt(12)
	v_cvt_pk_f32_fp8_e32 v[224:225], v160
	v_cvt_pk_f32_fp8_sdwa v[226:227], v160 src0_sel:WORD_1
	v_cvt_pk_f32_fp8_e32 v[228:229], v161
	v_cvt_pk_f32_fp8_sdwa v[230:231], v161 src0_sel:WORD_1
	v_pk_fma_f32 v[16:17], v[224:225], v[248:249], v[16:17] op_sel_hi:[1,0,1]
	v_pk_fma_f32 v[18:19], v[226:227], v[248:249], v[18:19] op_sel_hi:[1,0,1]
	v_pk_fma_f32 v[20:21], v[228:229], v[248:249], v[20:21] op_sel_hi:[1,0,1]
	v_pk_fma_f32 v[22:23], v[230:231], v[248:249], v[22:23] op_sel_hi:[1,0,1]
	v_cvt_pk_f32_fp8_e32 v[224:225], v162
	v_cvt_pk_f32_fp8_sdwa v[226:227], v162 src0_sel:WORD_1
	v_cvt_pk_f32_fp8_e32 v[228:229], v163
	v_cvt_pk_f32_fp8_sdwa v[230:231], v163 src0_sel:WORD_1
	v_pk_fma_f32 v[24:25], v[224:225], v[248:249], v[24:25] op_sel_hi:[1,0,1]
	v_pk_fma_f32 v[26:27], v[226:227], v[248:249], v[26:27] op_sel_hi:[1,0,1]
	v_pk_fma_f32 v[28:29], v[228:229], v[248:249], v[28:29] op_sel_hi:[1,0,1]
	v_pk_fma_f32 v[30:31], v[230:231], v[248:249], v[30:31] op_sel_hi:[1,0,1]
	v_cvt_pk_f32_fp8_e32 v[224:225], v164
	v_cvt_pk_f32_fp8_sdwa v[226:227], v164 src0_sel:WORD_1
	v_cvt_pk_f32_fp8_e32 v[228:229], v165
	v_cvt_pk_f32_fp8_sdwa v[230:231], v165 src0_sel:WORD_1
	v_pk_fma_f32 v[16:17], v[224:225], v[248:249], v[16:17] op_sel:[0,1,0] op_sel_hi:[1,1,1]
	v_pk_fma_f32 v[18:19], v[226:227], v[248:249], v[18:19] op_sel:[0,1,0] op_sel_hi:[1,1,1]
	v_pk_fma_f32 v[20:21], v[228:229], v[248:249], v[20:21] op_sel:[0,1,0] op_sel_hi:[1,1,1]
	v_pk_fma_f32 v[22:23], v[230:231], v[248:249], v[22:23] op_sel:[0,1,0] op_sel_hi:[1,1,1]
	v_cvt_pk_f32_fp8_e32 v[224:225], v166
	v_cvt_pk_f32_fp8_sdwa v[226:227], v166 src0_sel:WORD_1
	v_cvt_pk_f32_fp8_e32 v[228:229], v167
	v_cvt_pk_f32_fp8_sdwa v[230:231], v167 src0_sel:WORD_1
	v_pk_fma_f32 v[24:25], v[224:225], v[248:249], v[24:25] op_sel:[0,1,0] op_sel_hi:[1,1,1]
	v_pk_fma_f32 v[26:27], v[226:227], v[248:249], v[26:27] op_sel:[0,1,0] op_sel_hi:[1,1,1]
	v_pk_fma_f32 v[28:29], v[228:229], v[248:249], v[28:29] op_sel:[0,1,0] op_sel_hi:[1,1,1]
	v_pk_fma_f32 v[30:31], v[230:231], v[248:249], v[30:31] op_sel:[0,1,0] op_sel_hi:[1,1,1]
	v_cvt_pk_f32_fp8_e32 v[224:225], v168
	v_cvt_pk_f32_fp8_sdwa v[226:227], v168 src0_sel:WORD_1
	v_cvt_pk_f32_fp8_e32 v[228:229], v169
	v_cvt_pk_f32_fp8_sdwa v[230:231], v169 src0_sel:WORD_1
	v_pk_fma_f32 v[16:17], v[224:225], v[250:251], v[16:17] op_sel_hi:[1,0,1]
	v_pk_fma_f32 v[18:19], v[226:227], v[250:251], v[18:19] op_sel_hi:[1,0,1]
	v_pk_fma_f32 v[20:21], v[228:229], v[250:251], v[20:21] op_sel_hi:[1,0,1]
	v_pk_fma_f32 v[22:23], v[230:231], v[250:251], v[22:23] op_sel_hi:[1,0,1]
	v_cvt_pk_f32_fp8_e32 v[224:225], v170
	v_cvt_pk_f32_fp8_sdwa v[226:227], v170 src0_sel:WORD_1
	v_cvt_pk_f32_fp8_e32 v[228:229], v171
	v_cvt_pk_f32_fp8_sdwa v[230:231], v171 src0_sel:WORD_1
	v_pk_fma_f32 v[24:25], v[224:225], v[250:251], v[24:25] op_sel_hi:[1,0,1]
	v_pk_fma_f32 v[26:27], v[226:227], v[250:251], v[26:27] op_sel_hi:[1,0,1]
	v_pk_fma_f32 v[28:29], v[228:229], v[250:251], v[28:29] op_sel_hi:[1,0,1]
	v_pk_fma_f32 v[30:31], v[230:231], v[250:251], v[30:31] op_sel_hi:[1,0,1]
	v_cvt_pk_f32_fp8_e32 v[224:225], v172
	v_cvt_pk_f32_fp8_sdwa v[226:227], v172 src0_sel:WORD_1
	v_cvt_pk_f32_fp8_e32 v[228:229], v173
	v_cvt_pk_f32_fp8_sdwa v[230:231], v173 src0_sel:WORD_1
	v_pk_fma_f32 v[16:17], v[224:225], v[250:251], v[16:17] op_sel:[0,1,0] op_sel_hi:[1,1,1]
	v_pk_fma_f32 v[18:19], v[226:227], v[250:251], v[18:19] op_sel:[0,1,0] op_sel_hi:[1,1,1]
	v_pk_fma_f32 v[20:21], v[228:229], v[250:251], v[20:21] op_sel:[0,1,0] op_sel_hi:[1,1,1]
	v_pk_fma_f32 v[22:23], v[230:231], v[250:251], v[22:23] op_sel:[0,1,0] op_sel_hi:[1,1,1]
	v_cvt_pk_f32_fp8_e32 v[224:225], v174
	v_cvt_pk_f32_fp8_sdwa v[226:227], v174 src0_sel:WORD_1
	v_cvt_pk_f32_fp8_e32 v[228:229], v175
	v_cvt_pk_f32_fp8_sdwa v[230:231], v175 src0_sel:WORD_1
	v_pk_fma_f32 v[24:25], v[224:225], v[250:251], v[24:25] op_sel:[0,1,0] op_sel_hi:[1,1,1]
	v_pk_fma_f32 v[26:27], v[226:227], v[250:251], v[26:27] op_sel:[0,1,0] op_sel_hi:[1,1,1]
	v_pk_fma_f32 v[28:29], v[228:229], v[250:251], v[28:29] op_sel:[0,1,0] op_sel_hi:[1,1,1]
	v_pk_fma_f32 v[30:31], v[230:231], v[250:251], v[30:31] op_sel:[0,1,0] op_sel_hi:[1,1,1]
	s_sub_i32 s90, s90, 1
	s_cmp_eq_u32 s90, 0
	s_cbranch_scc1 .LV_sw3
.LV_t1_s3:
	s_waitcnt lgkmcnt(0)
	v_add_u32_e32 v236, v232, v240
	v_add_u32_e32 v237, v233, v240
	v_add_u32_e32 v238, v234, v240
	v_add_u32_e32 v239, v235, v240
	global_load_dwordx4 v[160:163], v236, s[6:7]
	global_load_dwordx4 v[164:167], v237, s[6:7]
	global_load_dwordx4 v[168:171], v238, s[6:7]
	global_load_dwordx4 v[172:175], v239, s[6:7]
	ds_read_b128 v[232:235], v213 offset:112
	ds_read_b128 v[248:251], v213 offset:5056
	s_waitcnt vmcnt(12)
	v_cvt_pk_f32_fp8_e32 v[224:225], v176
	v_cvt_pk_f32_fp8_sdwa v[226:227], v176 src0_sel:WORD_1
	v_cvt_pk_f32_fp8_e32 v[228:229], v177
	v_cvt_pk_f32_fp8_sdwa v[230:231], v177 src0_sel:WORD_1
	v_pk_fma_f32 v[16:17], v[224:225], v[252:253], v[16:17] op_sel_hi:[1,0,1]
	v_pk_fma_f32 v[18:19], v[226:227], v[252:253], v[18:19] op_sel_hi:[1,0,1]
	v_pk_fma_f32 v[20:21], v[228:229], v[252:253], v[20:21] op_sel_hi:[1,0,1]
	v_pk_fma_f32 v[22:23], v[230:231], v[252:253], v[22:23] op_sel_hi:[1,0,1]
	v_cvt_pk_f32_fp8_e32 v[224:225], v178
	v_cvt_pk_f32_fp8_sdwa v[226:227], v178 src0_sel:WORD_1
	v_cvt_pk_f32_fp8_e32 v[228:229], v179
	v_cvt_pk_f32_fp8_sdwa v[230:231], v179 src0_sel:WORD_1
	v_pk_fma_f32 v[24:25], v[224:225], v[252:253], v[24:25] op_sel_hi:[1,0,1]
	v_pk_fma_f32 v[26:27], v[226:227], v[252:253], v[26:27] op_sel_hi:[1,0,1]
	v_pk_fma_f32 v[28:29], v[228:229], v[252:253], v[28:29] op_sel_hi:[1,0,1]
	v_pk_fma_f32 v[30:31], v[230:231], v[252:253], v[30:31] op_sel_hi:[1,0,1]
	v_cvt_pk_f32_fp8_e32 v[224:225], v180
	v_cvt_pk_f32_fp8_sdwa v[226:227], v180 src0_sel:WORD_1
	v_cvt_pk_f32_fp8_e32 v[228:229], v181
	v_cvt_pk_f32_fp8_sdwa v[230:231], v181 src0_sel:WORD_1
	v_pk_fma_f32 v[16:17], v[224:225], v[252:253], v[16:17] op_sel:[0,1,0] op_sel_hi:[1,1,1]
	v_pk_fma_f32 v[18:19], v[226:227], v[252:253], v[18:19] op_sel:[0,1,0] op_sel_hi:[1,1,1]
	v_pk_fma_f32 v[20:21], v[228:229], v[252:253], v[20:21] op_sel:[0,1,0] op_sel_hi:[1,1,1]
	v_pk_fma_f32 v[22:23], v[230:231], v[252:253], v[22:23] op_sel:[0,1,0] op_sel_hi:[1,1,1]
	v_cvt_pk_f32_fp8_e32 v[224:225], v182
	v_cvt_pk_f32_fp8_sdwa v[226:227], v182 src0_sel:WORD_1
	v_cvt_pk_f32_fp8_e32 v[228:229], v183
	v_cvt_pk_f32_fp8_sdwa v[230:231], v183 src0_sel:WORD_1
	v_pk_fma_f32 v[24:25], v[224:225], v[252:253], v[24:25] op_sel:[0,1,0] op_sel_hi:[1,1,1]
	v_pk_fma_f32 v[26:27], v[226:227], v[252:253], v[26:27] op_sel:[0,1,0] op_sel_hi:[1,1,1]
	v_pk_fma_f32 v[28:29], v[228:229], v[252:253], v[28:29] op_sel:[0,1,0] op_sel_hi:[1,1,1]
	v_pk_fma_f32 v[30:31], v[230:231], v[252:253], v[30:31] op_sel:[0,1,0] op_sel_hi:[1,1,1]
	v_cvt_pk_f32_fp8_e32 v[224:225], v184
	v_cvt_pk_f32_fp8_sdwa v[226:227], v184 src0_sel:WORD_1
	v_cvt_pk_f32_fp8_e32 v[228:229], v185
	v_cvt_pk_f32_fp8_sdwa v[230:231], v185 src0_sel:WORD_1
	v_pk_fma_f32 v[16:17], v[224:225], v[254:255], v[16:17] op_sel_hi:[1,0,1]
	v_pk_fma_f32 v[18:19], v[226:227], v[254:255], v[18:19] op_sel_hi:[1,0,1]
	v_pk_fma_f32 v[20:21], v[228:229], v[254:255], v[20:21] op_sel_hi:[1,0,1]
	v_pk_fma_f32 v[22:23], v[230:231], v[254:255], v[22:23] op_sel_hi:[1,0,1]
	v_cvt_pk_f32_fp8_e32 v[224:225], v186
	v_cvt_pk_f32_fp8_sdwa v[226:227], v186 src0_sel:WORD_1
	v_cvt_pk_f32_fp8_e32 v[228:229], v187
	v_cvt_pk_f32_fp8_sdwa v[230:231], v187 src0_sel:WORD_1
	v_pk_fma_f32 v[24:25], v[224:225], v[254:255], v[24:25] op_sel_hi:[1,0,1]
	v_pk_fma_f32 v[26:27], v[226:227], v[254:255], v[26:27] op_sel_hi:[1,0,1]
	v_pk_fma_f32 v[28:29], v[228:229], v[254:255], v[28:29] op_sel_hi:[1,0,1]
	v_pk_fma_f32 v[30:31], v[230:231], v[254:255], v[30:31] op_sel_hi:[1,0,1]
	v_cvt_pk_f32_fp8_e32 v[224:225], v188
	v_cvt_pk_f32_fp8_sdwa v[226:227], v188 src0_sel:WORD_1
	v_cvt_pk_f32_fp8_e32 v[228:229], v189
	v_cvt_pk_f32_fp8_sdwa v[230:231], v189 src0_sel:WORD_1
	v_pk_fma_f32 v[16:17], v[224:225], v[254:255], v[16:17] op_sel:[0,1,0] op_sel_hi:[1,1,1]
	v_pk_fma_f32 v[18:19], v[226:227], v[254:255], v[18:19] op_sel:[0,1,0] op_sel_hi:[1,1,1]
	v_pk_fma_f32 v[20:21], v[228:229], v[254:255], v[20:21] op_sel:[0,1,0] op_sel_hi:[1,1,1]
	v_pk_fma_f32 v[22:23], v[230:231], v[254:255], v[22:23] op_sel:[0,1,0] op_sel_hi:[1,1,1]
	v_cvt_pk_f32_fp8_e32 v[224:225], v190
	v_cvt_pk_f32_fp8_sdwa v[226:227], v190 src0_sel:WORD_1
	v_cvt_pk_f32_fp8_e32 v[228:229], v191
	v_cvt_pk_f32_fp8_sdwa v[230:231], v191 src0_sel:WORD_1
	v_pk_fma_f32 v[24:25], v[224:225], v[254:255], v[24:25] op_sel:[0,1,0] op_sel_hi:[1,1,1]
	v_pk_fma_f32 v[26:27], v[226:227], v[254:255], v[26:27] op_sel:[0,1,0] op_sel_hi:[1,1,1]
	v_pk_fma_f32 v[28:29], v[228:229], v[254:255], v[28:29] op_sel:[0,1,0] op_sel_hi:[1,1,1]
	v_pk_fma_f32 v[30:31], v[230:231], v[254:255], v[30:31] op_sel:[0,1,0] op_sel_hi:[1,1,1]
	v_add_u32_e32 v213, 64, v213
	s_add_i32 s21, s21, 4
	s_sub_i32 s90, s90, 1
	s_cmp_eq_u32 s90, 0
	s_cbranch_scc1 .LV_sw0
	s_branch .LV_t1_s0
.LV_t2_s0:
	s_cmp_ge_u32 s21, s20
	s_cbranch_scc1 .LV_done
	s_waitcnt lgkmcnt(0)
	v_add_u32_e32 v236, v232, v240
	v_add_u32_e32 v237, v233, v240
	v_add_u32_e32 v238, v234, v240
	v_add_u32_e32 v239, v235, v240
	global_load_dwordx4 v[176:179], v236, s[6:7]
	global_load_dwordx4 v[180:183], v237, s[6:7]
	global_load_dwordx4 v[184:187], v238, s[6:7]
	global_load_dwordx4 v[188:191], v239, s[6:7]
	ds_read_b128 v[232:235], v213 offset:64
	ds_read_b128 v[252:255], v213 offset:5008
	s_waitcnt vmcnt(12)
	v_cvt_pk_f32_fp8_e32 v[224:225], v128
	v_cvt_pk_f32_fp8_sdwa v[226:227], v128 src0_sel:WORD_1
	v_cvt_pk_f32_fp8_e32 v[228:229], v129
	v_cvt_pk_f32_fp8_sdwa v[230:231], v129 src0_sel:WORD_1
	v_pk_fma_f32 v[32:33], v[224:225], v[248:249], v[32:33] op_sel_hi:[1,0,1]
	v_pk_fma_f32 v[34:35], v[226:227], v[248:249], v[34:35] op_sel_hi:[1,0,1]
	v_pk_fma_f32 v[36:37], v[228:229], v[248:249], v[36:37] op_sel_hi:[1,0,1]
	v_pk_fma_f32 v[38:39], v[230:231], v[248:249], v[38:39] op_sel_hi:[1,0,1]
	v_cvt_pk_f32_fp8_e32 v[224:225], v130
	v_cvt_pk_f32_fp8_sdwa v[226:227], v130 src0_sel:WORD_1
	v_cvt_pk_f32_fp8_e32 v[228:229], v131
	v_cvt_pk_f32_fp8_sdwa v[230:231], v131 src0_sel:WORD_1
	v_pk_fma_f32 v[40:41], v[224:225], v[248:249], v[40:41] op_sel_hi:[1,0,1]
	v_pk_fma_f32 v[42:43], v[226:227], v[248:249], v[42:43] op_sel_hi:[1,0,1]
	v_pk_fma_f32 v[44:45], v[228:229], v[248:249], v[44:45] op_sel_hi:[1,0,1]
	v_pk_fma_f32 v[46:47], v[230:231], v[248:249], v[46:47] op_sel_hi:[1,0,1]
	v_cvt_pk_f32_fp8_e32 v[224:225], v132
	v_cvt_pk_f32_fp8_sdwa v[226:227], v132 src0_sel:WORD_1
	v_cvt_pk_f32_fp8_e32 v[228:229], v133
	v_cvt_pk_f32_fp8_sdwa v[230:231], v133 src0_sel:WORD_1
	v_pk_fma_f32 v[32:33], v[224:225], v[248:249], v[32:33] op_sel:[0,1,0] op_sel_hi:[1,1,1]
	v_pk_fma_f32 v[34:35], v[226:227], v[248:249], v[34:35] op_sel:[0,1,0] op_sel_hi:[1,1,1]
	v_pk_fma_f32 v[36:37], v[228:229], v[248:249], v[36:37] op_sel:[0,1,0] op_sel_hi:[1,1,1]
	v_pk_fma_f32 v[38:39], v[230:231], v[248:249], v[38:39] op_sel:[0,1,0] op_sel_hi:[1,1,1]
	v_cvt_pk_f32_fp8_e32 v[224:225], v134
	v_cvt_pk_f32_fp8_sdwa v[226:227], v134 src0_sel:WORD_1
	v_cvt_pk_f32_fp8_e32 v[228:229], v135
	v_cvt_pk_f32_fp8_sdwa v[230:231], v135 src0_sel:WORD_1
	v_pk_fma_f32 v[40:41], v[224:225], v[248:249], v[40:41] op_sel:[0,1,0] op_sel_hi:[1,1,1]
	v_pk_fma_f32 v[42:43], v[226:227], v[248:249], v[42:43] op_sel:[0,1,0] op_sel_hi:[1,1,1]
	v_pk_fma_f32 v[44:45], v[228:229], v[248:249], v[44:45] op_sel:[0,1,0] op_sel_hi:[1,1,1]
	v_pk_fma_f32 v[46:47], v[230:231], v[248:249], v[46:47] op_sel:[0,1,0] op_sel_hi:[1,1,1]
	v_cvt_pk_f32_fp8_e32 v[224:225], v136
	v_cvt_pk_f32_fp8_sdwa v[226:227], v136 src0_sel:WORD_1
	v_cvt_pk_f32_fp8_e32 v[228:229], v137
	v_cvt_pk_f32_fp8_sdwa v[230:231], v137 src0_sel:WORD_1
	v_pk_fma_f32 v[32:33], v[224:225], v[250:251], v[32:33] op_sel_hi:[1,0,1]
	v_pk_fma_f32 v[34:35], v[226:227], v[250:251], v[34:35] op_sel_hi:[1,0,1]
	v_pk_fma_f32 v[36:37], v[228:229], v[250:251], v[36:37] op_sel_hi:[1,0,1]
	v_pk_fma_f32 v[38:39], v[230:231], v[250:251], v[38:39] op_sel_hi:[1,0,1]
	v_cvt_pk_f32_fp8_e32 v[224:225], v138
	v_cvt_pk_f32_fp8_sdwa v[226:227], v138 src0_sel:WORD_1
	v_cvt_pk_f32_fp8_e32 v[228:229], v139
	v_cvt_pk_f32_fp8_sdwa v[230:231], v139 src0_sel:WORD_1
	v_pk_fma_f32 v[40:41], v[224:225], v[250:251], v[40:41] op_sel_hi:[1,0,1]
	v_pk_fma_f32 v[42:43], v[226:227], v[250:251], v[42:43] op_sel_hi:[1,0,1]
	v_pk_fma_f32 v[44:45], v[228:229], v[250:251], v[44:45] op_sel_hi:[1,0,1]
	v_pk_fma_f32 v[46:47], v[230:231], v[250:251], v[46:47] op_sel_hi:[1,0,1]
	v_cvt_pk_f32_fp8_e32 v[224:225], v140
	v_cvt_pk_f32_fp8_sdwa v[226:227], v140 src0_sel:WORD_1
	v_cvt_pk_f32_fp8_e32 v[228:229], v141
	v_cvt_pk_f32_fp8_sdwa v[230:231], v141 src0_sel:WORD_1
	v_pk_fma_f32 v[32:33], v[224:225], v[250:251], v[32:33] op_sel:[0,1,0] op_sel_hi:[1,1,1]
	v_pk_fma_f32 v[34:35], v[226:227], v[250:251], v[34:35] op_sel:[0,1,0] op_sel_hi:[1,1,1]
	v_pk_fma_f32 v[36:37], v[228:229], v[250:251], v[36:37] op_sel:[0,1,0] op_sel_hi:[1,1,1]
	v_pk_fma_f32 v[38:39], v[230:231], v[250:251], v[38:39] op_sel:[0,1,0] op_sel_hi:[1,1,1]
	v_cvt_pk_f32_fp8_e32 v[224:225], v142
	v_cvt_pk_f32_fp8_sdwa v[226:227], v142 src0_sel:WORD_1
	v_cvt_pk_f32_fp8_e32 v[228:229], v143
	v_cvt_pk_f32_fp8_sdwa v[230:231], v143 src0_sel:WORD_1
	v_pk_fma_f32 v[40:41], v[224:225], v[250:251], v[40:41] op_sel:[0,1,0] op_sel_hi:[1,1,1]
	v_pk_fma_f32 v[42:43], v[226:227], v[250:251], v[42:43] op_sel:[0,1,0] op_sel_hi:[1,1,1]
	v_pk_fma_f32 v[44:45], v[228:229], v[250:251], v[44:45] op_sel:[0,1,0] op_sel_hi:[1,1,1]
	v_pk_fma_f32 v[46:47], v[230:231], v[250:251], v[46:47] op_sel:[0,1,0] op_sel_hi:[1,1,1]
	s_sub_i32 s90, s90, 1
	s_cmp_eq_u32 s90, 0
	s_cbranch_scc1 .LV_sw1
.LV_t2_s1:
	s_waitcnt lgkmcnt(0)
	v_add_u32_e32 v236, v232, v240
	v_add_u32_e32 v237, v233, v240
	v_add_u32_e32 v238, v234, v240
	v_add_u32_e32 v239, v235, v240
	global_load_dwordx4 v[128:131], v236, s[6:7]
	global_load_dwordx4 v[132:135], v237, s[6:7]
	global_load_dwordx4 v[136:139], v238, s[6:7]
	global_load_dwordx4 v[140:143], v239, s[6:7]
	ds_read_b128 v[232:235], v213 offset:80
	ds_read_b128 v[248:251], v213 offset:5024
	s_waitcnt vmcnt(12)
	v_cvt_pk_f32_fp8_e32 v[224:225], v144
	v_cvt_pk_f32_fp8_sdwa v[226:227], v144 src0_sel:WORD_1
	v_cvt_pk_f32_fp8_e32 v[228:229], v145
	v_cvt_pk_f32_fp8_sdwa v[230:231], v145 src0_sel:WORD_1
	v_pk_fma_f32 v[32:33], v[224:225], v[252:253], v[32:33] op_sel_hi:[1,0,1]
	v_pk_fma_f32 v[34:35], v[226:227], v[252:253], v[34:35] op_sel_hi:[1,0,1]
	v_pk_fma_f32 v[36:37], v[228:229], v[252:253], v[36:37] op_sel_hi:[1,0,1]
	v_pk_fma_f32 v[38:39], v[230:231], v[252:253], v[38:39] op_sel_hi:[1,0,1]
	v_cvt_pk_f32_fp8_e32 v[224:225], v146
	v_cvt_pk_f32_fp8_sdwa v[226:227], v146 src0_sel:WORD_1
	v_cvt_pk_f32_fp8_e32 v[228:229], v147
	v_cvt_pk_f32_fp8_sdwa v[230:231], v147 src0_sel:WORD_1
	v_pk_fma_f32 v[40:41], v[224:225], v[252:253], v[40:41] op_sel_hi:[1,0,1]
	v_pk_fma_f32 v[42:43], v[226:227], v[252:253], v[42:43] op_sel_hi:[1,0,1]
	v_pk_fma_f32 v[44:45], v[228:229], v[252:253], v[44:45] op_sel_hi:[1,0,1]
	v_pk_fma_f32 v[46:47], v[230:231], v[252:253], v[46:47] op_sel_hi:[1,0,1]
	v_cvt_pk_f32_fp8_e32 v[224:225], v148
	v_cvt_pk_f32_fp8_sdwa v[226:227], v148 src0_sel:WORD_1
	v_cvt_pk_f32_fp8_e32 v[228:229], v149
	v_cvt_pk_f32_fp8_sdwa v[230:231], v149 src0_sel:WORD_1
	v_pk_fma_f32 v[32:33], v[224:225], v[252:253], v[32:33] op_sel:[0,1,0] op_sel_hi:[1,1,1]
	v_pk_fma_f32 v[34:35], v[226:227], v[252:253], v[34:35] op_sel:[0,1,0] op_sel_hi:[1,1,1]
	v_pk_fma_f32 v[36:37], v[228:229], v[252:253], v[36:37] op_sel:[0,1,0] op_sel_hi:[1,1,1]
	v_pk_fma_f32 v[38:39], v[230:231], v[252:253], v[38:39] op_sel:[0,1,0] op_sel_hi:[1,1,1]
	v_cvt_pk_f32_fp8_e32 v[224:225], v150
	v_cvt_pk_f32_fp8_sdwa v[226:227], v150 src0_sel:WORD_1
	v_cvt_pk_f32_fp8_e32 v[228:229], v151
	v_cvt_pk_f32_fp8_sdwa v[230:231], v151 src0_sel:WORD_1
	v_pk_fma_f32 v[40:41], v[224:225], v[252:253], v[40:41] op_sel:[0,1,0] op_sel_hi:[1,1,1]
	v_pk_fma_f32 v[42:43], v[226:227], v[252:253], v[42:43] op_sel:[0,1,0] op_sel_hi:[1,1,1]
	v_pk_fma_f32 v[44:45], v[228:229], v[252:253], v[44:45] op_sel:[0,1,0] op_sel_hi:[1,1,1]
	v_pk_fma_f32 v[46:47], v[230:231], v[252:253], v[46:47] op_sel:[0,1,0] op_sel_hi:[1,1,1]
	v_cvt_pk_f32_fp8_e32 v[224:225], v152
	v_cvt_pk_f32_fp8_sdwa v[226:227], v152 src0_sel:WORD_1
	v_cvt_pk_f32_fp8_e32 v[228:229], v153
	v_cvt_pk_f32_fp8_sdwa v[230:231], v153 src0_sel:WORD_1
	v_pk_fma_f32 v[32:33], v[224:225], v[254:255], v[32:33] op_sel_hi:[1,0,1]
	v_pk_fma_f32 v[34:35], v[226:227], v[254:255], v[34:35] op_sel_hi:[1,0,1]
	v_pk_fma_f32 v[36:37], v[228:229], v[254:255], v[36:37] op_sel_hi:[1,0,1]
	v_pk_fma_f32 v[38:39], v[230:231], v[254:255], v[38:39] op_sel_hi:[1,0,1]
	v_cvt_pk_f32_fp8_e32 v[224:225], v154
	v_cvt_pk_f32_fp8_sdwa v[226:227], v154 src0_sel:WORD_1
	v_cvt_pk_f32_fp8_e32 v[228:229], v155
	v_cvt_pk_f32_fp8_sdwa v[230:231], v155 src0_sel:WORD_1
	v_pk_fma_f32 v[40:41], v[224:225], v[254:255], v[40:41] op_sel_hi:[1,0,1]
	v_pk_fma_f32 v[42:43], v[226:227], v[254:255], v[42:43] op_sel_hi:[1,0,1]
	v_pk_fma_f32 v[44:45], v[228:229], v[254:255], v[44:45] op_sel_hi:[1,0,1]
	v_pk_fma_f32 v[46:47], v[230:231], v[254:255], v[46:47] op_sel_hi:[1,0,1]
	v_cvt_pk_f32_fp8_e32 v[224:225], v156
	v_cvt_pk_f32_fp8_sdwa v[226:227], v156 src0_sel:WORD_1
	v_cvt_pk_f32_fp8_e32 v[228:229], v157
	v_cvt_pk_f32_fp8_sdwa v[230:231], v157 src0_sel:WORD_1
	v_pk_fma_f32 v[32:33], v[224:225], v[254:255], v[32:33] op_sel:[0,1,0] op_sel_hi:[1,1,1]
	v_pk_fma_f32 v[34:35], v[226:227], v[254:255], v[34:35] op_sel:[0,1,0] op_sel_hi:[1,1,1]
	v_pk_fma_f32 v[36:37], v[228:229], v[254:255], v[36:37] op_sel:[0,1,0] op_sel_hi:[1,1,1]
	v_pk_fma_f32 v[38:39], v[230:231], v[254:255], v[38:39] op_sel:[0,1,0] op_sel_hi:[1,1,1]
	v_cvt_pk_f32_fp8_e32 v[224:225], v158
	v_cvt_pk_f32_fp8_sdwa v[226:227], v158 src0_sel:WORD_1
	v_cvt_pk_f32_fp8_e32 v[228:229], v159
	v_cvt_pk_f32_fp8_sdwa v[230:231], v159 src0_sel:WORD_1
	v_pk_fma_f32 v[40:41], v[224:225], v[254:255], v[40:41] op_sel:[0,1,0] op_sel_hi:[1,1,1]
	v_pk_fma_f32 v[42:43], v[226:227], v[254:255], v[42:43] op_sel:[0,1,0] op_sel_hi:[1,1,1]
	v_pk_fma_f32 v[44:45], v[228:229], v[254:255], v[44:45] op_sel:[0,1,0] op_sel_hi:[1,1,1]
	v_pk_fma_f32 v[46:47], v[230:231], v[254:255], v[46:47] op_sel:[0,1,0] op_sel_hi:[1,1,1]
	s_sub_i32 s90, s90, 1
	s_cmp_eq_u32 s90, 0
	s_cbranch_scc1 .LV_sw2
.LV_t2_s2:
	s_waitcnt lgkmcnt(0)
	v_add_u32_e32 v236, v232, v240
	v_add_u32_e32 v237, v233, v240
	v_add_u32_e32 v238, v234, v240
	v_add_u32_e32 v239, v235, v240
	global_load_dwordx4 v[144:147], v236, s[6:7]
	global_load_dwordx4 v[148:151], v237, s[6:7]
	global_load_dwordx4 v[152:155], v238, s[6:7]
	global_load_dwordx4 v[156:159], v239, s[6:7]
	ds_read_b128 v[232:235], v213 offset:96
	ds_read_b128 v[252:255], v213 offset:5040
	s_waitcnt vmcnt(12)
	v_cvt_pk_f32_fp8_e32 v[224:225], v160
	v_cvt_pk_f32_fp8_sdwa v[226:227], v160 src0_sel:WORD_1
	v_cvt_pk_f32_fp8_e32 v[228:229], v161
	v_cvt_pk_f32_fp8_sdwa v[230:231], v161 src0_sel:WORD_1
	v_pk_fma_f32 v[32:33], v[224:225], v[248:249], v[32:33] op_sel_hi:[1,0,1]
	v_pk_fma_f32 v[34:35], v[226:227], v[248:249], v[34:35] op_sel_hi:[1,0,1]
	v_pk_fma_f32 v[36:37], v[228:229], v[248:249], v[36:37] op_sel_hi:[1,0,1]
	v_pk_fma_f32 v[38:39], v[230:231], v[248:249], v[38:39] op_sel_hi:[1,0,1]
	v_cvt_pk_f32_fp8_e32 v[224:225], v162
	v_cvt_pk_f32_fp8_sdwa v[226:227], v162 src0_sel:WORD_1
	v_cvt_pk_f32_fp8_e32 v[228:229], v163
	v_cvt_pk_f32_fp8_sdwa v[230:231], v163 src0_sel:WORD_1
	v_pk_fma_f32 v[40:41], v[224:225], v[248:249], v[40:41] op_sel_hi:[1,0,1]
	v_pk_fma_f32 v[42:43], v[226:227], v[248:249], v[42:43] op_sel_hi:[1,0,1]
	v_pk_fma_f32 v[44:45], v[228:229], v[248:249], v[44:45] op_sel_hi:[1,0,1]
	v_pk_fma_f32 v[46:47], v[230:231], v[248:249], v[46:47] op_sel_hi:[1,0,1]
	v_cvt_pk_f32_fp8_e32 v[224:225], v164
	v_cvt_pk_f32_fp8_sdwa v[226:227], v164 src0_sel:WORD_1
	v_cvt_pk_f32_fp8_e32 v[228:229], v165
	v_cvt_pk_f32_fp8_sdwa v[230:231], v165 src0_sel:WORD_1
	v_pk_fma_f32 v[32:33], v[224:225], v[248:249], v[32:33] op_sel:[0,1,0] op_sel_hi:[1,1,1]
	v_pk_fma_f32 v[34:35], v[226:227], v[248:249], v[34:35] op_sel:[0,1,0] op_sel_hi:[1,1,1]
	v_pk_fma_f32 v[36:37], v[228:229], v[248:249], v[36:37] op_sel:[0,1,0] op_sel_hi:[1,1,1]
	v_pk_fma_f32 v[38:39], v[230:231], v[248:249], v[38:39] op_sel:[0,1,0] op_sel_hi:[1,1,1]
	v_cvt_pk_f32_fp8_e32 v[224:225], v166
	v_cvt_pk_f32_fp8_sdwa v[226:227], v166 src0_sel:WORD_1
	v_cvt_pk_f32_fp8_e32 v[228:229], v167
	v_cvt_pk_f32_fp8_sdwa v[230:231], v167 src0_sel:WORD_1
	v_pk_fma_f32 v[40:41], v[224:225], v[248:249], v[40:41] op_sel:[0,1,0] op_sel_hi:[1,1,1]
	v_pk_fma_f32 v[42:43], v[226:227], v[248:249], v[42:43] op_sel:[0,1,0] op_sel_hi:[1,1,1]
	v_pk_fma_f32 v[44:45], v[228:229], v[248:249], v[44:45] op_sel:[0,1,0] op_sel_hi:[1,1,1]
	v_pk_fma_f32 v[46:47], v[230:231], v[248:249], v[46:47] op_sel:[0,1,0] op_sel_hi:[1,1,1]
	v_cvt_pk_f32_fp8_e32 v[224:225], v168
	v_cvt_pk_f32_fp8_sdwa v[226:227], v168 src0_sel:WORD_1
	v_cvt_pk_f32_fp8_e32 v[228:229], v169
	v_cvt_pk_f32_fp8_sdwa v[230:231], v169 src0_sel:WORD_1
	v_pk_fma_f32 v[32:33], v[224:225], v[250:251], v[32:33] op_sel_hi:[1,0,1]
	v_pk_fma_f32 v[34:35], v[226:227], v[250:251], v[34:35] op_sel_hi:[1,0,1]
	v_pk_fma_f32 v[36:37], v[228:229], v[250:251], v[36:37] op_sel_hi:[1,0,1]
	v_pk_fma_f32 v[38:39], v[230:231], v[250:251], v[38:39] op_sel_hi:[1,0,1]
	v_cvt_pk_f32_fp8_e32 v[224:225], v170
	v_cvt_pk_f32_fp8_sdwa v[226:227], v170 src0_sel:WORD_1
	v_cvt_pk_f32_fp8_e32 v[228:229], v171
	v_cvt_pk_f32_fp8_sdwa v[230:231], v171 src0_sel:WORD_1
	v_pk_fma_f32 v[40:41], v[224:225], v[250:251], v[40:41] op_sel_hi:[1,0,1]
	v_pk_fma_f32 v[42:43], v[226:227], v[250:251], v[42:43] op_sel_hi:[1,0,1]
	v_pk_fma_f32 v[44:45], v[228:229], v[250:251], v[44:45] op_sel_hi:[1,0,1]
	v_pk_fma_f32 v[46:47], v[230:231], v[250:251], v[46:47] op_sel_hi:[1,0,1]
	v_cvt_pk_f32_fp8_e32 v[224:225], v172
	v_cvt_pk_f32_fp8_sdwa v[226:227], v172 src0_sel:WORD_1
	v_cvt_pk_f32_fp8_e32 v[228:229], v173
	v_cvt_pk_f32_fp8_sdwa v[230:231], v173 src0_sel:WORD_1
	v_pk_fma_f32 v[32:33], v[224:225], v[250:251], v[32:33] op_sel:[0,1,0] op_sel_hi:[1,1,1]
	v_pk_fma_f32 v[34:35], v[226:227], v[250:251], v[34:35] op_sel:[0,1,0] op_sel_hi:[1,1,1]
	v_pk_fma_f32 v[36:37], v[228:229], v[250:251], v[36:37] op_sel:[0,1,0] op_sel_hi:[1,1,1]
	v_pk_fma_f32 v[38:39], v[230:231], v[250:251], v[38:39] op_sel:[0,1,0] op_sel_hi:[1,1,1]
	v_cvt_pk_f32_fp8_e32 v[224:225], v174
	v_cvt_pk_f32_fp8_sdwa v[226:227], v174 src0_sel:WORD_1
	v_cvt_pk_f32_fp8_e32 v[228:229], v175
	v_cvt_pk_f32_fp8_sdwa v[230:231], v175 src0_sel:WORD_1
	v_pk_fma_f32 v[40:41], v[224:225], v[250:251], v[40:41] op_sel:[0,1,0] op_sel_hi:[1,1,1]
	v_pk_fma_f32 v[42:43], v[226:227], v[250:251], v[42:43] op_sel:[0,1,0] op_sel_hi:[1,1,1]
	v_pk_fma_f32 v[44:45], v[228:229], v[250:251], v[44:45] op_sel:[0,1,0] op_sel_hi:[1,1,1]
	v_pk_fma_f32 v[46:47], v[230:231], v[250:251], v[46:47] op_sel:[0,1,0] op_sel_hi:[1,1,1]
	s_sub_i32 s90, s90, 1
	s_cmp_eq_u32 s90, 0
	s_cbranch_scc1 .LV_sw3
.LV_t2_s3:
	s_waitcnt lgkmcnt(0)
	v_add_u32_e32 v236, v232, v240
	v_add_u32_e32 v237, v233, v240
	v_add_u32_e32 v238, v234, v240
	v_add_u32_e32 v239, v235, v240
	global_load_dwordx4 v[160:163], v236, s[6:7]
	global_load_dwordx4 v[164:167], v237, s[6:7]
	global_load_dwordx4 v[168:171], v238, s[6:7]
	global_load_dwordx4 v[172:175], v239, s[6:7]
	ds_read_b128 v[232:235], v213 offset:112
	ds_read_b128 v[248:251], v213 offset:5056
	s_waitcnt vmcnt(12)
	v_cvt_pk_f32_fp8_e32 v[224:225], v176
	v_cvt_pk_f32_fp8_sdwa v[226:227], v176 src0_sel:WORD_1
	v_cvt_pk_f32_fp8_e32 v[228:229], v177
	v_cvt_pk_f32_fp8_sdwa v[230:231], v177 src0_sel:WORD_1
	v_pk_fma_f32 v[32:33], v[224:225], v[252:253], v[32:33] op_sel_hi:[1,0,1]
	v_pk_fma_f32 v[34:35], v[226:227], v[252:253], v[34:35] op_sel_hi:[1,0,1]
	v_pk_fma_f32 v[36:37], v[228:229], v[252:253], v[36:37] op_sel_hi:[1,0,1]
	v_pk_fma_f32 v[38:39], v[230:231], v[252:253], v[38:39] op_sel_hi:[1,0,1]
	v_cvt_pk_f32_fp8_e32 v[224:225], v178
	v_cvt_pk_f32_fp8_sdwa v[226:227], v178 src0_sel:WORD_1
	v_cvt_pk_f32_fp8_e32 v[228:229], v179
	v_cvt_pk_f32_fp8_sdwa v[230:231], v179 src0_sel:WORD_1
	v_pk_fma_f32 v[40:41], v[224:225], v[252:253], v[40:41] op_sel_hi:[1,0,1]
	v_pk_fma_f32 v[42:43], v[226:227], v[252:253], v[42:43] op_sel_hi:[1,0,1]
	v_pk_fma_f32 v[44:45], v[228:229], v[252:253], v[44:45] op_sel_hi:[1,0,1]
	v_pk_fma_f32 v[46:47], v[230:231], v[252:253], v[46:47] op_sel_hi:[1,0,1]
	v_cvt_pk_f32_fp8_e32 v[224:225], v180
	v_cvt_pk_f32_fp8_sdwa v[226:227], v180 src0_sel:WORD_1
	v_cvt_pk_f32_fp8_e32 v[228:229], v181
	v_cvt_pk_f32_fp8_sdwa v[230:231], v181 src0_sel:WORD_1
	v_pk_fma_f32 v[32:33], v[224:225], v[252:253], v[32:33] op_sel:[0,1,0] op_sel_hi:[1,1,1]
	v_pk_fma_f32 v[34:35], v[226:227], v[252:253], v[34:35] op_sel:[0,1,0] op_sel_hi:[1,1,1]
	v_pk_fma_f32 v[36:37], v[228:229], v[252:253], v[36:37] op_sel:[0,1,0] op_sel_hi:[1,1,1]
	v_pk_fma_f32 v[38:39], v[230:231], v[252:253], v[38:39] op_sel:[0,1,0] op_sel_hi:[1,1,1]
	v_cvt_pk_f32_fp8_e32 v[224:225], v182
	v_cvt_pk_f32_fp8_sdwa v[226:227], v182 src0_sel:WORD_1
	v_cvt_pk_f32_fp8_e32 v[228:229], v183
	v_cvt_pk_f32_fp8_sdwa v[230:231], v183 src0_sel:WORD_1
	v_pk_fma_f32 v[40:41], v[224:225], v[252:253], v[40:41] op_sel:[0,1,0] op_sel_hi:[1,1,1]
	v_pk_fma_f32 v[42:43], v[226:227], v[252:253], v[42:43] op_sel:[0,1,0] op_sel_hi:[1,1,1]
	v_pk_fma_f32 v[44:45], v[228:229], v[252:253], v[44:45] op_sel:[0,1,0] op_sel_hi:[1,1,1]
	v_pk_fma_f32 v[46:47], v[230:231], v[252:253], v[46:47] op_sel:[0,1,0] op_sel_hi:[1,1,1]
	v_cvt_pk_f32_fp8_e32 v[224:225], v184
	v_cvt_pk_f32_fp8_sdwa v[226:227], v184 src0_sel:WORD_1
	v_cvt_pk_f32_fp8_e32 v[228:229], v185
	v_cvt_pk_f32_fp8_sdwa v[230:231], v185 src0_sel:WORD_1
	v_pk_fma_f32 v[32:33], v[224:225], v[254:255], v[32:33] op_sel_hi:[1,0,1]
	v_pk_fma_f32 v[34:35], v[226:227], v[254:255], v[34:35] op_sel_hi:[1,0,1]
	v_pk_fma_f32 v[36:37], v[228:229], v[254:255], v[36:37] op_sel_hi:[1,0,1]
	v_pk_fma_f32 v[38:39], v[230:231], v[254:255], v[38:39] op_sel_hi:[1,0,1]
	v_cvt_pk_f32_fp8_e32 v[224:225], v186
	v_cvt_pk_f32_fp8_sdwa v[226:227], v186 src0_sel:WORD_1
	v_cvt_pk_f32_fp8_e32 v[228:229], v187
	v_cvt_pk_f32_fp8_sdwa v[230:231], v187 src0_sel:WORD_1
	v_pk_fma_f32 v[40:41], v[224:225], v[254:255], v[40:41] op_sel_hi:[1,0,1]
	v_pk_fma_f32 v[42:43], v[226:227], v[254:255], v[42:43] op_sel_hi:[1,0,1]
	v_pk_fma_f32 v[44:45], v[228:229], v[254:255], v[44:45] op_sel_hi:[1,0,1]
	v_pk_fma_f32 v[46:47], v[230:231], v[254:255], v[46:47] op_sel_hi:[1,0,1]
	v_cvt_pk_f32_fp8_e32 v[224:225], v188
	v_cvt_pk_f32_fp8_sdwa v[226:227], v188 src0_sel:WORD_1
	v_cvt_pk_f32_fp8_e32 v[228:229], v189
	v_cvt_pk_f32_fp8_sdwa v[230:231], v189 src0_sel:WORD_1
	v_pk_fma_f32 v[32:33], v[224:225], v[254:255], v[32:33] op_sel:[0,1,0] op_sel_hi:[1,1,1]
	v_pk_fma_f32 v[34:35], v[226:227], v[254:255], v[34:35] op_sel:[0,1,0] op_sel_hi:[1,1,1]
	v_pk_fma_f32 v[36:37], v[228:229], v[254:255], v[36:37] op_sel:[0,1,0] op_sel_hi:[1,1,1]
	v_pk_fma_f32 v[38:39], v[230:231], v[254:255], v[38:39] op_sel:[0,1,0] op_sel_hi:[1,1,1]
	v_cvt_pk_f32_fp8_e32 v[224:225], v190
	v_cvt_pk_f32_fp8_sdwa v[226:227], v190 src0_sel:WORD_1
	v_cvt_pk_f32_fp8_e32 v[228:229], v191
	v_cvt_pk_f32_fp8_sdwa v[230:231], v191 src0_sel:WORD_1
	v_pk_fma_f32 v[40:41], v[224:225], v[254:255], v[40:41] op_sel:[0,1,0] op_sel_hi:[1,1,1]
	v_pk_fma_f32 v[42:43], v[226:227], v[254:255], v[42:43] op_sel:[0,1,0] op_sel_hi:[1,1,1]
	v_pk_fma_f32 v[44:45], v[228:229], v[254:255], v[44:45] op_sel:[0,1,0] op_sel_hi:[1,1,1]
	v_pk_fma_f32 v[46:47], v[230:231], v[254:255], v[46:47] op_sel:[0,1,0] op_sel_hi:[1,1,1]
	v_add_u32_e32 v213, 64, v213
	s_add_i32 s21, s21, 4
	s_sub_i32 s90, s90, 1
	s_cmp_eq_u32 s90, 0
	s_cbranch_scc1 .LV_sw0
	s_branch .LV_t2_s0
.LV_t3_s0:
	s_cmp_ge_u32 s21, s20
	s_cbranch_scc1 .LV_done
	s_waitcnt lgkmcnt(0)
	v_add_u32_e32 v236, v232, v240
	v_add_u32_e32 v237, v233, v240
	v_add_u32_e32 v238, v234, v240
	v_add_u32_e32 v239, v235, v240
	global_load_dwordx4 v[176:179], v236, s[6:7]
	global_load_dwordx4 v[180:183], v237, s[6:7]
	global_load_dwordx4 v[184:187], v238, s[6:7]
	global_load_dwordx4 v[188:191], v239, s[6:7]
	ds_read_b128 v[232:235], v213 offset:64
	ds_read_b128 v[252:255], v213 offset:5008
	s_waitcnt vmcnt(12)
	v_cvt_pk_f32_fp8_e32 v[224:225], v128
	v_cvt_pk_f32_fp8_sdwa v[226:227], v128 src0_sel:WORD_1
	v_cvt_pk_f32_fp8_e32 v[228:229], v129
	v_cvt_pk_f32_fp8_sdwa v[230:231], v129 src0_sel:WORD_1
	v_pk_fma_f32 v[48:49], v[224:225], v[248:249], v[48:49] op_sel_hi:[1,0,1]
	v_pk_fma_f32 v[50:51], v[226:227], v[248:249], v[50:51] op_sel_hi:[1,0,1]
	v_pk_fma_f32 v[52:53], v[228:229], v[248:249], v[52:53] op_sel_hi:[1,0,1]
	v_pk_fma_f32 v[54:55], v[230:231], v[248:249], v[54:55] op_sel_hi:[1,0,1]
	v_cvt_pk_f32_fp8_e32 v[224:225], v130
	v_cvt_pk_f32_fp8_sdwa v[226:227], v130 src0_sel:WORD_1
	v_cvt_pk_f32_fp8_e32 v[228:229], v131
	v_cvt_pk_f32_fp8_sdwa v[230:231], v131 src0_sel:WORD_1
	v_pk_fma_f32 v[56:57], v[224:225], v[248:249], v[56:57] op_sel_hi:[1,0,1]
	v_pk_fma_f32 v[58:59], v[226:227], v[248:249], v[58:59] op_sel_hi:[1,0,1]
	v_pk_fma_f32 v[60:61], v[228:229], v[248:249], v[60:61] op_sel_hi:[1,0,1]
	v_pk_fma_f32 v[62:63], v[230:231], v[248:249], v[62:63] op_sel_hi:[1,0,1]
	v_cvt_pk_f32_fp8_e32 v[224:225], v132
	v_cvt_pk_f32_fp8_sdwa v[226:227], v132 src0_sel:WORD_1
	v_cvt_pk_f32_fp8_e32 v[228:229], v133
	v_cvt_pk_f32_fp8_sdwa v[230:231], v133 src0_sel:WORD_1
	v_pk_fma_f32 v[48:49], v[224:225], v[248:249], v[48:49] op_sel:[0,1,0] op_sel_hi:[1,1,1]
	v_pk_fma_f32 v[50:51], v[226:227], v[248:249], v[50:51] op_sel:[0,1,0] op_sel_hi:[1,1,1]
	v_pk_fma_f32 v[52:53], v[228:229], v[248:249], v[52:53] op_sel:[0,1,0] op_sel_hi:[1,1,1]
	v_pk_fma_f32 v[54:55], v[230:231], v[248:249], v[54:55] op_sel:[0,1,0] op_sel_hi:[1,1,1]
	v_cvt_pk_f32_fp8_e32 v[224:225], v134
	v_cvt_pk_f32_fp8_sdwa v[226:227], v134 src0_sel:WORD_1
	v_cvt_pk_f32_fp8_e32 v[228:229], v135
	v_cvt_pk_f32_fp8_sdwa v[230:231], v135 src0_sel:WORD_1
	v_pk_fma_f32 v[56:57], v[224:225], v[248:249], v[56:57] op_sel:[0,1,0] op_sel_hi:[1,1,1]
	v_pk_fma_f32 v[58:59], v[226:227], v[248:249], v[58:59] op_sel:[0,1,0] op_sel_hi:[1,1,1]
	v_pk_fma_f32 v[60:61], v[228:229], v[248:249], v[60:61] op_sel:[0,1,0] op_sel_hi:[1,1,1]
	v_pk_fma_f32 v[62:63], v[230:231], v[248:249], v[62:63] op_sel:[0,1,0] op_sel_hi:[1,1,1]
	v_cvt_pk_f32_fp8_e32 v[224:225], v136
	v_cvt_pk_f32_fp8_sdwa v[226:227], v136 src0_sel:WORD_1
	v_cvt_pk_f32_fp8_e32 v[228:229], v137
	v_cvt_pk_f32_fp8_sdwa v[230:231], v137 src0_sel:WORD_1
	v_pk_fma_f32 v[48:49], v[224:225], v[250:251], v[48:49] op_sel_hi:[1,0,1]
	v_pk_fma_f32 v[50:51], v[226:227], v[250:251], v[50:51] op_sel_hi:[1,0,1]
	v_pk_fma_f32 v[52:53], v[228:229], v[250:251], v[52:53] op_sel_hi:[1,0,1]
	v_pk_fma_f32 v[54:55], v[230:231], v[250:251], v[54:55] op_sel_hi:[1,0,1]
	v_cvt_pk_f32_fp8_e32 v[224:225], v138
	v_cvt_pk_f32_fp8_sdwa v[226:227], v138 src0_sel:WORD_1
	v_cvt_pk_f32_fp8_e32 v[228:229], v139
	v_cvt_pk_f32_fp8_sdwa v[230:231], v139 src0_sel:WORD_1
	v_pk_fma_f32 v[56:57], v[224:225], v[250:251], v[56:57] op_sel_hi:[1,0,1]
	v_pk_fma_f32 v[58:59], v[226:227], v[250:251], v[58:59] op_sel_hi:[1,0,1]
	v_pk_fma_f32 v[60:61], v[228:229], v[250:251], v[60:61] op_sel_hi:[1,0,1]
	v_pk_fma_f32 v[62:63], v[230:231], v[250:251], v[62:63] op_sel_hi:[1,0,1]
	v_cvt_pk_f32_fp8_e32 v[224:225], v140
	v_cvt_pk_f32_fp8_sdwa v[226:227], v140 src0_sel:WORD_1
	v_cvt_pk_f32_fp8_e32 v[228:229], v141
	v_cvt_pk_f32_fp8_sdwa v[230:231], v141 src0_sel:WORD_1
	v_pk_fma_f32 v[48:49], v[224:225], v[250:251], v[48:49] op_sel:[0,1,0] op_sel_hi:[1,1,1]
	v_pk_fma_f32 v[50:51], v[226:227], v[250:251], v[50:51] op_sel:[0,1,0] op_sel_hi:[1,1,1]
	v_pk_fma_f32 v[52:53], v[228:229], v[250:251], v[52:53] op_sel:[0,1,0] op_sel_hi:[1,1,1]
	v_pk_fma_f32 v[54:55], v[230:231], v[250:251], v[54:55] op_sel:[0,1,0] op_sel_hi:[1,1,1]
	v_cvt_pk_f32_fp8_e32 v[224:225], v142
	v_cvt_pk_f32_fp8_sdwa v[226:227], v142 src0_sel:WORD_1
	v_cvt_pk_f32_fp8_e32 v[228:229], v143
	v_cvt_pk_f32_fp8_sdwa v[230:231], v143 src0_sel:WORD_1
	v_pk_fma_f32 v[56:57], v[224:225], v[250:251], v[56:57] op_sel:[0,1,0] op_sel_hi:[1,1,1]
	v_pk_fma_f32 v[58:59], v[226:227], v[250:251], v[58:59] op_sel:[0,1,0] op_sel_hi:[1,1,1]
	v_pk_fma_f32 v[60:61], v[228:229], v[250:251], v[60:61] op_sel:[0,1,0] op_sel_hi:[1,1,1]
	v_pk_fma_f32 v[62:63], v[230:231], v[250:251], v[62:63] op_sel:[0,1,0] op_sel_hi:[1,1,1]
	s_sub_i32 s90, s90, 1
	s_cmp_eq_u32 s90, 0
	s_cbranch_scc1 .LV_sw1
.LV_t3_s1:
	s_waitcnt lgkmcnt(0)
	v_add_u32_e32 v236, v232, v240
	v_add_u32_e32 v237, v233, v240
	v_add_u32_e32 v238, v234, v240
	v_add_u32_e32 v239, v235, v240
	global_load_dwordx4 v[128:131], v236, s[6:7]
	global_load_dwordx4 v[132:135], v237, s[6:7]
	global_load_dwordx4 v[136:139], v238, s[6:7]
	global_load_dwordx4 v[140:143], v239, s[6:7]
	ds_read_b128 v[232:235], v213 offset:80
	ds_read_b128 v[248:251], v213 offset:5024
	s_waitcnt vmcnt(12)
	v_cvt_pk_f32_fp8_e32 v[224:225], v144
	v_cvt_pk_f32_fp8_sdwa v[226:227], v144 src0_sel:WORD_1
	v_cvt_pk_f32_fp8_e32 v[228:229], v145
	v_cvt_pk_f32_fp8_sdwa v[230:231], v145 src0_sel:WORD_1
	v_pk_fma_f32 v[48:49], v[224:225], v[252:253], v[48:49] op_sel_hi:[1,0,1]
	v_pk_fma_f32 v[50:51], v[226:227], v[252:253], v[50:51] op_sel_hi:[1,0,1]
	v_pk_fma_f32 v[52:53], v[228:229], v[252:253], v[52:53] op_sel_hi:[1,0,1]
	v_pk_fma_f32 v[54:55], v[230:231], v[252:253], v[54:55] op_sel_hi:[1,0,1]
	v_cvt_pk_f32_fp8_e32 v[224:225], v146
	v_cvt_pk_f32_fp8_sdwa v[226:227], v146 src0_sel:WORD_1
	v_cvt_pk_f32_fp8_e32 v[228:229], v147
	v_cvt_pk_f32_fp8_sdwa v[230:231], v147 src0_sel:WORD_1
	v_pk_fma_f32 v[56:57], v[224:225], v[252:253], v[56:57] op_sel_hi:[1,0,1]
	v_pk_fma_f32 v[58:59], v[226:227], v[252:253], v[58:59] op_sel_hi:[1,0,1]
	v_pk_fma_f32 v[60:61], v[228:229], v[252:253], v[60:61] op_sel_hi:[1,0,1]
	v_pk_fma_f32 v[62:63], v[230:231], v[252:253], v[62:63] op_sel_hi:[1,0,1]
	v_cvt_pk_f32_fp8_e32 v[224:225], v148
	v_cvt_pk_f32_fp8_sdwa v[226:227], v148 src0_sel:WORD_1
	v_cvt_pk_f32_fp8_e32 v[228:229], v149
	v_cvt_pk_f32_fp8_sdwa v[230:231], v149 src0_sel:WORD_1
	v_pk_fma_f32 v[48:49], v[224:225], v[252:253], v[48:49] op_sel:[0,1,0] op_sel_hi:[1,1,1]
	v_pk_fma_f32 v[50:51], v[226:227], v[252:253], v[50:51] op_sel:[0,1,0] op_sel_hi:[1,1,1]
	v_pk_fma_f32 v[52:53], v[228:229], v[252:253], v[52:53] op_sel:[0,1,0] op_sel_hi:[1,1,1]
	v_pk_fma_f32 v[54:55], v[230:231], v[252:253], v[54:55] op_sel:[0,1,0] op_sel_hi:[1,1,1]
	v_cvt_pk_f32_fp8_e32 v[224:225], v150
	v_cvt_pk_f32_fp8_sdwa v[226:227], v150 src0_sel:WORD_1
	v_cvt_pk_f32_fp8_e32 v[228:229], v151
	v_cvt_pk_f32_fp8_sdwa v[230:231], v151 src0_sel:WORD_1
	v_pk_fma_f32 v[56:57], v[224:225], v[252:253], v[56:57] op_sel:[0,1,0] op_sel_hi:[1,1,1]
	v_pk_fma_f32 v[58:59], v[226:227], v[252:253], v[58:59] op_sel:[0,1,0] op_sel_hi:[1,1,1]
	v_pk_fma_f32 v[60:61], v[228:229], v[252:253], v[60:61] op_sel:[0,1,0] op_sel_hi:[1,1,1]
	v_pk_fma_f32 v[62:63], v[230:231], v[252:253], v[62:63] op_sel:[0,1,0] op_sel_hi:[1,1,1]
	v_cvt_pk_f32_fp8_e32 v[224:225], v152
	v_cvt_pk_f32_fp8_sdwa v[226:227], v152 src0_sel:WORD_1
	v_cvt_pk_f32_fp8_e32 v[228:229], v153
	v_cvt_pk_f32_fp8_sdwa v[230:231], v153 src0_sel:WORD_1
	v_pk_fma_f32 v[48:49], v[224:225], v[254:255], v[48:49] op_sel_hi:[1,0,1]
	v_pk_fma_f32 v[50:51], v[226:227], v[254:255], v[50:51] op_sel_hi:[1,0,1]
	v_pk_fma_f32 v[52:53], v[228:229], v[254:255], v[52:53] op_sel_hi:[1,0,1]
	v_pk_fma_f32 v[54:55], v[230:231], v[254:255], v[54:55] op_sel_hi:[1,0,1]
	v_cvt_pk_f32_fp8_e32 v[224:225], v154
	v_cvt_pk_f32_fp8_sdwa v[226:227], v154 src0_sel:WORD_1
	v_cvt_pk_f32_fp8_e32 v[228:229], v155
	v_cvt_pk_f32_fp8_sdwa v[230:231], v155 src0_sel:WORD_1
	v_pk_fma_f32 v[56:57], v[224:225], v[254:255], v[56:57] op_sel_hi:[1,0,1]
	v_pk_fma_f32 v[58:59], v[226:227], v[254:255], v[58:59] op_sel_hi:[1,0,1]
	v_pk_fma_f32 v[60:61], v[228:229], v[254:255], v[60:61] op_sel_hi:[1,0,1]
	v_pk_fma_f32 v[62:63], v[230:231], v[254:255], v[62:63] op_sel_hi:[1,0,1]
	v_cvt_pk_f32_fp8_e32 v[224:225], v156
	v_cvt_pk_f32_fp8_sdwa v[226:227], v156 src0_sel:WORD_1
	v_cvt_pk_f32_fp8_e32 v[228:229], v157
	v_cvt_pk_f32_fp8_sdwa v[230:231], v157 src0_sel:WORD_1
	v_pk_fma_f32 v[48:49], v[224:225], v[254:255], v[48:49] op_sel:[0,1,0] op_sel_hi:[1,1,1]
	v_pk_fma_f32 v[50:51], v[226:227], v[254:255], v[50:51] op_sel:[0,1,0] op_sel_hi:[1,1,1]
	v_pk_fma_f32 v[52:53], v[228:229], v[254:255], v[52:53] op_sel:[0,1,0] op_sel_hi:[1,1,1]
	v_pk_fma_f32 v[54:55], v[230:231], v[254:255], v[54:55] op_sel:[0,1,0] op_sel_hi:[1,1,1]
	v_cvt_pk_f32_fp8_e32 v[224:225], v158
	v_cvt_pk_f32_fp8_sdwa v[226:227], v158 src0_sel:WORD_1
	v_cvt_pk_f32_fp8_e32 v[228:229], v159
	v_cvt_pk_f32_fp8_sdwa v[230:231], v159 src0_sel:WORD_1
	v_pk_fma_f32 v[56:57], v[224:225], v[254:255], v[56:57] op_sel:[0,1,0] op_sel_hi:[1,1,1]
	v_pk_fma_f32 v[58:59], v[226:227], v[254:255], v[58:59] op_sel:[0,1,0] op_sel_hi:[1,1,1]
	v_pk_fma_f32 v[60:61], v[228:229], v[254:255], v[60:61] op_sel:[0,1,0] op_sel_hi:[1,1,1]
	v_pk_fma_f32 v[62:63], v[230:231], v[254:255], v[62:63] op_sel:[0,1,0] op_sel_hi:[1,1,1]
	s_sub_i32 s90, s90, 1
	s_cmp_eq_u32 s90, 0
	s_cbranch_scc1 .LV_sw2
.LV_t3_s2:
	s_waitcnt lgkmcnt(0)
	v_add_u32_e32 v236, v232, v240
	v_add_u32_e32 v237, v233, v240
	v_add_u32_e32 v238, v234, v240
	v_add_u32_e32 v239, v235, v240
	global_load_dwordx4 v[144:147], v236, s[6:7]
	global_load_dwordx4 v[148:151], v237, s[6:7]
	global_load_dwordx4 v[152:155], v238, s[6:7]
	global_load_dwordx4 v[156:159], v239, s[6:7]
	ds_read_b128 v[232:235], v213 offset:96
	ds_read_b128 v[252:255], v213 offset:5040
	s_waitcnt vmcnt(12)
	v_cvt_pk_f32_fp8_e32 v[224:225], v160
	v_cvt_pk_f32_fp8_sdwa v[226:227], v160 src0_sel:WORD_1
	v_cvt_pk_f32_fp8_e32 v[228:229], v161
	v_cvt_pk_f32_fp8_sdwa v[230:231], v161 src0_sel:WORD_1
	v_pk_fma_f32 v[48:49], v[224:225], v[248:249], v[48:49] op_sel_hi:[1,0,1]
	v_pk_fma_f32 v[50:51], v[226:227], v[248:249], v[50:51] op_sel_hi:[1,0,1]
	v_pk_fma_f32 v[52:53], v[228:229], v[248:249], v[52:53] op_sel_hi:[1,0,1]
	v_pk_fma_f32 v[54:55], v[230:231], v[248:249], v[54:55] op_sel_hi:[1,0,1]
	v_cvt_pk_f32_fp8_e32 v[224:225], v162
	v_cvt_pk_f32_fp8_sdwa v[226:227], v162 src0_sel:WORD_1
	v_cvt_pk_f32_fp8_e32 v[228:229], v163
	v_cvt_pk_f32_fp8_sdwa v[230:231], v163 src0_sel:WORD_1
	v_pk_fma_f32 v[56:57], v[224:225], v[248:249], v[56:57] op_sel_hi:[1,0,1]
	v_pk_fma_f32 v[58:59], v[226:227], v[248:249], v[58:59] op_sel_hi:[1,0,1]
	v_pk_fma_f32 v[60:61], v[228:229], v[248:249], v[60:61] op_sel_hi:[1,0,1]
	v_pk_fma_f32 v[62:63], v[230:231], v[248:249], v[62:63] op_sel_hi:[1,0,1]
	v_cvt_pk_f32_fp8_e32 v[224:225], v164
	v_cvt_pk_f32_fp8_sdwa v[226:227], v164 src0_sel:WORD_1
	v_cvt_pk_f32_fp8_e32 v[228:229], v165
	v_cvt_pk_f32_fp8_sdwa v[230:231], v165 src0_sel:WORD_1
	v_pk_fma_f32 v[48:49], v[224:225], v[248:249], v[48:49] op_sel:[0,1,0] op_sel_hi:[1,1,1]
	v_pk_fma_f32 v[50:51], v[226:227], v[248:249], v[50:51] op_sel:[0,1,0] op_sel_hi:[1,1,1]
	v_pk_fma_f32 v[52:53], v[228:229], v[248:249], v[52:53] op_sel:[0,1,0] op_sel_hi:[1,1,1]
	v_pk_fma_f32 v[54:55], v[230:231], v[248:249], v[54:55] op_sel:[0,1,0] op_sel_hi:[1,1,1]
	v_cvt_pk_f32_fp8_e32 v[224:225], v166
	v_cvt_pk_f32_fp8_sdwa v[226:227], v166 src0_sel:WORD_1
	v_cvt_pk_f32_fp8_e32 v[228:229], v167
	v_cvt_pk_f32_fp8_sdwa v[230:231], v167 src0_sel:WORD_1
	v_pk_fma_f32 v[56:57], v[224:225], v[248:249], v[56:57] op_sel:[0,1,0] op_sel_hi:[1,1,1]
	v_pk_fma_f32 v[58:59], v[226:227], v[248:249], v[58:59] op_sel:[0,1,0] op_sel_hi:[1,1,1]
	v_pk_fma_f32 v[60:61], v[228:229], v[248:249], v[60:61] op_sel:[0,1,0] op_sel_hi:[1,1,1]
	v_pk_fma_f32 v[62:63], v[230:231], v[248:249], v[62:63] op_sel:[0,1,0] op_sel_hi:[1,1,1]
	v_cvt_pk_f32_fp8_e32 v[224:225], v168
	v_cvt_pk_f32_fp8_sdwa v[226:227], v168 src0_sel:WORD_1
	v_cvt_pk_f32_fp8_e32 v[228:229], v169
	v_cvt_pk_f32_fp8_sdwa v[230:231], v169 src0_sel:WORD_1
	v_pk_fma_f32 v[48:49], v[224:225], v[250:251], v[48:49] op_sel_hi:[1,0,1]
	v_pk_fma_f32 v[50:51], v[226:227], v[250:251], v[50:51] op_sel_hi:[1,0,1]
	v_pk_fma_f32 v[52:53], v[228:229], v[250:251], v[52:53] op_sel_hi:[1,0,1]
	v_pk_fma_f32 v[54:55], v[230:231], v[250:251], v[54:55] op_sel_hi:[1,0,1]
	v_cvt_pk_f32_fp8_e32 v[224:225], v170
	v_cvt_pk_f32_fp8_sdwa v[226:227], v170 src0_sel:WORD_1
	v_cvt_pk_f32_fp8_e32 v[228:229], v171
	v_cvt_pk_f32_fp8_sdwa v[230:231], v171 src0_sel:WORD_1
	v_pk_fma_f32 v[56:57], v[224:225], v[250:251], v[56:57] op_sel_hi:[1,0,1]
	v_pk_fma_f32 v[58:59], v[226:227], v[250:251], v[58:59] op_sel_hi:[1,0,1]
	v_pk_fma_f32 v[60:61], v[228:229], v[250:251], v[60:61] op_sel_hi:[1,0,1]
	v_pk_fma_f32 v[62:63], v[230:231], v[250:251], v[62:63] op_sel_hi:[1,0,1]
	v_cvt_pk_f32_fp8_e32 v[224:225], v172
	v_cvt_pk_f32_fp8_sdwa v[226:227], v172 src0_sel:WORD_1
	v_cvt_pk_f32_fp8_e32 v[228:229], v173
	v_cvt_pk_f32_fp8_sdwa v[230:231], v173 src0_sel:WORD_1
	v_pk_fma_f32 v[48:49], v[224:225], v[250:251], v[48:49] op_sel:[0,1,0] op_sel_hi:[1,1,1]
	v_pk_fma_f32 v[50:51], v[226:227], v[250:251], v[50:51] op_sel:[0,1,0] op_sel_hi:[1,1,1]
	v_pk_fma_f32 v[52:53], v[228:229], v[250:251], v[52:53] op_sel:[0,1,0] op_sel_hi:[1,1,1]
	v_pk_fma_f32 v[54:55], v[230:231], v[250:251], v[54:55] op_sel:[0,1,0] op_sel_hi:[1,1,1]
	v_cvt_pk_f32_fp8_e32 v[224:225], v174
	v_cvt_pk_f32_fp8_sdwa v[226:227], v174 src0_sel:WORD_1
	v_cvt_pk_f32_fp8_e32 v[228:229], v175
	v_cvt_pk_f32_fp8_sdwa v[230:231], v175 src0_sel:WORD_1
	v_pk_fma_f32 v[56:57], v[224:225], v[250:251], v[56:57] op_sel:[0,1,0] op_sel_hi:[1,1,1]
	v_pk_fma_f32 v[58:59], v[226:227], v[250:251], v[58:59] op_sel:[0,1,0] op_sel_hi:[1,1,1]
	v_pk_fma_f32 v[60:61], v[228:229], v[250:251], v[60:61] op_sel:[0,1,0] op_sel_hi:[1,1,1]
	v_pk_fma_f32 v[62:63], v[230:231], v[250:251], v[62:63] op_sel:[0,1,0] op_sel_hi:[1,1,1]
	s_sub_i32 s90, s90, 1
	s_cmp_eq_u32 s90, 0
	s_cbranch_scc1 .LV_sw3
.LV_t3_s3:
	s_waitcnt lgkmcnt(0)
	v_add_u32_e32 v236, v232, v240
	v_add_u32_e32 v237, v233, v240
	v_add_u32_e32 v238, v234, v240
	v_add_u32_e32 v239, v235, v240
	global_load_dwordx4 v[160:163], v236, s[6:7]
	global_load_dwordx4 v[164:167], v237, s[6:7]
	global_load_dwordx4 v[168:171], v238, s[6:7]
	global_load_dwordx4 v[172:175], v239, s[6:7]
	ds_read_b128 v[232:235], v213 offset:112
	ds_read_b128 v[248:251], v213 offset:5056
	s_waitcnt vmcnt(12)
	v_cvt_pk_f32_fp8_e32 v[224:225], v176
	v_cvt_pk_f32_fp8_sdwa v[226:227], v176 src0_sel:WORD_1
	v_cvt_pk_f32_fp8_e32 v[228:229], v177
	v_cvt_pk_f32_fp8_sdwa v[230:231], v177 src0_sel:WORD_1
	v_pk_fma_f32 v[48:49], v[224:225], v[252:253], v[48:49] op_sel_hi:[1,0,1]
	v_pk_fma_f32 v[50:51], v[226:227], v[252:253], v[50:51] op_sel_hi:[1,0,1]
	v_pk_fma_f32 v[52:53], v[228:229], v[252:253], v[52:53] op_sel_hi:[1,0,1]
	v_pk_fma_f32 v[54:55], v[230:231], v[252:253], v[54:55] op_sel_hi:[1,0,1]
	v_cvt_pk_f32_fp8_e32 v[224:225], v178
	v_cvt_pk_f32_fp8_sdwa v[226:227], v178 src0_sel:WORD_1
	v_cvt_pk_f32_fp8_e32 v[228:229], v179
	v_cvt_pk_f32_fp8_sdwa v[230:231], v179 src0_sel:WORD_1
	v_pk_fma_f32 v[56:57], v[224:225], v[252:253], v[56:57] op_sel_hi:[1,0,1]
	v_pk_fma_f32 v[58:59], v[226:227], v[252:253], v[58:59] op_sel_hi:[1,0,1]
	v_pk_fma_f32 v[60:61], v[228:229], v[252:253], v[60:61] op_sel_hi:[1,0,1]
	v_pk_fma_f32 v[62:63], v[230:231], v[252:253], v[62:63] op_sel_hi:[1,0,1]
	v_cvt_pk_f32_fp8_e32 v[224:225], v180
	v_cvt_pk_f32_fp8_sdwa v[226:227], v180 src0_sel:WORD_1
	v_cvt_pk_f32_fp8_e32 v[228:229], v181
	v_cvt_pk_f32_fp8_sdwa v[230:231], v181 src0_sel:WORD_1
	v_pk_fma_f32 v[48:49], v[224:225], v[252:253], v[48:49] op_sel:[0,1,0] op_sel_hi:[1,1,1]
	v_pk_fma_f32 v[50:51], v[226:227], v[252:253], v[50:51] op_sel:[0,1,0] op_sel_hi:[1,1,1]
	v_pk_fma_f32 v[52:53], v[228:229], v[252:253], v[52:53] op_sel:[0,1,0] op_sel_hi:[1,1,1]
	v_pk_fma_f32 v[54:55], v[230:231], v[252:253], v[54:55] op_sel:[0,1,0] op_sel_hi:[1,1,1]
	v_cvt_pk_f32_fp8_e32 v[224:225], v182
	v_cvt_pk_f32_fp8_sdwa v[226:227], v182 src0_sel:WORD_1
	v_cvt_pk_f32_fp8_e32 v[228:229], v183
	v_cvt_pk_f32_fp8_sdwa v[230:231], v183 src0_sel:WORD_1
	v_pk_fma_f32 v[56:57], v[224:225], v[252:253], v[56:57] op_sel:[0,1,0] op_sel_hi:[1,1,1]
	v_pk_fma_f32 v[58:59], v[226:227], v[252:253], v[58:59] op_sel:[0,1,0] op_sel_hi:[1,1,1]
	v_pk_fma_f32 v[60:61], v[228:229], v[252:253], v[60:61] op_sel:[0,1,0] op_sel_hi:[1,1,1]
	v_pk_fma_f32 v[62:63], v[230:231], v[252:253], v[62:63] op_sel:[0,1,0] op_sel_hi:[1,1,1]
	v_cvt_pk_f32_fp8_e32 v[224:225], v184
	v_cvt_pk_f32_fp8_sdwa v[226:227], v184 src0_sel:WORD_1
	v_cvt_pk_f32_fp8_e32 v[228:229], v185
	v_cvt_pk_f32_fp8_sdwa v[230:231], v185 src0_sel:WORD_1
	v_pk_fma_f32 v[48:49], v[224:225], v[254:255], v[48:49] op_sel_hi:[1,0,1]
	v_pk_fma_f32 v[50:51], v[226:227], v[254:255], v[50:51] op_sel_hi:[1,0,1]
	v_pk_fma_f32 v[52:53], v[228:229], v[254:255], v[52:53] op_sel_hi:[1,0,1]
	v_pk_fma_f32 v[54:55], v[230:231], v[254:255], v[54:55] op_sel_hi:[1,0,1]
	v_cvt_pk_f32_fp8_e32 v[224:225], v186
	v_cvt_pk_f32_fp8_sdwa v[226:227], v186 src0_sel:WORD_1
	v_cvt_pk_f32_fp8_e32 v[228:229], v187
	v_cvt_pk_f32_fp8_sdwa v[230:231], v187 src0_sel:WORD_1
	v_pk_fma_f32 v[56:57], v[224:225], v[254:255], v[56:57] op_sel_hi:[1,0,1]
	v_pk_fma_f32 v[58:59], v[226:227], v[254:255], v[58:59] op_sel_hi:[1,0,1]
	v_pk_fma_f32 v[60:61], v[228:229], v[254:255], v[60:61] op_sel_hi:[1,0,1]
	v_pk_fma_f32 v[62:63], v[230:231], v[254:255], v[62:63] op_sel_hi:[1,0,1]
	v_cvt_pk_f32_fp8_e32 v[224:225], v188
	v_cvt_pk_f32_fp8_sdwa v[226:227], v188 src0_sel:WORD_1
	v_cvt_pk_f32_fp8_e32 v[228:229], v189
	v_cvt_pk_f32_fp8_sdwa v[230:231], v189 src0_sel:WORD_1
	v_pk_fma_f32 v[48:49], v[224:225], v[254:255], v[48:49] op_sel:[0,1,0] op_sel_hi:[1,1,1]
	v_pk_fma_f32 v[50:51], v[226:227], v[254:255], v[50:51] op_sel:[0,1,0] op_sel_hi:[1,1,1]
	v_pk_fma_f32 v[52:53], v[228:229], v[254:255], v[52:53] op_sel:[0,1,0] op_sel_hi:[1,1,1]
	v_pk_fma_f32 v[54:55], v[230:231], v[254:255], v[54:55] op_sel:[0,1,0] op_sel_hi:[1,1,1]
	v_cvt_pk_f32_fp8_e32 v[224:225], v190
	v_cvt_pk_f32_fp8_sdwa v[226:227], v190 src0_sel:WORD_1
	v_cvt_pk_f32_fp8_e32 v[228:229], v191
	v_cvt_pk_f32_fp8_sdwa v[230:231], v191 src0_sel:WORD_1
	v_pk_fma_f32 v[56:57], v[224:225], v[254:255], v[56:57] op_sel:[0,1,0] op_sel_hi:[1,1,1]
	v_pk_fma_f32 v[58:59], v[226:227], v[254:255], v[58:59] op_sel:[0,1,0] op_sel_hi:[1,1,1]
	v_pk_fma_f32 v[60:61], v[228:229], v[254:255], v[60:61] op_sel:[0,1,0] op_sel_hi:[1,1,1]
	v_pk_fma_f32 v[62:63], v[230:231], v[254:255], v[62:63] op_sel:[0,1,0] op_sel_hi:[1,1,1]
	v_add_u32_e32 v213, 64, v213
	s_add_i32 s21, s21, 4
	s_sub_i32 s90, s90, 1
	s_cmp_eq_u32 s90, 0
	s_cbranch_scc1 .LV_sw0
	s_branch .LV_t3_s0
.LV_t4_s0:
	s_cmp_ge_u32 s21, s20
	s_cbranch_scc1 .LV_done
	s_waitcnt lgkmcnt(0)
	v_add_u32_e32 v236, v232, v240
	v_add_u32_e32 v237, v233, v240
	v_add_u32_e32 v238, v234, v240
	v_add_u32_e32 v239, v235, v240
	global_load_dwordx4 v[176:179], v236, s[6:7]
	global_load_dwordx4 v[180:183], v237, s[6:7]
	global_load_dwordx4 v[184:187], v238, s[6:7]
	global_load_dwordx4 v[188:191], v239, s[6:7]
	ds_read_b128 v[232:235], v213 offset:64
	ds_read_b128 v[252:255], v213 offset:5008
	s_waitcnt vmcnt(12)
	v_cvt_pk_f32_fp8_e32 v[224:225], v128
	v_cvt_pk_f32_fp8_sdwa v[226:227], v128 src0_sel:WORD_1
	v_cvt_pk_f32_fp8_e32 v[228:229], v129
	v_cvt_pk_f32_fp8_sdwa v[230:231], v129 src0_sel:WORD_1
	v_pk_fma_f32 v[64:65], v[224:225], v[248:249], v[64:65] op_sel_hi:[1,0,1]
	v_pk_fma_f32 v[66:67], v[226:227], v[248:249], v[66:67] op_sel_hi:[1,0,1]
	v_pk_fma_f32 v[68:69], v[228:229], v[248:249], v[68:69] op_sel_hi:[1,0,1]
	v_pk_fma_f32 v[70:71], v[230:231], v[248:249], v[70:71] op_sel_hi:[1,0,1]
	v_cvt_pk_f32_fp8_e32 v[224:225], v130
	v_cvt_pk_f32_fp8_sdwa v[226:227], v130 src0_sel:WORD_1
	v_cvt_pk_f32_fp8_e32 v[228:229], v131
	v_cvt_pk_f32_fp8_sdwa v[230:231], v131 src0_sel:WORD_1
	v_pk_fma_f32 v[72:73], v[224:225], v[248:249], v[72:73] op_sel_hi:[1,0,1]
	v_pk_fma_f32 v[74:75], v[226:227], v[248:249], v[74:75] op_sel_hi:[1,0,1]
	v_pk_fma_f32 v[76:77], v[228:229], v[248:249], v[76:77] op_sel_hi:[1,0,1]
	v_pk_fma_f32 v[78:79], v[230:231], v[248:249], v[78:79] op_sel_hi:[1,0,1]
	v_cvt_pk_f32_fp8_e32 v[224:225], v132
	v_cvt_pk_f32_fp8_sdwa v[226:227], v132 src0_sel:WORD_1
	v_cvt_pk_f32_fp8_e32 v[228:229], v133
	v_cvt_pk_f32_fp8_sdwa v[230:231], v133 src0_sel:WORD_1
	v_pk_fma_f32 v[64:65], v[224:225], v[248:249], v[64:65] op_sel:[0,1,0] op_sel_hi:[1,1,1]
	v_pk_fma_f32 v[66:67], v[226:227], v[248:249], v[66:67] op_sel:[0,1,0] op_sel_hi:[1,1,1]
	v_pk_fma_f32 v[68:69], v[228:229], v[248:249], v[68:69] op_sel:[0,1,0] op_sel_hi:[1,1,1]
	v_pk_fma_f32 v[70:71], v[230:231], v[248:249], v[70:71] op_sel:[0,1,0] op_sel_hi:[1,1,1]
	v_cvt_pk_f32_fp8_e32 v[224:225], v134
	v_cvt_pk_f32_fp8_sdwa v[226:227], v134 src0_sel:WORD_1
	v_cvt_pk_f32_fp8_e32 v[228:229], v135
	v_cvt_pk_f32_fp8_sdwa v[230:231], v135 src0_sel:WORD_1
	v_pk_fma_f32 v[72:73], v[224:225], v[248:249], v[72:73] op_sel:[0,1,0] op_sel_hi:[1,1,1]
	v_pk_fma_f32 v[74:75], v[226:227], v[248:249], v[74:75] op_sel:[0,1,0] op_sel_hi:[1,1,1]
	v_pk_fma_f32 v[76:77], v[228:229], v[248:249], v[76:77] op_sel:[0,1,0] op_sel_hi:[1,1,1]
	v_pk_fma_f32 v[78:79], v[230:231], v[248:249], v[78:79] op_sel:[0,1,0] op_sel_hi:[1,1,1]
	v_cvt_pk_f32_fp8_e32 v[224:225], v136
	v_cvt_pk_f32_fp8_sdwa v[226:227], v136 src0_sel:WORD_1
	v_cvt_pk_f32_fp8_e32 v[228:229], v137
	v_cvt_pk_f32_fp8_sdwa v[230:231], v137 src0_sel:WORD_1
	v_pk_fma_f32 v[64:65], v[224:225], v[250:251], v[64:65] op_sel_hi:[1,0,1]
	v_pk_fma_f32 v[66:67], v[226:227], v[250:251], v[66:67] op_sel_hi:[1,0,1]
	v_pk_fma_f32 v[68:69], v[228:229], v[250:251], v[68:69] op_sel_hi:[1,0,1]
	v_pk_fma_f32 v[70:71], v[230:231], v[250:251], v[70:71] op_sel_hi:[1,0,1]
	v_cvt_pk_f32_fp8_e32 v[224:225], v138
	v_cvt_pk_f32_fp8_sdwa v[226:227], v138 src0_sel:WORD_1
	v_cvt_pk_f32_fp8_e32 v[228:229], v139
	v_cvt_pk_f32_fp8_sdwa v[230:231], v139 src0_sel:WORD_1
	v_pk_fma_f32 v[72:73], v[224:225], v[250:251], v[72:73] op_sel_hi:[1,0,1]
	v_pk_fma_f32 v[74:75], v[226:227], v[250:251], v[74:75] op_sel_hi:[1,0,1]
	v_pk_fma_f32 v[76:77], v[228:229], v[250:251], v[76:77] op_sel_hi:[1,0,1]
	v_pk_fma_f32 v[78:79], v[230:231], v[250:251], v[78:79] op_sel_hi:[1,0,1]
	v_cvt_pk_f32_fp8_e32 v[224:225], v140
	v_cvt_pk_f32_fp8_sdwa v[226:227], v140 src0_sel:WORD_1
	v_cvt_pk_f32_fp8_e32 v[228:229], v141
	v_cvt_pk_f32_fp8_sdwa v[230:231], v141 src0_sel:WORD_1
	v_pk_fma_f32 v[64:65], v[224:225], v[250:251], v[64:65] op_sel:[0,1,0] op_sel_hi:[1,1,1]
	v_pk_fma_f32 v[66:67], v[226:227], v[250:251], v[66:67] op_sel:[0,1,0] op_sel_hi:[1,1,1]
	v_pk_fma_f32 v[68:69], v[228:229], v[250:251], v[68:69] op_sel:[0,1,0] op_sel_hi:[1,1,1]
	v_pk_fma_f32 v[70:71], v[230:231], v[250:251], v[70:71] op_sel:[0,1,0] op_sel_hi:[1,1,1]
	v_cvt_pk_f32_fp8_e32 v[224:225], v142
	v_cvt_pk_f32_fp8_sdwa v[226:227], v142 src0_sel:WORD_1
	v_cvt_pk_f32_fp8_e32 v[228:229], v143
	v_cvt_pk_f32_fp8_sdwa v[230:231], v143 src0_sel:WORD_1
	v_pk_fma_f32 v[72:73], v[224:225], v[250:251], v[72:73] op_sel:[0,1,0] op_sel_hi:[1,1,1]
	v_pk_fma_f32 v[74:75], v[226:227], v[250:251], v[74:75] op_sel:[0,1,0] op_sel_hi:[1,1,1]
	v_pk_fma_f32 v[76:77], v[228:229], v[250:251], v[76:77] op_sel:[0,1,0] op_sel_hi:[1,1,1]
	v_pk_fma_f32 v[78:79], v[230:231], v[250:251], v[78:79] op_sel:[0,1,0] op_sel_hi:[1,1,1]
	s_sub_i32 s90, s90, 1
	s_cmp_eq_u32 s90, 0
	s_cbranch_scc1 .LV_sw1
.LV_t4_s1:
	s_waitcnt lgkmcnt(0)
	v_add_u32_e32 v236, v232, v240
	v_add_u32_e32 v237, v233, v240
	v_add_u32_e32 v238, v234, v240
	v_add_u32_e32 v239, v235, v240
	global_load_dwordx4 v[128:131], v236, s[6:7]
	global_load_dwordx4 v[132:135], v237, s[6:7]
	global_load_dwordx4 v[136:139], v238, s[6:7]
	global_load_dwordx4 v[140:143], v239, s[6:7]
	ds_read_b128 v[232:235], v213 offset:80
	ds_read_b128 v[248:251], v213 offset:5024
	s_waitcnt vmcnt(12)
	v_cvt_pk_f32_fp8_e32 v[224:225], v144
	v_cvt_pk_f32_fp8_sdwa v[226:227], v144 src0_sel:WORD_1
	v_cvt_pk_f32_fp8_e32 v[228:229], v145
	v_cvt_pk_f32_fp8_sdwa v[230:231], v145 src0_sel:WORD_1
	v_pk_fma_f32 v[64:65], v[224:225], v[252:253], v[64:65] op_sel_hi:[1,0,1]
	v_pk_fma_f32 v[66:67], v[226:227], v[252:253], v[66:67] op_sel_hi:[1,0,1]
	v_pk_fma_f32 v[68:69], v[228:229], v[252:253], v[68:69] op_sel_hi:[1,0,1]
	v_pk_fma_f32 v[70:71], v[230:231], v[252:253], v[70:71] op_sel_hi:[1,0,1]
	v_cvt_pk_f32_fp8_e32 v[224:225], v146
	v_cvt_pk_f32_fp8_sdwa v[226:227], v146 src0_sel:WORD_1
	v_cvt_pk_f32_fp8_e32 v[228:229], v147
	v_cvt_pk_f32_fp8_sdwa v[230:231], v147 src0_sel:WORD_1
	v_pk_fma_f32 v[72:73], v[224:225], v[252:253], v[72:73] op_sel_hi:[1,0,1]
	v_pk_fma_f32 v[74:75], v[226:227], v[252:253], v[74:75] op_sel_hi:[1,0,1]
	v_pk_fma_f32 v[76:77], v[228:229], v[252:253], v[76:77] op_sel_hi:[1,0,1]
	v_pk_fma_f32 v[78:79], v[230:231], v[252:253], v[78:79] op_sel_hi:[1,0,1]
	v_cvt_pk_f32_fp8_e32 v[224:225], v148
	v_cvt_pk_f32_fp8_sdwa v[226:227], v148 src0_sel:WORD_1
	v_cvt_pk_f32_fp8_e32 v[228:229], v149
	v_cvt_pk_f32_fp8_sdwa v[230:231], v149 src0_sel:WORD_1
	v_pk_fma_f32 v[64:65], v[224:225], v[252:253], v[64:65] op_sel:[0,1,0] op_sel_hi:[1,1,1]
	v_pk_fma_f32 v[66:67], v[226:227], v[252:253], v[66:67] op_sel:[0,1,0] op_sel_hi:[1,1,1]
	v_pk_fma_f32 v[68:69], v[228:229], v[252:253], v[68:69] op_sel:[0,1,0] op_sel_hi:[1,1,1]
	v_pk_fma_f32 v[70:71], v[230:231], v[252:253], v[70:71] op_sel:[0,1,0] op_sel_hi:[1,1,1]
	v_cvt_pk_f32_fp8_e32 v[224:225], v150
	v_cvt_pk_f32_fp8_sdwa v[226:227], v150 src0_sel:WORD_1
	v_cvt_pk_f32_fp8_e32 v[228:229], v151
	v_cvt_pk_f32_fp8_sdwa v[230:231], v151 src0_sel:WORD_1
	v_pk_fma_f32 v[72:73], v[224:225], v[252:253], v[72:73] op_sel:[0,1,0] op_sel_hi:[1,1,1]
	v_pk_fma_f32 v[74:75], v[226:227], v[252:253], v[74:75] op_sel:[0,1,0] op_sel_hi:[1,1,1]
	v_pk_fma_f32 v[76:77], v[228:229], v[252:253], v[76:77] op_sel:[0,1,0] op_sel_hi:[1,1,1]
	v_pk_fma_f32 v[78:79], v[230:231], v[252:253], v[78:79] op_sel:[0,1,0] op_sel_hi:[1,1,1]
	v_cvt_pk_f32_fp8_e32 v[224:225], v152
	v_cvt_pk_f32_fp8_sdwa v[226:227], v152 src0_sel:WORD_1
	v_cvt_pk_f32_fp8_e32 v[228:229], v153
	v_cvt_pk_f32_fp8_sdwa v[230:231], v153 src0_sel:WORD_1
	v_pk_fma_f32 v[64:65], v[224:225], v[254:255], v[64:65] op_sel_hi:[1,0,1]
	v_pk_fma_f32 v[66:67], v[226:227], v[254:255], v[66:67] op_sel_hi:[1,0,1]
	v_pk_fma_f32 v[68:69], v[228:229], v[254:255], v[68:69] op_sel_hi:[1,0,1]
	v_pk_fma_f32 v[70:71], v[230:231], v[254:255], v[70:71] op_sel_hi:[1,0,1]
	v_cvt_pk_f32_fp8_e32 v[224:225], v154
	v_cvt_pk_f32_fp8_sdwa v[226:227], v154 src0_sel:WORD_1
	v_cvt_pk_f32_fp8_e32 v[228:229], v155
	v_cvt_pk_f32_fp8_sdwa v[230:231], v155 src0_sel:WORD_1
	v_pk_fma_f32 v[72:73], v[224:225], v[254:255], v[72:73] op_sel_hi:[1,0,1]
	v_pk_fma_f32 v[74:75], v[226:227], v[254:255], v[74:75] op_sel_hi:[1,0,1]
	v_pk_fma_f32 v[76:77], v[228:229], v[254:255], v[76:77] op_sel_hi:[1,0,1]
	v_pk_fma_f32 v[78:79], v[230:231], v[254:255], v[78:79] op_sel_hi:[1,0,1]
	v_cvt_pk_f32_fp8_e32 v[224:225], v156
	v_cvt_pk_f32_fp8_sdwa v[226:227], v156 src0_sel:WORD_1
	v_cvt_pk_f32_fp8_e32 v[228:229], v157
	v_cvt_pk_f32_fp8_sdwa v[230:231], v157 src0_sel:WORD_1
	v_pk_fma_f32 v[64:65], v[224:225], v[254:255], v[64:65] op_sel:[0,1,0] op_sel_hi:[1,1,1]
	v_pk_fma_f32 v[66:67], v[226:227], v[254:255], v[66:67] op_sel:[0,1,0] op_sel_hi:[1,1,1]
	v_pk_fma_f32 v[68:69], v[228:229], v[254:255], v[68:69] op_sel:[0,1,0] op_sel_hi:[1,1,1]
	v_pk_fma_f32 v[70:71], v[230:231], v[254:255], v[70:71] op_sel:[0,1,0] op_sel_hi:[1,1,1]
	v_cvt_pk_f32_fp8_e32 v[224:225], v158
	v_cvt_pk_f32_fp8_sdwa v[226:227], v158 src0_sel:WORD_1
	v_cvt_pk_f32_fp8_e32 v[228:229], v159
	v_cvt_pk_f32_fp8_sdwa v[230:231], v159 src0_sel:WORD_1
	v_pk_fma_f32 v[72:73], v[224:225], v[254:255], v[72:73] op_sel:[0,1,0] op_sel_hi:[1,1,1]
	v_pk_fma_f32 v[74:75], v[226:227], v[254:255], v[74:75] op_sel:[0,1,0] op_sel_hi:[1,1,1]
	v_pk_fma_f32 v[76:77], v[228:229], v[254:255], v[76:77] op_sel:[0,1,0] op_sel_hi:[1,1,1]
	v_pk_fma_f32 v[78:79], v[230:231], v[254:255], v[78:79] op_sel:[0,1,0] op_sel_hi:[1,1,1]
	s_sub_i32 s90, s90, 1
	s_cmp_eq_u32 s90, 0
	s_cbranch_scc1 .LV_sw2
.LV_t4_s2:
	s_waitcnt lgkmcnt(0)
	v_add_u32_e32 v236, v232, v240
	v_add_u32_e32 v237, v233, v240
	v_add_u32_e32 v238, v234, v240
	v_add_u32_e32 v239, v235, v240
	global_load_dwordx4 v[144:147], v236, s[6:7]
	global_load_dwordx4 v[148:151], v237, s[6:7]
	global_load_dwordx4 v[152:155], v238, s[6:7]
	global_load_dwordx4 v[156:159], v239, s[6:7]
	ds_read_b128 v[232:235], v213 offset:96
	ds_read_b128 v[252:255], v213 offset:5040
	s_waitcnt vmcnt(12)
	v_cvt_pk_f32_fp8_e32 v[224:225], v160
	v_cvt_pk_f32_fp8_sdwa v[226:227], v160 src0_sel:WORD_1
	v_cvt_pk_f32_fp8_e32 v[228:229], v161
	v_cvt_pk_f32_fp8_sdwa v[230:231], v161 src0_sel:WORD_1
	v_pk_fma_f32 v[64:65], v[224:225], v[248:249], v[64:65] op_sel_hi:[1,0,1]
	v_pk_fma_f32 v[66:67], v[226:227], v[248:249], v[66:67] op_sel_hi:[1,0,1]
	v_pk_fma_f32 v[68:69], v[228:229], v[248:249], v[68:69] op_sel_hi:[1,0,1]
	v_pk_fma_f32 v[70:71], v[230:231], v[248:249], v[70:71] op_sel_hi:[1,0,1]
	v_cvt_pk_f32_fp8_e32 v[224:225], v162
	v_cvt_pk_f32_fp8_sdwa v[226:227], v162 src0_sel:WORD_1
	v_cvt_pk_f32_fp8_e32 v[228:229], v163
	v_cvt_pk_f32_fp8_sdwa v[230:231], v163 src0_sel:WORD_1
	v_pk_fma_f32 v[72:73], v[224:225], v[248:249], v[72:73] op_sel_hi:[1,0,1]
	v_pk_fma_f32 v[74:75], v[226:227], v[248:249], v[74:75] op_sel_hi:[1,0,1]
	v_pk_fma_f32 v[76:77], v[228:229], v[248:249], v[76:77] op_sel_hi:[1,0,1]
	v_pk_fma_f32 v[78:79], v[230:231], v[248:249], v[78:79] op_sel_hi:[1,0,1]
	v_cvt_pk_f32_fp8_e32 v[224:225], v164
	v_cvt_pk_f32_fp8_sdwa v[226:227], v164 src0_sel:WORD_1
	v_cvt_pk_f32_fp8_e32 v[228:229], v165
	v_cvt_pk_f32_fp8_sdwa v[230:231], v165 src0_sel:WORD_1
	v_pk_fma_f32 v[64:65], v[224:225], v[248:249], v[64:65] op_sel:[0,1,0] op_sel_hi:[1,1,1]
	v_pk_fma_f32 v[66:67], v[226:227], v[248:249], v[66:67] op_sel:[0,1,0] op_sel_hi:[1,1,1]
	v_pk_fma_f32 v[68:69], v[228:229], v[248:249], v[68:69] op_sel:[0,1,0] op_sel_hi:[1,1,1]
	v_pk_fma_f32 v[70:71], v[230:231], v[248:249], v[70:71] op_sel:[0,1,0] op_sel_hi:[1,1,1]
	v_cvt_pk_f32_fp8_e32 v[224:225], v166
	v_cvt_pk_f32_fp8_sdwa v[226:227], v166 src0_sel:WORD_1
	v_cvt_pk_f32_fp8_e32 v[228:229], v167
	v_cvt_pk_f32_fp8_sdwa v[230:231], v167 src0_sel:WORD_1
	v_pk_fma_f32 v[72:73], v[224:225], v[248:249], v[72:73] op_sel:[0,1,0] op_sel_hi:[1,1,1]
	v_pk_fma_f32 v[74:75], v[226:227], v[248:249], v[74:75] op_sel:[0,1,0] op_sel_hi:[1,1,1]
	v_pk_fma_f32 v[76:77], v[228:229], v[248:249], v[76:77] op_sel:[0,1,0] op_sel_hi:[1,1,1]
	v_pk_fma_f32 v[78:79], v[230:231], v[248:249], v[78:79] op_sel:[0,1,0] op_sel_hi:[1,1,1]
	v_cvt_pk_f32_fp8_e32 v[224:225], v168
	v_cvt_pk_f32_fp8_sdwa v[226:227], v168 src0_sel:WORD_1
	v_cvt_pk_f32_fp8_e32 v[228:229], v169
	v_cvt_pk_f32_fp8_sdwa v[230:231], v169 src0_sel:WORD_1
	v_pk_fma_f32 v[64:65], v[224:225], v[250:251], v[64:65] op_sel_hi:[1,0,1]
	v_pk_fma_f32 v[66:67], v[226:227], v[250:251], v[66:67] op_sel_hi:[1,0,1]
	v_pk_fma_f32 v[68:69], v[228:229], v[250:251], v[68:69] op_sel_hi:[1,0,1]
	v_pk_fma_f32 v[70:71], v[230:231], v[250:251], v[70:71] op_sel_hi:[1,0,1]
	v_cvt_pk_f32_fp8_e32 v[224:225], v170
	v_cvt_pk_f32_fp8_sdwa v[226:227], v170 src0_sel:WORD_1
	v_cvt_pk_f32_fp8_e32 v[228:229], v171
	v_cvt_pk_f32_fp8_sdwa v[230:231], v171 src0_sel:WORD_1
	v_pk_fma_f32 v[72:73], v[224:225], v[250:251], v[72:73] op_sel_hi:[1,0,1]
	v_pk_fma_f32 v[74:75], v[226:227], v[250:251], v[74:75] op_sel_hi:[1,0,1]
	v_pk_fma_f32 v[76:77], v[228:229], v[250:251], v[76:77] op_sel_hi:[1,0,1]
	v_pk_fma_f32 v[78:79], v[230:231], v[250:251], v[78:79] op_sel_hi:[1,0,1]
	v_cvt_pk_f32_fp8_e32 v[224:225], v172
	v_cvt_pk_f32_fp8_sdwa v[226:227], v172 src0_sel:WORD_1
	v_cvt_pk_f32_fp8_e32 v[228:229], v173
	v_cvt_pk_f32_fp8_sdwa v[230:231], v173 src0_sel:WORD_1
	v_pk_fma_f32 v[64:65], v[224:225], v[250:251], v[64:65] op_sel:[0,1,0] op_sel_hi:[1,1,1]
	v_pk_fma_f32 v[66:67], v[226:227], v[250:251], v[66:67] op_sel:[0,1,0] op_sel_hi:[1,1,1]
	v_pk_fma_f32 v[68:69], v[228:229], v[250:251], v[68:69] op_sel:[0,1,0] op_sel_hi:[1,1,1]
	v_pk_fma_f32 v[70:71], v[230:231], v[250:251], v[70:71] op_sel:[0,1,0] op_sel_hi:[1,1,1]
	v_cvt_pk_f32_fp8_e32 v[224:225], v174
	v_cvt_pk_f32_fp8_sdwa v[226:227], v174 src0_sel:WORD_1
	v_cvt_pk_f32_fp8_e32 v[228:229], v175
	v_cvt_pk_f32_fp8_sdwa v[230:231], v175 src0_sel:WORD_1
	v_pk_fma_f32 v[72:73], v[224:225], v[250:251], v[72:73] op_sel:[0,1,0] op_sel_hi:[1,1,1]
	v_pk_fma_f32 v[74:75], v[226:227], v[250:251], v[74:75] op_sel:[0,1,0] op_sel_hi:[1,1,1]
	v_pk_fma_f32 v[76:77], v[228:229], v[250:251], v[76:77] op_sel:[0,1,0] op_sel_hi:[1,1,1]
	v_pk_fma_f32 v[78:79], v[230:231], v[250:251], v[78:79] op_sel:[0,1,0] op_sel_hi:[1,1,1]
	s_sub_i32 s90, s90, 1
	s_cmp_eq_u32 s90, 0
	s_cbranch_scc1 .LV_sw3
.LV_t4_s3:
	s_waitcnt lgkmcnt(0)
	v_add_u32_e32 v236, v232, v240
	v_add_u32_e32 v237, v233, v240
	v_add_u32_e32 v238, v234, v240
	v_add_u32_e32 v239, v235, v240
	global_load_dwordx4 v[160:163], v236, s[6:7]
	global_load_dwordx4 v[164:167], v237, s[6:7]
	global_load_dwordx4 v[168:171], v238, s[6:7]
	global_load_dwordx4 v[172:175], v239, s[6:7]
	ds_read_b128 v[232:235], v213 offset:112
	ds_read_b128 v[248:251], v213 offset:5056
	s_waitcnt vmcnt(12)
	v_cvt_pk_f32_fp8_e32 v[224:225], v176
	v_cvt_pk_f32_fp8_sdwa v[226:227], v176 src0_sel:WORD_1
	v_cvt_pk_f32_fp8_e32 v[228:229], v177
	v_cvt_pk_f32_fp8_sdwa v[230:231], v177 src0_sel:WORD_1
	v_pk_fma_f32 v[64:65], v[224:225], v[252:253], v[64:65] op_sel_hi:[1,0,1]
	v_pk_fma_f32 v[66:67], v[226:227], v[252:253], v[66:67] op_sel_hi:[1,0,1]
	v_pk_fma_f32 v[68:69], v[228:229], v[252:253], v[68:69] op_sel_hi:[1,0,1]
	v_pk_fma_f32 v[70:71], v[230:231], v[252:253], v[70:71] op_sel_hi:[1,0,1]
	v_cvt_pk_f32_fp8_e32 v[224:225], v178
	v_cvt_pk_f32_fp8_sdwa v[226:227], v178 src0_sel:WORD_1
	v_cvt_pk_f32_fp8_e32 v[228:229], v179
	v_cvt_pk_f32_fp8_sdwa v[230:231], v179 src0_sel:WORD_1
	v_pk_fma_f32 v[72:73], v[224:225], v[252:253], v[72:73] op_sel_hi:[1,0,1]
	v_pk_fma_f32 v[74:75], v[226:227], v[252:253], v[74:75] op_sel_hi:[1,0,1]
	v_pk_fma_f32 v[76:77], v[228:229], v[252:253], v[76:77] op_sel_hi:[1,0,1]
	v_pk_fma_f32 v[78:79], v[230:231], v[252:253], v[78:79] op_sel_hi:[1,0,1]
	v_cvt_pk_f32_fp8_e32 v[224:225], v180
	v_cvt_pk_f32_fp8_sdwa v[226:227], v180 src0_sel:WORD_1
	v_cvt_pk_f32_fp8_e32 v[228:229], v181
	v_cvt_pk_f32_fp8_sdwa v[230:231], v181 src0_sel:WORD_1
	v_pk_fma_f32 v[64:65], v[224:225], v[252:253], v[64:65] op_sel:[0,1,0] op_sel_hi:[1,1,1]
	v_pk_fma_f32 v[66:67], v[226:227], v[252:253], v[66:67] op_sel:[0,1,0] op_sel_hi:[1,1,1]
	v_pk_fma_f32 v[68:69], v[228:229], v[252:253], v[68:69] op_sel:[0,1,0] op_sel_hi:[1,1,1]
	v_pk_fma_f32 v[70:71], v[230:231], v[252:253], v[70:71] op_sel:[0,1,0] op_sel_hi:[1,1,1]
	v_cvt_pk_f32_fp8_e32 v[224:225], v182
	v_cvt_pk_f32_fp8_sdwa v[226:227], v182 src0_sel:WORD_1
	v_cvt_pk_f32_fp8_e32 v[228:229], v183
	v_cvt_pk_f32_fp8_sdwa v[230:231], v183 src0_sel:WORD_1
	v_pk_fma_f32 v[72:73], v[224:225], v[252:253], v[72:73] op_sel:[0,1,0] op_sel_hi:[1,1,1]
	v_pk_fma_f32 v[74:75], v[226:227], v[252:253], v[74:75] op_sel:[0,1,0] op_sel_hi:[1,1,1]
	v_pk_fma_f32 v[76:77], v[228:229], v[252:253], v[76:77] op_sel:[0,1,0] op_sel_hi:[1,1,1]
	v_pk_fma_f32 v[78:79], v[230:231], v[252:253], v[78:79] op_sel:[0,1,0] op_sel_hi:[1,1,1]
	v_cvt_pk_f32_fp8_e32 v[224:225], v184
	v_cvt_pk_f32_fp8_sdwa v[226:227], v184 src0_sel:WORD_1
	v_cvt_pk_f32_fp8_e32 v[228:229], v185
	v_cvt_pk_f32_fp8_sdwa v[230:231], v185 src0_sel:WORD_1
	v_pk_fma_f32 v[64:65], v[224:225], v[254:255], v[64:65] op_sel_hi:[1,0,1]
	v_pk_fma_f32 v[66:67], v[226:227], v[254:255], v[66:67] op_sel_hi:[1,0,1]
	v_pk_fma_f32 v[68:69], v[228:229], v[254:255], v[68:69] op_sel_hi:[1,0,1]
	v_pk_fma_f32 v[70:71], v[230:231], v[254:255], v[70:71] op_sel_hi:[1,0,1]
	v_cvt_pk_f32_fp8_e32 v[224:225], v186
	v_cvt_pk_f32_fp8_sdwa v[226:227], v186 src0_sel:WORD_1
	v_cvt_pk_f32_fp8_e32 v[228:229], v187
	v_cvt_pk_f32_fp8_sdwa v[230:231], v187 src0_sel:WORD_1
	v_pk_fma_f32 v[72:73], v[224:225], v[254:255], v[72:73] op_sel_hi:[1,0,1]
	v_pk_fma_f32 v[74:75], v[226:227], v[254:255], v[74:75] op_sel_hi:[1,0,1]
	v_pk_fma_f32 v[76:77], v[228:229], v[254:255], v[76:77] op_sel_hi:[1,0,1]
	v_pk_fma_f32 v[78:79], v[230:231], v[254:255], v[78:79] op_sel_hi:[1,0,1]
	v_cvt_pk_f32_fp8_e32 v[224:225], v188
	v_cvt_pk_f32_fp8_sdwa v[226:227], v188 src0_sel:WORD_1
	v_cvt_pk_f32_fp8_e32 v[228:229], v189
	v_cvt_pk_f32_fp8_sdwa v[230:231], v189 src0_sel:WORD_1
	v_pk_fma_f32 v[64:65], v[224:225], v[254:255], v[64:65] op_sel:[0,1,0] op_sel_hi:[1,1,1]
	v_pk_fma_f32 v[66:67], v[226:227], v[254:255], v[66:67] op_sel:[0,1,0] op_sel_hi:[1,1,1]
	v_pk_fma_f32 v[68:69], v[228:229], v[254:255], v[68:69] op_sel:[0,1,0] op_sel_hi:[1,1,1]
	v_pk_fma_f32 v[70:71], v[230:231], v[254:255], v[70:71] op_sel:[0,1,0] op_sel_hi:[1,1,1]
	v_cvt_pk_f32_fp8_e32 v[224:225], v190
	v_cvt_pk_f32_fp8_sdwa v[226:227], v190 src0_sel:WORD_1
	v_cvt_pk_f32_fp8_e32 v[228:229], v191
	v_cvt_pk_f32_fp8_sdwa v[230:231], v191 src0_sel:WORD_1
	v_pk_fma_f32 v[72:73], v[224:225], v[254:255], v[72:73] op_sel:[0,1,0] op_sel_hi:[1,1,1]
	v_pk_fma_f32 v[74:75], v[226:227], v[254:255], v[74:75] op_sel:[0,1,0] op_sel_hi:[1,1,1]
	v_pk_fma_f32 v[76:77], v[228:229], v[254:255], v[76:77] op_sel:[0,1,0] op_sel_hi:[1,1,1]
	v_pk_fma_f32 v[78:79], v[230:231], v[254:255], v[78:79] op_sel:[0,1,0] op_sel_hi:[1,1,1]
	v_add_u32_e32 v213, 64, v213
	s_add_i32 s21, s21, 4
	s_sub_i32 s90, s90, 1
	s_cmp_eq_u32 s90, 0
	s_cbranch_scc1 .LV_sw0
	s_branch .LV_t4_s0
.LV_t5_s0:
	s_cmp_ge_u32 s21, s20
	s_cbranch_scc1 .LV_done
	s_waitcnt lgkmcnt(0)
	v_add_u32_e32 v236, v232, v240
	v_add_u32_e32 v237, v233, v240
	v_add_u32_e32 v238, v234, v240
	v_add_u32_e32 v239, v235, v240
	global_load_dwordx4 v[176:179], v236, s[6:7]
	global_load_dwordx4 v[180:183], v237, s[6:7]
	global_load_dwordx4 v[184:187], v238, s[6:7]
	global_load_dwordx4 v[188:191], v239, s[6:7]
	ds_read_b128 v[232:235], v213 offset:64
	ds_read_b128 v[252:255], v213 offset:5008
	s_waitcnt vmcnt(12)
	v_cvt_pk_f32_fp8_e32 v[224:225], v128
	v_cvt_pk_f32_fp8_sdwa v[226:227], v128 src0_sel:WORD_1
	v_cvt_pk_f32_fp8_e32 v[228:229], v129
	v_cvt_pk_f32_fp8_sdwa v[230:231], v129 src0_sel:WORD_1
	v_pk_fma_f32 v[80:81], v[224:225], v[248:249], v[80:81] op_sel_hi:[1,0,1]
	v_pk_fma_f32 v[82:83], v[226:227], v[248:249], v[82:83] op_sel_hi:[1,0,1]
	v_pk_fma_f32 v[84:85], v[228:229], v[248:249], v[84:85] op_sel_hi:[1,0,1]
	v_pk_fma_f32 v[86:87], v[230:231], v[248:249], v[86:87] op_sel_hi:[1,0,1]
	v_cvt_pk_f32_fp8_e32 v[224:225], v130
	v_cvt_pk_f32_fp8_sdwa v[226:227], v130 src0_sel:WORD_1
	v_cvt_pk_f32_fp8_e32 v[228:229], v131
	v_cvt_pk_f32_fp8_sdwa v[230:231], v131 src0_sel:WORD_1
	v_pk_fma_f32 v[88:89], v[224:225], v[248:249], v[88:89] op_sel_hi:[1,0,1]
	v_pk_fma_f32 v[90:91], v[226:227], v[248:249], v[90:91] op_sel_hi:[1,0,1]
	v_pk_fma_f32 v[92:93], v[228:229], v[248:249], v[92:93] op_sel_hi:[1,0,1]
	v_pk_fma_f32 v[94:95], v[230:231], v[248:249], v[94:95] op_sel_hi:[1,0,1]
	v_cvt_pk_f32_fp8_e32 v[224:225], v132
	v_cvt_pk_f32_fp8_sdwa v[226:227], v132 src0_sel:WORD_1
	v_cvt_pk_f32_fp8_e32 v[228:229], v133
	v_cvt_pk_f32_fp8_sdwa v[230:231], v133 src0_sel:WORD_1
	v_pk_fma_f32 v[80:81], v[224:225], v[248:249], v[80:81] op_sel:[0,1,0] op_sel_hi:[1,1,1]
	v_pk_fma_f32 v[82:83], v[226:227], v[248:249], v[82:83] op_sel:[0,1,0] op_sel_hi:[1,1,1]
	v_pk_fma_f32 v[84:85], v[228:229], v[248:249], v[84:85] op_sel:[0,1,0] op_sel_hi:[1,1,1]
	v_pk_fma_f32 v[86:87], v[230:231], v[248:249], v[86:87] op_sel:[0,1,0] op_sel_hi:[1,1,1]
	v_cvt_pk_f32_fp8_e32 v[224:225], v134
	v_cvt_pk_f32_fp8_sdwa v[226:227], v134 src0_sel:WORD_1
	v_cvt_pk_f32_fp8_e32 v[228:229], v135
	v_cvt_pk_f32_fp8_sdwa v[230:231], v135 src0_sel:WORD_1
	v_pk_fma_f32 v[88:89], v[224:225], v[248:249], v[88:89] op_sel:[0,1,0] op_sel_hi:[1,1,1]
	v_pk_fma_f32 v[90:91], v[226:227], v[248:249], v[90:91] op_sel:[0,1,0] op_sel_hi:[1,1,1]
	v_pk_fma_f32 v[92:93], v[228:229], v[248:249], v[92:93] op_sel:[0,1,0] op_sel_hi:[1,1,1]
	v_pk_fma_f32 v[94:95], v[230:231], v[248:249], v[94:95] op_sel:[0,1,0] op_sel_hi:[1,1,1]
	v_cvt_pk_f32_fp8_e32 v[224:225], v136
	v_cvt_pk_f32_fp8_sdwa v[226:227], v136 src0_sel:WORD_1
	v_cvt_pk_f32_fp8_e32 v[228:229], v137
	v_cvt_pk_f32_fp8_sdwa v[230:231], v137 src0_sel:WORD_1
	v_pk_fma_f32 v[80:81], v[224:225], v[250:251], v[80:81] op_sel_hi:[1,0,1]
	v_pk_fma_f32 v[82:83], v[226:227], v[250:251], v[82:83] op_sel_hi:[1,0,1]
	v_pk_fma_f32 v[84:85], v[228:229], v[250:251], v[84:85] op_sel_hi:[1,0,1]
	v_pk_fma_f32 v[86:87], v[230:231], v[250:251], v[86:87] op_sel_hi:[1,0,1]
	v_cvt_pk_f32_fp8_e32 v[224:225], v138
	v_cvt_pk_f32_fp8_sdwa v[226:227], v138 src0_sel:WORD_1
	v_cvt_pk_f32_fp8_e32 v[228:229], v139
	v_cvt_pk_f32_fp8_sdwa v[230:231], v139 src0_sel:WORD_1
	v_pk_fma_f32 v[88:89], v[224:225], v[250:251], v[88:89] op_sel_hi:[1,0,1]
	v_pk_fma_f32 v[90:91], v[226:227], v[250:251], v[90:91] op_sel_hi:[1,0,1]
	v_pk_fma_f32 v[92:93], v[228:229], v[250:251], v[92:93] op_sel_hi:[1,0,1]
	v_pk_fma_f32 v[94:95], v[230:231], v[250:251], v[94:95] op_sel_hi:[1,0,1]
	v_cvt_pk_f32_fp8_e32 v[224:225], v140
	v_cvt_pk_f32_fp8_sdwa v[226:227], v140 src0_sel:WORD_1
	v_cvt_pk_f32_fp8_e32 v[228:229], v141
	v_cvt_pk_f32_fp8_sdwa v[230:231], v141 src0_sel:WORD_1
	v_pk_fma_f32 v[80:81], v[224:225], v[250:251], v[80:81] op_sel:[0,1,0] op_sel_hi:[1,1,1]
	v_pk_fma_f32 v[82:83], v[226:227], v[250:251], v[82:83] op_sel:[0,1,0] op_sel_hi:[1,1,1]
	v_pk_fma_f32 v[84:85], v[228:229], v[250:251], v[84:85] op_sel:[0,1,0] op_sel_hi:[1,1,1]
	v_pk_fma_f32 v[86:87], v[230:231], v[250:251], v[86:87] op_sel:[0,1,0] op_sel_hi:[1,1,1]
	v_cvt_pk_f32_fp8_e32 v[224:225], v142
	v_cvt_pk_f32_fp8_sdwa v[226:227], v142 src0_sel:WORD_1
	v_cvt_pk_f32_fp8_e32 v[228:229], v143
	v_cvt_pk_f32_fp8_sdwa v[230:231], v143 src0_sel:WORD_1
	v_pk_fma_f32 v[88:89], v[224:225], v[250:251], v[88:89] op_sel:[0,1,0] op_sel_hi:[1,1,1]
	v_pk_fma_f32 v[90:91], v[226:227], v[250:251], v[90:91] op_sel:[0,1,0] op_sel_hi:[1,1,1]
	v_pk_fma_f32 v[92:93], v[228:229], v[250:251], v[92:93] op_sel:[0,1,0] op_sel_hi:[1,1,1]
	v_pk_fma_f32 v[94:95], v[230:231], v[250:251], v[94:95] op_sel:[0,1,0] op_sel_hi:[1,1,1]
	s_sub_i32 s90, s90, 1
	s_cmp_eq_u32 s90, 0
	s_cbranch_scc1 .LV_sw1
.LV_t5_s1:
	s_waitcnt lgkmcnt(0)
	v_add_u32_e32 v236, v232, v240
	v_add_u32_e32 v237, v233, v240
	v_add_u32_e32 v238, v234, v240
	v_add_u32_e32 v239, v235, v240
	global_load_dwordx4 v[128:131], v236, s[6:7]
	global_load_dwordx4 v[132:135], v237, s[6:7]
	global_load_dwordx4 v[136:139], v238, s[6:7]
	global_load_dwordx4 v[140:143], v239, s[6:7]
	ds_read_b128 v[232:235], v213 offset:80
	ds_read_b128 v[248:251], v213 offset:5024
	s_waitcnt vmcnt(12)
	v_cvt_pk_f32_fp8_e32 v[224:225], v144
	v_cvt_pk_f32_fp8_sdwa v[226:227], v144 src0_sel:WORD_1
	v_cvt_pk_f32_fp8_e32 v[228:229], v145
	v_cvt_pk_f32_fp8_sdwa v[230:231], v145 src0_sel:WORD_1
	v_pk_fma_f32 v[80:81], v[224:225], v[252:253], v[80:81] op_sel_hi:[1,0,1]
	v_pk_fma_f32 v[82:83], v[226:227], v[252:253], v[82:83] op_sel_hi:[1,0,1]
	v_pk_fma_f32 v[84:85], v[228:229], v[252:253], v[84:85] op_sel_hi:[1,0,1]
	v_pk_fma_f32 v[86:87], v[230:231], v[252:253], v[86:87] op_sel_hi:[1,0,1]
	v_cvt_pk_f32_fp8_e32 v[224:225], v146
	v_cvt_pk_f32_fp8_sdwa v[226:227], v146 src0_sel:WORD_1
	v_cvt_pk_f32_fp8_e32 v[228:229], v147
	v_cvt_pk_f32_fp8_sdwa v[230:231], v147 src0_sel:WORD_1
	v_pk_fma_f32 v[88:89], v[224:225], v[252:253], v[88:89] op_sel_hi:[1,0,1]
	v_pk_fma_f32 v[90:91], v[226:227], v[252:253], v[90:91] op_sel_hi:[1,0,1]
	v_pk_fma_f32 v[92:93], v[228:229], v[252:253], v[92:93] op_sel_hi:[1,0,1]
	v_pk_fma_f32 v[94:95], v[230:231], v[252:253], v[94:95] op_sel_hi:[1,0,1]
	v_cvt_pk_f32_fp8_e32 v[224:225], v148
	v_cvt_pk_f32_fp8_sdwa v[226:227], v148 src0_sel:WORD_1
	v_cvt_pk_f32_fp8_e32 v[228:229], v149
	v_cvt_pk_f32_fp8_sdwa v[230:231], v149 src0_sel:WORD_1
	v_pk_fma_f32 v[80:81], v[224:225], v[252:253], v[80:81] op_sel:[0,1,0] op_sel_hi:[1,1,1]
	v_pk_fma_f32 v[82:83], v[226:227], v[252:253], v[82:83] op_sel:[0,1,0] op_sel_hi:[1,1,1]
	v_pk_fma_f32 v[84:85], v[228:229], v[252:253], v[84:85] op_sel:[0,1,0] op_sel_hi:[1,1,1]
	v_pk_fma_f32 v[86:87], v[230:231], v[252:253], v[86:87] op_sel:[0,1,0] op_sel_hi:[1,1,1]
	v_cvt_pk_f32_fp8_e32 v[224:225], v150
	v_cvt_pk_f32_fp8_sdwa v[226:227], v150 src0_sel:WORD_1
	v_cvt_pk_f32_fp8_e32 v[228:229], v151
	v_cvt_pk_f32_fp8_sdwa v[230:231], v151 src0_sel:WORD_1
	v_pk_fma_f32 v[88:89], v[224:225], v[252:253], v[88:89] op_sel:[0,1,0] op_sel_hi:[1,1,1]
	v_pk_fma_f32 v[90:91], v[226:227], v[252:253], v[90:91] op_sel:[0,1,0] op_sel_hi:[1,1,1]
	v_pk_fma_f32 v[92:93], v[228:229], v[252:253], v[92:93] op_sel:[0,1,0] op_sel_hi:[1,1,1]
	v_pk_fma_f32 v[94:95], v[230:231], v[252:253], v[94:95] op_sel:[0,1,0] op_sel_hi:[1,1,1]
	v_cvt_pk_f32_fp8_e32 v[224:225], v152
	v_cvt_pk_f32_fp8_sdwa v[226:227], v152 src0_sel:WORD_1
	v_cvt_pk_f32_fp8_e32 v[228:229], v153
	v_cvt_pk_f32_fp8_sdwa v[230:231], v153 src0_sel:WORD_1
	v_pk_fma_f32 v[80:81], v[224:225], v[254:255], v[80:81] op_sel_hi:[1,0,1]
	v_pk_fma_f32 v[82:83], v[226:227], v[254:255], v[82:83] op_sel_hi:[1,0,1]
	v_pk_fma_f32 v[84:85], v[228:229], v[254:255], v[84:85] op_sel_hi:[1,0,1]
	v_pk_fma_f32 v[86:87], v[230:231], v[254:255], v[86:87] op_sel_hi:[1,0,1]
	v_cvt_pk_f32_fp8_e32 v[224:225], v154
	v_cvt_pk_f32_fp8_sdwa v[226:227], v154 src0_sel:WORD_1
	v_cvt_pk_f32_fp8_e32 v[228:229], v155
	v_cvt_pk_f32_fp8_sdwa v[230:231], v155 src0_sel:WORD_1
	v_pk_fma_f32 v[88:89], v[224:225], v[254:255], v[88:89] op_sel_hi:[1,0,1]
	v_pk_fma_f32 v[90:91], v[226:227], v[254:255], v[90:91] op_sel_hi:[1,0,1]
	v_pk_fma_f32 v[92:93], v[228:229], v[254:255], v[92:93] op_sel_hi:[1,0,1]
	v_pk_fma_f32 v[94:95], v[230:231], v[254:255], v[94:95] op_sel_hi:[1,0,1]
	v_cvt_pk_f32_fp8_e32 v[224:225], v156
	v_cvt_pk_f32_fp8_sdwa v[226:227], v156 src0_sel:WORD_1
	v_cvt_pk_f32_fp8_e32 v[228:229], v157
	v_cvt_pk_f32_fp8_sdwa v[230:231], v157 src0_sel:WORD_1
	v_pk_fma_f32 v[80:81], v[224:225], v[254:255], v[80:81] op_sel:[0,1,0] op_sel_hi:[1,1,1]
	v_pk_fma_f32 v[82:83], v[226:227], v[254:255], v[82:83] op_sel:[0,1,0] op_sel_hi:[1,1,1]
	v_pk_fma_f32 v[84:85], v[228:229], v[254:255], v[84:85] op_sel:[0,1,0] op_sel_hi:[1,1,1]
	v_pk_fma_f32 v[86:87], v[230:231], v[254:255], v[86:87] op_sel:[0,1,0] op_sel_hi:[1,1,1]
	v_cvt_pk_f32_fp8_e32 v[224:225], v158
	v_cvt_pk_f32_fp8_sdwa v[226:227], v158 src0_sel:WORD_1
	v_cvt_pk_f32_fp8_e32 v[228:229], v159
	v_cvt_pk_f32_fp8_sdwa v[230:231], v159 src0_sel:WORD_1
	v_pk_fma_f32 v[88:89], v[224:225], v[254:255], v[88:89] op_sel:[0,1,0] op_sel_hi:[1,1,1]
	v_pk_fma_f32 v[90:91], v[226:227], v[254:255], v[90:91] op_sel:[0,1,0] op_sel_hi:[1,1,1]
	v_pk_fma_f32 v[92:93], v[228:229], v[254:255], v[92:93] op_sel:[0,1,0] op_sel_hi:[1,1,1]
	v_pk_fma_f32 v[94:95], v[230:231], v[254:255], v[94:95] op_sel:[0,1,0] op_sel_hi:[1,1,1]
	s_sub_i32 s90, s90, 1
	s_cmp_eq_u32 s90, 0
	s_cbranch_scc1 .LV_sw2
.LV_t5_s2:
	s_waitcnt lgkmcnt(0)
	v_add_u32_e32 v236, v232, v240
	v_add_u32_e32 v237, v233, v240
	v_add_u32_e32 v238, v234, v240
	v_add_u32_e32 v239, v235, v240
	global_load_dwordx4 v[144:147], v236, s[6:7]
	global_load_dwordx4 v[148:151], v237, s[6:7]
	global_load_dwordx4 v[152:155], v238, s[6:7]
	global_load_dwordx4 v[156:159], v239, s[6:7]
	ds_read_b128 v[232:235], v213 offset:96
	ds_read_b128 v[252:255], v213 offset:5040
	s_waitcnt vmcnt(12)
	v_cvt_pk_f32_fp8_e32 v[224:225], v160
	v_cvt_pk_f32_fp8_sdwa v[226:227], v160 src0_sel:WORD_1
	v_cvt_pk_f32_fp8_e32 v[228:229], v161
	v_cvt_pk_f32_fp8_sdwa v[230:231], v161 src0_sel:WORD_1
	v_pk_fma_f32 v[80:81], v[224:225], v[248:249], v[80:81] op_sel_hi:[1,0,1]
	v_pk_fma_f32 v[82:83], v[226:227], v[248:249], v[82:83] op_sel_hi:[1,0,1]
	v_pk_fma_f32 v[84:85], v[228:229], v[248:249], v[84:85] op_sel_hi:[1,0,1]
	v_pk_fma_f32 v[86:87], v[230:231], v[248:249], v[86:87] op_sel_hi:[1,0,1]
	v_cvt_pk_f32_fp8_e32 v[224:225], v162
	v_cvt_pk_f32_fp8_sdwa v[226:227], v162 src0_sel:WORD_1
	v_cvt_pk_f32_fp8_e32 v[228:229], v163
	v_cvt_pk_f32_fp8_sdwa v[230:231], v163 src0_sel:WORD_1
	v_pk_fma_f32 v[88:89], v[224:225], v[248:249], v[88:89] op_sel_hi:[1,0,1]
	v_pk_fma_f32 v[90:91], v[226:227], v[248:249], v[90:91] op_sel_hi:[1,0,1]
	v_pk_fma_f32 v[92:93], v[228:229], v[248:249], v[92:93] op_sel_hi:[1,0,1]
	v_pk_fma_f32 v[94:95], v[230:231], v[248:249], v[94:95] op_sel_hi:[1,0,1]
	v_cvt_pk_f32_fp8_e32 v[224:225], v164
	v_cvt_pk_f32_fp8_sdwa v[226:227], v164 src0_sel:WORD_1
	v_cvt_pk_f32_fp8_e32 v[228:229], v165
	v_cvt_pk_f32_fp8_sdwa v[230:231], v165 src0_sel:WORD_1
	v_pk_fma_f32 v[80:81], v[224:225], v[248:249], v[80:81] op_sel:[0,1,0] op_sel_hi:[1,1,1]
	v_pk_fma_f32 v[82:83], v[226:227], v[248:249], v[82:83] op_sel:[0,1,0] op_sel_hi:[1,1,1]
	v_pk_fma_f32 v[84:85], v[228:229], v[248:249], v[84:85] op_sel:[0,1,0] op_sel_hi:[1,1,1]
	v_pk_fma_f32 v[86:87], v[230:231], v[248:249], v[86:87] op_sel:[0,1,0] op_sel_hi:[1,1,1]
	v_cvt_pk_f32_fp8_e32 v[224:225], v166
	v_cvt_pk_f32_fp8_sdwa v[226:227], v166 src0_sel:WORD_1
	v_cvt_pk_f32_fp8_e32 v[228:229], v167
	v_cvt_pk_f32_fp8_sdwa v[230:231], v167 src0_sel:WORD_1
	v_pk_fma_f32 v[88:89], v[224:225], v[248:249], v[88:89] op_sel:[0,1,0] op_sel_hi:[1,1,1]
	v_pk_fma_f32 v[90:91], v[226:227], v[248:249], v[90:91] op_sel:[0,1,0] op_sel_hi:[1,1,1]
	v_pk_fma_f32 v[92:93], v[228:229], v[248:249], v[92:93] op_sel:[0,1,0] op_sel_hi:[1,1,1]
	v_pk_fma_f32 v[94:95], v[230:231], v[248:249], v[94:95] op_sel:[0,1,0] op_sel_hi:[1,1,1]
	v_cvt_pk_f32_fp8_e32 v[224:225], v168
	v_cvt_pk_f32_fp8_sdwa v[226:227], v168 src0_sel:WORD_1
	v_cvt_pk_f32_fp8_e32 v[228:229], v169
	v_cvt_pk_f32_fp8_sdwa v[230:231], v169 src0_sel:WORD_1
	v_pk_fma_f32 v[80:81], v[224:225], v[250:251], v[80:81] op_sel_hi:[1,0,1]
	v_pk_fma_f32 v[82:83], v[226:227], v[250:251], v[82:83] op_sel_hi:[1,0,1]
	v_pk_fma_f32 v[84:85], v[228:229], v[250:251], v[84:85] op_sel_hi:[1,0,1]
	v_pk_fma_f32 v[86:87], v[230:231], v[250:251], v[86:87] op_sel_hi:[1,0,1]
	v_cvt_pk_f32_fp8_e32 v[224:225], v170
	v_cvt_pk_f32_fp8_sdwa v[226:227], v170 src0_sel:WORD_1
	v_cvt_pk_f32_fp8_e32 v[228:229], v171
	v_cvt_pk_f32_fp8_sdwa v[230:231], v171 src0_sel:WORD_1
	v_pk_fma_f32 v[88:89], v[224:225], v[250:251], v[88:89] op_sel_hi:[1,0,1]
	v_pk_fma_f32 v[90:91], v[226:227], v[250:251], v[90:91] op_sel_hi:[1,0,1]
	v_pk_fma_f32 v[92:93], v[228:229], v[250:251], v[92:93] op_sel_hi:[1,0,1]
	v_pk_fma_f32 v[94:95], v[230:231], v[250:251], v[94:95] op_sel_hi:[1,0,1]
	v_cvt_pk_f32_fp8_e32 v[224:225], v172
	v_cvt_pk_f32_fp8_sdwa v[226:227], v172 src0_sel:WORD_1
	v_cvt_pk_f32_fp8_e32 v[228:229], v173
	v_cvt_pk_f32_fp8_sdwa v[230:231], v173 src0_sel:WORD_1
	v_pk_fma_f32 v[80:81], v[224:225], v[250:251], v[80:81] op_sel:[0,1,0] op_sel_hi:[1,1,1]
	v_pk_fma_f32 v[82:83], v[226:227], v[250:251], v[82:83] op_sel:[0,1,0] op_sel_hi:[1,1,1]
	v_pk_fma_f32 v[84:85], v[228:229], v[250:251], v[84:85] op_sel:[0,1,0] op_sel_hi:[1,1,1]
	v_pk_fma_f32 v[86:87], v[230:231], v[250:251], v[86:87] op_sel:[0,1,0] op_sel_hi:[1,1,1]
	v_cvt_pk_f32_fp8_e32 v[224:225], v174
	v_cvt_pk_f32_fp8_sdwa v[226:227], v174 src0_sel:WORD_1
	v_cvt_pk_f32_fp8_e32 v[228:229], v175
	v_cvt_pk_f32_fp8_sdwa v[230:231], v175 src0_sel:WORD_1
	v_pk_fma_f32 v[88:89], v[224:225], v[250:251], v[88:89] op_sel:[0,1,0] op_sel_hi:[1,1,1]
	v_pk_fma_f32 v[90:91], v[226:227], v[250:251], v[90:91] op_sel:[0,1,0] op_sel_hi:[1,1,1]
	v_pk_fma_f32 v[92:93], v[228:229], v[250:251], v[92:93] op_sel:[0,1,0] op_sel_hi:[1,1,1]
	v_pk_fma_f32 v[94:95], v[230:231], v[250:251], v[94:95] op_sel:[0,1,0] op_sel_hi:[1,1,1]
	s_sub_i32 s90, s90, 1
	s_cmp_eq_u32 s90, 0
	s_cbranch_scc1 .LV_sw3
.LV_t5_s3:
	s_waitcnt lgkmcnt(0)
	v_add_u32_e32 v236, v232, v240
	v_add_u32_e32 v237, v233, v240
	v_add_u32_e32 v238, v234, v240
	v_add_u32_e32 v239, v235, v240
	global_load_dwordx4 v[160:163], v236, s[6:7]
	global_load_dwordx4 v[164:167], v237, s[6:7]
	global_load_dwordx4 v[168:171], v238, s[6:7]
	global_load_dwordx4 v[172:175], v239, s[6:7]
	ds_read_b128 v[232:235], v213 offset:112
	ds_read_b128 v[248:251], v213 offset:5056
	s_waitcnt vmcnt(12)
	v_cvt_pk_f32_fp8_e32 v[224:225], v176
	v_cvt_pk_f32_fp8_sdwa v[226:227], v176 src0_sel:WORD_1
	v_cvt_pk_f32_fp8_e32 v[228:229], v177
	v_cvt_pk_f32_fp8_sdwa v[230:231], v177 src0_sel:WORD_1
	v_pk_fma_f32 v[80:81], v[224:225], v[252:253], v[80:81] op_sel_hi:[1,0,1]
	v_pk_fma_f32 v[82:83], v[226:227], v[252:253], v[82:83] op_sel_hi:[1,0,1]
	v_pk_fma_f32 v[84:85], v[228:229], v[252:253], v[84:85] op_sel_hi:[1,0,1]
	v_pk_fma_f32 v[86:87], v[230:231], v[252:253], v[86:87] op_sel_hi:[1,0,1]
	v_cvt_pk_f32_fp8_e32 v[224:225], v178
	v_cvt_pk_f32_fp8_sdwa v[226:227], v178 src0_sel:WORD_1
	v_cvt_pk_f32_fp8_e32 v[228:229], v179
	v_cvt_pk_f32_fp8_sdwa v[230:231], v179 src0_sel:WORD_1
	v_pk_fma_f32 v[88:89], v[224:225], v[252:253], v[88:89] op_sel_hi:[1,0,1]
	v_pk_fma_f32 v[90:91], v[226:227], v[252:253], v[90:91] op_sel_hi:[1,0,1]
	v_pk_fma_f32 v[92:93], v[228:229], v[252:253], v[92:93] op_sel_hi:[1,0,1]
	v_pk_fma_f32 v[94:95], v[230:231], v[252:253], v[94:95] op_sel_hi:[1,0,1]
	v_cvt_pk_f32_fp8_e32 v[224:225], v180
	v_cvt_pk_f32_fp8_sdwa v[226:227], v180 src0_sel:WORD_1
	v_cvt_pk_f32_fp8_e32 v[228:229], v181
	v_cvt_pk_f32_fp8_sdwa v[230:231], v181 src0_sel:WORD_1
	v_pk_fma_f32 v[80:81], v[224:225], v[252:253], v[80:81] op_sel:[0,1,0] op_sel_hi:[1,1,1]
	v_pk_fma_f32 v[82:83], v[226:227], v[252:253], v[82:83] op_sel:[0,1,0] op_sel_hi:[1,1,1]
	v_pk_fma_f32 v[84:85], v[228:229], v[252:253], v[84:85] op_sel:[0,1,0] op_sel_hi:[1,1,1]
	v_pk_fma_f32 v[86:87], v[230:231], v[252:253], v[86:87] op_sel:[0,1,0] op_sel_hi:[1,1,1]
	v_cvt_pk_f32_fp8_e32 v[224:225], v182
	v_cvt_pk_f32_fp8_sdwa v[226:227], v182 src0_sel:WORD_1
	v_cvt_pk_f32_fp8_e32 v[228:229], v183
	v_cvt_pk_f32_fp8_sdwa v[230:231], v183 src0_sel:WORD_1
	v_pk_fma_f32 v[88:89], v[224:225], v[252:253], v[88:89] op_sel:[0,1,0] op_sel_hi:[1,1,1]
	v_pk_fma_f32 v[90:91], v[226:227], v[252:253], v[90:91] op_sel:[0,1,0] op_sel_hi:[1,1,1]
	v_pk_fma_f32 v[92:93], v[228:229], v[252:253], v[92:93] op_sel:[0,1,0] op_sel_hi:[1,1,1]
	v_pk_fma_f32 v[94:95], v[230:231], v[252:253], v[94:95] op_sel:[0,1,0] op_sel_hi:[1,1,1]
	v_cvt_pk_f32_fp8_e32 v[224:225], v184
	v_cvt_pk_f32_fp8_sdwa v[226:227], v184 src0_sel:WORD_1
	v_cvt_pk_f32_fp8_e32 v[228:229], v185
	v_cvt_pk_f32_fp8_sdwa v[230:231], v185 src0_sel:WORD_1
	v_pk_fma_f32 v[80:81], v[224:225], v[254:255], v[80:81] op_sel_hi:[1,0,1]
	v_pk_fma_f32 v[82:83], v[226:227], v[254:255], v[82:83] op_sel_hi:[1,0,1]
	v_pk_fma_f32 v[84:85], v[228:229], v[254:255], v[84:85] op_sel_hi:[1,0,1]
	v_pk_fma_f32 v[86:87], v[230:231], v[254:255], v[86:87] op_sel_hi:[1,0,1]
	v_cvt_pk_f32_fp8_e32 v[224:225], v186
	v_cvt_pk_f32_fp8_sdwa v[226:227], v186 src0_sel:WORD_1
	v_cvt_pk_f32_fp8_e32 v[228:229], v187
	v_cvt_pk_f32_fp8_sdwa v[230:231], v187 src0_sel:WORD_1
	v_pk_fma_f32 v[88:89], v[224:225], v[254:255], v[88:89] op_sel_hi:[1,0,1]
	v_pk_fma_f32 v[90:91], v[226:227], v[254:255], v[90:91] op_sel_hi:[1,0,1]
	v_pk_fma_f32 v[92:93], v[228:229], v[254:255], v[92:93] op_sel_hi:[1,0,1]
	v_pk_fma_f32 v[94:95], v[230:231], v[254:255], v[94:95] op_sel_hi:[1,0,1]
	v_cvt_pk_f32_fp8_e32 v[224:225], v188
	v_cvt_pk_f32_fp8_sdwa v[226:227], v188 src0_sel:WORD_1
	v_cvt_pk_f32_fp8_e32 v[228:229], v189
	v_cvt_pk_f32_fp8_sdwa v[230:231], v189 src0_sel:WORD_1
	v_pk_fma_f32 v[80:81], v[224:225], v[254:255], v[80:81] op_sel:[0,1,0] op_sel_hi:[1,1,1]
	v_pk_fma_f32 v[82:83], v[226:227], v[254:255], v[82:83] op_sel:[0,1,0] op_sel_hi:[1,1,1]
	v_pk_fma_f32 v[84:85], v[228:229], v[254:255], v[84:85] op_sel:[0,1,0] op_sel_hi:[1,1,1]
	v_pk_fma_f32 v[86:87], v[230:231], v[254:255], v[86:87] op_sel:[0,1,0] op_sel_hi:[1,1,1]
	v_cvt_pk_f32_fp8_e32 v[224:225], v190
	v_cvt_pk_f32_fp8_sdwa v[226:227], v190 src0_sel:WORD_1
	v_cvt_pk_f32_fp8_e32 v[228:229], v191
	v_cvt_pk_f32_fp8_sdwa v[230:231], v191 src0_sel:WORD_1
	v_pk_fma_f32 v[88:89], v[224:225], v[254:255], v[88:89] op_sel:[0,1,0] op_sel_hi:[1,1,1]
	v_pk_fma_f32 v[90:91], v[226:227], v[254:255], v[90:91] op_sel:[0,1,0] op_sel_hi:[1,1,1]
	v_pk_fma_f32 v[92:93], v[228:229], v[254:255], v[92:93] op_sel:[0,1,0] op_sel_hi:[1,1,1]
	v_pk_fma_f32 v[94:95], v[230:231], v[254:255], v[94:95] op_sel:[0,1,0] op_sel_hi:[1,1,1]
	v_add_u32_e32 v213, 64, v213
	s_add_i32 s21, s21, 4
	s_sub_i32 s90, s90, 1
	s_cmp_eq_u32 s90, 0
	s_cbranch_scc1 .LV_sw0
	s_branch .LV_t5_s0
.LV_t6_s0:
	s_cmp_ge_u32 s21, s20
	s_cbranch_scc1 .LV_done
	s_waitcnt lgkmcnt(0)
	v_add_u32_e32 v236, v232, v240
	v_add_u32_e32 v237, v233, v240
	v_add_u32_e32 v238, v234, v240
	v_add_u32_e32 v239, v235, v240
	global_load_dwordx4 v[176:179], v236, s[6:7]
	global_load_dwordx4 v[180:183], v237, s[6:7]
	global_load_dwordx4 v[184:187], v238, s[6:7]
	global_load_dwordx4 v[188:191], v239, s[6:7]
	ds_read_b128 v[232:235], v213 offset:64
	ds_read_b128 v[252:255], v213 offset:5008
	s_waitcnt vmcnt(12)
	v_cvt_pk_f32_fp8_e32 v[224:225], v128
	v_cvt_pk_f32_fp8_sdwa v[226:227], v128 src0_sel:WORD_1
	v_cvt_pk_f32_fp8_e32 v[228:229], v129
	v_cvt_pk_f32_fp8_sdwa v[230:231], v129 src0_sel:WORD_1
	v_pk_fma_f32 v[96:97], v[224:225], v[248:249], v[96:97] op_sel_hi:[1,0,1]
	v_pk_fma_f32 v[98:99], v[226:227], v[248:249], v[98:99] op_sel_hi:[1,0,1]
	v_pk_fma_f32 v[100:101], v[228:229], v[248:249], v[100:101] op_sel_hi:[1,0,1]
	v_pk_fma_f32 v[102:103], v[230:231], v[248:249], v[102:103] op_sel_hi:[1,0,1]
	v_cvt_pk_f32_fp8_e32 v[224:225], v130
	v_cvt_pk_f32_fp8_sdwa v[226:227], v130 src0_sel:WORD_1
	v_cvt_pk_f32_fp8_e32 v[228:229], v131
	v_cvt_pk_f32_fp8_sdwa v[230:231], v131 src0_sel:WORD_1
	v_pk_fma_f32 v[104:105], v[224:225], v[248:249], v[104:105] op_sel_hi:[1,0,1]
	v_pk_fma_f32 v[106:107], v[226:227], v[248:249], v[106:107] op_sel_hi:[1,0,1]
	v_pk_fma_f32 v[108:109], v[228:229], v[248:249], v[108:109] op_sel_hi:[1,0,1]
	v_pk_fma_f32 v[110:111], v[230:231], v[248:249], v[110:111] op_sel_hi:[1,0,1]
	v_cvt_pk_f32_fp8_e32 v[224:225], v132
	v_cvt_pk_f32_fp8_sdwa v[226:227], v132 src0_sel:WORD_1
	v_cvt_pk_f32_fp8_e32 v[228:229], v133
	v_cvt_pk_f32_fp8_sdwa v[230:231], v133 src0_sel:WORD_1
	v_pk_fma_f32 v[96:97], v[224:225], v[248:249], v[96:97] op_sel:[0,1,0] op_sel_hi:[1,1,1]
	v_pk_fma_f32 v[98:99], v[226:227], v[248:249], v[98:99] op_sel:[0,1,0] op_sel_hi:[1,1,1]
	v_pk_fma_f32 v[100:101], v[228:229], v[248:249], v[100:101] op_sel:[0,1,0] op_sel_hi:[1,1,1]
	v_pk_fma_f32 v[102:103], v[230:231], v[248:249], v[102:103] op_sel:[0,1,0] op_sel_hi:[1,1,1]
	v_cvt_pk_f32_fp8_e32 v[224:225], v134
	v_cvt_pk_f32_fp8_sdwa v[226:227], v134 src0_sel:WORD_1
	v_cvt_pk_f32_fp8_e32 v[228:229], v135
	v_cvt_pk_f32_fp8_sdwa v[230:231], v135 src0_sel:WORD_1
	v_pk_fma_f32 v[104:105], v[224:225], v[248:249], v[104:105] op_sel:[0,1,0] op_sel_hi:[1,1,1]
	v_pk_fma_f32 v[106:107], v[226:227], v[248:249], v[106:107] op_sel:[0,1,0] op_sel_hi:[1,1,1]
	v_pk_fma_f32 v[108:109], v[228:229], v[248:249], v[108:109] op_sel:[0,1,0] op_sel_hi:[1,1,1]
	v_pk_fma_f32 v[110:111], v[230:231], v[248:249], v[110:111] op_sel:[0,1,0] op_sel_hi:[1,1,1]
	v_cvt_pk_f32_fp8_e32 v[224:225], v136
	v_cvt_pk_f32_fp8_sdwa v[226:227], v136 src0_sel:WORD_1
	v_cvt_pk_f32_fp8_e32 v[228:229], v137
	v_cvt_pk_f32_fp8_sdwa v[230:231], v137 src0_sel:WORD_1
	v_pk_fma_f32 v[96:97], v[224:225], v[250:251], v[96:97] op_sel_hi:[1,0,1]
	v_pk_fma_f32 v[98:99], v[226:227], v[250:251], v[98:99] op_sel_hi:[1,0,1]
	v_pk_fma_f32 v[100:101], v[228:229], v[250:251], v[100:101] op_sel_hi:[1,0,1]
	v_pk_fma_f32 v[102:103], v[230:231], v[250:251], v[102:103] op_sel_hi:[1,0,1]
	v_cvt_pk_f32_fp8_e32 v[224:225], v138
	v_cvt_pk_f32_fp8_sdwa v[226:227], v138 src0_sel:WORD_1
	v_cvt_pk_f32_fp8_e32 v[228:229], v139
	v_cvt_pk_f32_fp8_sdwa v[230:231], v139 src0_sel:WORD_1
	v_pk_fma_f32 v[104:105], v[224:225], v[250:251], v[104:105] op_sel_hi:[1,0,1]
	v_pk_fma_f32 v[106:107], v[226:227], v[250:251], v[106:107] op_sel_hi:[1,0,1]
	v_pk_fma_f32 v[108:109], v[228:229], v[250:251], v[108:109] op_sel_hi:[1,0,1]
	v_pk_fma_f32 v[110:111], v[230:231], v[250:251], v[110:111] op_sel_hi:[1,0,1]
	v_cvt_pk_f32_fp8_e32 v[224:225], v140
	v_cvt_pk_f32_fp8_sdwa v[226:227], v140 src0_sel:WORD_1
	v_cvt_pk_f32_fp8_e32 v[228:229], v141
	v_cvt_pk_f32_fp8_sdwa v[230:231], v141 src0_sel:WORD_1
	v_pk_fma_f32 v[96:97], v[224:225], v[250:251], v[96:97] op_sel:[0,1,0] op_sel_hi:[1,1,1]
	v_pk_fma_f32 v[98:99], v[226:227], v[250:251], v[98:99] op_sel:[0,1,0] op_sel_hi:[1,1,1]
	v_pk_fma_f32 v[100:101], v[228:229], v[250:251], v[100:101] op_sel:[0,1,0] op_sel_hi:[1,1,1]
	v_pk_fma_f32 v[102:103], v[230:231], v[250:251], v[102:103] op_sel:[0,1,0] op_sel_hi:[1,1,1]
	v_cvt_pk_f32_fp8_e32 v[224:225], v142
	v_cvt_pk_f32_fp8_sdwa v[226:227], v142 src0_sel:WORD_1
	v_cvt_pk_f32_fp8_e32 v[228:229], v143
	v_cvt_pk_f32_fp8_sdwa v[230:231], v143 src0_sel:WORD_1
	v_pk_fma_f32 v[104:105], v[224:225], v[250:251], v[104:105] op_sel:[0,1,0] op_sel_hi:[1,1,1]
	v_pk_fma_f32 v[106:107], v[226:227], v[250:251], v[106:107] op_sel:[0,1,0] op_sel_hi:[1,1,1]
	v_pk_fma_f32 v[108:109], v[228:229], v[250:251], v[108:109] op_sel:[0,1,0] op_sel_hi:[1,1,1]
	v_pk_fma_f32 v[110:111], v[230:231], v[250:251], v[110:111] op_sel:[0,1,0] op_sel_hi:[1,1,1]
	s_sub_i32 s90, s90, 1
	s_cmp_eq_u32 s90, 0
	s_cbranch_scc1 .LV_sw1
.LV_t6_s1:
	s_waitcnt lgkmcnt(0)
	v_add_u32_e32 v236, v232, v240
	v_add_u32_e32 v237, v233, v240
	v_add_u32_e32 v238, v234, v240
	v_add_u32_e32 v239, v235, v240
	global_load_dwordx4 v[128:131], v236, s[6:7]
	global_load_dwordx4 v[132:135], v237, s[6:7]
	global_load_dwordx4 v[136:139], v238, s[6:7]
	global_load_dwordx4 v[140:143], v239, s[6:7]
	ds_read_b128 v[232:235], v213 offset:80
	ds_read_b128 v[248:251], v213 offset:5024
	s_waitcnt vmcnt(12)
	v_cvt_pk_f32_fp8_e32 v[224:225], v144
	v_cvt_pk_f32_fp8_sdwa v[226:227], v144 src0_sel:WORD_1
	v_cvt_pk_f32_fp8_e32 v[228:229], v145
	v_cvt_pk_f32_fp8_sdwa v[230:231], v145 src0_sel:WORD_1
	v_pk_fma_f32 v[96:97], v[224:225], v[252:253], v[96:97] op_sel_hi:[1,0,1]
	v_pk_fma_f32 v[98:99], v[226:227], v[252:253], v[98:99] op_sel_hi:[1,0,1]
	v_pk_fma_f32 v[100:101], v[228:229], v[252:253], v[100:101] op_sel_hi:[1,0,1]
	v_pk_fma_f32 v[102:103], v[230:231], v[252:253], v[102:103] op_sel_hi:[1,0,1]
	v_cvt_pk_f32_fp8_e32 v[224:225], v146
	v_cvt_pk_f32_fp8_sdwa v[226:227], v146 src0_sel:WORD_1
	v_cvt_pk_f32_fp8_e32 v[228:229], v147
	v_cvt_pk_f32_fp8_sdwa v[230:231], v147 src0_sel:WORD_1
	v_pk_fma_f32 v[104:105], v[224:225], v[252:253], v[104:105] op_sel_hi:[1,0,1]
	v_pk_fma_f32 v[106:107], v[226:227], v[252:253], v[106:107] op_sel_hi:[1,0,1]
	v_pk_fma_f32 v[108:109], v[228:229], v[252:253], v[108:109] op_sel_hi:[1,0,1]
	v_pk_fma_f32 v[110:111], v[230:231], v[252:253], v[110:111] op_sel_hi:[1,0,1]
	v_cvt_pk_f32_fp8_e32 v[224:225], v148
	v_cvt_pk_f32_fp8_sdwa v[226:227], v148 src0_sel:WORD_1
	v_cvt_pk_f32_fp8_e32 v[228:229], v149
	v_cvt_pk_f32_fp8_sdwa v[230:231], v149 src0_sel:WORD_1
	v_pk_fma_f32 v[96:97], v[224:225], v[252:253], v[96:97] op_sel:[0,1,0] op_sel_hi:[1,1,1]
	v_pk_fma_f32 v[98:99], v[226:227], v[252:253], v[98:99] op_sel:[0,1,0] op_sel_hi:[1,1,1]
	v_pk_fma_f32 v[100:101], v[228:229], v[252:253], v[100:101] op_sel:[0,1,0] op_sel_hi:[1,1,1]
	v_pk_fma_f32 v[102:103], v[230:231], v[252:253], v[102:103] op_sel:[0,1,0] op_sel_hi:[1,1,1]
	v_cvt_pk_f32_fp8_e32 v[224:225], v150
	v_cvt_pk_f32_fp8_sdwa v[226:227], v150 src0_sel:WORD_1
	v_cvt_pk_f32_fp8_e32 v[228:229], v151
	v_cvt_pk_f32_fp8_sdwa v[230:231], v151 src0_sel:WORD_1
	v_pk_fma_f32 v[104:105], v[224:225], v[252:253], v[104:105] op_sel:[0,1,0] op_sel_hi:[1,1,1]
	v_pk_fma_f32 v[106:107], v[226:227], v[252:253], v[106:107] op_sel:[0,1,0] op_sel_hi:[1,1,1]
	v_pk_fma_f32 v[108:109], v[228:229], v[252:253], v[108:109] op_sel:[0,1,0] op_sel_hi:[1,1,1]
	v_pk_fma_f32 v[110:111], v[230:231], v[252:253], v[110:111] op_sel:[0,1,0] op_sel_hi:[1,1,1]
	v_cvt_pk_f32_fp8_e32 v[224:225], v152
	v_cvt_pk_f32_fp8_sdwa v[226:227], v152 src0_sel:WORD_1
	v_cvt_pk_f32_fp8_e32 v[228:229], v153
	v_cvt_pk_f32_fp8_sdwa v[230:231], v153 src0_sel:WORD_1
	v_pk_fma_f32 v[96:97], v[224:225], v[254:255], v[96:97] op_sel_hi:[1,0,1]
	v_pk_fma_f32 v[98:99], v[226:227], v[254:255], v[98:99] op_sel_hi:[1,0,1]
	v_pk_fma_f32 v[100:101], v[228:229], v[254:255], v[100:101] op_sel_hi:[1,0,1]
	v_pk_fma_f32 v[102:103], v[230:231], v[254:255], v[102:103] op_sel_hi:[1,0,1]
	v_cvt_pk_f32_fp8_e32 v[224:225], v154
	v_cvt_pk_f32_fp8_sdwa v[226:227], v154 src0_sel:WORD_1
	v_cvt_pk_f32_fp8_e32 v[228:229], v155
	v_cvt_pk_f32_fp8_sdwa v[230:231], v155 src0_sel:WORD_1
	v_pk_fma_f32 v[104:105], v[224:225], v[254:255], v[104:105] op_sel_hi:[1,0,1]
	v_pk_fma_f32 v[106:107], v[226:227], v[254:255], v[106:107] op_sel_hi:[1,0,1]
	v_pk_fma_f32 v[108:109], v[228:229], v[254:255], v[108:109] op_sel_hi:[1,0,1]
	v_pk_fma_f32 v[110:111], v[230:231], v[254:255], v[110:111] op_sel_hi:[1,0,1]
	v_cvt_pk_f32_fp8_e32 v[224:225], v156
	v_cvt_pk_f32_fp8_sdwa v[226:227], v156 src0_sel:WORD_1
	v_cvt_pk_f32_fp8_e32 v[228:229], v157
	v_cvt_pk_f32_fp8_sdwa v[230:231], v157 src0_sel:WORD_1
	v_pk_fma_f32 v[96:97], v[224:225], v[254:255], v[96:97] op_sel:[0,1,0] op_sel_hi:[1,1,1]
	v_pk_fma_f32 v[98:99], v[226:227], v[254:255], v[98:99] op_sel:[0,1,0] op_sel_hi:[1,1,1]
	v_pk_fma_f32 v[100:101], v[228:229], v[254:255], v[100:101] op_sel:[0,1,0] op_sel_hi:[1,1,1]
	v_pk_fma_f32 v[102:103], v[230:231], v[254:255], v[102:103] op_sel:[0,1,0] op_sel_hi:[1,1,1]
	v_cvt_pk_f32_fp8_e32 v[224:225], v158
	v_cvt_pk_f32_fp8_sdwa v[226:227], v158 src0_sel:WORD_1
	v_cvt_pk_f32_fp8_e32 v[228:229], v159
	v_cvt_pk_f32_fp8_sdwa v[230:231], v159 src0_sel:WORD_1
	v_pk_fma_f32 v[104:105], v[224:225], v[254:255], v[104:105] op_sel:[0,1,0] op_sel_hi:[1,1,1]
	v_pk_fma_f32 v[106:107], v[226:227], v[254:255], v[106:107] op_sel:[0,1,0] op_sel_hi:[1,1,1]
	v_pk_fma_f32 v[108:109], v[228:229], v[254:255], v[108:109] op_sel:[0,1,0] op_sel_hi:[1,1,1]
	v_pk_fma_f32 v[110:111], v[230:231], v[254:255], v[110:111] op_sel:[0,1,0] op_sel_hi:[1,1,1]
	s_sub_i32 s90, s90, 1
	s_cmp_eq_u32 s90, 0
	s_cbranch_scc1 .LV_sw2
.LV_t6_s2:
	s_waitcnt lgkmcnt(0)
	v_add_u32_e32 v236, v232, v240
	v_add_u32_e32 v237, v233, v240
	v_add_u32_e32 v238, v234, v240
	v_add_u32_e32 v239, v235, v240
	global_load_dwordx4 v[144:147], v236, s[6:7]
	global_load_dwordx4 v[148:151], v237, s[6:7]
	global_load_dwordx4 v[152:155], v238, s[6:7]
	global_load_dwordx4 v[156:159], v239, s[6:7]
	ds_read_b128 v[232:235], v213 offset:96
	ds_read_b128 v[252:255], v213 offset:5040
	s_waitcnt vmcnt(12)
	v_cvt_pk_f32_fp8_e32 v[224:225], v160
	v_cvt_pk_f32_fp8_sdwa v[226:227], v160 src0_sel:WORD_1
	v_cvt_pk_f32_fp8_e32 v[228:229], v161
	v_cvt_pk_f32_fp8_sdwa v[230:231], v161 src0_sel:WORD_1
	v_pk_fma_f32 v[96:97], v[224:225], v[248:249], v[96:97] op_sel_hi:[1,0,1]
	v_pk_fma_f32 v[98:99], v[226:227], v[248:249], v[98:99] op_sel_hi:[1,0,1]
	v_pk_fma_f32 v[100:101], v[228:229], v[248:249], v[100:101] op_sel_hi:[1,0,1]
	v_pk_fma_f32 v[102:103], v[230:231], v[248:249], v[102:103] op_sel_hi:[1,0,1]
	v_cvt_pk_f32_fp8_e32 v[224:225], v162
	v_cvt_pk_f32_fp8_sdwa v[226:227], v162 src0_sel:WORD_1
	v_cvt_pk_f32_fp8_e32 v[228:229], v163
	v_cvt_pk_f32_fp8_sdwa v[230:231], v163 src0_sel:WORD_1
	v_pk_fma_f32 v[104:105], v[224:225], v[248:249], v[104:105] op_sel_hi:[1,0,1]
	v_pk_fma_f32 v[106:107], v[226:227], v[248:249], v[106:107] op_sel_hi:[1,0,1]
	v_pk_fma_f32 v[108:109], v[228:229], v[248:249], v[108:109] op_sel_hi:[1,0,1]
	v_pk_fma_f32 v[110:111], v[230:231], v[248:249], v[110:111] op_sel_hi:[1,0,1]
	v_cvt_pk_f32_fp8_e32 v[224:225], v164
	v_cvt_pk_f32_fp8_sdwa v[226:227], v164 src0_sel:WORD_1
	v_cvt_pk_f32_fp8_e32 v[228:229], v165
	v_cvt_pk_f32_fp8_sdwa v[230:231], v165 src0_sel:WORD_1
	v_pk_fma_f32 v[96:97], v[224:225], v[248:249], v[96:97] op_sel:[0,1,0] op_sel_hi:[1,1,1]
	v_pk_fma_f32 v[98:99], v[226:227], v[248:249], v[98:99] op_sel:[0,1,0] op_sel_hi:[1,1,1]
	v_pk_fma_f32 v[100:101], v[228:229], v[248:249], v[100:101] op_sel:[0,1,0] op_sel_hi:[1,1,1]
	v_pk_fma_f32 v[102:103], v[230:231], v[248:249], v[102:103] op_sel:[0,1,0] op_sel_hi:[1,1,1]
	v_cvt_pk_f32_fp8_e32 v[224:225], v166
	v_cvt_pk_f32_fp8_sdwa v[226:227], v166 src0_sel:WORD_1
	v_cvt_pk_f32_fp8_e32 v[228:229], v167
	v_cvt_pk_f32_fp8_sdwa v[230:231], v167 src0_sel:WORD_1
	v_pk_fma_f32 v[104:105], v[224:225], v[248:249], v[104:105] op_sel:[0,1,0] op_sel_hi:[1,1,1]
	v_pk_fma_f32 v[106:107], v[226:227], v[248:249], v[106:107] op_sel:[0,1,0] op_sel_hi:[1,1,1]
	v_pk_fma_f32 v[108:109], v[228:229], v[248:249], v[108:109] op_sel:[0,1,0] op_sel_hi:[1,1,1]
	v_pk_fma_f32 v[110:111], v[230:231], v[248:249], v[110:111] op_sel:[0,1,0] op_sel_hi:[1,1,1]
	v_cvt_pk_f32_fp8_e32 v[224:225], v168
	v_cvt_pk_f32_fp8_sdwa v[226:227], v168 src0_sel:WORD_1
	v_cvt_pk_f32_fp8_e32 v[228:229], v169
	v_cvt_pk_f32_fp8_sdwa v[230:231], v169 src0_sel:WORD_1
	v_pk_fma_f32 v[96:97], v[224:225], v[250:251], v[96:97] op_sel_hi:[1,0,1]
	v_pk_fma_f32 v[98:99], v[226:227], v[250:251], v[98:99] op_sel_hi:[1,0,1]
	v_pk_fma_f32 v[100:101], v[228:229], v[250:251], v[100:101] op_sel_hi:[1,0,1]
	v_pk_fma_f32 v[102:103], v[230:231], v[250:251], v[102:103] op_sel_hi:[1,0,1]
	v_cvt_pk_f32_fp8_e32 v[224:225], v170
	v_cvt_pk_f32_fp8_sdwa v[226:227], v170 src0_sel:WORD_1
	v_cvt_pk_f32_fp8_e32 v[228:229], v171
	v_cvt_pk_f32_fp8_sdwa v[230:231], v171 src0_sel:WORD_1
	v_pk_fma_f32 v[104:105], v[224:225], v[250:251], v[104:105] op_sel_hi:[1,0,1]
	v_pk_fma_f32 v[106:107], v[226:227], v[250:251], v[106:107] op_sel_hi:[1,0,1]
	v_pk_fma_f32 v[108:109], v[228:229], v[250:251], v[108:109] op_sel_hi:[1,0,1]
	v_pk_fma_f32 v[110:111], v[230:231], v[250:251], v[110:111] op_sel_hi:[1,0,1]
	v_cvt_pk_f32_fp8_e32 v[224:225], v172
	v_cvt_pk_f32_fp8_sdwa v[226:227], v172 src0_sel:WORD_1
	v_cvt_pk_f32_fp8_e32 v[228:229], v173
	v_cvt_pk_f32_fp8_sdwa v[230:231], v173 src0_sel:WORD_1
	v_pk_fma_f32 v[96:97], v[224:225], v[250:251], v[96:97] op_sel:[0,1,0] op_sel_hi:[1,1,1]
	v_pk_fma_f32 v[98:99], v[226:227], v[250:251], v[98:99] op_sel:[0,1,0] op_sel_hi:[1,1,1]
	v_pk_fma_f32 v[100:101], v[228:229], v[250:251], v[100:101] op_sel:[0,1,0] op_sel_hi:[1,1,1]
	v_pk_fma_f32 v[102:103], v[230:231], v[250:251], v[102:103] op_sel:[0,1,0] op_sel_hi:[1,1,1]
	v_cvt_pk_f32_fp8_e32 v[224:225], v174
	v_cvt_pk_f32_fp8_sdwa v[226:227], v174 src0_sel:WORD_1
	v_cvt_pk_f32_fp8_e32 v[228:229], v175
	v_cvt_pk_f32_fp8_sdwa v[230:231], v175 src0_sel:WORD_1
	v_pk_fma_f32 v[104:105], v[224:225], v[250:251], v[104:105] op_sel:[0,1,0] op_sel_hi:[1,1,1]
	v_pk_fma_f32 v[106:107], v[226:227], v[250:251], v[106:107] op_sel:[0,1,0] op_sel_hi:[1,1,1]
	v_pk_fma_f32 v[108:109], v[228:229], v[250:251], v[108:109] op_sel:[0,1,0] op_sel_hi:[1,1,1]
	v_pk_fma_f32 v[110:111], v[230:231], v[250:251], v[110:111] op_sel:[0,1,0] op_sel_hi:[1,1,1]
	s_sub_i32 s90, s90, 1
	s_cmp_eq_u32 s90, 0
	s_cbranch_scc1 .LV_sw3
.LV_t6_s3:
	s_waitcnt lgkmcnt(0)
	v_add_u32_e32 v236, v232, v240
	v_add_u32_e32 v237, v233, v240
	v_add_u32_e32 v238, v234, v240
	v_add_u32_e32 v239, v235, v240
	global_load_dwordx4 v[160:163], v236, s[6:7]
	global_load_dwordx4 v[164:167], v237, s[6:7]
	global_load_dwordx4 v[168:171], v238, s[6:7]
	global_load_dwordx4 v[172:175], v239, s[6:7]
	ds_read_b128 v[232:235], v213 offset:112
	ds_read_b128 v[248:251], v213 offset:5056
	s_waitcnt vmcnt(12)
	v_cvt_pk_f32_fp8_e32 v[224:225], v176
	v_cvt_pk_f32_fp8_sdwa v[226:227], v176 src0_sel:WORD_1
	v_cvt_pk_f32_fp8_e32 v[228:229], v177
	v_cvt_pk_f32_fp8_sdwa v[230:231], v177 src0_sel:WORD_1
	v_pk_fma_f32 v[96:97], v[224:225], v[252:253], v[96:97] op_sel_hi:[1,0,1]
	v_pk_fma_f32 v[98:99], v[226:227], v[252:253], v[98:99] op_sel_hi:[1,0,1]
	v_pk_fma_f32 v[100:101], v[228:229], v[252:253], v[100:101] op_sel_hi:[1,0,1]
	v_pk_fma_f32 v[102:103], v[230:231], v[252:253], v[102:103] op_sel_hi:[1,0,1]
	v_cvt_pk_f32_fp8_e32 v[224:225], v178
	v_cvt_pk_f32_fp8_sdwa v[226:227], v178 src0_sel:WORD_1
	v_cvt_pk_f32_fp8_e32 v[228:229], v179
	v_cvt_pk_f32_fp8_sdwa v[230:231], v179 src0_sel:WORD_1
	v_pk_fma_f32 v[104:105], v[224:225], v[252:253], v[104:105] op_sel_hi:[1,0,1]
	v_pk_fma_f32 v[106:107], v[226:227], v[252:253], v[106:107] op_sel_hi:[1,0,1]
	v_pk_fma_f32 v[108:109], v[228:229], v[252:253], v[108:109] op_sel_hi:[1,0,1]
	v_pk_fma_f32 v[110:111], v[230:231], v[252:253], v[110:111] op_sel_hi:[1,0,1]
	v_cvt_pk_f32_fp8_e32 v[224:225], v180
	v_cvt_pk_f32_fp8_sdwa v[226:227], v180 src0_sel:WORD_1
	v_cvt_pk_f32_fp8_e32 v[228:229], v181
	v_cvt_pk_f32_fp8_sdwa v[230:231], v181 src0_sel:WORD_1
	v_pk_fma_f32 v[96:97], v[224:225], v[252:253], v[96:97] op_sel:[0,1,0] op_sel_hi:[1,1,1]
	v_pk_fma_f32 v[98:99], v[226:227], v[252:253], v[98:99] op_sel:[0,1,0] op_sel_hi:[1,1,1]
	v_pk_fma_f32 v[100:101], v[228:229], v[252:253], v[100:101] op_sel:[0,1,0] op_sel_hi:[1,1,1]
	v_pk_fma_f32 v[102:103], v[230:231], v[252:253], v[102:103] op_sel:[0,1,0] op_sel_hi:[1,1,1]
	v_cvt_pk_f32_fp8_e32 v[224:225], v182
	v_cvt_pk_f32_fp8_sdwa v[226:227], v182 src0_sel:WORD_1
	v_cvt_pk_f32_fp8_e32 v[228:229], v183
	v_cvt_pk_f32_fp8_sdwa v[230:231], v183 src0_sel:WORD_1
	v_pk_fma_f32 v[104:105], v[224:225], v[252:253], v[104:105] op_sel:[0,1,0] op_sel_hi:[1,1,1]
	v_pk_fma_f32 v[106:107], v[226:227], v[252:253], v[106:107] op_sel:[0,1,0] op_sel_hi:[1,1,1]
	v_pk_fma_f32 v[108:109], v[228:229], v[252:253], v[108:109] op_sel:[0,1,0] op_sel_hi:[1,1,1]
	v_pk_fma_f32 v[110:111], v[230:231], v[252:253], v[110:111] op_sel:[0,1,0] op_sel_hi:[1,1,1]
	v_cvt_pk_f32_fp8_e32 v[224:225], v184
	v_cvt_pk_f32_fp8_sdwa v[226:227], v184 src0_sel:WORD_1
	v_cvt_pk_f32_fp8_e32 v[228:229], v185
	v_cvt_pk_f32_fp8_sdwa v[230:231], v185 src0_sel:WORD_1
	v_pk_fma_f32 v[96:97], v[224:225], v[254:255], v[96:97] op_sel_hi:[1,0,1]
	v_pk_fma_f32 v[98:99], v[226:227], v[254:255], v[98:99] op_sel_hi:[1,0,1]
	v_pk_fma_f32 v[100:101], v[228:229], v[254:255], v[100:101] op_sel_hi:[1,0,1]
	v_pk_fma_f32 v[102:103], v[230:231], v[254:255], v[102:103] op_sel_hi:[1,0,1]
	v_cvt_pk_f32_fp8_e32 v[224:225], v186
	v_cvt_pk_f32_fp8_sdwa v[226:227], v186 src0_sel:WORD_1
	v_cvt_pk_f32_fp8_e32 v[228:229], v187
	v_cvt_pk_f32_fp8_sdwa v[230:231], v187 src0_sel:WORD_1
	v_pk_fma_f32 v[104:105], v[224:225], v[254:255], v[104:105] op_sel_hi:[1,0,1]
	v_pk_fma_f32 v[106:107], v[226:227], v[254:255], v[106:107] op_sel_hi:[1,0,1]
	v_pk_fma_f32 v[108:109], v[228:229], v[254:255], v[108:109] op_sel_hi:[1,0,1]
	v_pk_fma_f32 v[110:111], v[230:231], v[254:255], v[110:111] op_sel_hi:[1,0,1]
	v_cvt_pk_f32_fp8_e32 v[224:225], v188
	v_cvt_pk_f32_fp8_sdwa v[226:227], v188 src0_sel:WORD_1
	v_cvt_pk_f32_fp8_e32 v[228:229], v189
	v_cvt_pk_f32_fp8_sdwa v[230:231], v189 src0_sel:WORD_1
	v_pk_fma_f32 v[96:97], v[224:225], v[254:255], v[96:97] op_sel:[0,1,0] op_sel_hi:[1,1,1]
	v_pk_fma_f32 v[98:99], v[226:227], v[254:255], v[98:99] op_sel:[0,1,0] op_sel_hi:[1,1,1]
	v_pk_fma_f32 v[100:101], v[228:229], v[254:255], v[100:101] op_sel:[0,1,0] op_sel_hi:[1,1,1]
	v_pk_fma_f32 v[102:103], v[230:231], v[254:255], v[102:103] op_sel:[0,1,0] op_sel_hi:[1,1,1]
	v_cvt_pk_f32_fp8_e32 v[224:225], v190
	v_cvt_pk_f32_fp8_sdwa v[226:227], v190 src0_sel:WORD_1
	v_cvt_pk_f32_fp8_e32 v[228:229], v191
	v_cvt_pk_f32_fp8_sdwa v[230:231], v191 src0_sel:WORD_1
	v_pk_fma_f32 v[104:105], v[224:225], v[254:255], v[104:105] op_sel:[0,1,0] op_sel_hi:[1,1,1]
	v_pk_fma_f32 v[106:107], v[226:227], v[254:255], v[106:107] op_sel:[0,1,0] op_sel_hi:[1,1,1]
	v_pk_fma_f32 v[108:109], v[228:229], v[254:255], v[108:109] op_sel:[0,1,0] op_sel_hi:[1,1,1]
	v_pk_fma_f32 v[110:111], v[230:231], v[254:255], v[110:111] op_sel:[0,1,0] op_sel_hi:[1,1,1]
	v_add_u32_e32 v213, 64, v213
	s_add_i32 s21, s21, 4
	s_sub_i32 s90, s90, 1
	s_cmp_eq_u32 s90, 0
	s_cbranch_scc1 .LV_sw0
	s_branch .LV_t6_s0
.LV_t7_s0:
	s_cmp_ge_u32 s21, s20
	s_cbranch_scc1 .LV_done
	s_waitcnt lgkmcnt(0)
	v_add_u32_e32 v236, v232, v240
	v_add_u32_e32 v237, v233, v240
	v_add_u32_e32 v238, v234, v240
	v_add_u32_e32 v239, v235, v240
	global_load_dwordx4 v[176:179], v236, s[6:7]
	global_load_dwordx4 v[180:183], v237, s[6:7]
	global_load_dwordx4 v[184:187], v238, s[6:7]
	global_load_dwordx4 v[188:191], v239, s[6:7]
	ds_read_b128 v[232:235], v213 offset:64
	ds_read_b128 v[252:255], v213 offset:5008
	s_waitcnt vmcnt(12)
	v_cvt_pk_f32_fp8_e32 v[224:225], v128
	v_cvt_pk_f32_fp8_sdwa v[226:227], v128 src0_sel:WORD_1
	v_cvt_pk_f32_fp8_e32 v[228:229], v129
	v_cvt_pk_f32_fp8_sdwa v[230:231], v129 src0_sel:WORD_1
	v_pk_fma_f32 v[112:113], v[224:225], v[248:249], v[112:113] op_sel_hi:[1,0,1]
	v_pk_fma_f32 v[114:115], v[226:227], v[248:249], v[114:115] op_sel_hi:[1,0,1]
	v_pk_fma_f32 v[116:117], v[228:229], v[248:249], v[116:117] op_sel_hi:[1,0,1]
	v_pk_fma_f32 v[118:119], v[230:231], v[248:249], v[118:119] op_sel_hi:[1,0,1]
	v_cvt_pk_f32_fp8_e32 v[224:225], v130
	v_cvt_pk_f32_fp8_sdwa v[226:227], v130 src0_sel:WORD_1
	v_cvt_pk_f32_fp8_e32 v[228:229], v131
	v_cvt_pk_f32_fp8_sdwa v[230:231], v131 src0_sel:WORD_1
	v_pk_fma_f32 v[120:121], v[224:225], v[248:249], v[120:121] op_sel_hi:[1,0,1]
	v_pk_fma_f32 v[122:123], v[226:227], v[248:249], v[122:123] op_sel_hi:[1,0,1]
	v_pk_fma_f32 v[124:125], v[228:229], v[248:249], v[124:125] op_sel_hi:[1,0,1]
	v_pk_fma_f32 v[126:127], v[230:231], v[248:249], v[126:127] op_sel_hi:[1,0,1]
	v_cvt_pk_f32_fp8_e32 v[224:225], v132
	v_cvt_pk_f32_fp8_sdwa v[226:227], v132 src0_sel:WORD_1
	v_cvt_pk_f32_fp8_e32 v[228:229], v133
	v_cvt_pk_f32_fp8_sdwa v[230:231], v133 src0_sel:WORD_1
	v_pk_fma_f32 v[112:113], v[224:225], v[248:249], v[112:113] op_sel:[0,1,0] op_sel_hi:[1,1,1]
	v_pk_fma_f32 v[114:115], v[226:227], v[248:249], v[114:115] op_sel:[0,1,0] op_sel_hi:[1,1,1]
	v_pk_fma_f32 v[116:117], v[228:229], v[248:249], v[116:117] op_sel:[0,1,0] op_sel_hi:[1,1,1]
	v_pk_fma_f32 v[118:119], v[230:231], v[248:249], v[118:119] op_sel:[0,1,0] op_sel_hi:[1,1,1]
	v_cvt_pk_f32_fp8_e32 v[224:225], v134
	v_cvt_pk_f32_fp8_sdwa v[226:227], v134 src0_sel:WORD_1
	v_cvt_pk_f32_fp8_e32 v[228:229], v135
	v_cvt_pk_f32_fp8_sdwa v[230:231], v135 src0_sel:WORD_1
	v_pk_fma_f32 v[120:121], v[224:225], v[248:249], v[120:121] op_sel:[0,1,0] op_sel_hi:[1,1,1]
	v_pk_fma_f32 v[122:123], v[226:227], v[248:249], v[122:123] op_sel:[0,1,0] op_sel_hi:[1,1,1]
	v_pk_fma_f32 v[124:125], v[228:229], v[248:249], v[124:125] op_sel:[0,1,0] op_sel_hi:[1,1,1]
	v_pk_fma_f32 v[126:127], v[230:231], v[248:249], v[126:127] op_sel:[0,1,0] op_sel_hi:[1,1,1]
	v_cvt_pk_f32_fp8_e32 v[224:225], v136
	v_cvt_pk_f32_fp8_sdwa v[226:227], v136 src0_sel:WORD_1
	v_cvt_pk_f32_fp8_e32 v[228:229], v137
	v_cvt_pk_f32_fp8_sdwa v[230:231], v137 src0_sel:WORD_1
	v_pk_fma_f32 v[112:113], v[224:225], v[250:251], v[112:113] op_sel_hi:[1,0,1]
	v_pk_fma_f32 v[114:115], v[226:227], v[250:251], v[114:115] op_sel_hi:[1,0,1]
	v_pk_fma_f32 v[116:117], v[228:229], v[250:251], v[116:117] op_sel_hi:[1,0,1]
	v_pk_fma_f32 v[118:119], v[230:231], v[250:251], v[118:119] op_sel_hi:[1,0,1]
	v_cvt_pk_f32_fp8_e32 v[224:225], v138
	v_cvt_pk_f32_fp8_sdwa v[226:227], v138 src0_sel:WORD_1
	v_cvt_pk_f32_fp8_e32 v[228:229], v139
	v_cvt_pk_f32_fp8_sdwa v[230:231], v139 src0_sel:WORD_1
	v_pk_fma_f32 v[120:121], v[224:225], v[250:251], v[120:121] op_sel_hi:[1,0,1]
	v_pk_fma_f32 v[122:123], v[226:227], v[250:251], v[122:123] op_sel_hi:[1,0,1]
	v_pk_fma_f32 v[124:125], v[228:229], v[250:251], v[124:125] op_sel_hi:[1,0,1]
	v_pk_fma_f32 v[126:127], v[230:231], v[250:251], v[126:127] op_sel_hi:[1,0,1]
	v_cvt_pk_f32_fp8_e32 v[224:225], v140
	v_cvt_pk_f32_fp8_sdwa v[226:227], v140 src0_sel:WORD_1
	v_cvt_pk_f32_fp8_e32 v[228:229], v141
	v_cvt_pk_f32_fp8_sdwa v[230:231], v141 src0_sel:WORD_1
	v_pk_fma_f32 v[112:113], v[224:225], v[250:251], v[112:113] op_sel:[0,1,0] op_sel_hi:[1,1,1]
	v_pk_fma_f32 v[114:115], v[226:227], v[250:251], v[114:115] op_sel:[0,1,0] op_sel_hi:[1,1,1]
	v_pk_fma_f32 v[116:117], v[228:229], v[250:251], v[116:117] op_sel:[0,1,0] op_sel_hi:[1,1,1]
	v_pk_fma_f32 v[118:119], v[230:231], v[250:251], v[118:119] op_sel:[0,1,0] op_sel_hi:[1,1,1]
	v_cvt_pk_f32_fp8_e32 v[224:225], v142
	v_cvt_pk_f32_fp8_sdwa v[226:227], v142 src0_sel:WORD_1
	v_cvt_pk_f32_fp8_e32 v[228:229], v143
	v_cvt_pk_f32_fp8_sdwa v[230:231], v143 src0_sel:WORD_1
	v_pk_fma_f32 v[120:121], v[224:225], v[250:251], v[120:121] op_sel:[0,1,0] op_sel_hi:[1,1,1]
	v_pk_fma_f32 v[122:123], v[226:227], v[250:251], v[122:123] op_sel:[0,1,0] op_sel_hi:[1,1,1]
	v_pk_fma_f32 v[124:125], v[228:229], v[250:251], v[124:125] op_sel:[0,1,0] op_sel_hi:[1,1,1]
	v_pk_fma_f32 v[126:127], v[230:231], v[250:251], v[126:127] op_sel:[0,1,0] op_sel_hi:[1,1,1]
	s_sub_i32 s90, s90, 1
	s_cmp_eq_u32 s90, 0
	s_cbranch_scc1 .LV_sw1
.LV_t7_s1:
	s_waitcnt lgkmcnt(0)
	v_add_u32_e32 v236, v232, v240
	v_add_u32_e32 v237, v233, v240
	v_add_u32_e32 v238, v234, v240
	v_add_u32_e32 v239, v235, v240
	global_load_dwordx4 v[128:131], v236, s[6:7]
	global_load_dwordx4 v[132:135], v237, s[6:7]
	global_load_dwordx4 v[136:139], v238, s[6:7]
	global_load_dwordx4 v[140:143], v239, s[6:7]
	ds_read_b128 v[232:235], v213 offset:80
	ds_read_b128 v[248:251], v213 offset:5024
	s_waitcnt vmcnt(12)
	v_cvt_pk_f32_fp8_e32 v[224:225], v144
	v_cvt_pk_f32_fp8_sdwa v[226:227], v144 src0_sel:WORD_1
	v_cvt_pk_f32_fp8_e32 v[228:229], v145
	v_cvt_pk_f32_fp8_sdwa v[230:231], v145 src0_sel:WORD_1
	v_pk_fma_f32 v[112:113], v[224:225], v[252:253], v[112:113] op_sel_hi:[1,0,1]
	v_pk_fma_f32 v[114:115], v[226:227], v[252:253], v[114:115] op_sel_hi:[1,0,1]
	v_pk_fma_f32 v[116:117], v[228:229], v[252:253], v[116:117] op_sel_hi:[1,0,1]
	v_pk_fma_f32 v[118:119], v[230:231], v[252:253], v[118:119] op_sel_hi:[1,0,1]
	v_cvt_pk_f32_fp8_e32 v[224:225], v146
	v_cvt_pk_f32_fp8_sdwa v[226:227], v146 src0_sel:WORD_1
	v_cvt_pk_f32_fp8_e32 v[228:229], v147
	v_cvt_pk_f32_fp8_sdwa v[230:231], v147 src0_sel:WORD_1
	v_pk_fma_f32 v[120:121], v[224:225], v[252:253], v[120:121] op_sel_hi:[1,0,1]
	v_pk_fma_f32 v[122:123], v[226:227], v[252:253], v[122:123] op_sel_hi:[1,0,1]
	v_pk_fma_f32 v[124:125], v[228:229], v[252:253], v[124:125] op_sel_hi:[1,0,1]
	v_pk_fma_f32 v[126:127], v[230:231], v[252:253], v[126:127] op_sel_hi:[1,0,1]
	v_cvt_pk_f32_fp8_e32 v[224:225], v148
	v_cvt_pk_f32_fp8_sdwa v[226:227], v148 src0_sel:WORD_1
	v_cvt_pk_f32_fp8_e32 v[228:229], v149
	v_cvt_pk_f32_fp8_sdwa v[230:231], v149 src0_sel:WORD_1
	v_pk_fma_f32 v[112:113], v[224:225], v[252:253], v[112:113] op_sel:[0,1,0] op_sel_hi:[1,1,1]
	v_pk_fma_f32 v[114:115], v[226:227], v[252:253], v[114:115] op_sel:[0,1,0] op_sel_hi:[1,1,1]
	v_pk_fma_f32 v[116:117], v[228:229], v[252:253], v[116:117] op_sel:[0,1,0] op_sel_hi:[1,1,1]
	v_pk_fma_f32 v[118:119], v[230:231], v[252:253], v[118:119] op_sel:[0,1,0] op_sel_hi:[1,1,1]
	v_cvt_pk_f32_fp8_e32 v[224:225], v150
	v_cvt_pk_f32_fp8_sdwa v[226:227], v150 src0_sel:WORD_1
	v_cvt_pk_f32_fp8_e32 v[228:229], v151
	v_cvt_pk_f32_fp8_sdwa v[230:231], v151 src0_sel:WORD_1
	v_pk_fma_f32 v[120:121], v[224:225], v[252:253], v[120:121] op_sel:[0,1,0] op_sel_hi:[1,1,1]
	v_pk_fma_f32 v[122:123], v[226:227], v[252:253], v[122:123] op_sel:[0,1,0] op_sel_hi:[1,1,1]
	v_pk_fma_f32 v[124:125], v[228:229], v[252:253], v[124:125] op_sel:[0,1,0] op_sel_hi:[1,1,1]
	v_pk_fma_f32 v[126:127], v[230:231], v[252:253], v[126:127] op_sel:[0,1,0] op_sel_hi:[1,1,1]
	v_cvt_pk_f32_fp8_e32 v[224:225], v152
	v_cvt_pk_f32_fp8_sdwa v[226:227], v152 src0_sel:WORD_1
	v_cvt_pk_f32_fp8_e32 v[228:229], v153
	v_cvt_pk_f32_fp8_sdwa v[230:231], v153 src0_sel:WORD_1
	v_pk_fma_f32 v[112:113], v[224:225], v[254:255], v[112:113] op_sel_hi:[1,0,1]
	v_pk_fma_f32 v[114:115], v[226:227], v[254:255], v[114:115] op_sel_hi:[1,0,1]
	v_pk_fma_f32 v[116:117], v[228:229], v[254:255], v[116:117] op_sel_hi:[1,0,1]
	v_pk_fma_f32 v[118:119], v[230:231], v[254:255], v[118:119] op_sel_hi:[1,0,1]
	v_cvt_pk_f32_fp8_e32 v[224:225], v154
	v_cvt_pk_f32_fp8_sdwa v[226:227], v154 src0_sel:WORD_1
	v_cvt_pk_f32_fp8_e32 v[228:229], v155
	v_cvt_pk_f32_fp8_sdwa v[230:231], v155 src0_sel:WORD_1
	v_pk_fma_f32 v[120:121], v[224:225], v[254:255], v[120:121] op_sel_hi:[1,0,1]
	v_pk_fma_f32 v[122:123], v[226:227], v[254:255], v[122:123] op_sel_hi:[1,0,1]
	v_pk_fma_f32 v[124:125], v[228:229], v[254:255], v[124:125] op_sel_hi:[1,0,1]
	v_pk_fma_f32 v[126:127], v[230:231], v[254:255], v[126:127] op_sel_hi:[1,0,1]
	v_cvt_pk_f32_fp8_e32 v[224:225], v156
	v_cvt_pk_f32_fp8_sdwa v[226:227], v156 src0_sel:WORD_1
	v_cvt_pk_f32_fp8_e32 v[228:229], v157
	v_cvt_pk_f32_fp8_sdwa v[230:231], v157 src0_sel:WORD_1
	v_pk_fma_f32 v[112:113], v[224:225], v[254:255], v[112:113] op_sel:[0,1,0] op_sel_hi:[1,1,1]
	v_pk_fma_f32 v[114:115], v[226:227], v[254:255], v[114:115] op_sel:[0,1,0] op_sel_hi:[1,1,1]
	v_pk_fma_f32 v[116:117], v[228:229], v[254:255], v[116:117] op_sel:[0,1,0] op_sel_hi:[1,1,1]
	v_pk_fma_f32 v[118:119], v[230:231], v[254:255], v[118:119] op_sel:[0,1,0] op_sel_hi:[1,1,1]
	v_cvt_pk_f32_fp8_e32 v[224:225], v158
	v_cvt_pk_f32_fp8_sdwa v[226:227], v158 src0_sel:WORD_1
	v_cvt_pk_f32_fp8_e32 v[228:229], v159
	v_cvt_pk_f32_fp8_sdwa v[230:231], v159 src0_sel:WORD_1
	v_pk_fma_f32 v[120:121], v[224:225], v[254:255], v[120:121] op_sel:[0,1,0] op_sel_hi:[1,1,1]
	v_pk_fma_f32 v[122:123], v[226:227], v[254:255], v[122:123] op_sel:[0,1,0] op_sel_hi:[1,1,1]
	v_pk_fma_f32 v[124:125], v[228:229], v[254:255], v[124:125] op_sel:[0,1,0] op_sel_hi:[1,1,1]
	v_pk_fma_f32 v[126:127], v[230:231], v[254:255], v[126:127] op_sel:[0,1,0] op_sel_hi:[1,1,1]
	s_sub_i32 s90, s90, 1
	s_cmp_eq_u32 s90, 0
	s_cbranch_scc1 .LV_sw2
.LV_t7_s2:
	s_waitcnt lgkmcnt(0)
	v_add_u32_e32 v236, v232, v240
	v_add_u32_e32 v237, v233, v240
	v_add_u32_e32 v238, v234, v240
	v_add_u32_e32 v239, v235, v240
	global_load_dwordx4 v[144:147], v236, s[6:7]
	global_load_dwordx4 v[148:151], v237, s[6:7]
	global_load_dwordx4 v[152:155], v238, s[6:7]
	global_load_dwordx4 v[156:159], v239, s[6:7]
	ds_read_b128 v[232:235], v213 offset:96
	ds_read_b128 v[252:255], v213 offset:5040
	s_waitcnt vmcnt(12)
	v_cvt_pk_f32_fp8_e32 v[224:225], v160
	v_cvt_pk_f32_fp8_sdwa v[226:227], v160 src0_sel:WORD_1
	v_cvt_pk_f32_fp8_e32 v[228:229], v161
	v_cvt_pk_f32_fp8_sdwa v[230:231], v161 src0_sel:WORD_1
	v_pk_fma_f32 v[112:113], v[224:225], v[248:249], v[112:113] op_sel_hi:[1,0,1]
	v_pk_fma_f32 v[114:115], v[226:227], v[248:249], v[114:115] op_sel_hi:[1,0,1]
	v_pk_fma_f32 v[116:117], v[228:229], v[248:249], v[116:117] op_sel_hi:[1,0,1]
	v_pk_fma_f32 v[118:119], v[230:231], v[248:249], v[118:119] op_sel_hi:[1,0,1]
	v_cvt_pk_f32_fp8_e32 v[224:225], v162
	v_cvt_pk_f32_fp8_sdwa v[226:227], v162 src0_sel:WORD_1
	v_cvt_pk_f32_fp8_e32 v[228:229], v163
	v_cvt_pk_f32_fp8_sdwa v[230:231], v163 src0_sel:WORD_1
	v_pk_fma_f32 v[120:121], v[224:225], v[248:249], v[120:121] op_sel_hi:[1,0,1]
	v_pk_fma_f32 v[122:123], v[226:227], v[248:249], v[122:123] op_sel_hi:[1,0,1]
	v_pk_fma_f32 v[124:125], v[228:229], v[248:249], v[124:125] op_sel_hi:[1,0,1]
	v_pk_fma_f32 v[126:127], v[230:231], v[248:249], v[126:127] op_sel_hi:[1,0,1]
	v_cvt_pk_f32_fp8_e32 v[224:225], v164
	v_cvt_pk_f32_fp8_sdwa v[226:227], v164 src0_sel:WORD_1
	v_cvt_pk_f32_fp8_e32 v[228:229], v165
	v_cvt_pk_f32_fp8_sdwa v[230:231], v165 src0_sel:WORD_1
	v_pk_fma_f32 v[112:113], v[224:225], v[248:249], v[112:113] op_sel:[0,1,0] op_sel_hi:[1,1,1]
	v_pk_fma_f32 v[114:115], v[226:227], v[248:249], v[114:115] op_sel:[0,1,0] op_sel_hi:[1,1,1]
	v_pk_fma_f32 v[116:117], v[228:229], v[248:249], v[116:117] op_sel:[0,1,0] op_sel_hi:[1,1,1]
	v_pk_fma_f32 v[118:119], v[230:231], v[248:249], v[118:119] op_sel:[0,1,0] op_sel_hi:[1,1,1]
	v_cvt_pk_f32_fp8_e32 v[224:225], v166
	v_cvt_pk_f32_fp8_sdwa v[226:227], v166 src0_sel:WORD_1
	v_cvt_pk_f32_fp8_e32 v[228:229], v167
	v_cvt_pk_f32_fp8_sdwa v[230:231], v167 src0_sel:WORD_1
	v_pk_fma_f32 v[120:121], v[224:225], v[248:249], v[120:121] op_sel:[0,1,0] op_sel_hi:[1,1,1]
	v_pk_fma_f32 v[122:123], v[226:227], v[248:249], v[122:123] op_sel:[0,1,0] op_sel_hi:[1,1,1]
	v_pk_fma_f32 v[124:125], v[228:229], v[248:249], v[124:125] op_sel:[0,1,0] op_sel_hi:[1,1,1]
	v_pk_fma_f32 v[126:127], v[230:231], v[248:249], v[126:127] op_sel:[0,1,0] op_sel_hi:[1,1,1]
	v_cvt_pk_f32_fp8_e32 v[224:225], v168
	v_cvt_pk_f32_fp8_sdwa v[226:227], v168 src0_sel:WORD_1
	v_cvt_pk_f32_fp8_e32 v[228:229], v169
	v_cvt_pk_f32_fp8_sdwa v[230:231], v169 src0_sel:WORD_1
	v_pk_fma_f32 v[112:113], v[224:225], v[250:251], v[112:113] op_sel_hi:[1,0,1]
	v_pk_fma_f32 v[114:115], v[226:227], v[250:251], v[114:115] op_sel_hi:[1,0,1]
	v_pk_fma_f32 v[116:117], v[228:229], v[250:251], v[116:117] op_sel_hi:[1,0,1]
	v_pk_fma_f32 v[118:119], v[230:231], v[250:251], v[118:119] op_sel_hi:[1,0,1]
	v_cvt_pk_f32_fp8_e32 v[224:225], v170
	v_cvt_pk_f32_fp8_sdwa v[226:227], v170 src0_sel:WORD_1
	v_cvt_pk_f32_fp8_e32 v[228:229], v171
	v_cvt_pk_f32_fp8_sdwa v[230:231], v171 src0_sel:WORD_1
	v_pk_fma_f32 v[120:121], v[224:225], v[250:251], v[120:121] op_sel_hi:[1,0,1]
	v_pk_fma_f32 v[122:123], v[226:227], v[250:251], v[122:123] op_sel_hi:[1,0,1]
	v_pk_fma_f32 v[124:125], v[228:229], v[250:251], v[124:125] op_sel_hi:[1,0,1]
	v_pk_fma_f32 v[126:127], v[230:231], v[250:251], v[126:127] op_sel_hi:[1,0,1]
	v_cvt_pk_f32_fp8_e32 v[224:225], v172
	v_cvt_pk_f32_fp8_sdwa v[226:227], v172 src0_sel:WORD_1
	v_cvt_pk_f32_fp8_e32 v[228:229], v173
	v_cvt_pk_f32_fp8_sdwa v[230:231], v173 src0_sel:WORD_1
	v_pk_fma_f32 v[112:113], v[224:225], v[250:251], v[112:113] op_sel:[0,1,0] op_sel_hi:[1,1,1]
	v_pk_fma_f32 v[114:115], v[226:227], v[250:251], v[114:115] op_sel:[0,1,0] op_sel_hi:[1,1,1]
	v_pk_fma_f32 v[116:117], v[228:229], v[250:251], v[116:117] op_sel:[0,1,0] op_sel_hi:[1,1,1]
	v_pk_fma_f32 v[118:119], v[230:231], v[250:251], v[118:119] op_sel:[0,1,0] op_sel_hi:[1,1,1]
	v_cvt_pk_f32_fp8_e32 v[224:225], v174
	v_cvt_pk_f32_fp8_sdwa v[226:227], v174 src0_sel:WORD_1
	v_cvt_pk_f32_fp8_e32 v[228:229], v175
	v_cvt_pk_f32_fp8_sdwa v[230:231], v175 src0_sel:WORD_1
	v_pk_fma_f32 v[120:121], v[224:225], v[250:251], v[120:121] op_sel:[0,1,0] op_sel_hi:[1,1,1]
	v_pk_fma_f32 v[122:123], v[226:227], v[250:251], v[122:123] op_sel:[0,1,0] op_sel_hi:[1,1,1]
	v_pk_fma_f32 v[124:125], v[228:229], v[250:251], v[124:125] op_sel:[0,1,0] op_sel_hi:[1,1,1]
	v_pk_fma_f32 v[126:127], v[230:231], v[250:251], v[126:127] op_sel:[0,1,0] op_sel_hi:[1,1,1]
	s_sub_i32 s90, s90, 1
	s_cmp_eq_u32 s90, 0
	s_cbranch_scc1 .LV_sw3
.LV_t7_s3:
	s_waitcnt lgkmcnt(0)
	v_add_u32_e32 v236, v232, v240
	v_add_u32_e32 v237, v233, v240
	v_add_u32_e32 v238, v234, v240
	v_add_u32_e32 v239, v235, v240
	global_load_dwordx4 v[160:163], v236, s[6:7]
	global_load_dwordx4 v[164:167], v237, s[6:7]
	global_load_dwordx4 v[168:171], v238, s[6:7]
	global_load_dwordx4 v[172:175], v239, s[6:7]
	ds_read_b128 v[232:235], v213 offset:112
	ds_read_b128 v[248:251], v213 offset:5056
	s_waitcnt vmcnt(12)
	v_cvt_pk_f32_fp8_e32 v[224:225], v176
	v_cvt_pk_f32_fp8_sdwa v[226:227], v176 src0_sel:WORD_1
	v_cvt_pk_f32_fp8_e32 v[228:229], v177
	v_cvt_pk_f32_fp8_sdwa v[230:231], v177 src0_sel:WORD_1
	v_pk_fma_f32 v[112:113], v[224:225], v[252:253], v[112:113] op_sel_hi:[1,0,1]
	v_pk_fma_f32 v[114:115], v[226:227], v[252:253], v[114:115] op_sel_hi:[1,0,1]
	v_pk_fma_f32 v[116:117], v[228:229], v[252:253], v[116:117] op_sel_hi:[1,0,1]
	v_pk_fma_f32 v[118:119], v[230:231], v[252:253], v[118:119] op_sel_hi:[1,0,1]
	v_cvt_pk_f32_fp8_e32 v[224:225], v178
	v_cvt_pk_f32_fp8_sdwa v[226:227], v178 src0_sel:WORD_1
	v_cvt_pk_f32_fp8_e32 v[228:229], v179
	v_cvt_pk_f32_fp8_sdwa v[230:231], v179 src0_sel:WORD_1
	v_pk_fma_f32 v[120:121], v[224:225], v[252:253], v[120:121] op_sel_hi:[1,0,1]
	v_pk_fma_f32 v[122:123], v[226:227], v[252:253], v[122:123] op_sel_hi:[1,0,1]
	v_pk_fma_f32 v[124:125], v[228:229], v[252:253], v[124:125] op_sel_hi:[1,0,1]
	v_pk_fma_f32 v[126:127], v[230:231], v[252:253], v[126:127] op_sel_hi:[1,0,1]
	v_cvt_pk_f32_fp8_e32 v[224:225], v180
	v_cvt_pk_f32_fp8_sdwa v[226:227], v180 src0_sel:WORD_1
	v_cvt_pk_f32_fp8_e32 v[228:229], v181
	v_cvt_pk_f32_fp8_sdwa v[230:231], v181 src0_sel:WORD_1
	v_pk_fma_f32 v[112:113], v[224:225], v[252:253], v[112:113] op_sel:[0,1,0] op_sel_hi:[1,1,1]
	v_pk_fma_f32 v[114:115], v[226:227], v[252:253], v[114:115] op_sel:[0,1,0] op_sel_hi:[1,1,1]
	v_pk_fma_f32 v[116:117], v[228:229], v[252:253], v[116:117] op_sel:[0,1,0] op_sel_hi:[1,1,1]
	v_pk_fma_f32 v[118:119], v[230:231], v[252:253], v[118:119] op_sel:[0,1,0] op_sel_hi:[1,1,1]
	v_cvt_pk_f32_fp8_e32 v[224:225], v182
	v_cvt_pk_f32_fp8_sdwa v[226:227], v182 src0_sel:WORD_1
	v_cvt_pk_f32_fp8_e32 v[228:229], v183
	v_cvt_pk_f32_fp8_sdwa v[230:231], v183 src0_sel:WORD_1
	v_pk_fma_f32 v[120:121], v[224:225], v[252:253], v[120:121] op_sel:[0,1,0] op_sel_hi:[1,1,1]
	v_pk_fma_f32 v[122:123], v[226:227], v[252:253], v[122:123] op_sel:[0,1,0] op_sel_hi:[1,1,1]
	v_pk_fma_f32 v[124:125], v[228:229], v[252:253], v[124:125] op_sel:[0,1,0] op_sel_hi:[1,1,1]
	v_pk_fma_f32 v[126:127], v[230:231], v[252:253], v[126:127] op_sel:[0,1,0] op_sel_hi:[1,1,1]
	v_cvt_pk_f32_fp8_e32 v[224:225], v184
	v_cvt_pk_f32_fp8_sdwa v[226:227], v184 src0_sel:WORD_1
	v_cvt_pk_f32_fp8_e32 v[228:229], v185
	v_cvt_pk_f32_fp8_sdwa v[230:231], v185 src0_sel:WORD_1
	v_pk_fma_f32 v[112:113], v[224:225], v[254:255], v[112:113] op_sel_hi:[1,0,1]
	v_pk_fma_f32 v[114:115], v[226:227], v[254:255], v[114:115] op_sel_hi:[1,0,1]
	v_pk_fma_f32 v[116:117], v[228:229], v[254:255], v[116:117] op_sel_hi:[1,0,1]
	v_pk_fma_f32 v[118:119], v[230:231], v[254:255], v[118:119] op_sel_hi:[1,0,1]
	v_cvt_pk_f32_fp8_e32 v[224:225], v186
	v_cvt_pk_f32_fp8_sdwa v[226:227], v186 src0_sel:WORD_1
	v_cvt_pk_f32_fp8_e32 v[228:229], v187
	v_cvt_pk_f32_fp8_sdwa v[230:231], v187 src0_sel:WORD_1
	v_pk_fma_f32 v[120:121], v[224:225], v[254:255], v[120:121] op_sel_hi:[1,0,1]
	v_pk_fma_f32 v[122:123], v[226:227], v[254:255], v[122:123] op_sel_hi:[1,0,1]
	v_pk_fma_f32 v[124:125], v[228:229], v[254:255], v[124:125] op_sel_hi:[1,0,1]
	v_pk_fma_f32 v[126:127], v[230:231], v[254:255], v[126:127] op_sel_hi:[1,0,1]
	v_cvt_pk_f32_fp8_e32 v[224:225], v188
	v_cvt_pk_f32_fp8_sdwa v[226:227], v188 src0_sel:WORD_1
	v_cvt_pk_f32_fp8_e32 v[228:229], v189
	v_cvt_pk_f32_fp8_sdwa v[230:231], v189 src0_sel:WORD_1
	v_pk_fma_f32 v[112:113], v[224:225], v[254:255], v[112:113] op_sel:[0,1,0] op_sel_hi:[1,1,1]
	v_pk_fma_f32 v[114:115], v[226:227], v[254:255], v[114:115] op_sel:[0,1,0] op_sel_hi:[1,1,1]
	v_pk_fma_f32 v[116:117], v[228:229], v[254:255], v[116:117] op_sel:[0,1,0] op_sel_hi:[1,1,1]
	v_pk_fma_f32 v[118:119], v[230:231], v[254:255], v[118:119] op_sel:[0,1,0] op_sel_hi:[1,1,1]
	v_cvt_pk_f32_fp8_e32 v[224:225], v190
	v_cvt_pk_f32_fp8_sdwa v[226:227], v190 src0_sel:WORD_1
	v_cvt_pk_f32_fp8_e32 v[228:229], v191
	v_cvt_pk_f32_fp8_sdwa v[230:231], v191 src0_sel:WORD_1
	v_pk_fma_f32 v[120:121], v[224:225], v[254:255], v[120:121] op_sel:[0,1,0] op_sel_hi:[1,1,1]
	v_pk_fma_f32 v[122:123], v[226:227], v[254:255], v[122:123] op_sel:[0,1,0] op_sel_hi:[1,1,1]
	v_pk_fma_f32 v[124:125], v[228:229], v[254:255], v[124:125] op_sel:[0,1,0] op_sel_hi:[1,1,1]
	v_pk_fma_f32 v[126:127], v[230:231], v[254:255], v[126:127] op_sel:[0,1,0] op_sel_hi:[1,1,1]
	v_add_u32_e32 v213, 64, v213
	s_add_i32 s21, s21, 4
	s_sub_i32 s90, s90, 1
	s_cmp_eq_u32 s90, 0
	s_cbranch_scc1 .LV_sw0
	s_branch .LV_t7_s0
